# FFN gate/up epilogues: the G and H tile stores (2 x 190 MB per layer, each read once in the next phase) marked nt so they do not displace the residual stream and weights from the last-level cache
# baseline (speedup 1.0000x reference)
; __device__ __forceinline__ unsigned cvt_pk_bf16(float lo, float hi) { unsigned r; asm volatile("v_cvt_pk_bf16_f32 %0, %1, %2" : "=v"(r) : "v"(lo), "v"(hi)); return r; }
;     __device__ __forceinline__ void operator()(const f32x4 (&acc)[2][2][4][2], const Unit& u, int wr, int wc, int fr, int fq) const {
;     ...
;             for (int m = 0; m < 4; ++m) { const int row = row0 + ai * HALF + m * 16; bf16_t* rowp = G + (size_t)row * 2816 + col0;
;                 float* co = nullptr;
;                 if (row < 32768) { const int t = row & 8191; if (t >= 8190) co = outP + ((size_t)(row >> 13) * 2 + (t - 8190)) * 2816 + col0; }
;                 else { const int i = row & 7; if (i >= 6) co = outS + ((size_t)((row - 32768) >> 3) * 2 + (i - 6)) * 2816 + col0; }
;                 const float rs = rsqrtf(rsv[ai][m] * (1.f / 1024.f) + 1e-6f);
; #pragma unroll
;                 for (int bj = 0; bj < 2; ++bj) { const f32x4 v0 = acc[ai][bj][m][0] * rs, v1 = acc[ai][bj][m][1] * rs;
;                     u32x4 w; w.x = cvt_pk_bf16(v0[0], v0[1]); w.y = cvt_pk_bf16(v0[2], v0[3]); w.z = cvt_pk_bf16(v1[0], v1[1]); w.w = cvt_pk_bf16(v1[2], v1[3]);
;                     *(u32x4*)(rowp + bj * HALF) = w;
;                     if (co) { *(f32x4*)(co + bj * HALF) = v0; *(f32x4*)(co + bj * HALF + 4) = v1; } } }
.LBB0_836:
	s_or_b64 exec, exec, s[38:39]
	s_waitcnt vmcnt(0)
	v_fmamk_f32 v144, v144, 0x3a800000, v224
	v_cmp_gt_f32_e32 vcc, s71, v144
	v_mul_f32_e32 v145, 0x4b800000, v144
	v_readlane_b32 s38, v240, 12
	v_cndmask_b32_e32 v144, v144, v145, vcc
	v_rsq_f32_e32 v144, v144
	v_readlane_b32 s39, v240, 13
	v_mul_f32_e32 v145, 0x45800000, v144
	s_nop 0
	v_mov_b64_e32 v[142:143], s[38:39]
	v_mad_i64_i32 v[142:143], s[38:39], v2, s70, v[142:143]
	v_cndmask_b32_e32 v144, v144, v145, vcc
	v_lshl_add_u64 v[142:143], v[132:133], 1, v[142:143]
	v_cmp_ne_u64_e32 vcc, 0, v[140:141]
	v_pk_mul_f32 v[130:131], v[130:131], v[144:145] op_sel_hi:[1,0]
	v_pk_mul_f32 v[128:129], v[128:129], v[144:145] op_sel_hi:[1,0]
	v_pk_mul_f32 v[126:127], v[126:127], v[144:145] op_sel_hi:[1,0]
	v_pk_mul_f32 v[124:125], v[124:125], v[144:145] op_sel_hi:[1,0]
	v_cvt_pk_bf16_f32 v150, v128, v129
	v_cvt_pk_bf16_f32 v151, v130, v131
	s_nop 0
	v_cvt_pk_bf16_f32 v152, v124, v125
	v_cvt_pk_bf16_f32 v153, v126, v127
	global_store_dwordx4 v[142:143], v[150:153], off nt
	s_and_saveexec_b64 s[38:39], vcc
	s_cbranch_execz .LBB0_838
	global_store_dwordx4 v[140:141], v[128:131], off nt
	global_store_dwordx4 v[140:141], v[124:127], off offset:16 nt
.LBB0_838:
	s_or_b64 exec, exec, s[38:39]
	v_mov_b32_e32 v145, v144
	v_mov_b32_e32 v124, v144
	v_mov_b32_e32 v125, v144
	v_pk_mul_f32 v[122:123], v[122:123], v[124:125]
	v_pk_mul_f32 v[120:121], v[120:121], v[144:145]
	v_pk_mul_f32 v[118:119], v[118:119], v[124:125]
	v_pk_mul_f32 v[116:117], v[116:117], v[144:145]
	v_cvt_pk_bf16_f32 v124, v120, v121
	v_cvt_pk_bf16_f32 v125, v122, v123
	s_nop 0
	v_cvt_pk_bf16_f32 v126, v116, v117
	v_cvt_pk_bf16_f32 v127, v118, v119
	global_store_dwordx4 v[142:143], v[124:127], off offset:256 nt
	s_and_saveexec_b64 s[38:39], vcc
	s_cbranch_execz .LBB0_840
	global_store_dwordx4 v[140:141], v[120:123], off offset:512 nt
	global_store_dwordx4 v[140:141], v[116:119], off offset:528 nt

; __device__ __forceinline__ unsigned cvt_pk_bf16(float lo, float hi) { unsigned r; asm volatile("v_cvt_pk_bf16_f32 %0, %1, %2" : "=v"(r) : "v"(lo), "v"(hi)); return r; }
;     __device__ __forceinline__ void operator()(const f32x4 (&acc)[2][2][4][2], const Unit& u, int wr, int wc, int fr, int fq) const {
;     ...
;             for (int m = 0; m < 4; ++m) { const int row = row0 + ai * HALF + m * 16; bf16_t* rowp = G + (size_t)row * 2816 + col0;
;                 float* co = nullptr;
;                 if (row < 32768) { const int t = row & 8191; if (t >= 8190) co = outP + ((size_t)(row >> 13) * 2 + (t - 8190)) * 2816 + col0; }
;                 else { const int i = row & 7; if (i >= 6) co = outS + ((size_t)((row - 32768) >> 3) * 2 + (i - 6)) * 2816 + col0; }
;                 const float rs = rsqrtf(rsv[ai][m] * (1.f / 1024.f) + 1e-6f);
; #pragma unroll
;                 for (int bj = 0; bj < 2; ++bj) { const f32x4 v0 = acc[ai][bj][m][0] * rs, v1 = acc[ai][bj][m][1] * rs;
;                     u32x4 w; w.x = cvt_pk_bf16(v0[0], v0[1]); w.y = cvt_pk_bf16(v0[2], v0[3]); w.z = cvt_pk_bf16(v1[0], v1[1]); w.w = cvt_pk_bf16(v1[2], v1[3]);
;                     *(u32x4*)(rowp + bj * HALF) = w;
;                     if (co) { *(f32x4*)(co + bj * HALF) = v0; *(f32x4*)(co + bj * HALF + 4) = v1; } } }
.LBB0_848:
	s_or_b64 exec, exec, s[38:39]
	v_fmamk_f32 v120, v148, 0x3a800000, v224
	v_cmp_gt_f32_e32 vcc, s71, v120
	v_mul_f32_e32 v121, 0x4b800000, v120
	v_readlane_b32 s38, v240, 12
	v_cndmask_b32_e32 v120, v120, v121, vcc
	v_rsq_f32_e32 v120, v120
	v_readlane_b32 s39, v240, 13
	v_mul_f32_e32 v121, 0x45800000, v120
	s_nop 0
	v_mov_b64_e32 v[118:119], s[38:39]
	v_mad_i64_i32 v[118:119], s[38:39], v138, s70, v[118:119]
	v_cndmask_b32_e32 v120, v120, v121, vcc
	v_lshl_add_u64 v[118:119], v[132:133], 1, v[118:119]
	v_cmp_ne_u64_e32 vcc, 0, v[116:117]
	v_pk_mul_f32 v[114:115], v[114:115], v[120:121] op_sel_hi:[1,0]
	v_pk_mul_f32 v[112:113], v[112:113], v[120:121] op_sel_hi:[1,0]
	v_pk_mul_f32 v[110:111], v[110:111], v[120:121] op_sel_hi:[1,0]
	v_pk_mul_f32 v[108:109], v[108:109], v[120:121] op_sel_hi:[1,0]
	v_cvt_pk_bf16_f32 v122, v112, v113
	v_cvt_pk_bf16_f32 v123, v114, v115
	s_nop 0
	v_cvt_pk_bf16_f32 v124, v108, v109
	v_cvt_pk_bf16_f32 v125, v110, v111
	global_store_dwordx4 v[118:119], v[122:125], off nt
	s_and_saveexec_b64 s[38:39], vcc
	s_cbranch_execz .LBB0_850
	global_store_dwordx4 v[116:117], v[112:115], off nt
	global_store_dwordx4 v[116:117], v[108:111], off offset:16 nt
.LBB0_850:
	s_or_b64 exec, exec, s[38:39]
	v_mov_b32_e32 v121, v120
	v_mov_b32_e32 v108, v120
	v_mov_b32_e32 v109, v120
	v_pk_mul_f32 v[106:107], v[106:107], v[108:109]
	v_pk_mul_f32 v[104:105], v[104:105], v[120:121]
	v_pk_mul_f32 v[102:103], v[102:103], v[108:109]
	v_pk_mul_f32 v[100:101], v[100:101], v[120:121]
	v_cvt_pk_bf16_f32 v108, v104, v105
	v_cvt_pk_bf16_f32 v109, v106, v107
	s_nop 0
	v_cvt_pk_bf16_f32 v110, v100, v101
	v_cvt_pk_bf16_f32 v111, v102, v103
	global_store_dwordx4 v[118:119], v[108:111], off offset:256 nt
	s_and_saveexec_b64 s[38:39], vcc
	s_cbranch_execz .LBB0_852
	global_store_dwordx4 v[116:117], v[104:107], off offset:512 nt
	global_store_dwordx4 v[116:117], v[100:103], off offset:528 nt

; __device__ __forceinline__ unsigned cvt_pk_bf16(float lo, float hi) { unsigned r; asm volatile("v_cvt_pk_bf16_f32 %0, %1, %2" : "=v"(r) : "v"(lo), "v"(hi)); return r; }
;     __device__ __forceinline__ void operator()(const f32x4 (&acc)[2][2][4][2], const Unit& u, int wr, int wc, int fr, int fq) const {
;     ...
;             for (int m = 0; m < 4; ++m) { const int row = row0 + ai * HALF + m * 16; bf16_t* rowp = G + (size_t)row * 2816 + col0;
;                 float* co = nullptr;
;                 if (row < 32768) { const int t = row & 8191; if (t >= 8190) co = outP + ((size_t)(row >> 13) * 2 + (t - 8190)) * 2816 + col0; }
;                 else { const int i = row & 7; if (i >= 6) co = outS + ((size_t)((row - 32768) >> 3) * 2 + (i - 6)) * 2816 + col0; }
;                 const float rs = rsqrtf(rsv[ai][m] * (1.f / 1024.f) + 1e-6f);
; #pragma unroll
;                 for (int bj = 0; bj < 2; ++bj) { const f32x4 v0 = acc[ai][bj][m][0] * rs, v1 = acc[ai][bj][m][1] * rs;
;                     u32x4 w; w.x = cvt_pk_bf16(v0[0], v0[1]); w.y = cvt_pk_bf16(v0[2], v0[3]); w.z = cvt_pk_bf16(v1[0], v1[1]); w.w = cvt_pk_bf16(v1[2], v1[3]);
;                     *(u32x4*)(rowp + bj * HALF) = w;
;                     if (co) { *(f32x4*)(co + bj * HALF) = v0; *(f32x4*)(co + bj * HALF + 4) = v1; } } }
.LBB0_860:
	s_or_b64 exec, exec, s[38:39]
	v_fmamk_f32 v104, v147, 0x3a800000, v224
	v_cmp_gt_f32_e32 vcc, s71, v104
	v_mul_f32_e32 v105, 0x4b800000, v104
	v_readlane_b32 s38, v240, 12
	v_cndmask_b32_e32 v104, v104, v105, vcc
	v_rsq_f32_e32 v104, v104
	v_readlane_b32 s39, v240, 13
	v_mul_f32_e32 v105, 0x45800000, v104
	s_nop 0
	v_mov_b64_e32 v[102:103], s[38:39]
	v_mad_i64_i32 v[102:103], s[38:39], v136, s70, v[102:103]
	v_cndmask_b32_e32 v104, v104, v105, vcc
	v_lshl_add_u64 v[102:103], v[132:133], 1, v[102:103]
	v_cmp_ne_u64_e32 vcc, 0, v[100:101]
	v_pk_mul_f32 v[98:99], v[98:99], v[104:105] op_sel_hi:[1,0]
	v_pk_mul_f32 v[96:97], v[96:97], v[104:105] op_sel_hi:[1,0]
	v_pk_mul_f32 v[94:95], v[94:95], v[104:105] op_sel_hi:[1,0]
	v_pk_mul_f32 v[92:93], v[92:93], v[104:105] op_sel_hi:[1,0]
	v_cvt_pk_bf16_f32 v106, v96, v97
	v_cvt_pk_bf16_f32 v107, v98, v99
	s_nop 0
	v_cvt_pk_bf16_f32 v108, v92, v93
	v_cvt_pk_bf16_f32 v109, v94, v95
	global_store_dwordx4 v[102:103], v[106:109], off nt
	s_and_saveexec_b64 s[38:39], vcc
	s_cbranch_execz .LBB0_862
	global_store_dwordx4 v[100:101], v[96:99], off nt
	global_store_dwordx4 v[100:101], v[92:95], off offset:16 nt
.LBB0_862:
	s_or_b64 exec, exec, s[38:39]
	v_mov_b32_e32 v105, v104
	v_mov_b32_e32 v92, v104
	v_mov_b32_e32 v93, v104
	v_pk_mul_f32 v[90:91], v[90:91], v[92:93]
	v_pk_mul_f32 v[88:89], v[88:89], v[104:105]
	v_pk_mul_f32 v[86:87], v[86:87], v[92:93]
	v_pk_mul_f32 v[84:85], v[84:85], v[104:105]
	v_cvt_pk_bf16_f32 v92, v88, v89
	v_cvt_pk_bf16_f32 v93, v90, v91
	s_nop 0
	v_cvt_pk_bf16_f32 v94, v84, v85
	v_cvt_pk_bf16_f32 v95, v86, v87
	global_store_dwordx4 v[102:103], v[92:95], off offset:256 nt
	s_and_saveexec_b64 s[38:39], vcc
	s_cbranch_execz .LBB0_864
	global_store_dwordx4 v[100:101], v[88:91], off offset:512 nt
	global_store_dwordx4 v[100:101], v[84:87], off offset:528 nt

; __device__ __forceinline__ unsigned cvt_pk_bf16(float lo, float hi) { unsigned r; asm volatile("v_cvt_pk_bf16_f32 %0, %1, %2" : "=v"(r) : "v"(lo), "v"(hi)); return r; }
;     __device__ __forceinline__ void operator()(const f32x4 (&acc)[2][2][4][2], const Unit& u, int wr, int wc, int fr, int fq) const {
;     ...
;             for (int m = 0; m < 4; ++m) { const int row = row0 + ai * HALF + m * 16; bf16_t* rowp = G + (size_t)row * 2816 + col0;
;                 float* co = nullptr;
;                 if (row < 32768) { const int t = row & 8191; if (t >= 8190) co = outP + ((size_t)(row >> 13) * 2 + (t - 8190)) * 2816 + col0; }
;                 else { const int i = row & 7; if (i >= 6) co = outS + ((size_t)((row - 32768) >> 3) * 2 + (i - 6)) * 2816 + col0; }
;                 const float rs = rsqrtf(rsv[ai][m] * (1.f / 1024.f) + 1e-6f);
; #pragma unroll
;                 for (int bj = 0; bj < 2; ++bj) { const f32x4 v0 = acc[ai][bj][m][0] * rs, v1 = acc[ai][bj][m][1] * rs;
;                     u32x4 w; w.x = cvt_pk_bf16(v0[0], v0[1]); w.y = cvt_pk_bf16(v0[2], v0[3]); w.z = cvt_pk_bf16(v1[0], v1[1]); w.w = cvt_pk_bf16(v1[2], v1[3]);
;                     *(u32x4*)(rowp + bj * HALF) = w;
;                     if (co) { *(f32x4*)(co + bj * HALF) = v0; *(f32x4*)(co + bj * HALF + 4) = v1; } } }
.LBB0_872:
	s_or_b64 exec, exec, s[38:39]
	v_fmamk_f32 v88, v146, 0x3a800000, v224
	v_cmp_gt_f32_e32 vcc, s71, v88
	v_mul_f32_e32 v89, 0x4b800000, v88
	v_readlane_b32 s38, v240, 12
	v_cndmask_b32_e32 v88, v88, v89, vcc
	v_rsq_f32_e32 v88, v88
	v_readlane_b32 s39, v240, 13
	v_mul_f32_e32 v89, 0x45800000, v88
	s_nop 0
	v_mov_b64_e32 v[86:87], s[38:39]
	v_mad_i64_i32 v[86:87], s[38:39], v134, s70, v[86:87]
	v_cndmask_b32_e32 v88, v88, v89, vcc
	v_lshl_add_u64 v[86:87], v[132:133], 1, v[86:87]
	v_cmp_ne_u64_e32 vcc, 0, v[84:85]
	v_pk_mul_f32 v[82:83], v[82:83], v[88:89] op_sel_hi:[1,0]
	v_pk_mul_f32 v[80:81], v[80:81], v[88:89] op_sel_hi:[1,0]
	v_pk_mul_f32 v[78:79], v[78:79], v[88:89] op_sel_hi:[1,0]
	v_pk_mul_f32 v[76:77], v[76:77], v[88:89] op_sel_hi:[1,0]
	v_cvt_pk_bf16_f32 v90, v80, v81
	v_cvt_pk_bf16_f32 v91, v82, v83
	s_nop 0
	v_cvt_pk_bf16_f32 v92, v76, v77
	v_cvt_pk_bf16_f32 v93, v78, v79
	global_store_dwordx4 v[86:87], v[90:93], off nt
	s_and_saveexec_b64 s[38:39], vcc
	s_cbranch_execz .LBB0_874
	global_store_dwordx4 v[84:85], v[80:83], off nt
	global_store_dwordx4 v[84:85], v[76:79], off offset:16 nt
.LBB0_874:
	s_or_b64 exec, exec, s[38:39]
	v_mov_b32_e32 v89, v88
	v_mov_b32_e32 v76, v88
	v_mov_b32_e32 v77, v88
	v_pk_mul_f32 v[74:75], v[74:75], v[76:77]
	v_pk_mul_f32 v[72:73], v[72:73], v[88:89]
	v_pk_mul_f32 v[70:71], v[70:71], v[76:77]
	v_pk_mul_f32 v[68:69], v[68:69], v[88:89]
	v_cvt_pk_bf16_f32 v76, v72, v73
	v_cvt_pk_bf16_f32 v77, v74, v75
	s_nop 0
	v_cvt_pk_bf16_f32 v78, v68, v69
	v_cvt_pk_bf16_f32 v79, v70, v71
	global_store_dwordx4 v[86:87], v[76:79], off offset:256 nt
	s_and_saveexec_b64 s[38:39], vcc
	s_cbranch_execz .LBB0_925
	global_store_dwordx4 v[84:85], v[72:75], off offset:512 nt
	global_store_dwordx4 v[84:85], v[68:71], off offset:528 nt
	s_or_b64 exec, exec, s[38:39]
	s_and_b64 vcc, exec, s[8:9]
	s_cbranch_vccnz .LBB0_926

; __device__ __forceinline__ unsigned cvt_pk_bf16(float lo, float hi) { unsigned r; asm volatile("v_cvt_pk_bf16_f32 %0, %1, %2" : "=v"(r) : "v"(lo), "v"(hi)); return r; }
;     __device__ __forceinline__ void operator()(const f32x4 (&acc)[2][2][4][2], const Unit& u, int wr, int wc, int fr, int fq) const {
;     ...
;             for (int m = 0; m < 4; ++m) { const int row = row0 + ai * HALF + m * 16; bf16_t* rowp = G + (size_t)row * 2816 + col0;
;                 float* co = nullptr;
;                 if (row < 32768) { const int t = row & 8191; if (t >= 8190) co = outP + ((size_t)(row >> 13) * 2 + (t - 8190)) * 2816 + col0; }
;                 else { const int i = row & 7; if (i >= 6) co = outS + ((size_t)((row - 32768) >> 3) * 2 + (i - 6)) * 2816 + col0; }
;                 const float rs = rsqrtf(rsv[ai][m] * (1.f / 1024.f) + 1e-6f);
; #pragma unroll
;                 for (int bj = 0; bj < 2; ++bj) { const f32x4 v0 = acc[ai][bj][m][0] * rs, v1 = acc[ai][bj][m][1] * rs;
;                     u32x4 w; w.x = cvt_pk_bf16(v0[0], v0[1]); w.y = cvt_pk_bf16(v0[2], v0[3]); w.z = cvt_pk_bf16(v1[0], v1[1]); w.w = cvt_pk_bf16(v1[2], v1[3]);
;                     *(u32x4*)(rowp + bj * HALF) = w;
;                     if (co) { *(f32x4*)(co + bj * HALF) = v0; *(f32x4*)(co + bj * HALF + 4) = v1; } } }
.LBB0_884:
	s_or_b64 exec, exec, s[8:9]
	v_readlane_b32 s8, v240, 12
	v_readlane_b32 s9, v240, 13
	s_nop 1
	v_mov_b64_e32 v[72:73], s[8:9]
	v_mad_i64_i32 v[70:71], s[8:9], v70, s70, v[72:73]
	v_fmamk_f32 v72, v139, 0x3a800000, v224
	v_cmp_gt_f32_e32 vcc, s71, v72
	v_mul_f32_e32 v73, 0x4b800000, v72
	v_lshl_add_u64 v[70:71], v[132:133], 1, v[70:71]
	v_cndmask_b32_e32 v72, v72, v73, vcc
	v_rsq_f32_e32 v72, v72
	s_nop 0
	v_mul_f32_e32 v73, 0x45800000, v72
	v_cndmask_b32_e32 v72, v72, v73, vcc
	v_cmp_ne_u64_e32 vcc, 0, v[68:69]
	v_pk_mul_f32 v[66:67], v[66:67], v[72:73] op_sel_hi:[1,0]
	v_pk_mul_f32 v[64:65], v[64:65], v[72:73] op_sel_hi:[1,0]
	v_pk_mul_f32 v[62:63], v[62:63], v[72:73] op_sel_hi:[1,0]
	v_pk_mul_f32 v[60:61], v[60:61], v[72:73] op_sel_hi:[1,0]
	v_cvt_pk_bf16_f32 v74, v64, v65
	v_cvt_pk_bf16_f32 v75, v66, v67
	s_nop 0
	v_cvt_pk_bf16_f32 v76, v60, v61
	v_cvt_pk_bf16_f32 v77, v62, v63
	global_store_dwordx4 v[70:71], v[74:77], off nt
	s_and_saveexec_b64 s[8:9], vcc
	s_cbranch_execz .LBB0_886
	global_store_dwordx4 v[68:69], v[64:67], off nt
	global_store_dwordx4 v[68:69], v[60:63], off offset:16 nt
.LBB0_886:
	s_or_b64 exec, exec, s[8:9]
	v_mov_b32_e32 v73, v72
	v_mov_b32_e32 v60, v72
	v_mov_b32_e32 v61, v72
	v_pk_mul_f32 v[58:59], v[58:59], v[60:61]
	v_pk_mul_f32 v[56:57], v[56:57], v[72:73]
	v_pk_mul_f32 v[54:55], v[54:55], v[60:61]
	v_pk_mul_f32 v[52:53], v[52:53], v[72:73]
	v_cvt_pk_bf16_f32 v60, v56, v57
	v_cvt_pk_bf16_f32 v61, v58, v59
	s_nop 0
	v_cvt_pk_bf16_f32 v62, v52, v53
	v_cvt_pk_bf16_f32 v63, v54, v55
	global_store_dwordx4 v[70:71], v[60:63], off offset:256 nt
	s_and_saveexec_b64 s[8:9], vcc
	s_cbranch_execz .LBB0_888
	global_store_dwordx4 v[68:69], v[56:59], off offset:512 nt
	global_store_dwordx4 v[68:69], v[52:55], off offset:528 nt

; __device__ __forceinline__ unsigned cvt_pk_bf16(float lo, float hi) { unsigned r; asm volatile("v_cvt_pk_bf16_f32 %0, %1, %2" : "=v"(r) : "v"(lo), "v"(hi)); return r; }
;     __device__ __forceinline__ void operator()(const f32x4 (&acc)[2][2][4][2], const Unit& u, int wr, int wc, int fr, int fq) const {
;     ...
;             for (int m = 0; m < 4; ++m) { const int row = row0 + ai * HALF + m * 16; bf16_t* rowp = G + (size_t)row * 2816 + col0;
;                 float* co = nullptr;
;                 if (row < 32768) { const int t = row & 8191; if (t >= 8190) co = outP + ((size_t)(row >> 13) * 2 + (t - 8190)) * 2816 + col0; }
;                 else { const int i = row & 7; if (i >= 6) co = outS + ((size_t)((row - 32768) >> 3) * 2 + (i - 6)) * 2816 + col0; }
;                 const float rs = rsqrtf(rsv[ai][m] * (1.f / 1024.f) + 1e-6f);
; #pragma unroll
;                 for (int bj = 0; bj < 2; ++bj) { const f32x4 v0 = acc[ai][bj][m][0] * rs, v1 = acc[ai][bj][m][1] * rs;
;                     u32x4 w; w.x = cvt_pk_bf16(v0[0], v0[1]); w.y = cvt_pk_bf16(v0[2], v0[3]); w.z = cvt_pk_bf16(v1[0], v1[1]); w.w = cvt_pk_bf16(v1[2], v1[3]);
;                     *(u32x4*)(rowp + bj * HALF) = w;
;                     if (co) { *(f32x4*)(co + bj * HALF) = v0; *(f32x4*)(co + bj * HALF + 4) = v1; } } }
.LBB0_896:
	s_or_b64 exec, exec, s[8:9]
	v_readlane_b32 s8, v240, 12
	v_readlane_b32 s9, v240, 13
	s_nop 1
	v_mov_b64_e32 v[56:57], s[8:9]
	v_mad_i64_i32 v[54:55], s[8:9], v54, s70, v[56:57]
	v_fmamk_f32 v56, v137, 0x3a800000, v224
	v_cmp_gt_f32_e32 vcc, s71, v56
	v_mul_f32_e32 v57, 0x4b800000, v56
	v_lshl_add_u64 v[54:55], v[132:133], 1, v[54:55]
	v_cndmask_b32_e32 v56, v56, v57, vcc
	v_rsq_f32_e32 v56, v56
	s_nop 0
	v_mul_f32_e32 v57, 0x45800000, v56
	v_cndmask_b32_e32 v56, v56, v57, vcc
	v_cmp_ne_u64_e32 vcc, 0, v[52:53]
	v_pk_mul_f32 v[50:51], v[50:51], v[56:57] op_sel_hi:[1,0]
	v_pk_mul_f32 v[48:49], v[48:49], v[56:57] op_sel_hi:[1,0]
	v_pk_mul_f32 v[46:47], v[46:47], v[56:57] op_sel_hi:[1,0]
	v_pk_mul_f32 v[44:45], v[44:45], v[56:57] op_sel_hi:[1,0]
	v_cvt_pk_bf16_f32 v58, v48, v49
	v_cvt_pk_bf16_f32 v59, v50, v51
	s_nop 0
	v_cvt_pk_bf16_f32 v60, v44, v45
	v_cvt_pk_bf16_f32 v61, v46, v47
	global_store_dwordx4 v[54:55], v[58:61], off nt
	s_and_saveexec_b64 s[8:9], vcc
	s_cbranch_execz .LBB0_898
	global_store_dwordx4 v[52:53], v[48:51], off nt
	global_store_dwordx4 v[52:53], v[44:47], off offset:16 nt
.LBB0_898:
	s_or_b64 exec, exec, s[8:9]
	v_mov_b32_e32 v57, v56
	v_mov_b32_e32 v44, v56
	v_mov_b32_e32 v45, v56
	v_pk_mul_f32 v[42:43], v[42:43], v[44:45]
	v_pk_mul_f32 v[40:41], v[40:41], v[56:57]
	v_pk_mul_f32 v[38:39], v[38:39], v[44:45]
	v_pk_mul_f32 v[36:37], v[36:37], v[56:57]
	v_cvt_pk_bf16_f32 v44, v40, v41
	v_cvt_pk_bf16_f32 v45, v42, v43
	s_nop 0
	v_cvt_pk_bf16_f32 v46, v36, v37
	v_cvt_pk_bf16_f32 v47, v38, v39
	global_store_dwordx4 v[54:55], v[44:47], off offset:256 nt
	s_and_saveexec_b64 s[8:9], vcc
	s_cbranch_execz .LBB0_900
	global_store_dwordx4 v[52:53], v[40:43], off offset:512 nt
	global_store_dwordx4 v[52:53], v[36:39], off offset:528 nt

; __device__ __forceinline__ unsigned cvt_pk_bf16(float lo, float hi) { unsigned r; asm volatile("v_cvt_pk_bf16_f32 %0, %1, %2" : "=v"(r) : "v"(lo), "v"(hi)); return r; }
;     __device__ __forceinline__ void operator()(const f32x4 (&acc)[2][2][4][2], const Unit& u, int wr, int wc, int fr, int fq) const {
;     ...
;             for (int m = 0; m < 4; ++m) { const int row = row0 + ai * HALF + m * 16; bf16_t* rowp = G + (size_t)row * 2816 + col0;
;                 float* co = nullptr;
;                 if (row < 32768) { const int t = row & 8191; if (t >= 8190) co = outP + ((size_t)(row >> 13) * 2 + (t - 8190)) * 2816 + col0; }
;                 else { const int i = row & 7; if (i >= 6) co = outS + ((size_t)((row - 32768) >> 3) * 2 + (i - 6)) * 2816 + col0; }
;                 const float rs = rsqrtf(rsv[ai][m] * (1.f / 1024.f) + 1e-6f);
; #pragma unroll
;                 for (int bj = 0; bj < 2; ++bj) { const f32x4 v0 = acc[ai][bj][m][0] * rs, v1 = acc[ai][bj][m][1] * rs;
;                     u32x4 w; w.x = cvt_pk_bf16(v0[0], v0[1]); w.y = cvt_pk_bf16(v0[2], v0[3]); w.z = cvt_pk_bf16(v1[0], v1[1]); w.w = cvt_pk_bf16(v1[2], v1[3]);
;                     *(u32x4*)(rowp + bj * HALF) = w;
;                     if (co) { *(f32x4*)(co + bj * HALF) = v0; *(f32x4*)(co + bj * HALF + 4) = v1; } } }
.LBB0_908:
	s_or_b64 exec, exec, s[8:9]
	v_readlane_b32 s8, v240, 12
	v_readlane_b32 s9, v240, 13
	s_nop 1
	v_mov_b64_e32 v[40:41], s[8:9]
	v_mad_i64_i32 v[38:39], s[8:9], v38, s70, v[40:41]
	v_fmamk_f32 v40, v135, 0x3a800000, v224
	v_cmp_gt_f32_e32 vcc, s71, v40
	v_mul_f32_e32 v41, 0x4b800000, v40
	v_lshl_add_u64 v[38:39], v[132:133], 1, v[38:39]
	v_cndmask_b32_e32 v40, v40, v41, vcc
	v_rsq_f32_e32 v40, v40
	s_nop 0
	v_mul_f32_e32 v41, 0x45800000, v40
	v_cndmask_b32_e32 v40, v40, v41, vcc
	v_cmp_ne_u64_e32 vcc, 0, v[36:37]
	v_pk_mul_f32 v[34:35], v[34:35], v[40:41] op_sel_hi:[1,0]
	v_pk_mul_f32 v[32:33], v[32:33], v[40:41] op_sel_hi:[1,0]
	v_pk_mul_f32 v[30:31], v[30:31], v[40:41] op_sel_hi:[1,0]
	v_pk_mul_f32 v[28:29], v[28:29], v[40:41] op_sel_hi:[1,0]
	v_cvt_pk_bf16_f32 v42, v32, v33
	v_cvt_pk_bf16_f32 v43, v34, v35
	s_nop 0
	v_cvt_pk_bf16_f32 v44, v28, v29
	v_cvt_pk_bf16_f32 v45, v30, v31
	global_store_dwordx4 v[38:39], v[42:45], off nt
	s_and_saveexec_b64 s[8:9], vcc
	s_cbranch_execz .LBB0_910
	global_store_dwordx4 v[36:37], v[32:35], off nt
	global_store_dwordx4 v[36:37], v[28:31], off offset:16 nt
.LBB0_910:
	s_or_b64 exec, exec, s[8:9]
	v_mov_b32_e32 v41, v40
	v_mov_b32_e32 v28, v40
	v_mov_b32_e32 v29, v40
	v_pk_mul_f32 v[26:27], v[26:27], v[28:29]
	v_pk_mul_f32 v[24:25], v[24:25], v[40:41]
	v_pk_mul_f32 v[22:23], v[22:23], v[28:29]
	v_pk_mul_f32 v[20:21], v[20:21], v[40:41]
	v_cvt_pk_bf16_f32 v28, v24, v25
	v_cvt_pk_bf16_f32 v29, v26, v27
	s_nop 0
	v_cvt_pk_bf16_f32 v30, v20, v21
	v_cvt_pk_bf16_f32 v31, v22, v23
	global_store_dwordx4 v[38:39], v[28:31], off offset:256 nt
	s_and_saveexec_b64 s[8:9], vcc
	s_cbranch_execz .LBB0_912
	global_store_dwordx4 v[36:37], v[24:27], off offset:512 nt
	global_store_dwordx4 v[36:37], v[20:23], off offset:528 nt

; __device__ __forceinline__ unsigned cvt_pk_bf16(float lo, float hi) { unsigned r; asm volatile("v_cvt_pk_bf16_f32 %0, %1, %2" : "=v"(r) : "v"(lo), "v"(hi)); return r; }
;     __device__ __forceinline__ void operator()(const f32x4 (&acc)[2][2][4][2], const Unit& u, int wr, int wc, int fr, int fq) const {
;     ...
;             for (int m = 0; m < 4; ++m) { const int row = row0 + ai * HALF + m * 16; bf16_t* rowp = G + (size_t)row * 2816 + col0;
;                 float* co = nullptr;
;                 if (row < 32768) { const int t = row & 8191; if (t >= 8190) co = outP + ((size_t)(row >> 13) * 2 + (t - 8190)) * 2816 + col0; }
;                 else { const int i = row & 7; if (i >= 6) co = outS + ((size_t)((row - 32768) >> 3) * 2 + (i - 6)) * 2816 + col0; }
;                 const float rs = rsqrtf(rsv[ai][m] * (1.f / 1024.f) + 1e-6f);
; #pragma unroll
;                 for (int bj = 0; bj < 2; ++bj) { const f32x4 v0 = acc[ai][bj][m][0] * rs, v1 = acc[ai][bj][m][1] * rs;
;                     u32x4 w; w.x = cvt_pk_bf16(v0[0], v0[1]); w.y = cvt_pk_bf16(v0[2], v0[3]); w.z = cvt_pk_bf16(v1[0], v1[1]); w.w = cvt_pk_bf16(v1[2], v1[3]);
;                     *(u32x4*)(rowp + bj * HALF) = w;
;                     if (co) { *(f32x4*)(co + bj * HALF) = v0; *(f32x4*)(co + bj * HALF + 4) = v1; } } }
.LBB0_920:
	s_or_b64 exec, exec, s[0:1]
	v_readlane_b32 s0, v240, 12
	v_readlane_b32 s1, v240, 13
	v_fmamk_f32 v1, v1, 0x3a800000, v224
	v_cmp_gt_f32_e32 vcc, s71, v1
	v_mov_b64_e32 v[22:23], s[0:1]
	v_mad_i64_i32 v[2:3], s[0:1], v2, s70, v[22:23]
	v_mul_f32_e32 v22, 0x4b800000, v1
	v_cndmask_b32_e32 v1, v1, v22, vcc
	v_rsq_f32_e32 v1, v1
	v_lshl_add_u64 v[2:3], v[132:133], 1, v[2:3]
	v_mul_f32_e32 v22, 0x45800000, v1
	v_cndmask_b32_e32 v22, v1, v22, vcc
	v_cmp_ne_u64_e32 vcc, 0, v[20:21]
	v_pk_mul_f32 v[18:19], v[18:19], v[22:23] op_sel_hi:[1,0]
	v_pk_mul_f32 v[16:17], v[16:17], v[22:23] op_sel_hi:[1,0]
	v_pk_mul_f32 v[14:15], v[14:15], v[22:23] op_sel_hi:[1,0]
	v_pk_mul_f32 v[12:13], v[12:13], v[22:23] op_sel_hi:[1,0]
	v_cvt_pk_bf16_f32 v24, v16, v17
	v_cvt_pk_bf16_f32 v25, v18, v19
	s_nop 0
	v_cvt_pk_bf16_f32 v26, v12, v13
	v_cvt_pk_bf16_f32 v27, v14, v15
	global_store_dwordx4 v[2:3], v[24:27], off nt
	s_and_saveexec_b64 s[0:1], vcc
	s_cbranch_execz .LBB0_922
	global_store_dwordx4 v[20:21], v[16:19], off nt
	global_store_dwordx4 v[20:21], v[12:15], off offset:16 nt
.LBB0_922:
	s_or_b64 exec, exec, s[0:1]
	v_mov_b32_e32 v23, v22
	v_mov_b32_e32 v12, v22
	v_mov_b32_e32 v13, v22
	v_pk_mul_f32 v[10:11], v[10:11], v[12:13]
	v_pk_mul_f32 v[8:9], v[8:9], v[22:23]
	v_pk_mul_f32 v[6:7], v[6:7], v[12:13]
	v_pk_mul_f32 v[4:5], v[4:5], v[22:23]
	v_cvt_pk_bf16_f32 v12, v8, v9
	v_cvt_pk_bf16_f32 v13, v10, v11
	s_nop 0
	v_cvt_pk_bf16_f32 v14, v4, v5
	v_cvt_pk_bf16_f32 v15, v6, v7
	global_store_dwordx4 v[2:3], v[12:15], off offset:256 nt
	s_and_saveexec_b64 s[0:1], vcc
	s_cbranch_execz .LBB0_924
	global_store_dwordx4 v[20:21], v[8:11], off offset:512 nt
	global_store_dwordx4 v[20:21], v[4:7], off offset:528 nt

;     static __device__ __forceinline__ void unpk4(const u32x2 w, float (&o)[4]) { o[0] = bf_lo(w.x); o[1] = bf_hi(w.x); o[2] = bf_lo(w.y); o[3] = bf_hi(w.y); }
;     template <int N> static __device__ __forceinline__ u32x2 dpp_prev(const u32x2 pv, const u32x2 cur) { u32x2 r; r.x = dpp_prev1<N>(pv.x, cur.x); r.y = dpp_prev1<N>(pv.y, cur.y); return r; }
;     __device__ __forceinline__ void operator()(const f32x4 (&acc)[2][2][4][2], const Unit& u, int wr, int wc, int fr, int fq) const {
;     ...
;             for (int m = 0; m < 4; ++m) rs8[ai][m] = rsqrtf(SS[u.rb + (u.half ? 0 : ai * HALF) + wr * 64 + fr + 16 * m] * (1.f / 1024.f) + 1e-6f);
;         if (u.pm < 128) {
;     ...
;         for (int bj = 0; bj < 2; ++bj)
; #pragma unroll
;           for (int hv = 0; hv < 2; ++hv) {
;             const int col = u.pn * BM + bj * HALF + wc * 32 + 8 * fq + 4 * hv;
;             float w0[4], w1[4], w2[4], bb[4];
;             ld4f(cw + col, w0); ld4f(cw + 2816 + col, w1); ld4f(cw + 2 * 2816 + col, w2); ld4f(cb + col, bb);
;             {
;                 const int i = fr & 7;
;                 u32x2 gq[4];
; #pragma unroll
;                 for (int m = 0; m < 4; ++m) { const int row = row0 + m * 16; gq[m] = *(const u32x2*)(G + (size_t)row * 2816 + col); }
; #pragma unroll
;                 for (int mh = 0; mh < 4; mh += 2) {
;                 f32x4 c0[4], c1[4];
; #pragma unroll
;                 for (int m = mh; m < mh + 2; ++m) { const int row = row0 + m * 16; const float* cx = ctx + (size_t)((row - 32768) >> 3) * 2 * 2816 + col;
;                     c0[m] = *(const f32x4*)cx; c1[m] = *(const f32x4*)(cx + 2816); }
; #pragma unroll
;                 for (int m = mh; m < mh + 2; ++m) { const int row = row0 + m * 16; const u32x2 cur = gq[m];
;                     const u32x2 q1 = dpp_prev<1>(cur, cur), q2 = dpp_prev<2>(cur, cur);
;                     float g0[4], g1[4], g2[4]; unpk4(cur, g0); unpk4(q1, g1); unpk4(q2, g2);
.LBB0_1007:
	v_readlane_b32 s0, v240, 29
	v_mov_b32_e32 v1, v218
	v_mov_b32_e32 v132, v219
	s_add_i32 s2, s2, s0
	v_readlane_b32 s0, v240, 31
	v_add_u32_e32 v210, s2, v1
	v_ashrrev_i32_e32 v211, 31, v210
	v_lshl_add_u64 v[2:3], v[210:211], 2, s[12:13]
	global_load_dword v2, v[2:3], off
	s_waitcnt lgkmcnt(0)
	v_add_u32_e32 v194, 16, v210
	v_ashrrev_i32_e32 v195, 31, v194
	v_add_u32_e32 v192, 32, v210
	v_ashrrev_i32_e32 v193, 31, v192
	v_add_u32_e32 v190, 48, v210
	v_ashrrev_i32_e32 v191, 31, v190
	s_cmpk_lt_i32 s7, 0x80
	s_waitcnt vmcnt(0)
	v_fmamk_f32 v2, v2, 0x3a800000, v224
	v_cmp_gt_f32_e32 vcc, s5, v2
	v_mul_f32_e32 v3, 0x4b800000, v2
	s_nop 0
	v_cndmask_b32_e32 v2, v2, v3, vcc
	v_rsq_f32_e32 v2, v2
	s_nop 0
	v_mul_f32_e32 v3, 0x45800000, v2
	v_cndmask_b32_e32 v188, v2, v3, vcc
	v_lshl_add_u64 v[2:3], v[194:195], 2, s[12:13]
	global_load_dword v2, v[2:3], off
	s_waitcnt vmcnt(0)
	v_fmamk_f32 v2, v2, 0x3a800000, v224
	v_cmp_gt_f32_e32 vcc, s5, v2
	v_mul_f32_e32 v3, 0x4b800000, v2
	s_nop 0
	v_cndmask_b32_e32 v2, v2, v3, vcc
	v_rsq_f32_e32 v2, v2
	s_nop 0
	v_mul_f32_e32 v3, 0x45800000, v2
	v_cndmask_b32_e32 v186, v2, v3, vcc
	v_lshl_add_u64 v[2:3], v[192:193], 2, s[12:13]
	global_load_dword v2, v[2:3], off
	s_waitcnt vmcnt(0)
	v_fmamk_f32 v2, v2, 0x3a800000, v224
	v_cmp_gt_f32_e32 vcc, s5, v2
	v_mul_f32_e32 v3, 0x4b800000, v2
	s_nop 0
	v_cndmask_b32_e32 v2, v2, v3, vcc
	v_rsq_f32_e32 v2, v2
	s_nop 0
	v_mul_f32_e32 v3, 0x45800000, v2
	v_cndmask_b32_e32 v184, v2, v3, vcc
	v_lshl_add_u64 v[2:3], v[190:191], 2, s[12:13]
	global_load_dword v2, v[2:3], off
	s_waitcnt vmcnt(0)
	v_fmamk_f32 v2, v2, 0x3a800000, v224
	v_cmp_gt_f32_e32 vcc, s5, v2
	v_mul_f32_e32 v3, 0x4b800000, v2
	s_nop 0
	v_cndmask_b32_e32 v2, v2, v3, vcc
	v_rsq_f32_e32 v2, v2
	s_nop 0
	v_mul_f32_e32 v3, 0x45800000, v2
	v_cndmask_b32_e32 v2, v2, v3, vcc
	v_lshl_add_u32 v3, v132, 3, s0
	s_mov_b64 s[0:1], -1
	s_cbranch_scc1 .LBB0_1009
	v_lshl_add_u32 v150, s70, 8, v3
	v_ashrrev_i32_e32 v151, 31, v150
	v_readlane_b32 s68, v240, 12
	v_lshlrev_b64 v[160:161], 1, v[150:151]
	v_readlane_b32 s69, v240, 13
	v_add_u32_e32 v134, 0xffff8000, v210
	s_mov_b64 s[86:87], s[54:55]
	v_lshl_add_u64 v[162:163], s[68:69], 0, v[160:161]
	v_mad_i64_i32 v[132:133], s[0:1], v210, s91, v[162:163]
	global_load_dwordx2 v[154:155], v[132:133], off
	v_lshlrev_b64 v[132:133], 2, v[150:151]
	v_lshl_add_u64 v[156:157], s[82:83], 0, v[132:133]
	v_ashrrev_i32_e32 v151, 3, v134
	v_mad_i64_i32 v[134:135], s[0:1], v151, s45, v[156:157]
	v_readlane_b32 s52, v240, 62
	v_add_co_u32_e32 v136, vcc, s41, v134
	v_readlane_b32 s53, v240, 63
	s_nop 0
	v_addc_co_u32_e32 v137, vcc, 0, v135, vcc
	global_load_dwordx4 v[170:173], v[134:135], off
	global_load_dwordx4 v[174:177], v[136:137], off offset:3072
	v_readlane_b32 s54, v239, 0
	v_readlane_b32 s55, v239, 1
	v_readlane_b32 s66, v239, 12
	v_readlane_b32 s67, v239, 13
	v_readlane_b32 s52, v240, 19
	v_readlane_b32 s53, v240, 20
	v_lshl_add_u64 v[134:135], s[66:67], 0, v[132:133]
	v_readlane_b32 s54, v240, 21
	v_lshl_add_u64 v[136:137], s[88:89], 0, v[132:133]
	global_load_dwordx4 v[140:143], v[134:135], off
	global_load_dwordx4 v[144:147], v[136:137], off
	v_lshl_add_u64 v[134:135], s[52:53], 0, v[132:133]
	v_readlane_b32 s55, v240, 22
	global_load_dwordx4 v[136:139], v[134:135], off
	v_add_u32_e32 v152, 0xffff8010, v210
	v_lshl_add_u64 v[132:133], s[54:55], 0, v[132:133]
	global_load_dwordx4 v[132:135], v[132:133], off
	v_readlane_b32 s0, v240, 58
	v_readlane_b32 s1, v240, 59
	v_ashrrev_i32_e32 v168, 3, v152
	v_and_b32_e32 v169, 7, v1
	v_mov_b64_e32 v[158:159], s[0:1]
	v_mad_i64_i32 v[180:181], s[0:1], v168, s45, v[156:157]
	v_mad_i64_i32 v[164:165], s[0:1], v194, s91, v[162:163]
	v_mad_i64_i32 v[178:179], s[0:1], v192, s91, v[162:163]
	v_mad_i64_i32 v[162:163], s[0:1], v190, s91, v[162:163]
	v_add_co_u32_e32 v212, vcc, s41, v180
	global_load_dwordx2 v[166:167], v[164:165], off
	s_nop 0
	global_load_dwordx2 v[164:165], v[178:179], off
	s_nop 0
	global_load_dwordx2 v[162:163], v[162:163], off
	v_addc_co_u32_e32 v213, vcc, 0, v181, vcc
	global_load_dwordx4 v[178:181], v[180:181], off
	s_nop 0
	global_load_dwordx4 v[212:215], v[212:213], off offset:3072
	v_mad_i64_i32 v[152:153], s[0:1], v210, s91, v[158:159]
	v_cmp_eq_u32_e32 vcc, 1, v169
	v_cmp_eq_u32_e64 s[0:1], 0, v169
	v_cmp_gt_u32_e64 s[8:9], 2, v169
	v_mov_b64_e32 v[148:149], s[36:37]
	v_lshl_add_u64 v[182:183], v[152:153], 0, v[160:161]
	v_readlane_b32 s64, v239, 10
	v_readlane_b32 s65, v239, 11
	v_readlane_b32 s64, v240, 23
	v_readlane_b32 s65, v240, 24
	v_readlane_b32 s56, v239, 2
	v_readlane_b32 s57, v239, 3
	v_readlane_b32 s58, v239, 4
	v_readlane_b32 s59, v239, 5
	v_readlane_b32 s60, v239, 6
	v_readlane_b32 s61, v239, 7
	v_readlane_b32 s62, v239, 8
	v_readlane_b32 s63, v239, 9
	s_waitcnt vmcnt(11)
	v_mov_b32_dpp v185, v154 row_ror:1 row_mask:0xf bank_mask:0xf bound_ctrl:1
	v_mov_b32_dpp v187, v155 row_ror:1 row_mask:0xf bank_mask:0xf bound_ctrl:1
	v_mov_b32_dpp v189, v154 row_ror:2 row_mask:0xf bank_mask:0xf bound_ctrl:1
	v_mov_b32_dpp v185, v154 row_shr:1 row_mask:0xf bank_mask:0xf
	v_mov_b32_dpp v187, v155 row_shr:1 row_mask:0xf bank_mask:0xf
	v_mov_b32_dpp v189, v154 row_shr:2 row_mask:0xf bank_mask:0xf
	v_mov_b32_dpp v191, v155 row_ror:2 row_mask:0xf bank_mask:0xf bound_ctrl:1
	v_lshlrev_b32_e32 v226, 16, v154
	v_and_b32_e32 v227, 0xffff0000, v154
	v_mov_b32_dpp v191, v155 row_shr:2 row_mask:0xf bank_mask:0xf
	s_waitcnt vmcnt(9)
; __device__ __forceinline__ unsigned cvt_pk_bf16(float lo, float hi) { unsigned r; asm volatile("v_cvt_pk_bf16_f32 %0, %1, %2" : "=v"(r) : "v"(lo), "v"(hi)); return r; }
;     static __device__ __forceinline__ void unpk4(const u32x2 w, float (&o)[4]) { o[0] = bf_lo(w.x); o[1] = bf_hi(w.x); o[2] = bf_lo(w.y); o[3] = bf_hi(w.y); }
;     template <int N> static __device__ __forceinline__ u32x2 dpp_prev(const u32x2 pv, const u32x2 cur) { u32x2 r; r.x = dpp_prev1<N>(pv.x, cur.x); r.y = dpp_prev1<N>(pv.y, cur.y); return r; }
;     static __device__ __forceinline__ void finish(const float (&g0)[4], const float (&g1)[4], const float (&g2)[4], const float (&w0)[4], const float (&w1)[4], const float (&w2)[4], const float (&bb)[4],
;                                                   const f32x4 v, float rs, bf16_t* dst) {
;         float h[4];
; #pragma unroll
;         for (int j = 0; j < 4; j += 2) {
;             const f32x2 gc = (f32x2){bb[j] + w0[j] * g2[j] + w1[j] * g1[j] + w2[j] * g0[j], bb[j + 1] + w0[j + 1] * g2[j + 1] + w1[j + 1] * g1[j + 1] + w2[j + 1] * g0[j + 1]};
;             const f32x2 ge = gelu_pk(gc); h[j] = ge.x * v[j] * rs; h[j + 1] = ge.y * v[j + 1] * rs; }
;         u32x2 w; w.x = cvt_pk_bf16(h[0], h[1]); w.y = cvt_pk_bf16(h[2], h[3]);
;         *(u32x2*)dst = w;
;     }
;     __device__ __forceinline__ void operator()(const f32x4 (&acc)[2][2][4][2], const Unit& u, int wr, int wc, int fr, int fq) const {
;     ...
;                 for (int m = mh; m < mh + 2; ++m) { const int row = row0 + m * 16; const u32x2 cur = gq[m];
;                     const u32x2 q1 = dpp_prev<1>(cur, cur), q2 = dpp_prev<2>(cur, cur);
;                     float g0[4], g1[4], g2[4]; unpk4(cur, g0); unpk4(q1, g1); unpk4(q2, g2);
; #pragma unroll
;                     for (int j = 0; j < 4; ++j) { const float x1 = c1[m][j], x0 = c0[m][j];
;                         if (i < 1) g1[j] = x1;
;                         if (i < 2) g2[j] = (i == 1) ? x1 : x0; }
;                     finish(g0, g1, g2, w0, w1, w2, bb, acc[0][bj][m][hv], rs8[0][m], H + (size_t)row * 2816 + col); }
	v_cndmask_b32_e32 v154, v170, v174, vcc
	v_cndmask_b32_e32 v193, v171, v175, vcc
	v_cndmask_b32_e32 v195, v172, v176, vcc
	v_cndmask_b32_e32 v211, v173, v177, vcc
	v_lshlrev_b32_e32 v170, 16, v185
	v_and_b32_e32 v171, 0xffff0000, v185
	v_lshlrev_b32_e32 v172, 16, v187
	v_and_b32_e32 v173, 0xffff0000, v187
	v_lshlrev_b32_e32 v185, 16, v189
	v_and_b32_e32 v187, 0xffff0000, v189
	v_cndmask_b32_e64 v173, v173, v177, s[0:1]
	v_cndmask_b32_e64 v172, v172, v176, s[0:1]
	v_cndmask_b32_e64 v177, v187, v193, s[8:9]
	v_cndmask_b32_e64 v176, v185, v154, s[8:9]
	v_lshlrev_b32_e32 v189, 16, v191
	v_and_b32_e32 v191, 0xffff0000, v191
	v_cndmask_b32_e64 v171, v171, v175, s[0:1]
	v_cndmask_b32_e64 v170, v170, v174, s[0:1]
	s_waitcnt vmcnt(7)
	v_pk_fma_f32 v[176:177], v[140:141], v[176:177], v[144:145]
	v_cndmask_b32_e64 v175, v191, v211, s[8:9]
	v_cndmask_b32_e64 v174, v189, v195, s[8:9]
	s_waitcnt vmcnt(6)
	v_pk_fma_f32 v[170:171], v[136:137], v[170:171], v[176:177]
	v_pk_fma_f32 v[174:175], v[142:143], v[174:175], v[146:147]
	s_waitcnt vmcnt(5)
	v_pk_fma_f32 v[170:171], v[132:133], v[226:227], v[170:171]
	v_pk_fma_f32 v[172:173], v[138:139], v[172:173], v[174:175]
	v_pk_mul_f32 v[174:175], v[170:171], s[30:31] op_sel_hi:[1,0]
	v_pk_mul_f32 v[170:171], v[170:171], 0.5 op_sel_hi:[1,0]
	v_med3_f32 v174, v174, s47, v225
	v_med3_f32 v175, v175, s47, v225
	v_pk_mul_f32 v[176:177], v[174:175], v[174:175]
	s_nop 0
	v_pk_fma_f32 v[226:227], v[176:177], s[34:35], v[148:149] op_sel_hi:[1,0,0] neg_lo:[1,0,0] neg_hi:[1,0,0]
	s_nop 0
	v_pk_fma_f32 v[226:227], v[176:177], v[226:227], s[38:39] op_sel_hi:[1,1,0]
	s_nop 0
	v_pk_fma_f32 v[226:227], v[176:177], v[226:227], s[40:41] op_sel_hi:[1,1,0]
	s_nop 0
	v_pk_fma_f32 v[226:227], v[176:177], v[226:227], s[42:43] op_sel_hi:[1,1,0]
	s_nop 0
	v_pk_fma_f32 v[226:227], v[176:177], v[226:227], s[44:45] op_sel_hi:[1,1,0]
	s_nop 0
	v_pk_fma_f32 v[226:227], v[176:177], v[226:227], s[46:47] op_sel_hi:[1,1,0]
	s_nop 0
	v_pk_fma_f32 v[176:177], v[176:177], v[226:227], s[48:49] op_sel_hi:[1,1,0]
	s_nop 0
	v_pk_mul_f32 v[174:175], v[174:175], v[176:177]
	s_nop 0
	v_pk_fma_f32 v[170:171], v[170:171], v[174:175], v[170:171]
	s_nop 0
	v_mul_f32_e32 v154, v128, v170
	v_mul_f32_e32 v169, v188, v154
	v_mul_f32_e32 v154, v129, v171
	v_mul_f32_e32 v176, v188, v154
	v_lshlrev_b32_e32 v154, 16, v155
	v_and_b32_e32 v155, 0xffff0000, v155
	v_pk_fma_f32 v[154:155], v[134:135], v[154:155], v[172:173]
	s_nop 0
	v_pk_mul_f32 v[170:171], v[154:155], s[30:31] op_sel_hi:[1,0]
	v_pk_mul_f32 v[154:155], v[154:155], 0.5 op_sel_hi:[1,0]
	v_med3_f32 v170, v170, s47, v225
	v_med3_f32 v171, v171, s47, v225
	v_pk_mul_f32 v[172:173], v[170:171], v[170:171]
	s_nop 0
	v_pk_fma_f32 v[174:175], v[172:173], s[34:35], v[148:149] op_sel_hi:[1,0,0] neg_lo:[1,0,0] neg_hi:[1,0,0]
	s_nop 0
	v_pk_fma_f32 v[174:175], v[172:173], v[174:175], s[38:39] op_sel_hi:[1,1,0]
	s_nop 0
	v_pk_fma_f32 v[174:175], v[172:173], v[174:175], s[40:41] op_sel_hi:[1,1,0]
	s_nop 0
	v_pk_fma_f32 v[174:175], v[172:173], v[174:175], s[42:43] op_sel_hi:[1,1,0]
	s_nop 0
	v_pk_fma_f32 v[174:175], v[172:173], v[174:175], s[44:45] op_sel_hi:[1,1,0]
	s_nop 0
	v_pk_fma_f32 v[174:175], v[172:173], v[174:175], s[46:47] op_sel_hi:[1,1,0]
	s_nop 0
	v_pk_fma_f32 v[172:173], v[172:173], v[174:175], s[48:49] op_sel_hi:[1,1,0]
	s_nop 0
	v_pk_mul_f32 v[170:171], v[170:171], v[172:173]
	s_nop 0
	v_pk_fma_f32 v[154:155], v[154:155], v[170:171], v[154:155]
	s_nop 0
	v_mul_f32_e32 v154, v130, v154
	v_mul_f32_e32 v170, v188, v154
	v_mul_f32_e32 v154, v131, v155
	v_mul_f32_e32 v155, v188, v154
	v_cvt_pk_bf16_f32 v154, v169, v176
	v_cvt_pk_bf16_f32 v155, v170, v155
	global_store_dwordx2 v[182:183], v[154:155], off nt
	s_waitcnt vmcnt(5)
	v_mov_b32_dpp v169, v166 row_ror:2 row_mask:0xf bank_mask:0xf bound_ctrl:1
	v_mov_b32_dpp v154, v166 row_ror:1 row_mask:0xf bank_mask:0xf bound_ctrl:1
	v_mov_b32_dpp v155, v167 row_ror:1 row_mask:0xf bank_mask:0xf bound_ctrl:1
	v_mov_b32_dpp v170, v167 row_ror:2 row_mask:0xf bank_mask:0xf bound_ctrl:1
	v_mov_b32_dpp v154, v166 row_shr:1 row_mask:0xf bank_mask:0xf
	v_mov_b32_dpp v155, v167 row_shr:1 row_mask:0xf bank_mask:0xf
	v_mov_b32_dpp v169, v166 row_shr:2 row_mask:0xf bank_mask:0xf
	v_mov_b32_dpp v170, v167 row_shr:2 row_mask:0xf bank_mask:0xf
	v_lshlrev_b32_e32 v172, 16, v154
	v_and_b32_e32 v154, 0xffff0000, v154
	v_lshlrev_b32_e32 v174, 16, v155
	v_and_b32_e32 v155, 0xffff0000, v155
	v_lshlrev_b32_e32 v176, 16, v169
	v_and_b32_e32 v169, 0xffff0000, v169
	v_lshlrev_b32_e32 v177, 16, v170
	v_and_b32_e32 v175, 0xffff0000, v170
	s_waitcnt vmcnt(1)
; __device__ __forceinline__ unsigned cvt_pk_bf16(float lo, float hi) { unsigned r; asm volatile("v_cvt_pk_bf16_f32 %0, %1, %2" : "=v"(r) : "v"(lo), "v"(hi)); return r; }
;     static __device__ __forceinline__ void unpk4(const u32x2 w, float (&o)[4]) { o[0] = bf_lo(w.x); o[1] = bf_hi(w.x); o[2] = bf_lo(w.y); o[3] = bf_hi(w.y); }
;     template <int N> static __device__ __forceinline__ u32x2 dpp_prev(const u32x2 pv, const u32x2 cur) { u32x2 r; r.x = dpp_prev1<N>(pv.x, cur.x); r.y = dpp_prev1<N>(pv.y, cur.y); return r; }
;     static __device__ __forceinline__ void finish(const float (&g0)[4], const float (&g1)[4], const float (&g2)[4], const float (&w0)[4], const float (&w1)[4], const float (&w2)[4], const float (&bb)[4],
;                                                   const f32x4 v, float rs, bf16_t* dst) {
;         float h[4];
; #pragma unroll
;         for (int j = 0; j < 4; j += 2) {
;             const f32x2 gc = (f32x2){bb[j] + w0[j] * g2[j] + w1[j] * g1[j] + w2[j] * g0[j], bb[j + 1] + w0[j + 1] * g2[j + 1] + w1[j + 1] * g1[j + 1] + w2[j + 1] * g0[j + 1]};
;             const f32x2 ge = gelu_pk(gc); h[j] = ge.x * v[j] * rs; h[j + 1] = ge.y * v[j + 1] * rs; }
;         u32x2 w; w.x = cvt_pk_bf16(h[0], h[1]); w.y = cvt_pk_bf16(h[2], h[3]);
;         *(u32x2*)dst = w;
;     }
;     __device__ __forceinline__ void operator()(const f32x4 (&acc)[2][2][4][2], const Unit& u, int wr, int wc, int fr, int fq) const {
;     ...
; #pragma unroll
;                 for (int m = mh; m < mh + 2; ++m) { const int row = row0 + m * 16; const float* cx = ctx + (size_t)((row - 32768) >> 3) * 2 * 2816 + col;
;                     c0[m] = *(const f32x4*)cx; c1[m] = *(const f32x4*)(cx + 2816); }
; #pragma unroll
;                 for (int m = mh; m < mh + 2; ++m) { const int row = row0 + m * 16; const u32x2 cur = gq[m];
;                     const u32x2 q1 = dpp_prev<1>(cur, cur), q2 = dpp_prev<2>(cur, cur);
;                     float g0[4], g1[4], g2[4]; unpk4(cur, g0); unpk4(q1, g1); unpk4(q2, g2);
; #pragma unroll
;                     for (int j = 0; j < 4; ++j) { const float x1 = c1[m][j], x0 = c0[m][j];
;                         if (i < 1) g1[j] = x1;
;                         if (i < 2) g2[j] = (i == 1) ? x1 : x0; }
;                     finish(g0, g1, g2, w0, w1, w2, bb, acc[0][bj][m][hv], rs8[0][m], H + (size_t)row * 2816 + col); }
	v_cndmask_b32_e64 v171, v154, v213, s[0:1]
	v_cndmask_b32_e64 v170, v172, v212, s[0:1]
	v_cndmask_b32_e64 v173, v155, v215, s[0:1]
	v_cndmask_b32_e64 v172, v174, v214, s[0:1]
	v_cndmask_b32_e32 v154, v178, v212, vcc
	v_cndmask_b32_e32 v155, v179, v213, vcc
	v_cndmask_b32_e32 v174, v180, v214, vcc
	v_cndmask_b32_e64 v174, v177, v174, s[8:9]
	v_cndmask_b32_e64 v177, v169, v155, s[8:9]
	v_cndmask_b32_e64 v176, v176, v154, s[8:9]
	v_cndmask_b32_e32 v178, v181, v215, vcc
	v_pk_fma_f32 v[176:177], v[140:141], v[176:177], v[144:145]
	v_cndmask_b32_e64 v175, v175, v178, s[8:9]
	v_lshlrev_b32_e32 v180, 16, v166
	v_and_b32_e32 v181, 0xffff0000, v166
	v_pk_fma_f32 v[170:171], v[136:137], v[170:171], v[176:177]
	v_pk_fma_f32 v[174:175], v[142:143], v[174:175], v[146:147]
	v_pk_fma_f32 v[170:171], v[132:133], v[180:181], v[170:171]
	v_pk_fma_f32 v[172:173], v[138:139], v[172:173], v[174:175]
	v_pk_mul_f32 v[174:175], v[170:171], s[30:31] op_sel_hi:[1,0]
	v_pk_mul_f32 v[170:171], v[170:171], 0.5 op_sel_hi:[1,0]
	v_med3_f32 v174, v174, s47, v225
	v_med3_f32 v175, v175, s47, v225
	v_pk_mul_f32 v[176:177], v[174:175], v[174:175]
	v_mad_i64_i32 v[154:155], s[10:11], v194, s91, v[158:159]
	v_pk_fma_f32 v[180:181], v[176:177], s[34:35], v[148:149] op_sel_hi:[1,0,0] neg_lo:[1,0,0] neg_hi:[1,0,0]
	v_lshl_add_u64 v[178:179], v[154:155], 0, v[160:161]
	v_pk_fma_f32 v[180:181], v[176:177], v[180:181], s[38:39] op_sel_hi:[1,1,0]
	s_nop 0
	v_pk_fma_f32 v[180:181], v[176:177], v[180:181], s[40:41] op_sel_hi:[1,1,0]
	s_nop 0
	v_pk_fma_f32 v[180:181], v[176:177], v[180:181], s[42:43] op_sel_hi:[1,1,0]
	s_nop 0
	v_pk_fma_f32 v[180:181], v[176:177], v[180:181], s[44:45] op_sel_hi:[1,1,0]
	s_nop 0
	v_pk_fma_f32 v[180:181], v[176:177], v[180:181], s[46:47] op_sel_hi:[1,1,0]
	s_nop 0
	v_pk_fma_f32 v[176:177], v[176:177], v[180:181], s[48:49] op_sel_hi:[1,1,0]
	s_nop 0
	v_pk_mul_f32 v[174:175], v[174:175], v[176:177]
	s_nop 0
	v_pk_fma_f32 v[170:171], v[170:171], v[174:175], v[170:171]
	s_nop 0
	v_mul_f32_e32 v166, v120, v170
	v_mul_f32_e32 v169, v186, v166
	v_mul_f32_e32 v166, v121, v171
	v_mul_f32_e32 v176, v186, v166
	v_lshlrev_b32_e32 v166, 16, v167
	v_and_b32_e32 v167, 0xffff0000, v167
	v_pk_fma_f32 v[166:167], v[134:135], v[166:167], v[172:173]
	s_nop 0
	v_pk_mul_f32 v[170:171], v[166:167], s[30:31] op_sel_hi:[1,0]
	v_pk_mul_f32 v[166:167], v[166:167], 0.5 op_sel_hi:[1,0]
	v_med3_f32 v170, v170, s47, v225
	v_med3_f32 v171, v171, s47, v225
	v_pk_mul_f32 v[172:173], v[170:171], v[170:171]
	s_nop 0
	v_pk_fma_f32 v[174:175], v[172:173], s[34:35], v[148:149] op_sel_hi:[1,0,0] neg_lo:[1,0,0] neg_hi:[1,0,0]
	s_nop 0
	v_pk_fma_f32 v[174:175], v[172:173], v[174:175], s[38:39] op_sel_hi:[1,1,0]
	s_nop 0
	v_pk_fma_f32 v[174:175], v[172:173], v[174:175], s[40:41] op_sel_hi:[1,1,0]
	s_nop 0
	v_pk_fma_f32 v[174:175], v[172:173], v[174:175], s[42:43] op_sel_hi:[1,1,0]
	s_nop 0
	v_pk_fma_f32 v[174:175], v[172:173], v[174:175], s[44:45] op_sel_hi:[1,1,0]
	s_nop 0
	v_pk_fma_f32 v[174:175], v[172:173], v[174:175], s[46:47] op_sel_hi:[1,1,0]
	s_nop 0
	v_pk_fma_f32 v[172:173], v[172:173], v[174:175], s[48:49] op_sel_hi:[1,1,0]
	s_nop 0
	v_pk_mul_f32 v[170:171], v[170:171], v[172:173]
	s_nop 0
	v_pk_fma_f32 v[166:167], v[166:167], v[170:171], v[166:167]
	s_nop 0
	v_mul_f32_e32 v166, v122, v166
	v_mul_f32_e32 v170, v186, v166
	v_mul_f32_e32 v166, v123, v167
	v_mul_f32_e32 v167, v186, v166
	v_cvt_pk_bf16_f32 v166, v169, v176
	v_cvt_pk_bf16_f32 v167, v170, v167
	global_store_dwordx2 v[178:179], v[166:167], off nt
	v_add_u32_e32 v166, 0xffff8020, v210
	v_ashrrev_i32_e32 v166, 3, v166
	v_mad_i64_i32 v[174:175], s[10:11], v166, s45, v[156:157]
	v_add_co_u32_e64 v170, s[10:11], s41, v174
	v_add_u32_e32 v167, 0xffff8030, v210
	s_nop 0
	v_addc_co_u32_e64 v171, s[10:11], 0, v175, s[10:11]
	global_load_dwordx4 v[170:173], v[170:171], off offset:3072
	s_nop 0
	global_load_dwordx4 v[174:177], v[174:175], off
	v_ashrrev_i32_e32 v167, 3, v167
	v_mad_i64_i32 v[156:157], s[10:11], v167, s45, v[156:157]
	v_add_co_u32_e64 v182, s[10:11], s41, v156
	v_mov_b32_dpp v169, v164 row_ror:2 row_mask:0xf bank_mask:0xf bound_ctrl:1
	s_nop 0
	v_addc_co_u32_e64 v183, s[10:11], 0, v157, s[10:11]
	global_load_dwordx4 v[178:181], v[156:157], off
	global_load_dwordx4 v[212:215], v[182:183], off offset:3072
	v_mov_b32_dpp v156, v164 row_ror:1 row_mask:0xf bank_mask:0xf bound_ctrl:1
	v_mov_b32_dpp v157, v165 row_ror:1 row_mask:0xf bank_mask:0xf bound_ctrl:1
	v_mov_b32_dpp v169, v164 row_shr:2 row_mask:0xf bank_mask:0xf
	v_mov_b32_dpp v156, v164 row_shr:1 row_mask:0xf bank_mask:0xf
	v_mov_b32_dpp v157, v165 row_shr:1 row_mask:0xf bank_mask:0xf
	v_mov_b32_dpp v182, v165 row_ror:2 row_mask:0xf bank_mask:0xf bound_ctrl:1
	v_lshlrev_b32_e32 v185, 16, v156
	v_and_b32_e32 v156, 0xffff0000, v156
	v_lshlrev_b32_e32 v187, 16, v157
	v_and_b32_e32 v157, 0xffff0000, v157
	v_mov_b32_dpp v182, v165 row_shr:2 row_mask:0xf bank_mask:0xf
	v_lshlrev_b32_e32 v189, 16, v169
	v_and_b32_e32 v169, 0xffff0000, v169
	v_lshlrev_b32_e32 v191, 16, v182
	v_and_b32_e32 v193, 0xffff0000, v182
	s_waitcnt vmcnt(3)
	v_cndmask_b32_e64 v183, v156, v171, s[0:1]
	v_cndmask_b32_e64 v227, v157, v173, s[0:1]
	s_waitcnt vmcnt(2)
; __device__ __forceinline__ unsigned cvt_pk_bf16(float lo, float hi) { unsigned r; asm volatile("v_cvt_pk_bf16_f32 %0, %1, %2" : "=v"(r) : "v"(lo), "v"(hi)); return r; }
;     static __device__ __forceinline__ void unpk4(const u32x2 w, float (&o)[4]) { o[0] = bf_lo(w.x); o[1] = bf_hi(w.x); o[2] = bf_lo(w.y); o[3] = bf_hi(w.y); }
;     template <int N> static __device__ __forceinline__ u32x2 dpp_prev(const u32x2 pv, const u32x2 cur) { u32x2 r; r.x = dpp_prev1<N>(pv.x, cur.x); r.y = dpp_prev1<N>(pv.y, cur.y); return r; }
;     static __device__ __forceinline__ void finish(const float (&g0)[4], const float (&g1)[4], const float (&g2)[4], const float (&w0)[4], const float (&w1)[4], const float (&w2)[4], const float (&bb)[4],
;                                                   const f32x4 v, float rs, bf16_t* dst) {
;         float h[4];
; #pragma unroll
;         for (int j = 0; j < 4; j += 2) {
;             const f32x2 gc = (f32x2){bb[j] + w0[j] * g2[j] + w1[j] * g1[j] + w2[j] * g0[j], bb[j + 1] + w0[j + 1] * g2[j + 1] + w1[j + 1] * g1[j + 1] + w2[j + 1] * g0[j + 1]};
;             const f32x2 ge = gelu_pk(gc); h[j] = ge.x * v[j] * rs; h[j + 1] = ge.y * v[j + 1] * rs; }
;         u32x2 w; w.x = cvt_pk_bf16(h[0], h[1]); w.y = cvt_pk_bf16(h[2], h[3]);
;         *(u32x2*)dst = w;
;     __device__ __forceinline__ void operator()(const f32x4 (&acc)[2][2][4][2], const Unit& u, int wr, int wc, int fr, int fq) const {
;     ...
;                 for (int m = mh; m < mh + 2; ++m) { const int row = row0 + m * 16; const u32x2 cur = gq[m];
;                     const u32x2 q1 = dpp_prev<1>(cur, cur), q2 = dpp_prev<2>(cur, cur);
;                     float g0[4], g1[4], g2[4]; unpk4(cur, g0); unpk4(q1, g1); unpk4(q2, g2);
; #pragma unroll
;                     for (int j = 0; j < 4; ++j) { const float x1 = c1[m][j], x0 = c0[m][j];
;                         if (i < 1) g1[j] = x1;
;                         if (i < 2) g2[j] = (i == 1) ? x1 : x0; }
;                     finish(g0, g1, g2, w0, w1, w2, bb, acc[0][bj][m][hv], rs8[0][m], H + (size_t)row * 2816 + col); }
	v_cndmask_b32_e32 v156, v174, v170, vcc
	v_cndmask_b32_e32 v157, v175, v171, vcc
	v_cndmask_b32_e64 v182, v185, v170, s[0:1]
	v_cndmask_b32_e64 v226, v187, v172, s[0:1]
	v_cndmask_b32_e32 v170, v176, v172, vcc
	v_cndmask_b32_e32 v171, v177, v173, vcc
	v_cndmask_b32_e64 v173, v169, v157, s[8:9]
	v_cndmask_b32_e64 v172, v189, v156, s[8:9]
	v_pk_fma_f32 v[172:173], v[140:141], v[172:173], v[144:145]
	v_lshlrev_b32_e32 v176, 16, v164
	v_and_b32_e32 v177, 0xffff0000, v164
	v_pk_fma_f32 v[172:173], v[136:137], v[182:183], v[172:173]
	v_cndmask_b32_e64 v171, v193, v171, s[8:9]
	v_pk_fma_f32 v[172:173], v[132:133], v[176:177], v[172:173]
	v_cndmask_b32_e64 v170, v191, v170, s[8:9]
	v_pk_mul_f32 v[176:177], v[172:173], s[30:31] op_sel_hi:[1,0]
	v_pk_fma_f32 v[170:171], v[142:143], v[170:171], v[146:147]
	v_med3_f32 v176, v176, s47, v225
	v_med3_f32 v177, v177, s47, v225
	v_pk_mul_f32 v[182:183], v[176:177], v[176:177]
	v_pk_fma_f32 v[170:171], v[138:139], v[226:227], v[170:171]
	v_pk_fma_f32 v[226:227], v[182:183], s[34:35], v[148:149] op_sel_hi:[1,0,0] neg_lo:[1,0,0] neg_hi:[1,0,0]
	v_pk_mul_f32 v[172:173], v[172:173], 0.5 op_sel_hi:[1,0]
	v_pk_fma_f32 v[226:227], v[182:183], v[226:227], s[38:39] op_sel_hi:[1,1,0]
	v_mad_i64_i32 v[156:157], s[10:11], v192, s91, v[158:159]
	v_pk_fma_f32 v[226:227], v[182:183], v[226:227], s[40:41] op_sel_hi:[1,1,0]
	v_lshl_add_u64 v[174:175], v[156:157], 0, v[160:161]
	v_pk_fma_f32 v[226:227], v[182:183], v[226:227], s[42:43] op_sel_hi:[1,1,0]
	v_mad_i64_i32 v[158:159], s[10:11], v190, s91, v[158:159]
	v_pk_fma_f32 v[226:227], v[182:183], v[226:227], s[44:45] op_sel_hi:[1,1,0]
	v_lshl_add_u64 v[160:161], v[158:159], 0, v[160:161]
	v_pk_fma_f32 v[226:227], v[182:183], v[226:227], s[46:47] op_sel_hi:[1,1,0]
	s_nop 0
	v_pk_fma_f32 v[182:183], v[182:183], v[226:227], s[48:49] op_sel_hi:[1,1,0]
	s_nop 0
	v_pk_mul_f32 v[176:177], v[176:177], v[182:183]
	s_nop 0
	v_pk_fma_f32 v[172:173], v[172:173], v[176:177], v[172:173]
	s_nop 0
	v_mul_f32_e32 v164, v112, v172
	v_mul_f32_e32 v169, v184, v164
	v_mul_f32_e32 v164, v113, v173
	v_mul_f32_e32 v182, v184, v164
	v_lshlrev_b32_e32 v164, 16, v165
	v_and_b32_e32 v165, 0xffff0000, v165
	v_pk_fma_f32 v[164:165], v[134:135], v[164:165], v[170:171]
	s_nop 0
	v_pk_mul_f32 v[170:171], v[164:165], s[30:31] op_sel_hi:[1,0]
	v_pk_mul_f32 v[164:165], v[164:165], 0.5 op_sel_hi:[1,0]
	v_med3_f32 v170, v170, s47, v225
	v_med3_f32 v171, v171, s47, v225
	v_pk_mul_f32 v[172:173], v[170:171], v[170:171]
	s_nop 0
	v_pk_fma_f32 v[176:177], v[172:173], s[34:35], v[148:149] op_sel_hi:[1,0,0] neg_lo:[1,0,0] neg_hi:[1,0,0]
	s_nop 0
	v_pk_fma_f32 v[176:177], v[172:173], v[176:177], s[38:39] op_sel_hi:[1,1,0]
	s_nop 0
	v_pk_fma_f32 v[176:177], v[172:173], v[176:177], s[40:41] op_sel_hi:[1,1,0]
	s_nop 0
	v_pk_fma_f32 v[176:177], v[172:173], v[176:177], s[42:43] op_sel_hi:[1,1,0]
	s_nop 0
	v_pk_fma_f32 v[176:177], v[172:173], v[176:177], s[44:45] op_sel_hi:[1,1,0]
	s_nop 0
	v_pk_fma_f32 v[176:177], v[172:173], v[176:177], s[46:47] op_sel_hi:[1,1,0]
	s_nop 0
	v_pk_fma_f32 v[172:173], v[172:173], v[176:177], s[48:49] op_sel_hi:[1,1,0]
	s_waitcnt vmcnt(0)
	v_cndmask_b32_e32 v177, v178, v212, vcc
	v_pk_mul_f32 v[170:171], v[170:171], v[172:173]
	v_cndmask_b32_e32 v178, v179, v213, vcc
	v_pk_fma_f32 v[164:165], v[164:165], v[170:171], v[164:165]
	s_nop 0
	v_mul_f32_e32 v164, v114, v164
	v_mul_f32_e32 v170, v184, v164
	v_mul_f32_e32 v164, v115, v165
	v_mul_f32_e32 v165, v184, v164
	v_cvt_pk_bf16_f32 v164, v169, v182
	v_cvt_pk_bf16_f32 v165, v170, v165
	global_store_dwordx2 v[174:175], v[164:165], off nt
	v_mov_b32_dpp v169, v162 row_ror:2 row_mask:0xf bank_mask:0xf bound_ctrl:1
	v_mov_b32_dpp v165, v163 row_ror:1 row_mask:0xf bank_mask:0xf bound_ctrl:1
	v_mov_b32_dpp v170, v163 row_ror:2 row_mask:0xf bank_mask:0xf bound_ctrl:1
	v_mov_b32_dpp v164, v162 row_ror:1 row_mask:0xf bank_mask:0xf bound_ctrl:1
	v_mov_b32_dpp v165, v163 row_shr:1 row_mask:0xf bank_mask:0xf
	v_mov_b32_dpp v169, v162 row_shr:2 row_mask:0xf bank_mask:0xf
	v_mov_b32_dpp v170, v163 row_shr:2 row_mask:0xf bank_mask:0xf
	v_lshlrev_b32_e32 v172, 16, v165
	v_mov_b32_dpp v164, v162 row_shr:1 row_mask:0xf bank_mask:0xf
	v_lshlrev_b32_e32 v174, 16, v169
	v_and_b32_e32 v169, 0xffff0000, v169
	v_lshlrev_b32_e32 v175, 16, v170
	v_and_b32_e32 v176, 0xffff0000, v170
	v_cndmask_b32_e64 v170, v172, v214, s[0:1]
	v_cndmask_b32_e32 v172, v180, v214, vcc
	v_lshlrev_b32_e32 v171, 16, v164
	v_and_b32_e32 v164, 0xffff0000, v164
	v_and_b32_e32 v173, 0xffff0000, v165
	v_cndmask_b32_e64 v172, v175, v172, s[8:9]
	v_cndmask_b32_e64 v175, v169, v178, s[8:9]
	v_cndmask_b32_e64 v174, v174, v177, s[8:9]
	v_cndmask_b32_e64 v165, v164, v213, s[0:1]
	v_cndmask_b32_e64 v164, v171, v212, s[0:1]
	v_cndmask_b32_e64 v171, v173, v215, s[0:1]
	v_cndmask_b32_e32 v173, v181, v215, vcc
	v_pk_fma_f32 v[140:141], v[140:141], v[174:175], v[144:145]
	v_cndmask_b32_e64 v173, v176, v173, s[8:9]
	v_lshlrev_b32_e32 v176, 16, v162
	v_and_b32_e32 v177, 0xffff0000, v162
	v_pk_fma_f32 v[136:137], v[136:137], v[164:165], v[140:141]
	v_pk_fma_f32 v[142:143], v[142:143], v[172:173], v[146:147]
	v_pk_fma_f32 v[132:133], v[132:133], v[176:177], v[136:137]
	v_pk_fma_f32 v[138:139], v[138:139], v[170:171], v[142:143]
	v_pk_mul_f32 v[136:137], v[132:133], s[30:31] op_sel_hi:[1,0]
	v_pk_mul_f32 v[132:133], v[132:133], 0.5 op_sel_hi:[1,0]
	v_med3_f32 v136, v136, s47, v225
	v_med3_f32 v137, v137, s47, v225
	v_pk_mul_f32 v[140:141], v[136:137], v[136:137]
	s_nop 0
	v_pk_fma_f32 v[142:143], v[140:141], s[34:35], v[148:149] op_sel_hi:[1,0,0] neg_lo:[1,0,0] neg_hi:[1,0,0]
	s_nop 0
; __device__ __forceinline__ unsigned cvt_pk_bf16(float lo, float hi) { unsigned r; asm volatile("v_cvt_pk_bf16_f32 %0, %1, %2" : "=v"(r) : "v"(lo), "v"(hi)); return r; }
;     static __device__ __forceinline__ void finish(const float (&g0)[4], const float (&g1)[4], const float (&g2)[4], const float (&w0)[4], const float (&w1)[4], const float (&w2)[4], const float (&bb)[4],
;                                                   const f32x4 v, float rs, bf16_t* dst) {
;         float h[4];
; #pragma unroll
;         for (int j = 0; j < 4; j += 2) {
;             const f32x2 gc = (f32x2){bb[j] + w0[j] * g2[j] + w1[j] * g1[j] + w2[j] * g0[j], bb[j + 1] + w0[j + 1] * g2[j + 1] + w1[j + 1] * g1[j + 1] + w2[j + 1] * g0[j + 1]};
;             const f32x2 ge = gelu_pk(gc); h[j] = ge.x * v[j] * rs; h[j + 1] = ge.y * v[j + 1] * rs; }
;         u32x2 w; w.x = cvt_pk_bf16(h[0], h[1]); w.y = cvt_pk_bf16(h[2], h[3]);
;         *(u32x2*)dst = w;
;     __device__ __forceinline__ void operator()(const f32x4 (&acc)[2][2][4][2], const Unit& u, int wr, int wc, int fr, int fq) const {
;     ...
;             const int col = u.pn * BM + bj * HALF + wc * 32 + 8 * fq + 4 * hv;
;             float w0[4], w1[4], w2[4], bb[4];
;             ld4f(cw + col, w0); ld4f(cw + 2816 + col, w1); ld4f(cw + 2 * 2816 + col, w2); ld4f(cb + col, bb);
;             {
;                 const int i = fr & 7;
;                 u32x2 gq[4];
; #pragma unroll
;                 for (int m = 0; m < 4; ++m) { const int row = row0 + m * 16; gq[m] = *(const u32x2*)(G + (size_t)row * 2816 + col); }
; #pragma unroll
;                 for (int mh = 0; mh < 4; mh += 2) {
;                 f32x4 c0[4], c1[4];
; #pragma unroll
;                 for (int m = mh; m < mh + 2; ++m) { const int row = row0 + m * 16; const float* cx = ctx + (size_t)((row - 32768) >> 3) * 2 * 2816 + col;
;                     c0[m] = *(const f32x4*)cx; c1[m] = *(const f32x4*)(cx + 2816); }
	v_pk_fma_f32 v[142:143], v[140:141], v[142:143], s[38:39] op_sel_hi:[1,1,0]
	s_nop 0
	v_pk_fma_f32 v[142:143], v[140:141], v[142:143], s[40:41] op_sel_hi:[1,1,0]
	s_nop 0
	v_pk_fma_f32 v[142:143], v[140:141], v[142:143], s[42:43] op_sel_hi:[1,1,0]
	s_nop 0
	v_pk_fma_f32 v[142:143], v[140:141], v[142:143], s[44:45] op_sel_hi:[1,1,0]
	s_nop 0
	v_pk_fma_f32 v[142:143], v[140:141], v[142:143], s[46:47] op_sel_hi:[1,1,0]
	s_nop 0
	v_pk_fma_f32 v[140:141], v[140:141], v[142:143], s[48:49] op_sel_hi:[1,1,0]
	s_nop 0
	v_pk_mul_f32 v[136:137], v[136:137], v[140:141]
	s_nop 0
	v_pk_fma_f32 v[132:133], v[132:133], v[136:137], v[132:133]
	s_nop 0
	v_mul_f32_e32 v132, v104, v132
	v_mul_f32_e32 v140, v2, v132
	v_mul_f32_e32 v132, v105, v133
	v_mul_f32_e32 v141, v2, v132
	v_lshlrev_b32_e32 v132, 16, v163
	v_and_b32_e32 v133, 0xffff0000, v163
	v_pk_fma_f32 v[132:133], v[134:135], v[132:133], v[138:139]
	s_nop 0
	v_pk_mul_f32 v[134:135], v[132:133], s[30:31] op_sel_hi:[1,0]
	v_pk_mul_f32 v[132:133], v[132:133], 0.5 op_sel_hi:[1,0]
	v_med3_f32 v134, v134, s47, v225
	v_med3_f32 v135, v135, s47, v225
	v_pk_mul_f32 v[136:137], v[134:135], v[134:135]
	s_nop 0
	v_pk_fma_f32 v[138:139], v[136:137], s[34:35], v[148:149] op_sel_hi:[1,0,0] neg_lo:[1,0,0] neg_hi:[1,0,0]
	s_nop 0
	v_pk_fma_f32 v[138:139], v[136:137], v[138:139], s[38:39] op_sel_hi:[1,1,0]
	s_nop 0
	v_pk_fma_f32 v[138:139], v[136:137], v[138:139], s[40:41] op_sel_hi:[1,1,0]
	s_nop 0
	v_pk_fma_f32 v[138:139], v[136:137], v[138:139], s[42:43] op_sel_hi:[1,1,0]
	s_nop 0
	v_pk_fma_f32 v[138:139], v[136:137], v[138:139], s[44:45] op_sel_hi:[1,1,0]
	s_nop 0
	v_pk_fma_f32 v[138:139], v[136:137], v[138:139], s[46:47] op_sel_hi:[1,1,0]
	s_nop 0
	v_pk_fma_f32 v[136:137], v[136:137], v[138:139], s[48:49] op_sel_hi:[1,1,0]
	s_nop 0
	v_pk_mul_f32 v[134:135], v[134:135], v[136:137]
	s_nop 0
	v_pk_fma_f32 v[132:133], v[132:133], v[134:135], v[132:133]
	s_nop 0
	v_mul_f32_e32 v132, v106, v132
	v_mul_f32_e32 v134, v2, v132
	v_mul_f32_e32 v132, v107, v133
	v_mul_f32_e32 v133, v2, v132
	v_cvt_pk_bf16_f32 v132, v140, v141
	v_cvt_pk_bf16_f32 v133, v134, v133
	global_store_dwordx2 v[160:161], v[132:133], off nt
	v_add_u32_e32 v132, 4, v150
	v_ashrrev_i32_e32 v133, 31, v132
	v_lshlrev_b64 v[162:163], 1, v[132:133]
	v_lshl_add_u64 v[160:161], s[68:69], 0, v[162:163]
	v_lshlrev_b64 v[132:133], 2, v[132:133]
	v_mad_i64_i32 v[134:135], s[10:11], v210, s91, v[160:161]
	v_lshl_add_u64 v[226:227], s[82:83], 0, v[132:133]
	global_load_dwordx2 v[182:183], v[134:135], off
	v_mad_i64_i32 v[134:135], s[10:11], v151, s45, v[226:227]
	v_add_co_u32_e64 v136, s[10:11], s41, v134
	s_waitcnt vmcnt(0)
	v_mov_b32_dpp v169, v182 row_ror:1 row_mask:0xf bank_mask:0xf bound_ctrl:1
	v_addc_co_u32_e64 v137, s[10:11], 0, v135, s[10:11]
	global_load_dwordx4 v[170:173], v[136:137], off offset:3072
	global_load_dwordx4 v[174:177], v[134:135], off
	v_lshl_add_u64 v[134:135], s[66:67], 0, v[132:133]
	global_load_dwordx4 v[140:143], v[134:135], off
	v_lshl_add_u64 v[134:135], s[88:89], 0, v[132:133]
	global_load_dwordx4 v[144:147], v[134:135], off
	v_lshl_add_u64 v[134:135], s[52:53], 0, v[132:133]
	global_load_dwordx4 v[136:139], v[134:135], off
	v_lshl_add_u64 v[132:133], s[54:55], 0, v[132:133]
	global_load_dwordx4 v[132:135], v[132:133], off
	v_mad_i64_i32 v[164:165], s[10:11], v194, s91, v[160:161]
	v_mad_i64_i32 v[178:179], s[10:11], v192, s91, v[160:161]
	v_mad_i64_i32 v[160:161], s[10:11], v190, s91, v[160:161]
	global_load_dwordx2 v[228:229], v[164:165], off
	s_nop 0
	global_load_dwordx2 v[164:165], v[178:179], off
	s_nop 0
	global_load_dwordx2 v[160:161], v[160:161], off
	v_mad_i64_i32 v[178:179], s[10:11], v168, s45, v[226:227]
	v_add_co_u32_e64 v212, s[10:11], s41, v178
	v_mov_b32_dpp v169, v182 row_shr:1 row_mask:0xf bank_mask:0xf
	s_nop 0
	v_addc_co_u32_e64 v213, s[10:11], 0, v179, s[10:11]
	global_load_dwordx4 v[178:181], v[178:179], off
	s_nop 0
	global_load_dwordx4 v[212:215], v[212:213], off offset:3072
	v_mov_b32_dpp v185, v183 row_ror:1 row_mask:0xf bank_mask:0xf bound_ctrl:1
	v_mov_b32_dpp v187, v182 row_ror:2 row_mask:0xf bank_mask:0xf bound_ctrl:1
	v_lshlrev_b32_e32 v191, 16, v169
	v_mov_b32_dpp v185, v183 row_shr:1 row_mask:0xf bank_mask:0xf
	v_mov_b32_dpp v187, v182 row_shr:2 row_mask:0xf bank_mask:0xf
	v_and_b32_e32 v169, 0xffff0000, v169
	v_lshlrev_b32_e32 v193, 16, v185
	v_and_b32_e32 v185, 0xffff0000, v185
	v_lshlrev_b32_e32 v195, 16, v187
	v_and_b32_e32 v187, 0xffff0000, v187
	v_mov_b32_dpp v189, v183 row_ror:2 row_mask:0xf bank_mask:0xf bound_ctrl:1
	s_waitcnt vmcnt(10)
	v_cndmask_b32_e64 v231, v169, v171, s[0:1]
	s_waitcnt vmcnt(9)
	v_cndmask_b32_e32 v169, v174, v170, vcc
	v_cndmask_b32_e32 v174, v175, v171, vcc
	v_cndmask_b32_e64 v230, v191, v170, s[0:1]
	v_cndmask_b32_e64 v233, v185, v173, s[0:1]
	v_cndmask_b32_e64 v232, v193, v172, s[0:1]
	v_cndmask_b32_e32 v170, v176, v172, vcc
	v_cndmask_b32_e32 v171, v177, v173, vcc
	v_cndmask_b32_e64 v173, v187, v174, s[8:9]
	v_cndmask_b32_e64 v172, v195, v169, s[8:9]
	s_waitcnt vmcnt(7)
	v_pk_fma_f32 v[172:173], v[140:141], v[172:173], v[144:145]
	v_lshlrev_b32_e32 v176, 16, v182
	v_and_b32_e32 v177, 0xffff0000, v182
	s_waitcnt vmcnt(6)
	v_pk_fma_f32 v[172:173], v[136:137], v[230:231], v[172:173]
	v_mov_b32_dpp v189, v183 row_shr:2 row_mask:0xf bank_mask:0xf
	s_waitcnt vmcnt(5)
; __device__ __forceinline__ unsigned cvt_pk_bf16(float lo, float hi) { unsigned r; asm volatile("v_cvt_pk_bf16_f32 %0, %1, %2" : "=v"(r) : "v"(lo), "v"(hi)); return r; }
;     static __device__ __forceinline__ void unpk4(const u32x2 w, float (&o)[4]) { o[0] = bf_lo(w.x); o[1] = bf_hi(w.x); o[2] = bf_lo(w.y); o[3] = bf_hi(w.y); }
;     template <int N> static __device__ __forceinline__ u32x2 dpp_prev(const u32x2 pv, const u32x2 cur) { u32x2 r; r.x = dpp_prev1<N>(pv.x, cur.x); r.y = dpp_prev1<N>(pv.y, cur.y); return r; }
;     static __device__ __forceinline__ void finish(const float (&g0)[4], const float (&g1)[4], const float (&g2)[4], const float (&w0)[4], const float (&w1)[4], const float (&w2)[4], const float (&bb)[4],
;                                                   const f32x4 v, float rs, bf16_t* dst) {
;         float h[4];
; #pragma unroll
;         for (int j = 0; j < 4; j += 2) {
;             const f32x2 gc = (f32x2){bb[j] + w0[j] * g2[j] + w1[j] * g1[j] + w2[j] * g0[j], bb[j + 1] + w0[j + 1] * g2[j + 1] + w1[j + 1] * g1[j + 1] + w2[j + 1] * g0[j + 1]};
;             const f32x2 ge = gelu_pk(gc); h[j] = ge.x * v[j] * rs; h[j + 1] = ge.y * v[j + 1] * rs; }
;         u32x2 w; w.x = cvt_pk_bf16(h[0], h[1]); w.y = cvt_pk_bf16(h[2], h[3]);
;         *(u32x2*)dst = w;
;     __device__ __forceinline__ void operator()(const f32x4 (&acc)[2][2][4][2], const Unit& u, int wr, int wc, int fr, int fq) const {
;     ...
;                 for (int m = mh; m < mh + 2; ++m) { const int row = row0 + m * 16; const u32x2 cur = gq[m];
;                     const u32x2 q1 = dpp_prev<1>(cur, cur), q2 = dpp_prev<2>(cur, cur);
;                     float g0[4], g1[4], g2[4]; unpk4(cur, g0); unpk4(q1, g1); unpk4(q2, g2);
; #pragma unroll
;                     for (int j = 0; j < 4; ++j) { const float x1 = c1[m][j], x0 = c0[m][j];
;                         if (i < 1) g1[j] = x1;
;                         if (i < 2) g2[j] = (i == 1) ? x1 : x0; }
;                     finish(g0, g1, g2, w0, w1, w2, bb, acc[0][bj][m][hv], rs8[0][m], H + (size_t)row * 2816 + col); }
	v_pk_fma_f32 v[172:173], v[132:133], v[176:177], v[172:173]
	v_lshlrev_b32_e32 v211, 16, v189
	v_and_b32_e32 v189, 0xffff0000, v189
	v_pk_mul_f32 v[176:177], v[172:173], s[30:31] op_sel_hi:[1,0]
	v_cndmask_b32_e64 v171, v189, v171, s[8:9]
	v_cndmask_b32_e64 v170, v211, v170, s[8:9]
	v_med3_f32 v176, v176, s47, v225
	v_med3_f32 v177, v177, s47, v225
	v_pk_fma_f32 v[170:171], v[142:143], v[170:171], v[146:147]
	v_pk_mul_f32 v[230:231], v[176:177], v[176:177]
	v_pk_fma_f32 v[170:171], v[138:139], v[232:233], v[170:171]
	v_pk_fma_f32 v[232:233], v[230:231], s[34:35], v[148:149] op_sel_hi:[1,0,0] neg_lo:[1,0,0] neg_hi:[1,0,0]
	v_pk_mul_f32 v[172:173], v[172:173], 0.5 op_sel_hi:[1,0]
	v_pk_fma_f32 v[232:233], v[230:231], v[232:233], s[38:39] op_sel_hi:[1,1,0]
	v_lshl_add_u64 v[174:175], v[152:153], 0, v[162:163]
	v_pk_fma_f32 v[232:233], v[230:231], v[232:233], s[40:41] op_sel_hi:[1,1,0]
	s_nop 0
	v_pk_fma_f32 v[232:233], v[230:231], v[232:233], s[42:43] op_sel_hi:[1,1,0]
	s_nop 0
	v_pk_fma_f32 v[232:233], v[230:231], v[232:233], s[44:45] op_sel_hi:[1,1,0]
	s_nop 0
	v_pk_fma_f32 v[232:233], v[230:231], v[232:233], s[46:47] op_sel_hi:[1,1,0]
	s_nop 0
	v_pk_fma_f32 v[230:231], v[230:231], v[232:233], s[48:49] op_sel_hi:[1,1,0]
	s_nop 0
	v_pk_mul_f32 v[176:177], v[176:177], v[230:231]
	s_nop 0
	v_pk_fma_f32 v[172:173], v[172:173], v[176:177], v[172:173]
	s_nop 0
	v_mul_f32_e32 v169, v124, v172
	v_mul_f32_e32 v172, v125, v173
	v_mul_f32_e32 v185, v188, v172
	v_lshlrev_b32_e32 v172, 16, v183
	v_and_b32_e32 v173, 0xffff0000, v183
	v_pk_fma_f32 v[170:171], v[134:135], v[172:173], v[170:171]
	v_mul_f32_e32 v169, v188, v169
	v_pk_mul_f32 v[172:173], v[170:171], s[30:31] op_sel_hi:[1,0]
	v_pk_mul_f32 v[170:171], v[170:171], 0.5 op_sel_hi:[1,0]
	v_med3_f32 v172, v172, s47, v225
	v_med3_f32 v173, v173, s47, v225
	v_pk_mul_f32 v[176:177], v[172:173], v[172:173]
	s_nop 0
	v_pk_fma_f32 v[182:183], v[176:177], s[34:35], v[148:149] op_sel_hi:[1,0,0] neg_lo:[1,0,0] neg_hi:[1,0,0]
	s_nop 0
	v_pk_fma_f32 v[182:183], v[176:177], v[182:183], s[38:39] op_sel_hi:[1,1,0]
	s_nop 0
	v_pk_fma_f32 v[182:183], v[176:177], v[182:183], s[40:41] op_sel_hi:[1,1,0]
	s_nop 0
	v_pk_fma_f32 v[182:183], v[176:177], v[182:183], s[42:43] op_sel_hi:[1,1,0]
	s_nop 0
	v_pk_fma_f32 v[182:183], v[176:177], v[182:183], s[44:45] op_sel_hi:[1,1,0]
	s_nop 0
	v_pk_fma_f32 v[182:183], v[176:177], v[182:183], s[46:47] op_sel_hi:[1,1,0]
	s_nop 0
	v_pk_fma_f32 v[176:177], v[176:177], v[182:183], s[48:49] op_sel_hi:[1,1,0]
	s_nop 0
	v_pk_mul_f32 v[172:173], v[172:173], v[176:177]
	s_nop 0
	v_pk_fma_f32 v[170:171], v[170:171], v[172:173], v[170:171]
	s_nop 0
	v_mul_f32_e32 v170, v126, v170
	v_mul_f32_e32 v172, v188, v170
	v_mul_f32_e32 v170, v127, v171
	v_mul_f32_e32 v171, v188, v170
	v_cvt_pk_bf16_f32 v170, v169, v185
	v_cvt_pk_bf16_f32 v171, v172, v171
	s_waitcnt vmcnt(4)
	v_mov_b32_dpp v169, v228 row_ror:1 row_mask:0xf bank_mask:0xf bound_ctrl:1
	global_store_dwordx2 v[174:175], v[170:171], off nt
	v_mov_b32_dpp v171, v228 row_ror:2 row_mask:0xf bank_mask:0xf bound_ctrl:1
	v_mov_b32_dpp v169, v228 row_shr:1 row_mask:0xf bank_mask:0xf
	v_mov_b32_dpp v170, v229 row_ror:1 row_mask:0xf bank_mask:0xf bound_ctrl:1
	v_mov_b32_dpp v171, v228 row_shr:2 row_mask:0xf bank_mask:0xf
	v_lshlrev_b32_e32 v173, 16, v169
	v_and_b32_e32 v169, 0xffff0000, v169
	v_mov_b32_dpp v170, v229 row_shr:1 row_mask:0xf bank_mask:0xf
	v_mov_b32_dpp v172, v229 row_ror:2 row_mask:0xf bank_mask:0xf bound_ctrl:1
	v_lshlrev_b32_e32 v176, 16, v171
	v_and_b32_e32 v177, 0xffff0000, v171
	s_waitcnt vmcnt(1)
	v_cndmask_b32_e64 v171, v169, v213, s[0:1]
	v_cndmask_b32_e32 v169, v178, v212, vcc
	v_cndmask_b32_e32 v178, v179, v213, vcc
	v_mov_b32_dpp v172, v229 row_shr:2 row_mask:0xf bank_mask:0xf
	v_lshlrev_b32_e32 v174, 16, v170
	v_and_b32_e32 v175, 0xffff0000, v170
	v_cndmask_b32_e64 v177, v177, v178, s[8:9]
	v_cndmask_b32_e64 v176, v176, v169, s[8:9]
	v_lshlrev_b32_e32 v182, 16, v172
	v_and_b32_e32 v183, 0xffff0000, v172
	v_cndmask_b32_e64 v170, v173, v212, s[0:1]
	v_cndmask_b32_e64 v173, v175, v215, s[0:1]
	v_cndmask_b32_e64 v172, v174, v214, s[0:1]
	v_cndmask_b32_e32 v174, v180, v214, vcc
	v_cndmask_b32_e32 v175, v181, v215, vcc
	v_pk_fma_f32 v[176:177], v[140:141], v[176:177], v[144:145]
	v_cndmask_b32_e64 v175, v183, v175, s[8:9]
	v_cndmask_b32_e64 v174, v182, v174, s[8:9]
	v_lshlrev_b32_e32 v180, 16, v228
	v_and_b32_e32 v181, 0xffff0000, v228
	v_pk_fma_f32 v[170:171], v[136:137], v[170:171], v[176:177]
	v_pk_fma_f32 v[174:175], v[142:143], v[174:175], v[146:147]
	v_pk_fma_f32 v[170:171], v[132:133], v[180:181], v[170:171]
	v_pk_fma_f32 v[172:173], v[138:139], v[172:173], v[174:175]
	v_pk_mul_f32 v[174:175], v[170:171], s[30:31] op_sel_hi:[1,0]
	v_pk_mul_f32 v[170:171], v[170:171], 0.5 op_sel_hi:[1,0]
	v_med3_f32 v174, v174, s47, v225
	v_med3_f32 v175, v175, s47, v225
	v_pk_mul_f32 v[176:177], v[174:175], v[174:175]
	v_lshl_add_u64 v[178:179], v[154:155], 0, v[162:163]
	v_pk_fma_f32 v[180:181], v[176:177], s[34:35], v[148:149] op_sel_hi:[1,0,0] neg_lo:[1,0,0] neg_hi:[1,0,0]
	v_mov_b32_dpp v185, v165 row_ror:2 row_mask:0xf bank_mask:0xf bound_ctrl:1
	v_pk_fma_f32 v[180:181], v[176:177], v[180:181], s[38:39] op_sel_hi:[1,1,0]
	s_nop 0
	v_pk_fma_f32 v[180:181], v[176:177], v[180:181], s[40:41] op_sel_hi:[1,1,0]
	v_mov_b32_dpp v185, v165 row_shr:2 row_mask:0xf bank_mask:0xf
	v_pk_fma_f32 v[180:181], v[176:177], v[180:181], s[42:43] op_sel_hi:[1,1,0]
	v_lshlrev_b32_e32 v211, 16, v185
	v_pk_fma_f32 v[180:181], v[176:177], v[180:181], s[44:45] op_sel_hi:[1,1,0]
	v_and_b32_e32 v185, 0xffff0000, v185
; __device__ __forceinline__ unsigned cvt_pk_bf16(float lo, float hi) { unsigned r; asm volatile("v_cvt_pk_bf16_f32 %0, %1, %2" : "=v"(r) : "v"(lo), "v"(hi)); return r; }
;     static __device__ __forceinline__ void unpk4(const u32x2 w, float (&o)[4]) { o[0] = bf_lo(w.x); o[1] = bf_hi(w.x); o[2] = bf_lo(w.y); o[3] = bf_hi(w.y); }
;     template <int N> static __device__ __forceinline__ u32x2 dpp_prev(const u32x2 pv, const u32x2 cur) { u32x2 r; r.x = dpp_prev1<N>(pv.x, cur.x); r.y = dpp_prev1<N>(pv.y, cur.y); return r; }
;     static __device__ __forceinline__ void finish(const float (&g0)[4], const float (&g1)[4], const float (&g2)[4], const float (&w0)[4], const float (&w1)[4], const float (&w2)[4], const float (&bb)[4],
;                                                   const f32x4 v, float rs, bf16_t* dst) {
;         float h[4];
; #pragma unroll
;         for (int j = 0; j < 4; j += 2) {
;             const f32x2 gc = (f32x2){bb[j] + w0[j] * g2[j] + w1[j] * g1[j] + w2[j] * g0[j], bb[j + 1] + w0[j + 1] * g2[j + 1] + w1[j + 1] * g1[j + 1] + w2[j + 1] * g0[j + 1]};
;             const f32x2 ge = gelu_pk(gc); h[j] = ge.x * v[j] * rs; h[j + 1] = ge.y * v[j + 1] * rs; }
;         u32x2 w; w.x = cvt_pk_bf16(h[0], h[1]); w.y = cvt_pk_bf16(h[2], h[3]);
;         *(u32x2*)dst = w;
;     __device__ __forceinline__ void operator()(const f32x4 (&acc)[2][2][4][2], const Unit& u, int wr, int wc, int fr, int fq) const {
;     ...
;                 for (int m = mh; m < mh + 2; ++m) { const int row = row0 + m * 16; const u32x2 cur = gq[m];
;                     const u32x2 q1 = dpp_prev<1>(cur, cur), q2 = dpp_prev<2>(cur, cur);
;                     float g0[4], g1[4], g2[4]; unpk4(cur, g0); unpk4(q1, g1); unpk4(q2, g2);
; #pragma unroll
;                     for (int j = 0; j < 4; ++j) { const float x1 = c1[m][j], x0 = c0[m][j];
;                         if (i < 1) g1[j] = x1;
;                         if (i < 2) g2[j] = (i == 1) ? x1 : x0; }
;                     finish(g0, g1, g2, w0, w1, w2, bb, acc[0][bj][m][hv], rs8[0][m], H + (size_t)row * 2816 + col); }
	v_pk_fma_f32 v[180:181], v[176:177], v[180:181], s[46:47] op_sel_hi:[1,1,0]
	s_nop 0
	v_pk_fma_f32 v[176:177], v[176:177], v[180:181], s[48:49] op_sel_hi:[1,1,0]
	s_nop 0
	v_pk_mul_f32 v[174:175], v[174:175], v[176:177]
	s_nop 0
	v_pk_fma_f32 v[170:171], v[170:171], v[174:175], v[170:171]
	s_nop 0
	v_mul_f32_e32 v169, v116, v170
	v_mul_f32_e32 v170, v117, v171
	v_mul_f32_e32 v180, v186, v170
	v_lshlrev_b32_e32 v170, 16, v229
	v_and_b32_e32 v171, 0xffff0000, v229
	v_pk_fma_f32 v[170:171], v[134:135], v[170:171], v[172:173]
	v_mul_f32_e32 v169, v186, v169
	v_pk_mul_f32 v[172:173], v[170:171], s[30:31] op_sel_hi:[1,0]
	v_pk_mul_f32 v[170:171], v[170:171], 0.5 op_sel_hi:[1,0]
	v_med3_f32 v172, v172, s47, v225
	v_med3_f32 v173, v173, s47, v225
	v_pk_mul_f32 v[174:175], v[172:173], v[172:173]
	s_nop 0
	v_pk_fma_f32 v[176:177], v[174:175], s[34:35], v[148:149] op_sel_hi:[1,0,0] neg_lo:[1,0,0] neg_hi:[1,0,0]
	s_nop 0
	v_pk_fma_f32 v[176:177], v[174:175], v[176:177], s[38:39] op_sel_hi:[1,1,0]
	s_nop 0
	v_pk_fma_f32 v[176:177], v[174:175], v[176:177], s[40:41] op_sel_hi:[1,1,0]
	s_nop 0
	v_pk_fma_f32 v[176:177], v[174:175], v[176:177], s[42:43] op_sel_hi:[1,1,0]
	s_nop 0
	v_pk_fma_f32 v[176:177], v[174:175], v[176:177], s[44:45] op_sel_hi:[1,1,0]
	s_nop 0
	v_pk_fma_f32 v[176:177], v[174:175], v[176:177], s[46:47] op_sel_hi:[1,1,0]
	s_nop 0
	v_pk_fma_f32 v[174:175], v[174:175], v[176:177], s[48:49] op_sel_hi:[1,1,0]
	s_nop 0
	v_pk_mul_f32 v[172:173], v[172:173], v[174:175]
	v_mad_i64_i32 v[174:175], s[10:11], v166, s45, v[226:227]
	v_pk_fma_f32 v[170:171], v[170:171], v[172:173], v[170:171]
	s_nop 0
	v_mul_f32_e32 v170, v118, v170
	v_mul_f32_e32 v172, v186, v170
	v_mul_f32_e32 v170, v119, v171
	v_mul_f32_e32 v171, v186, v170
	v_cvt_pk_bf16_f32 v170, v169, v180
	v_cvt_pk_bf16_f32 v171, v172, v171
	global_store_dwordx2 v[178:179], v[170:171], off nt
	v_add_co_u32_e64 v170, s[10:11], s41, v174
	v_mov_b32_dpp v169, v164 row_ror:1 row_mask:0xf bank_mask:0xf bound_ctrl:1
	s_nop 0
	v_addc_co_u32_e64 v171, s[10:11], 0, v175, s[10:11]
	global_load_dwordx4 v[170:173], v[170:171], off offset:3072
	s_nop 0
	global_load_dwordx4 v[174:177], v[174:175], off
	v_mad_i64_i32 v[178:179], s[10:11], v167, s45, v[226:227]
	v_add_co_u32_e64 v182, s[10:11], s41, v178
	v_mov_b32_dpp v169, v164 row_shr:1 row_mask:0xf bank_mask:0xf
	s_nop 0
	v_addc_co_u32_e64 v183, s[10:11], 0, v179, s[10:11]
	global_load_dwordx4 v[178:181], v[178:179], off
	s_nop 0
	global_load_dwordx4 v[212:215], v[182:183], off offset:3072
	v_mov_b32_dpp v182, v165 row_ror:1 row_mask:0xf bank_mask:0xf bound_ctrl:1
	v_mov_b32_dpp v183, v164 row_ror:2 row_mask:0xf bank_mask:0xf bound_ctrl:1
	v_lshlrev_b32_e32 v187, 16, v169
	v_mov_b32_dpp v182, v165 row_shr:1 row_mask:0xf bank_mask:0xf
	v_mov_b32_dpp v183, v164 row_shr:2 row_mask:0xf bank_mask:0xf
	v_and_b32_e32 v169, 0xffff0000, v169
	v_lshlrev_b32_e32 v189, 16, v182
	v_and_b32_e32 v191, 0xffff0000, v182
	v_lshlrev_b32_e32 v193, 16, v183
	v_and_b32_e32 v195, 0xffff0000, v183
	s_waitcnt vmcnt(3)
	v_cndmask_b32_e64 v183, v169, v171, s[0:1]
	s_waitcnt vmcnt(2)
	v_cndmask_b32_e32 v169, v174, v170, vcc
	v_cndmask_b32_e32 v174, v175, v171, vcc
	v_cndmask_b32_e64 v182, v187, v170, s[0:1]
	v_cndmask_b32_e64 v227, v191, v173, s[0:1]
	v_cndmask_b32_e64 v226, v189, v172, s[0:1]
	v_cndmask_b32_e32 v170, v176, v172, vcc
	v_cndmask_b32_e32 v171, v177, v173, vcc
	v_cndmask_b32_e64 v173, v195, v174, s[8:9]
	v_cndmask_b32_e64 v172, v193, v169, s[8:9]
	v_pk_fma_f32 v[172:173], v[140:141], v[172:173], v[144:145]
	v_lshlrev_b32_e32 v176, 16, v164
	v_and_b32_e32 v177, 0xffff0000, v164
	v_pk_fma_f32 v[172:173], v[136:137], v[182:183], v[172:173]
	v_cndmask_b32_e64 v171, v185, v171, s[8:9]
	v_pk_fma_f32 v[172:173], v[132:133], v[176:177], v[172:173]
	v_cndmask_b32_e64 v170, v211, v170, s[8:9]
	v_pk_mul_f32 v[176:177], v[172:173], s[30:31] op_sel_hi:[1,0]
	v_pk_fma_f32 v[170:171], v[142:143], v[170:171], v[146:147]
	v_med3_f32 v176, v176, s47, v225
	v_med3_f32 v177, v177, s47, v225
	v_pk_mul_f32 v[182:183], v[176:177], v[176:177]
	v_pk_fma_f32 v[170:171], v[138:139], v[226:227], v[170:171]
	v_pk_fma_f32 v[226:227], v[182:183], s[34:35], v[148:149] op_sel_hi:[1,0,0] neg_lo:[1,0,0] neg_hi:[1,0,0]
	v_pk_mul_f32 v[172:173], v[172:173], 0.5 op_sel_hi:[1,0]
	v_pk_fma_f32 v[226:227], v[182:183], v[226:227], s[38:39] op_sel_hi:[1,1,0]
	v_lshl_add_u64 v[174:175], v[156:157], 0, v[162:163]
	v_pk_fma_f32 v[226:227], v[182:183], v[226:227], s[40:41] op_sel_hi:[1,1,0]
	v_lshl_add_u64 v[162:163], v[158:159], 0, v[162:163]
	v_pk_fma_f32 v[226:227], v[182:183], v[226:227], s[42:43] op_sel_hi:[1,1,0]
	s_nop 0
	v_pk_fma_f32 v[226:227], v[182:183], v[226:227], s[44:45] op_sel_hi:[1,1,0]
	s_nop 0
	v_pk_fma_f32 v[226:227], v[182:183], v[226:227], s[46:47] op_sel_hi:[1,1,0]
	s_nop 0
	v_pk_fma_f32 v[182:183], v[182:183], v[226:227], s[48:49] op_sel_hi:[1,1,0]
	s_nop 0
	v_pk_mul_f32 v[176:177], v[176:177], v[182:183]
	s_nop 0
	v_pk_fma_f32 v[172:173], v[172:173], v[176:177], v[172:173]
	s_nop 0
	v_mul_f32_e32 v164, v108, v172
	v_mul_f32_e32 v169, v184, v164
	v_mul_f32_e32 v164, v109, v173
	v_mul_f32_e32 v182, v184, v164
	v_lshlrev_b32_e32 v164, 16, v165
	v_and_b32_e32 v165, 0xffff0000, v165
	v_pk_fma_f32 v[164:165], v[134:135], v[164:165], v[170:171]
	s_nop 0
	v_pk_mul_f32 v[170:171], v[164:165], s[30:31] op_sel_hi:[1,0]
	v_pk_mul_f32 v[164:165], v[164:165], 0.5 op_sel_hi:[1,0]
	v_med3_f32 v170, v170, s47, v225
	v_med3_f32 v171, v171, s47, v225
	v_pk_mul_f32 v[172:173], v[170:171], v[170:171]
	s_nop 0
	v_pk_fma_f32 v[176:177], v[172:173], s[34:35], v[148:149] op_sel_hi:[1,0,0] neg_lo:[1,0,0] neg_hi:[1,0,0]
	s_nop 0
	v_pk_fma_f32 v[176:177], v[172:173], v[176:177], s[38:39] op_sel_hi:[1,1,0]
	s_nop 0
	v_pk_fma_f32 v[176:177], v[172:173], v[176:177], s[40:41] op_sel_hi:[1,1,0]
	s_nop 0
	v_pk_fma_f32 v[176:177], v[172:173], v[176:177], s[42:43] op_sel_hi:[1,1,0]
	s_nop 0
	v_pk_fma_f32 v[176:177], v[172:173], v[176:177], s[44:45] op_sel_hi:[1,1,0]
	s_nop 0
	v_pk_fma_f32 v[176:177], v[172:173], v[176:177], s[46:47] op_sel_hi:[1,1,0]
	s_nop 0
	v_pk_fma_f32 v[172:173], v[172:173], v[176:177], s[48:49] op_sel_hi:[1,1,0]
	s_waitcnt vmcnt(0)
;     static __device__ __forceinline__ void finish(const float (&g0)[4], const float (&g1)[4], const float (&g2)[4], const float (&w0)[4], const float (&w1)[4], const float (&w2)[4], const float (&bb)[4],
;                                                   const f32x4 v, float rs, bf16_t* dst) {
;         float h[4];
; #pragma unroll
;         for (int j = 0; j < 4; j += 2) {
;             const f32x2 gc = (f32x2){bb[j] + w0[j] * g2[j] + w1[j] * g1[j] + w2[j] * g0[j], bb[j + 1] + w0[j + 1] * g2[j + 1] + w1[j + 1] * g1[j + 1] + w2[j + 1] * g0[j + 1]};
;             const f32x2 ge = gelu_pk(gc); h[j] = ge.x * v[j] * rs; h[j + 1] = ge.y * v[j + 1] * rs; }
;         u32x2 w; w.x = cvt_pk_bf16(h[0], h[1]); w.y = cvt_pk_bf16(h[2], h[3]);
;         *(u32x2*)dst = w;
;     __device__ __forceinline__ void operator()(const f32x4 (&acc)[2][2][4][2], const Unit& u, int wr, int wc, int fr, int fq) const {
;     ...
;             const int col = u.pn * BM + bj * HALF + wc * 32 + 8 * fq + 4 * hv;
;             float w0[4], w1[4], w2[4], bb[4];
;             ld4f(cw + col, w0); ld4f(cw + 2816 + col, w1); ld4f(cw + 2 * 2816 + col, w2); ld4f(cb + col, bb);
;             {
;                 const int i = fr & 7;
;                 u32x2 gq[4];
; #pragma unroll
;                 for (int m = 0; m < 4; ++m) { const int row = row0 + m * 16; gq[m] = *(const u32x2*)(G + (size_t)row * 2816 + col); }
; #pragma unroll
;                 for (int mh = 0; mh < 4; mh += 2) {
;                 f32x4 c0[4], c1[4];
; #pragma unroll
;                 for (int m = mh; m < mh + 2; ++m) { const int row = row0 + m * 16; const float* cx = ctx + (size_t)((row - 32768) >> 3) * 2 * 2816 + col;
;                     c0[m] = *(const f32x4*)cx; c1[m] = *(const f32x4*)(cx + 2816); }
;     ...
;                 for (int m = mh; m < mh + 2; ++m) { const int row = row0 + m * 16; const u32x2 cur = gq[m];
;                     const u32x2 q1 = dpp_prev<1>(cur, cur), q2 = dpp_prev<2>(cur, cur);
;                     float g0[4], g1[4], g2[4]; unpk4(cur, g0); unpk4(q1, g1); unpk4(q2, g2);
; #pragma unroll
;                     for (int j = 0; j < 4; ++j) { const float x1 = c1[m][j], x0 = c0[m][j];
;                         if (i < 1) g1[j] = x1;
;                         if (i < 2) g2[j] = (i == 1) ? x1 : x0; }
;                     finish(g0, g1, g2, w0, w1, w2, bb, acc[0][bj][m][hv], rs8[0][m], H + (size_t)row * 2816 + col); }
	v_cndmask_b32_e32 v177, v178, v212, vcc
	v_pk_mul_f32 v[170:171], v[170:171], v[172:173]
	v_cndmask_b32_e32 v178, v179, v213, vcc
	v_pk_fma_f32 v[164:165], v[164:165], v[170:171], v[164:165]
	s_nop 0
	v_mul_f32_e32 v164, v110, v164
	v_mul_f32_e32 v170, v184, v164
	v_mul_f32_e32 v164, v111, v165
	v_mul_f32_e32 v165, v184, v164
	v_cvt_pk_bf16_f32 v164, v169, v182
	v_cvt_pk_bf16_f32 v165, v170, v165
	global_store_dwordx2 v[174:175], v[164:165], off nt
	v_mov_b32_dpp v169, v160 row_ror:2 row_mask:0xf bank_mask:0xf bound_ctrl:1
	v_mov_b32_dpp v165, v161 row_ror:1 row_mask:0xf bank_mask:0xf bound_ctrl:1
	v_mov_b32_dpp v170, v161 row_ror:2 row_mask:0xf bank_mask:0xf bound_ctrl:1
	v_mov_b32_dpp v164, v160 row_ror:1 row_mask:0xf bank_mask:0xf bound_ctrl:1
	v_mov_b32_dpp v165, v161 row_shr:1 row_mask:0xf bank_mask:0xf
	v_mov_b32_dpp v169, v160 row_shr:2 row_mask:0xf bank_mask:0xf
	v_mov_b32_dpp v170, v161 row_shr:2 row_mask:0xf bank_mask:0xf
	v_lshlrev_b32_e32 v172, 16, v165
	v_mov_b32_dpp v164, v160 row_shr:1 row_mask:0xf bank_mask:0xf
	v_lshlrev_b32_e32 v174, 16, v169
	v_and_b32_e32 v169, 0xffff0000, v169
	v_lshlrev_b32_e32 v175, 16, v170
	v_and_b32_e32 v176, 0xffff0000, v170
	v_cndmask_b32_e64 v170, v172, v214, s[0:1]
	v_cndmask_b32_e32 v172, v180, v214, vcc
	v_lshlrev_b32_e32 v171, 16, v164
	v_and_b32_e32 v164, 0xffff0000, v164
	v_and_b32_e32 v173, 0xffff0000, v165
	v_cndmask_b32_e64 v172, v175, v172, s[8:9]
	v_cndmask_b32_e64 v175, v169, v178, s[8:9]
	v_cndmask_b32_e64 v174, v174, v177, s[8:9]
	v_cndmask_b32_e64 v165, v164, v213, s[0:1]
	v_cndmask_b32_e64 v164, v171, v212, s[0:1]
	v_cndmask_b32_e64 v171, v173, v215, s[0:1]
	v_cndmask_b32_e32 v173, v181, v215, vcc
	v_pk_fma_f32 v[140:141], v[140:141], v[174:175], v[144:145]
	v_cndmask_b32_e64 v173, v176, v173, s[8:9]
	v_lshlrev_b32_e32 v176, 16, v160
	v_and_b32_e32 v177, 0xffff0000, v160
	v_pk_fma_f32 v[136:137], v[136:137], v[164:165], v[140:141]
	v_pk_fma_f32 v[142:143], v[142:143], v[172:173], v[146:147]
	v_pk_fma_f32 v[132:133], v[132:133], v[176:177], v[136:137]
	v_pk_fma_f32 v[138:139], v[138:139], v[170:171], v[142:143]
	v_pk_mul_f32 v[136:137], v[132:133], s[30:31] op_sel_hi:[1,0]
	v_pk_mul_f32 v[132:133], v[132:133], 0.5 op_sel_hi:[1,0]
	v_med3_f32 v136, v136, s47, v225
	v_med3_f32 v137, v137, s47, v225
	v_pk_mul_f32 v[140:141], v[136:137], v[136:137]
	s_nop 0
	v_pk_fma_f32 v[142:143], v[140:141], s[34:35], v[148:149] op_sel_hi:[1,0,0] neg_lo:[1,0,0] neg_hi:[1,0,0]
	s_nop 0
	v_pk_fma_f32 v[142:143], v[140:141], v[142:143], s[38:39] op_sel_hi:[1,1,0]
	s_nop 0
	v_pk_fma_f32 v[142:143], v[140:141], v[142:143], s[40:41] op_sel_hi:[1,1,0]
	s_nop 0
	v_pk_fma_f32 v[142:143], v[140:141], v[142:143], s[42:43] op_sel_hi:[1,1,0]
	s_nop 0
	v_pk_fma_f32 v[142:143], v[140:141], v[142:143], s[44:45] op_sel_hi:[1,1,0]
	s_nop 0
	v_pk_fma_f32 v[142:143], v[140:141], v[142:143], s[46:47] op_sel_hi:[1,1,0]
	s_nop 0
	v_pk_fma_f32 v[140:141], v[140:141], v[142:143], s[48:49] op_sel_hi:[1,1,0]
	s_nop 0
	v_pk_mul_f32 v[136:137], v[136:137], v[140:141]
	s_nop 0
	v_pk_fma_f32 v[132:133], v[132:133], v[136:137], v[132:133]
	s_nop 0
	v_mul_f32_e32 v132, v100, v132
	v_mul_f32_e32 v140, v2, v132
	v_mul_f32_e32 v132, v101, v133
	v_mul_f32_e32 v141, v2, v132
	v_lshlrev_b32_e32 v132, 16, v161
	v_and_b32_e32 v133, 0xffff0000, v161
	v_pk_fma_f32 v[132:133], v[134:135], v[132:133], v[138:139]
	s_nop 0
	v_pk_mul_f32 v[134:135], v[132:133], s[30:31] op_sel_hi:[1,0]
	v_pk_mul_f32 v[132:133], v[132:133], 0.5 op_sel_hi:[1,0]
	v_med3_f32 v134, v134, s47, v225
	v_med3_f32 v135, v135, s47, v225
	v_pk_mul_f32 v[136:137], v[134:135], v[134:135]
	s_nop 0
	v_pk_fma_f32 v[138:139], v[136:137], s[34:35], v[148:149] op_sel_hi:[1,0,0] neg_lo:[1,0,0] neg_hi:[1,0,0]
	s_nop 0
	v_pk_fma_f32 v[138:139], v[136:137], v[138:139], s[38:39] op_sel_hi:[1,1,0]
	s_nop 0
	v_pk_fma_f32 v[138:139], v[136:137], v[138:139], s[40:41] op_sel_hi:[1,1,0]
	s_nop 0
	v_pk_fma_f32 v[138:139], v[136:137], v[138:139], s[42:43] op_sel_hi:[1,1,0]
	s_nop 0
	v_pk_fma_f32 v[138:139], v[136:137], v[138:139], s[44:45] op_sel_hi:[1,1,0]
	s_nop 0
	v_pk_fma_f32 v[138:139], v[136:137], v[138:139], s[46:47] op_sel_hi:[1,1,0]
	s_nop 0
	v_pk_fma_f32 v[136:137], v[136:137], v[138:139], s[48:49] op_sel_hi:[1,1,0]
	s_nop 0
	v_pk_mul_f32 v[134:135], v[134:135], v[136:137]
	s_nop 0
	v_pk_fma_f32 v[132:133], v[132:133], v[134:135], v[132:133]
	s_nop 0
	v_mul_f32_e32 v132, v102, v132
	v_mul_f32_e32 v134, v2, v132
	v_mul_f32_e32 v132, v103, v133
	v_mul_f32_e32 v133, v2, v132
	v_cvt_pk_bf16_f32 v132, v140, v141
	v_cvt_pk_bf16_f32 v133, v134, v133
	global_store_dwordx2 v[162:163], v[132:133], off nt
	v_add_u32_e32 v132, 0x80, v150
	v_ashrrev_i32_e32 v133, 31, v132
	v_lshlrev_b64 v[162:163], 1, v[132:133]
	v_lshl_add_u64 v[160:161], s[68:69], 0, v[162:163]
	v_lshlrev_b64 v[132:133], 2, v[132:133]
	v_mad_i64_i32 v[134:135], s[10:11], v210, s91, v[160:161]
	v_lshl_add_u64 v[226:227], s[82:83], 0, v[132:133]
	global_load_dwordx2 v[182:183], v[134:135], off
	v_mad_i64_i32 v[134:135], s[10:11], v151, s45, v[226:227]
	v_add_co_u32_e64 v136, s[10:11], s41, v134
	s_waitcnt vmcnt(0)
;     static __device__ __forceinline__ void unpk4(const u32x2 w, float (&o)[4]) { o[0] = bf_lo(w.x); o[1] = bf_hi(w.x); o[2] = bf_lo(w.y); o[3] = bf_hi(w.y); }
;     template <int N> static __device__ __forceinline__ u32x2 dpp_prev(const u32x2 pv, const u32x2 cur) { u32x2 r; r.x = dpp_prev1<N>(pv.x, cur.x); r.y = dpp_prev1<N>(pv.y, cur.y); return r; }
;     __device__ __forceinline__ void operator()(const f32x4 (&acc)[2][2][4][2], const Unit& u, int wr, int wc, int fr, int fq) const {
;     ...
;             const int col = u.pn * BM + bj * HALF + wc * 32 + 8 * fq + 4 * hv;
;             float w0[4], w1[4], w2[4], bb[4];
;             ld4f(cw + col, w0); ld4f(cw + 2816 + col, w1); ld4f(cw + 2 * 2816 + col, w2); ld4f(cb + col, bb);
;             {
;                 const int i = fr & 7;
;                 u32x2 gq[4];
; #pragma unroll
;                 for (int m = 0; m < 4; ++m) { const int row = row0 + m * 16; gq[m] = *(const u32x2*)(G + (size_t)row * 2816 + col); }
; #pragma unroll
;                 for (int mh = 0; mh < 4; mh += 2) {
;                 f32x4 c0[4], c1[4];
; #pragma unroll
;                 for (int m = mh; m < mh + 2; ++m) { const int row = row0 + m * 16; const float* cx = ctx + (size_t)((row - 32768) >> 3) * 2 * 2816 + col;
;                     c0[m] = *(const f32x4*)cx; c1[m] = *(const f32x4*)(cx + 2816); }
; #pragma unroll
;                 for (int m = mh; m < mh + 2; ++m) { const int row = row0 + m * 16; const u32x2 cur = gq[m];
;                     const u32x2 q1 = dpp_prev<1>(cur, cur), q2 = dpp_prev<2>(cur, cur);
;                     float g0[4], g1[4], g2[4]; unpk4(cur, g0); unpk4(q1, g1); unpk4(q2, g2);
; #pragma unroll
;                     for (int j = 0; j < 4; ++j) { const float x1 = c1[m][j], x0 = c0[m][j];
;                         if (i < 1) g1[j] = x1;
;                         if (i < 2) g2[j] = (i == 1) ? x1 : x0; }
;                     finish(g0, g1, g2, w0, w1, w2, bb, acc[0][bj][m][hv], rs8[0][m], H + (size_t)row * 2816 + col); }
	v_mov_b32_dpp v169, v182 row_ror:1 row_mask:0xf bank_mask:0xf bound_ctrl:1
	v_addc_co_u32_e64 v137, s[10:11], 0, v135, s[10:11]
	global_load_dwordx4 v[170:173], v[136:137], off offset:3072
	global_load_dwordx4 v[174:177], v[134:135], off
	v_lshl_add_u64 v[134:135], s[66:67], 0, v[132:133]
	global_load_dwordx4 v[140:143], v[134:135], off
	v_lshl_add_u64 v[134:135], s[88:89], 0, v[132:133]
	global_load_dwordx4 v[144:147], v[134:135], off
	v_lshl_add_u64 v[134:135], s[52:53], 0, v[132:133]
	global_load_dwordx4 v[136:139], v[134:135], off
	v_lshl_add_u64 v[132:133], s[54:55], 0, v[132:133]
	global_load_dwordx4 v[132:135], v[132:133], off
	v_mad_i64_i32 v[164:165], s[10:11], v194, s91, v[160:161]
	v_mad_i64_i32 v[178:179], s[10:11], v192, s91, v[160:161]
	v_mad_i64_i32 v[160:161], s[10:11], v190, s91, v[160:161]
	global_load_dwordx2 v[228:229], v[164:165], off
	s_nop 0
	global_load_dwordx2 v[164:165], v[178:179], off
	s_nop 0
	global_load_dwordx2 v[160:161], v[160:161], off
	v_mad_i64_i32 v[178:179], s[10:11], v168, s45, v[226:227]
	v_add_co_u32_e64 v212, s[10:11], s41, v178
	v_mov_b32_dpp v169, v182 row_shr:1 row_mask:0xf bank_mask:0xf
	s_nop 0
	v_addc_co_u32_e64 v213, s[10:11], 0, v179, s[10:11]
	global_load_dwordx4 v[178:181], v[178:179], off
	s_nop 0
	global_load_dwordx4 v[212:215], v[212:213], off offset:3072
	v_mov_b32_dpp v185, v183 row_ror:1 row_mask:0xf bank_mask:0xf bound_ctrl:1
	v_mov_b32_dpp v187, v182 row_ror:2 row_mask:0xf bank_mask:0xf bound_ctrl:1
	v_lshlrev_b32_e32 v191, 16, v169
	v_mov_b32_dpp v185, v183 row_shr:1 row_mask:0xf bank_mask:0xf
	v_mov_b32_dpp v187, v182 row_shr:2 row_mask:0xf bank_mask:0xf
	v_and_b32_e32 v169, 0xffff0000, v169
	v_lshlrev_b32_e32 v193, 16, v185
	v_and_b32_e32 v185, 0xffff0000, v185
	v_lshlrev_b32_e32 v195, 16, v187
	v_and_b32_e32 v187, 0xffff0000, v187
	v_mov_b32_dpp v189, v183 row_ror:2 row_mask:0xf bank_mask:0xf bound_ctrl:1
	s_waitcnt vmcnt(10)
	v_cndmask_b32_e64 v231, v169, v171, s[0:1]
	s_waitcnt vmcnt(9)
	v_cndmask_b32_e32 v169, v174, v170, vcc
	v_cndmask_b32_e32 v174, v175, v171, vcc
	v_cndmask_b32_e64 v230, v191, v170, s[0:1]
	v_cndmask_b32_e64 v233, v185, v173, s[0:1]
	v_cndmask_b32_e64 v232, v193, v172, s[0:1]
	v_cndmask_b32_e32 v170, v176, v172, vcc
	v_cndmask_b32_e32 v171, v177, v173, vcc
	v_cndmask_b32_e64 v173, v187, v174, s[8:9]
	v_cndmask_b32_e64 v172, v195, v169, s[8:9]
	s_waitcnt vmcnt(7)
	v_pk_fma_f32 v[172:173], v[140:141], v[172:173], v[144:145]
	v_lshlrev_b32_e32 v176, 16, v182
	v_and_b32_e32 v177, 0xffff0000, v182
	s_waitcnt vmcnt(6)
	v_pk_fma_f32 v[172:173], v[136:137], v[230:231], v[172:173]
	v_mov_b32_dpp v189, v183 row_shr:2 row_mask:0xf bank_mask:0xf
	s_waitcnt vmcnt(5)
	v_pk_fma_f32 v[172:173], v[132:133], v[176:177], v[172:173]
	v_lshlrev_b32_e32 v211, 16, v189
	v_and_b32_e32 v189, 0xffff0000, v189
	v_pk_mul_f32 v[176:177], v[172:173], s[30:31] op_sel_hi:[1,0]
	v_cndmask_b32_e64 v171, v189, v171, s[8:9]
	v_cndmask_b32_e64 v170, v211, v170, s[8:9]
	v_med3_f32 v176, v176, s47, v225
	v_med3_f32 v177, v177, s47, v225
	v_pk_fma_f32 v[170:171], v[142:143], v[170:171], v[146:147]
	v_pk_mul_f32 v[230:231], v[176:177], v[176:177]
	v_pk_fma_f32 v[170:171], v[138:139], v[232:233], v[170:171]
	v_pk_fma_f32 v[232:233], v[230:231], s[34:35], v[148:149] op_sel_hi:[1,0,0] neg_lo:[1,0,0] neg_hi:[1,0,0]
	v_pk_mul_f32 v[172:173], v[172:173], 0.5 op_sel_hi:[1,0]
	v_pk_fma_f32 v[232:233], v[230:231], v[232:233], s[38:39] op_sel_hi:[1,1,0]
	v_lshl_add_u64 v[174:175], v[152:153], 0, v[162:163]
	v_pk_fma_f32 v[232:233], v[230:231], v[232:233], s[40:41] op_sel_hi:[1,1,0]
	s_nop 0
	v_pk_fma_f32 v[232:233], v[230:231], v[232:233], s[42:43] op_sel_hi:[1,1,0]
	s_nop 0
	v_pk_fma_f32 v[232:233], v[230:231], v[232:233], s[44:45] op_sel_hi:[1,1,0]
	s_nop 0
	v_pk_fma_f32 v[232:233], v[230:231], v[232:233], s[46:47] op_sel_hi:[1,1,0]
	s_nop 0
	v_pk_fma_f32 v[230:231], v[230:231], v[232:233], s[48:49] op_sel_hi:[1,1,0]
	s_nop 0
	v_pk_mul_f32 v[176:177], v[176:177], v[230:231]
	s_nop 0
	v_pk_fma_f32 v[172:173], v[172:173], v[176:177], v[172:173]
	s_nop 0
	v_mul_f32_e32 v169, v68, v172
	v_mul_f32_e32 v172, v69, v173
	v_mul_f32_e32 v185, v188, v172
	v_lshlrev_b32_e32 v172, 16, v183
	v_and_b32_e32 v173, 0xffff0000, v183
	v_pk_fma_f32 v[170:171], v[134:135], v[172:173], v[170:171]
	v_mul_f32_e32 v169, v188, v169
	v_pk_mul_f32 v[172:173], v[170:171], s[30:31] op_sel_hi:[1,0]
	v_pk_mul_f32 v[170:171], v[170:171], 0.5 op_sel_hi:[1,0]
	v_med3_f32 v172, v172, s47, v225
	v_med3_f32 v173, v173, s47, v225
	v_pk_mul_f32 v[176:177], v[172:173], v[172:173]
	s_nop 0
	v_pk_fma_f32 v[182:183], v[176:177], s[34:35], v[148:149] op_sel_hi:[1,0,0] neg_lo:[1,0,0] neg_hi:[1,0,0]
	s_nop 0
	v_pk_fma_f32 v[182:183], v[176:177], v[182:183], s[38:39] op_sel_hi:[1,1,0]
	s_nop 0
	v_pk_fma_f32 v[182:183], v[176:177], v[182:183], s[40:41] op_sel_hi:[1,1,0]
	s_nop 0
	v_pk_fma_f32 v[182:183], v[176:177], v[182:183], s[42:43] op_sel_hi:[1,1,0]
	s_nop 0
	v_pk_fma_f32 v[182:183], v[176:177], v[182:183], s[44:45] op_sel_hi:[1,1,0]
	s_nop 0
	v_pk_fma_f32 v[182:183], v[176:177], v[182:183], s[46:47] op_sel_hi:[1,1,0]
	s_nop 0
	v_pk_fma_f32 v[176:177], v[176:177], v[182:183], s[48:49] op_sel_hi:[1,1,0]
	s_nop 0
	v_pk_mul_f32 v[172:173], v[172:173], v[176:177]
	s_nop 0
	v_pk_fma_f32 v[170:171], v[170:171], v[172:173], v[170:171]
	s_nop 0
	v_mul_f32_e32 v170, v70, v170
	v_mul_f32_e32 v172, v188, v170
	v_mul_f32_e32 v170, v71, v171
	v_mul_f32_e32 v171, v188, v170
	v_cvt_pk_bf16_f32 v170, v169, v185
	v_cvt_pk_bf16_f32 v171, v172, v171
	s_waitcnt vmcnt(4)
; __device__ __forceinline__ unsigned cvt_pk_bf16(float lo, float hi) { unsigned r; asm volatile("v_cvt_pk_bf16_f32 %0, %1, %2" : "=v"(r) : "v"(lo), "v"(hi)); return r; }
;     static __device__ __forceinline__ void unpk4(const u32x2 w, float (&o)[4]) { o[0] = bf_lo(w.x); o[1] = bf_hi(w.x); o[2] = bf_lo(w.y); o[3] = bf_hi(w.y); }
;     template <int N> static __device__ __forceinline__ u32x2 dpp_prev(const u32x2 pv, const u32x2 cur) { u32x2 r; r.x = dpp_prev1<N>(pv.x, cur.x); r.y = dpp_prev1<N>(pv.y, cur.y); return r; }
;     static __device__ __forceinline__ void finish(const float (&g0)[4], const float (&g1)[4], const float (&g2)[4], const float (&w0)[4], const float (&w1)[4], const float (&w2)[4], const float (&bb)[4],
;                                                   const f32x4 v, float rs, bf16_t* dst) {
;         float h[4];
; #pragma unroll
;         for (int j = 0; j < 4; j += 2) {
;             const f32x2 gc = (f32x2){bb[j] + w0[j] * g2[j] + w1[j] * g1[j] + w2[j] * g0[j], bb[j + 1] + w0[j + 1] * g2[j + 1] + w1[j + 1] * g1[j + 1] + w2[j + 1] * g0[j + 1]};
;             const f32x2 ge = gelu_pk(gc); h[j] = ge.x * v[j] * rs; h[j + 1] = ge.y * v[j + 1] * rs; }
;         u32x2 w; w.x = cvt_pk_bf16(h[0], h[1]); w.y = cvt_pk_bf16(h[2], h[3]);
;         *(u32x2*)dst = w;
;     __device__ __forceinline__ void operator()(const f32x4 (&acc)[2][2][4][2], const Unit& u, int wr, int wc, int fr, int fq) const {
;     ...
;                 for (int m = mh; m < mh + 2; ++m) { const int row = row0 + m * 16; const u32x2 cur = gq[m];
;                     const u32x2 q1 = dpp_prev<1>(cur, cur), q2 = dpp_prev<2>(cur, cur);
;                     float g0[4], g1[4], g2[4]; unpk4(cur, g0); unpk4(q1, g1); unpk4(q2, g2);
; #pragma unroll
;                     for (int j = 0; j < 4; ++j) { const float x1 = c1[m][j], x0 = c0[m][j];
;                         if (i < 1) g1[j] = x1;
;                         if (i < 2) g2[j] = (i == 1) ? x1 : x0; }
;                     finish(g0, g1, g2, w0, w1, w2, bb, acc[0][bj][m][hv], rs8[0][m], H + (size_t)row * 2816 + col); }
	v_mov_b32_dpp v169, v228 row_ror:1 row_mask:0xf bank_mask:0xf bound_ctrl:1
	global_store_dwordx2 v[174:175], v[170:171], off nt
	v_mov_b32_dpp v171, v228 row_ror:2 row_mask:0xf bank_mask:0xf bound_ctrl:1
	v_mov_b32_dpp v169, v228 row_shr:1 row_mask:0xf bank_mask:0xf
	v_mov_b32_dpp v170, v229 row_ror:1 row_mask:0xf bank_mask:0xf bound_ctrl:1
	v_mov_b32_dpp v171, v228 row_shr:2 row_mask:0xf bank_mask:0xf
	v_lshlrev_b32_e32 v173, 16, v169
	v_and_b32_e32 v169, 0xffff0000, v169
	v_mov_b32_dpp v170, v229 row_shr:1 row_mask:0xf bank_mask:0xf
	v_mov_b32_dpp v172, v229 row_ror:2 row_mask:0xf bank_mask:0xf bound_ctrl:1
	v_lshlrev_b32_e32 v176, 16, v171
	v_and_b32_e32 v177, 0xffff0000, v171
	s_waitcnt vmcnt(1)
	v_cndmask_b32_e64 v171, v169, v213, s[0:1]
	v_cndmask_b32_e32 v169, v178, v212, vcc
	v_cndmask_b32_e32 v178, v179, v213, vcc
	v_mov_b32_dpp v172, v229 row_shr:2 row_mask:0xf bank_mask:0xf
	v_lshlrev_b32_e32 v174, 16, v170
	v_and_b32_e32 v175, 0xffff0000, v170
	v_cndmask_b32_e64 v177, v177, v178, s[8:9]
	v_cndmask_b32_e64 v176, v176, v169, s[8:9]
	v_lshlrev_b32_e32 v182, 16, v172
	v_and_b32_e32 v183, 0xffff0000, v172
	v_cndmask_b32_e64 v170, v173, v212, s[0:1]
	v_cndmask_b32_e64 v173, v175, v215, s[0:1]
	v_cndmask_b32_e64 v172, v174, v214, s[0:1]
	v_cndmask_b32_e32 v174, v180, v214, vcc
	v_cndmask_b32_e32 v175, v181, v215, vcc
	v_pk_fma_f32 v[176:177], v[140:141], v[176:177], v[144:145]
	v_cndmask_b32_e64 v175, v183, v175, s[8:9]
	v_cndmask_b32_e64 v174, v182, v174, s[8:9]
	v_lshlrev_b32_e32 v180, 16, v228
	v_and_b32_e32 v181, 0xffff0000, v228
	v_pk_fma_f32 v[170:171], v[136:137], v[170:171], v[176:177]
	v_pk_fma_f32 v[174:175], v[142:143], v[174:175], v[146:147]
	v_pk_fma_f32 v[170:171], v[132:133], v[180:181], v[170:171]
	v_pk_fma_f32 v[172:173], v[138:139], v[172:173], v[174:175]
	v_pk_mul_f32 v[174:175], v[170:171], s[30:31] op_sel_hi:[1,0]
	v_pk_mul_f32 v[170:171], v[170:171], 0.5 op_sel_hi:[1,0]
	v_med3_f32 v174, v174, s47, v225
	v_med3_f32 v175, v175, s47, v225
	v_pk_mul_f32 v[176:177], v[174:175], v[174:175]
	v_lshl_add_u64 v[178:179], v[154:155], 0, v[162:163]
	v_pk_fma_f32 v[180:181], v[176:177], s[34:35], v[148:149] op_sel_hi:[1,0,0] neg_lo:[1,0,0] neg_hi:[1,0,0]
	v_mov_b32_dpp v185, v165 row_ror:2 row_mask:0xf bank_mask:0xf bound_ctrl:1
	v_pk_fma_f32 v[180:181], v[176:177], v[180:181], s[38:39] op_sel_hi:[1,1,0]
	s_nop 0
	v_pk_fma_f32 v[180:181], v[176:177], v[180:181], s[40:41] op_sel_hi:[1,1,0]
	v_mov_b32_dpp v185, v165 row_shr:2 row_mask:0xf bank_mask:0xf
	v_pk_fma_f32 v[180:181], v[176:177], v[180:181], s[42:43] op_sel_hi:[1,1,0]
	v_lshlrev_b32_e32 v211, 16, v185
	v_pk_fma_f32 v[180:181], v[176:177], v[180:181], s[44:45] op_sel_hi:[1,1,0]
	v_and_b32_e32 v185, 0xffff0000, v185
	v_pk_fma_f32 v[180:181], v[176:177], v[180:181], s[46:47] op_sel_hi:[1,1,0]
	s_nop 0
	v_pk_fma_f32 v[176:177], v[176:177], v[180:181], s[48:49] op_sel_hi:[1,1,0]
	s_nop 0
	v_pk_mul_f32 v[174:175], v[174:175], v[176:177]
	s_nop 0
	v_pk_fma_f32 v[170:171], v[170:171], v[174:175], v[170:171]
	s_nop 0
	v_mul_f32_e32 v169, v56, v170
	v_mul_f32_e32 v170, v57, v171
	v_mul_f32_e32 v180, v186, v170
	v_lshlrev_b32_e32 v170, 16, v229
	v_and_b32_e32 v171, 0xffff0000, v229
	v_pk_fma_f32 v[170:171], v[134:135], v[170:171], v[172:173]
	v_mul_f32_e32 v169, v186, v169
	v_pk_mul_f32 v[172:173], v[170:171], s[30:31] op_sel_hi:[1,0]
	v_pk_mul_f32 v[170:171], v[170:171], 0.5 op_sel_hi:[1,0]
	v_med3_f32 v172, v172, s47, v225
	v_med3_f32 v173, v173, s47, v225
	v_pk_mul_f32 v[174:175], v[172:173], v[172:173]
	s_nop 0
	v_pk_fma_f32 v[176:177], v[174:175], s[34:35], v[148:149] op_sel_hi:[1,0,0] neg_lo:[1,0,0] neg_hi:[1,0,0]
	s_nop 0
	v_pk_fma_f32 v[176:177], v[174:175], v[176:177], s[38:39] op_sel_hi:[1,1,0]
	s_nop 0
	v_pk_fma_f32 v[176:177], v[174:175], v[176:177], s[40:41] op_sel_hi:[1,1,0]
	s_nop 0
	v_pk_fma_f32 v[176:177], v[174:175], v[176:177], s[42:43] op_sel_hi:[1,1,0]
	s_nop 0
	v_pk_fma_f32 v[176:177], v[174:175], v[176:177], s[44:45] op_sel_hi:[1,1,0]
	s_nop 0
	v_pk_fma_f32 v[176:177], v[174:175], v[176:177], s[46:47] op_sel_hi:[1,1,0]
	s_nop 0
	v_pk_fma_f32 v[174:175], v[174:175], v[176:177], s[48:49] op_sel_hi:[1,1,0]
	s_nop 0
	v_pk_mul_f32 v[172:173], v[172:173], v[174:175]
	v_mad_i64_i32 v[174:175], s[10:11], v166, s45, v[226:227]
	v_pk_fma_f32 v[170:171], v[170:171], v[172:173], v[170:171]
	s_nop 0
	v_mul_f32_e32 v170, v58, v170
	v_mul_f32_e32 v172, v186, v170
	v_mul_f32_e32 v170, v59, v171
	v_mul_f32_e32 v171, v186, v170
	v_cvt_pk_bf16_f32 v170, v169, v180
	v_cvt_pk_bf16_f32 v171, v172, v171
	global_store_dwordx2 v[178:179], v[170:171], off nt
	v_add_co_u32_e64 v170, s[10:11], s41, v174
	v_mov_b32_dpp v169, v164 row_ror:1 row_mask:0xf bank_mask:0xf bound_ctrl:1
	s_nop 0
	v_addc_co_u32_e64 v171, s[10:11], 0, v175, s[10:11]
	global_load_dwordx4 v[170:173], v[170:171], off offset:3072
	s_nop 0
	global_load_dwordx4 v[174:177], v[174:175], off
	v_mad_i64_i32 v[178:179], s[10:11], v167, s45, v[226:227]
	v_add_co_u32_e64 v182, s[10:11], s41, v178
	v_mov_b32_dpp v169, v164 row_shr:1 row_mask:0xf bank_mask:0xf
	s_nop 0
	v_addc_co_u32_e64 v183, s[10:11], 0, v179, s[10:11]
	global_load_dwordx4 v[178:181], v[178:179], off
	s_nop 0
	global_load_dwordx4 v[212:215], v[182:183], off offset:3072
	v_mov_b32_dpp v182, v165 row_ror:1 row_mask:0xf bank_mask:0xf bound_ctrl:1
	v_mov_b32_dpp v183, v164 row_ror:2 row_mask:0xf bank_mask:0xf bound_ctrl:1
	v_lshlrev_b32_e32 v187, 16, v169
	v_mov_b32_dpp v182, v165 row_shr:1 row_mask:0xf bank_mask:0xf
	v_mov_b32_dpp v183, v164 row_shr:2 row_mask:0xf bank_mask:0xf
	v_and_b32_e32 v169, 0xffff0000, v169
	v_lshlrev_b32_e32 v189, 16, v182
	v_and_b32_e32 v191, 0xffff0000, v182
	v_lshlrev_b32_e32 v193, 16, v183
	v_and_b32_e32 v195, 0xffff0000, v183
	s_waitcnt vmcnt(3)
; __device__ __forceinline__ unsigned cvt_pk_bf16(float lo, float hi) { unsigned r; asm volatile("v_cvt_pk_bf16_f32 %0, %1, %2" : "=v"(r) : "v"(lo), "v"(hi)); return r; }
;     static __device__ __forceinline__ void unpk4(const u32x2 w, float (&o)[4]) { o[0] = bf_lo(w.x); o[1] = bf_hi(w.x); o[2] = bf_lo(w.y); o[3] = bf_hi(w.y); }
;     template <int N> static __device__ __forceinline__ u32x2 dpp_prev(const u32x2 pv, const u32x2 cur) { u32x2 r; r.x = dpp_prev1<N>(pv.x, cur.x); r.y = dpp_prev1<N>(pv.y, cur.y); return r; }
;     static __device__ __forceinline__ void finish(const float (&g0)[4], const float (&g1)[4], const float (&g2)[4], const float (&w0)[4], const float (&w1)[4], const float (&w2)[4], const float (&bb)[4],
;                                                   const f32x4 v, float rs, bf16_t* dst) {
;         float h[4];
; #pragma unroll
;         for (int j = 0; j < 4; j += 2) {
;             const f32x2 gc = (f32x2){bb[j] + w0[j] * g2[j] + w1[j] * g1[j] + w2[j] * g0[j], bb[j + 1] + w0[j + 1] * g2[j + 1] + w1[j + 1] * g1[j + 1] + w2[j + 1] * g0[j + 1]};
;             const f32x2 ge = gelu_pk(gc); h[j] = ge.x * v[j] * rs; h[j + 1] = ge.y * v[j + 1] * rs; }
;         u32x2 w; w.x = cvt_pk_bf16(h[0], h[1]); w.y = cvt_pk_bf16(h[2], h[3]);
;         *(u32x2*)dst = w;
;     __device__ __forceinline__ void operator()(const f32x4 (&acc)[2][2][4][2], const Unit& u, int wr, int wc, int fr, int fq) const {
;     ...
;                 for (int m = mh; m < mh + 2; ++m) { const int row = row0 + m * 16; const u32x2 cur = gq[m];
;                     const u32x2 q1 = dpp_prev<1>(cur, cur), q2 = dpp_prev<2>(cur, cur);
;                     float g0[4], g1[4], g2[4]; unpk4(cur, g0); unpk4(q1, g1); unpk4(q2, g2);
; #pragma unroll
;                     for (int j = 0; j < 4; ++j) { const float x1 = c1[m][j], x0 = c0[m][j];
;                         if (i < 1) g1[j] = x1;
;                         if (i < 2) g2[j] = (i == 1) ? x1 : x0; }
;                     finish(g0, g1, g2, w0, w1, w2, bb, acc[0][bj][m][hv], rs8[0][m], H + (size_t)row * 2816 + col); }
	v_cndmask_b32_e64 v183, v169, v171, s[0:1]
	s_waitcnt vmcnt(2)
	v_cndmask_b32_e32 v169, v174, v170, vcc
	v_cndmask_b32_e32 v174, v175, v171, vcc
	v_cndmask_b32_e64 v182, v187, v170, s[0:1]
	v_cndmask_b32_e64 v227, v191, v173, s[0:1]
	v_cndmask_b32_e64 v226, v189, v172, s[0:1]
	v_cndmask_b32_e32 v170, v176, v172, vcc
	v_cndmask_b32_e32 v171, v177, v173, vcc
	v_cndmask_b32_e64 v173, v195, v174, s[8:9]
	v_cndmask_b32_e64 v172, v193, v169, s[8:9]
	v_pk_fma_f32 v[172:173], v[140:141], v[172:173], v[144:145]
	v_lshlrev_b32_e32 v176, 16, v164
	v_and_b32_e32 v177, 0xffff0000, v164
	v_pk_fma_f32 v[172:173], v[136:137], v[182:183], v[172:173]
	v_cndmask_b32_e64 v171, v185, v171, s[8:9]
	v_pk_fma_f32 v[172:173], v[132:133], v[176:177], v[172:173]
	v_cndmask_b32_e64 v170, v211, v170, s[8:9]
	v_pk_mul_f32 v[176:177], v[172:173], s[30:31] op_sel_hi:[1,0]
	v_pk_fma_f32 v[170:171], v[142:143], v[170:171], v[146:147]
	v_med3_f32 v176, v176, s47, v225
	v_med3_f32 v177, v177, s47, v225
	v_pk_mul_f32 v[182:183], v[176:177], v[176:177]
	v_pk_fma_f32 v[170:171], v[138:139], v[226:227], v[170:171]
	v_pk_fma_f32 v[226:227], v[182:183], s[34:35], v[148:149] op_sel_hi:[1,0,0] neg_lo:[1,0,0] neg_hi:[1,0,0]
	v_pk_mul_f32 v[172:173], v[172:173], 0.5 op_sel_hi:[1,0]
	v_pk_fma_f32 v[226:227], v[182:183], v[226:227], s[38:39] op_sel_hi:[1,1,0]
	v_lshl_add_u64 v[174:175], v[156:157], 0, v[162:163]
	v_pk_fma_f32 v[226:227], v[182:183], v[226:227], s[40:41] op_sel_hi:[1,1,0]
	v_lshl_add_u64 v[162:163], v[158:159], 0, v[162:163]
	v_pk_fma_f32 v[226:227], v[182:183], v[226:227], s[42:43] op_sel_hi:[1,1,0]
	s_nop 0
	v_pk_fma_f32 v[226:227], v[182:183], v[226:227], s[44:45] op_sel_hi:[1,1,0]
	s_nop 0
	v_pk_fma_f32 v[226:227], v[182:183], v[226:227], s[46:47] op_sel_hi:[1,1,0]
	s_nop 0
	v_pk_fma_f32 v[182:183], v[182:183], v[226:227], s[48:49] op_sel_hi:[1,1,0]
	s_nop 0
	v_pk_mul_f32 v[176:177], v[176:177], v[182:183]
	s_nop 0
	v_pk_fma_f32 v[172:173], v[172:173], v[176:177], v[172:173]
	s_nop 0
	v_mul_f32_e32 v164, v48, v172
	v_mul_f32_e32 v169, v184, v164
	v_mul_f32_e32 v164, v49, v173
	v_mul_f32_e32 v182, v184, v164
	v_lshlrev_b32_e32 v164, 16, v165
	v_and_b32_e32 v165, 0xffff0000, v165
	v_pk_fma_f32 v[164:165], v[134:135], v[164:165], v[170:171]
	s_nop 0
	v_pk_mul_f32 v[170:171], v[164:165], s[30:31] op_sel_hi:[1,0]
	v_pk_mul_f32 v[164:165], v[164:165], 0.5 op_sel_hi:[1,0]
	v_med3_f32 v170, v170, s47, v225
	v_med3_f32 v171, v171, s47, v225
	v_pk_mul_f32 v[172:173], v[170:171], v[170:171]
	s_nop 0
	v_pk_fma_f32 v[176:177], v[172:173], s[34:35], v[148:149] op_sel_hi:[1,0,0] neg_lo:[1,0,0] neg_hi:[1,0,0]
	s_nop 0
	v_pk_fma_f32 v[176:177], v[172:173], v[176:177], s[38:39] op_sel_hi:[1,1,0]
	s_nop 0
	v_pk_fma_f32 v[176:177], v[172:173], v[176:177], s[40:41] op_sel_hi:[1,1,0]
	s_nop 0
	v_pk_fma_f32 v[176:177], v[172:173], v[176:177], s[42:43] op_sel_hi:[1,1,0]
	s_nop 0
	v_pk_fma_f32 v[176:177], v[172:173], v[176:177], s[44:45] op_sel_hi:[1,1,0]
	s_nop 0
	v_pk_fma_f32 v[176:177], v[172:173], v[176:177], s[46:47] op_sel_hi:[1,1,0]
	s_nop 0
	v_pk_fma_f32 v[172:173], v[172:173], v[176:177], s[48:49] op_sel_hi:[1,1,0]
	s_waitcnt vmcnt(0)
	v_cndmask_b32_e32 v177, v178, v212, vcc
	v_pk_mul_f32 v[170:171], v[170:171], v[172:173]
	v_cndmask_b32_e32 v178, v179, v213, vcc
	v_pk_fma_f32 v[164:165], v[164:165], v[170:171], v[164:165]
	s_nop 0
	v_mul_f32_e32 v164, v50, v164
	v_mul_f32_e32 v170, v184, v164
	v_mul_f32_e32 v164, v51, v165
	v_mul_f32_e32 v165, v184, v164
	v_cvt_pk_bf16_f32 v164, v169, v182
	v_cvt_pk_bf16_f32 v165, v170, v165
	global_store_dwordx2 v[174:175], v[164:165], off nt
	v_mov_b32_dpp v169, v160 row_ror:2 row_mask:0xf bank_mask:0xf bound_ctrl:1
	v_mov_b32_dpp v165, v161 row_ror:1 row_mask:0xf bank_mask:0xf bound_ctrl:1
	v_mov_b32_dpp v170, v161 row_ror:2 row_mask:0xf bank_mask:0xf bound_ctrl:1
	v_mov_b32_dpp v164, v160 row_ror:1 row_mask:0xf bank_mask:0xf bound_ctrl:1
	v_mov_b32_dpp v165, v161 row_shr:1 row_mask:0xf bank_mask:0xf
	v_mov_b32_dpp v169, v160 row_shr:2 row_mask:0xf bank_mask:0xf
	v_mov_b32_dpp v170, v161 row_shr:2 row_mask:0xf bank_mask:0xf
	v_lshlrev_b32_e32 v172, 16, v165
	v_mov_b32_dpp v164, v160 row_shr:1 row_mask:0xf bank_mask:0xf
	v_lshlrev_b32_e32 v174, 16, v169
	v_and_b32_e32 v169, 0xffff0000, v169
	v_lshlrev_b32_e32 v175, 16, v170
	v_and_b32_e32 v176, 0xffff0000, v170
	v_cndmask_b32_e64 v170, v172, v214, s[0:1]
	v_cndmask_b32_e32 v172, v180, v214, vcc
	v_lshlrev_b32_e32 v171, 16, v164
	v_and_b32_e32 v164, 0xffff0000, v164
	v_and_b32_e32 v173, 0xffff0000, v165
	v_cndmask_b32_e64 v172, v175, v172, s[8:9]
	v_cndmask_b32_e64 v175, v169, v178, s[8:9]
	v_cndmask_b32_e64 v174, v174, v177, s[8:9]
	v_cndmask_b32_e64 v165, v164, v213, s[0:1]
	v_cndmask_b32_e64 v164, v171, v212, s[0:1]
	v_cndmask_b32_e64 v171, v173, v215, s[0:1]
	v_cndmask_b32_e32 v173, v181, v215, vcc
	v_pk_fma_f32 v[140:141], v[140:141], v[174:175], v[144:145]
	v_cndmask_b32_e64 v173, v176, v173, s[8:9]
	v_lshlrev_b32_e32 v176, 16, v160
	v_and_b32_e32 v177, 0xffff0000, v160
	v_pk_fma_f32 v[136:137], v[136:137], v[164:165], v[140:141]
	v_pk_fma_f32 v[142:143], v[142:143], v[172:173], v[146:147]
	v_pk_fma_f32 v[132:133], v[132:133], v[176:177], v[136:137]
	v_pk_fma_f32 v[138:139], v[138:139], v[170:171], v[142:143]
	v_pk_mul_f32 v[136:137], v[132:133], s[30:31] op_sel_hi:[1,0]
	v_pk_mul_f32 v[132:133], v[132:133], 0.5 op_sel_hi:[1,0]
	v_med3_f32 v136, v136, s47, v225
	v_med3_f32 v137, v137, s47, v225
	v_pk_mul_f32 v[140:141], v[136:137], v[136:137]
	s_nop 0
	v_pk_fma_f32 v[142:143], v[140:141], s[34:35], v[148:149] op_sel_hi:[1,0,0] neg_lo:[1,0,0] neg_hi:[1,0,0]
	s_nop 0
; __device__ __forceinline__ unsigned cvt_pk_bf16(float lo, float hi) { unsigned r; asm volatile("v_cvt_pk_bf16_f32 %0, %1, %2" : "=v"(r) : "v"(lo), "v"(hi)); return r; }
;     static __device__ __forceinline__ void finish(const float (&g0)[4], const float (&g1)[4], const float (&g2)[4], const float (&w0)[4], const float (&w1)[4], const float (&w2)[4], const float (&bb)[4],
;                                                   const f32x4 v, float rs, bf16_t* dst) {
;         float h[4];
; #pragma unroll
;         for (int j = 0; j < 4; j += 2) {
;             const f32x2 gc = (f32x2){bb[j] + w0[j] * g2[j] + w1[j] * g1[j] + w2[j] * g0[j], bb[j + 1] + w0[j + 1] * g2[j + 1] + w1[j + 1] * g1[j + 1] + w2[j + 1] * g0[j + 1]};
;             const f32x2 ge = gelu_pk(gc); h[j] = ge.x * v[j] * rs; h[j + 1] = ge.y * v[j + 1] * rs; }
;         u32x2 w; w.x = cvt_pk_bf16(h[0], h[1]); w.y = cvt_pk_bf16(h[2], h[3]);
;         *(u32x2*)dst = w;
;     __device__ __forceinline__ void operator()(const f32x4 (&acc)[2][2][4][2], const Unit& u, int wr, int wc, int fr, int fq) const {
;     ...
;             const int col = u.pn * BM + bj * HALF + wc * 32 + 8 * fq + 4 * hv;
;             float w0[4], w1[4], w2[4], bb[4];
;             ld4f(cw + col, w0); ld4f(cw + 2816 + col, w1); ld4f(cw + 2 * 2816 + col, w2); ld4f(cb + col, bb);
;             {
;                 const int i = fr & 7;
;                 u32x2 gq[4];
; #pragma unroll
;                 for (int m = 0; m < 4; ++m) { const int row = row0 + m * 16; gq[m] = *(const u32x2*)(G + (size_t)row * 2816 + col); }
; #pragma unroll
;                 for (int mh = 0; mh < 4; mh += 2) {
;                 f32x4 c0[4], c1[4];
; #pragma unroll
;                 for (int m = mh; m < mh + 2; ++m) { const int row = row0 + m * 16; const float* cx = ctx + (size_t)((row - 32768) >> 3) * 2 * 2816 + col;
;                     c0[m] = *(const f32x4*)cx; c1[m] = *(const f32x4*)(cx + 2816); }
	v_pk_fma_f32 v[142:143], v[140:141], v[142:143], s[38:39] op_sel_hi:[1,1,0]
	s_nop 0
	v_pk_fma_f32 v[142:143], v[140:141], v[142:143], s[40:41] op_sel_hi:[1,1,0]
	s_nop 0
	v_pk_fma_f32 v[142:143], v[140:141], v[142:143], s[42:43] op_sel_hi:[1,1,0]
	s_nop 0
	v_pk_fma_f32 v[142:143], v[140:141], v[142:143], s[44:45] op_sel_hi:[1,1,0]
	s_nop 0
	v_pk_fma_f32 v[142:143], v[140:141], v[142:143], s[46:47] op_sel_hi:[1,1,0]
	s_nop 0
	v_pk_fma_f32 v[140:141], v[140:141], v[142:143], s[48:49] op_sel_hi:[1,1,0]
	s_nop 0
	v_pk_mul_f32 v[136:137], v[136:137], v[140:141]
	s_nop 0
	v_pk_fma_f32 v[132:133], v[132:133], v[136:137], v[132:133]
	s_nop 0
	v_mul_f32_e32 v132, v40, v132
	v_mul_f32_e32 v140, v2, v132
	v_mul_f32_e32 v132, v41, v133
	v_mul_f32_e32 v141, v2, v132
	v_lshlrev_b32_e32 v132, 16, v161
	v_and_b32_e32 v133, 0xffff0000, v161
	v_pk_fma_f32 v[132:133], v[134:135], v[132:133], v[138:139]
	s_nop 0
	v_pk_mul_f32 v[134:135], v[132:133], s[30:31] op_sel_hi:[1,0]
	v_pk_mul_f32 v[132:133], v[132:133], 0.5 op_sel_hi:[1,0]
	v_med3_f32 v134, v134, s47, v225
	v_med3_f32 v135, v135, s47, v225
	v_pk_mul_f32 v[136:137], v[134:135], v[134:135]
	s_nop 0
	v_pk_fma_f32 v[138:139], v[136:137], s[34:35], v[148:149] op_sel_hi:[1,0,0] neg_lo:[1,0,0] neg_hi:[1,0,0]
	s_nop 0
	v_pk_fma_f32 v[138:139], v[136:137], v[138:139], s[38:39] op_sel_hi:[1,1,0]
	s_nop 0
	v_pk_fma_f32 v[138:139], v[136:137], v[138:139], s[40:41] op_sel_hi:[1,1,0]
	s_nop 0
	v_pk_fma_f32 v[138:139], v[136:137], v[138:139], s[42:43] op_sel_hi:[1,1,0]
	s_nop 0
	v_pk_fma_f32 v[138:139], v[136:137], v[138:139], s[44:45] op_sel_hi:[1,1,0]
	s_nop 0
	v_pk_fma_f32 v[138:139], v[136:137], v[138:139], s[46:47] op_sel_hi:[1,1,0]
	s_nop 0
	v_pk_fma_f32 v[136:137], v[136:137], v[138:139], s[48:49] op_sel_hi:[1,1,0]
	s_nop 0
	v_pk_mul_f32 v[134:135], v[134:135], v[136:137]
	s_nop 0
	v_pk_fma_f32 v[132:133], v[132:133], v[134:135], v[132:133]
	s_nop 0
	v_mul_f32_e32 v132, v42, v132
	v_mul_f32_e32 v134, v2, v132
	v_mul_f32_e32 v132, v43, v133
	v_mul_f32_e32 v133, v2, v132
	v_cvt_pk_bf16_f32 v132, v140, v141
	v_cvt_pk_bf16_f32 v133, v134, v133
	global_store_dwordx2 v[162:163], v[132:133], off nt
	v_add_u32_e32 v132, 0x84, v150
	v_ashrrev_i32_e32 v133, 31, v132
	v_lshlrev_b64 v[160:161], 1, v[132:133]
	v_lshl_add_u64 v[162:163], s[68:69], 0, v[160:161]
	v_lshlrev_b64 v[132:133], 2, v[132:133]
	v_mad_i64_i32 v[134:135], s[10:11], v210, s91, v[162:163]
	v_lshl_add_u64 v[182:183], s[82:83], 0, v[132:133]
	global_load_dwordx2 v[164:165], v[134:135], off
	v_mad_i64_i32 v[134:135], s[10:11], v151, s45, v[182:183]
	v_add_co_u32_e64 v136, s[10:11], s41, v134
	v_lshl_add_u64 v[152:153], v[152:153], 0, v[160:161]
	s_nop 0
	v_addc_co_u32_e64 v137, s[10:11], 0, v135, s[10:11]
	global_load_dwordx4 v[170:173], v[136:137], off offset:3072
	global_load_dwordx4 v[174:177], v[134:135], off
	v_lshl_add_u64 v[134:135], s[66:67], 0, v[132:133]
	global_load_dwordx4 v[140:143], v[134:135], off
	v_lshl_add_u64 v[134:135], s[88:89], 0, v[132:133]
	global_load_dwordx4 v[144:147], v[134:135], off
	v_lshl_add_u64 v[134:135], s[52:53], 0, v[132:133]
	global_load_dwordx4 v[136:139], v[134:135], off
	v_lshl_add_u64 v[132:133], s[54:55], 0, v[132:133]
	global_load_dwordx4 v[132:135], v[132:133], off
	v_mad_i64_i32 v[150:151], s[10:11], v194, s91, v[162:163]
	v_mad_i64_i32 v[178:179], s[10:11], v192, s91, v[162:163]
	v_mad_i64_i32 v[180:181], s[10:11], v190, s91, v[162:163]
	v_mad_i64_i32 v[168:169], s[10:11], v168, s45, v[182:183]
	v_add_co_u32_e64 v212, s[10:11], s41, v168
	global_load_dwordx2 v[226:227], v[150:151], off
	global_load_dwordx2 v[162:163], v[178:179], off
	s_nop 0
	global_load_dwordx2 v[150:151], v[180:181], off
	v_addc_co_u32_e64 v213, s[10:11], 0, v169, s[10:11]
	global_load_dwordx4 v[178:181], v[168:169], off
	s_nop 0
	global_load_dwordx4 v[212:215], v[212:213], off offset:3072
	v_lshl_add_u64 v[154:155], v[154:155], 0, v[160:161]
	v_lshl_add_u64 v[156:157], v[156:157], 0, v[160:161]
	v_lshl_add_u64 v[158:159], v[158:159], 0, v[160:161]
	s_mov_b64 s[54:55], s[86:87]
	s_waitcnt vmcnt(11)
	v_mov_b32_dpp v168, v164 row_ror:1 row_mask:0xf bank_mask:0xf bound_ctrl:1
	v_mov_b32_dpp v169, v165 row_ror:1 row_mask:0xf bank_mask:0xf bound_ctrl:1
	v_mov_b32_dpp v185, v164 row_ror:2 row_mask:0xf bank_mask:0xf bound_ctrl:1
	v_mov_b32_dpp v168, v164 row_shr:1 row_mask:0xf bank_mask:0xf
	v_mov_b32_dpp v169, v165 row_shr:1 row_mask:0xf bank_mask:0xf
	v_mov_b32_dpp v185, v164 row_shr:2 row_mask:0xf bank_mask:0xf
	v_lshlrev_b32_e32 v189, 16, v168
	v_and_b32_e32 v168, 0xffff0000, v168
	v_lshlrev_b32_e32 v191, 16, v169
	v_and_b32_e32 v193, 0xffff0000, v169
	v_lshlrev_b32_e32 v195, 16, v185
	v_and_b32_e32 v185, 0xffff0000, v185
	s_waitcnt vmcnt(9)
	v_cndmask_b32_e32 v174, v174, v170, vcc
	v_cndmask_b32_e32 v175, v175, v171, vcc
	v_cndmask_b32_e64 v169, v168, v171, s[0:1]
	v_cndmask_b32_e64 v168, v189, v170, s[0:1]
	v_cndmask_b32_e64 v229, v193, v173, s[0:1]
	v_cndmask_b32_e64 v228, v191, v172, s[0:1]
	v_cndmask_b32_e32 v170, v176, v172, vcc
	v_cndmask_b32_e32 v171, v177, v173, vcc
	v_cndmask_b32_e64 v173, v185, v175, s[8:9]
	v_cndmask_b32_e64 v172, v195, v174, s[8:9]
	s_waitcnt vmcnt(7)
	v_pk_fma_f32 v[172:173], v[140:141], v[172:173], v[144:145]
	v_lshlrev_b32_e32 v174, 16, v164
	v_and_b32_e32 v175, 0xffff0000, v164
	s_waitcnt vmcnt(6)
	v_pk_fma_f32 v[168:169], v[136:137], v[168:169], v[172:173]
	v_mov_b32_dpp v187, v165 row_ror:2 row_mask:0xf bank_mask:0xf bound_ctrl:1
	s_waitcnt vmcnt(5)
	v_pk_fma_f32 v[168:169], v[132:133], v[174:175], v[168:169]
	s_waitcnt vmcnt(2)
; __device__ __forceinline__ unsigned cvt_pk_bf16(float lo, float hi) { unsigned r; asm volatile("v_cvt_pk_bf16_f32 %0, %1, %2" : "=v"(r) : "v"(lo), "v"(hi)); return r; }
;     static __device__ __forceinline__ void unpk4(const u32x2 w, float (&o)[4]) { o[0] = bf_lo(w.x); o[1] = bf_hi(w.x); o[2] = bf_lo(w.y); o[3] = bf_hi(w.y); }
;     template <int N> static __device__ __forceinline__ u32x2 dpp_prev(const u32x2 pv, const u32x2 cur) { u32x2 r; r.x = dpp_prev1<N>(pv.x, cur.x); r.y = dpp_prev1<N>(pv.y, cur.y); return r; }
;     static __device__ __forceinline__ void finish(const float (&g0)[4], const float (&g1)[4], const float (&g2)[4], const float (&w0)[4], const float (&w1)[4], const float (&w2)[4], const float (&bb)[4],
;                                                   const f32x4 v, float rs, bf16_t* dst) {
;         float h[4];
; #pragma unroll
;         for (int j = 0; j < 4; j += 2) {
;             const f32x2 gc = (f32x2){bb[j] + w0[j] * g2[j] + w1[j] * g1[j] + w2[j] * g0[j], bb[j + 1] + w0[j + 1] * g2[j + 1] + w1[j + 1] * g1[j + 1] + w2[j + 1] * g0[j + 1]};
;             const f32x2 ge = gelu_pk(gc); h[j] = ge.x * v[j] * rs; h[j + 1] = ge.y * v[j + 1] * rs; }
;         u32x2 w; w.x = cvt_pk_bf16(h[0], h[1]); w.y = cvt_pk_bf16(h[2], h[3]);
;         *(u32x2*)dst = w;
;     __device__ __forceinline__ void operator()(const f32x4 (&acc)[2][2][4][2], const Unit& u, int wr, int wc, int fr, int fq) const {
;     ...
;                 for (int m = mh; m < mh + 2; ++m) { const int row = row0 + m * 16; const u32x2 cur = gq[m];
;                     const u32x2 q1 = dpp_prev<1>(cur, cur), q2 = dpp_prev<2>(cur, cur);
;                     float g0[4], g1[4], g2[4]; unpk4(cur, g0); unpk4(q1, g1); unpk4(q2, g2);
; #pragma unroll
;                     for (int j = 0; j < 4; ++j) { const float x1 = c1[m][j], x0 = c0[m][j];
;                         if (i < 1) g1[j] = x1;
;                         if (i < 2) g2[j] = (i == 1) ? x1 : x0; }
;                     finish(g0, g1, g2, w0, w1, w2, bb, acc[0][bj][m][hv], rs8[0][m], H + (size_t)row * 2816 + col); }
	v_lshlrev_b32_e32 v160, 16, v150
	v_pk_mul_f32 v[172:173], v[168:169], s[30:31] op_sel_hi:[1,0]
	v_mov_b32_dpp v187, v165 row_shr:2 row_mask:0xf bank_mask:0xf
	v_med3_f32 v172, v172, s47, v225
	v_med3_f32 v173, v173, s47, v225
	v_pk_mul_f32 v[174:175], v[172:173], v[172:173]
	v_pk_mul_f32 v[168:169], v[168:169], 0.5 op_sel_hi:[1,0]
	v_pk_fma_f32 v[176:177], v[174:175], s[34:35], v[148:149] op_sel_hi:[1,0,0] neg_lo:[1,0,0] neg_hi:[1,0,0]
	v_lshlrev_b32_e32 v211, 16, v187
	v_pk_fma_f32 v[176:177], v[174:175], v[176:177], s[38:39] op_sel_hi:[1,1,0]
	v_and_b32_e32 v187, 0xffff0000, v187
	v_pk_fma_f32 v[176:177], v[174:175], v[176:177], s[40:41] op_sel_hi:[1,1,0]
	v_cndmask_b32_e64 v171, v187, v171, s[8:9]
	v_pk_fma_f32 v[176:177], v[174:175], v[176:177], s[42:43] op_sel_hi:[1,1,0]
	v_cndmask_b32_e64 v170, v211, v170, s[8:9]
	v_pk_fma_f32 v[176:177], v[174:175], v[176:177], s[44:45] op_sel_hi:[1,1,0]
	v_pk_fma_f32 v[170:171], v[142:143], v[170:171], v[146:147]
	v_pk_fma_f32 v[176:177], v[174:175], v[176:177], s[46:47] op_sel_hi:[1,1,0]
	v_pk_fma_f32 v[170:171], v[138:139], v[228:229], v[170:171]
	v_pk_fma_f32 v[174:175], v[174:175], v[176:177], s[48:49] op_sel_hi:[1,1,0]
	v_mov_b32_dpp v176, v162 row_ror:1 row_mask:0xf bank_mask:0xf bound_ctrl:1
	v_pk_mul_f32 v[172:173], v[172:173], v[174:175]
	v_mov_b32_dpp v177, v163 row_ror:1 row_mask:0xf bank_mask:0xf bound_ctrl:1
	v_pk_fma_f32 v[168:169], v[168:169], v[172:173], v[168:169]
	v_mov_b32_dpp v176, v162 row_shr:1 row_mask:0xf bank_mask:0xf
	v_mul_f32_e32 v164, v60, v168
	v_mul_f32_e32 v174, v188, v164
	v_mul_f32_e32 v164, v61, v169
	v_mul_f32_e32 v175, v188, v164
	v_lshlrev_b32_e32 v164, 16, v165
	v_and_b32_e32 v165, 0xffff0000, v165
	v_pk_fma_f32 v[164:165], v[134:135], v[164:165], v[170:171]
	v_mov_b32_dpp v177, v163 row_shr:1 row_mask:0xf bank_mask:0xf
	v_pk_mul_f32 v[168:169], v[164:165], s[30:31] op_sel_hi:[1,0]
	v_pk_mul_f32 v[164:165], v[164:165], 0.5 op_sel_hi:[1,0]
	v_med3_f32 v168, v168, s47, v225
	v_med3_f32 v169, v169, s47, v225
	v_pk_mul_f32 v[170:171], v[168:169], v[168:169]
	v_and_b32_e32 v161, 0xffff0000, v150
	v_pk_fma_f32 v[172:173], v[170:171], s[34:35], v[148:149] op_sel_hi:[1,0,0] neg_lo:[1,0,0] neg_hi:[1,0,0]
	s_nop 0
	v_pk_fma_f32 v[172:173], v[170:171], v[172:173], s[38:39] op_sel_hi:[1,1,0]
	s_nop 0
	v_pk_fma_f32 v[172:173], v[170:171], v[172:173], s[40:41] op_sel_hi:[1,1,0]
	s_nop 0
	v_pk_fma_f32 v[172:173], v[170:171], v[172:173], s[42:43] op_sel_hi:[1,1,0]
	s_nop 0
	v_pk_fma_f32 v[172:173], v[170:171], v[172:173], s[44:45] op_sel_hi:[1,1,0]
	s_nop 0
	v_pk_fma_f32 v[172:173], v[170:171], v[172:173], s[46:47] op_sel_hi:[1,1,0]
	s_nop 0
	v_pk_fma_f32 v[170:171], v[170:171], v[172:173], s[48:49] op_sel_hi:[1,1,0]
	s_nop 0
	v_pk_mul_f32 v[168:169], v[168:169], v[170:171]
	s_nop 0
	v_pk_fma_f32 v[164:165], v[164:165], v[168:169], v[164:165]
	s_nop 0
	v_mul_f32_e32 v164, v62, v164
	v_mul_f32_e32 v168, v188, v164
	v_mul_f32_e32 v164, v63, v165
	v_mul_f32_e32 v165, v188, v164
	v_cvt_pk_bf16_f32 v164, v174, v175
	v_cvt_pk_bf16_f32 v165, v168, v165
	global_store_dwordx2 v[152:153], v[164:165], off nt
	v_mov_b32_dpp v153, v227 row_ror:1 row_mask:0xf bank_mask:0xf bound_ctrl:1
	v_mov_b32_dpp v164, v226 row_ror:2 row_mask:0xf bank_mask:0xf bound_ctrl:1
	v_mov_b32_dpp v165, v227 row_ror:2 row_mask:0xf bank_mask:0xf bound_ctrl:1
	v_mov_b32_dpp v153, v227 row_shr:1 row_mask:0xf bank_mask:0xf
	v_mov_b32_dpp v152, v226 row_ror:1 row_mask:0xf bank_mask:0xf bound_ctrl:1
	v_mov_b32_dpp v164, v226 row_shr:2 row_mask:0xf bank_mask:0xf
	v_mov_b32_dpp v165, v227 row_shr:2 row_mask:0xf bank_mask:0xf
	v_and_b32_e32 v170, 0xffff0000, v153
	v_mov_b32_dpp v152, v226 row_shr:1 row_mask:0xf bank_mask:0xf
	v_lshlrev_b32_e32 v172, 16, v164
	v_and_b32_e32 v171, 0xffff0000, v164
	v_lshlrev_b32_e32 v173, 16, v165
	v_and_b32_e32 v174, 0xffff0000, v165
	s_waitcnt vmcnt(1)
	v_cndmask_b32_e64 v165, v170, v215, s[0:1]
	v_cndmask_b32_e32 v170, v178, v212, vcc
	v_cndmask_b32_e32 v175, v179, v213, vcc
	v_lshlrev_b32_e32 v168, 16, v152
	v_and_b32_e32 v152, 0xffff0000, v152
	v_lshlrev_b32_e32 v169, 16, v153
	v_cndmask_b32_e64 v171, v171, v175, s[8:9]
	v_cndmask_b32_e64 v170, v172, v170, s[8:9]
	v_cndmask_b32_e64 v153, v152, v213, s[0:1]
	v_cndmask_b32_e64 v152, v168, v212, s[0:1]
	v_cndmask_b32_e64 v164, v169, v214, s[0:1]
	v_cndmask_b32_e32 v168, v180, v214, vcc
	v_cndmask_b32_e32 v169, v181, v215, vcc
	v_pk_fma_f32 v[170:171], v[140:141], v[170:171], v[144:145]
	v_cndmask_b32_e64 v169, v174, v169, s[8:9]
	v_cndmask_b32_e64 v168, v173, v168, s[8:9]
	v_lshlrev_b32_e32 v172, 16, v226
	v_and_b32_e32 v173, 0xffff0000, v226
	v_pk_fma_f32 v[152:153], v[136:137], v[152:153], v[170:171]
	v_pk_fma_f32 v[168:169], v[142:143], v[168:169], v[146:147]
	v_pk_fma_f32 v[152:153], v[132:133], v[172:173], v[152:153]
	v_pk_fma_f32 v[164:165], v[138:139], v[164:165], v[168:169]
	v_pk_mul_f32 v[168:169], v[152:153], s[30:31] op_sel_hi:[1,0]
	v_pk_mul_f32 v[152:153], v[152:153], 0.5 op_sel_hi:[1,0]
	v_med3_f32 v168, v168, s47, v225
	v_med3_f32 v169, v169, s47, v225
	v_pk_mul_f32 v[170:171], v[168:169], v[168:169]
	v_mov_b32_dpp v178, v162 row_ror:2 row_mask:0xf bank_mask:0xf bound_ctrl:1
	v_pk_fma_f32 v[172:173], v[170:171], s[34:35], v[148:149] op_sel_hi:[1,0,0] neg_lo:[1,0,0] neg_hi:[1,0,0]
	v_mov_b32_dpp v179, v163 row_ror:2 row_mask:0xf bank_mask:0xf bound_ctrl:1
	v_pk_fma_f32 v[172:173], v[170:171], v[172:173], s[38:39] op_sel_hi:[1,1,0]
	v_mov_b32_dpp v178, v162 row_shr:2 row_mask:0xf bank_mask:0xf
	v_pk_fma_f32 v[172:173], v[170:171], v[172:173], s[40:41] op_sel_hi:[1,1,0]
	v_mov_b32_dpp v179, v163 row_shr:2 row_mask:0xf bank_mask:0xf
; __device__ __forceinline__ unsigned cvt_pk_bf16(float lo, float hi) { unsigned r; asm volatile("v_cvt_pk_bf16_f32 %0, %1, %2" : "=v"(r) : "v"(lo), "v"(hi)); return r; }
;     static __device__ __forceinline__ void unpk4(const u32x2 w, float (&o)[4]) { o[0] = bf_lo(w.x); o[1] = bf_hi(w.x); o[2] = bf_lo(w.y); o[3] = bf_hi(w.y); }
;     template <int N> static __device__ __forceinline__ u32x2 dpp_prev(const u32x2 pv, const u32x2 cur) { u32x2 r; r.x = dpp_prev1<N>(pv.x, cur.x); r.y = dpp_prev1<N>(pv.y, cur.y); return r; }
;     static __device__ __forceinline__ void finish(const float (&g0)[4], const float (&g1)[4], const float (&g2)[4], const float (&w0)[4], const float (&w1)[4], const float (&w2)[4], const float (&bb)[4],
;                                                   const f32x4 v, float rs, bf16_t* dst) {
;         float h[4];
; #pragma unroll
;         for (int j = 0; j < 4; j += 2) {
;             const f32x2 gc = (f32x2){bb[j] + w0[j] * g2[j] + w1[j] * g1[j] + w2[j] * g0[j], bb[j + 1] + w0[j + 1] * g2[j + 1] + w1[j + 1] * g1[j + 1] + w2[j + 1] * g0[j + 1]};
;             const f32x2 ge = gelu_pk(gc); h[j] = ge.x * v[j] * rs; h[j + 1] = ge.y * v[j + 1] * rs; }
;         u32x2 w; w.x = cvt_pk_bf16(h[0], h[1]); w.y = cvt_pk_bf16(h[2], h[3]);
;         *(u32x2*)dst = w;
;     __device__ __forceinline__ void operator()(const f32x4 (&acc)[2][2][4][2], const Unit& u, int wr, int wc, int fr, int fq) const {
;     ...
;                 for (int m = mh; m < mh + 2; ++m) { const int row = row0 + m * 16; const u32x2 cur = gq[m];
;                     const u32x2 q1 = dpp_prev<1>(cur, cur), q2 = dpp_prev<2>(cur, cur);
;                     float g0[4], g1[4], g2[4]; unpk4(cur, g0); unpk4(q1, g1); unpk4(q2, g2);
; #pragma unroll
;                     for (int j = 0; j < 4; ++j) { const float x1 = c1[m][j], x0 = c0[m][j];
;                         if (i < 1) g1[j] = x1;
;                         if (i < 2) g2[j] = (i == 1) ? x1 : x0; }
;                     finish(g0, g1, g2, w0, w1, w2, bb, acc[0][bj][m][hv], rs8[0][m], H + (size_t)row * 2816 + col); }
	v_pk_fma_f32 v[172:173], v[170:171], v[172:173], s[42:43] op_sel_hi:[1,1,0]
	v_lshlrev_b32_e32 v180, 16, v176
	v_pk_fma_f32 v[172:173], v[170:171], v[172:173], s[44:45] op_sel_hi:[1,1,0]
	v_and_b32_e32 v176, 0xffff0000, v176
	v_pk_fma_f32 v[172:173], v[170:171], v[172:173], s[46:47] op_sel_hi:[1,1,0]
	v_lshlrev_b32_e32 v181, 16, v177
	v_pk_fma_f32 v[170:171], v[170:171], v[172:173], s[48:49] op_sel_hi:[1,1,0]
	v_and_b32_e32 v185, 0xffff0000, v178
	v_pk_mul_f32 v[168:169], v[168:169], v[170:171]
	v_lshlrev_b32_e32 v187, 16, v179
	v_pk_fma_f32 v[152:153], v[152:153], v[168:169], v[152:153]
	v_and_b32_e32 v189, 0xffff0000, v179
	v_mul_f32_e32 v152, v52, v152
	v_mul_f32_e32 v172, v186, v152
	v_mul_f32_e32 v152, v53, v153
	v_mul_f32_e32 v173, v186, v152
	v_lshlrev_b32_e32 v152, 16, v227
	v_and_b32_e32 v153, 0xffff0000, v227
	v_pk_fma_f32 v[152:153], v[134:135], v[152:153], v[164:165]
	s_nop 0
	v_pk_mul_f32 v[164:165], v[152:153], s[30:31] op_sel_hi:[1,0]
	v_pk_mul_f32 v[152:153], v[152:153], 0.5 op_sel_hi:[1,0]
	v_med3_f32 v164, v164, s47, v225
	v_med3_f32 v165, v165, s47, v225
	v_pk_mul_f32 v[168:169], v[164:165], v[164:165]
	s_nop 0
	v_pk_fma_f32 v[170:171], v[168:169], s[34:35], v[148:149] op_sel_hi:[1,0,0] neg_lo:[1,0,0] neg_hi:[1,0,0]
	s_nop 0
	v_pk_fma_f32 v[170:171], v[168:169], v[170:171], s[38:39] op_sel_hi:[1,1,0]
	s_nop 0
	v_pk_fma_f32 v[170:171], v[168:169], v[170:171], s[40:41] op_sel_hi:[1,1,0]
	s_nop 0
	v_pk_fma_f32 v[170:171], v[168:169], v[170:171], s[42:43] op_sel_hi:[1,1,0]
	s_nop 0
	v_pk_fma_f32 v[170:171], v[168:169], v[170:171], s[44:45] op_sel_hi:[1,1,0]
	s_nop 0
	v_pk_fma_f32 v[170:171], v[168:169], v[170:171], s[46:47] op_sel_hi:[1,1,0]
	s_nop 0
	v_pk_fma_f32 v[168:169], v[168:169], v[170:171], s[48:49] op_sel_hi:[1,1,0]
	s_nop 0
	v_pk_mul_f32 v[164:165], v[164:165], v[168:169]
	s_nop 0
	v_pk_fma_f32 v[152:153], v[152:153], v[164:165], v[152:153]
	s_nop 0
	v_mul_f32_e32 v152, v54, v152
	v_mul_f32_e32 v164, v186, v152
	v_mul_f32_e32 v152, v55, v153
	v_mul_f32_e32 v153, v186, v152
	v_cvt_pk_bf16_f32 v152, v172, v173
	v_cvt_pk_bf16_f32 v153, v164, v153
	v_mad_i64_i32 v[164:165], s[10:11], v166, s45, v[182:183]
	global_store_dwordx2 v[154:155], v[152:153], off nt
	v_add_co_u32_e64 v152, s[10:11], s41, v164
	s_nop 1
	v_addc_co_u32_e64 v153, s[10:11], 0, v165, s[10:11]
	global_load_dwordx4 v[152:155], v[152:153], off offset:3072
	s_nop 0
	global_load_dwordx4 v[168:171], v[164:165], off
	v_mad_i64_i32 v[164:165], s[10:11], v167, s45, v[182:183]
	v_add_co_u32_e64 v172, s[10:11], s41, v164
	v_and_b32_e32 v182, 0xffff0000, v177
	s_nop 0
	v_addc_co_u32_e64 v173, s[10:11], 0, v165, s[10:11]
	global_load_dwordx4 v[164:167], v[164:165], off
	s_nop 0
	global_load_dwordx4 v[172:175], v[172:173], off offset:3072
	v_lshlrev_b32_e32 v183, 16, v178
	s_waitcnt vmcnt(3)
	v_cndmask_b32_e64 v177, v176, v153, s[0:1]
	s_waitcnt vmcnt(2)
	v_cndmask_b32_e32 v168, v168, v152, vcc
	v_cndmask_b32_e32 v169, v169, v153, vcc
	v_cndmask_b32_e64 v176, v180, v152, s[0:1]
	v_cndmask_b32_e64 v179, v182, v155, s[0:1]
	v_cndmask_b32_e64 v178, v181, v154, s[0:1]
	v_cndmask_b32_e32 v152, v170, v154, vcc
	v_cndmask_b32_e32 v153, v171, v155, vcc
	v_cndmask_b32_e64 v155, v185, v169, s[8:9]
	v_cndmask_b32_e64 v154, v183, v168, s[8:9]
	v_pk_fma_f32 v[154:155], v[140:141], v[154:155], v[144:145]
	v_lshlrev_b32_e32 v168, 16, v162
	v_and_b32_e32 v169, 0xffff0000, v162
	v_pk_fma_f32 v[154:155], v[136:137], v[176:177], v[154:155]
	v_cndmask_b32_e64 v153, v189, v153, s[8:9]
	v_pk_fma_f32 v[154:155], v[132:133], v[168:169], v[154:155]
	v_cndmask_b32_e64 v152, v187, v152, s[8:9]
	v_pk_mul_f32 v[168:169], v[154:155], s[30:31] op_sel_hi:[1,0]
	v_pk_mul_f32 v[154:155], v[154:155], 0.5 op_sel_hi:[1,0]
	v_med3_f32 v168, v168, s47, v225
	v_med3_f32 v169, v169, s47, v225
	v_pk_mul_f32 v[170:171], v[168:169], v[168:169]
	v_pk_fma_f32 v[152:153], v[142:143], v[152:153], v[146:147]
	v_pk_fma_f32 v[176:177], v[170:171], s[34:35], v[148:149] op_sel_hi:[1,0,0] neg_lo:[1,0,0] neg_hi:[1,0,0]
	v_pk_fma_f32 v[152:153], v[138:139], v[178:179], v[152:153]
	v_pk_fma_f32 v[176:177], v[170:171], v[176:177], s[38:39] op_sel_hi:[1,1,0]
	s_nop 0
	v_pk_fma_f32 v[176:177], v[170:171], v[176:177], s[40:41] op_sel_hi:[1,1,0]
	s_nop 0
	v_pk_fma_f32 v[176:177], v[170:171], v[176:177], s[42:43] op_sel_hi:[1,1,0]
	s_nop 0
	v_pk_fma_f32 v[176:177], v[170:171], v[176:177], s[44:45] op_sel_hi:[1,1,0]
	s_nop 0
	v_pk_fma_f32 v[176:177], v[170:171], v[176:177], s[46:47] op_sel_hi:[1,1,0]
	s_nop 0
	v_pk_fma_f32 v[170:171], v[170:171], v[176:177], s[48:49] op_sel_hi:[1,1,0]
	s_nop 0
	v_pk_mul_f32 v[168:169], v[168:169], v[170:171]
	s_nop 0
	v_pk_fma_f32 v[154:155], v[154:155], v[168:169], v[154:155]
	s_nop 0
	v_mul_f32_e32 v154, v44, v154
	v_mul_f32_e32 v170, v184, v154
	v_mul_f32_e32 v154, v45, v155
	v_mul_f32_e32 v171, v184, v154
	v_lshlrev_b32_e32 v154, 16, v163
	v_and_b32_e32 v155, 0xffff0000, v163
	v_pk_fma_f32 v[152:153], v[134:135], v[154:155], v[152:153]
	s_nop 0
	v_pk_mul_f32 v[154:155], v[152:153], s[30:31] op_sel_hi:[1,0]
	v_pk_mul_f32 v[152:153], v[152:153], 0.5 op_sel_hi:[1,0]
	v_med3_f32 v154, v154, s47, v225
	v_med3_f32 v155, v155, s47, v225
	v_pk_mul_f32 v[162:163], v[154:155], v[154:155]
	s_nop 0
	v_pk_fma_f32 v[168:169], v[162:163], s[34:35], v[148:149] op_sel_hi:[1,0,0] neg_lo:[1,0,0] neg_hi:[1,0,0]
	s_nop 0
	v_pk_fma_f32 v[168:169], v[162:163], v[168:169], s[38:39] op_sel_hi:[1,1,0]
	s_nop 0
	v_pk_fma_f32 v[168:169], v[162:163], v[168:169], s[40:41] op_sel_hi:[1,1,0]
	s_nop 0
	v_pk_fma_f32 v[168:169], v[162:163], v[168:169], s[42:43] op_sel_hi:[1,1,0]
	s_nop 0
	v_pk_fma_f32 v[168:169], v[162:163], v[168:169], s[44:45] op_sel_hi:[1,1,0]
	s_nop 0
	v_pk_fma_f32 v[168:169], v[162:163], v[168:169], s[46:47] op_sel_hi:[1,1,0]
	s_nop 0
	v_pk_fma_f32 v[162:163], v[162:163], v[168:169], s[48:49] op_sel_hi:[1,1,0]
	s_nop 0
	v_pk_mul_f32 v[154:155], v[154:155], v[162:163]
	s_nop 0
	v_pk_fma_f32 v[152:153], v[152:153], v[154:155], v[152:153]
	v_mov_b32_dpp v155, v151 row_ror:2 row_mask:0xf bank_mask:0xf bound_ctrl:1
	v_mul_f32_e32 v152, v46, v152
	v_mul_f32_e32 v154, v184, v152
	v_mul_f32_e32 v152, v47, v153
	v_mul_f32_e32 v153, v184, v152
	v_cvt_pk_bf16_f32 v152, v170, v171
	v_cvt_pk_bf16_f32 v153, v154, v153
	global_store_dwordx2 v[156:157], v[152:153], off nt
	v_mov_b32_dpp v154, v150 row_ror:2 row_mask:0xf bank_mask:0xf bound_ctrl:1
	v_mov_b32_dpp v153, v151 row_ror:1 row_mask:0xf bank_mask:0xf bound_ctrl:1
	v_mov_b32_dpp v152, v150 row_ror:1 row_mask:0xf bank_mask:0xf bound_ctrl:1
	v_mov_b32_dpp v154, v150 row_shr:2 row_mask:0xf bank_mask:0xf
	v_mov_b32_dpp v153, v151 row_shr:1 row_mask:0xf bank_mask:0xf
	v_mov_b32_dpp v155, v151 row_shr:2 row_mask:0xf bank_mask:0xf
	v_and_b32_e32 v162, 0xffff0000, v153
	v_mov_b32_dpp v152, v150 row_shr:1 row_mask:0xf bank_mask:0xf
	v_lshlrev_b32_e32 v168, 16, v154
	v_and_b32_e32 v163, 0xffff0000, v154
	v_lshlrev_b32_e32 v169, 16, v155
	v_and_b32_e32 v170, 0xffff0000, v155
	s_waitcnt vmcnt(1)
; __device__ __forceinline__ unsigned cvt_pk_bf16(float lo, float hi) { unsigned r; asm volatile("v_cvt_pk_bf16_f32 %0, %1, %2" : "=v"(r) : "v"(lo), "v"(hi)); return r; }
;     static __device__ __forceinline__ void unpk4(const u32x2 w, float (&o)[4]) { o[0] = bf_lo(w.x); o[1] = bf_hi(w.x); o[2] = bf_lo(w.y); o[3] = bf_hi(w.y); }
;     template <int N> static __device__ __forceinline__ u32x2 dpp_prev(const u32x2 pv, const u32x2 cur) { u32x2 r; r.x = dpp_prev1<N>(pv.x, cur.x); r.y = dpp_prev1<N>(pv.y, cur.y); return r; }
;     static __device__ __forceinline__ void finish(const float (&g0)[4], const float (&g1)[4], const float (&g2)[4], const float (&w0)[4], const float (&w1)[4], const float (&w2)[4], const float (&bb)[4],
;                                                   const f32x4 v, float rs, bf16_t* dst) {
;         float h[4];
; #pragma unroll
;         for (int j = 0; j < 4; j += 2) {
;             const f32x2 gc = (f32x2){bb[j] + w0[j] * g2[j] + w1[j] * g1[j] + w2[j] * g0[j], bb[j + 1] + w0[j + 1] * g2[j + 1] + w1[j + 1] * g1[j + 1] + w2[j + 1] * g0[j + 1]};
;             const f32x2 ge = gelu_pk(gc); h[j] = ge.x * v[j] * rs; h[j + 1] = ge.y * v[j + 1] * rs; }
;         u32x2 w; w.x = cvt_pk_bf16(h[0], h[1]); w.y = cvt_pk_bf16(h[2], h[3]);
;         *(u32x2*)dst = w;
;     __device__ __forceinline__ void operator()(const f32x4 (&acc)[2][2][4][2], const Unit& u, int wr, int wc, int fr, int fq) const {
;     ...
;                 for (int m = mh; m < mh + 2; ++m) { const int row = row0 + m * 16; const u32x2 cur = gq[m];
;                     const u32x2 q1 = dpp_prev<1>(cur, cur), q2 = dpp_prev<2>(cur, cur);
;                     float g0[4], g1[4], g2[4]; unpk4(cur, g0); unpk4(q1, g1); unpk4(q2, g2);
; #pragma unroll
;                     for (int j = 0; j < 4; ++j) { const float x1 = c1[m][j], x0 = c0[m][j];
;                         if (i < 1) g1[j] = x1;
;                         if (i < 2) g2[j] = (i == 1) ? x1 : x0; }
;                     finish(g0, g1, g2, w0, w1, w2, bb, acc[0][bj][m][hv], rs8[0][m], H + (size_t)row * 2816 + col); }
	v_cndmask_b32_e64 v155, v162, v175, s[0:1]
	v_cndmask_b32_e32 v162, v164, v172, vcc
	v_cndmask_b32_e32 v164, v165, v173, vcc
	v_lshlrev_b32_e32 v156, 16, v152
	v_and_b32_e32 v152, 0xffff0000, v152
	v_cndmask_b32_e64 v163, v163, v164, s[8:9]
	v_cndmask_b32_e64 v162, v168, v162, s[8:9]
	v_lshlrev_b32_e32 v157, 16, v153
	v_cndmask_b32_e64 v153, v152, v173, s[0:1]
	v_cndmask_b32_e64 v152, v156, v172, s[0:1]
	v_pk_fma_f32 v[140:141], v[140:141], v[162:163], v[144:145]
	v_cndmask_b32_e64 v154, v157, v174, s[0:1]
	v_pk_fma_f32 v[136:137], v[136:137], v[152:153], v[140:141]
	v_cndmask_b32_e32 v156, v166, v174, vcc
	v_pk_fma_f32 v[132:133], v[132:133], v[160:161], v[136:137]
	v_cndmask_b32_e32 v157, v167, v175, vcc
	v_pk_mul_f32 v[136:137], v[132:133], s[30:31] op_sel_hi:[1,0]
	v_cndmask_b32_e64 v157, v170, v157, s[8:9]
	v_cndmask_b32_e64 v156, v169, v156, s[8:9]
	v_med3_f32 v136, v136, s47, v225
	v_med3_f32 v137, v137, s47, v225
	v_pk_fma_f32 v[142:143], v[142:143], v[156:157], v[146:147]
	v_pk_mul_f32 v[140:141], v[136:137], v[136:137]
	v_pk_fma_f32 v[138:139], v[138:139], v[154:155], v[142:143]
	v_pk_fma_f32 v[142:143], v[140:141], s[34:35], v[148:149] op_sel_hi:[1,0,0] neg_lo:[1,0,0] neg_hi:[1,0,0]
	v_pk_mul_f32 v[132:133], v[132:133], 0.5 op_sel_hi:[1,0]
	v_pk_fma_f32 v[142:143], v[140:141], v[142:143], s[38:39] op_sel_hi:[1,1,0]
	s_mov_b64 s[0:1], 0
	v_pk_fma_f32 v[142:143], v[140:141], v[142:143], s[40:41] op_sel_hi:[1,1,0]
	s_nop 0
	v_pk_fma_f32 v[142:143], v[140:141], v[142:143], s[42:43] op_sel_hi:[1,1,0]
	s_nop 0
	v_pk_fma_f32 v[142:143], v[140:141], v[142:143], s[44:45] op_sel_hi:[1,1,0]
	s_nop 0
	v_pk_fma_f32 v[142:143], v[140:141], v[142:143], s[46:47] op_sel_hi:[1,1,0]
	s_nop 0
	v_pk_fma_f32 v[140:141], v[140:141], v[142:143], s[48:49] op_sel_hi:[1,1,0]
	s_nop 0
	v_pk_mul_f32 v[136:137], v[136:137], v[140:141]
	s_nop 0
	v_pk_fma_f32 v[132:133], v[132:133], v[136:137], v[132:133]
	s_nop 0
	v_mul_f32_e32 v132, v36, v132
	v_mul_f32_e32 v140, v2, v132
	v_mul_f32_e32 v132, v37, v133
	v_mul_f32_e32 v141, v2, v132
	v_lshlrev_b32_e32 v132, 16, v151
	v_and_b32_e32 v133, 0xffff0000, v151
	v_pk_fma_f32 v[132:133], v[134:135], v[132:133], v[138:139]
	s_nop 0
	v_pk_mul_f32 v[134:135], v[132:133], s[30:31] op_sel_hi:[1,0]
	v_pk_mul_f32 v[132:133], v[132:133], 0.5 op_sel_hi:[1,0]
	v_med3_f32 v134, v134, s47, v225
	v_med3_f32 v135, v135, s47, v225
	v_pk_mul_f32 v[136:137], v[134:135], v[134:135]
	s_nop 0
	v_pk_fma_f32 v[138:139], v[136:137], s[34:35], v[148:149] op_sel_hi:[1,0,0] neg_lo:[1,0,0] neg_hi:[1,0,0]
	s_nop 0
	v_pk_fma_f32 v[138:139], v[136:137], v[138:139], s[38:39] op_sel_hi:[1,1,0]
	s_nop 0
	v_pk_fma_f32 v[138:139], v[136:137], v[138:139], s[40:41] op_sel_hi:[1,1,0]
	s_nop 0
	v_pk_fma_f32 v[138:139], v[136:137], v[138:139], s[42:43] op_sel_hi:[1,1,0]
	s_nop 0
	v_pk_fma_f32 v[138:139], v[136:137], v[138:139], s[44:45] op_sel_hi:[1,1,0]
	s_nop 0
	v_pk_fma_f32 v[138:139], v[136:137], v[138:139], s[46:47] op_sel_hi:[1,1,0]
	s_nop 0
	v_pk_fma_f32 v[136:137], v[136:137], v[138:139], s[48:49] op_sel_hi:[1,1,0]
	s_nop 0
	v_pk_mul_f32 v[134:135], v[134:135], v[136:137]
	s_nop 0
	v_pk_fma_f32 v[132:133], v[132:133], v[134:135], v[132:133]
	s_nop 0
	v_mul_f32_e32 v132, v38, v132
	v_mul_f32_e32 v134, v2, v132
	v_mul_f32_e32 v132, v39, v133
	v_mul_f32_e32 v133, v2, v132
	v_cvt_pk_bf16_f32 v132, v140, v141
	v_cvt_pk_bf16_f32 v133, v134, v133
	global_store_dwordx2 v[158:159], v[132:133], off nt

; __device__ __forceinline__ unsigned cvt_pk_bf16(float lo, float hi) { unsigned r; asm volatile("v_cvt_pk_bf16_f32 %0, %1, %2" : "=v"(r) : "v"(lo), "v"(hi)); return r; }
;     static __device__ __forceinline__ void unpk4(const u32x2 w, float (&o)[4]) { o[0] = bf_lo(w.x); o[1] = bf_hi(w.x); o[2] = bf_lo(w.y); o[3] = bf_hi(w.y); }
;     template <int N> static __device__ __forceinline__ u32x2 dpp_prev(const u32x2 pv, const u32x2 cur) { u32x2 r; r.x = dpp_prev1<N>(pv.x, cur.x); r.y = dpp_prev1<N>(pv.y, cur.y); return r; }
;     static __device__ __forceinline__ u32x2 finish2(const float (&g0)[4], const float (&g1)[4], const float (&g2)[4], const float (&w0)[4], const float (&w1)[4], const float (&w2)[4], const float (&bb)[4],
;                                                     const f32x4 v, float rs) {
;         float h[4];
; #pragma unroll
;         for (int j = 0; j < 4; j += 2) {
;             const f32x2 gc = (f32x2){bb[j] + w0[j] * g2[j] + w1[j] * g1[j] + w2[j] * g0[j], bb[j + 1] + w0[j + 1] * g2[j + 1] + w1[j + 1] * g1[j + 1] + w2[j + 1] * g0[j + 1]};
;             const f32x2 ge = gelu_pk(gc) * ((f32x2){v[j], v[j + 1]} * rs); h[j] = ge.x; h[j + 1] = ge.y; }
;         u32x2 w; w.x = cvt_pk_bf16(h[0], h[1]); w.y = cvt_pk_bf16(h[2], h[3]); return w;
;     __device__ __forceinline__ void operator()(const f32x4 (&acc)[2][2][4][2], const Unit& u, int wr, int wc, int fr, int fq) const {
;     ...
;                 for (int m = 0; m < 4; ++m) { const u32x4 cur = gq[m]; u32x4 hw;
; #pragma unroll
;                     for (int hv = 0; hv < 2; ++hv) { const u32x2 c2 = half2(cur, hv), p2 = half2(pv, hv);
;                         const u32x2 q1 = dpp_prev<1>(p2, c2), q2 = dpp_prev<2>(p2, c2);
;                         float g0[4], g1[4], g2[4]; unpk4(c2, g0); unpk4(q1, g1); unpk4(q2, g2);
;                         const u32x2 r = finish2(g0, g1, g2, w0[hv], w1[hv], w2[hv], bb[hv], acc[ai][bj][m][hv], rs8[ai][m]);
;                         if (hv == 0) { hw.x = r.x; hw.y = r.y; } else { hw.z = r.x; hw.w = r.y; } }
;                     *(u32x4*)(H + (size_t)(R0 + fr + 16 * m) * 2816 + col8) = hw;
.LBB0_1013:
	s_waitcnt vmcnt(0)
	v_mov_b32_dpp v195, v180 row_ror:2 row_mask:0xf bank_mask:0xf bound_ctrl:1
	v_mov_b32_dpp v191, v180 row_ror:1 row_mask:0xf bank_mask:0xf bound_ctrl:1
	v_mad_i64_i32 v[230:231], s[8:9], v210, s91, 0
	v_mov_b32_dpp v195, v176 row_shr:2 row_mask:0xf bank_mask:0xf
	v_mov_b32_dpp v191, v176 row_shr:1 row_mask:0xf bank_mask:0xf
	v_lshlrev_b32_e32 v210, 16, v195
	v_and_b32_e32 v211, 0xffff0000, v195
	v_mov_b32_dpp v193, v181 row_ror:1 row_mask:0xf bank_mask:0xf bound_ctrl:1
	v_mov_b32_dpp v229, v181 row_ror:2 row_mask:0xf bank_mask:0xf bound_ctrl:1
	v_lshlrev_b32_e32 v180, 16, v191
	v_and_b32_e32 v181, 0xffff0000, v191
	v_pk_fma_f32 v[210:211], v[148:149], v[210:211], v[160:161]
	v_lshlrev_b32_e32 v232, 16, v176
	v_and_b32_e32 v233, 0xffff0000, v176
	v_pk_fma_f32 v[180:181], v[152:153], v[180:181], v[210:211]
	v_mov_b32_dpp v229, v177 row_shr:2 row_mask:0xf bank_mask:0xf
	v_pk_fma_f32 v[180:181], v[156:157], v[232:233], v[180:181]
	v_mov_b32_dpp v193, v177 row_shr:1 row_mask:0xf bank_mask:0xf
	v_pk_mul_f32 v[210:211], v[180:181], s[30:31] op_sel_hi:[1,0]
	v_lshlrev_b32_e32 v228, 16, v229
	v_med3_f32 v232, v210, s47, v225
	v_med3_f32 v233, v211, s47, v225
	v_pk_mul_f32 v[234:235], v[232:233], v[232:233]
	v_mov_b64_e32 v[210:211], s[36:37]
	v_pk_fma_f32 v[236:237], v[234:235], s[34:35], v[210:211] op_sel_hi:[1,0,0] neg_lo:[1,0,0] neg_hi:[1,0,0]
	v_and_b32_e32 v229, 0xffff0000, v229
	v_pk_fma_f32 v[236:237], v[234:235], v[236:237], s[38:39] op_sel_hi:[1,1,0]
	v_pk_mul_f32 v[180:181], v[180:181], 0.5 op_sel_hi:[1,0]
	v_pk_fma_f32 v[236:237], v[234:235], v[236:237], s[40:41] op_sel_hi:[1,1,0]
	v_lshlrev_b32_e32 v226, 16, v193
	v_pk_fma_f32 v[236:237], v[234:235], v[236:237], s[42:43] op_sel_hi:[1,1,0]
	v_and_b32_e32 v227, 0xffff0000, v193
	v_pk_fma_f32 v[236:237], v[234:235], v[236:237], s[44:45] op_sel_hi:[1,1,0]
	v_pk_mul_f32 v[128:129], v[128:129], v[188:189] op_sel_hi:[1,0]
	v_pk_fma_f32 v[236:237], v[234:235], v[236:237], s[46:47] op_sel_hi:[1,1,0]
	v_pk_fma_f32 v[228:229], v[150:151], v[228:229], v[162:163]
	v_pk_fma_f32 v[234:235], v[234:235], v[236:237], s[48:49] op_sel_hi:[1,1,0]
	v_pk_fma_f32 v[226:227], v[154:155], v[226:227], v[228:229]
	v_pk_mul_f32 v[232:233], v[232:233], v[234:235]
	v_pk_mul_f32 v[130:131], v[130:131], v[188:189] op_sel_hi:[1,0]
	v_pk_fma_f32 v[180:181], v[180:181], v[232:233], v[180:181]
	v_pk_mul_f32 v[124:125], v[124:125], v[188:189] op_sel_hi:[1,0]
	v_pk_mul_f32 v[128:129], v[128:129], v[180:181]
	v_lshlrev_b32_e32 v180, 16, v177
	v_and_b32_e32 v181, 0xffff0000, v177
	v_pk_fma_f32 v[180:181], v[158:159], v[180:181], v[226:227]
	v_readlane_b32 s8, v240, 58
	v_pk_mul_f32 v[226:227], v[180:181], s[30:31] op_sel_hi:[1,0]
	v_pk_mul_f32 v[180:181], v[180:181], 0.5 op_sel_hi:[1,0]
	v_med3_f32 v226, v226, s47, v225
	v_med3_f32 v227, v227, s47, v225
	v_pk_mul_f32 v[228:229], v[226:227], v[226:227]
	v_readlane_b32 s9, v240, 59
	v_pk_fma_f32 v[232:233], v[228:229], s[34:35], v[210:211] op_sel_hi:[1,0,0] neg_lo:[1,0,0] neg_hi:[1,0,0]
	v_pk_mul_f32 v[126:127], v[126:127], v[188:189] op_sel_hi:[1,0]
	v_pk_fma_f32 v[232:233], v[228:229], v[232:233], s[38:39] op_sel_hi:[1,1,0]
	v_pk_mul_f32 v[120:121], v[120:121], v[186:187] op_sel_hi:[1,0]
	v_pk_fma_f32 v[232:233], v[228:229], v[232:233], s[40:41] op_sel_hi:[1,1,0]
	v_pk_mul_f32 v[122:123], v[122:123], v[186:187] op_sel_hi:[1,0]
	v_pk_fma_f32 v[232:233], v[228:229], v[232:233], s[42:43] op_sel_hi:[1,1,0]
	v_pk_mul_f32 v[116:117], v[116:117], v[186:187] op_sel_hi:[1,0]
	v_pk_fma_f32 v[232:233], v[228:229], v[232:233], s[44:45] op_sel_hi:[1,1,0]
	v_pk_mul_f32 v[118:119], v[118:119], v[186:187] op_sel_hi:[1,0]
	v_pk_fma_f32 v[232:233], v[228:229], v[232:233], s[46:47] op_sel_hi:[1,1,0]
	v_pk_mul_f32 v[112:113], v[112:113], v[184:185] op_sel_hi:[1,0]
	v_pk_fma_f32 v[228:229], v[228:229], v[232:233], s[48:49] op_sel_hi:[1,1,0]
	v_pk_mul_f32 v[114:115], v[114:115], v[184:185] op_sel_hi:[1,0]
	v_pk_mul_f32 v[226:227], v[226:227], v[228:229]
	v_lshlrev_b32_e32 v228, 16, v178
	v_pk_fma_f32 v[180:181], v[180:181], v[226:227], v[180:181]
	v_cvt_pk_bf16_f32 v226, v128, v129
	v_mov_b32_dpp v129, v182 row_ror:1 row_mask:0xf bank_mask:0xf bound_ctrl:1
	v_pk_mul_f32 v[130:131], v[130:131], v[180:181]
	v_mov_b32_dpp v181, v182 row_ror:2 row_mask:0xf bank_mask:0xf bound_ctrl:1
	v_mov_b32_dpp v129, v178 row_shr:1 row_mask:0xf bank_mask:0xf
	v_lshlrev_b32_e32 v128, 16, v129
	v_mov_b32_dpp v181, v178 row_shr:2 row_mask:0xf bank_mask:0xf
	v_lshlrev_b32_e32 v180, 16, v181
	v_and_b32_e32 v181, 0xffff0000, v181
	v_and_b32_e32 v129, 0xffff0000, v129
	v_pk_fma_f32 v[180:181], v[132:133], v[180:181], v[144:145]
	v_and_b32_e32 v229, 0xffff0000, v178
	v_pk_fma_f32 v[128:129], v[136:137], v[128:129], v[180:181]
	v_cvt_pk_bf16_f32 v227, v130, v131
	v_mov_b32_dpp v131, v183 row_ror:1 row_mask:0xf bank_mask:0xf bound_ctrl:1
	v_pk_fma_f32 v[128:129], v[140:141], v[228:229], v[128:129]
	v_mov_b32_dpp v183, v183 row_ror:2 row_mask:0xf bank_mask:0xf bound_ctrl:1
	v_pk_mul_f32 v[180:181], v[128:129], s[30:31] op_sel_hi:[1,0]
	v_mov_b32_dpp v131, v179 row_shr:1 row_mask:0xf bank_mask:0xf
	v_med3_f32 v180, v180, s47, v225
	v_med3_f32 v181, v181, s47, v225
	v_pk_mul_f32 v[228:229], v[180:181], v[180:181]
	v_mov_b32_dpp v183, v179 row_shr:2 row_mask:0xf bank_mask:0xf
	v_pk_fma_f32 v[232:233], v[228:229], s[34:35], v[210:211] op_sel_hi:[1,0,0] neg_lo:[1,0,0] neg_hi:[1,0,0]
	v_lshlrev_b32_e32 v182, 16, v183
	v_pk_fma_f32 v[232:233], v[228:229], v[232:233], s[38:39] op_sel_hi:[1,1,0]
	v_and_b32_e32 v183, 0xffff0000, v183
	v_pk_fma_f32 v[232:233], v[228:229], v[232:233], s[40:41] op_sel_hi:[1,1,0]
; __device__ __forceinline__ unsigned cvt_pk_bf16(float lo, float hi) { unsigned r; asm volatile("v_cvt_pk_bf16_f32 %0, %1, %2" : "=v"(r) : "v"(lo), "v"(hi)); return r; }
;     static __device__ __forceinline__ void unpk4(const u32x2 w, float (&o)[4]) { o[0] = bf_lo(w.x); o[1] = bf_hi(w.x); o[2] = bf_lo(w.y); o[3] = bf_hi(w.y); }
;     template <int N> static __device__ __forceinline__ u32x2 dpp_prev(const u32x2 pv, const u32x2 cur) { u32x2 r; r.x = dpp_prev1<N>(pv.x, cur.x); r.y = dpp_prev1<N>(pv.y, cur.y); return r; }
;     static __device__ __forceinline__ u32x2 finish2(const float (&g0)[4], const float (&g1)[4], const float (&g2)[4], const float (&w0)[4], const float (&w1)[4], const float (&w2)[4], const float (&bb)[4],
;                                                     const f32x4 v, float rs) {
;         float h[4];
; #pragma unroll
;         for (int j = 0; j < 4; j += 2) {
;             const f32x2 gc = (f32x2){bb[j] + w0[j] * g2[j] + w1[j] * g1[j] + w2[j] * g0[j], bb[j + 1] + w0[j + 1] * g2[j + 1] + w1[j + 1] * g1[j + 1] + w2[j + 1] * g0[j + 1]};
;             const f32x2 ge = gelu_pk(gc) * ((f32x2){v[j], v[j + 1]} * rs); h[j] = ge.x; h[j + 1] = ge.y; }
;         u32x2 w; w.x = cvt_pk_bf16(h[0], h[1]); w.y = cvt_pk_bf16(h[2], h[3]); return w;
;     __device__ __forceinline__ void operator()(const f32x4 (&acc)[2][2][4][2], const Unit& u, int wr, int wc, int fr, int fq) const {
;     ...
;                 for (int m = 0; m < 4; ++m) { const u32x4 cur = gq[m]; u32x4 hw;
; #pragma unroll
;                     for (int hv = 0; hv < 2; ++hv) { const u32x2 c2 = half2(cur, hv), p2 = half2(pv, hv);
;                         const u32x2 q1 = dpp_prev<1>(p2, c2), q2 = dpp_prev<2>(p2, c2);
;                         float g0[4], g1[4], g2[4]; unpk4(c2, g0); unpk4(q1, g1); unpk4(q2, g2);
;                         const u32x2 r = finish2(g0, g1, g2, w0[hv], w1[hv], w2[hv], bb[hv], acc[ai][bj][m][hv], rs8[ai][m]);
;                         if (hv == 0) { hw.x = r.x; hw.y = r.y; } else { hw.z = r.x; hw.w = r.y; } }
;                     *(u32x4*)(H + (size_t)(R0 + fr + 16 * m) * 2816 + col8) = hw;
	v_pk_mul_f32 v[128:129], v[128:129], 0.5 op_sel_hi:[1,0]
	v_pk_fma_f32 v[232:233], v[228:229], v[232:233], s[42:43] op_sel_hi:[1,1,0]
	v_lshlrev_b32_e32 v130, 16, v131
	v_pk_fma_f32 v[232:233], v[228:229], v[232:233], s[44:45] op_sel_hi:[1,1,0]
	v_and_b32_e32 v131, 0xffff0000, v131
	v_pk_fma_f32 v[232:233], v[228:229], v[232:233], s[46:47] op_sel_hi:[1,1,0]
	v_pk_mul_f32 v[108:109], v[108:109], v[184:185] op_sel_hi:[1,0]
	v_pk_fma_f32 v[228:229], v[228:229], v[232:233], s[48:49] op_sel_hi:[1,1,0]
	v_pk_mul_f32 v[110:111], v[110:111], v[184:185] op_sel_hi:[1,0]
	v_pk_mul_f32 v[180:181], v[180:181], v[228:229]
	v_pk_mul_f32 v[104:105], v[104:105], v[2:3] op_sel_hi:[1,0]
	v_pk_fma_f32 v[128:129], v[128:129], v[180:181], v[128:129]
	v_pk_fma_f32 v[180:181], v[134:135], v[182:183], v[146:147]
	v_pk_mul_f32 v[124:125], v[124:125], v[128:129]
	v_lshlrev_b32_e32 v128, 16, v179
	v_and_b32_e32 v129, 0xffff0000, v179
	v_pk_fma_f32 v[130:131], v[138:139], v[130:131], v[180:181]
	v_cvt_pk_bf16_f32 v228, v124, v125
	v_pk_mul_f32 v[106:107], v[106:107], v[2:3] op_sel_hi:[1,0]
	v_pk_fma_f32 v[128:129], v[142:143], v[128:129], v[130:131]
	v_pk_mul_f32 v[100:101], v[100:101], v[2:3] op_sel_hi:[1,0]
	v_pk_mul_f32 v[130:131], v[128:129], s[30:31] op_sel_hi:[1,0]
	v_pk_mul_f32 v[128:129], v[128:129], 0.5 op_sel_hi:[1,0]
	v_med3_f32 v130, v130, s47, v225
	v_med3_f32 v131, v131, s47, v225
	v_pk_mul_f32 v[180:181], v[130:131], v[130:131]
	s_add_i32 s7, s2, 0x80
	v_pk_fma_f32 v[182:183], v[180:181], s[34:35], v[210:211] op_sel_hi:[1,0,0] neg_lo:[1,0,0] neg_hi:[1,0,0]
	v_readlane_b32 s2, v240, 12
	v_pk_fma_f32 v[182:183], v[180:181], v[182:183], s[38:39] op_sel_hi:[1,1,0]
	v_readlane_b32 s3, v240, 13
	v_pk_fma_f32 v[182:183], v[180:181], v[182:183], s[40:41] op_sel_hi:[1,1,0]
	v_add_u32_e32 v1, s7, v1
	v_pk_fma_f32 v[182:183], v[180:181], v[182:183], s[42:43] op_sel_hi:[1,1,0]
	v_pk_mul_f32 v[102:103], v[102:103], v[2:3] op_sel_hi:[1,0]
	v_pk_fma_f32 v[182:183], v[180:181], v[182:183], s[44:45] op_sel_hi:[1,1,0]
	s_and_b32 s7, s7, 0x1fff
	v_pk_fma_f32 v[182:183], v[180:181], v[182:183], s[46:47] op_sel_hi:[1,1,0]
	s_cmp_lg_u32 s7, 0
	v_pk_fma_f32 v[180:181], v[180:181], v[182:183], s[48:49] op_sel_hi:[1,1,0]
	v_lshlrev_b32_e32 v182, 16, v172
	v_pk_mul_f32 v[130:131], v[130:131], v[180:181]
	v_lshlrev_b64 v[180:181], 1, v[212:213]
	v_pk_fma_f32 v[128:129], v[128:129], v[130:131], v[128:129]
	v_lshl_add_u64 v[130:131], s[8:9], 0, v[230:231]
	v_pk_mul_f32 v[126:127], v[126:127], v[128:129]
	v_lshl_add_u64 v[124:125], v[130:131], 0, v[180:181]
	v_mov_b32_dpp v129, v176 row_ror:2 row_mask:0xf bank_mask:0xf bound_ctrl:1
	v_cvt_pk_bf16_f32 v229, v126, v127
	global_store_dwordx4 v[124:125], v[226:229], off nt
	v_mov_b32_dpp v125, v176 row_ror:1 row_mask:0xf bank_mask:0xf bound_ctrl:1
	v_mov_b32_dpp v129, v172 row_shr:2 row_mask:0xf bank_mask:0xf
	v_lshlrev_b32_e32 v128, 16, v129
	v_mov_b32_dpp v125, v172 row_shr:1 row_mask:0xf bank_mask:0xf
	v_and_b32_e32 v129, 0xffff0000, v129
	v_lshlrev_b32_e32 v124, 16, v125
	v_and_b32_e32 v125, 0xffff0000, v125
	v_pk_fma_f32 v[128:129], v[148:149], v[128:129], v[160:161]
	v_and_b32_e32 v183, 0xffff0000, v172
	v_pk_fma_f32 v[124:125], v[152:153], v[124:125], v[128:129]
	v_mov_b32_dpp v127, v177 row_ror:1 row_mask:0xf bank_mask:0xf bound_ctrl:1
	v_pk_fma_f32 v[124:125], v[156:157], v[182:183], v[124:125]
	v_mov_b32_dpp v177, v177 row_ror:2 row_mask:0xf bank_mask:0xf bound_ctrl:1
	v_pk_mul_f32 v[128:129], v[124:125], s[30:31] op_sel_hi:[1,0]
	v_mov_b32_dpp v127, v173 row_shr:1 row_mask:0xf bank_mask:0xf
	v_med3_f32 v128, v128, s47, v225
	v_med3_f32 v129, v129, s47, v225
	v_pk_mul_f32 v[182:183], v[128:129], v[128:129]
	v_mov_b32_dpp v177, v173 row_shr:2 row_mask:0xf bank_mask:0xf
	v_pk_fma_f32 v[226:227], v[182:183], s[34:35], v[210:211] op_sel_hi:[1,0,0] neg_lo:[1,0,0] neg_hi:[1,0,0]
	v_lshlrev_b32_e32 v176, 16, v177
	v_pk_fma_f32 v[226:227], v[182:183], v[226:227], s[38:39] op_sel_hi:[1,1,0]
	v_and_b32_e32 v177, 0xffff0000, v177
	v_pk_fma_f32 v[226:227], v[182:183], v[226:227], s[40:41] op_sel_hi:[1,1,0]
	v_pk_mul_f32 v[124:125], v[124:125], 0.5 op_sel_hi:[1,0]
	v_pk_fma_f32 v[226:227], v[182:183], v[226:227], s[42:43] op_sel_hi:[1,1,0]
	v_lshlrev_b32_e32 v126, 16, v127
	v_pk_fma_f32 v[226:227], v[182:183], v[226:227], s[44:45] op_sel_hi:[1,1,0]
	v_and_b32_e32 v127, 0xffff0000, v127
	v_pk_fma_f32 v[226:227], v[182:183], v[226:227], s[46:47] op_sel_hi:[1,1,0]
	s_nop 0
	v_pk_fma_f32 v[182:183], v[182:183], v[226:227], s[48:49] op_sel_hi:[1,1,0]
	s_nop 0
	v_pk_mul_f32 v[128:129], v[128:129], v[182:183]
	s_nop 0
	v_pk_fma_f32 v[124:125], v[124:125], v[128:129], v[124:125]
	v_pk_fma_f32 v[128:129], v[150:151], v[176:177], v[162:163]
	v_pk_mul_f32 v[120:121], v[120:121], v[124:125]
	v_lshlrev_b32_e32 v124, 16, v173
	v_and_b32_e32 v125, 0xffff0000, v173
	v_pk_fma_f32 v[126:127], v[154:155], v[126:127], v[128:129]
	v_cvt_pk_bf16_f32 v120, v120, v121
	s_nop 0
	v_pk_fma_f32 v[124:125], v[158:159], v[124:125], v[126:127]
	s_nop 0
	v_pk_mul_f32 v[126:127], v[124:125], s[30:31] op_sel_hi:[1,0]
	v_pk_mul_f32 v[124:125], v[124:125], 0.5 op_sel_hi:[1,0]
	v_med3_f32 v126, v126, s47, v225
	v_med3_f32 v127, v127, s47, v225
	v_pk_mul_f32 v[128:129], v[126:127], v[126:127]
	s_nop 0
	v_pk_fma_f32 v[176:177], v[128:129], s[34:35], v[210:211] op_sel_hi:[1,0,0] neg_lo:[1,0,0] neg_hi:[1,0,0]
	s_nop 0
	v_pk_fma_f32 v[176:177], v[128:129], v[176:177], s[38:39] op_sel_hi:[1,1,0]
	s_nop 0
	v_pk_fma_f32 v[176:177], v[128:129], v[176:177], s[40:41] op_sel_hi:[1,1,0]
	s_nop 0
	v_pk_fma_f32 v[176:177], v[128:129], v[176:177], s[42:43] op_sel_hi:[1,1,0]
	s_nop 0
; __device__ __forceinline__ unsigned cvt_pk_bf16(float lo, float hi) { unsigned r; asm volatile("v_cvt_pk_bf16_f32 %0, %1, %2" : "=v"(r) : "v"(lo), "v"(hi)); return r; }
;     static __device__ __forceinline__ void unpk4(const u32x2 w, float (&o)[4]) { o[0] = bf_lo(w.x); o[1] = bf_hi(w.x); o[2] = bf_lo(w.y); o[3] = bf_hi(w.y); }
;     template <int N> static __device__ __forceinline__ u32x2 dpp_prev(const u32x2 pv, const u32x2 cur) { u32x2 r; r.x = dpp_prev1<N>(pv.x, cur.x); r.y = dpp_prev1<N>(pv.y, cur.y); return r; }
;     static __device__ __forceinline__ u32x2 finish2(const float (&g0)[4], const float (&g1)[4], const float (&g2)[4], const float (&w0)[4], const float (&w1)[4], const float (&w2)[4], const float (&bb)[4],
;                                                     const f32x4 v, float rs) {
;         float h[4];
; #pragma unroll
;         for (int j = 0; j < 4; j += 2) {
;             const f32x2 gc = (f32x2){bb[j] + w0[j] * g2[j] + w1[j] * g1[j] + w2[j] * g0[j], bb[j + 1] + w0[j + 1] * g2[j + 1] + w1[j + 1] * g1[j + 1] + w2[j + 1] * g0[j + 1]};
;             const f32x2 ge = gelu_pk(gc) * ((f32x2){v[j], v[j + 1]} * rs); h[j] = ge.x; h[j + 1] = ge.y; }
;         u32x2 w; w.x = cvt_pk_bf16(h[0], h[1]); w.y = cvt_pk_bf16(h[2], h[3]); return w;
;     __device__ __forceinline__ void operator()(const f32x4 (&acc)[2][2][4][2], const Unit& u, int wr, int wc, int fr, int fq) const {
;     ...
;                 for (int m = 0; m < 4; ++m) { const u32x4 cur = gq[m]; u32x4 hw;
; #pragma unroll
;                     for (int hv = 0; hv < 2; ++hv) { const u32x2 c2 = half2(cur, hv), p2 = half2(pv, hv);
;                         const u32x2 q1 = dpp_prev<1>(p2, c2), q2 = dpp_prev<2>(p2, c2);
;                         float g0[4], g1[4], g2[4]; unpk4(c2, g0); unpk4(q1, g1); unpk4(q2, g2);
;                         const u32x2 r = finish2(g0, g1, g2, w0[hv], w1[hv], w2[hv], bb[hv], acc[ai][bj][m][hv], rs8[ai][m]);
;                         if (hv == 0) { hw.x = r.x; hw.y = r.y; } else { hw.z = r.x; hw.w = r.y; } }
;                     *(u32x4*)(H + (size_t)(R0 + fr + 16 * m) * 2816 + col8) = hw;
	v_pk_fma_f32 v[176:177], v[128:129], v[176:177], s[44:45] op_sel_hi:[1,1,0]
	s_nop 0
	v_pk_fma_f32 v[176:177], v[128:129], v[176:177], s[46:47] op_sel_hi:[1,1,0]
	s_nop 0
	v_pk_fma_f32 v[128:129], v[128:129], v[176:177], s[48:49] op_sel_hi:[1,1,0]
	v_lshlrev_b32_e32 v176, 16, v174
	v_pk_mul_f32 v[126:127], v[126:127], v[128:129]
	v_and_b32_e32 v177, 0xffff0000, v174
	v_pk_fma_f32 v[124:125], v[124:125], v[126:127], v[124:125]
	v_mov_b32_dpp v127, v178 row_ror:2 row_mask:0xf bank_mask:0xf bound_ctrl:1
	v_pk_mul_f32 v[122:123], v[122:123], v[124:125]
	v_mov_b32_dpp v125, v179 row_ror:1 row_mask:0xf bank_mask:0xf bound_ctrl:1
	v_cvt_pk_bf16_f32 v121, v122, v123
	v_mov_b32_dpp v127, v174 row_shr:2 row_mask:0xf bank_mask:0xf
	v_mov_b32_dpp v123, v178 row_ror:1 row_mask:0xf bank_mask:0xf bound_ctrl:1
	v_lshlrev_b32_e32 v126, 16, v127
	v_and_b32_e32 v127, 0xffff0000, v127
	v_mov_b32_dpp v123, v174 row_shr:1 row_mask:0xf bank_mask:0xf
	v_lshlrev_b32_e32 v122, 16, v123
	v_and_b32_e32 v123, 0xffff0000, v123
	v_pk_fma_f32 v[126:127], v[132:133], v[126:127], v[144:145]
	v_mov_b32_dpp v129, v179 row_ror:2 row_mask:0xf bank_mask:0xf bound_ctrl:1
	v_pk_fma_f32 v[122:123], v[136:137], v[122:123], v[126:127]
	v_mov_b32_dpp v125, v175 row_shr:1 row_mask:0xf bank_mask:0xf
	v_pk_fma_f32 v[122:123], v[140:141], v[176:177], v[122:123]
	v_mov_b32_dpp v129, v175 row_shr:2 row_mask:0xf bank_mask:0xf
	v_pk_mul_f32 v[126:127], v[122:123], s[30:31] op_sel_hi:[1,0]
	v_lshlrev_b32_e32 v128, 16, v129
	v_med3_f32 v126, v126, s47, v225
	v_med3_f32 v127, v127, s47, v225
	v_pk_mul_f32 v[176:177], v[126:127], v[126:127]
	v_and_b32_e32 v129, 0xffff0000, v129
	v_pk_fma_f32 v[178:179], v[176:177], s[34:35], v[210:211] op_sel_hi:[1,0,0] neg_lo:[1,0,0] neg_hi:[1,0,0]
	v_pk_mul_f32 v[122:123], v[122:123], 0.5 op_sel_hi:[1,0]
	v_pk_fma_f32 v[178:179], v[176:177], v[178:179], s[38:39] op_sel_hi:[1,1,0]
	v_lshlrev_b32_e32 v124, 16, v125
	v_pk_fma_f32 v[178:179], v[176:177], v[178:179], s[40:41] op_sel_hi:[1,1,0]
	v_and_b32_e32 v125, 0xffff0000, v125
	v_pk_fma_f32 v[178:179], v[176:177], v[178:179], s[42:43] op_sel_hi:[1,1,0]
	s_nop 0
	v_pk_fma_f32 v[178:179], v[176:177], v[178:179], s[44:45] op_sel_hi:[1,1,0]
	s_nop 0
	v_pk_fma_f32 v[178:179], v[176:177], v[178:179], s[46:47] op_sel_hi:[1,1,0]
	s_nop 0
	v_pk_fma_f32 v[176:177], v[176:177], v[178:179], s[48:49] op_sel_hi:[1,1,0]
	s_nop 0
	v_pk_mul_f32 v[126:127], v[126:127], v[176:177]
	s_nop 0
	v_pk_fma_f32 v[122:123], v[122:123], v[126:127], v[122:123]
	v_pk_fma_f32 v[126:127], v[134:135], v[128:129], v[146:147]
	v_pk_mul_f32 v[116:117], v[116:117], v[122:123]
	v_lshlrev_b32_e32 v122, 16, v175
	v_and_b32_e32 v123, 0xffff0000, v175
	v_pk_fma_f32 v[124:125], v[138:139], v[124:125], v[126:127]
	s_nop 0
	v_pk_fma_f32 v[122:123], v[142:143], v[122:123], v[124:125]
	s_nop 0
	v_pk_mul_f32 v[124:125], v[122:123], s[30:31] op_sel_hi:[1,0]
	v_pk_mul_f32 v[122:123], v[122:123], 0.5 op_sel_hi:[1,0]
	v_med3_f32 v124, v124, s47, v225
	v_med3_f32 v125, v125, s47, v225
	v_pk_mul_f32 v[126:127], v[124:125], v[124:125]
	s_nop 0
	v_pk_fma_f32 v[128:129], v[126:127], s[34:35], v[210:211] op_sel_hi:[1,0,0] neg_lo:[1,0,0] neg_hi:[1,0,0]
	s_nop 0
	v_pk_fma_f32 v[128:129], v[126:127], v[128:129], s[38:39] op_sel_hi:[1,1,0]
	s_nop 0
	v_pk_fma_f32 v[128:129], v[126:127], v[128:129], s[40:41] op_sel_hi:[1,1,0]
	s_nop 0
	v_pk_fma_f32 v[128:129], v[126:127], v[128:129], s[42:43] op_sel_hi:[1,1,0]
	s_nop 0
	v_pk_fma_f32 v[128:129], v[126:127], v[128:129], s[44:45] op_sel_hi:[1,1,0]
	s_nop 0
	v_pk_fma_f32 v[128:129], v[126:127], v[128:129], s[46:47] op_sel_hi:[1,1,0]
	s_nop 0
	v_pk_fma_f32 v[126:127], v[126:127], v[128:129], s[48:49] op_sel_hi:[1,1,0]
	s_nop 0
	v_pk_mul_f32 v[124:125], v[124:125], v[126:127]
	v_lshlrev_b32_e32 v126, 16, v168
	v_pk_fma_f32 v[122:123], v[122:123], v[124:125], v[122:123]
	v_and_b32_e32 v127, 0xffff0000, v168
	v_pk_mul_f32 v[118:119], v[118:119], v[122:123]
	v_cvt_pk_bf16_f32 v122, v116, v117
	v_mov_b64_e32 v[116:117], s[8:9]
	v_mad_i64_i32 v[176:177], s[8:9], v194, s91, v[116:117]
	v_cvt_pk_bf16_f32 v123, v118, v119
	v_lshl_add_u64 v[118:119], v[176:177], 0, v[180:181]
	global_store_dwordx4 v[118:119], v[120:123], off nt
	v_mov_b32_dpp v125, v173 row_ror:2 row_mask:0xf bank_mask:0xf bound_ctrl:1
	v_mov_b32_dpp v119, v172 row_ror:1 row_mask:0xf bank_mask:0xf bound_ctrl:1
	v_mov_b32_dpp v123, v172 row_ror:2 row_mask:0xf bank_mask:0xf bound_ctrl:1
	v_mov_b32_dpp v121, v173 row_ror:1 row_mask:0xf bank_mask:0xf bound_ctrl:1
	v_mov_b32_dpp v119, v168 row_shr:1 row_mask:0xf bank_mask:0xf
	v_mov_b32_dpp v123, v168 row_shr:2 row_mask:0xf bank_mask:0xf
	v_lshlrev_b32_e32 v122, 16, v123
	v_and_b32_e32 v123, 0xffff0000, v123
	v_lshlrev_b32_e32 v118, 16, v119
	v_and_b32_e32 v119, 0xffff0000, v119
	v_pk_fma_f32 v[122:123], v[148:149], v[122:123], v[160:161]
	v_mov_b32_dpp v125, v169 row_shr:2 row_mask:0xf bank_mask:0xf
	v_pk_fma_f32 v[118:119], v[152:153], v[118:119], v[122:123]
	v_mov_b32_dpp v121, v169 row_shr:1 row_mask:0xf bank_mask:0xf
	v_pk_fma_f32 v[118:119], v[156:157], v[126:127], v[118:119]
	v_lshlrev_b32_e32 v124, 16, v125
	v_pk_mul_f32 v[122:123], v[118:119], s[30:31] op_sel_hi:[1,0]
	v_and_b32_e32 v125, 0xffff0000, v125
	v_med3_f32 v122, v122, s47, v225
	v_med3_f32 v123, v123, s47, v225
	v_pk_mul_f32 v[126:127], v[122:123], v[122:123]
	v_pk_mul_f32 v[118:119], v[118:119], 0.5 op_sel_hi:[1,0]
	v_pk_fma_f32 v[128:129], v[126:127], s[34:35], v[210:211] op_sel_hi:[1,0,0] neg_lo:[1,0,0] neg_hi:[1,0,0]
	v_lshlrev_b32_e32 v120, 16, v121
	v_pk_fma_f32 v[128:129], v[126:127], v[128:129], s[38:39] op_sel_hi:[1,1,0]
	v_and_b32_e32 v121, 0xffff0000, v121
; __device__ __forceinline__ unsigned cvt_pk_bf16(float lo, float hi) { unsigned r; asm volatile("v_cvt_pk_bf16_f32 %0, %1, %2" : "=v"(r) : "v"(lo), "v"(hi)); return r; }
;     static __device__ __forceinline__ void unpk4(const u32x2 w, float (&o)[4]) { o[0] = bf_lo(w.x); o[1] = bf_hi(w.x); o[2] = bf_lo(w.y); o[3] = bf_hi(w.y); }
;     template <int N> static __device__ __forceinline__ u32x2 dpp_prev(const u32x2 pv, const u32x2 cur) { u32x2 r; r.x = dpp_prev1<N>(pv.x, cur.x); r.y = dpp_prev1<N>(pv.y, cur.y); return r; }
;     static __device__ __forceinline__ u32x2 finish2(const float (&g0)[4], const float (&g1)[4], const float (&g2)[4], const float (&w0)[4], const float (&w1)[4], const float (&w2)[4], const float (&bb)[4],
;                                                     const f32x4 v, float rs) {
;         float h[4];
; #pragma unroll
;         for (int j = 0; j < 4; j += 2) {
;             const f32x2 gc = (f32x2){bb[j] + w0[j] * g2[j] + w1[j] * g1[j] + w2[j] * g0[j], bb[j + 1] + w0[j + 1] * g2[j + 1] + w1[j + 1] * g1[j + 1] + w2[j + 1] * g0[j + 1]};
;             const f32x2 ge = gelu_pk(gc) * ((f32x2){v[j], v[j + 1]} * rs); h[j] = ge.x; h[j + 1] = ge.y; }
;         u32x2 w; w.x = cvt_pk_bf16(h[0], h[1]); w.y = cvt_pk_bf16(h[2], h[3]); return w;
;     __device__ __forceinline__ void operator()(const f32x4 (&acc)[2][2][4][2], const Unit& u, int wr, int wc, int fr, int fq) const {
;     ...
;                 for (int m = 0; m < 4; ++m) { const u32x4 cur = gq[m]; u32x4 hw;
; #pragma unroll
;                     for (int hv = 0; hv < 2; ++hv) { const u32x2 c2 = half2(cur, hv), p2 = half2(pv, hv);
;                         const u32x2 q1 = dpp_prev<1>(p2, c2), q2 = dpp_prev<2>(p2, c2);
;                         float g0[4], g1[4], g2[4]; unpk4(c2, g0); unpk4(q1, g1); unpk4(q2, g2);
;                         const u32x2 r = finish2(g0, g1, g2, w0[hv], w1[hv], w2[hv], bb[hv], acc[ai][bj][m][hv], rs8[ai][m]);
;                         if (hv == 0) { hw.x = r.x; hw.y = r.y; } else { hw.z = r.x; hw.w = r.y; } }
;                     *(u32x4*)(H + (size_t)(R0 + fr + 16 * m) * 2816 + col8) = hw;
	v_pk_fma_f32 v[128:129], v[126:127], v[128:129], s[40:41] op_sel_hi:[1,1,0]
	v_mad_i64_i32 v[172:173], s[8:9], v192, s91, v[116:117]
	v_pk_fma_f32 v[128:129], v[126:127], v[128:129], s[42:43] op_sel_hi:[1,1,0]
	s_nop 0
	v_pk_fma_f32 v[128:129], v[126:127], v[128:129], s[44:45] op_sel_hi:[1,1,0]
	s_nop 0
	v_pk_fma_f32 v[128:129], v[126:127], v[128:129], s[46:47] op_sel_hi:[1,1,0]
	s_nop 0
	v_pk_fma_f32 v[126:127], v[126:127], v[128:129], s[48:49] op_sel_hi:[1,1,0]
	s_nop 0
	v_pk_mul_f32 v[122:123], v[122:123], v[126:127]
	s_nop 0
	v_pk_fma_f32 v[118:119], v[118:119], v[122:123], v[118:119]
	v_pk_fma_f32 v[122:123], v[150:151], v[124:125], v[162:163]
	v_pk_mul_f32 v[112:113], v[112:113], v[118:119]
	v_lshlrev_b32_e32 v118, 16, v169
	v_and_b32_e32 v119, 0xffff0000, v169
	v_pk_fma_f32 v[120:121], v[154:155], v[120:121], v[122:123]
	v_cvt_pk_bf16_f32 v112, v112, v113
	s_nop 0
	v_pk_fma_f32 v[118:119], v[158:159], v[118:119], v[120:121]
	s_nop 0
	v_pk_mul_f32 v[120:121], v[118:119], s[30:31] op_sel_hi:[1,0]
	v_pk_mul_f32 v[118:119], v[118:119], 0.5 op_sel_hi:[1,0]
	v_med3_f32 v120, v120, s47, v225
	v_med3_f32 v121, v121, s47, v225
	v_pk_mul_f32 v[122:123], v[120:121], v[120:121]
	s_nop 0
	v_pk_fma_f32 v[124:125], v[122:123], s[34:35], v[210:211] op_sel_hi:[1,0,0] neg_lo:[1,0,0] neg_hi:[1,0,0]
	s_nop 0
	v_pk_fma_f32 v[124:125], v[122:123], v[124:125], s[38:39] op_sel_hi:[1,1,0]
	s_nop 0
	v_pk_fma_f32 v[124:125], v[122:123], v[124:125], s[40:41] op_sel_hi:[1,1,0]
	s_nop 0
	v_pk_fma_f32 v[124:125], v[122:123], v[124:125], s[42:43] op_sel_hi:[1,1,0]
	s_nop 0
	v_pk_fma_f32 v[124:125], v[122:123], v[124:125], s[44:45] op_sel_hi:[1,1,0]
	s_nop 0
	v_pk_fma_f32 v[124:125], v[122:123], v[124:125], s[46:47] op_sel_hi:[1,1,0]
	s_nop 0
	v_pk_fma_f32 v[122:123], v[122:123], v[124:125], s[48:49] op_sel_hi:[1,1,0]
	v_lshlrev_b32_e32 v124, 16, v170
	v_pk_mul_f32 v[120:121], v[120:121], v[122:123]
	v_and_b32_e32 v125, 0xffff0000, v170
	v_pk_fma_f32 v[118:119], v[118:119], v[120:121], v[118:119]
	v_mov_b32_dpp v121, v174 row_ror:2 row_mask:0xf bank_mask:0xf bound_ctrl:1
	v_pk_mul_f32 v[114:115], v[114:115], v[118:119]
	v_mov_b32_dpp v123, v175 row_ror:2 row_mask:0xf bank_mask:0xf bound_ctrl:1
	v_cvt_pk_bf16_f32 v113, v114, v115
	v_mov_b32_dpp v121, v170 row_shr:2 row_mask:0xf bank_mask:0xf
	v_mov_b32_dpp v115, v174 row_ror:1 row_mask:0xf bank_mask:0xf bound_ctrl:1
	v_lshlrev_b32_e32 v120, 16, v121
	v_and_b32_e32 v121, 0xffff0000, v121
	v_mov_b32_dpp v115, v170 row_shr:1 row_mask:0xf bank_mask:0xf
	v_lshlrev_b32_e32 v114, 16, v115
	v_and_b32_e32 v115, 0xffff0000, v115
	v_pk_fma_f32 v[120:121], v[132:133], v[120:121], v[144:145]
	v_mov_b32_dpp v119, v175 row_ror:1 row_mask:0xf bank_mask:0xf bound_ctrl:1
	v_pk_fma_f32 v[114:115], v[136:137], v[114:115], v[120:121]
	v_mov_b32_dpp v123, v171 row_shr:2 row_mask:0xf bank_mask:0xf
	v_pk_fma_f32 v[114:115], v[140:141], v[124:125], v[114:115]
	v_mov_b32_dpp v119, v171 row_shr:1 row_mask:0xf bank_mask:0xf
	v_pk_mul_f32 v[120:121], v[114:115], s[30:31] op_sel_hi:[1,0]
	v_lshlrev_b32_e32 v122, 16, v123
	v_med3_f32 v120, v120, s47, v225
	v_med3_f32 v121, v121, s47, v225
	v_pk_mul_f32 v[124:125], v[120:121], v[120:121]
	v_and_b32_e32 v123, 0xffff0000, v123
	v_pk_fma_f32 v[126:127], v[124:125], s[34:35], v[210:211] op_sel_hi:[1,0,0] neg_lo:[1,0,0] neg_hi:[1,0,0]
	v_pk_mul_f32 v[114:115], v[114:115], 0.5 op_sel_hi:[1,0]
	v_pk_fma_f32 v[126:127], v[124:125], v[126:127], s[38:39] op_sel_hi:[1,1,0]
	v_lshlrev_b32_e32 v118, 16, v119
	v_pk_fma_f32 v[126:127], v[124:125], v[126:127], s[40:41] op_sel_hi:[1,1,0]
	v_and_b32_e32 v119, 0xffff0000, v119
	v_pk_fma_f32 v[126:127], v[124:125], v[126:127], s[42:43] op_sel_hi:[1,1,0]
	s_nop 0
	v_pk_fma_f32 v[126:127], v[124:125], v[126:127], s[44:45] op_sel_hi:[1,1,0]
	s_nop 0
	v_pk_fma_f32 v[126:127], v[124:125], v[126:127], s[46:47] op_sel_hi:[1,1,0]
	s_nop 0
	v_pk_fma_f32 v[124:125], v[124:125], v[126:127], s[48:49] op_sel_hi:[1,1,0]
	s_nop 0
	v_pk_mul_f32 v[120:121], v[120:121], v[124:125]
	s_nop 0
	v_pk_fma_f32 v[114:115], v[114:115], v[120:121], v[114:115]
	v_pk_fma_f32 v[120:121], v[134:135], v[122:123], v[146:147]
	v_pk_mul_f32 v[108:109], v[108:109], v[114:115]
	v_lshlrev_b32_e32 v114, 16, v171
	v_and_b32_e32 v115, 0xffff0000, v171
	v_pk_fma_f32 v[118:119], v[138:139], v[118:119], v[120:121]
	s_nop 0
	v_pk_fma_f32 v[114:115], v[142:143], v[114:115], v[118:119]
	s_nop 0
	v_pk_mul_f32 v[118:119], v[114:115], s[30:31] op_sel_hi:[1,0]
	v_pk_mul_f32 v[114:115], v[114:115], 0.5 op_sel_hi:[1,0]
	v_med3_f32 v118, v118, s47, v225
	v_med3_f32 v119, v119, s47, v225
	v_pk_mul_f32 v[120:121], v[118:119], v[118:119]
	s_nop 0
	v_pk_fma_f32 v[122:123], v[120:121], s[34:35], v[210:211] op_sel_hi:[1,0,0] neg_lo:[1,0,0] neg_hi:[1,0,0]
	s_nop 0
	v_pk_fma_f32 v[122:123], v[120:121], v[122:123], s[38:39] op_sel_hi:[1,1,0]
	s_nop 0
	v_pk_fma_f32 v[122:123], v[120:121], v[122:123], s[40:41] op_sel_hi:[1,1,0]
	s_nop 0
	v_pk_fma_f32 v[122:123], v[120:121], v[122:123], s[42:43] op_sel_hi:[1,1,0]
	s_nop 0
	v_pk_fma_f32 v[122:123], v[120:121], v[122:123], s[44:45] op_sel_hi:[1,1,0]
	s_nop 0
	v_pk_fma_f32 v[122:123], v[120:121], v[122:123], s[46:47] op_sel_hi:[1,1,0]
	s_nop 0
	v_pk_fma_f32 v[120:121], v[120:121], v[122:123], s[48:49] op_sel_hi:[1,1,0]
	s_nop 0
	v_pk_mul_f32 v[118:119], v[118:119], v[120:121]
	s_nop 0
	v_pk_fma_f32 v[114:115], v[114:115], v[118:119], v[114:115]
	v_lshlrev_b32_e32 v118, 16, v164
	v_pk_mul_f32 v[110:111], v[110:111], v[114:115]
	v_cvt_pk_bf16_f32 v114, v108, v109
	v_lshl_add_u64 v[108:109], v[172:173], 0, v[180:181]
	v_cvt_pk_bf16_f32 v115, v110, v111
	global_store_dwordx4 v[108:109], v[112:115], off nt
; __device__ __forceinline__ unsigned cvt_pk_bf16(float lo, float hi) { unsigned r; asm volatile("v_cvt_pk_bf16_f32 %0, %1, %2" : "=v"(r) : "v"(lo), "v"(hi)); return r; }
;     static __device__ __forceinline__ void unpk4(const u32x2 w, float (&o)[4]) { o[0] = bf_lo(w.x); o[1] = bf_hi(w.x); o[2] = bf_lo(w.y); o[3] = bf_hi(w.y); }
;     template <int N> static __device__ __forceinline__ u32x2 dpp_prev(const u32x2 pv, const u32x2 cur) { u32x2 r; r.x = dpp_prev1<N>(pv.x, cur.x); r.y = dpp_prev1<N>(pv.y, cur.y); return r; }
;     static __device__ __forceinline__ u32x2 finish2(const float (&g0)[4], const float (&g1)[4], const float (&g2)[4], const float (&w0)[4], const float (&w1)[4], const float (&w2)[4], const float (&bb)[4],
;                                                     const f32x4 v, float rs) {
;         float h[4];
; #pragma unroll
;         for (int j = 0; j < 4; j += 2) {
;             const f32x2 gc = (f32x2){bb[j] + w0[j] * g2[j] + w1[j] * g1[j] + w2[j] * g0[j], bb[j + 1] + w0[j + 1] * g2[j + 1] + w1[j + 1] * g1[j + 1] + w2[j + 1] * g0[j + 1]};
;             const f32x2 ge = gelu_pk(gc) * ((f32x2){v[j], v[j + 1]} * rs); h[j] = ge.x; h[j + 1] = ge.y; }
;         u32x2 w; w.x = cvt_pk_bf16(h[0], h[1]); w.y = cvt_pk_bf16(h[2], h[3]); return w;
;     __device__ __forceinline__ void operator()(const f32x4 (&acc)[2][2][4][2], const Unit& u, int wr, int wc, int fr, int fq) const {
;     ...
;                 for (int m = 0; m < 4; ++m) { const u32x4 cur = gq[m]; u32x4 hw;
; #pragma unroll
;                     for (int hv = 0; hv < 2; ++hv) { const u32x2 c2 = half2(cur, hv), p2 = half2(pv, hv);
;                         const u32x2 q1 = dpp_prev<1>(p2, c2), q2 = dpp_prev<2>(p2, c2);
;                         float g0[4], g1[4], g2[4]; unpk4(c2, g0); unpk4(q1, g1); unpk4(q2, g2);
;                         const u32x2 r = finish2(g0, g1, g2, w0[hv], w1[hv], w2[hv], bb[hv], acc[ai][bj][m][hv], rs8[ai][m]);
;                         if (hv == 0) { hw.x = r.x; hw.y = r.y; } else { hw.z = r.x; hw.w = r.y; } }
;                     *(u32x4*)(H + (size_t)(R0 + fr + 16 * m) * 2816 + col8) = hw;
	v_and_b32_e32 v119, 0xffff0000, v164
	v_mov_b32_dpp v109, v168 row_ror:1 row_mask:0xf bank_mask:0xf bound_ctrl:1
	v_mov_b32_dpp v113, v168 row_ror:2 row_mask:0xf bank_mask:0xf bound_ctrl:1
	v_mov_b32_dpp v115, v169 row_ror:2 row_mask:0xf bank_mask:0xf bound_ctrl:1
	v_mov_b32_dpp v109, v164 row_shr:1 row_mask:0xf bank_mask:0xf
	v_mov_b32_dpp v113, v164 row_shr:2 row_mask:0xf bank_mask:0xf
	v_lshlrev_b32_e32 v112, 16, v113
	v_and_b32_e32 v113, 0xffff0000, v113
	v_lshlrev_b32_e32 v108, 16, v109
	v_and_b32_e32 v109, 0xffff0000, v109
	v_pk_fma_f32 v[112:113], v[148:149], v[112:113], v[160:161]
	v_mov_b32_dpp v111, v169 row_ror:1 row_mask:0xf bank_mask:0xf bound_ctrl:1
	v_pk_fma_f32 v[108:109], v[152:153], v[108:109], v[112:113]
	v_mov_b32_dpp v115, v165 row_shr:2 row_mask:0xf bank_mask:0xf
	v_pk_fma_f32 v[108:109], v[156:157], v[118:119], v[108:109]
	v_mov_b32_dpp v111, v165 row_shr:1 row_mask:0xf bank_mask:0xf
	v_pk_mul_f32 v[112:113], v[108:109], s[30:31] op_sel_hi:[1,0]
	v_lshlrev_b32_e32 v114, 16, v115
	v_med3_f32 v112, v112, s47, v225
	v_med3_f32 v113, v113, s47, v225
	v_pk_mul_f32 v[118:119], v[112:113], v[112:113]
	v_and_b32_e32 v115, 0xffff0000, v115
	v_pk_fma_f32 v[120:121], v[118:119], s[34:35], v[210:211] op_sel_hi:[1,0,0] neg_lo:[1,0,0] neg_hi:[1,0,0]
	v_pk_mul_f32 v[108:109], v[108:109], 0.5 op_sel_hi:[1,0]
	v_pk_fma_f32 v[120:121], v[118:119], v[120:121], s[38:39] op_sel_hi:[1,1,0]
	v_lshlrev_b32_e32 v110, 16, v111
	v_pk_fma_f32 v[120:121], v[118:119], v[120:121], s[40:41] op_sel_hi:[1,1,0]
	v_and_b32_e32 v111, 0xffff0000, v111
	v_pk_fma_f32 v[120:121], v[118:119], v[120:121], s[42:43] op_sel_hi:[1,1,0]
	s_nop 0
	v_pk_fma_f32 v[120:121], v[118:119], v[120:121], s[44:45] op_sel_hi:[1,1,0]
	s_nop 0
	v_pk_fma_f32 v[120:121], v[118:119], v[120:121], s[46:47] op_sel_hi:[1,1,0]
	s_nop 0
	v_pk_fma_f32 v[118:119], v[118:119], v[120:121], s[48:49] op_sel_hi:[1,1,0]
	s_nop 0
	v_pk_mul_f32 v[112:113], v[112:113], v[118:119]
	s_nop 0
	v_pk_fma_f32 v[108:109], v[108:109], v[112:113], v[108:109]
	v_pk_fma_f32 v[112:113], v[150:151], v[114:115], v[162:163]
	v_pk_mul_f32 v[104:105], v[104:105], v[108:109]
	v_lshlrev_b32_e32 v108, 16, v165
	v_and_b32_e32 v109, 0xffff0000, v165
	v_pk_fma_f32 v[110:111], v[154:155], v[110:111], v[112:113]
	v_cvt_pk_bf16_f32 v120, v104, v105
	v_mov_b32_dpp v105, v170 row_ror:1 row_mask:0xf bank_mask:0xf bound_ctrl:1
	v_pk_fma_f32 v[108:109], v[158:159], v[108:109], v[110:111]
	s_nop 0
	v_pk_mul_f32 v[110:111], v[108:109], s[30:31] op_sel_hi:[1,0]
	v_pk_mul_f32 v[108:109], v[108:109], 0.5 op_sel_hi:[1,0]
	v_med3_f32 v110, v110, s47, v225
	v_med3_f32 v111, v111, s47, v225
	v_pk_mul_f32 v[112:113], v[110:111], v[110:111]
	v_mov_b32_dpp v105, v166 row_shr:1 row_mask:0xf bank_mask:0xf
	v_pk_fma_f32 v[114:115], v[112:113], s[34:35], v[210:211] op_sel_hi:[1,0,0] neg_lo:[1,0,0] neg_hi:[1,0,0]
	v_lshlrev_b32_e32 v104, 16, v105
	v_pk_fma_f32 v[114:115], v[112:113], v[114:115], s[38:39] op_sel_hi:[1,1,0]
	v_and_b32_e32 v105, 0xffff0000, v105
	v_pk_fma_f32 v[114:115], v[112:113], v[114:115], s[40:41] op_sel_hi:[1,1,0]
	s_nop 0
	v_pk_fma_f32 v[114:115], v[112:113], v[114:115], s[42:43] op_sel_hi:[1,1,0]
	s_nop 0
	v_pk_fma_f32 v[114:115], v[112:113], v[114:115], s[44:45] op_sel_hi:[1,1,0]
	s_nop 0
	v_pk_fma_f32 v[114:115], v[112:113], v[114:115], s[46:47] op_sel_hi:[1,1,0]
	s_nop 0
	v_pk_fma_f32 v[112:113], v[112:113], v[114:115], s[48:49] op_sel_hi:[1,1,0]
	s_nop 0
	v_pk_mul_f32 v[110:111], v[110:111], v[112:113]
	v_lshlrev_b32_e32 v112, 16, v166
	v_pk_fma_f32 v[108:109], v[108:109], v[110:111], v[108:109]
	v_and_b32_e32 v113, 0xffff0000, v166
	v_pk_mul_f32 v[106:107], v[106:107], v[108:109]
	v_mov_b32_dpp v109, v170 row_ror:2 row_mask:0xf bank_mask:0xf bound_ctrl:1
	v_mov_b32_dpp v111, v171 row_ror:2 row_mask:0xf bank_mask:0xf bound_ctrl:1
	v_cvt_pk_bf16_f32 v121, v106, v107
	v_mov_b32_dpp v107, v171 row_ror:1 row_mask:0xf bank_mask:0xf bound_ctrl:1
;     static __device__ __forceinline__ void unpk4(const u32x2 w, float (&o)[4]) { o[0] = bf_lo(w.x); o[1] = bf_hi(w.x); o[2] = bf_lo(w.y); o[3] = bf_hi(w.y); }
;     template <int N> static __device__ __forceinline__ u32x2 dpp_prev(const u32x2 pv, const u32x2 cur) { u32x2 r; r.x = dpp_prev1<N>(pv.x, cur.x); r.y = dpp_prev1<N>(pv.y, cur.y); return r; }
;     __device__ __forceinline__ void operator()(const f32x4 (&acc)[2][2][4][2], const Unit& u, int wr, int wc, int fr, int fq) const {
;     ...
;             for (int ai = 0; ai < 2; ++ai) { const int R0 = u.rb + ai * HALF + wr * 64; const bf16_t* gp = G + (size_t)(R0 + fr) * 2816 + col8;
;                 u32x4 gq[4], prv = (u32x4){0u, 0u, 0u, 0u};
; #pragma unroll
;                 for (int m = 0; m < 4; ++m) gq[m] = *(const u32x4*)(gp + (size_t)m * 16 * 2816);
;                 if ((R0 & 8191) != 0) prv = *(const u32x4*)(gp - (size_t)16 * 2816);
;     ...
;                 for (int m = 0; m < 4; ++m) { const u32x4 cur = gq[m]; u32x4 hw;
; #pragma unroll
;                     for (int hv = 0; hv < 2; ++hv) { const u32x2 c2 = half2(cur, hv), p2 = half2(pv, hv);
;                         const u32x2 q1 = dpp_prev<1>(p2, c2), q2 = dpp_prev<2>(p2, c2);
;                         float g0[4], g1[4], g2[4]; unpk4(c2, g0); unpk4(q1, g1); unpk4(q2, g2);
;                         const u32x2 r = finish2(g0, g1, g2, w0[hv], w1[hv], w2[hv], bb[hv], acc[ai][bj][m][hv], rs8[ai][m]);
;                         if (hv == 0) { hw.x = r.x; hw.y = r.y; } else { hw.z = r.x; hw.w = r.y; } }
;                     *(u32x4*)(H + (size_t)(R0 + fr + 16 * m) * 2816 + col8) = hw;
;                     pv = cur; } }
	v_mov_b32_dpp v109, v166 row_shr:2 row_mask:0xf bank_mask:0xf
	v_lshlrev_b32_e32 v108, 16, v109
	v_and_b32_e32 v109, 0xffff0000, v109
	v_pk_fma_f32 v[108:109], v[132:133], v[108:109], v[144:145]
	v_mov_b32_dpp v111, v167 row_shr:2 row_mask:0xf bank_mask:0xf
	v_pk_fma_f32 v[104:105], v[136:137], v[104:105], v[108:109]
	v_mov_b32_dpp v107, v167 row_shr:1 row_mask:0xf bank_mask:0xf
	v_pk_fma_f32 v[104:105], v[140:141], v[112:113], v[104:105]
	v_lshlrev_b32_e32 v110, 16, v111
	v_pk_mul_f32 v[108:109], v[104:105], s[30:31] op_sel_hi:[1,0]
	v_and_b32_e32 v111, 0xffff0000, v111
	v_med3_f32 v108, v108, s47, v225
	v_med3_f32 v109, v109, s47, v225
	v_pk_mul_f32 v[112:113], v[108:109], v[108:109]
	v_pk_mul_f32 v[104:105], v[104:105], 0.5 op_sel_hi:[1,0]
	v_pk_fma_f32 v[114:115], v[112:113], s[34:35], v[210:211] op_sel_hi:[1,0,0] neg_lo:[1,0,0] neg_hi:[1,0,0]
	v_lshlrev_b32_e32 v106, 16, v107
	v_pk_fma_f32 v[114:115], v[112:113], v[114:115], s[38:39] op_sel_hi:[1,1,0]
	v_and_b32_e32 v107, 0xffff0000, v107
	v_pk_fma_f32 v[114:115], v[112:113], v[114:115], s[40:41] op_sel_hi:[1,1,0]
	s_nop 0
	v_pk_fma_f32 v[114:115], v[112:113], v[114:115], s[42:43] op_sel_hi:[1,1,0]
	s_nop 0
	v_pk_fma_f32 v[114:115], v[112:113], v[114:115], s[44:45] op_sel_hi:[1,1,0]
	s_nop 0
	v_pk_fma_f32 v[114:115], v[112:113], v[114:115], s[46:47] op_sel_hi:[1,1,0]
	s_nop 0
	v_pk_fma_f32 v[112:113], v[112:113], v[114:115], s[48:49] op_sel_hi:[1,1,0]
	s_nop 0
	v_pk_mul_f32 v[108:109], v[108:109], v[112:113]
	s_nop 0
	v_pk_fma_f32 v[104:105], v[104:105], v[108:109], v[104:105]
	v_pk_fma_f32 v[108:109], v[134:135], v[110:111], v[146:147]
	v_pk_mul_f32 v[100:101], v[100:101], v[104:105]
	v_lshlrev_b32_e32 v104, 16, v167
	v_and_b32_e32 v105, 0xffff0000, v167
	v_pk_fma_f32 v[106:107], v[138:139], v[106:107], v[108:109]
	v_cvt_pk_bf16_f32 v122, v100, v101
	v_mov_b64_e32 v[100:101], s[2:3]
	v_pk_fma_f32 v[104:105], v[142:143], v[104:105], v[106:107]
	v_mad_i64_i32 v[164:165], s[2:3], v1, s91, v[100:101]
	v_pk_mul_f32 v[106:107], v[104:105], s[30:31] op_sel_hi:[1,0]
	v_lshl_add_u64 v[118:119], v[164:165], 0, v[180:181]
	v_med3_f32 v106, v106, s47, v225
	v_med3_f32 v107, v107, s47, v225
	v_pk_mul_f32 v[108:109], v[106:107], v[106:107]
	v_pk_mul_f32 v[104:105], v[104:105], 0.5 op_sel_hi:[1,0]
	v_pk_fma_f32 v[110:111], v[108:109], s[34:35], v[210:211] op_sel_hi:[1,0,0] neg_lo:[1,0,0] neg_hi:[1,0,0]
	v_add_co_u32_e32 v100, vcc, s10, v118
	v_pk_fma_f32 v[110:111], v[108:109], v[110:111], s[38:39] op_sel_hi:[1,1,0]
	s_nop 0
	v_addc_co_u32_e32 v101, vcc, 0, v119, vcc
	v_pk_fma_f32 v[110:111], v[108:109], v[110:111], s[40:41] op_sel_hi:[1,1,0]
	v_mad_i64_i32 v[166:167], s[2:3], v190, s91, v[116:117]
	v_pk_fma_f32 v[110:111], v[108:109], v[110:111], s[42:43] op_sel_hi:[1,1,0]
	v_lshl_add_u64 v[116:117], v[166:167], 0, v[180:181]
	v_pk_fma_f32 v[110:111], v[108:109], v[110:111], s[44:45] op_sel_hi:[1,1,0]
	s_cselect_b64 s[2:3], -1, 0
	v_pk_fma_f32 v[110:111], v[108:109], v[110:111], s[46:47] op_sel_hi:[1,1,0]
	s_cmp_eq_u32 s7, 0
	v_pk_fma_f32 v[108:109], v[108:109], v[110:111], s[48:49] op_sel_hi:[1,1,0]
	s_nop 0
	v_pk_mul_f32 v[106:107], v[106:107], v[108:109]
	s_nop 0
	v_pk_fma_f32 v[104:105], v[104:105], v[106:107], v[104:105]
	s_nop 0
	v_pk_mul_f32 v[102:103], v[102:103], v[104:105]
	s_nop 0
	v_cvt_pk_bf16_f32 v123, v102, v103
	global_load_dwordx4 v[112:115], v[118:119], off
	global_load_dwordx4 v[108:111], v[100:101], off
	v_add_co_u32_e32 v100, vcc, 0x2c000, v118
	s_nop 1
	v_addc_co_u32_e32 v101, vcc, 0, v119, vcc
	v_add_co_u32_e32 v102, vcc, 0x42000, v118
	s_nop 1
	v_addc_co_u32_e32 v103, vcc, 0, v119, vcc
	global_load_dwordx4 v[104:107], v[100:101], off
	s_nop 0
	global_load_dwordx4 v[100:103], v[102:103], off
	s_nop 0
	global_store_dwordx4 v[116:117], v[120:123], off nt
	s_cbranch_scc1 .LBB0_1015
	v_add_co_u32_e32 v116, vcc, 0xfffea000, v118
	s_nop 1
	v_addc_co_u32_e32 v117, vcc, -1, v119, vcc
	global_load_dwordx4 v[116:119], v[116:117], off
	s_branch .LBB0_1016

;     static __device__ __forceinline__ void unpk4(const u32x2 w, float (&o)[4]) { o[0] = bf_lo(w.x); o[1] = bf_hi(w.x); o[2] = bf_lo(w.y); o[3] = bf_hi(w.y); }
;     template <int N> static __device__ __forceinline__ u32x2 dpp_prev(const u32x2 pv, const u32x2 cur) { u32x2 r; r.x = dpp_prev1<N>(pv.x, cur.x); r.y = dpp_prev1<N>(pv.y, cur.y); return r; }
;     __device__ __forceinline__ void operator()(const f32x4 (&acc)[2][2][4][2], const Unit& u, int wr, int wc, int fr, int fq) const {
;     ...
;         float rs8[2][4];
; #pragma unroll
;         for (int ai = 0; ai < 2; ++ai)
; #pragma unroll
;             for (int m = 0; m < 4; ++m) rs8[ai][m] = rsqrtf(SS[u.rb + (u.half ? 0 : ai * HALF) + wr * 64 + fr + 16 * m] * (1.f / 1024.f) + 1e-6f);
;     ...
;                 for (int m = 0; m < 4; ++m) { const u32x4 cur = gq[m]; u32x4 hw;
; #pragma unroll
;                     for (int hv = 0; hv < 2; ++hv) { const u32x2 c2 = half2(cur, hv), p2 = half2(pv, hv);
;                         const u32x2 q1 = dpp_prev<1>(p2, c2), q2 = dpp_prev<2>(p2, c2);
;                         float g0[4], g1[4], g2[4]; unpk4(c2, g0); unpk4(q1, g1); unpk4(q2, g2);
;                         const u32x2 r = finish2(g0, g1, g2, w0[hv], w1[hv], w2[hv], bb[hv], acc[ai][bj][m][hv], rs8[ai][m]);
;                         if (hv == 0) { hw.x = r.x; hw.y = r.y; } else { hw.z = r.x; hw.w = r.y; } }
.LBB0_1016:
	v_fmamk_f32 v122, v189, 0x3a800000, v224
	v_cmp_gt_f32_e32 vcc, s5, v122
	v_mul_f32_e32 v123, 0x4b800000, v122
	v_fmamk_f32 v3, v3, 0x3a800000, v224
	v_cndmask_b32_e32 v122, v122, v123, vcc
	v_rsq_f32_e32 v122, v122
	s_waitcnt vmcnt(0)
	v_mov_b32_dpp v125, v116 row_ror:2 row_mask:0xf bank_mask:0xf bound_ctrl:1
	v_mov_b32_dpp v127, v117 row_ror:2 row_mask:0xf bank_mask:0xf bound_ctrl:1
	v_lshlrev_b32_e32 v178, 16, v112
	v_mul_f32_e32 v123, 0x45800000, v122
	v_cndmask_b32_e32 v128, v122, v123, vcc
	v_fmamk_f32 v122, v187, 0x3a800000, v224
	v_cmp_gt_f32_e32 vcc, s5, v122
	v_mul_f32_e32 v123, 0x4b800000, v122
	v_mov_b32_dpp v125, v112 row_shr:2 row_mask:0xf bank_mask:0xf
	v_cndmask_b32_e32 v122, v122, v123, vcc
	v_rsq_f32_e32 v122, v122
	v_lshlrev_b32_e32 v170, 16, v125
	v_and_b32_e32 v171, 0xffff0000, v125
	v_pk_fma_f32 v[170:171], v[148:149], v[170:171], v[160:161]
	v_mul_f32_e32 v123, 0x45800000, v122
	v_cndmask_b32_e32 v126, v122, v123, vcc
	v_cmp_gt_f32_e32 vcc, s5, v3
	v_mul_f32_e32 v122, 0x4b800000, v3
	v_mov_b32_dpp v123, v117 row_ror:1 row_mask:0xf bank_mask:0xf bound_ctrl:1
	v_cndmask_b32_e32 v3, v3, v122, vcc
	v_rsq_f32_e32 v3, v3
	v_and_b32_e32 v179, 0xffff0000, v112
	v_mov_b32_dpp v127, v113 row_shr:2 row_mask:0xf bank_mask:0xf
	v_mov_b32_dpp v123, v113 row_shr:1 row_mask:0xf bank_mask:0xf
	v_mul_f32_e32 v122, 0x45800000, v3
	v_cndmask_b32_e32 v124, v3, v122, vcc
	v_fmamk_f32 v3, v185, 0x3a800000, v224
	v_cmp_gt_f32_e32 vcc, s5, v3
	v_mul_f32_e32 v122, 0x4b800000, v3
	v_lshlrev_b32_e32 v174, 16, v127
	v_cndmask_b32_e32 v3, v3, v122, vcc
	v_rsq_f32_e32 v3, v3
	v_and_b32_e32 v175, 0xffff0000, v127
	v_lshlrev_b32_e32 v168, 16, v123
	v_and_b32_e32 v169, 0xffff0000, v123
	v_mul_f32_e32 v122, 0x45800000, v3
	v_cndmask_b32_e32 v122, v3, v122, vcc
	v_mov_b32_dpp v3, v116 row_ror:1 row_mask:0xf bank_mask:0xf bound_ctrl:1
	v_pk_mul_f32 v[96:97], v[96:97], v[128:129] op_sel_hi:[1,0]
	v_pk_fma_f32 v[174:175], v[150:151], v[174:175], v[162:163]
	v_mov_b32_dpp v3, v112 row_shr:1 row_mask:0xf bank_mask:0xf
	v_lshlrev_b32_e32 v116, 16, v3
	v_and_b32_e32 v117, 0xffff0000, v3
	v_pk_fma_f32 v[116:117], v[152:153], v[116:117], v[170:171]
	v_pk_fma_f32 v[168:169], v[154:155], v[168:169], v[174:175]
	v_pk_fma_f32 v[170:171], v[156:157], v[178:179], v[116:117]
	v_mov_b32_dpp v125, v118 row_ror:2 row_mask:0xf bank_mask:0xf bound_ctrl:1
	v_pk_mul_f32 v[116:117], v[170:171], s[30:31] op_sel_hi:[1,0]
	v_pk_mul_f32 v[170:171], v[170:171], 0.5 op_sel_hi:[1,0]
	v_med3_f32 v178, v116, s47, v225
	v_med3_f32 v179, v117, s47, v225
	v_pk_mul_f32 v[182:183], v[178:179], v[178:179]
	v_mov_b64_e32 v[116:117], s[36:37]
	v_pk_fma_f32 v[190:191], v[182:183], s[34:35], v[116:117] op_sel_hi:[1,0,0] neg_lo:[1,0,0] neg_hi:[1,0,0]
	v_pk_mul_f32 v[98:99], v[98:99], v[128:129] op_sel_hi:[1,0]
	v_pk_fma_f32 v[190:191], v[182:183], v[190:191], s[38:39] op_sel_hi:[1,1,0]
	v_mov_b32_dpp v3, v118 row_ror:1 row_mask:0xf bank_mask:0xf bound_ctrl:1
	v_pk_fma_f32 v[190:191], v[182:183], v[190:191], s[40:41] op_sel_hi:[1,1,0]
	v_mov_b32_dpp v125, v114 row_shr:2 row_mask:0xf bank_mask:0xf
	v_pk_fma_f32 v[190:191], v[182:183], v[190:191], s[42:43] op_sel_hi:[1,1,0]
	v_mov_b32_dpp v3, v114 row_shr:1 row_mask:0xf bank_mask:0xf
	v_pk_fma_f32 v[190:191], v[182:183], v[190:191], s[44:45] op_sel_hi:[1,1,0]
	v_mov_b32_dpp v127, v119 row_ror:2 row_mask:0xf bank_mask:0xf bound_ctrl:1
	v_pk_fma_f32 v[190:191], v[182:183], v[190:191], s[46:47] op_sel_hi:[1,1,0]
	v_mov_b32_dpp v123, v119 row_ror:1 row_mask:0xf bank_mask:0xf bound_ctrl:1
	v_pk_fma_f32 v[182:183], v[182:183], v[190:191], s[48:49] op_sel_hi:[1,1,0]
	v_mov_b32_dpp v127, v115 row_shr:2 row_mask:0xf bank_mask:0xf
	v_pk_mul_f32 v[178:179], v[178:179], v[182:183]
	v_mov_b32_dpp v123, v115 row_shr:1 row_mask:0xf bank_mask:0xf
	v_pk_fma_f32 v[170:171], v[170:171], v[178:179], v[170:171]
	v_lshlrev_b32_e32 v118, 16, v123
	v_pk_mul_f32 v[96:97], v[96:97], v[170:171]
	v_lshlrev_b32_e32 v170, 16, v113
	v_and_b32_e32 v171, 0xffff0000, v113
	v_pk_fma_f32 v[168:169], v[158:159], v[170:171], v[168:169]
	v_cvt_pk_bf16_f32 v96, v96, v97
	v_and_b32_e32 v119, 0xffff0000, v123
	v_pk_mul_f32 v[170:171], v[168:169], s[30:31] op_sel_hi:[1,0]
	v_pk_mul_f32 v[168:169], v[168:169], 0.5 op_sel_hi:[1,0]
	v_med3_f32 v170, v170, s47, v225
	v_med3_f32 v171, v171, s47, v225
	v_pk_mul_f32 v[174:175], v[170:171], v[170:171]
	v_pk_mul_f32 v[92:93], v[92:93], v[128:129] op_sel_hi:[1,0]
	v_pk_fma_f32 v[178:179], v[174:175], s[34:35], v[116:117] op_sel_hi:[1,0,0] neg_lo:[1,0,0] neg_hi:[1,0,0]
	v_mad_i64_i32 v[120:121], s[8:9], v1, s91, 0
	v_pk_fma_f32 v[178:179], v[174:175], v[178:179], s[38:39] op_sel_hi:[1,1,0]
	v_readlane_b32 s8, v240, 58
	v_pk_fma_f32 v[178:179], v[174:175], v[178:179], s[40:41] op_sel_hi:[1,1,0]
	v_readlane_b32 s9, v240, 59
	v_pk_fma_f32 v[178:179], v[174:175], v[178:179], s[42:43] op_sel_hi:[1,1,0]
	v_pk_mul_f32 v[94:95], v[94:95], v[128:129] op_sel_hi:[1,0]
	v_pk_fma_f32 v[178:179], v[174:175], v[178:179], s[44:45] op_sel_hi:[1,1,0]
	v_pk_mul_f32 v[88:89], v[88:89], v[126:127] op_sel_hi:[1,0]
	v_pk_fma_f32 v[178:179], v[174:175], v[178:179], s[46:47] op_sel_hi:[1,1,0]
	v_pk_mul_f32 v[90:91], v[90:91], v[126:127] op_sel_hi:[1,0]
	v_pk_fma_f32 v[174:175], v[174:175], v[178:179], s[48:49] op_sel_hi:[1,1,0]
	v_pk_mul_f32 v[84:85], v[84:85], v[126:127] op_sel_hi:[1,0]
	v_pk_mul_f32 v[170:171], v[170:171], v[174:175]
	v_lshlrev_b32_e32 v174, 16, v114
	v_pk_fma_f32 v[168:169], v[168:169], v[170:171], v[168:169]
	v_and_b32_e32 v175, 0xffff0000, v114
	v_pk_mul_f32 v[98:99], v[98:99], v[168:169]
	v_lshlrev_b32_e32 v168, 16, v125
; __device__ __forceinline__ unsigned cvt_pk_bf16(float lo, float hi) { unsigned r; asm volatile("v_cvt_pk_bf16_f32 %0, %1, %2" : "=v"(r) : "v"(lo), "v"(hi)); return r; }
;     static __device__ __forceinline__ void unpk4(const u32x2 w, float (&o)[4]) { o[0] = bf_lo(w.x); o[1] = bf_hi(w.x); o[2] = bf_lo(w.y); o[3] = bf_hi(w.y); }
;     template <int N> static __device__ __forceinline__ u32x2 dpp_prev(const u32x2 pv, const u32x2 cur) { u32x2 r; r.x = dpp_prev1<N>(pv.x, cur.x); r.y = dpp_prev1<N>(pv.y, cur.y); return r; }
;     static __device__ __forceinline__ u32x2 finish2(const float (&g0)[4], const float (&g1)[4], const float (&g2)[4], const float (&w0)[4], const float (&w1)[4], const float (&w2)[4], const float (&bb)[4],
;                                                     const f32x4 v, float rs) {
;         float h[4];
; #pragma unroll
;         for (int j = 0; j < 4; j += 2) {
;             const f32x2 gc = (f32x2){bb[j] + w0[j] * g2[j] + w1[j] * g1[j] + w2[j] * g0[j], bb[j + 1] + w0[j + 1] * g2[j + 1] + w1[j + 1] * g1[j + 1] + w2[j + 1] * g0[j + 1]};
;             const f32x2 ge = gelu_pk(gc) * ((f32x2){v[j], v[j + 1]} * rs); h[j] = ge.x; h[j + 1] = ge.y; }
;         u32x2 w; w.x = cvt_pk_bf16(h[0], h[1]); w.y = cvt_pk_bf16(h[2], h[3]); return w;
;     __device__ __forceinline__ void operator()(const f32x4 (&acc)[2][2][4][2], const Unit& u, int wr, int wc, int fr, int fq) const {
;     ...
;                 for (int m = 0; m < 4; ++m) { const u32x4 cur = gq[m]; u32x4 hw;
; #pragma unroll
;                     for (int hv = 0; hv < 2; ++hv) { const u32x2 c2 = half2(cur, hv), p2 = half2(pv, hv);
;                         const u32x2 q1 = dpp_prev<1>(p2, c2), q2 = dpp_prev<2>(p2, c2);
;                         float g0[4], g1[4], g2[4]; unpk4(c2, g0); unpk4(q1, g1); unpk4(q2, g2);
;                         const u32x2 r = finish2(g0, g1, g2, w0[hv], w1[hv], w2[hv], bb[hv], acc[ai][bj][m][hv], rs8[ai][m]);
;                         if (hv == 0) { hw.x = r.x; hw.y = r.y; } else { hw.z = r.x; hw.w = r.y; } }
;                     *(u32x4*)(H + (size_t)(R0 + fr + 16 * m) * 2816 + col8) = hw;
	v_and_b32_e32 v169, 0xffff0000, v125
	v_cvt_pk_bf16_f32 v97, v98, v99
	v_lshlrev_b32_e32 v98, 16, v3
	v_and_b32_e32 v99, 0xffff0000, v3
	v_pk_fma_f32 v[168:169], v[132:133], v[168:169], v[144:145]
	v_lshlrev_b32_e32 v170, 16, v127
	v_pk_fma_f32 v[98:99], v[136:137], v[98:99], v[168:169]
	v_and_b32_e32 v171, 0xffff0000, v127
	v_pk_fma_f32 v[98:99], v[140:141], v[174:175], v[98:99]
	v_mov_b32_dpp v3, v112 row_ror:1 row_mask:0xf bank_mask:0xf bound_ctrl:1
	v_pk_mul_f32 v[168:169], v[98:99], s[30:31] op_sel_hi:[1,0]
	v_pk_mul_f32 v[98:99], v[98:99], 0.5 op_sel_hi:[1,0]
	v_med3_f32 v168, v168, s47, v225
	v_med3_f32 v169, v169, s47, v225
	v_pk_mul_f32 v[174:175], v[168:169], v[168:169]
	v_mov_b32_dpp v3, v108 row_shr:1 row_mask:0xf bank_mask:0xf
	v_pk_fma_f32 v[178:179], v[174:175], s[34:35], v[116:117] op_sel_hi:[1,0,0] neg_lo:[1,0,0] neg_hi:[1,0,0]
	v_pk_mul_f32 v[86:87], v[86:87], v[126:127] op_sel_hi:[1,0]
	v_pk_fma_f32 v[178:179], v[174:175], v[178:179], s[38:39] op_sel_hi:[1,1,0]
	v_pk_mul_f32 v[80:81], v[80:81], v[124:125] op_sel_hi:[1,0]
	v_pk_fma_f32 v[178:179], v[174:175], v[178:179], s[40:41] op_sel_hi:[1,1,0]
	v_pk_mul_f32 v[82:83], v[82:83], v[124:125] op_sel_hi:[1,0]
	v_pk_fma_f32 v[178:179], v[174:175], v[178:179], s[42:43] op_sel_hi:[1,1,0]
	v_pk_mul_f32 v[76:77], v[76:77], v[124:125] op_sel_hi:[1,0]
	v_pk_fma_f32 v[178:179], v[174:175], v[178:179], s[44:45] op_sel_hi:[1,1,0]
	v_pk_mul_f32 v[78:79], v[78:79], v[124:125] op_sel_hi:[1,0]
	v_pk_fma_f32 v[178:179], v[174:175], v[178:179], s[46:47] op_sel_hi:[1,1,0]
	v_pk_mul_f32 v[72:73], v[72:73], v[122:123] op_sel_hi:[1,0]
	v_pk_fma_f32 v[174:175], v[174:175], v[178:179], s[48:49] op_sel_hi:[1,1,0]
	v_pk_mul_f32 v[74:75], v[74:75], v[122:123] op_sel_hi:[1,0]
	v_pk_mul_f32 v[168:169], v[168:169], v[174:175]
	v_pk_mul_f32 v[64:65], v[64:65], v[122:123] op_sel_hi:[1,0]
	v_pk_fma_f32 v[98:99], v[98:99], v[168:169], v[98:99]
	v_pk_fma_f32 v[168:169], v[134:135], v[170:171], v[146:147]
	v_pk_mul_f32 v[92:93], v[92:93], v[98:99]
	v_lshlrev_b32_e32 v98, 16, v115
	v_and_b32_e32 v99, 0xffff0000, v115
	v_pk_fma_f32 v[118:119], v[138:139], v[118:119], v[168:169]
	v_pk_mul_f32 v[66:67], v[66:67], v[122:123] op_sel_hi:[1,0]
	v_pk_fma_f32 v[98:99], v[142:143], v[98:99], v[118:119]
	v_readlane_b32 s52, v240, 62
	v_pk_mul_f32 v[118:119], v[98:99], s[30:31] op_sel_hi:[1,0]
	v_pk_mul_f32 v[98:99], v[98:99], 0.5 op_sel_hi:[1,0]
	v_med3_f32 v118, v118, s47, v225
	v_med3_f32 v119, v119, s47, v225
	v_pk_mul_f32 v[168:169], v[118:119], v[118:119]
	v_readlane_b32 s66, v239, 12
	v_pk_fma_f32 v[170:171], v[168:169], s[34:35], v[116:117] op_sel_hi:[1,0,0] neg_lo:[1,0,0] neg_hi:[1,0,0]
	v_readlane_b32 s67, v239, 13
	v_pk_fma_f32 v[170:171], v[168:169], v[170:171], s[38:39] op_sel_hi:[1,1,0]
	v_readlane_b32 s53, v240, 63
	v_pk_fma_f32 v[170:171], v[168:169], v[170:171], s[40:41] op_sel_hi:[1,1,0]
	v_readlane_b32 s54, v239, 0
	v_pk_fma_f32 v[170:171], v[168:169], v[170:171], s[42:43] op_sel_hi:[1,1,0]
	v_readlane_b32 s55, v239, 1
	v_pk_fma_f32 v[170:171], v[168:169], v[170:171], s[44:45] op_sel_hi:[1,1,0]
	v_readlane_b32 s56, v239, 2
	v_pk_fma_f32 v[170:171], v[168:169], v[170:171], s[46:47] op_sel_hi:[1,1,0]
	v_readlane_b32 s57, v239, 3
	v_pk_fma_f32 v[168:169], v[168:169], v[170:171], s[48:49] op_sel_hi:[1,1,0]
	v_readlane_b32 s58, v239, 4
	v_pk_mul_f32 v[118:119], v[118:119], v[168:169]
	v_lshl_add_u64 v[168:169], s[8:9], 0, v[120:121]
	v_pk_fma_f32 v[98:99], v[98:99], v[118:119], v[98:99]
	v_mov_b32_e32 v120, 0
	v_pk_mul_f32 v[94:95], v[94:95], v[98:99]
	v_cvt_pk_bf16_f32 v98, v92, v93
	v_lshl_add_u64 v[92:93], v[168:169], 0, v[180:181]
	v_cvt_pk_bf16_f32 v99, v94, v95
	global_store_dwordx4 v[92:93], v[96:99], off nt
	v_lshlrev_b32_e32 v92, 16, v3
	v_and_b32_e32 v93, 0xffff0000, v3
	v_mov_b32_dpp v97, v112 row_ror:2 row_mask:0xf bank_mask:0xf bound_ctrl:1
	v_mov_b32_dpp v95, v113 row_ror:1 row_mask:0xf bank_mask:0xf bound_ctrl:1
	v_mov_b32_dpp v99, v113 row_ror:2 row_mask:0xf bank_mask:0xf bound_ctrl:1
	v_mov_b32_dpp v97, v108 row_shr:2 row_mask:0xf bank_mask:0xf
	v_lshlrev_b32_e32 v96, 16, v97
	v_and_b32_e32 v97, 0xffff0000, v97
	v_pk_fma_f32 v[96:97], v[148:149], v[96:97], v[160:161]
	v_lshlrev_b32_e32 v112, 16, v108
	v_and_b32_e32 v113, 0xffff0000, v108
	v_pk_fma_f32 v[92:93], v[152:153], v[92:93], v[96:97]
	v_mov_b32_dpp v99, v109 row_shr:2 row_mask:0xf bank_mask:0xf
	v_pk_fma_f32 v[92:93], v[156:157], v[112:113], v[92:93]
	v_mov_b32_dpp v95, v109 row_shr:1 row_mask:0xf bank_mask:0xf
	v_pk_mul_f32 v[96:97], v[92:93], s[30:31] op_sel_hi:[1,0]
	v_lshlrev_b32_e32 v98, 16, v99
	v_med3_f32 v96, v96, s47, v225
	v_med3_f32 v97, v97, s47, v225
	v_pk_mul_f32 v[112:113], v[96:97], v[96:97]
	v_and_b32_e32 v99, 0xffff0000, v99
	v_pk_fma_f32 v[118:119], v[112:113], s[34:35], v[116:117] op_sel_hi:[1,0,0] neg_lo:[1,0,0] neg_hi:[1,0,0]
	v_pk_mul_f32 v[92:93], v[92:93], 0.5 op_sel_hi:[1,0]
	v_pk_fma_f32 v[118:119], v[112:113], v[118:119], s[38:39] op_sel_hi:[1,1,0]
	v_lshlrev_b32_e32 v94, 16, v95
	v_pk_fma_f32 v[118:119], v[112:113], v[118:119], s[40:41] op_sel_hi:[1,1,0]
	v_and_b32_e32 v95, 0xffff0000, v95
	v_pk_fma_f32 v[118:119], v[112:113], v[118:119], s[42:43] op_sel_hi:[1,1,0]
	v_mov_b32_dpp v3, v114 row_ror:1 row_mask:0xf bank_mask:0xf bound_ctrl:1
	v_pk_fma_f32 v[118:119], v[112:113], v[118:119], s[44:45] op_sel_hi:[1,1,0]
	v_mov_b32_e32 v121, 0
	v_pk_fma_f32 v[118:119], v[112:113], v[118:119], s[46:47] op_sel_hi:[1,1,0]
	v_mov_b32_dpp v3, v110 row_shr:1 row_mask:0xf bank_mask:0xf
	v_pk_fma_f32 v[112:113], v[112:113], v[118:119], s[48:49] op_sel_hi:[1,1,0]
	v_mov_b32_e32 v118, 0
	v_pk_mul_f32 v[96:97], v[96:97], v[112:113]
; __device__ __forceinline__ unsigned cvt_pk_bf16(float lo, float hi) { unsigned r; asm volatile("v_cvt_pk_bf16_f32 %0, %1, %2" : "=v"(r) : "v"(lo), "v"(hi)); return r; }
;     static __device__ __forceinline__ void unpk4(const u32x2 w, float (&o)[4]) { o[0] = bf_lo(w.x); o[1] = bf_hi(w.x); o[2] = bf_lo(w.y); o[3] = bf_hi(w.y); }
;     template <int N> static __device__ __forceinline__ u32x2 dpp_prev(const u32x2 pv, const u32x2 cur) { u32x2 r; r.x = dpp_prev1<N>(pv.x, cur.x); r.y = dpp_prev1<N>(pv.y, cur.y); return r; }
;     static __device__ __forceinline__ u32x2 finish2(const float (&g0)[4], const float (&g1)[4], const float (&g2)[4], const float (&w0)[4], const float (&w1)[4], const float (&w2)[4], const float (&bb)[4],
;                                                     const f32x4 v, float rs) {
;         float h[4];
; #pragma unroll
;         for (int j = 0; j < 4; j += 2) {
;             const f32x2 gc = (f32x2){bb[j] + w0[j] * g2[j] + w1[j] * g1[j] + w2[j] * g0[j], bb[j + 1] + w0[j + 1] * g2[j + 1] + w1[j + 1] * g1[j + 1] + w2[j + 1] * g0[j + 1]};
;             const f32x2 ge = gelu_pk(gc) * ((f32x2){v[j], v[j + 1]} * rs); h[j] = ge.x; h[j + 1] = ge.y; }
;         u32x2 w; w.x = cvt_pk_bf16(h[0], h[1]); w.y = cvt_pk_bf16(h[2], h[3]); return w;
;     __device__ __forceinline__ void operator()(const f32x4 (&acc)[2][2][4][2], const Unit& u, int wr, int wc, int fr, int fq) const {
;     ...
;                 for (int m = 0; m < 4; ++m) { const u32x4 cur = gq[m]; u32x4 hw;
; #pragma unroll
;                     for (int hv = 0; hv < 2; ++hv) { const u32x2 c2 = half2(cur, hv), p2 = half2(pv, hv);
;                         const u32x2 q1 = dpp_prev<1>(p2, c2), q2 = dpp_prev<2>(p2, c2);
;                         float g0[4], g1[4], g2[4]; unpk4(c2, g0); unpk4(q1, g1); unpk4(q2, g2);
;                         const u32x2 r = finish2(g0, g1, g2, w0[hv], w1[hv], w2[hv], bb[hv], acc[ai][bj][m][hv], rs8[ai][m]);
;                         if (hv == 0) { hw.x = r.x; hw.y = r.y; } else { hw.z = r.x; hw.w = r.y; } }
;                     *(u32x4*)(H + (size_t)(R0 + fr + 16 * m) * 2816 + col8) = hw;
	v_mov_b32_e32 v119, 0
	v_pk_fma_f32 v[92:93], v[92:93], v[96:97], v[92:93]
	v_pk_fma_f32 v[96:97], v[150:151], v[98:99], v[162:163]
	v_pk_mul_f32 v[88:89], v[88:89], v[92:93]
	v_lshlrev_b32_e32 v92, 16, v109
	v_and_b32_e32 v93, 0xffff0000, v109
	v_pk_fma_f32 v[94:95], v[154:155], v[94:95], v[96:97]
	v_cvt_pk_bf16_f32 v88, v88, v89
	v_readlane_b32 s59, v239, 5
	v_pk_fma_f32 v[92:93], v[158:159], v[92:93], v[94:95]
	v_readlane_b32 s60, v239, 6
	v_pk_mul_f32 v[94:95], v[92:93], s[30:31] op_sel_hi:[1,0]
	v_pk_mul_f32 v[92:93], v[92:93], 0.5 op_sel_hi:[1,0]
	v_med3_f32 v94, v94, s47, v225
	v_med3_f32 v95, v95, s47, v225
	v_pk_mul_f32 v[96:97], v[94:95], v[94:95]
	v_readlane_b32 s61, v239, 7
	v_pk_fma_f32 v[98:99], v[96:97], s[34:35], v[116:117] op_sel_hi:[1,0,0] neg_lo:[1,0,0] neg_hi:[1,0,0]
	v_readlane_b32 s62, v239, 8
	v_pk_fma_f32 v[98:99], v[96:97], v[98:99], s[38:39] op_sel_hi:[1,1,0]
	v_readlane_b32 s63, v239, 9
	v_pk_fma_f32 v[98:99], v[96:97], v[98:99], s[40:41] op_sel_hi:[1,1,0]
	v_readlane_b32 s64, v239, 10
	v_pk_fma_f32 v[98:99], v[96:97], v[98:99], s[42:43] op_sel_hi:[1,1,0]
	v_readlane_b32 s65, v239, 11
	v_pk_fma_f32 v[98:99], v[96:97], v[98:99], s[44:45] op_sel_hi:[1,1,0]
	s_nop 0
	v_pk_fma_f32 v[98:99], v[96:97], v[98:99], s[46:47] op_sel_hi:[1,1,0]
	s_nop 0
	v_pk_fma_f32 v[96:97], v[96:97], v[98:99], s[48:49] op_sel_hi:[1,1,0]
	v_lshlrev_b32_e32 v98, 16, v110
	v_pk_mul_f32 v[94:95], v[94:95], v[96:97]
	v_and_b32_e32 v99, 0xffff0000, v110
	v_pk_fma_f32 v[92:93], v[92:93], v[94:95], v[92:93]
	v_mov_b32_dpp v95, v114 row_ror:2 row_mask:0xf bank_mask:0xf bound_ctrl:1
	v_pk_mul_f32 v[90:91], v[90:91], v[92:93]
	v_mov_b32_dpp v97, v115 row_ror:2 row_mask:0xf bank_mask:0xf bound_ctrl:1
	v_mov_b32_dpp v95, v110 row_shr:2 row_mask:0xf bank_mask:0xf
	v_lshlrev_b32_e32 v94, 16, v95
	v_and_b32_e32 v95, 0xffff0000, v95
	v_cvt_pk_bf16_f32 v89, v90, v91
	v_lshlrev_b32_e32 v90, 16, v3
	v_and_b32_e32 v91, 0xffff0000, v3
	v_pk_fma_f32 v[94:95], v[132:133], v[94:95], v[144:145]
	v_mov_b32_dpp v93, v115 row_ror:1 row_mask:0xf bank_mask:0xf bound_ctrl:1
	v_pk_fma_f32 v[90:91], v[136:137], v[90:91], v[94:95]
	v_mov_b32_dpp v97, v111 row_shr:2 row_mask:0xf bank_mask:0xf
	v_pk_fma_f32 v[90:91], v[140:141], v[98:99], v[90:91]
	v_mov_b32_dpp v93, v111 row_shr:1 row_mask:0xf bank_mask:0xf
	v_pk_mul_f32 v[94:95], v[90:91], s[30:31] op_sel_hi:[1,0]
	v_lshlrev_b32_e32 v96, 16, v97
	v_med3_f32 v94, v94, s47, v225
	v_med3_f32 v95, v95, s47, v225
	v_pk_mul_f32 v[98:99], v[94:95], v[94:95]
	v_and_b32_e32 v97, 0xffff0000, v97
	v_pk_fma_f32 v[112:113], v[98:99], s[34:35], v[116:117] op_sel_hi:[1,0,0] neg_lo:[1,0,0] neg_hi:[1,0,0]
	v_pk_mul_f32 v[90:91], v[90:91], 0.5 op_sel_hi:[1,0]
	v_pk_fma_f32 v[112:113], v[98:99], v[112:113], s[38:39] op_sel_hi:[1,1,0]
	v_lshlrev_b32_e32 v92, 16, v93
	v_pk_fma_f32 v[112:113], v[98:99], v[112:113], s[40:41] op_sel_hi:[1,1,0]
	v_and_b32_e32 v93, 0xffff0000, v93
	v_pk_fma_f32 v[112:113], v[98:99], v[112:113], s[42:43] op_sel_hi:[1,1,0]
	v_add_u32_e32 v3, 16, v1
	v_pk_fma_f32 v[112:113], v[98:99], v[112:113], s[44:45] op_sel_hi:[1,1,0]
	s_nop 0
	v_pk_fma_f32 v[112:113], v[98:99], v[112:113], s[46:47] op_sel_hi:[1,1,0]
	s_nop 0
	v_pk_fma_f32 v[98:99], v[98:99], v[112:113], s[48:49] op_sel_hi:[1,1,0]
	s_nop 0
	v_pk_mul_f32 v[94:95], v[94:95], v[98:99]
	s_nop 0
	v_pk_fma_f32 v[90:91], v[90:91], v[94:95], v[90:91]
	v_pk_fma_f32 v[94:95], v[134:135], v[96:97], v[146:147]
	v_pk_mul_f32 v[84:85], v[84:85], v[90:91]
	v_lshlrev_b32_e32 v90, 16, v111
	v_and_b32_e32 v91, 0xffff0000, v111
	v_pk_fma_f32 v[92:93], v[138:139], v[92:93], v[94:95]
	s_nop 0
	v_pk_fma_f32 v[90:91], v[142:143], v[90:91], v[92:93]
	s_nop 0
	v_pk_mul_f32 v[92:93], v[90:91], s[30:31] op_sel_hi:[1,0]
	v_pk_mul_f32 v[90:91], v[90:91], 0.5 op_sel_hi:[1,0]
	v_med3_f32 v92, v92, s47, v225
	v_med3_f32 v93, v93, s47, v225
	v_pk_mul_f32 v[94:95], v[92:93], v[92:93]
	s_nop 0
	v_pk_fma_f32 v[96:97], v[94:95], s[34:35], v[116:117] op_sel_hi:[1,0,0] neg_lo:[1,0,0] neg_hi:[1,0,0]
	s_nop 0
	v_pk_fma_f32 v[96:97], v[94:95], v[96:97], s[38:39] op_sel_hi:[1,1,0]
	s_nop 0
	v_pk_fma_f32 v[96:97], v[94:95], v[96:97], s[40:41] op_sel_hi:[1,1,0]
	s_nop 0
	v_pk_fma_f32 v[96:97], v[94:95], v[96:97], s[42:43] op_sel_hi:[1,1,0]
	s_nop 0
	v_pk_fma_f32 v[96:97], v[94:95], v[96:97], s[44:45] op_sel_hi:[1,1,0]
	s_nop 0
	v_pk_fma_f32 v[96:97], v[94:95], v[96:97], s[46:47] op_sel_hi:[1,1,0]
	s_nop 0
	v_pk_fma_f32 v[94:95], v[94:95], v[96:97], s[48:49] op_sel_hi:[1,1,0]
	s_nop 0
	v_pk_mul_f32 v[92:93], v[92:93], v[94:95]
	v_lshlrev_b32_e32 v94, 16, v104
	v_pk_fma_f32 v[90:91], v[90:91], v[92:93], v[90:91]
	v_and_b32_e32 v95, 0xffff0000, v104
	v_pk_mul_f32 v[86:87], v[86:87], v[90:91]
	v_cvt_pk_bf16_f32 v90, v84, v85
	v_mov_b64_e32 v[84:85], s[8:9]
	v_mad_i64_i32 v[170:171], s[8:9], v3, s91, v[84:85]
	v_cvt_pk_bf16_f32 v91, v86, v87
	v_lshl_add_u64 v[86:87], v[170:171], 0, v[180:181]
	global_store_dwordx4 v[86:87], v[88:91], off nt
	v_mov_b32_dpp v3, v108 row_ror:1 row_mask:0xf bank_mask:0xf bound_ctrl:1
	v_mov_b32_dpp v93, v109 row_ror:2 row_mask:0xf bank_mask:0xf bound_ctrl:1
	v_mov_b32_dpp v91, v108 row_ror:2 row_mask:0xf bank_mask:0xf bound_ctrl:1
	v_mov_b32_dpp v3, v104 row_shr:1 row_mask:0xf bank_mask:0xf
	v_lshlrev_b32_e32 v86, 16, v3
	v_mov_b32_dpp v91, v104 row_shr:2 row_mask:0xf bank_mask:0xf
	v_lshlrev_b32_e32 v90, 16, v91
	v_and_b32_e32 v91, 0xffff0000, v91
	v_and_b32_e32 v87, 0xffff0000, v3
	v_pk_fma_f32 v[90:91], v[148:149], v[90:91], v[160:161]
	v_mov_b32_dpp v89, v109 row_ror:1 row_mask:0xf bank_mask:0xf bound_ctrl:1
	v_pk_fma_f32 v[86:87], v[152:153], v[86:87], v[90:91]
; __device__ __forceinline__ unsigned cvt_pk_bf16(float lo, float hi) { unsigned r; asm volatile("v_cvt_pk_bf16_f32 %0, %1, %2" : "=v"(r) : "v"(lo), "v"(hi)); return r; }
;     static __device__ __forceinline__ void unpk4(const u32x2 w, float (&o)[4]) { o[0] = bf_lo(w.x); o[1] = bf_hi(w.x); o[2] = bf_lo(w.y); o[3] = bf_hi(w.y); }
;     template <int N> static __device__ __forceinline__ u32x2 dpp_prev(const u32x2 pv, const u32x2 cur) { u32x2 r; r.x = dpp_prev1<N>(pv.x, cur.x); r.y = dpp_prev1<N>(pv.y, cur.y); return r; }
;     static __device__ __forceinline__ u32x2 finish2(const float (&g0)[4], const float (&g1)[4], const float (&g2)[4], const float (&w0)[4], const float (&w1)[4], const float (&w2)[4], const float (&bb)[4],
;                                                     const f32x4 v, float rs) {
;         float h[4];
; #pragma unroll
;         for (int j = 0; j < 4; j += 2) {
;             const f32x2 gc = (f32x2){bb[j] + w0[j] * g2[j] + w1[j] * g1[j] + w2[j] * g0[j], bb[j + 1] + w0[j + 1] * g2[j + 1] + w1[j + 1] * g1[j + 1] + w2[j + 1] * g0[j + 1]};
;             const f32x2 ge = gelu_pk(gc) * ((f32x2){v[j], v[j + 1]} * rs); h[j] = ge.x; h[j + 1] = ge.y; }
;         u32x2 w; w.x = cvt_pk_bf16(h[0], h[1]); w.y = cvt_pk_bf16(h[2], h[3]); return w;
;     __device__ __forceinline__ void operator()(const f32x4 (&acc)[2][2][4][2], const Unit& u, int wr, int wc, int fr, int fq) const {
;     ...
;                 for (int m = 0; m < 4; ++m) { const u32x4 cur = gq[m]; u32x4 hw;
; #pragma unroll
;                     for (int hv = 0; hv < 2; ++hv) { const u32x2 c2 = half2(cur, hv), p2 = half2(pv, hv);
;                         const u32x2 q1 = dpp_prev<1>(p2, c2), q2 = dpp_prev<2>(p2, c2);
;                         float g0[4], g1[4], g2[4]; unpk4(c2, g0); unpk4(q1, g1); unpk4(q2, g2);
;                         const u32x2 r = finish2(g0, g1, g2, w0[hv], w1[hv], w2[hv], bb[hv], acc[ai][bj][m][hv], rs8[ai][m]);
;                         if (hv == 0) { hw.x = r.x; hw.y = r.y; } else { hw.z = r.x; hw.w = r.y; } }
;                     *(u32x4*)(H + (size_t)(R0 + fr + 16 * m) * 2816 + col8) = hw;
	v_mov_b32_dpp v93, v105 row_shr:2 row_mask:0xf bank_mask:0xf
	v_pk_fma_f32 v[86:87], v[156:157], v[94:95], v[86:87]
	v_mov_b32_dpp v89, v105 row_shr:1 row_mask:0xf bank_mask:0xf
	v_pk_mul_f32 v[90:91], v[86:87], s[30:31] op_sel_hi:[1,0]
	v_lshlrev_b32_e32 v92, 16, v93
	v_med3_f32 v90, v90, s47, v225
	v_med3_f32 v91, v91, s47, v225
	v_pk_mul_f32 v[94:95], v[90:91], v[90:91]
	v_and_b32_e32 v93, 0xffff0000, v93
	v_pk_fma_f32 v[96:97], v[94:95], s[34:35], v[116:117] op_sel_hi:[1,0,0] neg_lo:[1,0,0] neg_hi:[1,0,0]
	v_pk_mul_f32 v[86:87], v[86:87], 0.5 op_sel_hi:[1,0]
	v_pk_fma_f32 v[96:97], v[94:95], v[96:97], s[38:39] op_sel_hi:[1,1,0]
	v_lshlrev_b32_e32 v88, 16, v89
	v_pk_fma_f32 v[96:97], v[94:95], v[96:97], s[40:41] op_sel_hi:[1,1,0]
	v_and_b32_e32 v89, 0xffff0000, v89
	v_pk_fma_f32 v[96:97], v[94:95], v[96:97], s[42:43] op_sel_hi:[1,1,0]
	v_mov_b32_dpp v3, v110 row_ror:1 row_mask:0xf bank_mask:0xf bound_ctrl:1
	v_pk_fma_f32 v[96:97], v[94:95], v[96:97], s[44:45] op_sel_hi:[1,1,0]
	s_nop 0
	v_pk_fma_f32 v[96:97], v[94:95], v[96:97], s[46:47] op_sel_hi:[1,1,0]
	v_mov_b32_dpp v3, v106 row_shr:1 row_mask:0xf bank_mask:0xf
	v_pk_fma_f32 v[94:95], v[94:95], v[96:97], s[48:49] op_sel_hi:[1,1,0]
	s_nop 0
	v_pk_mul_f32 v[90:91], v[90:91], v[94:95]
	s_nop 0
	v_pk_fma_f32 v[86:87], v[86:87], v[90:91], v[86:87]
	v_pk_fma_f32 v[90:91], v[150:151], v[92:93], v[162:163]
	v_pk_mul_f32 v[80:81], v[80:81], v[86:87]
	v_lshlrev_b32_e32 v86, 16, v105
	v_and_b32_e32 v87, 0xffff0000, v105
	v_pk_fma_f32 v[88:89], v[154:155], v[88:89], v[90:91]
	v_cvt_pk_bf16_f32 v80, v80, v81
	s_nop 0
	v_pk_fma_f32 v[86:87], v[158:159], v[86:87], v[88:89]
	s_nop 0
	v_pk_mul_f32 v[88:89], v[86:87], s[30:31] op_sel_hi:[1,0]
	v_pk_mul_f32 v[86:87], v[86:87], 0.5 op_sel_hi:[1,0]
	v_med3_f32 v88, v88, s47, v225
	v_med3_f32 v89, v89, s47, v225
	v_pk_mul_f32 v[90:91], v[88:89], v[88:89]
	s_nop 0
	v_pk_fma_f32 v[92:93], v[90:91], s[34:35], v[116:117] op_sel_hi:[1,0,0] neg_lo:[1,0,0] neg_hi:[1,0,0]
	s_nop 0
	v_pk_fma_f32 v[92:93], v[90:91], v[92:93], s[38:39] op_sel_hi:[1,1,0]
	s_nop 0
	v_pk_fma_f32 v[92:93], v[90:91], v[92:93], s[40:41] op_sel_hi:[1,1,0]
	s_nop 0
	v_pk_fma_f32 v[92:93], v[90:91], v[92:93], s[42:43] op_sel_hi:[1,1,0]
	s_nop 0
	v_pk_fma_f32 v[92:93], v[90:91], v[92:93], s[44:45] op_sel_hi:[1,1,0]
	s_nop 0
	v_pk_fma_f32 v[92:93], v[90:91], v[92:93], s[46:47] op_sel_hi:[1,1,0]
	s_nop 0
	v_pk_fma_f32 v[90:91], v[90:91], v[92:93], s[48:49] op_sel_hi:[1,1,0]
	v_lshlrev_b32_e32 v92, 16, v106
	v_pk_mul_f32 v[88:89], v[88:89], v[90:91]
	v_and_b32_e32 v93, 0xffff0000, v106
	v_pk_fma_f32 v[86:87], v[86:87], v[88:89], v[86:87]
	v_mov_b32_dpp v89, v110 row_ror:2 row_mask:0xf bank_mask:0xf bound_ctrl:1
	v_pk_mul_f32 v[82:83], v[82:83], v[86:87]
	v_mov_b32_dpp v91, v111 row_ror:2 row_mask:0xf bank_mask:0xf bound_ctrl:1
	v_mov_b32_dpp v89, v106 row_shr:2 row_mask:0xf bank_mask:0xf
	v_lshlrev_b32_e32 v88, 16, v89
	v_and_b32_e32 v89, 0xffff0000, v89
	v_cvt_pk_bf16_f32 v81, v82, v83
	v_lshlrev_b32_e32 v82, 16, v3
	v_and_b32_e32 v83, 0xffff0000, v3
	v_pk_fma_f32 v[88:89], v[132:133], v[88:89], v[144:145]
	v_mov_b32_dpp v87, v111 row_ror:1 row_mask:0xf bank_mask:0xf bound_ctrl:1
	v_pk_fma_f32 v[82:83], v[136:137], v[82:83], v[88:89]
	v_mov_b32_dpp v91, v107 row_shr:2 row_mask:0xf bank_mask:0xf
	v_pk_fma_f32 v[82:83], v[140:141], v[92:93], v[82:83]
	v_mov_b32_dpp v87, v107 row_shr:1 row_mask:0xf bank_mask:0xf
	v_pk_mul_f32 v[88:89], v[82:83], s[30:31] op_sel_hi:[1,0]
	v_lshlrev_b32_e32 v90, 16, v91
	v_med3_f32 v88, v88, s47, v225
	v_med3_f32 v89, v89, s47, v225
	v_pk_mul_f32 v[92:93], v[88:89], v[88:89]
	v_and_b32_e32 v91, 0xffff0000, v91
	v_pk_fma_f32 v[94:95], v[92:93], s[34:35], v[116:117] op_sel_hi:[1,0,0] neg_lo:[1,0,0] neg_hi:[1,0,0]
	v_pk_mul_f32 v[82:83], v[82:83], 0.5 op_sel_hi:[1,0]
	v_pk_fma_f32 v[94:95], v[92:93], v[94:95], s[38:39] op_sel_hi:[1,1,0]
	v_lshlrev_b32_e32 v86, 16, v87
	v_pk_fma_f32 v[94:95], v[92:93], v[94:95], s[40:41] op_sel_hi:[1,1,0]
	v_and_b32_e32 v87, 0xffff0000, v87
	v_pk_fma_f32 v[94:95], v[92:93], v[94:95], s[42:43] op_sel_hi:[1,1,0]
	v_add_u32_e32 v3, 32, v1
	v_pk_fma_f32 v[94:95], v[92:93], v[94:95], s[44:45] op_sel_hi:[1,1,0]
	v_mad_i64_i32 v[174:175], s[8:9], v3, s91, v[84:85]
	v_pk_fma_f32 v[94:95], v[92:93], v[94:95], s[46:47] op_sel_hi:[1,1,0]
	v_mov_b32_dpp v3, v104 row_ror:1 row_mask:0xf bank_mask:0xf bound_ctrl:1
	v_pk_fma_f32 v[92:93], v[92:93], v[94:95], s[48:49] op_sel_hi:[1,1,0]
	v_add_u32_e32 v1, 48, v1
	v_pk_mul_f32 v[88:89], v[88:89], v[92:93]
	v_mov_b32_dpp v3, v100 row_shr:1 row_mask:0xf bank_mask:0xf
	v_pk_fma_f32 v[82:83], v[82:83], v[88:89], v[82:83]
	v_pk_fma_f32 v[88:89], v[134:135], v[90:91], v[146:147]
	v_pk_mul_f32 v[76:77], v[76:77], v[82:83]
	v_lshlrev_b32_e32 v82, 16, v107
	v_and_b32_e32 v83, 0xffff0000, v107
	v_pk_fma_f32 v[86:87], v[138:139], v[86:87], v[88:89]
	s_nop 0
	v_pk_fma_f32 v[82:83], v[142:143], v[82:83], v[86:87]
	s_nop 0
	v_pk_mul_f32 v[86:87], v[82:83], s[30:31] op_sel_hi:[1,0]
	v_pk_mul_f32 v[82:83], v[82:83], 0.5 op_sel_hi:[1,0]
	v_med3_f32 v86, v86, s47, v225
	v_med3_f32 v87, v87, s47, v225
	v_pk_mul_f32 v[88:89], v[86:87], v[86:87]
	s_nop 0
	v_pk_fma_f32 v[90:91], v[88:89], s[34:35], v[116:117] op_sel_hi:[1,0,0] neg_lo:[1,0,0] neg_hi:[1,0,0]
	s_nop 0
	v_pk_fma_f32 v[90:91], v[88:89], v[90:91], s[38:39] op_sel_hi:[1,1,0]
	s_nop 0
	v_pk_fma_f32 v[90:91], v[88:89], v[90:91], s[40:41] op_sel_hi:[1,1,0]
	s_nop 0
	v_pk_fma_f32 v[90:91], v[88:89], v[90:91], s[42:43] op_sel_hi:[1,1,0]
	s_nop 0
	v_pk_fma_f32 v[90:91], v[88:89], v[90:91], s[44:45] op_sel_hi:[1,1,0]
	s_nop 0
	v_pk_fma_f32 v[90:91], v[88:89], v[90:91], s[46:47] op_sel_hi:[1,1,0]
; __device__ __forceinline__ unsigned cvt_pk_bf16(float lo, float hi) { unsigned r; asm volatile("v_cvt_pk_bf16_f32 %0, %1, %2" : "=v"(r) : "v"(lo), "v"(hi)); return r; }
;     static __device__ __forceinline__ void unpk4(const u32x2 w, float (&o)[4]) { o[0] = bf_lo(w.x); o[1] = bf_hi(w.x); o[2] = bf_lo(w.y); o[3] = bf_hi(w.y); }
;     template <int N> static __device__ __forceinline__ u32x2 dpp_prev(const u32x2 pv, const u32x2 cur) { u32x2 r; r.x = dpp_prev1<N>(pv.x, cur.x); r.y = dpp_prev1<N>(pv.y, cur.y); return r; }
;     static __device__ __forceinline__ u32x2 finish2(const float (&g0)[4], const float (&g1)[4], const float (&g2)[4], const float (&w0)[4], const float (&w1)[4], const float (&w2)[4], const float (&bb)[4],
;                                                     const f32x4 v, float rs) {
;         float h[4];
; #pragma unroll
;         for (int j = 0; j < 4; j += 2) {
;             const f32x2 gc = (f32x2){bb[j] + w0[j] * g2[j] + w1[j] * g1[j] + w2[j] * g0[j], bb[j + 1] + w0[j + 1] * g2[j + 1] + w1[j + 1] * g1[j + 1] + w2[j + 1] * g0[j + 1]};
;             const f32x2 ge = gelu_pk(gc) * ((f32x2){v[j], v[j + 1]} * rs); h[j] = ge.x; h[j + 1] = ge.y; }
;         u32x2 w; w.x = cvt_pk_bf16(h[0], h[1]); w.y = cvt_pk_bf16(h[2], h[3]); return w;
;     }
;     __device__ __forceinline__ void operator()(const f32x4 (&acc)[2][2][4][2], const Unit& u, int wr, int wc, int fr, int fq) const {
;     ...
;                 for (int m = 0; m < 4; ++m) { const u32x4 cur = gq[m]; u32x4 hw;
; #pragma unroll
;                     for (int hv = 0; hv < 2; ++hv) { const u32x2 c2 = half2(cur, hv), p2 = half2(pv, hv);
;                         const u32x2 q1 = dpp_prev<1>(p2, c2), q2 = dpp_prev<2>(p2, c2);
;                         float g0[4], g1[4], g2[4]; unpk4(c2, g0); unpk4(q1, g1); unpk4(q2, g2);
;                         const u32x2 r = finish2(g0, g1, g2, w0[hv], w1[hv], w2[hv], bb[hv], acc[ai][bj][m][hv], rs8[ai][m]);
;                         if (hv == 0) { hw.x = r.x; hw.y = r.y; } else { hw.z = r.x; hw.w = r.y; } }
;                     *(u32x4*)(H + (size_t)(R0 + fr + 16 * m) * 2816 + col8) = hw;
;                     pv = cur; } }
	s_nop 0
	v_pk_fma_f32 v[88:89], v[88:89], v[90:91], s[48:49] op_sel_hi:[1,1,0]
	s_nop 0
	v_pk_mul_f32 v[86:87], v[86:87], v[88:89]
	s_nop 0
	v_pk_fma_f32 v[82:83], v[82:83], v[86:87], v[82:83]
	v_lshlrev_b32_e32 v86, 16, v100
	v_pk_mul_f32 v[78:79], v[78:79], v[82:83]
	v_cvt_pk_bf16_f32 v82, v76, v77
	v_lshl_add_u64 v[76:77], v[174:175], 0, v[180:181]
	v_cvt_pk_bf16_f32 v83, v78, v79
	global_store_dwordx4 v[76:77], v[80:83], off nt
	v_lshlrev_b32_e32 v76, 16, v3
	v_and_b32_e32 v77, 0xffff0000, v3
	v_mov_b32_dpp v81, v104 row_ror:2 row_mask:0xf bank_mask:0xf bound_ctrl:1
	v_and_b32_e32 v87, 0xffff0000, v100
	v_mov_b32_dpp v83, v105 row_ror:2 row_mask:0xf bank_mask:0xf bound_ctrl:1
	v_mov_b32_dpp v81, v100 row_shr:2 row_mask:0xf bank_mask:0xf
	v_lshlrev_b32_e32 v80, 16, v81
	v_and_b32_e32 v81, 0xffff0000, v81
	v_pk_fma_f32 v[80:81], v[148:149], v[80:81], v[160:161]
	v_mov_b32_dpp v79, v105 row_ror:1 row_mask:0xf bank_mask:0xf bound_ctrl:1
	v_pk_fma_f32 v[76:77], v[152:153], v[76:77], v[80:81]
	v_mov_b32_dpp v83, v101 row_shr:2 row_mask:0xf bank_mask:0xf
	v_pk_fma_f32 v[76:77], v[156:157], v[86:87], v[76:77]
	v_mov_b32_dpp v79, v101 row_shr:1 row_mask:0xf bank_mask:0xf
	v_pk_mul_f32 v[80:81], v[76:77], s[30:31] op_sel_hi:[1,0]
	v_lshlrev_b32_e32 v82, 16, v83
	v_med3_f32 v80, v80, s47, v225
	v_med3_f32 v81, v81, s47, v225
	v_pk_mul_f32 v[86:87], v[80:81], v[80:81]
	v_and_b32_e32 v83, 0xffff0000, v83
	v_pk_fma_f32 v[88:89], v[86:87], s[34:35], v[116:117] op_sel_hi:[1,0,0] neg_lo:[1,0,0] neg_hi:[1,0,0]
	v_pk_mul_f32 v[76:77], v[76:77], 0.5 op_sel_hi:[1,0]
	v_pk_fma_f32 v[88:89], v[86:87], v[88:89], s[38:39] op_sel_hi:[1,1,0]
	v_lshlrev_b32_e32 v78, 16, v79
	v_pk_fma_f32 v[88:89], v[86:87], v[88:89], s[40:41] op_sel_hi:[1,1,0]
	v_and_b32_e32 v79, 0xffff0000, v79
	v_pk_fma_f32 v[88:89], v[86:87], v[88:89], s[42:43] op_sel_hi:[1,1,0]
	v_mov_b32_dpp v3, v106 row_ror:1 row_mask:0xf bank_mask:0xf bound_ctrl:1
	v_pk_fma_f32 v[88:89], v[86:87], v[88:89], s[44:45] op_sel_hi:[1,1,0]
	s_nop 0
	v_pk_fma_f32 v[88:89], v[86:87], v[88:89], s[46:47] op_sel_hi:[1,1,0]
	v_mov_b32_dpp v3, v102 row_shr:1 row_mask:0xf bank_mask:0xf
	v_pk_fma_f32 v[86:87], v[86:87], v[88:89], s[48:49] op_sel_hi:[1,1,0]
	s_nop 0
	v_pk_mul_f32 v[80:81], v[80:81], v[86:87]
	s_nop 0
	v_pk_fma_f32 v[76:77], v[76:77], v[80:81], v[76:77]
	v_pk_fma_f32 v[80:81], v[150:151], v[82:83], v[162:163]
	v_pk_mul_f32 v[72:73], v[72:73], v[76:77]
	v_lshlrev_b32_e32 v76, 16, v101
	v_and_b32_e32 v77, 0xffff0000, v101
	v_pk_fma_f32 v[78:79], v[154:155], v[78:79], v[80:81]
	v_cvt_pk_bf16_f32 v72, v72, v73
	s_nop 0
	v_pk_fma_f32 v[76:77], v[158:159], v[76:77], v[78:79]
	s_nop 0
	v_pk_mul_f32 v[78:79], v[76:77], s[30:31] op_sel_hi:[1,0]
	v_pk_mul_f32 v[76:77], v[76:77], 0.5 op_sel_hi:[1,0]
	v_med3_f32 v78, v78, s47, v225
	v_med3_f32 v79, v79, s47, v225
	v_pk_mul_f32 v[80:81], v[78:79], v[78:79]
	s_nop 0
	v_pk_fma_f32 v[82:83], v[80:81], s[34:35], v[116:117] op_sel_hi:[1,0,0] neg_lo:[1,0,0] neg_hi:[1,0,0]
	s_nop 0
	v_pk_fma_f32 v[82:83], v[80:81], v[82:83], s[38:39] op_sel_hi:[1,1,0]
	s_nop 0
	v_pk_fma_f32 v[82:83], v[80:81], v[82:83], s[40:41] op_sel_hi:[1,1,0]
	s_nop 0
	v_pk_fma_f32 v[82:83], v[80:81], v[82:83], s[42:43] op_sel_hi:[1,1,0]
	s_nop 0
	v_pk_fma_f32 v[82:83], v[80:81], v[82:83], s[44:45] op_sel_hi:[1,1,0]
	s_nop 0
	v_pk_fma_f32 v[82:83], v[80:81], v[82:83], s[46:47] op_sel_hi:[1,1,0]
	s_nop 0
	v_pk_fma_f32 v[80:81], v[80:81], v[82:83], s[48:49] op_sel_hi:[1,1,0]
	v_lshlrev_b32_e32 v82, 16, v102
	v_pk_mul_f32 v[78:79], v[78:79], v[80:81]
	v_and_b32_e32 v83, 0xffff0000, v102
	v_pk_fma_f32 v[76:77], v[76:77], v[78:79], v[76:77]
	v_mov_b32_dpp v79, v106 row_ror:2 row_mask:0xf bank_mask:0xf bound_ctrl:1
	v_pk_mul_f32 v[74:75], v[74:75], v[76:77]
	v_mov_b32_dpp v81, v107 row_ror:2 row_mask:0xf bank_mask:0xf bound_ctrl:1
	v_mov_b32_dpp v79, v102 row_shr:2 row_mask:0xf bank_mask:0xf
	v_lshlrev_b32_e32 v78, 16, v79
	v_and_b32_e32 v79, 0xffff0000, v79
	v_cvt_pk_bf16_f32 v73, v74, v75
	v_lshlrev_b32_e32 v74, 16, v3
	v_and_b32_e32 v75, 0xffff0000, v3
	v_pk_fma_f32 v[78:79], v[132:133], v[78:79], v[144:145]
	v_mov_b32_dpp v77, v107 row_ror:1 row_mask:0xf bank_mask:0xf bound_ctrl:1
	v_pk_fma_f32 v[74:75], v[136:137], v[74:75], v[78:79]
	v_mov_b32_dpp v81, v103 row_shr:2 row_mask:0xf bank_mask:0xf
	v_pk_fma_f32 v[74:75], v[140:141], v[82:83], v[74:75]
	v_mov_b32_dpp v77, v103 row_shr:1 row_mask:0xf bank_mask:0xf
	v_pk_mul_f32 v[78:79], v[74:75], s[30:31] op_sel_hi:[1,0]
	v_lshlrev_b32_e32 v80, 16, v81
	v_med3_f32 v78, v78, s47, v225
	v_med3_f32 v79, v79, s47, v225
	v_pk_mul_f32 v[82:83], v[78:79], v[78:79]
	v_and_b32_e32 v81, 0xffff0000, v81
	v_pk_fma_f32 v[86:87], v[82:83], s[34:35], v[116:117] op_sel_hi:[1,0,0] neg_lo:[1,0,0] neg_hi:[1,0,0]
	v_pk_mul_f32 v[74:75], v[74:75], 0.5 op_sel_hi:[1,0]
	v_pk_fma_f32 v[86:87], v[82:83], v[86:87], s[38:39] op_sel_hi:[1,1,0]
	v_lshlrev_b32_e32 v76, 16, v77
	v_pk_fma_f32 v[86:87], v[82:83], v[86:87], s[40:41] op_sel_hi:[1,1,0]
	v_and_b32_e32 v77, 0xffff0000, v77
	v_pk_fma_f32 v[86:87], v[82:83], v[86:87], s[42:43] op_sel_hi:[1,1,0]
	v_mad_i64_i32 v[132:133], s[8:9], v1, s91, v[84:85]
	v_pk_fma_f32 v[86:87], v[82:83], v[86:87], s[44:45] op_sel_hi:[1,1,0]
	v_readlane_b32 s8, v240, 19
	v_pk_fma_f32 v[86:87], v[82:83], v[86:87], s[46:47] op_sel_hi:[1,1,0]
	v_readlane_b32 s9, v240, 20
	v_pk_fma_f32 v[82:83], v[82:83], v[86:87], s[48:49] op_sel_hi:[1,1,0]
	s_nop 0
	v_pk_mul_f32 v[78:79], v[78:79], v[82:83]
	s_nop 0
	v_pk_fma_f32 v[74:75], v[74:75], v[78:79], v[74:75]
	v_pk_fma_f32 v[78:79], v[134:135], v[80:81], v[146:147]
	v_pk_mul_f32 v[64:65], v[64:65], v[74:75]
;     static __device__ __forceinline__ void unpk4(const u32x2 w, float (&o)[4]) { o[0] = bf_lo(w.x); o[1] = bf_hi(w.x); o[2] = bf_lo(w.y); o[3] = bf_hi(w.y); }
;     template <int N> static __device__ __forceinline__ u32x2 dpp_prev(const u32x2 pv, const u32x2 cur) { u32x2 r; r.x = dpp_prev1<N>(pv.x, cur.x); r.y = dpp_prev1<N>(pv.y, cur.y); return r; }
;     __device__ __forceinline__ void operator()(const f32x4 (&acc)[2][2][4][2], const Unit& u, int wr, int wc, int fr, int fq) const {
;     ...
;             const int col8 = u.pn * BM + bj * HALF + wc * 32 + 8 * fq;
;             float w0[2][4], w1[2][4], w2[2][4], bb[2][4];
; #pragma unroll
;             for (int hv = 0; hv < 2; ++hv) { ld4f(cw + col8 + 4 * hv, w0[hv]); ld4f(cw + 2816 + col8 + 4 * hv, w1[hv]); ld4f(cw + 2 * 2816 + col8 + 4 * hv, w2[hv]); ld4f(cb + col8 + 4 * hv, bb[hv]); }
; #pragma unroll
;             for (int ai = 0; ai < 2; ++ai) { const int R0 = u.rb + ai * HALF + wr * 64; const bf16_t* gp = G + (size_t)(R0 + fr) * 2816 + col8;
;                 u32x4 gq[4], prv = (u32x4){0u, 0u, 0u, 0u};
; #pragma unroll
;                 for (int m = 0; m < 4; ++m) gq[m] = *(const u32x4*)(gp + (size_t)m * 16 * 2816);
;                 if ((R0 & 8191) != 0) prv = *(const u32x4*)(gp - (size_t)16 * 2816);
;                 u32x4 pv = prv;
; #pragma unroll
;                 for (int m = 0; m < 4; ++m) { const u32x4 cur = gq[m]; u32x4 hw;
; #pragma unroll
;                     for (int hv = 0; hv < 2; ++hv) { const u32x2 c2 = half2(cur, hv), p2 = half2(pv, hv);
;                         const u32x2 q1 = dpp_prev<1>(p2, c2), q2 = dpp_prev<2>(p2, c2);
;                         float g0[4], g1[4], g2[4]; unpk4(c2, g0); unpk4(q1, g1); unpk4(q2, g2);
;                         const u32x2 r = finish2(g0, g1, g2, w0[hv], w1[hv], w2[hv], bb[hv], acc[ai][bj][m][hv], rs8[ai][m]);
;                         if (hv == 0) { hw.x = r.x; hw.y = r.y; } else { hw.z = r.x; hw.w = r.y; } }
;                     *(u32x4*)(H + (size_t)(R0 + fr + 16 * m) * 2816 + col8) = hw;
;                     pv = cur; } }
	v_lshlrev_b32_e32 v74, 16, v103
	v_and_b32_e32 v75, 0xffff0000, v103
	v_pk_fma_f32 v[76:77], v[138:139], v[76:77], v[78:79]
	v_add_u32_e32 v134, 0x80, v212
	v_pk_fma_f32 v[74:75], v[142:143], v[74:75], v[76:77]
	v_ashrrev_i32_e32 v135, 31, v134
	v_pk_mul_f32 v[76:77], v[74:75], s[30:31] op_sel_hi:[1,0]
	v_pk_mul_f32 v[74:75], v[74:75], 0.5 op_sel_hi:[1,0]
	v_med3_f32 v76, v76, s47, v225
	v_med3_f32 v77, v77, s47, v225
	v_pk_mul_f32 v[78:79], v[76:77], v[76:77]
	v_lshl_add_u64 v[136:137], v[134:135], 1, v[214:215]
	v_pk_fma_f32 v[80:81], v[78:79], s[34:35], v[116:117] op_sel_hi:[1,0,0] neg_lo:[1,0,0] neg_hi:[1,0,0]
	v_add_co_u32_e32 v100, vcc, s10, v136
	v_pk_fma_f32 v[80:81], v[78:79], v[80:81], s[38:39] op_sel_hi:[1,1,0]
	s_nop 0
	v_addc_co_u32_e32 v101, vcc, 0, v137, vcc
	v_pk_fma_f32 v[80:81], v[78:79], v[80:81], s[40:41] op_sel_hi:[1,1,0]
	s_nop 0
	v_pk_fma_f32 v[80:81], v[78:79], v[80:81], s[42:43] op_sel_hi:[1,1,0]
	s_nop 0
	v_pk_fma_f32 v[80:81], v[78:79], v[80:81], s[44:45] op_sel_hi:[1,1,0]
	s_nop 0
	v_pk_fma_f32 v[80:81], v[78:79], v[80:81], s[46:47] op_sel_hi:[1,1,0]
	s_nop 0
	v_pk_fma_f32 v[78:79], v[78:79], v[80:81], s[48:49] op_sel_hi:[1,1,0]
	s_nop 0
	v_pk_mul_f32 v[76:77], v[76:77], v[78:79]
	s_nop 0
	v_pk_fma_f32 v[74:75], v[74:75], v[76:77], v[74:75]
	s_nop 0
	v_pk_mul_f32 v[66:67], v[66:67], v[74:75]
	v_cvt_pk_bf16_f32 v74, v64, v65
	v_lshl_add_u64 v[64:65], v[132:133], 0, v[180:181]
	v_cvt_pk_bf16_f32 v75, v66, v67
	global_store_dwordx4 v[64:65], v[72:75], off nt
	v_lshlrev_b64 v[64:65], 2, v[134:135]
	v_lshl_add_u64 v[76:77], s[8:9], 0, v[64:65]
	v_readlane_b32 s8, v240, 21
	v_readlane_b32 s9, v240, 22
	v_lshl_add_u64 v[72:73], s[66:67], 0, v[64:65]
	v_lshl_add_u64 v[96:97], s[88:89], 0, v[64:65]
	v_lshl_add_u64 v[80:81], s[8:9], 0, v[64:65]
	global_load_dwordx4 v[64:67], v[72:73], off offset:16
	global_load_dwordx4 v[84:87], v[72:73], off
	s_nop 0
	global_load_dwordx4 v[72:75], v[76:77], off offset:16
	global_load_dwordx4 v[88:91], v[76:77], off
	s_nop 0
	global_load_dwordx4 v[76:79], v[80:81], off offset:16
	global_load_dwordx4 v[92:95], v[80:81], off
	s_nop 0
	global_load_dwordx4 v[80:83], v[96:97], off offset:16
	s_nop 0
	global_load_dwordx4 v[96:99], v[96:97], off
	s_nop 0
	global_load_dwordx4 v[114:117], v[136:137], off
	global_load_dwordx4 v[110:113], v[100:101], off
	v_add_co_u32_e32 v100, vcc, 0x2c000, v136
	s_nop 1
	v_addc_co_u32_e32 v101, vcc, 0, v137, vcc
	global_load_dwordx4 v[106:109], v[100:101], off
	v_add_co_u32_e32 v100, vcc, 0x42000, v136
	s_nop 1
	v_addc_co_u32_e32 v101, vcc, 0, v137, vcc
	global_load_dwordx4 v[102:105], v[100:101], off
	v_mov_b32_e32 v100, 0
	s_andn2_b64 vcc, exec, s[0:1]
	s_cbranch_vccnz .LBB0_1018
	v_add_co_u32_e32 v118, vcc, 0xfffea000, v136
	s_nop 1
	v_addc_co_u32_e32 v119, vcc, -1, v137, vcc
	global_load_dwordx4 v[118:121], v[118:119], off
.LBB0_1018:
	s_waitcnt vmcnt(0)
	s_nop 0
	v_mov_b32_dpp v123, v118 row_ror:2 row_mask:0xf bank_mask:0xf bound_ctrl:1
	v_mov_b32_dpp v1, v118 row_ror:1 row_mask:0xf bank_mask:0xf bound_ctrl:1
	v_mov_b32_dpp v101, v119 row_ror:1 row_mask:0xf bank_mask:0xf bound_ctrl:1
	v_mov_b32_dpp v123, v114 row_shr:2 row_mask:0xf bank_mask:0xf
	v_mov_b32_dpp v1, v114 row_shr:1 row_mask:0xf bank_mask:0xf
	v_lshlrev_b32_e32 v138, 16, v123
	v_and_b32_e32 v139, 0xffff0000, v123
	v_mov_b32_dpp v125, v119 row_ror:2 row_mask:0xf bank_mask:0xf bound_ctrl:1
	v_lshlrev_b32_e32 v118, 16, v1
	v_and_b32_e32 v119, 0xffff0000, v1
	v_pk_fma_f32 v[138:139], v[84:85], v[138:139], v[96:97]
	v_lshlrev_b32_e32 v142, 16, v114
	v_and_b32_e32 v143, 0xffff0000, v114
	v_pk_fma_f32 v[118:119], v[88:89], v[118:119], v[138:139]
	v_mov_b32_dpp v125, v115 row_shr:2 row_mask:0xf bank_mask:0xf
	v_pk_fma_f32 v[138:139], v[92:93], v[142:143], v[118:119]
	v_mov_b32_e32 v189, v188
	v_pk_mul_f32 v[118:119], v[138:139], s[30:31] op_sel_hi:[1,0]
	v_mov_b32_dpp v101, v115 row_shr:1 row_mask:0xf bank_mask:0xf
	v_med3_f32 v142, v118, s47, v225
	v_med3_f32 v143, v119, s47, v225
	v_pk_mul_f32 v[144:145], v[142:143], v[142:143]
	v_mov_b64_e32 v[118:119], s[36:37]
	v_pk_fma_f32 v[146:147], v[144:145], s[34:35], v[118:119] op_sel_hi:[1,0,0] neg_lo:[1,0,0] neg_hi:[1,0,0]
	v_lshlrev_b32_e32 v140, 16, v125
	v_pk_fma_f32 v[146:147], v[144:145], v[146:147], s[38:39] op_sel_hi:[1,1,0]
	v_and_b32_e32 v141, 0xffff0000, v125
	v_pk_fma_f32 v[146:147], v[144:145], v[146:147], s[40:41] op_sel_hi:[1,1,0]
	v_pk_mul_f32 v[138:139], v[138:139], 0.5 op_sel_hi:[1,0]
	v_pk_fma_f32 v[146:147], v[144:145], v[146:147], s[42:43] op_sel_hi:[1,1,0]
	v_lshlrev_b32_e32 v136, 16, v101
	v_pk_fma_f32 v[146:147], v[144:145], v[146:147], s[44:45] op_sel_hi:[1,1,0]
	v_and_b32_e32 v137, 0xffff0000, v101
	v_pk_fma_f32 v[146:147], v[144:145], v[146:147], s[46:47] op_sel_hi:[1,1,0]
	v_pk_mul_f32 v[68:69], v[68:69], v[188:189]
	v_pk_fma_f32 v[144:145], v[144:145], v[146:147], s[48:49] op_sel_hi:[1,1,0]
	v_pk_fma_f32 v[140:141], v[86:87], v[140:141], v[98:99]
	v_pk_mul_f32 v[142:143], v[142:143], v[144:145]
	v_pk_fma_f32 v[136:137], v[90:91], v[136:137], v[140:141]
	v_pk_fma_f32 v[138:139], v[138:139], v[142:143], v[138:139]
	v_mov_b32_dpp v123, v120 row_ror:2 row_mask:0xf bank_mask:0xf bound_ctrl:1
	v_pk_mul_f32 v[68:69], v[68:69], v[138:139]
	v_lshlrev_b32_e32 v138, 16, v115
	v_and_b32_e32 v139, 0xffff0000, v115
	v_pk_fma_f32 v[136:137], v[94:95], v[138:139], v[136:137]
	v_pk_mul_f32 v[70:71], v[70:71], v[188:189]
	v_pk_mul_f32 v[138:139], v[136:137], s[30:31] op_sel_hi:[1,0]
	v_pk_mul_f32 v[136:137], v[136:137], 0.5 op_sel_hi:[1,0]
	v_med3_f32 v138, v138, s47, v225
	v_med3_f32 v139, v139, s47, v225
	v_pk_mul_f32 v[140:141], v[138:139], v[138:139]
; __device__ __forceinline__ unsigned cvt_pk_bf16(float lo, float hi) { unsigned r; asm volatile("v_cvt_pk_bf16_f32 %0, %1, %2" : "=v"(r) : "v"(lo), "v"(hi)); return r; }
;     static __device__ __forceinline__ void unpk4(const u32x2 w, float (&o)[4]) { o[0] = bf_lo(w.x); o[1] = bf_hi(w.x); o[2] = bf_lo(w.y); o[3] = bf_hi(w.y); }
;     template <int N> static __device__ __forceinline__ u32x2 dpp_prev(const u32x2 pv, const u32x2 cur) { u32x2 r; r.x = dpp_prev1<N>(pv.x, cur.x); r.y = dpp_prev1<N>(pv.y, cur.y); return r; }
;     static __device__ __forceinline__ u32x2 finish2(const float (&g0)[4], const float (&g1)[4], const float (&g2)[4], const float (&w0)[4], const float (&w1)[4], const float (&w2)[4], const float (&bb)[4],
;                                                     const f32x4 v, float rs) {
;         float h[4];
; #pragma unroll
;         for (int j = 0; j < 4; j += 2) {
;             const f32x2 gc = (f32x2){bb[j] + w0[j] * g2[j] + w1[j] * g1[j] + w2[j] * g0[j], bb[j + 1] + w0[j + 1] * g2[j + 1] + w1[j + 1] * g1[j + 1] + w2[j + 1] * g0[j + 1]};
;             const f32x2 ge = gelu_pk(gc) * ((f32x2){v[j], v[j + 1]} * rs); h[j] = ge.x; h[j + 1] = ge.y; }
;         u32x2 w; w.x = cvt_pk_bf16(h[0], h[1]); w.y = cvt_pk_bf16(h[2], h[3]); return w;
;     }
;     __device__ __forceinline__ void operator()(const f32x4 (&acc)[2][2][4][2], const Unit& u, int wr, int wc, int fr, int fq) const {
;     ...
;                 for (int m = 0; m < 4; ++m) { const u32x4 cur = gq[m]; u32x4 hw;
; #pragma unroll
;                     for (int hv = 0; hv < 2; ++hv) { const u32x2 c2 = half2(cur, hv), p2 = half2(pv, hv);
;                         const u32x2 q1 = dpp_prev<1>(p2, c2), q2 = dpp_prev<2>(p2, c2);
;                         float g0[4], g1[4], g2[4]; unpk4(c2, g0); unpk4(q1, g1); unpk4(q2, g2);
;                         const u32x2 r = finish2(g0, g1, g2, w0[hv], w1[hv], w2[hv], bb[hv], acc[ai][bj][m][hv], rs8[ai][m]);
;                         if (hv == 0) { hw.x = r.x; hw.y = r.y; } else { hw.z = r.x; hw.w = r.y; } }
;                     *(u32x4*)(H + (size_t)(R0 + fr + 16 * m) * 2816 + col8) = hw;
;                     pv = cur; } }
	v_mov_b32_dpp v1, v120 row_ror:1 row_mask:0xf bank_mask:0xf bound_ctrl:1
	v_pk_fma_f32 v[142:143], v[140:141], s[34:35], v[118:119] op_sel_hi:[1,0,0] neg_lo:[1,0,0] neg_hi:[1,0,0]
	v_mov_b32_dpp v123, v116 row_shr:2 row_mask:0xf bank_mask:0xf
	v_pk_fma_f32 v[142:143], v[140:141], v[142:143], s[38:39] op_sel_hi:[1,1,0]
	v_mov_b32_dpp v1, v116 row_shr:1 row_mask:0xf bank_mask:0xf
	v_pk_fma_f32 v[142:143], v[140:141], v[142:143], s[40:41] op_sel_hi:[1,1,0]
	v_cvt_pk_bf16_f32 v68, v68, v69
	v_mov_b32_dpp v125, v121 row_ror:2 row_mask:0xf bank_mask:0xf bound_ctrl:1
	v_pk_fma_f32 v[142:143], v[140:141], v[142:143], s[42:43] op_sel_hi:[1,1,0]
	v_mov_b32_dpp v101, v121 row_ror:1 row_mask:0xf bank_mask:0xf bound_ctrl:1
	v_pk_fma_f32 v[142:143], v[140:141], v[142:143], s[44:45] op_sel_hi:[1,1,0]
	v_mov_b32_dpp v125, v117 row_shr:2 row_mask:0xf bank_mask:0xf
	v_pk_fma_f32 v[142:143], v[140:141], v[142:143], s[46:47] op_sel_hi:[1,1,0]
	v_mov_b32_dpp v101, v117 row_shr:1 row_mask:0xf bank_mask:0xf
	v_pk_fma_f32 v[140:141], v[140:141], v[142:143], s[48:49] op_sel_hi:[1,1,0]
	v_lshlrev_b32_e32 v120, 16, v101
	v_pk_mul_f32 v[138:139], v[138:139], v[140:141]
	v_lshlrev_b32_e32 v140, 16, v116
	v_pk_fma_f32 v[136:137], v[136:137], v[138:139], v[136:137]
	v_and_b32_e32 v141, 0xffff0000, v116
	v_pk_mul_f32 v[70:71], v[70:71], v[136:137]
	v_lshlrev_b32_e32 v136, 16, v123
	v_and_b32_e32 v137, 0xffff0000, v123
	v_cvt_pk_bf16_f32 v69, v70, v71
	v_lshlrev_b32_e32 v70, 16, v1
	v_and_b32_e32 v71, 0xffff0000, v1
	v_pk_fma_f32 v[136:137], v[64:65], v[136:137], v[80:81]
	v_lshlrev_b32_e32 v138, 16, v125
	v_pk_fma_f32 v[70:71], v[72:73], v[70:71], v[136:137]
	v_and_b32_e32 v139, 0xffff0000, v125
	v_pk_fma_f32 v[70:71], v[76:77], v[140:141], v[70:71]
	v_and_b32_e32 v121, 0xffff0000, v101
	v_pk_mul_f32 v[136:137], v[70:71], s[30:31] op_sel_hi:[1,0]
	v_pk_mul_f32 v[70:71], v[70:71], 0.5 op_sel_hi:[1,0]
	v_med3_f32 v136, v136, s47, v225
	v_med3_f32 v137, v137, s47, v225
	v_pk_mul_f32 v[140:141], v[136:137], v[136:137]
	v_pk_mul_f32 v[60:61], v[60:61], v[188:189]
	v_pk_fma_f32 v[142:143], v[140:141], s[34:35], v[118:119] op_sel_hi:[1,0,0] neg_lo:[1,0,0] neg_hi:[1,0,0]
	v_pk_mul_f32 v[62:63], v[62:63], v[188:189]
	v_pk_fma_f32 v[142:143], v[140:141], v[142:143], s[38:39] op_sel_hi:[1,1,0]
	v_mov_b32_dpp v1, v114 row_ror:1 row_mask:0xf bank_mask:0xf bound_ctrl:1
	v_pk_fma_f32 v[142:143], v[140:141], v[142:143], s[40:41] op_sel_hi:[1,1,0]
	v_mov_b32_dpp v101, v115 row_ror:2 row_mask:0xf bank_mask:0xf bound_ctrl:1
	v_pk_fma_f32 v[142:143], v[140:141], v[142:143], s[42:43] op_sel_hi:[1,1,0]
	v_mov_b32_dpp v1, v110 row_shr:1 row_mask:0xf bank_mask:0xf
	v_pk_fma_f32 v[142:143], v[140:141], v[142:143], s[44:45] op_sel_hi:[1,1,0]
	v_mov_b32_dpp v101, v111 row_shr:2 row_mask:0xf bank_mask:0xf
	v_pk_fma_f32 v[142:143], v[140:141], v[142:143], s[46:47] op_sel_hi:[1,1,0]
	v_mov_b32_e32 v187, v186
	v_pk_fma_f32 v[140:141], v[140:141], v[142:143], s[48:49] op_sel_hi:[1,1,0]
	v_pk_mul_f32 v[56:57], v[56:57], v[186:187]
	v_pk_mul_f32 v[136:137], v[136:137], v[140:141]
	v_pk_mul_f32 v[58:59], v[58:59], v[186:187]
	v_pk_fma_f32 v[70:71], v[70:71], v[136:137], v[70:71]
	v_pk_fma_f32 v[136:137], v[66:67], v[138:139], v[82:83]
	v_pk_mul_f32 v[60:61], v[60:61], v[70:71]
	v_lshlrev_b32_e32 v70, 16, v117
	v_and_b32_e32 v71, 0xffff0000, v117
	v_pk_fma_f32 v[120:121], v[74:75], v[120:121], v[136:137]
	v_pk_mul_f32 v[52:53], v[52:53], v[186:187]
	v_pk_fma_f32 v[70:71], v[78:79], v[70:71], v[120:121]
	v_pk_mul_f32 v[54:55], v[54:55], v[186:187]
	v_pk_mul_f32 v[120:121], v[70:71], s[30:31] op_sel_hi:[1,0]
	v_pk_mul_f32 v[70:71], v[70:71], 0.5 op_sel_hi:[1,0]
	v_med3_f32 v120, v120, s47, v225
	v_med3_f32 v121, v121, s47, v225
	v_pk_mul_f32 v[136:137], v[120:121], v[120:121]
	v_mov_b32_e32 v185, v184
	v_pk_fma_f32 v[138:139], v[136:137], s[34:35], v[118:119] op_sel_hi:[1,0,0] neg_lo:[1,0,0] neg_hi:[1,0,0]
	v_pk_mul_f32 v[48:49], v[48:49], v[184:185]
	v_pk_fma_f32 v[138:139], v[136:137], v[138:139], s[38:39] op_sel_hi:[1,1,0]
	v_pk_mul_f32 v[50:51], v[50:51], v[184:185]
	v_pk_fma_f32 v[138:139], v[136:137], v[138:139], s[40:41] op_sel_hi:[1,1,0]
	v_pk_mul_f32 v[44:45], v[44:45], v[184:185]
	v_pk_fma_f32 v[138:139], v[136:137], v[138:139], s[42:43] op_sel_hi:[1,1,0]
	v_pk_mul_f32 v[46:47], v[46:47], v[184:185]
	v_pk_fma_f32 v[138:139], v[136:137], v[138:139], s[44:45] op_sel_hi:[1,1,0]
	v_mov_b32_e32 v3, v2
	v_pk_fma_f32 v[138:139], v[136:137], v[138:139], s[46:47] op_sel_hi:[1,1,0]
	v_pk_mul_f32 v[40:41], v[40:41], v[2:3]
	v_pk_fma_f32 v[136:137], v[136:137], v[138:139], s[48:49] op_sel_hi:[1,1,0]
	v_pk_mul_f32 v[42:43], v[42:43], v[2:3]
	v_pk_mul_f32 v[120:121], v[120:121], v[136:137]
	v_pk_mul_f32 v[36:37], v[36:37], v[2:3]
	v_pk_fma_f32 v[70:71], v[70:71], v[120:121], v[70:71]
	v_lshlrev_b32_e32 v120, 16, v110
	v_pk_mul_f32 v[62:63], v[62:63], v[70:71]
	v_cvt_pk_bf16_f32 v70, v60, v61
	v_lshlrev_b64 v[60:61], 1, v[134:135]
	v_cvt_pk_bf16_f32 v71, v62, v63
	v_lshl_add_u64 v[62:63], v[130:131], 0, v[60:61]
	global_store_dwordx4 v[62:63], v[68:71], off nt
	v_lshlrev_b32_e32 v62, 16, v1
	v_and_b32_e32 v63, 0xffff0000, v1
	v_mov_b32_dpp v71, v114 row_ror:2 row_mask:0xf bank_mask:0xf bound_ctrl:1
	v_and_b32_e32 v121, 0xffff0000, v110
	v_mov_b32_dpp v69, v115 row_ror:1 row_mask:0xf bank_mask:0xf bound_ctrl:1
	v_mov_b32_dpp v71, v110 row_shr:2 row_mask:0xf bank_mask:0xf
	v_lshlrev_b32_e32 v70, 16, v71
	v_and_b32_e32 v71, 0xffff0000, v71
	v_pk_fma_f32 v[70:71], v[84:85], v[70:71], v[96:97]
	v_mov_b32_dpp v69, v111 row_shr:1 row_mask:0xf bank_mask:0xf
	v_pk_fma_f32 v[62:63], v[88:89], v[62:63], v[70:71]
; __device__ __forceinline__ unsigned cvt_pk_bf16(float lo, float hi) { unsigned r; asm volatile("v_cvt_pk_bf16_f32 %0, %1, %2" : "=v"(r) : "v"(lo), "v"(hi)); return r; }
;     static __device__ __forceinline__ void unpk4(const u32x2 w, float (&o)[4]) { o[0] = bf_lo(w.x); o[1] = bf_hi(w.x); o[2] = bf_lo(w.y); o[3] = bf_hi(w.y); }
;     template <int N> static __device__ __forceinline__ u32x2 dpp_prev(const u32x2 pv, const u32x2 cur) { u32x2 r; r.x = dpp_prev1<N>(pv.x, cur.x); r.y = dpp_prev1<N>(pv.y, cur.y); return r; }
;     static __device__ __forceinline__ u32x2 finish2(const float (&g0)[4], const float (&g1)[4], const float (&g2)[4], const float (&w0)[4], const float (&w1)[4], const float (&w2)[4], const float (&bb)[4],
;                                                     const f32x4 v, float rs) {
;         float h[4];
; #pragma unroll
;         for (int j = 0; j < 4; j += 2) {
;             const f32x2 gc = (f32x2){bb[j] + w0[j] * g2[j] + w1[j] * g1[j] + w2[j] * g0[j], bb[j + 1] + w0[j + 1] * g2[j + 1] + w1[j + 1] * g1[j + 1] + w2[j + 1] * g0[j + 1]};
;             const f32x2 ge = gelu_pk(gc) * ((f32x2){v[j], v[j + 1]} * rs); h[j] = ge.x; h[j + 1] = ge.y; }
;         u32x2 w; w.x = cvt_pk_bf16(h[0], h[1]); w.y = cvt_pk_bf16(h[2], h[3]); return w;
;     }
;     __device__ __forceinline__ void operator()(const f32x4 (&acc)[2][2][4][2], const Unit& u, int wr, int wc, int fr, int fq) const {
;     ...
;                 for (int m = 0; m < 4; ++m) { const u32x4 cur = gq[m]; u32x4 hw;
; #pragma unroll
;                     for (int hv = 0; hv < 2; ++hv) { const u32x2 c2 = half2(cur, hv), p2 = half2(pv, hv);
;                         const u32x2 q1 = dpp_prev<1>(p2, c2), q2 = dpp_prev<2>(p2, c2);
;                         float g0[4], g1[4], g2[4]; unpk4(c2, g0); unpk4(q1, g1); unpk4(q2, g2);
;                         const u32x2 r = finish2(g0, g1, g2, w0[hv], w1[hv], w2[hv], bb[hv], acc[ai][bj][m][hv], rs8[ai][m]);
;                         if (hv == 0) { hw.x = r.x; hw.y = r.y; } else { hw.z = r.x; hw.w = r.y; } }
	v_lshlrev_b32_e32 v114, 16, v101
	v_pk_fma_f32 v[62:63], v[92:93], v[120:121], v[62:63]
	v_and_b32_e32 v115, 0xffff0000, v101
	v_pk_mul_f32 v[70:71], v[62:63], s[30:31] op_sel_hi:[1,0]
	v_pk_mul_f32 v[62:63], v[62:63], 0.5 op_sel_hi:[1,0]
	v_med3_f32 v70, v70, s47, v225
	v_med3_f32 v71, v71, s47, v225
	v_pk_mul_f32 v[120:121], v[70:71], v[70:71]
	v_lshlrev_b32_e32 v68, 16, v69
	v_pk_fma_f32 v[130:131], v[120:121], s[34:35], v[118:119] op_sel_hi:[1,0,0] neg_lo:[1,0,0] neg_hi:[1,0,0]
	v_and_b32_e32 v69, 0xffff0000, v69
	v_pk_fma_f32 v[130:131], v[120:121], v[130:131], s[38:39] op_sel_hi:[1,1,0]
	v_mov_b32_dpp v1, v116 row_ror:1 row_mask:0xf bank_mask:0xf bound_ctrl:1
	v_pk_fma_f32 v[130:131], v[120:121], v[130:131], s[40:41] op_sel_hi:[1,1,0]
	v_pk_mul_f32 v[2:3], v[38:39], v[2:3]
	v_pk_fma_f32 v[130:131], v[120:121], v[130:131], s[42:43] op_sel_hi:[1,1,0]
	v_mov_b32_dpp v1, v112 row_shr:1 row_mask:0xf bank_mask:0xf
	v_pk_fma_f32 v[130:131], v[120:121], v[130:131], s[44:45] op_sel_hi:[1,1,0]
	v_readlane_b32 s64, v240, 23
	v_pk_fma_f32 v[130:131], v[120:121], v[130:131], s[46:47] op_sel_hi:[1,1,0]
	v_mov_b32_e32 v101, 0
	v_pk_fma_f32 v[120:121], v[120:121], v[130:131], s[48:49] op_sel_hi:[1,1,0]
	v_readlane_b32 s65, v240, 24
	v_pk_mul_f32 v[70:71], v[70:71], v[120:121]
	s_mov_b64 s[54:55], s[68:69]
	v_pk_fma_f32 v[62:63], v[62:63], v[70:71], v[62:63]
	v_pk_fma_f32 v[70:71], v[86:87], v[114:115], v[98:99]
	v_pk_mul_f32 v[56:57], v[56:57], v[62:63]
	v_lshlrev_b32_e32 v62, 16, v111
	v_and_b32_e32 v63, 0xffff0000, v111
	v_pk_fma_f32 v[68:69], v[90:91], v[68:69], v[70:71]
	v_cvt_pk_bf16_f32 v56, v56, v57
	s_nop 0
	v_pk_fma_f32 v[62:63], v[94:95], v[62:63], v[68:69]
	s_nop 0
	v_pk_mul_f32 v[68:69], v[62:63], s[30:31] op_sel_hi:[1,0]
	v_pk_mul_f32 v[62:63], v[62:63], 0.5 op_sel_hi:[1,0]
	v_med3_f32 v68, v68, s47, v225
	v_med3_f32 v69, v69, s47, v225
	v_pk_mul_f32 v[70:71], v[68:69], v[68:69]
	s_nop 0
	v_pk_fma_f32 v[114:115], v[70:71], s[34:35], v[118:119] op_sel_hi:[1,0,0] neg_lo:[1,0,0] neg_hi:[1,0,0]
	s_nop 0
	v_pk_fma_f32 v[114:115], v[70:71], v[114:115], s[38:39] op_sel_hi:[1,1,0]
	s_nop 0
	v_pk_fma_f32 v[114:115], v[70:71], v[114:115], s[40:41] op_sel_hi:[1,1,0]
	s_nop 0
	v_pk_fma_f32 v[114:115], v[70:71], v[114:115], s[42:43] op_sel_hi:[1,1,0]
	s_nop 0
	v_pk_fma_f32 v[114:115], v[70:71], v[114:115], s[44:45] op_sel_hi:[1,1,0]
	s_nop 0
	v_pk_fma_f32 v[114:115], v[70:71], v[114:115], s[46:47] op_sel_hi:[1,1,0]
	s_nop 0
	v_pk_fma_f32 v[70:71], v[70:71], v[114:115], s[48:49] op_sel_hi:[1,1,0]
	v_lshlrev_b32_e32 v114, 16, v112
	v_pk_mul_f32 v[68:69], v[68:69], v[70:71]
	v_and_b32_e32 v115, 0xffff0000, v112
	v_pk_fma_f32 v[62:63], v[62:63], v[68:69], v[62:63]
	v_mov_b32_dpp v69, v116 row_ror:2 row_mask:0xf bank_mask:0xf bound_ctrl:1
	v_pk_mul_f32 v[58:59], v[58:59], v[62:63]
	v_mov_b32_dpp v63, v117 row_ror:1 row_mask:0xf bank_mask:0xf bound_ctrl:1
	v_mov_b32_dpp v69, v112 row_shr:2 row_mask:0xf bank_mask:0xf
	v_lshlrev_b32_e32 v68, 16, v69
	v_and_b32_e32 v69, 0xffff0000, v69
	v_cvt_pk_bf16_f32 v57, v58, v59
	v_lshlrev_b32_e32 v58, 16, v1
	v_and_b32_e32 v59, 0xffff0000, v1
	v_pk_fma_f32 v[68:69], v[64:65], v[68:69], v[80:81]
	v_mov_b32_dpp v71, v117 row_ror:2 row_mask:0xf bank_mask:0xf bound_ctrl:1
	v_pk_fma_f32 v[58:59], v[72:73], v[58:59], v[68:69]
	v_mov_b32_dpp v63, v113 row_shr:1 row_mask:0xf bank_mask:0xf
	v_pk_fma_f32 v[58:59], v[76:77], v[114:115], v[58:59]
	v_mov_b32_dpp v71, v113 row_shr:2 row_mask:0xf bank_mask:0xf
	v_pk_mul_f32 v[68:69], v[58:59], s[30:31] op_sel_hi:[1,0]
	v_lshlrev_b32_e32 v70, 16, v71
	v_med3_f32 v68, v68, s47, v225
	v_med3_f32 v69, v69, s47, v225
	v_pk_mul_f32 v[114:115], v[68:69], v[68:69]
	v_and_b32_e32 v71, 0xffff0000, v71
	v_pk_fma_f32 v[116:117], v[114:115], s[34:35], v[118:119] op_sel_hi:[1,0,0] neg_lo:[1,0,0] neg_hi:[1,0,0]
	v_pk_mul_f32 v[58:59], v[58:59], 0.5 op_sel_hi:[1,0]
	v_pk_fma_f32 v[116:117], v[114:115], v[116:117], s[38:39] op_sel_hi:[1,1,0]
	v_lshlrev_b32_e32 v62, 16, v63
	v_pk_fma_f32 v[116:117], v[114:115], v[116:117], s[40:41] op_sel_hi:[1,1,0]
	v_and_b32_e32 v63, 0xffff0000, v63
	v_pk_fma_f32 v[116:117], v[114:115], v[116:117], s[42:43] op_sel_hi:[1,1,0]
	v_mov_b32_dpp v1, v110 row_ror:1 row_mask:0xf bank_mask:0xf bound_ctrl:1
	v_pk_fma_f32 v[116:117], v[114:115], v[116:117], s[44:45] op_sel_hi:[1,1,0]
	s_nop 0
	v_pk_fma_f32 v[116:117], v[114:115], v[116:117], s[46:47] op_sel_hi:[1,1,0]
	v_mov_b32_dpp v1, v106 row_shr:1 row_mask:0xf bank_mask:0xf
	v_pk_fma_f32 v[114:115], v[114:115], v[116:117], s[48:49] op_sel_hi:[1,1,0]
	s_nop 0
	v_pk_mul_f32 v[68:69], v[68:69], v[114:115]
	s_nop 0
	v_pk_fma_f32 v[58:59], v[58:59], v[68:69], v[58:59]
	v_pk_fma_f32 v[68:69], v[66:67], v[70:71], v[82:83]
	v_pk_mul_f32 v[52:53], v[52:53], v[58:59]
	v_lshlrev_b32_e32 v58, 16, v113
	v_and_b32_e32 v59, 0xffff0000, v113
	v_pk_fma_f32 v[62:63], v[74:75], v[62:63], v[68:69]
	s_nop 0
	v_pk_fma_f32 v[58:59], v[78:79], v[58:59], v[62:63]
	s_nop 0
	v_pk_mul_f32 v[62:63], v[58:59], s[30:31] op_sel_hi:[1,0]
	v_pk_mul_f32 v[58:59], v[58:59], 0.5 op_sel_hi:[1,0]
	v_med3_f32 v62, v62, s47, v225
	v_med3_f32 v63, v63, s47, v225
	v_pk_mul_f32 v[68:69], v[62:63], v[62:63]
	s_nop 0
	v_pk_fma_f32 v[70:71], v[68:69], s[34:35], v[118:119] op_sel_hi:[1,0,0] neg_lo:[1,0,0] neg_hi:[1,0,0]
	s_nop 0
	v_pk_fma_f32 v[70:71], v[68:69], v[70:71], s[38:39] op_sel_hi:[1,1,0]
	s_nop 0
	v_pk_fma_f32 v[70:71], v[68:69], v[70:71], s[40:41] op_sel_hi:[1,1,0]
	s_nop 0
	v_pk_fma_f32 v[70:71], v[68:69], v[70:71], s[42:43] op_sel_hi:[1,1,0]
	s_nop 0
	v_pk_fma_f32 v[70:71], v[68:69], v[70:71], s[44:45] op_sel_hi:[1,1,0]
	s_nop 0
; __device__ __forceinline__ unsigned cvt_pk_bf16(float lo, float hi) { unsigned r; asm volatile("v_cvt_pk_bf16_f32 %0, %1, %2" : "=v"(r) : "v"(lo), "v"(hi)); return r; }
;     static __device__ __forceinline__ void unpk4(const u32x2 w, float (&o)[4]) { o[0] = bf_lo(w.x); o[1] = bf_hi(w.x); o[2] = bf_lo(w.y); o[3] = bf_hi(w.y); }
;     template <int N> static __device__ __forceinline__ u32x2 dpp_prev(const u32x2 pv, const u32x2 cur) { u32x2 r; r.x = dpp_prev1<N>(pv.x, cur.x); r.y = dpp_prev1<N>(pv.y, cur.y); return r; }
;     static __device__ __forceinline__ u32x2 finish2(const float (&g0)[4], const float (&g1)[4], const float (&g2)[4], const float (&w0)[4], const float (&w1)[4], const float (&w2)[4], const float (&bb)[4],
;                                                     const f32x4 v, float rs) {
;         float h[4];
; #pragma unroll
;         for (int j = 0; j < 4; j += 2) {
;             const f32x2 gc = (f32x2){bb[j] + w0[j] * g2[j] + w1[j] * g1[j] + w2[j] * g0[j], bb[j + 1] + w0[j + 1] * g2[j + 1] + w1[j + 1] * g1[j + 1] + w2[j + 1] * g0[j + 1]};
;             const f32x2 ge = gelu_pk(gc) * ((f32x2){v[j], v[j + 1]} * rs); h[j] = ge.x; h[j + 1] = ge.y; }
;         u32x2 w; w.x = cvt_pk_bf16(h[0], h[1]); w.y = cvt_pk_bf16(h[2], h[3]); return w;
;     }
;     __device__ __forceinline__ void operator()(const f32x4 (&acc)[2][2][4][2], const Unit& u, int wr, int wc, int fr, int fq) const {
;     ...
;                 for (int m = 0; m < 4; ++m) { const u32x4 cur = gq[m]; u32x4 hw;
; #pragma unroll
;                     for (int hv = 0; hv < 2; ++hv) { const u32x2 c2 = half2(cur, hv), p2 = half2(pv, hv);
;                         const u32x2 q1 = dpp_prev<1>(p2, c2), q2 = dpp_prev<2>(p2, c2);
;                         float g0[4], g1[4], g2[4]; unpk4(c2, g0); unpk4(q1, g1); unpk4(q2, g2);
;                         const u32x2 r = finish2(g0, g1, g2, w0[hv], w1[hv], w2[hv], bb[hv], acc[ai][bj][m][hv], rs8[ai][m]);
;                         if (hv == 0) { hw.x = r.x; hw.y = r.y; } else { hw.z = r.x; hw.w = r.y; } }
;                     *(u32x4*)(H + (size_t)(R0 + fr + 16 * m) * 2816 + col8) = hw;
;                     pv = cur; } }
	v_pk_fma_f32 v[70:71], v[68:69], v[70:71], s[46:47] op_sel_hi:[1,1,0]
	s_nop 0
	v_pk_fma_f32 v[68:69], v[68:69], v[70:71], s[48:49] op_sel_hi:[1,1,0]
	s_nop 0
	v_pk_mul_f32 v[62:63], v[62:63], v[68:69]
	s_nop 0
	v_pk_fma_f32 v[58:59], v[58:59], v[62:63], v[58:59]
	v_lshlrev_b32_e32 v62, 16, v106
	v_pk_mul_f32 v[54:55], v[54:55], v[58:59]
	v_cvt_pk_bf16_f32 v58, v52, v53
	v_lshl_add_u64 v[52:53], v[176:177], 0, v[60:61]
	v_cvt_pk_bf16_f32 v59, v54, v55
	global_store_dwordx4 v[52:53], v[56:59], off nt
	v_lshlrev_b32_e32 v52, 16, v1
	v_and_b32_e32 v53, 0xffff0000, v1
	v_mov_b32_dpp v57, v110 row_ror:2 row_mask:0xf bank_mask:0xf bound_ctrl:1
	v_and_b32_e32 v63, 0xffff0000, v106
	v_mov_b32_dpp v59, v111 row_ror:2 row_mask:0xf bank_mask:0xf bound_ctrl:1
	v_mov_b32_dpp v57, v106 row_shr:2 row_mask:0xf bank_mask:0xf
	v_lshlrev_b32_e32 v56, 16, v57
	v_and_b32_e32 v57, 0xffff0000, v57
	v_pk_fma_f32 v[56:57], v[84:85], v[56:57], v[96:97]
	v_mov_b32_dpp v55, v111 row_ror:1 row_mask:0xf bank_mask:0xf bound_ctrl:1
	v_pk_fma_f32 v[52:53], v[88:89], v[52:53], v[56:57]
	v_mov_b32_dpp v59, v107 row_shr:2 row_mask:0xf bank_mask:0xf
	v_pk_fma_f32 v[52:53], v[92:93], v[62:63], v[52:53]
	v_mov_b32_dpp v55, v107 row_shr:1 row_mask:0xf bank_mask:0xf
	v_pk_mul_f32 v[56:57], v[52:53], s[30:31] op_sel_hi:[1,0]
	v_lshlrev_b32_e32 v58, 16, v59
	v_med3_f32 v56, v56, s47, v225
	v_med3_f32 v57, v57, s47, v225
	v_pk_mul_f32 v[62:63], v[56:57], v[56:57]
	v_and_b32_e32 v59, 0xffff0000, v59
	v_pk_fma_f32 v[68:69], v[62:63], s[34:35], v[118:119] op_sel_hi:[1,0,0] neg_lo:[1,0,0] neg_hi:[1,0,0]
	v_pk_mul_f32 v[52:53], v[52:53], 0.5 op_sel_hi:[1,0]
	v_pk_fma_f32 v[68:69], v[62:63], v[68:69], s[38:39] op_sel_hi:[1,1,0]
	v_lshlrev_b32_e32 v54, 16, v55
	v_pk_fma_f32 v[68:69], v[62:63], v[68:69], s[40:41] op_sel_hi:[1,1,0]
	v_and_b32_e32 v55, 0xffff0000, v55
	v_pk_fma_f32 v[68:69], v[62:63], v[68:69], s[42:43] op_sel_hi:[1,1,0]
	v_mov_b32_dpp v1, v112 row_ror:1 row_mask:0xf bank_mask:0xf bound_ctrl:1
	v_pk_fma_f32 v[68:69], v[62:63], v[68:69], s[44:45] op_sel_hi:[1,1,0]
	s_nop 0
	v_pk_fma_f32 v[68:69], v[62:63], v[68:69], s[46:47] op_sel_hi:[1,1,0]
	v_mov_b32_dpp v1, v108 row_shr:1 row_mask:0xf bank_mask:0xf
	v_pk_fma_f32 v[62:63], v[62:63], v[68:69], s[48:49] op_sel_hi:[1,1,0]
	s_nop 0
	v_pk_mul_f32 v[56:57], v[56:57], v[62:63]
	s_nop 0
	v_pk_fma_f32 v[52:53], v[52:53], v[56:57], v[52:53]
	v_pk_fma_f32 v[56:57], v[86:87], v[58:59], v[98:99]
	v_pk_mul_f32 v[48:49], v[48:49], v[52:53]
	v_lshlrev_b32_e32 v52, 16, v107
	v_and_b32_e32 v53, 0xffff0000, v107
	v_pk_fma_f32 v[54:55], v[90:91], v[54:55], v[56:57]
	v_cvt_pk_bf16_f32 v48, v48, v49
	s_nop 0
	v_pk_fma_f32 v[52:53], v[94:95], v[52:53], v[54:55]
	s_nop 0
	v_pk_mul_f32 v[54:55], v[52:53], s[30:31] op_sel_hi:[1,0]
	v_pk_mul_f32 v[52:53], v[52:53], 0.5 op_sel_hi:[1,0]
	v_med3_f32 v54, v54, s47, v225
	v_med3_f32 v55, v55, s47, v225
	v_pk_mul_f32 v[56:57], v[54:55], v[54:55]
	s_nop 0
	v_pk_fma_f32 v[58:59], v[56:57], s[34:35], v[118:119] op_sel_hi:[1,0,0] neg_lo:[1,0,0] neg_hi:[1,0,0]
	s_nop 0
	v_pk_fma_f32 v[58:59], v[56:57], v[58:59], s[38:39] op_sel_hi:[1,1,0]
	s_nop 0
	v_pk_fma_f32 v[58:59], v[56:57], v[58:59], s[40:41] op_sel_hi:[1,1,0]
	s_nop 0
	v_pk_fma_f32 v[58:59], v[56:57], v[58:59], s[42:43] op_sel_hi:[1,1,0]
	s_nop 0
	v_pk_fma_f32 v[58:59], v[56:57], v[58:59], s[44:45] op_sel_hi:[1,1,0]
	s_nop 0
	v_pk_fma_f32 v[58:59], v[56:57], v[58:59], s[46:47] op_sel_hi:[1,1,0]
	s_nop 0
	v_pk_fma_f32 v[56:57], v[56:57], v[58:59], s[48:49] op_sel_hi:[1,1,0]
	v_lshlrev_b32_e32 v58, 16, v108
	v_pk_mul_f32 v[54:55], v[54:55], v[56:57]
	v_and_b32_e32 v59, 0xffff0000, v108
	v_pk_fma_f32 v[52:53], v[52:53], v[54:55], v[52:53]
	v_mov_b32_dpp v55, v112 row_ror:2 row_mask:0xf bank_mask:0xf bound_ctrl:1
	v_pk_mul_f32 v[50:51], v[50:51], v[52:53]
	v_mov_b32_dpp v57, v113 row_ror:2 row_mask:0xf bank_mask:0xf bound_ctrl:1
	v_mov_b32_dpp v55, v108 row_shr:2 row_mask:0xf bank_mask:0xf
	v_lshlrev_b32_e32 v54, 16, v55
	v_and_b32_e32 v55, 0xffff0000, v55
	v_cvt_pk_bf16_f32 v49, v50, v51
	v_lshlrev_b32_e32 v50, 16, v1
	v_and_b32_e32 v51, 0xffff0000, v1
	v_pk_fma_f32 v[54:55], v[64:65], v[54:55], v[80:81]
	v_mov_b32_dpp v53, v113 row_ror:1 row_mask:0xf bank_mask:0xf bound_ctrl:1
	v_pk_fma_f32 v[50:51], v[72:73], v[50:51], v[54:55]
	v_mov_b32_dpp v57, v109 row_shr:2 row_mask:0xf bank_mask:0xf
	v_pk_fma_f32 v[50:51], v[76:77], v[58:59], v[50:51]
	v_mov_b32_dpp v53, v109 row_shr:1 row_mask:0xf bank_mask:0xf
	v_pk_mul_f32 v[54:55], v[50:51], s[30:31] op_sel_hi:[1,0]
	v_lshlrev_b32_e32 v56, 16, v57
	v_med3_f32 v54, v54, s47, v225
	v_med3_f32 v55, v55, s47, v225
	v_pk_mul_f32 v[58:59], v[54:55], v[54:55]
	v_and_b32_e32 v57, 0xffff0000, v57
	v_pk_fma_f32 v[62:63], v[58:59], s[34:35], v[118:119] op_sel_hi:[1,0,0] neg_lo:[1,0,0] neg_hi:[1,0,0]
	v_pk_mul_f32 v[50:51], v[50:51], 0.5 op_sel_hi:[1,0]
	v_pk_fma_f32 v[62:63], v[58:59], v[62:63], s[38:39] op_sel_hi:[1,1,0]
	v_lshlrev_b32_e32 v52, 16, v53
	v_pk_fma_f32 v[62:63], v[58:59], v[62:63], s[40:41] op_sel_hi:[1,1,0]
	v_and_b32_e32 v53, 0xffff0000, v53
	v_pk_fma_f32 v[62:63], v[58:59], v[62:63], s[42:43] op_sel_hi:[1,1,0]
	v_mov_b32_dpp v1, v106 row_ror:1 row_mask:0xf bank_mask:0xf bound_ctrl:1
	v_pk_fma_f32 v[62:63], v[58:59], v[62:63], s[44:45] op_sel_hi:[1,1,0]
	s_nop 0
	v_pk_fma_f32 v[62:63], v[58:59], v[62:63], s[46:47] op_sel_hi:[1,1,0]
	v_mov_b32_dpp v1, v102 row_shr:1 row_mask:0xf bank_mask:0xf
	v_pk_fma_f32 v[58:59], v[58:59], v[62:63], s[48:49] op_sel_hi:[1,1,0]
	s_nop 0
	v_pk_mul_f32 v[54:55], v[54:55], v[58:59]
	s_nop 0
	v_pk_fma_f32 v[50:51], v[50:51], v[54:55], v[50:51]
; __device__ __forceinline__ unsigned cvt_pk_bf16(float lo, float hi) { unsigned r; asm volatile("v_cvt_pk_bf16_f32 %0, %1, %2" : "=v"(r) : "v"(lo), "v"(hi)); return r; }
;     static __device__ __forceinline__ void unpk4(const u32x2 w, float (&o)[4]) { o[0] = bf_lo(w.x); o[1] = bf_hi(w.x); o[2] = bf_lo(w.y); o[3] = bf_hi(w.y); }
;     template <int N> static __device__ __forceinline__ u32x2 dpp_prev(const u32x2 pv, const u32x2 cur) { u32x2 r; r.x = dpp_prev1<N>(pv.x, cur.x); r.y = dpp_prev1<N>(pv.y, cur.y); return r; }
;     static __device__ __forceinline__ u32x2 finish2(const float (&g0)[4], const float (&g1)[4], const float (&g2)[4], const float (&w0)[4], const float (&w1)[4], const float (&w2)[4], const float (&bb)[4],
;                                                     const f32x4 v, float rs) {
;         float h[4];
; #pragma unroll
;         for (int j = 0; j < 4; j += 2) {
;             const f32x2 gc = (f32x2){bb[j] + w0[j] * g2[j] + w1[j] * g1[j] + w2[j] * g0[j], bb[j + 1] + w0[j + 1] * g2[j + 1] + w1[j + 1] * g1[j + 1] + w2[j + 1] * g0[j + 1]};
;             const f32x2 ge = gelu_pk(gc) * ((f32x2){v[j], v[j + 1]} * rs); h[j] = ge.x; h[j + 1] = ge.y; }
;         u32x2 w; w.x = cvt_pk_bf16(h[0], h[1]); w.y = cvt_pk_bf16(h[2], h[3]); return w;
;     }
;     __device__ __forceinline__ void operator()(const f32x4 (&acc)[2][2][4][2], const Unit& u, int wr, int wc, int fr, int fq) const {
;     ...
;                 for (int m = 0; m < 4; ++m) { const u32x4 cur = gq[m]; u32x4 hw;
; #pragma unroll
;                     for (int hv = 0; hv < 2; ++hv) { const u32x2 c2 = half2(cur, hv), p2 = half2(pv, hv);
;                         const u32x2 q1 = dpp_prev<1>(p2, c2), q2 = dpp_prev<2>(p2, c2);
;                         float g0[4], g1[4], g2[4]; unpk4(c2, g0); unpk4(q1, g1); unpk4(q2, g2);
;                         const u32x2 r = finish2(g0, g1, g2, w0[hv], w1[hv], w2[hv], bb[hv], acc[ai][bj][m][hv], rs8[ai][m]);
;                         if (hv == 0) { hw.x = r.x; hw.y = r.y; } else { hw.z = r.x; hw.w = r.y; } }
;                     *(u32x4*)(H + (size_t)(R0 + fr + 16 * m) * 2816 + col8) = hw;
;                     pv = cur; } }
	v_pk_fma_f32 v[54:55], v[66:67], v[56:57], v[82:83]
	v_pk_mul_f32 v[44:45], v[44:45], v[50:51]
	v_lshlrev_b32_e32 v50, 16, v109
	v_and_b32_e32 v51, 0xffff0000, v109
	v_pk_fma_f32 v[52:53], v[74:75], v[52:53], v[54:55]
	s_nop 0
	v_pk_fma_f32 v[50:51], v[78:79], v[50:51], v[52:53]
	s_nop 0
	v_pk_mul_f32 v[52:53], v[50:51], s[30:31] op_sel_hi:[1,0]
	v_pk_mul_f32 v[50:51], v[50:51], 0.5 op_sel_hi:[1,0]
	v_med3_f32 v52, v52, s47, v225
	v_med3_f32 v53, v53, s47, v225
	v_pk_mul_f32 v[54:55], v[52:53], v[52:53]
	s_nop 0
	v_pk_fma_f32 v[56:57], v[54:55], s[34:35], v[118:119] op_sel_hi:[1,0,0] neg_lo:[1,0,0] neg_hi:[1,0,0]
	s_nop 0
	v_pk_fma_f32 v[56:57], v[54:55], v[56:57], s[38:39] op_sel_hi:[1,1,0]
	s_nop 0
	v_pk_fma_f32 v[56:57], v[54:55], v[56:57], s[40:41] op_sel_hi:[1,1,0]
	s_nop 0
	v_pk_fma_f32 v[56:57], v[54:55], v[56:57], s[42:43] op_sel_hi:[1,1,0]
	s_nop 0
	v_pk_fma_f32 v[56:57], v[54:55], v[56:57], s[44:45] op_sel_hi:[1,1,0]
	s_nop 0
	v_pk_fma_f32 v[56:57], v[54:55], v[56:57], s[46:47] op_sel_hi:[1,1,0]
	s_nop 0
	v_pk_fma_f32 v[54:55], v[54:55], v[56:57], s[48:49] op_sel_hi:[1,1,0]
	v_lshl_add_u64 v[56:57], v[166:167], 0, v[60:61]
	v_pk_mul_f32 v[52:53], v[52:53], v[54:55]
	s_nop 0
	v_pk_fma_f32 v[50:51], v[50:51], v[52:53], v[50:51]
	v_lshlrev_b32_e32 v52, 16, v102
	v_pk_mul_f32 v[46:47], v[46:47], v[50:51]
	v_cvt_pk_bf16_f32 v50, v44, v45
	v_lshl_add_u64 v[44:45], v[172:173], 0, v[60:61]
	v_cvt_pk_bf16_f32 v51, v46, v47
	global_store_dwordx4 v[44:45], v[48:51], off nt
	v_lshlrev_b32_e32 v44, 16, v1
	v_and_b32_e32 v45, 0xffff0000, v1
	v_mov_b32_dpp v49, v106 row_ror:2 row_mask:0xf bank_mask:0xf bound_ctrl:1
	v_and_b32_e32 v53, 0xffff0000, v102
	v_mov_b32_dpp v51, v107 row_ror:2 row_mask:0xf bank_mask:0xf bound_ctrl:1
	v_mov_b32_dpp v49, v102 row_shr:2 row_mask:0xf bank_mask:0xf
	v_lshlrev_b32_e32 v48, 16, v49
	v_and_b32_e32 v49, 0xffff0000, v49
	v_pk_fma_f32 v[48:49], v[84:85], v[48:49], v[96:97]
	v_mov_b32_dpp v47, v107 row_ror:1 row_mask:0xf bank_mask:0xf bound_ctrl:1
	v_pk_fma_f32 v[44:45], v[88:89], v[44:45], v[48:49]
	v_mov_b32_dpp v51, v103 row_shr:2 row_mask:0xf bank_mask:0xf
	v_pk_fma_f32 v[44:45], v[92:93], v[52:53], v[44:45]
	v_mov_b32_dpp v47, v103 row_shr:1 row_mask:0xf bank_mask:0xf
	v_pk_mul_f32 v[48:49], v[44:45], s[30:31] op_sel_hi:[1,0]
	v_lshlrev_b32_e32 v50, 16, v51
	v_med3_f32 v48, v48, s47, v225
	v_med3_f32 v49, v49, s47, v225
	v_pk_mul_f32 v[52:53], v[48:49], v[48:49]
	v_and_b32_e32 v51, 0xffff0000, v51
	v_pk_fma_f32 v[54:55], v[52:53], s[34:35], v[118:119] op_sel_hi:[1,0,0] neg_lo:[1,0,0] neg_hi:[1,0,0]
	v_pk_mul_f32 v[44:45], v[44:45], 0.5 op_sel_hi:[1,0]
	v_pk_fma_f32 v[54:55], v[52:53], v[54:55], s[38:39] op_sel_hi:[1,1,0]
	v_lshlrev_b32_e32 v46, 16, v47
	v_pk_fma_f32 v[54:55], v[52:53], v[54:55], s[40:41] op_sel_hi:[1,1,0]
	v_and_b32_e32 v47, 0xffff0000, v47
	v_pk_fma_f32 v[54:55], v[52:53], v[54:55], s[42:43] op_sel_hi:[1,1,0]
	v_mov_b32_dpp v1, v108 row_ror:1 row_mask:0xf bank_mask:0xf bound_ctrl:1
	v_pk_fma_f32 v[54:55], v[52:53], v[54:55], s[44:45] op_sel_hi:[1,1,0]
	v_mov_b32_e32 v102, 0
	v_pk_fma_f32 v[54:55], v[52:53], v[54:55], s[46:47] op_sel_hi:[1,1,0]
	v_mov_b32_dpp v1, v104 row_shr:1 row_mask:0xf bank_mask:0xf
	v_pk_fma_f32 v[52:53], v[52:53], v[54:55], s[48:49] op_sel_hi:[1,1,0]
	s_nop 0
	v_pk_mul_f32 v[48:49], v[48:49], v[52:53]
	s_nop 0
	v_pk_fma_f32 v[44:45], v[44:45], v[48:49], v[44:45]
	v_pk_fma_f32 v[48:49], v[86:87], v[50:51], v[98:99]
	v_pk_mul_f32 v[40:41], v[40:41], v[44:45]
	v_lshlrev_b32_e32 v44, 16, v103
	v_and_b32_e32 v45, 0xffff0000, v103
	v_pk_fma_f32 v[46:47], v[90:91], v[46:47], v[48:49]
	v_cvt_pk_bf16_f32 v52, v40, v41
	v_lshlrev_b32_e32 v40, 16, v1
	v_pk_fma_f32 v[44:45], v[94:95], v[44:45], v[46:47]
	v_and_b32_e32 v41, 0xffff0000, v1
	v_pk_mul_f32 v[46:47], v[44:45], s[30:31] op_sel_hi:[1,0]
	v_pk_mul_f32 v[44:45], v[44:45], 0.5 op_sel_hi:[1,0]
	v_med3_f32 v46, v46, s47, v225
	v_med3_f32 v47, v47, s47, v225
	v_pk_mul_f32 v[48:49], v[46:47], v[46:47]
	v_mov_b32_e32 v103, 0
	v_pk_fma_f32 v[50:51], v[48:49], s[34:35], v[118:119] op_sel_hi:[1,0,0] neg_lo:[1,0,0] neg_hi:[1,0,0]
	s_nop 0
	v_pk_fma_f32 v[50:51], v[48:49], v[50:51], s[38:39] op_sel_hi:[1,1,0]
	s_nop 0
	v_pk_fma_f32 v[50:51], v[48:49], v[50:51], s[40:41] op_sel_hi:[1,1,0]
	s_nop 0
	v_pk_fma_f32 v[50:51], v[48:49], v[50:51], s[42:43] op_sel_hi:[1,1,0]
	s_nop 0
	v_pk_fma_f32 v[50:51], v[48:49], v[50:51], s[44:45] op_sel_hi:[1,1,0]
	s_nop 0
	v_pk_fma_f32 v[50:51], v[48:49], v[50:51], s[46:47] op_sel_hi:[1,1,0]
	s_nop 0
	v_pk_fma_f32 v[48:49], v[48:49], v[50:51], s[48:49] op_sel_hi:[1,1,0]
	s_nop 0
	v_pk_mul_f32 v[46:47], v[46:47], v[48:49]
	v_lshlrev_b32_e32 v48, 16, v104
	v_pk_fma_f32 v[44:45], v[44:45], v[46:47], v[44:45]
	v_and_b32_e32 v49, 0xffff0000, v104
	v_pk_mul_f32 v[42:43], v[42:43], v[44:45]
	v_mov_b32_dpp v45, v108 row_ror:2 row_mask:0xf bank_mask:0xf bound_ctrl:1
	v_mov_b32_dpp v47, v109 row_ror:2 row_mask:0xf bank_mask:0xf bound_ctrl:1
	v_cvt_pk_bf16_f32 v53, v42, v43
	v_mov_b32_dpp v43, v109 row_ror:1 row_mask:0xf bank_mask:0xf bound_ctrl:1
	v_mov_b32_dpp v45, v104 row_shr:2 row_mask:0xf bank_mask:0xf
	v_lshlrev_b32_e32 v44, 16, v45
	v_and_b32_e32 v45, 0xffff0000, v45
	v_pk_fma_f32 v[44:45], v[64:65], v[44:45], v[80:81]
	v_mov_b32_dpp v47, v105 row_shr:2 row_mask:0xf bank_mask:0xf
	v_pk_fma_f32 v[40:41], v[72:73], v[40:41], v[44:45]
	v_mov_b32_dpp v43, v105 row_shr:1 row_mask:0xf bank_mask:0xf
	v_pk_fma_f32 v[40:41], v[76:77], v[48:49], v[40:41]
	v_lshlrev_b32_e32 v46, 16, v47
	v_pk_mul_f32 v[44:45], v[40:41], s[30:31] op_sel_hi:[1,0]
	v_and_b32_e32 v47, 0xffff0000, v47
	v_med3_f32 v44, v44, s47, v225
; __device__ __forceinline__ unsigned cvt_pk_bf16(float lo, float hi) { unsigned r; asm volatile("v_cvt_pk_bf16_f32 %0, %1, %2" : "=v"(r) : "v"(lo), "v"(hi)); return r; }
;     static __device__ __forceinline__ u32x2 finish2(const float (&g0)[4], const float (&g1)[4], const float (&g2)[4], const float (&w0)[4], const float (&w1)[4], const float (&w2)[4], const float (&bb)[4],
;                                                     const f32x4 v, float rs) {
;         float h[4];
; #pragma unroll
;         for (int j = 0; j < 4; j += 2) {
;             const f32x2 gc = (f32x2){bb[j] + w0[j] * g2[j] + w1[j] * g1[j] + w2[j] * g0[j], bb[j + 1] + w0[j + 1] * g2[j + 1] + w1[j + 1] * g1[j + 1] + w2[j + 1] * g0[j + 1]};
;             const f32x2 ge = gelu_pk(gc) * ((f32x2){v[j], v[j + 1]} * rs); h[j] = ge.x; h[j + 1] = ge.y; }
;         u32x2 w; w.x = cvt_pk_bf16(h[0], h[1]); w.y = cvt_pk_bf16(h[2], h[3]); return w;
;     }
;     __device__ __forceinline__ void operator()(const f32x4 (&acc)[2][2][4][2], const Unit& u, int wr, int wc, int fr, int fq) const {
;     ...
;             for (int ai = 0; ai < 2; ++ai) { const int R0 = u.rb + ai * HALF + wr * 64; const bf16_t* gp = G + (size_t)(R0 + fr) * 2816 + col8;
;                 u32x4 gq[4], prv = (u32x4){0u, 0u, 0u, 0u};
; #pragma unroll
;                 for (int m = 0; m < 4; ++m) gq[m] = *(const u32x4*)(gp + (size_t)m * 16 * 2816);
;                 if ((R0 & 8191) != 0) prv = *(const u32x4*)(gp - (size_t)16 * 2816);
;                 u32x4 pv = prv;
; #pragma unroll
;                 for (int m = 0; m < 4; ++m) { const u32x4 cur = gq[m]; u32x4 hw;
; #pragma unroll
;                     for (int hv = 0; hv < 2; ++hv) { const u32x2 c2 = half2(cur, hv), p2 = half2(pv, hv);
;                         const u32x2 q1 = dpp_prev<1>(p2, c2), q2 = dpp_prev<2>(p2, c2);
;                         float g0[4], g1[4], g2[4]; unpk4(c2, g0); unpk4(q1, g1); unpk4(q2, g2);
;                         const u32x2 r = finish2(g0, g1, g2, w0[hv], w1[hv], w2[hv], bb[hv], acc[ai][bj][m][hv], rs8[ai][m]);
;                         if (hv == 0) { hw.x = r.x; hw.y = r.y; } else { hw.z = r.x; hw.w = r.y; } }
;                     *(u32x4*)(H + (size_t)(R0 + fr + 16 * m) * 2816 + col8) = hw;
;                     pv = cur; } }
	v_med3_f32 v45, v45, s47, v225
	v_pk_mul_f32 v[48:49], v[44:45], v[44:45]
	v_pk_mul_f32 v[40:41], v[40:41], 0.5 op_sel_hi:[1,0]
	v_pk_fma_f32 v[50:51], v[48:49], s[34:35], v[118:119] op_sel_hi:[1,0,0] neg_lo:[1,0,0] neg_hi:[1,0,0]
	v_lshlrev_b32_e32 v42, 16, v43
	v_pk_fma_f32 v[50:51], v[48:49], v[50:51], s[38:39] op_sel_hi:[1,1,0]
	v_and_b32_e32 v43, 0xffff0000, v43
	v_pk_fma_f32 v[50:51], v[48:49], v[50:51], s[40:41] op_sel_hi:[1,1,0]
	s_nop 0
	v_pk_fma_f32 v[50:51], v[48:49], v[50:51], s[42:43] op_sel_hi:[1,1,0]
	s_nop 0
	v_pk_fma_f32 v[50:51], v[48:49], v[50:51], s[44:45] op_sel_hi:[1,1,0]
	s_nop 0
	v_pk_fma_f32 v[50:51], v[48:49], v[50:51], s[46:47] op_sel_hi:[1,1,0]
	s_nop 0
	v_pk_fma_f32 v[48:49], v[48:49], v[50:51], s[48:49] op_sel_hi:[1,1,0]
	s_nop 0
	v_pk_mul_f32 v[44:45], v[44:45], v[48:49]
	s_nop 0
	v_pk_fma_f32 v[40:41], v[40:41], v[44:45], v[40:41]
	v_pk_fma_f32 v[44:45], v[66:67], v[46:47], v[82:83]
	v_pk_mul_f32 v[36:37], v[36:37], v[40:41]
	v_lshlrev_b32_e32 v40, 16, v105
	v_and_b32_e32 v41, 0xffff0000, v105
	v_pk_fma_f32 v[42:43], v[74:75], v[42:43], v[44:45]
	v_cvt_pk_bf16_f32 v54, v36, v37
	s_nop 0
	v_pk_fma_f32 v[40:41], v[78:79], v[40:41], v[42:43]
	s_nop 0
	v_pk_mul_f32 v[42:43], v[40:41], s[30:31] op_sel_hi:[1,0]
	v_pk_mul_f32 v[40:41], v[40:41], 0.5 op_sel_hi:[1,0]
	v_med3_f32 v42, v42, s47, v225
	v_med3_f32 v43, v43, s47, v225
	v_pk_mul_f32 v[44:45], v[42:43], v[42:43]
	s_nop 0
	v_pk_fma_f32 v[46:47], v[44:45], s[34:35], v[118:119] op_sel_hi:[1,0,0] neg_lo:[1,0,0] neg_hi:[1,0,0]
	s_nop 0
	v_pk_fma_f32 v[46:47], v[44:45], v[46:47], s[38:39] op_sel_hi:[1,1,0]
	s_nop 0
	v_pk_fma_f32 v[46:47], v[44:45], v[46:47], s[40:41] op_sel_hi:[1,1,0]
	s_nop 0
	v_pk_fma_f32 v[46:47], v[44:45], v[46:47], s[42:43] op_sel_hi:[1,1,0]
	s_nop 0
	v_pk_fma_f32 v[46:47], v[44:45], v[46:47], s[44:45] op_sel_hi:[1,1,0]
	s_nop 0
	v_pk_fma_f32 v[46:47], v[44:45], v[46:47], s[46:47] op_sel_hi:[1,1,0]
	s_nop 0
	v_pk_fma_f32 v[44:45], v[44:45], v[46:47], s[48:49] op_sel_hi:[1,1,0]
	s_nop 0
	v_pk_mul_f32 v[42:43], v[42:43], v[44:45]
	s_nop 0
	v_pk_fma_f32 v[40:41], v[40:41], v[42:43], v[40:41]
	s_nop 0
	v_pk_mul_f32 v[2:3], v[2:3], v[40:41]
	s_nop 0
	v_cvt_pk_bf16_f32 v55, v2, v3
	v_lshl_add_u64 v[2:3], v[164:165], 0, v[60:61]
	v_add_co_u32_e32 v36, vcc, s10, v2
	s_nop 1
	v_addc_co_u32_e32 v37, vcc, 0, v3, vcc
	global_load_dwordx4 v[48:51], v[2:3], off
	global_load_dwordx4 v[44:47], v[36:37], off
	v_add_co_u32_e32 v36, vcc, 0x2c000, v2
	s_nop 1
	v_addc_co_u32_e32 v37, vcc, 0, v3, vcc
	v_add_co_u32_e32 v38, vcc, 0x42000, v2
	s_nop 1
	v_addc_co_u32_e32 v39, vcc, 0, v3, vcc
	global_load_dwordx4 v[40:43], v[36:37], off
	s_nop 0
	global_load_dwordx4 v[36:39], v[38:39], off
	s_andn2_b64 vcc, exec, s[2:3]
	global_store_dwordx4 v[56:57], v[52:55], off nt
	s_cbranch_vccnz .LBB0_1020
	v_add_co_u32_e32 v2, vcc, 0xfffea000, v2
	s_nop 1
	v_addc_co_u32_e32 v3, vcc, -1, v3, vcc
	global_load_dwordx4 v[100:103], v[2:3], off
.LBB0_1020:
	s_waitcnt vmcnt(0)
	s_nop 0
	v_mov_b32_dpp v55, v100 row_ror:2 row_mask:0xf bank_mask:0xf bound_ctrl:1
	v_mov_b32_dpp v1, v100 row_ror:1 row_mask:0xf bank_mask:0xf bound_ctrl:1
	v_lshlrev_b32_e32 v58, 16, v48
	v_mov_b32_dpp v55, v48 row_shr:2 row_mask:0xf bank_mask:0xf
	v_mov_b32_dpp v1, v48 row_shr:1 row_mask:0xf bank_mask:0xf
	v_lshlrev_b32_e32 v54, 16, v55
	v_and_b32_e32 v55, 0xffff0000, v55
	v_lshlrev_b32_e32 v2, 16, v1
	v_and_b32_e32 v3, 0xffff0000, v1
	v_pk_fma_f32 v[54:55], v[84:85], v[54:55], v[96:97]
	v_and_b32_e32 v59, 0xffff0000, v48
	v_pk_fma_f32 v[2:3], v[88:89], v[2:3], v[54:55]
	v_mov_b32_dpp v57, v101 row_ror:2 row_mask:0xf bank_mask:0xf bound_ctrl:1
	v_pk_fma_f32 v[54:55], v[92:93], v[58:59], v[2:3]
	v_mov_b32_dpp v53, v101 row_ror:1 row_mask:0xf bank_mask:0xf bound_ctrl:1
	v_pk_mul_f32 v[2:3], v[54:55], s[30:31] op_sel_hi:[1,0]
	v_mov_b32_dpp v57, v49 row_shr:2 row_mask:0xf bank_mask:0xf
	v_med3_f32 v58, v2, s47, v225
	v_med3_f32 v59, v3, s47, v225
	v_pk_mul_f32 v[62:63], v[58:59], v[58:59]
	v_mov_b64_e32 v[2:3], s[36:37]
	v_pk_fma_f32 v[68:69], v[62:63], s[34:35], v[2:3] op_sel_hi:[1,0,0] neg_lo:[1,0,0] neg_hi:[1,0,0]
	v_mov_b32_e32 v129, v128
	v_pk_fma_f32 v[68:69], v[62:63], v[68:69], s[38:39] op_sel_hi:[1,1,0]
	v_mov_b32_dpp v53, v49 row_shr:1 row_mask:0xf bank_mask:0xf
	v_pk_fma_f32 v[68:69], v[62:63], v[68:69], s[40:41] op_sel_hi:[1,1,0]
	v_lshlrev_b32_e32 v56, 16, v57
	v_pk_fma_f32 v[68:69], v[62:63], v[68:69], s[42:43] op_sel_hi:[1,1,0]
	v_and_b32_e32 v57, 0xffff0000, v57
	v_pk_fma_f32 v[68:69], v[62:63], v[68:69], s[44:45] op_sel_hi:[1,1,0]
	v_pk_mul_f32 v[54:55], v[54:55], 0.5 op_sel_hi:[1,0]
	v_pk_fma_f32 v[68:69], v[62:63], v[68:69], s[46:47] op_sel_hi:[1,1,0]
	v_lshlrev_b32_e32 v52, 16, v53
	v_pk_fma_f32 v[62:63], v[62:63], v[68:69], s[48:49] op_sel_hi:[1,1,0]
	v_and_b32_e32 v53, 0xffff0000, v53
	v_pk_mul_f32 v[58:59], v[58:59], v[62:63]
	v_pk_mul_f32 v[32:33], v[32:33], v[128:129]
	v_pk_fma_f32 v[54:55], v[54:55], v[58:59], v[54:55]
	v_pk_fma_f32 v[56:57], v[86:87], v[56:57], v[98:99]
	v_pk_mul_f32 v[32:33], v[32:33], v[54:55]
	v_lshlrev_b32_e32 v54, 16, v49
	v_and_b32_e32 v55, 0xffff0000, v49
	v_pk_fma_f32 v[52:53], v[90:91], v[52:53], v[56:57]
	v_pk_mul_f32 v[34:35], v[34:35], v[128:129]
	v_pk_fma_f32 v[52:53], v[94:95], v[54:55], v[52:53]
	v_mov_b32_dpp v1, v102 row_ror:1 row_mask:0xf bank_mask:0xf bound_ctrl:1
	v_pk_mul_f32 v[54:55], v[52:53], s[30:31] op_sel_hi:[1,0]
	v_pk_mul_f32 v[52:53], v[52:53], 0.5 op_sel_hi:[1,0]
	v_med3_f32 v54, v54, s47, v225
	v_med3_f32 v55, v55, s47, v225
	v_pk_mul_f32 v[56:57], v[54:55], v[54:55]
	v_mov_b32_dpp v1, v50 row_shr:1 row_mask:0xf bank_mask:0xf
; __device__ __forceinline__ unsigned cvt_pk_bf16(float lo, float hi) { unsigned r; asm volatile("v_cvt_pk_bf16_f32 %0, %1, %2" : "=v"(r) : "v"(lo), "v"(hi)); return r; }
;     static __device__ __forceinline__ void unpk4(const u32x2 w, float (&o)[4]) { o[0] = bf_lo(w.x); o[1] = bf_hi(w.x); o[2] = bf_lo(w.y); o[3] = bf_hi(w.y); }
;     template <int N> static __device__ __forceinline__ u32x2 dpp_prev(const u32x2 pv, const u32x2 cur) { u32x2 r; r.x = dpp_prev1<N>(pv.x, cur.x); r.y = dpp_prev1<N>(pv.y, cur.y); return r; }
;     static __device__ __forceinline__ u32x2 finish2(const float (&g0)[4], const float (&g1)[4], const float (&g2)[4], const float (&w0)[4], const float (&w1)[4], const float (&w2)[4], const float (&bb)[4],
;                                                     const f32x4 v, float rs) {
;         float h[4];
; #pragma unroll
;         for (int j = 0; j < 4; j += 2) {
;             const f32x2 gc = (f32x2){bb[j] + w0[j] * g2[j] + w1[j] * g1[j] + w2[j] * g0[j], bb[j + 1] + w0[j + 1] * g2[j + 1] + w1[j + 1] * g1[j + 1] + w2[j + 1] * g0[j + 1]};
;             const f32x2 ge = gelu_pk(gc) * ((f32x2){v[j], v[j + 1]} * rs); h[j] = ge.x; h[j + 1] = ge.y; }
;         u32x2 w; w.x = cvt_pk_bf16(h[0], h[1]); w.y = cvt_pk_bf16(h[2], h[3]); return w;
;     }
;     __device__ __forceinline__ void operator()(const f32x4 (&acc)[2][2][4][2], const Unit& u, int wr, int wc, int fr, int fq) const {
;     ...
;                 for (int m = 0; m < 4; ++m) { const u32x4 cur = gq[m]; u32x4 hw;
; #pragma unroll
;                     for (int hv = 0; hv < 2; ++hv) { const u32x2 c2 = half2(cur, hv), p2 = half2(pv, hv);
;                         const u32x2 q1 = dpp_prev<1>(p2, c2), q2 = dpp_prev<2>(p2, c2);
;                         float g0[4], g1[4], g2[4]; unpk4(c2, g0); unpk4(q1, g1); unpk4(q2, g2);
;                         const u32x2 r = finish2(g0, g1, g2, w0[hv], w1[hv], w2[hv], bb[hv], acc[ai][bj][m][hv], rs8[ai][m]);
;                         if (hv == 0) { hw.x = r.x; hw.y = r.y; } else { hw.z = r.x; hw.w = r.y; } }
;                     *(u32x4*)(H + (size_t)(R0 + fr + 16 * m) * 2816 + col8) = hw;
;                     pv = cur; } }
	v_pk_fma_f32 v[58:59], v[56:57], s[34:35], v[2:3] op_sel_hi:[1,0,0] neg_lo:[1,0,0] neg_hi:[1,0,0]
	v_cvt_pk_bf16_f32 v32, v32, v33
	v_pk_mul_f32 v[28:29], v[28:29], v[128:129]
	v_pk_fma_f32 v[58:59], v[56:57], v[58:59], s[38:39] op_sel_hi:[1,1,0]
	v_pk_mul_f32 v[30:31], v[30:31], v[128:129]
	v_pk_fma_f32 v[58:59], v[56:57], v[58:59], s[40:41] op_sel_hi:[1,1,0]
	v_mov_b32_e32 v127, v126
	v_pk_fma_f32 v[58:59], v[56:57], v[58:59], s[42:43] op_sel_hi:[1,1,0]
	v_pk_mul_f32 v[24:25], v[24:25], v[126:127]
	v_pk_fma_f32 v[58:59], v[56:57], v[58:59], s[44:45] op_sel_hi:[1,1,0]
	v_pk_mul_f32 v[26:27], v[26:27], v[126:127]
	v_pk_fma_f32 v[58:59], v[56:57], v[58:59], s[46:47] op_sel_hi:[1,1,0]
	v_pk_mul_f32 v[20:21], v[20:21], v[126:127]
	v_pk_fma_f32 v[56:57], v[56:57], v[58:59], s[48:49] op_sel_hi:[1,1,0]
	v_lshlrev_b32_e32 v58, 16, v50
	v_pk_mul_f32 v[54:55], v[54:55], v[56:57]
	v_and_b32_e32 v59, 0xffff0000, v50
	v_pk_fma_f32 v[52:53], v[52:53], v[54:55], v[52:53]
	v_mov_b32_dpp v55, v102 row_ror:2 row_mask:0xf bank_mask:0xf bound_ctrl:1
	v_pk_mul_f32 v[34:35], v[34:35], v[52:53]
	v_mov_b32_dpp v57, v103 row_ror:2 row_mask:0xf bank_mask:0xf bound_ctrl:1
	v_mov_b32_dpp v55, v50 row_shr:2 row_mask:0xf bank_mask:0xf
	v_lshlrev_b32_e32 v54, 16, v55
	v_and_b32_e32 v55, 0xffff0000, v55
	v_cvt_pk_bf16_f32 v33, v34, v35
	v_lshlrev_b32_e32 v34, 16, v1
	v_and_b32_e32 v35, 0xffff0000, v1
	v_pk_fma_f32 v[54:55], v[64:65], v[54:55], v[80:81]
	v_mov_b32_dpp v53, v103 row_ror:1 row_mask:0xf bank_mask:0xf bound_ctrl:1
	v_pk_fma_f32 v[34:35], v[72:73], v[34:35], v[54:55]
	v_mov_b32_dpp v57, v51 row_shr:2 row_mask:0xf bank_mask:0xf
	v_pk_fma_f32 v[34:35], v[76:77], v[58:59], v[34:35]
	v_mov_b32_dpp v53, v51 row_shr:1 row_mask:0xf bank_mask:0xf
	v_pk_mul_f32 v[54:55], v[34:35], s[30:31] op_sel_hi:[1,0]
	v_lshlrev_b32_e32 v56, 16, v57
	v_med3_f32 v54, v54, s47, v225
	v_med3_f32 v55, v55, s47, v225
	v_pk_mul_f32 v[58:59], v[54:55], v[54:55]
	v_and_b32_e32 v57, 0xffff0000, v57
	v_pk_fma_f32 v[62:63], v[58:59], s[34:35], v[2:3] op_sel_hi:[1,0,0] neg_lo:[1,0,0] neg_hi:[1,0,0]
	v_pk_mul_f32 v[34:35], v[34:35], 0.5 op_sel_hi:[1,0]
	v_pk_fma_f32 v[62:63], v[58:59], v[62:63], s[38:39] op_sel_hi:[1,1,0]
	v_lshlrev_b32_e32 v52, 16, v53
	v_pk_fma_f32 v[62:63], v[58:59], v[62:63], s[40:41] op_sel_hi:[1,1,0]
	v_and_b32_e32 v53, 0xffff0000, v53
	v_pk_fma_f32 v[62:63], v[58:59], v[62:63], s[42:43] op_sel_hi:[1,1,0]
	v_mov_b32_dpp v1, v48 row_ror:1 row_mask:0xf bank_mask:0xf bound_ctrl:1
	v_pk_fma_f32 v[62:63], v[58:59], v[62:63], s[44:45] op_sel_hi:[1,1,0]
	v_pk_mul_f32 v[22:23], v[22:23], v[126:127]
	v_pk_fma_f32 v[62:63], v[58:59], v[62:63], s[46:47] op_sel_hi:[1,1,0]
	v_mov_b32_dpp v1, v44 row_shr:1 row_mask:0xf bank_mask:0xf
	v_pk_fma_f32 v[58:59], v[58:59], v[62:63], s[48:49] op_sel_hi:[1,1,0]
	v_mov_b32_e32 v125, v124
	v_pk_mul_f32 v[54:55], v[54:55], v[58:59]
	v_pk_mul_f32 v[16:17], v[16:17], v[124:125]
	v_pk_fma_f32 v[34:35], v[34:35], v[54:55], v[34:35]
	v_pk_fma_f32 v[54:55], v[66:67], v[56:57], v[82:83]
	v_pk_mul_f32 v[28:29], v[28:29], v[34:35]
	v_lshlrev_b32_e32 v34, 16, v51
	v_and_b32_e32 v35, 0xffff0000, v51
	v_pk_fma_f32 v[52:53], v[74:75], v[52:53], v[54:55]
	v_pk_mul_f32 v[18:19], v[18:19], v[124:125]
	v_pk_fma_f32 v[34:35], v[78:79], v[34:35], v[52:53]
	v_pk_mul_f32 v[12:13], v[12:13], v[124:125]
	v_pk_mul_f32 v[52:53], v[34:35], s[30:31] op_sel_hi:[1,0]
	v_pk_mul_f32 v[34:35], v[34:35], 0.5 op_sel_hi:[1,0]
	v_med3_f32 v52, v52, s47, v225
	v_med3_f32 v53, v53, s47, v225
	v_pk_mul_f32 v[54:55], v[52:53], v[52:53]
	v_pk_mul_f32 v[14:15], v[14:15], v[124:125]
	v_pk_fma_f32 v[56:57], v[54:55], s[34:35], v[2:3] op_sel_hi:[1,0,0] neg_lo:[1,0,0] neg_hi:[1,0,0]
	v_mov_b32_e32 v123, v122
	v_pk_fma_f32 v[56:57], v[54:55], v[56:57], s[38:39] op_sel_hi:[1,1,0]
	v_pk_mul_f32 v[8:9], v[8:9], v[122:123]
	v_pk_fma_f32 v[56:57], v[54:55], v[56:57], s[40:41] op_sel_hi:[1,1,0]
	v_pk_mul_f32 v[10:11], v[10:11], v[122:123]
	v_pk_fma_f32 v[56:57], v[54:55], v[56:57], s[42:43] op_sel_hi:[1,1,0]
	v_pk_mul_f32 v[4:5], v[4:5], v[122:123]
	v_pk_fma_f32 v[56:57], v[54:55], v[56:57], s[44:45] op_sel_hi:[1,1,0]
	v_pk_mul_f32 v[6:7], v[6:7], v[122:123]
	v_pk_fma_f32 v[56:57], v[54:55], v[56:57], s[46:47] op_sel_hi:[1,1,0]
	s_nop 0
	v_pk_fma_f32 v[54:55], v[54:55], v[56:57], s[48:49] op_sel_hi:[1,1,0]
	s_nop 0
	v_pk_mul_f32 v[52:53], v[52:53], v[54:55]
	s_nop 0
	v_pk_fma_f32 v[34:35], v[34:35], v[52:53], v[34:35]
	s_nop 0
	v_pk_mul_f32 v[30:31], v[30:31], v[34:35]
	v_cvt_pk_bf16_f32 v34, v28, v29
	v_lshl_add_u64 v[28:29], v[168:169], 0, v[60:61]
	v_cvt_pk_bf16_f32 v35, v30, v31
	global_store_dwordx4 v[28:29], v[32:35], off nt
	v_lshlrev_b32_e32 v28, 16, v1
	v_and_b32_e32 v29, 0xffff0000, v1
	v_mov_b32_dpp v33, v48 row_ror:2 row_mask:0xf bank_mask:0xf bound_ctrl:1
	v_mov_b32_dpp v31, v49 row_ror:1 row_mask:0xf bank_mask:0xf bound_ctrl:1
	v_mov_b32_dpp v35, v49 row_ror:2 row_mask:0xf bank_mask:0xf bound_ctrl:1
	v_mov_b32_dpp v33, v44 row_shr:2 row_mask:0xf bank_mask:0xf
	v_lshlrev_b32_e32 v32, 16, v33
	v_and_b32_e32 v33, 0xffff0000, v33
	v_pk_fma_f32 v[32:33], v[84:85], v[32:33], v[96:97]
	v_lshlrev_b32_e32 v48, 16, v44
	v_and_b32_e32 v49, 0xffff0000, v44
	v_pk_fma_f32 v[28:29], v[88:89], v[28:29], v[32:33]
	v_mov_b32_dpp v35, v45 row_shr:2 row_mask:0xf bank_mask:0xf
	v_pk_fma_f32 v[28:29], v[92:93], v[48:49], v[28:29]
	v_mov_b32_dpp v31, v45 row_shr:1 row_mask:0xf bank_mask:0xf
	v_pk_mul_f32 v[32:33], v[28:29], s[30:31] op_sel_hi:[1,0]
	v_lshlrev_b32_e32 v34, 16, v35
	v_med3_f32 v32, v32, s47, v225
	v_med3_f32 v33, v33, s47, v225
	v_pk_mul_f32 v[48:49], v[32:33], v[32:33]
; __device__ __forceinline__ unsigned cvt_pk_bf16(float lo, float hi) { unsigned r; asm volatile("v_cvt_pk_bf16_f32 %0, %1, %2" : "=v"(r) : "v"(lo), "v"(hi)); return r; }
;     static __device__ __forceinline__ void unpk4(const u32x2 w, float (&o)[4]) { o[0] = bf_lo(w.x); o[1] = bf_hi(w.x); o[2] = bf_lo(w.y); o[3] = bf_hi(w.y); }
;     template <int N> static __device__ __forceinline__ u32x2 dpp_prev(const u32x2 pv, const u32x2 cur) { u32x2 r; r.x = dpp_prev1<N>(pv.x, cur.x); r.y = dpp_prev1<N>(pv.y, cur.y); return r; }
;     static __device__ __forceinline__ u32x2 finish2(const float (&g0)[4], const float (&g1)[4], const float (&g2)[4], const float (&w0)[4], const float (&w1)[4], const float (&w2)[4], const float (&bb)[4],
;                                                     const f32x4 v, float rs) {
;         float h[4];
; #pragma unroll
;         for (int j = 0; j < 4; j += 2) {
;             const f32x2 gc = (f32x2){bb[j] + w0[j] * g2[j] + w1[j] * g1[j] + w2[j] * g0[j], bb[j + 1] + w0[j + 1] * g2[j + 1] + w1[j + 1] * g1[j + 1] + w2[j + 1] * g0[j + 1]};
;             const f32x2 ge = gelu_pk(gc) * ((f32x2){v[j], v[j + 1]} * rs); h[j] = ge.x; h[j + 1] = ge.y; }
;         u32x2 w; w.x = cvt_pk_bf16(h[0], h[1]); w.y = cvt_pk_bf16(h[2], h[3]); return w;
;     }
;     __device__ __forceinline__ void operator()(const f32x4 (&acc)[2][2][4][2], const Unit& u, int wr, int wc, int fr, int fq) const {
;     ...
;                 for (int m = 0; m < 4; ++m) { const u32x4 cur = gq[m]; u32x4 hw;
; #pragma unroll
;                     for (int hv = 0; hv < 2; ++hv) { const u32x2 c2 = half2(cur, hv), p2 = half2(pv, hv);
;                         const u32x2 q1 = dpp_prev<1>(p2, c2), q2 = dpp_prev<2>(p2, c2);
;                         float g0[4], g1[4], g2[4]; unpk4(c2, g0); unpk4(q1, g1); unpk4(q2, g2);
;                         const u32x2 r = finish2(g0, g1, g2, w0[hv], w1[hv], w2[hv], bb[hv], acc[ai][bj][m][hv], rs8[ai][m]);
;                         if (hv == 0) { hw.x = r.x; hw.y = r.y; } else { hw.z = r.x; hw.w = r.y; } }
;                     *(u32x4*)(H + (size_t)(R0 + fr + 16 * m) * 2816 + col8) = hw;
;                     pv = cur; } }
	v_and_b32_e32 v35, 0xffff0000, v35
	v_pk_fma_f32 v[52:53], v[48:49], s[34:35], v[2:3] op_sel_hi:[1,0,0] neg_lo:[1,0,0] neg_hi:[1,0,0]
	v_pk_mul_f32 v[28:29], v[28:29], 0.5 op_sel_hi:[1,0]
	v_pk_fma_f32 v[52:53], v[48:49], v[52:53], s[38:39] op_sel_hi:[1,1,0]
	v_lshlrev_b32_e32 v30, 16, v31
	v_pk_fma_f32 v[52:53], v[48:49], v[52:53], s[40:41] op_sel_hi:[1,1,0]
	v_and_b32_e32 v31, 0xffff0000, v31
	v_pk_fma_f32 v[52:53], v[48:49], v[52:53], s[42:43] op_sel_hi:[1,1,0]
	v_mov_b32_dpp v1, v50 row_ror:1 row_mask:0xf bank_mask:0xf bound_ctrl:1
	v_pk_fma_f32 v[52:53], v[48:49], v[52:53], s[44:45] op_sel_hi:[1,1,0]
	s_nop 0
	v_pk_fma_f32 v[52:53], v[48:49], v[52:53], s[46:47] op_sel_hi:[1,1,0]
	v_mov_b32_dpp v1, v46 row_shr:1 row_mask:0xf bank_mask:0xf
	v_pk_fma_f32 v[48:49], v[48:49], v[52:53], s[48:49] op_sel_hi:[1,1,0]
	s_nop 0
	v_pk_mul_f32 v[32:33], v[32:33], v[48:49]
	s_nop 0
	v_pk_fma_f32 v[28:29], v[28:29], v[32:33], v[28:29]
	v_pk_fma_f32 v[32:33], v[86:87], v[34:35], v[98:99]
	v_pk_mul_f32 v[24:25], v[24:25], v[28:29]
	v_lshlrev_b32_e32 v28, 16, v45
	v_and_b32_e32 v29, 0xffff0000, v45
	v_pk_fma_f32 v[30:31], v[90:91], v[30:31], v[32:33]
	v_cvt_pk_bf16_f32 v24, v24, v25
	s_nop 0
	v_pk_fma_f32 v[28:29], v[94:95], v[28:29], v[30:31]
	s_nop 0
	v_pk_mul_f32 v[30:31], v[28:29], s[30:31] op_sel_hi:[1,0]
	v_pk_mul_f32 v[28:29], v[28:29], 0.5 op_sel_hi:[1,0]
	v_med3_f32 v30, v30, s47, v225
	v_med3_f32 v31, v31, s47, v225
	v_pk_mul_f32 v[32:33], v[30:31], v[30:31]
	s_nop 0
	v_pk_fma_f32 v[34:35], v[32:33], s[34:35], v[2:3] op_sel_hi:[1,0,0] neg_lo:[1,0,0] neg_hi:[1,0,0]
	s_nop 0
	v_pk_fma_f32 v[34:35], v[32:33], v[34:35], s[38:39] op_sel_hi:[1,1,0]
	s_nop 0
	v_pk_fma_f32 v[34:35], v[32:33], v[34:35], s[40:41] op_sel_hi:[1,1,0]
	s_nop 0
	v_pk_fma_f32 v[34:35], v[32:33], v[34:35], s[42:43] op_sel_hi:[1,1,0]
	s_nop 0
	v_pk_fma_f32 v[34:35], v[32:33], v[34:35], s[44:45] op_sel_hi:[1,1,0]
	s_nop 0
	v_pk_fma_f32 v[34:35], v[32:33], v[34:35], s[46:47] op_sel_hi:[1,1,0]
	s_nop 0
	v_pk_fma_f32 v[32:33], v[32:33], v[34:35], s[48:49] op_sel_hi:[1,1,0]
	v_lshlrev_b32_e32 v34, 16, v46
	v_pk_mul_f32 v[30:31], v[30:31], v[32:33]
	v_and_b32_e32 v35, 0xffff0000, v46
	v_pk_fma_f32 v[28:29], v[28:29], v[30:31], v[28:29]
	v_mov_b32_dpp v31, v50 row_ror:2 row_mask:0xf bank_mask:0xf bound_ctrl:1
	v_pk_mul_f32 v[26:27], v[26:27], v[28:29]
	v_mov_b32_dpp v33, v51 row_ror:2 row_mask:0xf bank_mask:0xf bound_ctrl:1
	v_mov_b32_dpp v31, v46 row_shr:2 row_mask:0xf bank_mask:0xf
	v_lshlrev_b32_e32 v30, 16, v31
	v_and_b32_e32 v31, 0xffff0000, v31
	v_cvt_pk_bf16_f32 v25, v26, v27
	v_lshlrev_b32_e32 v26, 16, v1
	v_and_b32_e32 v27, 0xffff0000, v1
	v_pk_fma_f32 v[30:31], v[64:65], v[30:31], v[80:81]
	v_mov_b32_dpp v29, v51 row_ror:1 row_mask:0xf bank_mask:0xf bound_ctrl:1
	v_pk_fma_f32 v[26:27], v[72:73], v[26:27], v[30:31]
	v_mov_b32_dpp v33, v47 row_shr:2 row_mask:0xf bank_mask:0xf
	v_pk_fma_f32 v[26:27], v[76:77], v[34:35], v[26:27]
	v_mov_b32_dpp v29, v47 row_shr:1 row_mask:0xf bank_mask:0xf
	v_pk_mul_f32 v[30:31], v[26:27], s[30:31] op_sel_hi:[1,0]
	v_lshlrev_b32_e32 v32, 16, v33
	v_med3_f32 v30, v30, s47, v225
	v_med3_f32 v31, v31, s47, v225
	v_pk_mul_f32 v[34:35], v[30:31], v[30:31]
	v_and_b32_e32 v33, 0xffff0000, v33
	v_pk_fma_f32 v[48:49], v[34:35], s[34:35], v[2:3] op_sel_hi:[1,0,0] neg_lo:[1,0,0] neg_hi:[1,0,0]
	v_pk_mul_f32 v[26:27], v[26:27], 0.5 op_sel_hi:[1,0]
	v_pk_fma_f32 v[48:49], v[34:35], v[48:49], s[38:39] op_sel_hi:[1,1,0]
	v_lshlrev_b32_e32 v28, 16, v29
	v_pk_fma_f32 v[48:49], v[34:35], v[48:49], s[40:41] op_sel_hi:[1,1,0]
	v_and_b32_e32 v29, 0xffff0000, v29
	v_pk_fma_f32 v[48:49], v[34:35], v[48:49], s[42:43] op_sel_hi:[1,1,0]
	v_mov_b32_dpp v1, v44 row_ror:1 row_mask:0xf bank_mask:0xf bound_ctrl:1
	v_pk_fma_f32 v[48:49], v[34:35], v[48:49], s[44:45] op_sel_hi:[1,1,0]
	s_nop 0
	v_pk_fma_f32 v[48:49], v[34:35], v[48:49], s[46:47] op_sel_hi:[1,1,0]
	v_mov_b32_dpp v1, v40 row_shr:1 row_mask:0xf bank_mask:0xf
	v_pk_fma_f32 v[34:35], v[34:35], v[48:49], s[48:49] op_sel_hi:[1,1,0]
	s_nop 0
	v_pk_mul_f32 v[30:31], v[30:31], v[34:35]
	s_nop 0
	v_pk_fma_f32 v[26:27], v[26:27], v[30:31], v[26:27]
	v_pk_fma_f32 v[30:31], v[66:67], v[32:33], v[82:83]
	v_pk_mul_f32 v[20:21], v[20:21], v[26:27]
	v_lshlrev_b32_e32 v26, 16, v47
	v_and_b32_e32 v27, 0xffff0000, v47
	v_pk_fma_f32 v[28:29], v[74:75], v[28:29], v[30:31]
	s_nop 0
	v_pk_fma_f32 v[26:27], v[78:79], v[26:27], v[28:29]
	s_nop 0
	v_pk_mul_f32 v[28:29], v[26:27], s[30:31] op_sel_hi:[1,0]
	v_pk_mul_f32 v[26:27], v[26:27], 0.5 op_sel_hi:[1,0]
	v_med3_f32 v28, v28, s47, v225
	v_med3_f32 v29, v29, s47, v225
	v_pk_mul_f32 v[30:31], v[28:29], v[28:29]
	s_nop 0
	v_pk_fma_f32 v[32:33], v[30:31], s[34:35], v[2:3] op_sel_hi:[1,0,0] neg_lo:[1,0,0] neg_hi:[1,0,0]
	s_nop 0
	v_pk_fma_f32 v[32:33], v[30:31], v[32:33], s[38:39] op_sel_hi:[1,1,0]
	s_nop 0
	v_pk_fma_f32 v[32:33], v[30:31], v[32:33], s[40:41] op_sel_hi:[1,1,0]
	s_nop 0
	v_pk_fma_f32 v[32:33], v[30:31], v[32:33], s[42:43] op_sel_hi:[1,1,0]
	s_nop 0
	v_pk_fma_f32 v[32:33], v[30:31], v[32:33], s[44:45] op_sel_hi:[1,1,0]
	s_nop 0
	v_pk_fma_f32 v[32:33], v[30:31], v[32:33], s[46:47] op_sel_hi:[1,1,0]
	s_nop 0
	v_pk_fma_f32 v[30:31], v[30:31], v[32:33], s[48:49] op_sel_hi:[1,1,0]
	s_nop 0
	v_pk_mul_f32 v[28:29], v[28:29], v[30:31]
	s_nop 0
	v_pk_fma_f32 v[26:27], v[26:27], v[28:29], v[26:27]
	v_lshlrev_b32_e32 v28, 16, v40
	v_pk_mul_f32 v[22:23], v[22:23], v[26:27]
	v_cvt_pk_bf16_f32 v26, v20, v21
	v_lshl_add_u64 v[20:21], v[170:171], 0, v[60:61]
	v_cvt_pk_bf16_f32 v27, v22, v23
	global_store_dwordx4 v[20:21], v[24:27], off nt
	v_lshlrev_b32_e32 v20, 16, v1
; __device__ __forceinline__ unsigned cvt_pk_bf16(float lo, float hi) { unsigned r; asm volatile("v_cvt_pk_bf16_f32 %0, %1, %2" : "=v"(r) : "v"(lo), "v"(hi)); return r; }
;     static __device__ __forceinline__ void unpk4(const u32x2 w, float (&o)[4]) { o[0] = bf_lo(w.x); o[1] = bf_hi(w.x); o[2] = bf_lo(w.y); o[3] = bf_hi(w.y); }
;     template <int N> static __device__ __forceinline__ u32x2 dpp_prev(const u32x2 pv, const u32x2 cur) { u32x2 r; r.x = dpp_prev1<N>(pv.x, cur.x); r.y = dpp_prev1<N>(pv.y, cur.y); return r; }
;     static __device__ __forceinline__ u32x2 finish2(const float (&g0)[4], const float (&g1)[4], const float (&g2)[4], const float (&w0)[4], const float (&w1)[4], const float (&w2)[4], const float (&bb)[4],
;                                                     const f32x4 v, float rs) {
;         float h[4];
; #pragma unroll
;         for (int j = 0; j < 4; j += 2) {
;             const f32x2 gc = (f32x2){bb[j] + w0[j] * g2[j] + w1[j] * g1[j] + w2[j] * g0[j], bb[j + 1] + w0[j + 1] * g2[j + 1] + w1[j + 1] * g1[j + 1] + w2[j + 1] * g0[j + 1]};
;             const f32x2 ge = gelu_pk(gc) * ((f32x2){v[j], v[j + 1]} * rs); h[j] = ge.x; h[j + 1] = ge.y; }
;         u32x2 w; w.x = cvt_pk_bf16(h[0], h[1]); w.y = cvt_pk_bf16(h[2], h[3]); return w;
;     }
;     __device__ __forceinline__ void operator()(const f32x4 (&acc)[2][2][4][2], const Unit& u, int wr, int wc, int fr, int fq) const {
;     ...
;                 for (int m = 0; m < 4; ++m) { const u32x4 cur = gq[m]; u32x4 hw;
; #pragma unroll
;                     for (int hv = 0; hv < 2; ++hv) { const u32x2 c2 = half2(cur, hv), p2 = half2(pv, hv);
;                         const u32x2 q1 = dpp_prev<1>(p2, c2), q2 = dpp_prev<2>(p2, c2);
;                         float g0[4], g1[4], g2[4]; unpk4(c2, g0); unpk4(q1, g1); unpk4(q2, g2);
;                         const u32x2 r = finish2(g0, g1, g2, w0[hv], w1[hv], w2[hv], bb[hv], acc[ai][bj][m][hv], rs8[ai][m]);
;                         if (hv == 0) { hw.x = r.x; hw.y = r.y; } else { hw.z = r.x; hw.w = r.y; } }
;                     *(u32x4*)(H + (size_t)(R0 + fr + 16 * m) * 2816 + col8) = hw;
	v_and_b32_e32 v21, 0xffff0000, v1
	v_mov_b32_dpp v25, v44 row_ror:2 row_mask:0xf bank_mask:0xf bound_ctrl:1
	v_and_b32_e32 v29, 0xffff0000, v40
	v_mov_b32_dpp v27, v45 row_ror:2 row_mask:0xf bank_mask:0xf bound_ctrl:1
	v_mov_b32_dpp v25, v40 row_shr:2 row_mask:0xf bank_mask:0xf
	v_lshlrev_b32_e32 v24, 16, v25
	v_and_b32_e32 v25, 0xffff0000, v25
	v_pk_fma_f32 v[24:25], v[84:85], v[24:25], v[96:97]
	v_mov_b32_dpp v23, v45 row_ror:1 row_mask:0xf bank_mask:0xf bound_ctrl:1
	v_pk_fma_f32 v[20:21], v[88:89], v[20:21], v[24:25]
	v_mov_b32_dpp v27, v41 row_shr:2 row_mask:0xf bank_mask:0xf
	v_pk_fma_f32 v[20:21], v[92:93], v[28:29], v[20:21]
	v_mov_b32_dpp v23, v41 row_shr:1 row_mask:0xf bank_mask:0xf
	v_pk_mul_f32 v[24:25], v[20:21], s[30:31] op_sel_hi:[1,0]
	v_lshlrev_b32_e32 v26, 16, v27
	v_med3_f32 v24, v24, s47, v225
	v_med3_f32 v25, v25, s47, v225
	v_pk_mul_f32 v[28:29], v[24:25], v[24:25]
	v_and_b32_e32 v27, 0xffff0000, v27
	v_pk_fma_f32 v[30:31], v[28:29], s[34:35], v[2:3] op_sel_hi:[1,0,0] neg_lo:[1,0,0] neg_hi:[1,0,0]
	v_pk_mul_f32 v[20:21], v[20:21], 0.5 op_sel_hi:[1,0]
	v_pk_fma_f32 v[30:31], v[28:29], v[30:31], s[38:39] op_sel_hi:[1,1,0]
	v_lshlrev_b32_e32 v22, 16, v23
	v_pk_fma_f32 v[30:31], v[28:29], v[30:31], s[40:41] op_sel_hi:[1,1,0]
	v_and_b32_e32 v23, 0xffff0000, v23
	v_pk_fma_f32 v[30:31], v[28:29], v[30:31], s[42:43] op_sel_hi:[1,1,0]
	v_mov_b32_dpp v1, v46 row_ror:1 row_mask:0xf bank_mask:0xf bound_ctrl:1
	v_pk_fma_f32 v[30:31], v[28:29], v[30:31], s[44:45] op_sel_hi:[1,1,0]
	s_nop 0
	v_pk_fma_f32 v[30:31], v[28:29], v[30:31], s[46:47] op_sel_hi:[1,1,0]
	v_mov_b32_dpp v1, v42 row_shr:1 row_mask:0xf bank_mask:0xf
	v_pk_fma_f32 v[28:29], v[28:29], v[30:31], s[48:49] op_sel_hi:[1,1,0]
	s_nop 0
	v_pk_mul_f32 v[24:25], v[24:25], v[28:29]
	s_nop 0
	v_pk_fma_f32 v[20:21], v[20:21], v[24:25], v[20:21]
	v_pk_fma_f32 v[24:25], v[86:87], v[26:27], v[98:99]
	v_pk_mul_f32 v[16:17], v[16:17], v[20:21]
	v_lshlrev_b32_e32 v20, 16, v41
	v_and_b32_e32 v21, 0xffff0000, v41
	v_pk_fma_f32 v[22:23], v[90:91], v[22:23], v[24:25]
	v_cvt_pk_bf16_f32 v16, v16, v17
	s_nop 0
	v_pk_fma_f32 v[20:21], v[94:95], v[20:21], v[22:23]
	s_nop 0
	v_pk_mul_f32 v[22:23], v[20:21], s[30:31] op_sel_hi:[1,0]
	v_pk_mul_f32 v[20:21], v[20:21], 0.5 op_sel_hi:[1,0]
	v_med3_f32 v22, v22, s47, v225
	v_med3_f32 v23, v23, s47, v225
	v_pk_mul_f32 v[24:25], v[22:23], v[22:23]
	s_nop 0
	v_pk_fma_f32 v[26:27], v[24:25], s[34:35], v[2:3] op_sel_hi:[1,0,0] neg_lo:[1,0,0] neg_hi:[1,0,0]
	s_nop 0
	v_pk_fma_f32 v[26:27], v[24:25], v[26:27], s[38:39] op_sel_hi:[1,1,0]
	s_nop 0
	v_pk_fma_f32 v[26:27], v[24:25], v[26:27], s[40:41] op_sel_hi:[1,1,0]
	s_nop 0
	v_pk_fma_f32 v[26:27], v[24:25], v[26:27], s[42:43] op_sel_hi:[1,1,0]
	s_nop 0
	v_pk_fma_f32 v[26:27], v[24:25], v[26:27], s[44:45] op_sel_hi:[1,1,0]
	s_nop 0
	v_pk_fma_f32 v[26:27], v[24:25], v[26:27], s[46:47] op_sel_hi:[1,1,0]
	s_nop 0
	v_pk_fma_f32 v[24:25], v[24:25], v[26:27], s[48:49] op_sel_hi:[1,1,0]
	v_lshlrev_b32_e32 v26, 16, v42
	v_pk_mul_f32 v[22:23], v[22:23], v[24:25]
	v_and_b32_e32 v27, 0xffff0000, v42
	v_pk_fma_f32 v[20:21], v[20:21], v[22:23], v[20:21]
	v_mov_b32_dpp v23, v46 row_ror:2 row_mask:0xf bank_mask:0xf bound_ctrl:1
	v_pk_mul_f32 v[18:19], v[18:19], v[20:21]
	v_mov_b32_dpp v25, v47 row_ror:2 row_mask:0xf bank_mask:0xf bound_ctrl:1
	v_mov_b32_dpp v23, v42 row_shr:2 row_mask:0xf bank_mask:0xf
	v_lshlrev_b32_e32 v22, 16, v23
	v_and_b32_e32 v23, 0xffff0000, v23
	v_cvt_pk_bf16_f32 v17, v18, v19
	v_lshlrev_b32_e32 v18, 16, v1
	v_and_b32_e32 v19, 0xffff0000, v1
	v_pk_fma_f32 v[22:23], v[64:65], v[22:23], v[80:81]
	v_mov_b32_dpp v21, v47 row_ror:1 row_mask:0xf bank_mask:0xf bound_ctrl:1
	v_pk_fma_f32 v[18:19], v[72:73], v[18:19], v[22:23]
	v_mov_b32_dpp v25, v43 row_shr:2 row_mask:0xf bank_mask:0xf
	v_pk_fma_f32 v[18:19], v[76:77], v[26:27], v[18:19]
	v_mov_b32_dpp v21, v43 row_shr:1 row_mask:0xf bank_mask:0xf
	v_pk_mul_f32 v[22:23], v[18:19], s[30:31] op_sel_hi:[1,0]
	v_lshlrev_b32_e32 v24, 16, v25
	v_med3_f32 v22, v22, s47, v225
	v_med3_f32 v23, v23, s47, v225
	v_pk_mul_f32 v[26:27], v[22:23], v[22:23]
	v_and_b32_e32 v25, 0xffff0000, v25
	v_pk_fma_f32 v[28:29], v[26:27], s[34:35], v[2:3] op_sel_hi:[1,0,0] neg_lo:[1,0,0] neg_hi:[1,0,0]
	v_pk_mul_f32 v[18:19], v[18:19], 0.5 op_sel_hi:[1,0]
	v_pk_fma_f32 v[28:29], v[26:27], v[28:29], s[38:39] op_sel_hi:[1,1,0]
	v_lshlrev_b32_e32 v20, 16, v21
	v_pk_fma_f32 v[28:29], v[26:27], v[28:29], s[40:41] op_sel_hi:[1,1,0]
	v_and_b32_e32 v21, 0xffff0000, v21
	v_pk_fma_f32 v[28:29], v[26:27], v[28:29], s[42:43] op_sel_hi:[1,1,0]
	v_mov_b32_dpp v1, v40 row_ror:1 row_mask:0xf bank_mask:0xf bound_ctrl:1
	v_pk_fma_f32 v[28:29], v[26:27], v[28:29], s[44:45] op_sel_hi:[1,1,0]
	s_nop 0
	v_pk_fma_f32 v[28:29], v[26:27], v[28:29], s[46:47] op_sel_hi:[1,1,0]
	v_mov_b32_dpp v1, v36 row_shr:1 row_mask:0xf bank_mask:0xf
	v_pk_fma_f32 v[26:27], v[26:27], v[28:29], s[48:49] op_sel_hi:[1,1,0]
	s_nop 0
	v_pk_mul_f32 v[22:23], v[22:23], v[26:27]
	s_nop 0
	v_pk_fma_f32 v[18:19], v[18:19], v[22:23], v[18:19]
	v_pk_fma_f32 v[22:23], v[66:67], v[24:25], v[82:83]
	v_pk_mul_f32 v[12:13], v[12:13], v[18:19]
	v_lshlrev_b32_e32 v18, 16, v43
	v_and_b32_e32 v19, 0xffff0000, v43
	v_pk_fma_f32 v[20:21], v[74:75], v[20:21], v[22:23]
	s_nop 0
	v_pk_fma_f32 v[18:19], v[78:79], v[18:19], v[20:21]
	s_nop 0
	v_pk_mul_f32 v[20:21], v[18:19], s[30:31] op_sel_hi:[1,0]
	v_pk_mul_f32 v[18:19], v[18:19], 0.5 op_sel_hi:[1,0]
	v_med3_f32 v20, v20, s47, v225
	v_med3_f32 v21, v21, s47, v225
	v_pk_mul_f32 v[22:23], v[20:21], v[20:21]
	s_nop 0
	v_pk_fma_f32 v[24:25], v[22:23], s[34:35], v[2:3] op_sel_hi:[1,0,0] neg_lo:[1,0,0] neg_hi:[1,0,0]
; __device__ __forceinline__ unsigned cvt_pk_bf16(float lo, float hi) { unsigned r; asm volatile("v_cvt_pk_bf16_f32 %0, %1, %2" : "=v"(r) : "v"(lo), "v"(hi)); return r; }
;     static __device__ __forceinline__ void unpk4(const u32x2 w, float (&o)[4]) { o[0] = bf_lo(w.x); o[1] = bf_hi(w.x); o[2] = bf_lo(w.y); o[3] = bf_hi(w.y); }
;     template <int N> static __device__ __forceinline__ u32x2 dpp_prev(const u32x2 pv, const u32x2 cur) { u32x2 r; r.x = dpp_prev1<N>(pv.x, cur.x); r.y = dpp_prev1<N>(pv.y, cur.y); return r; }
;     static __device__ __forceinline__ u32x2 finish2(const float (&g0)[4], const float (&g1)[4], const float (&g2)[4], const float (&w0)[4], const float (&w1)[4], const float (&w2)[4], const float (&bb)[4],
;                                                     const f32x4 v, float rs) {
;         float h[4];
; #pragma unroll
;         for (int j = 0; j < 4; j += 2) {
;             const f32x2 gc = (f32x2){bb[j] + w0[j] * g2[j] + w1[j] * g1[j] + w2[j] * g0[j], bb[j + 1] + w0[j + 1] * g2[j + 1] + w1[j + 1] * g1[j + 1] + w2[j + 1] * g0[j + 1]};
;             const f32x2 ge = gelu_pk(gc) * ((f32x2){v[j], v[j + 1]} * rs); h[j] = ge.x; h[j + 1] = ge.y; }
;         u32x2 w; w.x = cvt_pk_bf16(h[0], h[1]); w.y = cvt_pk_bf16(h[2], h[3]); return w;
;     }
;     __device__ __forceinline__ void operator()(const f32x4 (&acc)[2][2][4][2], const Unit& u, int wr, int wc, int fr, int fq) const {
;     ...
;                 for (int m = 0; m < 4; ++m) { const u32x4 cur = gq[m]; u32x4 hw;
; #pragma unroll
;                     for (int hv = 0; hv < 2; ++hv) { const u32x2 c2 = half2(cur, hv), p2 = half2(pv, hv);
;                         const u32x2 q1 = dpp_prev<1>(p2, c2), q2 = dpp_prev<2>(p2, c2);
;                         float g0[4], g1[4], g2[4]; unpk4(c2, g0); unpk4(q1, g1); unpk4(q2, g2);
;                         const u32x2 r = finish2(g0, g1, g2, w0[hv], w1[hv], w2[hv], bb[hv], acc[ai][bj][m][hv], rs8[ai][m]);
;                         if (hv == 0) { hw.x = r.x; hw.y = r.y; } else { hw.z = r.x; hw.w = r.y; } }
;                     *(u32x4*)(H + (size_t)(R0 + fr + 16 * m) * 2816 + col8) = hw;
;                     pv = cur; } }
	s_nop 0
	v_pk_fma_f32 v[24:25], v[22:23], v[24:25], s[38:39] op_sel_hi:[1,1,0]
	s_nop 0
	v_pk_fma_f32 v[24:25], v[22:23], v[24:25], s[40:41] op_sel_hi:[1,1,0]
	s_nop 0
	v_pk_fma_f32 v[24:25], v[22:23], v[24:25], s[42:43] op_sel_hi:[1,1,0]
	s_nop 0
	v_pk_fma_f32 v[24:25], v[22:23], v[24:25], s[44:45] op_sel_hi:[1,1,0]
	s_nop 0
	v_pk_fma_f32 v[24:25], v[22:23], v[24:25], s[46:47] op_sel_hi:[1,1,0]
	s_nop 0
	v_pk_fma_f32 v[22:23], v[22:23], v[24:25], s[48:49] op_sel_hi:[1,1,0]
	s_nop 0
	v_pk_mul_f32 v[20:21], v[20:21], v[22:23]
	s_nop 0
	v_pk_fma_f32 v[18:19], v[18:19], v[20:21], v[18:19]
	v_lshlrev_b32_e32 v20, 16, v36
	v_pk_mul_f32 v[14:15], v[14:15], v[18:19]
	v_cvt_pk_bf16_f32 v18, v12, v13
	v_lshl_add_u64 v[12:13], v[174:175], 0, v[60:61]
	v_cvt_pk_bf16_f32 v19, v14, v15
	global_store_dwordx4 v[12:13], v[16:19], off nt
	v_lshlrev_b32_e32 v12, 16, v1
	v_and_b32_e32 v13, 0xffff0000, v1
	v_mov_b32_dpp v17, v40 row_ror:2 row_mask:0xf bank_mask:0xf bound_ctrl:1
	v_and_b32_e32 v21, 0xffff0000, v36
	v_mov_b32_dpp v19, v41 row_ror:2 row_mask:0xf bank_mask:0xf bound_ctrl:1
	v_mov_b32_dpp v17, v36 row_shr:2 row_mask:0xf bank_mask:0xf
	v_lshlrev_b32_e32 v16, 16, v17
	v_and_b32_e32 v17, 0xffff0000, v17
	v_pk_fma_f32 v[16:17], v[84:85], v[16:17], v[96:97]
	v_mov_b32_dpp v15, v41 row_ror:1 row_mask:0xf bank_mask:0xf bound_ctrl:1
	v_pk_fma_f32 v[12:13], v[88:89], v[12:13], v[16:17]
	v_mov_b32_dpp v19, v37 row_shr:2 row_mask:0xf bank_mask:0xf
	v_pk_fma_f32 v[12:13], v[92:93], v[20:21], v[12:13]
	v_mov_b32_dpp v15, v37 row_shr:1 row_mask:0xf bank_mask:0xf
	v_pk_mul_f32 v[16:17], v[12:13], s[30:31] op_sel_hi:[1,0]
	v_lshlrev_b32_e32 v18, 16, v19
	v_med3_f32 v16, v16, s47, v225
	v_med3_f32 v17, v17, s47, v225
	v_pk_mul_f32 v[20:21], v[16:17], v[16:17]
	v_and_b32_e32 v19, 0xffff0000, v19
	v_pk_fma_f32 v[22:23], v[20:21], s[34:35], v[2:3] op_sel_hi:[1,0,0] neg_lo:[1,0,0] neg_hi:[1,0,0]
	v_pk_mul_f32 v[12:13], v[12:13], 0.5 op_sel_hi:[1,0]
	v_pk_fma_f32 v[22:23], v[20:21], v[22:23], s[38:39] op_sel_hi:[1,1,0]
	v_lshlrev_b32_e32 v14, 16, v15
	v_pk_fma_f32 v[22:23], v[20:21], v[22:23], s[40:41] op_sel_hi:[1,1,0]
	v_and_b32_e32 v15, 0xffff0000, v15
	v_pk_fma_f32 v[22:23], v[20:21], v[22:23], s[42:43] op_sel_hi:[1,1,0]
	v_mov_b32_dpp v1, v42 row_ror:1 row_mask:0xf bank_mask:0xf bound_ctrl:1
	v_pk_fma_f32 v[22:23], v[20:21], v[22:23], s[44:45] op_sel_hi:[1,1,0]
	s_nop 0
	v_pk_fma_f32 v[22:23], v[20:21], v[22:23], s[46:47] op_sel_hi:[1,1,0]
	v_mov_b32_dpp v1, v38 row_shr:1 row_mask:0xf bank_mask:0xf
	v_pk_fma_f32 v[20:21], v[20:21], v[22:23], s[48:49] op_sel_hi:[1,1,0]
	s_nop 0
	v_pk_mul_f32 v[16:17], v[16:17], v[20:21]
	s_nop 0
	v_pk_fma_f32 v[12:13], v[12:13], v[16:17], v[12:13]
	v_pk_fma_f32 v[16:17], v[86:87], v[18:19], v[98:99]
	v_pk_mul_f32 v[8:9], v[8:9], v[12:13]
	v_lshlrev_b32_e32 v12, 16, v37
	v_and_b32_e32 v13, 0xffff0000, v37
	v_pk_fma_f32 v[14:15], v[90:91], v[14:15], v[16:17]
	v_cvt_pk_bf16_f32 v8, v8, v9
	s_nop 0
	v_pk_fma_f32 v[12:13], v[94:95], v[12:13], v[14:15]
	s_nop 0
	v_pk_mul_f32 v[14:15], v[12:13], s[30:31] op_sel_hi:[1,0]
	v_pk_mul_f32 v[12:13], v[12:13], 0.5 op_sel_hi:[1,0]
	v_med3_f32 v14, v14, s47, v225
	v_med3_f32 v15, v15, s47, v225
	v_pk_mul_f32 v[16:17], v[14:15], v[14:15]
	s_nop 0
	v_pk_fma_f32 v[18:19], v[16:17], s[34:35], v[2:3] op_sel_hi:[1,0,0] neg_lo:[1,0,0] neg_hi:[1,0,0]
	s_nop 0
	v_pk_fma_f32 v[18:19], v[16:17], v[18:19], s[38:39] op_sel_hi:[1,1,0]
	s_nop 0
	v_pk_fma_f32 v[18:19], v[16:17], v[18:19], s[40:41] op_sel_hi:[1,1,0]
	s_nop 0
	v_pk_fma_f32 v[18:19], v[16:17], v[18:19], s[42:43] op_sel_hi:[1,1,0]
; __device__ __forceinline__ unsigned cvt_pk_bf16(float lo, float hi) { unsigned r; asm volatile("v_cvt_pk_bf16_f32 %0, %1, %2" : "=v"(r) : "v"(lo), "v"(hi)); return r; }
;     static __device__ __forceinline__ void unpk4(const u32x2 w, float (&o)[4]) { o[0] = bf_lo(w.x); o[1] = bf_hi(w.x); o[2] = bf_lo(w.y); o[3] = bf_hi(w.y); }
;     template <int N> static __device__ __forceinline__ u32x2 dpp_prev(const u32x2 pv, const u32x2 cur) { u32x2 r; r.x = dpp_prev1<N>(pv.x, cur.x); r.y = dpp_prev1<N>(pv.y, cur.y); return r; }
;     static __device__ __forceinline__ u32x2 finish2(const float (&g0)[4], const float (&g1)[4], const float (&g2)[4], const float (&w0)[4], const float (&w1)[4], const float (&w2)[4], const float (&bb)[4],
;                                                     const f32x4 v, float rs) {
;         float h[4];
; #pragma unroll
;         for (int j = 0; j < 4; j += 2) {
;             const f32x2 gc = (f32x2){bb[j] + w0[j] * g2[j] + w1[j] * g1[j] + w2[j] * g0[j], bb[j + 1] + w0[j + 1] * g2[j + 1] + w1[j + 1] * g1[j + 1] + w2[j + 1] * g0[j + 1]};
;             const f32x2 ge = gelu_pk(gc) * ((f32x2){v[j], v[j + 1]} * rs); h[j] = ge.x; h[j + 1] = ge.y; }
;         u32x2 w; w.x = cvt_pk_bf16(h[0], h[1]); w.y = cvt_pk_bf16(h[2], h[3]); return w;
;     }
;     __device__ __forceinline__ void operator()(const f32x4 (&acc)[2][2][4][2], const Unit& u, int wr, int wc, int fr, int fq) const {
;     ...
;                 for (int m = 0; m < 4; ++m) { const u32x4 cur = gq[m]; u32x4 hw;
; #pragma unroll
;                     for (int hv = 0; hv < 2; ++hv) { const u32x2 c2 = half2(cur, hv), p2 = half2(pv, hv);
;                         const u32x2 q1 = dpp_prev<1>(p2, c2), q2 = dpp_prev<2>(p2, c2);
;                         float g0[4], g1[4], g2[4]; unpk4(c2, g0); unpk4(q1, g1); unpk4(q2, g2);
;                         const u32x2 r = finish2(g0, g1, g2, w0[hv], w1[hv], w2[hv], bb[hv], acc[ai][bj][m][hv], rs8[ai][m]);
;                         if (hv == 0) { hw.x = r.x; hw.y = r.y; } else { hw.z = r.x; hw.w = r.y; } }
;                     *(u32x4*)(H + (size_t)(R0 + fr + 16 * m) * 2816 + col8) = hw;
;                     pv = cur; } }
	s_nop 0
	v_pk_fma_f32 v[18:19], v[16:17], v[18:19], s[44:45] op_sel_hi:[1,1,0]
	s_nop 0
	v_pk_fma_f32 v[18:19], v[16:17], v[18:19], s[46:47] op_sel_hi:[1,1,0]
	s_nop 0
	v_pk_fma_f32 v[16:17], v[16:17], v[18:19], s[48:49] op_sel_hi:[1,1,0]
	v_lshlrev_b32_e32 v18, 16, v38
	v_pk_mul_f32 v[14:15], v[14:15], v[16:17]
	v_and_b32_e32 v19, 0xffff0000, v38
	v_pk_fma_f32 v[12:13], v[12:13], v[14:15], v[12:13]
	v_mov_b32_dpp v15, v42 row_ror:2 row_mask:0xf bank_mask:0xf bound_ctrl:1
	v_pk_mul_f32 v[10:11], v[10:11], v[12:13]
	v_mov_b32_dpp v17, v43 row_ror:2 row_mask:0xf bank_mask:0xf bound_ctrl:1
	v_mov_b32_dpp v15, v38 row_shr:2 row_mask:0xf bank_mask:0xf
	v_lshlrev_b32_e32 v14, 16, v15
	v_and_b32_e32 v15, 0xffff0000, v15
	v_cvt_pk_bf16_f32 v9, v10, v11
	v_lshlrev_b32_e32 v10, 16, v1
	v_and_b32_e32 v11, 0xffff0000, v1
	v_pk_fma_f32 v[14:15], v[64:65], v[14:15], v[80:81]
	v_mov_b32_dpp v13, v43 row_ror:1 row_mask:0xf bank_mask:0xf bound_ctrl:1
	v_pk_fma_f32 v[10:11], v[72:73], v[10:11], v[14:15]
	v_mov_b32_dpp v17, v39 row_shr:2 row_mask:0xf bank_mask:0xf
	v_pk_fma_f32 v[10:11], v[76:77], v[18:19], v[10:11]
	v_mov_b32_dpp v13, v39 row_shr:1 row_mask:0xf bank_mask:0xf
	v_pk_mul_f32 v[14:15], v[10:11], s[30:31] op_sel_hi:[1,0]
	v_lshlrev_b32_e32 v16, 16, v17
	v_med3_f32 v14, v14, s47, v225
	v_med3_f32 v15, v15, s47, v225
	v_pk_mul_f32 v[18:19], v[14:15], v[14:15]
	v_and_b32_e32 v17, 0xffff0000, v17
	v_pk_fma_f32 v[20:21], v[18:19], s[34:35], v[2:3] op_sel_hi:[1,0,0] neg_lo:[1,0,0] neg_hi:[1,0,0]
	v_pk_mul_f32 v[10:11], v[10:11], 0.5 op_sel_hi:[1,0]
	v_pk_fma_f32 v[20:21], v[18:19], v[20:21], s[38:39] op_sel_hi:[1,1,0]
	v_lshlrev_b32_e32 v12, 16, v13
	v_pk_fma_f32 v[20:21], v[18:19], v[20:21], s[40:41] op_sel_hi:[1,1,0]
	v_and_b32_e32 v13, 0xffff0000, v13
	v_pk_fma_f32 v[20:21], v[18:19], v[20:21], s[42:43] op_sel_hi:[1,1,0]
	s_nop 0
	v_pk_fma_f32 v[20:21], v[18:19], v[20:21], s[44:45] op_sel_hi:[1,1,0]
	s_nop 0
	v_pk_fma_f32 v[20:21], v[18:19], v[20:21], s[46:47] op_sel_hi:[1,1,0]
	s_nop 0
	v_pk_fma_f32 v[18:19], v[18:19], v[20:21], s[48:49] op_sel_hi:[1,1,0]
	s_nop 0
	v_pk_mul_f32 v[14:15], v[14:15], v[18:19]
	s_nop 0
	v_pk_fma_f32 v[10:11], v[10:11], v[14:15], v[10:11]
	v_pk_fma_f32 v[14:15], v[66:67], v[16:17], v[82:83]
	v_pk_mul_f32 v[4:5], v[4:5], v[10:11]
	v_lshlrev_b32_e32 v10, 16, v39
	v_and_b32_e32 v11, 0xffff0000, v39
	v_pk_fma_f32 v[12:13], v[74:75], v[12:13], v[14:15]
	s_nop 0
	v_pk_fma_f32 v[10:11], v[78:79], v[10:11], v[12:13]
	s_nop 0
	v_pk_mul_f32 v[12:13], v[10:11], s[30:31] op_sel_hi:[1,0]
	v_pk_mul_f32 v[10:11], v[10:11], 0.5 op_sel_hi:[1,0]
	v_med3_f32 v12, v12, s47, v225
	v_med3_f32 v13, v13, s47, v225
	v_pk_mul_f32 v[14:15], v[12:13], v[12:13]
	s_nop 0
	v_pk_fma_f32 v[2:3], v[14:15], s[34:35], v[2:3] op_sel_hi:[1,0,0] neg_lo:[1,0,0] neg_hi:[1,0,0]
	s_nop 0
	v_pk_fma_f32 v[2:3], v[14:15], v[2:3], s[38:39] op_sel_hi:[1,1,0]
	s_nop 0
	v_pk_fma_f32 v[2:3], v[14:15], v[2:3], s[40:41] op_sel_hi:[1,1,0]
	s_nop 0
	v_pk_fma_f32 v[2:3], v[14:15], v[2:3], s[42:43] op_sel_hi:[1,1,0]
	s_nop 0
	v_pk_fma_f32 v[2:3], v[14:15], v[2:3], s[44:45] op_sel_hi:[1,1,0]
	s_nop 0
	v_pk_fma_f32 v[2:3], v[14:15], v[2:3], s[46:47] op_sel_hi:[1,1,0]
	s_nop 0
	v_pk_fma_f32 v[2:3], v[14:15], v[2:3], s[48:49] op_sel_hi:[1,1,0]
	s_nop 0
	v_pk_mul_f32 v[2:3], v[12:13], v[2:3]
	s_nop 0
	v_pk_fma_f32 v[2:3], v[10:11], v[2:3], v[10:11]
	v_cvt_pk_bf16_f32 v10, v4, v5
	s_nop 0
	v_pk_mul_f32 v[2:3], v[6:7], v[2:3]
	s_nop 0
	v_cvt_pk_bf16_f32 v11, v2, v3
	v_lshl_add_u64 v[2:3], v[132:133], 0, v[60:61]
	global_store_dwordx4 v[2:3], v[8:11], off nt

; __device__ __forceinline__ unsigned cvt_pk_bf16(float lo, float hi) { unsigned r; asm volatile("v_cvt_pk_bf16_f32 %0, %1, %2" : "=v"(r) : "v"(lo), "v"(hi)); return r; }
;     __device__ __forceinline__ void operator()(const f32x4 (&acc)[2][2][4][2], const Unit& u, int wr, int wc, int fr, int fq) const {
;     ...
;             for (int m = 0; m < 4; ++m) { const int row = row0 + ai * HALF + m * 16; bf16_t* rowp = G + (size_t)row * 2816 + col0;
;                 float* co = nullptr;
;                 if (row < 32768) { const int t = row & 8191; if (t >= 8190) co = outP + ((size_t)(row >> 13) * 2 + (t - 8190)) * 2816 + col0; }
;                 else { const int i = row & 7; if (i >= 6) co = outS + ((size_t)((row - 32768) >> 3) * 2 + (i - 6)) * 2816 + col0; }
;                 const float rs = rsqrtf(rsv[ai][m] * (1.f / 1024.f) + 1e-6f);
; #pragma unroll
;                 for (int bj = 0; bj < 2; ++bj) { const f32x4 v0 = acc[ai][bj][m][0] * rs, v1 = acc[ai][bj][m][1] * rs;
;                     u32x4 w; w.x = cvt_pk_bf16(v0[0], v0[1]); w.y = cvt_pk_bf16(v0[2], v0[3]); w.z = cvt_pk_bf16(v1[0], v1[1]); w.w = cvt_pk_bf16(v1[2], v1[3]);
;                     *(u32x4*)(rowp + bj * HALF) = w;
;                     if (co) { *(f32x4*)(co + bj * HALF) = v0; *(f32x4*)(co + bj * HALF + 4) = v1; } } }
.LBB0_2967:
	s_or_b64 exec, exec, s[26:27]
	s_waitcnt vmcnt(0)
	v_fmamk_f32 v142, v142, 0x3a800000, v223
	v_mul_f32_e32 v143, 0x4b800000, v142
	v_cmp_gt_f32_e32 vcc, s53, v142
	v_readlane_b32 s26, v240, 12
	v_readlane_b32 s27, v240, 13
	v_cndmask_b32_e32 v142, v142, v143, vcc
	v_rsq_f32_e32 v149, v142
	v_mov_b64_e32 v[144:145], s[26:27]
	v_mad_i64_i32 v[142:143], s[26:27], v2, s52, v[144:145]
	v_mul_f32_e32 v144, 0x45800000, v149
	v_cndmask_b32_e32 v144, v149, v144, vcc
	v_lshl_add_u64 v[142:143], v[132:133], 1, v[142:143]
	v_cmp_ne_u64_e32 vcc, 0, v[140:141]
	v_pk_mul_f32 v[130:131], v[130:131], v[144:145] op_sel_hi:[1,0]
	v_pk_mul_f32 v[128:129], v[128:129], v[144:145] op_sel_hi:[1,0]
	v_pk_mul_f32 v[126:127], v[126:127], v[144:145] op_sel_hi:[1,0]
	v_pk_mul_f32 v[124:125], v[124:125], v[144:145] op_sel_hi:[1,0]
	v_cvt_pk_bf16_f32 v150, v128, v129
	v_cvt_pk_bf16_f32 v151, v130, v131
	s_nop 0
	v_cvt_pk_bf16_f32 v152, v124, v125
	v_cvt_pk_bf16_f32 v153, v126, v127
	global_store_dwordx4 v[142:143], v[150:153], off nt
	s_and_saveexec_b64 s[26:27], vcc
	s_cbranch_execz .LBB0_2969
	global_store_dwordx4 v[140:141], v[128:131], off nt
	global_store_dwordx4 v[140:141], v[124:127], off offset:16 nt
.LBB0_2969:
	s_or_b64 exec, exec, s[26:27]
	v_mov_b32_e32 v145, v144
	v_mov_b32_e32 v124, v144
	v_mov_b32_e32 v125, v144
	v_pk_mul_f32 v[122:123], v[122:123], v[124:125]
	v_pk_mul_f32 v[120:121], v[120:121], v[144:145]
	v_pk_mul_f32 v[118:119], v[118:119], v[124:125]
	v_pk_mul_f32 v[116:117], v[116:117], v[144:145]
	v_cvt_pk_bf16_f32 v124, v120, v121
	v_cvt_pk_bf16_f32 v125, v122, v123
	s_nop 0
	v_cvt_pk_bf16_f32 v126, v116, v117
	v_cvt_pk_bf16_f32 v127, v118, v119
	global_store_dwordx4 v[142:143], v[124:127], off offset:256 nt
	s_and_saveexec_b64 s[26:27], vcc
	s_cbranch_execz .LBB0_2971
	global_store_dwordx4 v[140:141], v[120:123], off offset:512 nt
	global_store_dwordx4 v[140:141], v[116:119], off offset:528 nt

; __device__ __forceinline__ unsigned cvt_pk_bf16(float lo, float hi) { unsigned r; asm volatile("v_cvt_pk_bf16_f32 %0, %1, %2" : "=v"(r) : "v"(lo), "v"(hi)); return r; }
;     __device__ __forceinline__ void operator()(const f32x4 (&acc)[2][2][4][2], const Unit& u, int wr, int wc, int fr, int fq) const {
;     ...
;             for (int m = 0; m < 4; ++m) { const int row = row0 + ai * HALF + m * 16; bf16_t* rowp = G + (size_t)row * 2816 + col0;
;                 float* co = nullptr;
;                 if (row < 32768) { const int t = row & 8191; if (t >= 8190) co = outP + ((size_t)(row >> 13) * 2 + (t - 8190)) * 2816 + col0; }
;                 else { const int i = row & 7; if (i >= 6) co = outS + ((size_t)((row - 32768) >> 3) * 2 + (i - 6)) * 2816 + col0; }
;                 const float rs = rsqrtf(rsv[ai][m] * (1.f / 1024.f) + 1e-6f);
; #pragma unroll
;                 for (int bj = 0; bj < 2; ++bj) { const f32x4 v0 = acc[ai][bj][m][0] * rs, v1 = acc[ai][bj][m][1] * rs;
;                     u32x4 w; w.x = cvt_pk_bf16(v0[0], v0[1]); w.y = cvt_pk_bf16(v0[2], v0[3]); w.z = cvt_pk_bf16(v1[0], v1[1]); w.w = cvt_pk_bf16(v1[2], v1[3]);
;                     *(u32x4*)(rowp + bj * HALF) = w;
;                     if (co) { *(f32x4*)(co + bj * HALF) = v0; *(f32x4*)(co + bj * HALF + 4) = v1; } } }
.LBB0_2979:
	s_or_b64 exec, exec, s[26:27]
	v_fmamk_f32 v120, v148, 0x3a800000, v223
	v_mul_f32_e32 v121, 0x4b800000, v120
	v_cmp_gt_f32_e32 vcc, s53, v120
	v_readlane_b32 s26, v240, 12
	v_readlane_b32 s27, v240, 13
	v_cndmask_b32_e32 v120, v120, v121, vcc
	v_rsq_f32_e32 v120, v120
	v_mov_b64_e32 v[118:119], s[26:27]
	v_mad_i64_i32 v[118:119], s[26:27], v138, s52, v[118:119]
	v_mul_f32_e32 v121, 0x45800000, v120
	v_cndmask_b32_e32 v120, v120, v121, vcc
	v_lshl_add_u64 v[118:119], v[132:133], 1, v[118:119]
	v_cmp_ne_u64_e32 vcc, 0, v[116:117]
	v_pk_mul_f32 v[114:115], v[114:115], v[120:121] op_sel_hi:[1,0]
	v_pk_mul_f32 v[112:113], v[112:113], v[120:121] op_sel_hi:[1,0]
	v_pk_mul_f32 v[110:111], v[110:111], v[120:121] op_sel_hi:[1,0]
	v_pk_mul_f32 v[108:109], v[108:109], v[120:121] op_sel_hi:[1,0]
	v_cvt_pk_bf16_f32 v122, v112, v113
	v_cvt_pk_bf16_f32 v123, v114, v115
	s_nop 0
	v_cvt_pk_bf16_f32 v124, v108, v109
	v_cvt_pk_bf16_f32 v125, v110, v111
	global_store_dwordx4 v[118:119], v[122:125], off nt
	s_and_saveexec_b64 s[26:27], vcc
	s_cbranch_execz .LBB0_2981
	global_store_dwordx4 v[116:117], v[112:115], off nt
	global_store_dwordx4 v[116:117], v[108:111], off offset:16 nt
.LBB0_2981:
	s_or_b64 exec, exec, s[26:27]
	v_mov_b32_e32 v121, v120
	v_mov_b32_e32 v108, v120
	v_mov_b32_e32 v109, v120
	v_pk_mul_f32 v[106:107], v[106:107], v[108:109]
	v_pk_mul_f32 v[104:105], v[104:105], v[120:121]
	v_pk_mul_f32 v[102:103], v[102:103], v[108:109]
	v_pk_mul_f32 v[100:101], v[100:101], v[120:121]
	v_cvt_pk_bf16_f32 v108, v104, v105
	v_cvt_pk_bf16_f32 v109, v106, v107
	s_nop 0
	v_cvt_pk_bf16_f32 v110, v100, v101
	v_cvt_pk_bf16_f32 v111, v102, v103
	global_store_dwordx4 v[118:119], v[108:111], off offset:256 nt
	s_and_saveexec_b64 s[26:27], vcc
	s_cbranch_execz .LBB0_2983
	global_store_dwordx4 v[116:117], v[104:107], off offset:512 nt
	global_store_dwordx4 v[116:117], v[100:103], off offset:528 nt

; __device__ __forceinline__ unsigned cvt_pk_bf16(float lo, float hi) { unsigned r; asm volatile("v_cvt_pk_bf16_f32 %0, %1, %2" : "=v"(r) : "v"(lo), "v"(hi)); return r; }
;     __device__ __forceinline__ void operator()(const f32x4 (&acc)[2][2][4][2], const Unit& u, int wr, int wc, int fr, int fq) const {
;     ...
;             for (int m = 0; m < 4; ++m) { const int row = row0 + ai * HALF + m * 16; bf16_t* rowp = G + (size_t)row * 2816 + col0;
;                 float* co = nullptr;
;                 if (row < 32768) { const int t = row & 8191; if (t >= 8190) co = outP + ((size_t)(row >> 13) * 2 + (t - 8190)) * 2816 + col0; }
;                 else { const int i = row & 7; if (i >= 6) co = outS + ((size_t)((row - 32768) >> 3) * 2 + (i - 6)) * 2816 + col0; }
;                 const float rs = rsqrtf(rsv[ai][m] * (1.f / 1024.f) + 1e-6f);
; #pragma unroll
;                 for (int bj = 0; bj < 2; ++bj) { const f32x4 v0 = acc[ai][bj][m][0] * rs, v1 = acc[ai][bj][m][1] * rs;
;                     u32x4 w; w.x = cvt_pk_bf16(v0[0], v0[1]); w.y = cvt_pk_bf16(v0[2], v0[3]); w.z = cvt_pk_bf16(v1[0], v1[1]); w.w = cvt_pk_bf16(v1[2], v1[3]);
;                     *(u32x4*)(rowp + bj * HALF) = w;
;                     if (co) { *(f32x4*)(co + bj * HALF) = v0; *(f32x4*)(co + bj * HALF + 4) = v1; } } }
.LBB0_2991:
	s_or_b64 exec, exec, s[26:27]
	v_fmamk_f32 v104, v147, 0x3a800000, v223
	v_mul_f32_e32 v105, 0x4b800000, v104
	v_cmp_gt_f32_e32 vcc, s53, v104
	v_readlane_b32 s26, v240, 12
	v_readlane_b32 s27, v240, 13
	v_cndmask_b32_e32 v104, v104, v105, vcc
	v_rsq_f32_e32 v104, v104
	v_mov_b64_e32 v[102:103], s[26:27]
	v_mad_i64_i32 v[102:103], s[26:27], v136, s52, v[102:103]
	v_mul_f32_e32 v105, 0x45800000, v104
	v_cndmask_b32_e32 v104, v104, v105, vcc
	v_lshl_add_u64 v[102:103], v[132:133], 1, v[102:103]
	v_cmp_ne_u64_e32 vcc, 0, v[100:101]
	v_pk_mul_f32 v[98:99], v[98:99], v[104:105] op_sel_hi:[1,0]
	v_pk_mul_f32 v[96:97], v[96:97], v[104:105] op_sel_hi:[1,0]
	v_pk_mul_f32 v[94:95], v[94:95], v[104:105] op_sel_hi:[1,0]
	v_pk_mul_f32 v[92:93], v[92:93], v[104:105] op_sel_hi:[1,0]
	v_cvt_pk_bf16_f32 v106, v96, v97
	v_cvt_pk_bf16_f32 v107, v98, v99
	s_nop 0
	v_cvt_pk_bf16_f32 v108, v92, v93
	v_cvt_pk_bf16_f32 v109, v94, v95
	global_store_dwordx4 v[102:103], v[106:109], off nt
	s_and_saveexec_b64 s[26:27], vcc
	s_cbranch_execz .LBB0_2993
	global_store_dwordx4 v[100:101], v[96:99], off nt
	global_store_dwordx4 v[100:101], v[92:95], off offset:16 nt
.LBB0_2993:
	s_or_b64 exec, exec, s[26:27]
	v_mov_b32_e32 v105, v104
	v_mov_b32_e32 v92, v104
	v_mov_b32_e32 v93, v104
	v_pk_mul_f32 v[90:91], v[90:91], v[92:93]
	v_pk_mul_f32 v[88:89], v[88:89], v[104:105]
	v_pk_mul_f32 v[86:87], v[86:87], v[92:93]
	v_pk_mul_f32 v[84:85], v[84:85], v[104:105]
	v_cvt_pk_bf16_f32 v92, v88, v89
	v_cvt_pk_bf16_f32 v93, v90, v91
	s_nop 0
	v_cvt_pk_bf16_f32 v94, v84, v85
	v_cvt_pk_bf16_f32 v95, v86, v87
	global_store_dwordx4 v[102:103], v[92:95], off offset:256 nt
	s_and_saveexec_b64 s[26:27], vcc
	s_cbranch_execz .LBB0_2995
	global_store_dwordx4 v[100:101], v[88:91], off offset:512 nt
	global_store_dwordx4 v[100:101], v[84:87], off offset:528 nt

; __device__ __forceinline__ unsigned cvt_pk_bf16(float lo, float hi) { unsigned r; asm volatile("v_cvt_pk_bf16_f32 %0, %1, %2" : "=v"(r) : "v"(lo), "v"(hi)); return r; }
;     __device__ __forceinline__ void operator()(const f32x4 (&acc)[2][2][4][2], const Unit& u, int wr, int wc, int fr, int fq) const {
;     ...
;             for (int m = 0; m < 4; ++m) { const int row = row0 + ai * HALF + m * 16; bf16_t* rowp = G + (size_t)row * 2816 + col0;
;                 float* co = nullptr;
;                 if (row < 32768) { const int t = row & 8191; if (t >= 8190) co = outP + ((size_t)(row >> 13) * 2 + (t - 8190)) * 2816 + col0; }
;                 else { const int i = row & 7; if (i >= 6) co = outS + ((size_t)((row - 32768) >> 3) * 2 + (i - 6)) * 2816 + col0; }
;                 const float rs = rsqrtf(rsv[ai][m] * (1.f / 1024.f) + 1e-6f);
; #pragma unroll
;                 for (int bj = 0; bj < 2; ++bj) { const f32x4 v0 = acc[ai][bj][m][0] * rs, v1 = acc[ai][bj][m][1] * rs;
;                     u32x4 w; w.x = cvt_pk_bf16(v0[0], v0[1]); w.y = cvt_pk_bf16(v0[2], v0[3]); w.z = cvt_pk_bf16(v1[0], v1[1]); w.w = cvt_pk_bf16(v1[2], v1[3]);
;                     *(u32x4*)(rowp + bj * HALF) = w;
;                     if (co) { *(f32x4*)(co + bj * HALF) = v0; *(f32x4*)(co + bj * HALF + 4) = v1; } } }
.LBB0_3003:
	s_or_b64 exec, exec, s[26:27]
	v_fmamk_f32 v88, v146, 0x3a800000, v223
	v_mul_f32_e32 v89, 0x4b800000, v88
	v_cmp_gt_f32_e32 vcc, s53, v88
	v_readlane_b32 s26, v240, 12
	v_readlane_b32 s27, v240, 13
	v_cndmask_b32_e32 v88, v88, v89, vcc
	v_rsq_f32_e32 v88, v88
	v_mov_b64_e32 v[86:87], s[26:27]
	v_mad_i64_i32 v[86:87], s[26:27], v134, s52, v[86:87]
	v_mul_f32_e32 v89, 0x45800000, v88
	v_cndmask_b32_e32 v88, v88, v89, vcc
	v_lshl_add_u64 v[86:87], v[132:133], 1, v[86:87]
	v_cmp_ne_u64_e32 vcc, 0, v[84:85]
	v_pk_mul_f32 v[82:83], v[82:83], v[88:89] op_sel_hi:[1,0]
	v_pk_mul_f32 v[80:81], v[80:81], v[88:89] op_sel_hi:[1,0]
	v_pk_mul_f32 v[78:79], v[78:79], v[88:89] op_sel_hi:[1,0]
	v_pk_mul_f32 v[76:77], v[76:77], v[88:89] op_sel_hi:[1,0]
	v_cvt_pk_bf16_f32 v90, v80, v81
	v_cvt_pk_bf16_f32 v91, v82, v83
	s_nop 0
	v_cvt_pk_bf16_f32 v92, v76, v77
	v_cvt_pk_bf16_f32 v93, v78, v79
	global_store_dwordx4 v[86:87], v[90:93], off nt
	s_and_saveexec_b64 s[26:27], vcc
	s_cbranch_execz .LBB0_3005
	global_store_dwordx4 v[84:85], v[80:83], off nt
	global_store_dwordx4 v[84:85], v[76:79], off offset:16 nt
.LBB0_3005:
	s_or_b64 exec, exec, s[26:27]
	v_mov_b32_e32 v89, v88
	v_mov_b32_e32 v76, v88
	v_mov_b32_e32 v77, v88
	v_pk_mul_f32 v[74:75], v[74:75], v[76:77]
	v_pk_mul_f32 v[72:73], v[72:73], v[88:89]
	v_pk_mul_f32 v[70:71], v[70:71], v[76:77]
	v_pk_mul_f32 v[68:69], v[68:69], v[88:89]
	v_cvt_pk_bf16_f32 v76, v72, v73
	v_cvt_pk_bf16_f32 v77, v74, v75
	s_nop 0
	v_cvt_pk_bf16_f32 v78, v68, v69
	v_cvt_pk_bf16_f32 v79, v70, v71
	global_store_dwordx4 v[86:87], v[76:79], off offset:256 nt
	s_and_saveexec_b64 s[26:27], vcc
	s_cbranch_execz .LBB0_3056
	global_store_dwordx4 v[84:85], v[72:75], off offset:512 nt
	global_store_dwordx4 v[84:85], v[68:71], off offset:528 nt
	s_or_b64 exec, exec, s[26:27]
	s_and_b64 vcc, exec, s[6:7]
	s_cbranch_vccnz .LBB0_3057

; __device__ __forceinline__ unsigned cvt_pk_bf16(float lo, float hi) { unsigned r; asm volatile("v_cvt_pk_bf16_f32 %0, %1, %2" : "=v"(r) : "v"(lo), "v"(hi)); return r; }
;     __device__ __forceinline__ void operator()(const f32x4 (&acc)[2][2][4][2], const Unit& u, int wr, int wc, int fr, int fq) const {
;     ...
;             for (int m = 0; m < 4; ++m) { const int row = row0 + ai * HALF + m * 16; bf16_t* rowp = G + (size_t)row * 2816 + col0;
;                 float* co = nullptr;
;                 if (row < 32768) { const int t = row & 8191; if (t >= 8190) co = outP + ((size_t)(row >> 13) * 2 + (t - 8190)) * 2816 + col0; }
;                 else { const int i = row & 7; if (i >= 6) co = outS + ((size_t)((row - 32768) >> 3) * 2 + (i - 6)) * 2816 + col0; }
;                 const float rs = rsqrtf(rsv[ai][m] * (1.f / 1024.f) + 1e-6f);
; #pragma unroll
;                 for (int bj = 0; bj < 2; ++bj) { const f32x4 v0 = acc[ai][bj][m][0] * rs, v1 = acc[ai][bj][m][1] * rs;
;                     u32x4 w; w.x = cvt_pk_bf16(v0[0], v0[1]); w.y = cvt_pk_bf16(v0[2], v0[3]); w.z = cvt_pk_bf16(v1[0], v1[1]); w.w = cvt_pk_bf16(v1[2], v1[3]);
;                     *(u32x4*)(rowp + bj * HALF) = w;
;                     if (co) { *(f32x4*)(co + bj * HALF) = v0; *(f32x4*)(co + bj * HALF + 4) = v1; } } }
.LBB0_3015:
	s_or_b64 exec, exec, s[6:7]
	v_fmamk_f32 v71, v139, 0x3a800000, v223
	v_mul_f32_e32 v74, 0x4b800000, v71
	v_cmp_gt_f32_e32 vcc, s53, v71
	v_readlane_b32 s6, v240, 12
	v_readlane_b32 s7, v240, 13
	v_cndmask_b32_e32 v71, v71, v74, vcc
	v_rsq_f32_e32 v74, v71
	v_mov_b64_e32 v[72:73], s[6:7]
	v_mad_i64_i32 v[70:71], s[6:7], v70, s52, v[72:73]
	v_mul_f32_e32 v72, 0x45800000, v74
	v_cndmask_b32_e32 v72, v74, v72, vcc
	v_lshl_add_u64 v[70:71], v[132:133], 1, v[70:71]
	v_cmp_ne_u64_e32 vcc, 0, v[68:69]
	v_pk_mul_f32 v[66:67], v[66:67], v[72:73] op_sel_hi:[1,0]
	v_pk_mul_f32 v[64:65], v[64:65], v[72:73] op_sel_hi:[1,0]
	v_pk_mul_f32 v[62:63], v[62:63], v[72:73] op_sel_hi:[1,0]
	v_pk_mul_f32 v[60:61], v[60:61], v[72:73] op_sel_hi:[1,0]
	v_cvt_pk_bf16_f32 v74, v64, v65
	v_cvt_pk_bf16_f32 v75, v66, v67
	s_nop 0
	v_cvt_pk_bf16_f32 v76, v60, v61
	v_cvt_pk_bf16_f32 v77, v62, v63
	global_store_dwordx4 v[70:71], v[74:77], off nt
	s_and_saveexec_b64 s[6:7], vcc
	s_cbranch_execz .LBB0_3017
	global_store_dwordx4 v[68:69], v[64:67], off nt
	global_store_dwordx4 v[68:69], v[60:63], off offset:16 nt
.LBB0_3017:
	s_or_b64 exec, exec, s[6:7]
	v_mov_b32_e32 v73, v72
	v_mov_b32_e32 v60, v72
	v_mov_b32_e32 v61, v72
	v_pk_mul_f32 v[58:59], v[58:59], v[60:61]
	v_pk_mul_f32 v[56:57], v[56:57], v[72:73]
	v_pk_mul_f32 v[54:55], v[54:55], v[60:61]
	v_pk_mul_f32 v[52:53], v[52:53], v[72:73]
	v_cvt_pk_bf16_f32 v60, v56, v57
	v_cvt_pk_bf16_f32 v61, v58, v59
	s_nop 0
	v_cvt_pk_bf16_f32 v62, v52, v53
	v_cvt_pk_bf16_f32 v63, v54, v55
	global_store_dwordx4 v[70:71], v[60:63], off offset:256 nt
	s_and_saveexec_b64 s[6:7], vcc
	s_cbranch_execz .LBB0_3019
	global_store_dwordx4 v[68:69], v[56:59], off offset:512 nt
	global_store_dwordx4 v[68:69], v[52:55], off offset:528 nt

; __device__ __forceinline__ unsigned cvt_pk_bf16(float lo, float hi) { unsigned r; asm volatile("v_cvt_pk_bf16_f32 %0, %1, %2" : "=v"(r) : "v"(lo), "v"(hi)); return r; }
;     __device__ __forceinline__ void operator()(const f32x4 (&acc)[2][2][4][2], const Unit& u, int wr, int wc, int fr, int fq) const {
;     ...
;             for (int m = 0; m < 4; ++m) { const int row = row0 + ai * HALF + m * 16; bf16_t* rowp = G + (size_t)row * 2816 + col0;
;                 float* co = nullptr;
;                 if (row < 32768) { const int t = row & 8191; if (t >= 8190) co = outP + ((size_t)(row >> 13) * 2 + (t - 8190)) * 2816 + col0; }
;                 else { const int i = row & 7; if (i >= 6) co = outS + ((size_t)((row - 32768) >> 3) * 2 + (i - 6)) * 2816 + col0; }
;                 const float rs = rsqrtf(rsv[ai][m] * (1.f / 1024.f) + 1e-6f);
; #pragma unroll
;                 for (int bj = 0; bj < 2; ++bj) { const f32x4 v0 = acc[ai][bj][m][0] * rs, v1 = acc[ai][bj][m][1] * rs;
;                     u32x4 w; w.x = cvt_pk_bf16(v0[0], v0[1]); w.y = cvt_pk_bf16(v0[2], v0[3]); w.z = cvt_pk_bf16(v1[0], v1[1]); w.w = cvt_pk_bf16(v1[2], v1[3]);
;                     *(u32x4*)(rowp + bj * HALF) = w;
;                     if (co) { *(f32x4*)(co + bj * HALF) = v0; *(f32x4*)(co + bj * HALF + 4) = v1; } } }
.LBB0_3027:
	s_or_b64 exec, exec, s[6:7]
	v_fmamk_f32 v55, v137, 0x3a800000, v223
	v_mul_f32_e32 v58, 0x4b800000, v55
	v_cmp_gt_f32_e32 vcc, s53, v55
	v_readlane_b32 s6, v240, 12
	v_readlane_b32 s7, v240, 13
	v_cndmask_b32_e32 v55, v55, v58, vcc
	v_rsq_f32_e32 v58, v55
	v_mov_b64_e32 v[56:57], s[6:7]
	v_mad_i64_i32 v[54:55], s[6:7], v54, s52, v[56:57]
	v_mul_f32_e32 v56, 0x45800000, v58
	v_cndmask_b32_e32 v56, v58, v56, vcc
	v_lshl_add_u64 v[54:55], v[132:133], 1, v[54:55]
	v_cmp_ne_u64_e32 vcc, 0, v[52:53]
	v_pk_mul_f32 v[50:51], v[50:51], v[56:57] op_sel_hi:[1,0]
	v_pk_mul_f32 v[48:49], v[48:49], v[56:57] op_sel_hi:[1,0]
	v_pk_mul_f32 v[46:47], v[46:47], v[56:57] op_sel_hi:[1,0]
	v_pk_mul_f32 v[44:45], v[44:45], v[56:57] op_sel_hi:[1,0]
	v_cvt_pk_bf16_f32 v58, v48, v49
	v_cvt_pk_bf16_f32 v59, v50, v51
	s_nop 0
	v_cvt_pk_bf16_f32 v60, v44, v45
	v_cvt_pk_bf16_f32 v61, v46, v47
	global_store_dwordx4 v[54:55], v[58:61], off nt
	s_and_saveexec_b64 s[6:7], vcc
	s_cbranch_execz .LBB0_3029
	global_store_dwordx4 v[52:53], v[48:51], off nt
	global_store_dwordx4 v[52:53], v[44:47], off offset:16 nt
.LBB0_3029:
	s_or_b64 exec, exec, s[6:7]
	v_mov_b32_e32 v57, v56
	v_mov_b32_e32 v44, v56
	v_mov_b32_e32 v45, v56
	v_pk_mul_f32 v[42:43], v[42:43], v[44:45]
	v_pk_mul_f32 v[40:41], v[40:41], v[56:57]
	v_pk_mul_f32 v[38:39], v[38:39], v[44:45]
	v_pk_mul_f32 v[36:37], v[36:37], v[56:57]
	v_cvt_pk_bf16_f32 v44, v40, v41
	v_cvt_pk_bf16_f32 v45, v42, v43
	s_nop 0
	v_cvt_pk_bf16_f32 v46, v36, v37
	v_cvt_pk_bf16_f32 v47, v38, v39
	global_store_dwordx4 v[54:55], v[44:47], off offset:256 nt
	s_and_saveexec_b64 s[6:7], vcc
	s_cbranch_execz .LBB0_3031
	global_store_dwordx4 v[52:53], v[40:43], off offset:512 nt
	global_store_dwordx4 v[52:53], v[36:39], off offset:528 nt

; __device__ __forceinline__ unsigned cvt_pk_bf16(float lo, float hi) { unsigned r; asm volatile("v_cvt_pk_bf16_f32 %0, %1, %2" : "=v"(r) : "v"(lo), "v"(hi)); return r; }
;     __device__ __forceinline__ void operator()(const f32x4 (&acc)[2][2][4][2], const Unit& u, int wr, int wc, int fr, int fq) const {
;     ...
;             for (int m = 0; m < 4; ++m) { const int row = row0 + ai * HALF + m * 16; bf16_t* rowp = G + (size_t)row * 2816 + col0;
;                 float* co = nullptr;
;                 if (row < 32768) { const int t = row & 8191; if (t >= 8190) co = outP + ((size_t)(row >> 13) * 2 + (t - 8190)) * 2816 + col0; }
;                 else { const int i = row & 7; if (i >= 6) co = outS + ((size_t)((row - 32768) >> 3) * 2 + (i - 6)) * 2816 + col0; }
;                 const float rs = rsqrtf(rsv[ai][m] * (1.f / 1024.f) + 1e-6f);
; #pragma unroll
;                 for (int bj = 0; bj < 2; ++bj) { const f32x4 v0 = acc[ai][bj][m][0] * rs, v1 = acc[ai][bj][m][1] * rs;
;                     u32x4 w; w.x = cvt_pk_bf16(v0[0], v0[1]); w.y = cvt_pk_bf16(v0[2], v0[3]); w.z = cvt_pk_bf16(v1[0], v1[1]); w.w = cvt_pk_bf16(v1[2], v1[3]);
;                     *(u32x4*)(rowp + bj * HALF) = w;
;                     if (co) { *(f32x4*)(co + bj * HALF) = v0; *(f32x4*)(co + bj * HALF + 4) = v1; } } }
.LBB0_3039:
	s_or_b64 exec, exec, s[6:7]
	v_fmamk_f32 v39, v135, 0x3a800000, v223
	v_mul_f32_e32 v42, 0x4b800000, v39
	v_cmp_gt_f32_e32 vcc, s53, v39
	v_readlane_b32 s6, v240, 12
	v_readlane_b32 s7, v240, 13
	v_cndmask_b32_e32 v39, v39, v42, vcc
	v_rsq_f32_e32 v42, v39
	v_mov_b64_e32 v[40:41], s[6:7]
	v_mad_i64_i32 v[38:39], s[6:7], v38, s52, v[40:41]
	v_mul_f32_e32 v40, 0x45800000, v42
	v_cndmask_b32_e32 v40, v42, v40, vcc
	v_lshl_add_u64 v[38:39], v[132:133], 1, v[38:39]
	v_cmp_ne_u64_e32 vcc, 0, v[36:37]
	v_pk_mul_f32 v[34:35], v[34:35], v[40:41] op_sel_hi:[1,0]
	v_pk_mul_f32 v[32:33], v[32:33], v[40:41] op_sel_hi:[1,0]
	v_pk_mul_f32 v[30:31], v[30:31], v[40:41] op_sel_hi:[1,0]
	v_pk_mul_f32 v[28:29], v[28:29], v[40:41] op_sel_hi:[1,0]
	v_cvt_pk_bf16_f32 v42, v32, v33
	v_cvt_pk_bf16_f32 v43, v34, v35
	s_nop 0
	v_cvt_pk_bf16_f32 v44, v28, v29
	v_cvt_pk_bf16_f32 v45, v30, v31
	global_store_dwordx4 v[38:39], v[42:45], off nt
	s_and_saveexec_b64 s[6:7], vcc
	s_cbranch_execz .LBB0_3041
	global_store_dwordx4 v[36:37], v[32:35], off nt
	global_store_dwordx4 v[36:37], v[28:31], off offset:16 nt
.LBB0_3041:
	s_or_b64 exec, exec, s[6:7]
	v_mov_b32_e32 v41, v40
	v_mov_b32_e32 v28, v40
	v_mov_b32_e32 v29, v40
	v_pk_mul_f32 v[26:27], v[26:27], v[28:29]
	v_pk_mul_f32 v[24:25], v[24:25], v[40:41]
	v_pk_mul_f32 v[22:23], v[22:23], v[28:29]
	v_pk_mul_f32 v[20:21], v[20:21], v[40:41]
	v_cvt_pk_bf16_f32 v28, v24, v25
	v_cvt_pk_bf16_f32 v29, v26, v27
	s_nop 0
	v_cvt_pk_bf16_f32 v30, v20, v21
	v_cvt_pk_bf16_f32 v31, v22, v23
	global_store_dwordx4 v[38:39], v[28:31], off offset:256 nt
	s_and_saveexec_b64 s[6:7], vcc
	s_cbranch_execz .LBB0_3043
	global_store_dwordx4 v[36:37], v[24:27], off offset:512 nt
	global_store_dwordx4 v[36:37], v[20:23], off offset:528 nt

; __device__ __forceinline__ unsigned cvt_pk_bf16(float lo, float hi) { unsigned r; asm volatile("v_cvt_pk_bf16_f32 %0, %1, %2" : "=v"(r) : "v"(lo), "v"(hi)); return r; }
;     __device__ __forceinline__ void operator()(const f32x4 (&acc)[2][2][4][2], const Unit& u, int wr, int wc, int fr, int fq) const {
;     ...
;             for (int m = 0; m < 4; ++m) { const int row = row0 + ai * HALF + m * 16; bf16_t* rowp = G + (size_t)row * 2816 + col0;
;                 float* co = nullptr;
;                 if (row < 32768) { const int t = row & 8191; if (t >= 8190) co = outP + ((size_t)(row >> 13) * 2 + (t - 8190)) * 2816 + col0; }
;                 else { const int i = row & 7; if (i >= 6) co = outS + ((size_t)((row - 32768) >> 3) * 2 + (i - 6)) * 2816 + col0; }
;                 const float rs = rsqrtf(rsv[ai][m] * (1.f / 1024.f) + 1e-6f);
; #pragma unroll
;                 for (int bj = 0; bj < 2; ++bj) { const f32x4 v0 = acc[ai][bj][m][0] * rs, v1 = acc[ai][bj][m][1] * rs;
;                     u32x4 w; w.x = cvt_pk_bf16(v0[0], v0[1]); w.y = cvt_pk_bf16(v0[2], v0[3]); w.z = cvt_pk_bf16(v1[0], v1[1]); w.w = cvt_pk_bf16(v1[2], v1[3]);
;                     *(u32x4*)(rowp + bj * HALF) = w;
;                     if (co) { *(f32x4*)(co + bj * HALF) = v0; *(f32x4*)(co + bj * HALF + 4) = v1; } } }
.LBB0_3051:
	s_or_b64 exec, exec, s[0:1]
	v_fmamk_f32 v1, v1, 0x3a800000, v223
	v_mul_f32_e32 v3, 0x4b800000, v1
	v_cmp_gt_f32_e32 vcc, s53, v1
	v_readlane_b32 s0, v240, 12
	v_readlane_b32 s1, v240, 13
	v_cndmask_b32_e32 v1, v1, v3, vcc
	v_rsq_f32_e32 v1, v1
	v_mov_b64_e32 v[22:23], s[0:1]
	v_mad_i64_i32 v[2:3], s[0:1], v2, s52, v[22:23]
	v_mul_f32_e32 v22, 0x45800000, v1
	v_cndmask_b32_e32 v22, v1, v22, vcc
	v_lshl_add_u64 v[2:3], v[132:133], 1, v[2:3]
	v_cmp_ne_u64_e32 vcc, 0, v[20:21]
	v_pk_mul_f32 v[18:19], v[18:19], v[22:23] op_sel_hi:[1,0]
	v_pk_mul_f32 v[16:17], v[16:17], v[22:23] op_sel_hi:[1,0]
	v_pk_mul_f32 v[14:15], v[14:15], v[22:23] op_sel_hi:[1,0]
	v_pk_mul_f32 v[12:13], v[12:13], v[22:23] op_sel_hi:[1,0]
	v_cvt_pk_bf16_f32 v24, v16, v17
	v_cvt_pk_bf16_f32 v25, v18, v19
	s_nop 0
	v_cvt_pk_bf16_f32 v26, v12, v13
	v_cvt_pk_bf16_f32 v27, v14, v15
	global_store_dwordx4 v[2:3], v[24:27], off nt
	s_and_saveexec_b64 s[0:1], vcc
	s_cbranch_execz .LBB0_3053
	global_store_dwordx4 v[20:21], v[16:19], off nt
	global_store_dwordx4 v[20:21], v[12:15], off offset:16 nt

;     static __device__ __forceinline__ void unpk4(const u32x2 w, float (&o)[4]) { o[0] = bf_lo(w.x); o[1] = bf_hi(w.x); o[2] = bf_lo(w.y); o[3] = bf_hi(w.y); }
;     template <int N> static __device__ __forceinline__ u32x2 dpp_prev(const u32x2 pv, const u32x2 cur) { u32x2 r; r.x = dpp_prev1<N>(pv.x, cur.x); r.y = dpp_prev1<N>(pv.y, cur.y); return r; }
;     __device__ __forceinline__ void operator()(const f32x4 (&acc)[2][2][4][2], const Unit& u, int wr, int wc, int fr, int fq) const {
;     ...
;             for (int m = 0; m < 4; ++m) rs8[ai][m] = rsqrtf(SS[u.rb + (u.half ? 0 : ai * HALF) + wr * 64 + fr + 16 * m] * (1.f / 1024.f) + 1e-6f);
;         if (u.pm < 128) {
;     ...
;         for (int bj = 0; bj < 2; ++bj)
; #pragma unroll
;           for (int hv = 0; hv < 2; ++hv) {
;             const int col = u.pn * BM + bj * HALF + wc * 32 + 8 * fq + 4 * hv;
;             float w0[4], w1[4], w2[4], bb[4];
;             ld4f(cw + col, w0); ld4f(cw + 2816 + col, w1); ld4f(cw + 2 * 2816 + col, w2); ld4f(cb + col, bb);
;             {
;                 const int i = fr & 7;
;                 u32x2 gq[4];
; #pragma unroll
;                 for (int m = 0; m < 4; ++m) { const int row = row0 + m * 16; gq[m] = *(const u32x2*)(G + (size_t)row * 2816 + col); }
; #pragma unroll
;                 for (int mh = 0; mh < 4; mh += 2) {
;                 f32x4 c0[4], c1[4];
; #pragma unroll
;                 for (int m = mh; m < mh + 2; ++m) { const int row = row0 + m * 16; const float* cx = ctx + (size_t)((row - 32768) >> 3) * 2 * 2816 + col;
;                     c0[m] = *(const f32x4*)cx; c1[m] = *(const f32x4*)(cx + 2816); }
; #pragma unroll
;                 for (int m = mh; m < mh + 2; ++m) { const int row = row0 + m * 16; const u32x2 cur = gq[m];
;                     const u32x2 q1 = dpp_prev<1>(cur, cur), q2 = dpp_prev<2>(cur, cur);
;                     float g0[4], g1[4], g2[4]; unpk4(cur, g0); unpk4(q1, g1); unpk4(q2, g2);
; #pragma unroll
;                     for (int j = 0; j < 4; ++j) { const float x1 = c1[m][j], x0 = c0[m][j];
;                         if (i < 1) g1[j] = x1;
;                         if (i < 2) g2[j] = (i == 1) ? x1 : x0; }
;                     finish(g0, g1, g2, w0, w1, w2, bb, acc[0][bj][m][hv], rs8[0][m], H + (size_t)row * 2816 + col); }
.LBB0_3138:
	v_mov_b32_e32 v1, v217
	v_mov_b32_e32 v136, v218
	s_add_i32 s47, s82, s58
	s_cmpk_lt_i32 s79, 0x80
	v_add_u32_e32 v210, s47, v1
	v_ashrrev_i32_e32 v211, 31, v210
	s_waitcnt lgkmcnt(0)
	v_add_u32_e32 v194, 16, v210
	v_add_u32_e32 v192, 32, v210
	v_lshl_add_u64 v[2:3], v[210:211], 2, s[10:11]
	v_ashrrev_i32_e32 v195, 31, v194
	v_ashrrev_i32_e32 v193, 31, v192
	v_add_u32_e32 v190, 48, v210
	global_load_dword v137, v[2:3], off
	v_lshl_add_u64 v[2:3], v[194:195], 2, s[10:11]
	v_lshl_add_u64 v[132:133], v[192:193], 2, s[10:11]
	v_ashrrev_i32_e32 v191, 31, v190
	v_lshl_add_u64 v[134:135], v[190:191], 2, s[10:11]
	global_load_dword v2, v[2:3], off
	s_nop 0
	global_load_dword v132, v[132:133], off
	s_nop 0
	global_load_dword v133, v[134:135], off
	v_lshl_add_u32 v3, v136, 3, s59
	s_waitcnt vmcnt(0)
	v_fmamk_f32 v134, v137, 0x3a800000, v223
	v_mul_f32_e32 v135, 0x4b800000, v134
	v_cmp_gt_f32_e32 vcc, s66, v134
	v_fmamk_f32 v2, v2, 0x3a800000, v223
	v_fmamk_f32 v132, v132, 0x3a800000, v223
	v_fmamk_f32 v133, v133, 0x3a800000, v223
	v_cndmask_b32_e32 v134, v134, v135, vcc
	v_mul_f32_e32 v135, 0x4b800000, v2
	v_mul_f32_e32 v136, 0x4b800000, v132
	v_mul_f32_e32 v137, 0x4b800000, v133
	v_cmp_gt_f32_e64 s[0:1], s66, v2
	v_cmp_gt_f32_e64 s[6:7], s66, v132
	v_cmp_gt_f32_e64 s[8:9], s66, v133
	v_rsq_f32_e32 v134, v134
	v_cndmask_b32_e64 v2, v2, v135, s[0:1]
	v_cndmask_b32_e64 v132, v132, v136, s[6:7]
	v_cndmask_b32_e64 v133, v133, v137, s[8:9]
	v_rsq_f32_e32 v2, v2
	v_rsq_f32_e32 v132, v132
	v_rsq_f32_e32 v133, v133
	v_mul_f32_e32 v135, 0x45800000, v134
	v_cndmask_b32_e32 v188, v134, v135, vcc
	v_mul_f32_e32 v134, 0x45800000, v2
	v_mul_f32_e32 v135, 0x45800000, v132
	v_mul_f32_e32 v136, 0x45800000, v133
	v_cndmask_b32_e64 v186, v2, v134, s[0:1]
	v_cndmask_b32_e64 v184, v132, v135, s[6:7]
	v_cndmask_b32_e64 v2, v133, v136, s[8:9]
	s_mov_b64 s[0:1], -1
	s_cbranch_scc1 .LBB0_3141
	v_lshl_add_u32 v150, s80, 8, v3
	v_ashrrev_i32_e32 v151, 31, v150
	v_readlane_b32 s56, v240, 12
	v_lshlrev_b64 v[160:161], 1, v[150:151]
	v_readlane_b32 s57, v240, 13
	v_add_u32_e32 v134, 0xffff8000, v210
	v_add_u32_e32 v152, 0xffff8010, v210
	v_lshl_add_u64 v[154:155], s[56:57], 0, v[160:161]
	v_mad_i64_i32 v[132:133], s[0:1], v210, s67, v[154:155]
	global_load_dwordx2 v[212:213], v[132:133], off
	v_lshlrev_b64 v[132:133], 2, v[150:151]
	v_lshl_add_u64 v[156:157], s[16:17], 0, v[132:133]
	v_ashrrev_i32_e32 v151, 3, v134
	v_mad_i64_i32 v[134:135], s[0:1], v151, s70, v[156:157]
	v_add_co_u32_e32 v136, vcc, s41, v134
	v_readlane_b32 s0, v240, 58
	s_nop 0
	v_addc_co_u32_e32 v137, vcc, 0, v135, vcc
	global_load_dwordx4 v[168:171], v[134:135], off
	global_load_dwordx4 v[172:175], v[136:137], off offset:3072
	v_lshl_add_u64 v[134:135], s[12:13], 0, v[132:133]
	v_lshl_add_u64 v[136:137], s[14:15], 0, v[132:133]
	global_load_dwordx4 v[140:143], v[134:135], off
	global_load_dwordx4 v[144:147], v[136:137], off
	v_lshl_add_u64 v[134:135], s[18:19], 0, v[132:133]
	global_load_dwordx4 v[136:139], v[134:135], off
	v_lshl_add_u64 v[132:133], s[20:21], 0, v[132:133]
	global_load_dwordx4 v[132:135], v[132:133], off
	v_readlane_b32 s1, v240, 59
	v_ashrrev_i32_e32 v166, 3, v152
	v_and_b32_e32 v167, 7, v1
	v_mov_b64_e32 v[158:159], s[0:1]
	v_mad_i64_i32 v[162:163], s[0:1], v194, s67, v[154:155]
	v_mad_i64_i32 v[164:165], s[0:1], v192, s67, v[154:155]
	v_mad_i64_i32 v[154:155], s[0:1], v190, s67, v[154:155]
	v_mad_i64_i32 v[176:177], s[0:1], v166, s70, v[156:157]
	global_load_dwordx2 v[226:227], v[162:163], off
	s_nop 0
	global_load_dwordx2 v[164:165], v[164:165], off
	s_nop 0
	global_load_dwordx2 v[162:163], v[154:155], off
	v_add_co_u32_e32 v154, vcc, s41, v176
	v_mad_i64_i32 v[152:153], s[0:1], v210, s67, v[158:159]
	s_nop 0
	v_addc_co_u32_e32 v155, vcc, 0, v177, vcc
	global_load_dwordx4 v[176:179], v[176:177], off
	s_nop 0
	global_load_dwordx4 v[180:183], v[154:155], off offset:3072
	v_cmp_eq_u32_e32 vcc, 1, v167
	v_cmp_eq_u32_e64 s[6:7], 0, v167
	v_cmp_gt_u32_e64 s[0:1], 2, v167
	v_mov_b64_e32 v[148:149], s[30:31]
	v_lshl_add_u64 v[214:215], v[152:153], 0, v[160:161]
	s_waitcnt vmcnt(11)
	v_mov_b32_dpp v185, v212 row_ror:1 row_mask:0xf bank_mask:0xf bound_ctrl:1
	v_mov_b32_dpp v187, v213 row_ror:1 row_mask:0xf bank_mask:0xf bound_ctrl:1
	v_mov_b32_dpp v189, v212 row_ror:2 row_mask:0xf bank_mask:0xf bound_ctrl:1
	v_mov_b32_dpp v185, v212 row_shr:1 row_mask:0xf bank_mask:0xf
	v_mov_b32_dpp v187, v213 row_shr:1 row_mask:0xf bank_mask:0xf
	v_mov_b32_dpp v189, v212 row_shr:2 row_mask:0xf bank_mask:0xf
	v_lshlrev_b32_e32 v154, 16, v212
	v_and_b32_e32 v155, 0xffff0000, v212
	v_mov_b32_dpp v191, v213 row_ror:2 row_mask:0xf bank_mask:0xf bound_ctrl:1
	s_waitcnt vmcnt(9)
	v_cndmask_b32_e32 v193, v168, v172, vcc
	v_cndmask_b32_e32 v195, v169, v173, vcc
	v_cndmask_b32_e32 v211, v170, v174, vcc
	v_cndmask_b32_e32 v212, v171, v175, vcc
	v_lshlrev_b32_e32 v168, 16, v185
	v_and_b32_e32 v169, 0xffff0000, v185
	v_lshlrev_b32_e32 v170, 16, v187
	v_and_b32_e32 v171, 0xffff0000, v187
	v_lshlrev_b32_e32 v185, 16, v189
	v_and_b32_e32 v187, 0xffff0000, v189
	v_cndmask_b32_e64 v171, v171, v175, s[6:7]
	v_cndmask_b32_e64 v170, v170, v174, s[6:7]
	v_cndmask_b32_e64 v175, v187, v195, s[0:1]
	v_cndmask_b32_e64 v174, v185, v193, s[0:1]
	v_cndmask_b32_e64 v169, v169, v173, s[6:7]
	v_cndmask_b32_e64 v168, v168, v172, s[6:7]
	s_waitcnt vmcnt(7)
	v_pk_fma_f32 v[174:175], v[140:141], v[174:175], v[144:145]
	v_mov_b32_dpp v191, v213 row_shr:2 row_mask:0xf bank_mask:0xf
	s_waitcnt vmcnt(6)
	v_pk_fma_f32 v[168:169], v[136:137], v[168:169], v[174:175]
	v_lshlrev_b32_e32 v189, 16, v191
	v_and_b32_e32 v191, 0xffff0000, v191
	s_waitcnt vmcnt(5)
; __device__ __forceinline__ unsigned cvt_pk_bf16(float lo, float hi) { unsigned r; asm volatile("v_cvt_pk_bf16_f32 %0, %1, %2" : "=v"(r) : "v"(lo), "v"(hi)); return r; }
;     static __device__ __forceinline__ void unpk4(const u32x2 w, float (&o)[4]) { o[0] = bf_lo(w.x); o[1] = bf_hi(w.x); o[2] = bf_lo(w.y); o[3] = bf_hi(w.y); }
;     template <int N> static __device__ __forceinline__ u32x2 dpp_prev(const u32x2 pv, const u32x2 cur) { u32x2 r; r.x = dpp_prev1<N>(pv.x, cur.x); r.y = dpp_prev1<N>(pv.y, cur.y); return r; }
;     static __device__ __forceinline__ void finish(const float (&g0)[4], const float (&g1)[4], const float (&g2)[4], const float (&w0)[4], const float (&w1)[4], const float (&w2)[4], const float (&bb)[4],
;                                                   const f32x4 v, float rs, bf16_t* dst) {
;         float h[4];
; #pragma unroll
;         for (int j = 0; j < 4; j += 2) {
;             const f32x2 gc = (f32x2){bb[j] + w0[j] * g2[j] + w1[j] * g1[j] + w2[j] * g0[j], bb[j + 1] + w0[j + 1] * g2[j + 1] + w1[j + 1] * g1[j + 1] + w2[j + 1] * g0[j + 1]};
;             const f32x2 ge = gelu_pk(gc); h[j] = ge.x * v[j] * rs; h[j + 1] = ge.y * v[j + 1] * rs; }
;         u32x2 w; w.x = cvt_pk_bf16(h[0], h[1]); w.y = cvt_pk_bf16(h[2], h[3]);
;         *(u32x2*)dst = w;
;     __device__ __forceinline__ void operator()(const f32x4 (&acc)[2][2][4][2], const Unit& u, int wr, int wc, int fr, int fq) const {
;     ...
;                 for (int m = mh; m < mh + 2; ++m) { const int row = row0 + m * 16; const u32x2 cur = gq[m];
;                     const u32x2 q1 = dpp_prev<1>(cur, cur), q2 = dpp_prev<2>(cur, cur);
;                     float g0[4], g1[4], g2[4]; unpk4(cur, g0); unpk4(q1, g1); unpk4(q2, g2);
; #pragma unroll
;                     for (int j = 0; j < 4; ++j) { const float x1 = c1[m][j], x0 = c0[m][j];
;                         if (i < 1) g1[j] = x1;
;                         if (i < 2) g2[j] = (i == 1) ? x1 : x0; }
;                     finish(g0, g1, g2, w0, w1, w2, bb, acc[0][bj][m][hv], rs8[0][m], H + (size_t)row * 2816 + col); }
	v_pk_fma_f32 v[154:155], v[132:133], v[154:155], v[168:169]
	v_cndmask_b32_e64 v173, v191, v212, s[0:1]
	v_cndmask_b32_e64 v172, v189, v211, s[0:1]
	v_pk_mul_f32 v[168:169], v[154:155], s[26:27] op_sel_hi:[1,0]
	v_pk_fma_f32 v[172:173], v[142:143], v[172:173], v[146:147]
	v_med3_f32 v168, v168, s71, v224
	v_med3_f32 v169, v169, s71, v224
	v_pk_fma_f32 v[170:171], v[138:139], v[170:171], v[172:173]
	v_pk_mul_f32 v[172:173], v[168:169], v[168:169]
	v_pk_mul_f32 v[154:155], v[154:155], 0.5 op_sel_hi:[1,0]
	v_pk_fma_f32 v[174:175], v[172:173], s[28:29], v[148:149] op_sel_hi:[1,0,0] neg_lo:[1,0,0] neg_hi:[1,0,0]
	s_nop 0
	v_pk_fma_f32 v[174:175], v[172:173], v[174:175], s[34:35] op_sel_hi:[1,1,0]
	s_nop 0
	v_pk_fma_f32 v[174:175], v[172:173], v[174:175], s[36:37] op_sel_hi:[1,1,0]
	s_nop 0
	v_pk_fma_f32 v[174:175], v[172:173], v[174:175], s[38:39] op_sel_hi:[1,1,0]
	s_nop 0
	v_pk_fma_f32 v[174:175], v[172:173], v[174:175], s[40:41] op_sel_hi:[1,1,0]
	s_nop 0
	v_pk_fma_f32 v[174:175], v[172:173], v[174:175], s[42:43] op_sel_hi:[1,1,0]
	s_nop 0
	v_pk_fma_f32 v[172:173], v[172:173], v[174:175], s[44:45] op_sel_hi:[1,1,0]
	s_nop 0
	v_pk_mul_f32 v[168:169], v[168:169], v[172:173]
	s_nop 0
	v_pk_fma_f32 v[154:155], v[154:155], v[168:169], v[154:155]
	s_nop 0
	v_mul_f32_e32 v154, v128, v154
	v_mul_f32_e32 v167, v188, v154
	v_mul_f32_e32 v154, v129, v155
	v_mul_f32_e32 v174, v188, v154
	v_lshlrev_b32_e32 v154, 16, v213
	v_and_b32_e32 v155, 0xffff0000, v213
	v_pk_fma_f32 v[154:155], v[134:135], v[154:155], v[170:171]
	s_nop 0
	v_pk_mul_f32 v[168:169], v[154:155], s[26:27] op_sel_hi:[1,0]
	v_pk_mul_f32 v[154:155], v[154:155], 0.5 op_sel_hi:[1,0]
	v_med3_f32 v168, v168, s71, v224
	v_med3_f32 v169, v169, s71, v224
	v_pk_mul_f32 v[170:171], v[168:169], v[168:169]
	s_nop 0
	v_pk_fma_f32 v[172:173], v[170:171], s[28:29], v[148:149] op_sel_hi:[1,0,0] neg_lo:[1,0,0] neg_hi:[1,0,0]
	s_nop 0
	v_pk_fma_f32 v[172:173], v[170:171], v[172:173], s[34:35] op_sel_hi:[1,1,0]
	s_nop 0
	v_pk_fma_f32 v[172:173], v[170:171], v[172:173], s[36:37] op_sel_hi:[1,1,0]
	s_nop 0
	v_pk_fma_f32 v[172:173], v[170:171], v[172:173], s[38:39] op_sel_hi:[1,1,0]
	s_nop 0
	v_pk_fma_f32 v[172:173], v[170:171], v[172:173], s[40:41] op_sel_hi:[1,1,0]
	s_nop 0
	v_pk_fma_f32 v[172:173], v[170:171], v[172:173], s[42:43] op_sel_hi:[1,1,0]
	s_nop 0
	v_pk_fma_f32 v[170:171], v[170:171], v[172:173], s[44:45] op_sel_hi:[1,1,0]
	s_nop 0
	v_pk_mul_f32 v[168:169], v[168:169], v[170:171]
	s_nop 0
	v_pk_fma_f32 v[154:155], v[154:155], v[168:169], v[154:155]
	s_nop 0
	v_mul_f32_e32 v154, v130, v154
	v_mul_f32_e32 v168, v188, v154
	v_mul_f32_e32 v154, v131, v155
	v_mul_f32_e32 v155, v188, v154
	v_cvt_pk_bf16_f32 v154, v167, v174
	v_cvt_pk_bf16_f32 v155, v168, v155
	global_store_dwordx2 v[214:215], v[154:155], off nt
	s_waitcnt vmcnt(5)
	v_mov_b32_dpp v167, v226 row_ror:2 row_mask:0xf bank_mask:0xf bound_ctrl:1
	v_mov_b32_dpp v154, v226 row_ror:1 row_mask:0xf bank_mask:0xf bound_ctrl:1
	v_mov_b32_dpp v155, v227 row_ror:1 row_mask:0xf bank_mask:0xf bound_ctrl:1
	v_mov_b32_dpp v168, v227 row_ror:2 row_mask:0xf bank_mask:0xf bound_ctrl:1
	v_mov_b32_dpp v154, v226 row_shr:1 row_mask:0xf bank_mask:0xf
	v_mov_b32_dpp v155, v227 row_shr:1 row_mask:0xf bank_mask:0xf
	v_mov_b32_dpp v167, v226 row_shr:2 row_mask:0xf bank_mask:0xf
	v_mov_b32_dpp v168, v227 row_shr:2 row_mask:0xf bank_mask:0xf
	v_lshlrev_b32_e32 v170, 16, v154
	v_and_b32_e32 v154, 0xffff0000, v154
	v_lshlrev_b32_e32 v172, 16, v155
	v_and_b32_e32 v155, 0xffff0000, v155
	v_lshlrev_b32_e32 v174, 16, v167
	v_and_b32_e32 v167, 0xffff0000, v167
	v_lshlrev_b32_e32 v175, 16, v168
	v_and_b32_e32 v173, 0xffff0000, v168
	s_waitcnt vmcnt(1)
	v_cndmask_b32_e64 v169, v154, v181, s[6:7]
	v_cndmask_b32_e64 v168, v170, v180, s[6:7]
	v_cndmask_b32_e64 v171, v155, v183, s[6:7]
	v_cndmask_b32_e64 v170, v172, v182, s[6:7]
	v_cndmask_b32_e32 v154, v176, v180, vcc
	v_cndmask_b32_e32 v155, v177, v181, vcc
	v_cndmask_b32_e32 v172, v178, v182, vcc
	v_cndmask_b32_e64 v172, v175, v172, s[0:1]
	v_cndmask_b32_e64 v175, v167, v155, s[0:1]
	v_cndmask_b32_e64 v174, v174, v154, s[0:1]
	v_cndmask_b32_e32 v176, v179, v183, vcc
	v_pk_fma_f32 v[174:175], v[140:141], v[174:175], v[144:145]
	v_cndmask_b32_e64 v173, v173, v176, s[0:1]
	v_lshlrev_b32_e32 v178, 16, v226
	v_and_b32_e32 v179, 0xffff0000, v226
	v_pk_fma_f32 v[168:169], v[136:137], v[168:169], v[174:175]
	v_pk_fma_f32 v[172:173], v[142:143], v[172:173], v[146:147]
	v_pk_fma_f32 v[168:169], v[132:133], v[178:179], v[168:169]
	v_pk_fma_f32 v[170:171], v[138:139], v[170:171], v[172:173]
	v_pk_mul_f32 v[172:173], v[168:169], s[26:27] op_sel_hi:[1,0]
	v_pk_mul_f32 v[168:169], v[168:169], 0.5 op_sel_hi:[1,0]
	v_med3_f32 v172, v172, s71, v224
	v_med3_f32 v173, v173, s71, v224
	v_pk_mul_f32 v[174:175], v[172:173], v[172:173]
	v_mad_i64_i32 v[154:155], s[8:9], v194, s67, v[158:159]
	v_pk_fma_f32 v[178:179], v[174:175], s[28:29], v[148:149] op_sel_hi:[1,0,0] neg_lo:[1,0,0] neg_hi:[1,0,0]
	v_lshl_add_u64 v[176:177], v[154:155], 0, v[160:161]
	v_pk_fma_f32 v[178:179], v[174:175], v[178:179], s[34:35] op_sel_hi:[1,1,0]
	s_nop 0
	v_pk_fma_f32 v[178:179], v[174:175], v[178:179], s[36:37] op_sel_hi:[1,1,0]
	s_nop 0
	v_pk_fma_f32 v[178:179], v[174:175], v[178:179], s[38:39] op_sel_hi:[1,1,0]
	s_nop 0
	v_pk_fma_f32 v[178:179], v[174:175], v[178:179], s[40:41] op_sel_hi:[1,1,0]
	s_nop 0
	v_pk_fma_f32 v[178:179], v[174:175], v[178:179], s[42:43] op_sel_hi:[1,1,0]
	s_nop 0
	v_pk_fma_f32 v[174:175], v[174:175], v[178:179], s[44:45] op_sel_hi:[1,1,0]
	s_nop 0
	v_pk_mul_f32 v[172:173], v[172:173], v[174:175]
	s_nop 0
	v_pk_fma_f32 v[168:169], v[168:169], v[172:173], v[168:169]
; __device__ __forceinline__ unsigned cvt_pk_bf16(float lo, float hi) { unsigned r; asm volatile("v_cvt_pk_bf16_f32 %0, %1, %2" : "=v"(r) : "v"(lo), "v"(hi)); return r; }
;     static __device__ __forceinline__ void unpk4(const u32x2 w, float (&o)[4]) { o[0] = bf_lo(w.x); o[1] = bf_hi(w.x); o[2] = bf_lo(w.y); o[3] = bf_hi(w.y); }
;     template <int N> static __device__ __forceinline__ u32x2 dpp_prev(const u32x2 pv, const u32x2 cur) { u32x2 r; r.x = dpp_prev1<N>(pv.x, cur.x); r.y = dpp_prev1<N>(pv.y, cur.y); return r; }
;     static __device__ __forceinline__ void finish(const float (&g0)[4], const float (&g1)[4], const float (&g2)[4], const float (&w0)[4], const float (&w1)[4], const float (&w2)[4], const float (&bb)[4],
;                                                   const f32x4 v, float rs, bf16_t* dst) {
;         float h[4];
; #pragma unroll
;         for (int j = 0; j < 4; j += 2) {
;             const f32x2 gc = (f32x2){bb[j] + w0[j] * g2[j] + w1[j] * g1[j] + w2[j] * g0[j], bb[j + 1] + w0[j + 1] * g2[j + 1] + w1[j + 1] * g1[j + 1] + w2[j + 1] * g0[j + 1]};
;             const f32x2 ge = gelu_pk(gc); h[j] = ge.x * v[j] * rs; h[j + 1] = ge.y * v[j + 1] * rs; }
;         u32x2 w; w.x = cvt_pk_bf16(h[0], h[1]); w.y = cvt_pk_bf16(h[2], h[3]);
;         *(u32x2*)dst = w;
;     __device__ __forceinline__ void operator()(const f32x4 (&acc)[2][2][4][2], const Unit& u, int wr, int wc, int fr, int fq) const {
;     ...
;                 for (int m = mh; m < mh + 2; ++m) { const int row = row0 + m * 16; const float* cx = ctx + (size_t)((row - 32768) >> 3) * 2 * 2816 + col;
;                     c0[m] = *(const f32x4*)cx; c1[m] = *(const f32x4*)(cx + 2816); }
; #pragma unroll
;                 for (int m = mh; m < mh + 2; ++m) { const int row = row0 + m * 16; const u32x2 cur = gq[m];
;                     const u32x2 q1 = dpp_prev<1>(cur, cur), q2 = dpp_prev<2>(cur, cur);
;                     float g0[4], g1[4], g2[4]; unpk4(cur, g0); unpk4(q1, g1); unpk4(q2, g2);
; #pragma unroll
;                     for (int j = 0; j < 4; ++j) { const float x1 = c1[m][j], x0 = c0[m][j];
;                         if (i < 1) g1[j] = x1;
;                         if (i < 2) g2[j] = (i == 1) ? x1 : x0; }
;                     finish(g0, g1, g2, w0, w1, w2, bb, acc[0][bj][m][hv], rs8[0][m], H + (size_t)row * 2816 + col); }
	s_nop 0
	v_mul_f32_e32 v167, v120, v168
	v_mul_f32_e32 v168, v121, v169
	v_mul_f32_e32 v178, v186, v168
	v_lshlrev_b32_e32 v168, 16, v227
	v_and_b32_e32 v169, 0xffff0000, v227
	v_pk_fma_f32 v[168:169], v[134:135], v[168:169], v[170:171]
	v_mul_f32_e32 v167, v186, v167
	v_pk_mul_f32 v[170:171], v[168:169], s[26:27] op_sel_hi:[1,0]
	v_pk_mul_f32 v[168:169], v[168:169], 0.5 op_sel_hi:[1,0]
	v_med3_f32 v170, v170, s71, v224
	v_med3_f32 v171, v171, s71, v224
	v_pk_mul_f32 v[172:173], v[170:171], v[170:171]
	s_nop 0
	v_pk_fma_f32 v[174:175], v[172:173], s[28:29], v[148:149] op_sel_hi:[1,0,0] neg_lo:[1,0,0] neg_hi:[1,0,0]
	s_nop 0
	v_pk_fma_f32 v[174:175], v[172:173], v[174:175], s[34:35] op_sel_hi:[1,1,0]
	s_nop 0
	v_pk_fma_f32 v[174:175], v[172:173], v[174:175], s[36:37] op_sel_hi:[1,1,0]
	s_nop 0
	v_pk_fma_f32 v[174:175], v[172:173], v[174:175], s[38:39] op_sel_hi:[1,1,0]
	s_nop 0
	v_pk_fma_f32 v[174:175], v[172:173], v[174:175], s[40:41] op_sel_hi:[1,1,0]
	s_nop 0
	v_pk_fma_f32 v[174:175], v[172:173], v[174:175], s[42:43] op_sel_hi:[1,1,0]
	s_nop 0
	v_pk_fma_f32 v[172:173], v[172:173], v[174:175], s[44:45] op_sel_hi:[1,1,0]
	s_nop 0
	v_pk_mul_f32 v[170:171], v[170:171], v[172:173]
	s_nop 0
	v_pk_fma_f32 v[168:169], v[168:169], v[170:171], v[168:169]
	s_nop 0
	v_mul_f32_e32 v168, v122, v168
	v_mul_f32_e32 v170, v186, v168
	v_mul_f32_e32 v168, v123, v169
	v_mul_f32_e32 v169, v186, v168
	v_cvt_pk_bf16_f32 v168, v167, v178
	v_add_u32_e32 v167, 0xffff8020, v210
	v_cvt_pk_bf16_f32 v169, v170, v169
	v_ashrrev_i32_e32 v167, 3, v167
	global_store_dwordx2 v[176:177], v[168:169], off nt
	v_mad_i64_i32 v[168:169], s[8:9], v167, s70, v[156:157]
	v_add_co_u32_e64 v170, s[8:9], s41, v168
	s_nop 1
	v_addc_co_u32_e64 v171, s[8:9], 0, v169, s[8:9]
	global_load_dwordx4 v[170:173], v[170:171], off offset:3072
	s_nop 0
	global_load_dwordx4 v[174:177], v[168:169], off
	v_add_u32_e32 v168, 0xffff8030, v210
	v_ashrrev_i32_e32 v168, 3, v168
	v_mad_i64_i32 v[156:157], s[8:9], v168, s70, v[156:157]
	v_add_co_u32_e64 v182, s[8:9], s41, v156
	v_mov_b32_dpp v169, v164 row_ror:2 row_mask:0xf bank_mask:0xf bound_ctrl:1
	s_nop 0
	v_addc_co_u32_e64 v183, s[8:9], 0, v157, s[8:9]
	global_load_dwordx4 v[178:181], v[156:157], off
	global_load_dwordx4 v[212:215], v[182:183], off offset:3072
	v_mov_b32_dpp v156, v164 row_ror:1 row_mask:0xf bank_mask:0xf bound_ctrl:1
	v_mov_b32_dpp v157, v165 row_ror:1 row_mask:0xf bank_mask:0xf bound_ctrl:1
	v_mov_b32_dpp v169, v164 row_shr:2 row_mask:0xf bank_mask:0xf
	v_mov_b32_dpp v156, v164 row_shr:1 row_mask:0xf bank_mask:0xf
	v_mov_b32_dpp v157, v165 row_shr:1 row_mask:0xf bank_mask:0xf
	v_mov_b32_dpp v182, v165 row_ror:2 row_mask:0xf bank_mask:0xf bound_ctrl:1
	v_lshlrev_b32_e32 v185, 16, v156
	v_and_b32_e32 v156, 0xffff0000, v156
	v_lshlrev_b32_e32 v187, 16, v157
	v_and_b32_e32 v157, 0xffff0000, v157
	v_mov_b32_dpp v182, v165 row_shr:2 row_mask:0xf bank_mask:0xf
	v_lshlrev_b32_e32 v189, 16, v169
	v_and_b32_e32 v169, 0xffff0000, v169
	v_lshlrev_b32_e32 v191, 16, v182
	v_and_b32_e32 v193, 0xffff0000, v182
	s_waitcnt vmcnt(3)
	v_cndmask_b32_e64 v183, v156, v171, s[6:7]
	v_cndmask_b32_e64 v227, v157, v173, s[6:7]
	s_waitcnt vmcnt(2)
	v_cndmask_b32_e32 v156, v174, v170, vcc
	v_cndmask_b32_e32 v157, v175, v171, vcc
	v_cndmask_b32_e64 v182, v185, v170, s[6:7]
	v_cndmask_b32_e64 v226, v187, v172, s[6:7]
	v_cndmask_b32_e32 v170, v176, v172, vcc
	v_cndmask_b32_e32 v171, v177, v173, vcc
	v_cndmask_b32_e64 v173, v169, v157, s[0:1]
	v_cndmask_b32_e64 v172, v189, v156, s[0:1]
	v_pk_fma_f32 v[172:173], v[140:141], v[172:173], v[144:145]
	v_lshlrev_b32_e32 v176, 16, v164
	v_and_b32_e32 v177, 0xffff0000, v164
	v_pk_fma_f32 v[172:173], v[136:137], v[182:183], v[172:173]
	v_cndmask_b32_e64 v171, v193, v171, s[0:1]
	v_pk_fma_f32 v[172:173], v[132:133], v[176:177], v[172:173]
	v_cndmask_b32_e64 v170, v191, v170, s[0:1]
	v_pk_mul_f32 v[176:177], v[172:173], s[26:27] op_sel_hi:[1,0]
	v_pk_fma_f32 v[170:171], v[142:143], v[170:171], v[146:147]
	v_med3_f32 v176, v176, s71, v224
	v_med3_f32 v177, v177, s71, v224
	v_pk_mul_f32 v[182:183], v[176:177], v[176:177]
	v_pk_fma_f32 v[170:171], v[138:139], v[226:227], v[170:171]
	v_pk_fma_f32 v[226:227], v[182:183], s[28:29], v[148:149] op_sel_hi:[1,0,0] neg_lo:[1,0,0] neg_hi:[1,0,0]
	v_pk_mul_f32 v[172:173], v[172:173], 0.5 op_sel_hi:[1,0]
	v_pk_fma_f32 v[226:227], v[182:183], v[226:227], s[34:35] op_sel_hi:[1,1,0]
	v_mad_i64_i32 v[156:157], s[8:9], v192, s67, v[158:159]
	v_pk_fma_f32 v[226:227], v[182:183], v[226:227], s[36:37] op_sel_hi:[1,1,0]
	v_lshl_add_u64 v[174:175], v[156:157], 0, v[160:161]
	v_pk_fma_f32 v[226:227], v[182:183], v[226:227], s[38:39] op_sel_hi:[1,1,0]
	v_mad_i64_i32 v[158:159], s[8:9], v190, s67, v[158:159]
	v_pk_fma_f32 v[226:227], v[182:183], v[226:227], s[40:41] op_sel_hi:[1,1,0]
	v_lshl_add_u64 v[160:161], v[158:159], 0, v[160:161]
	v_pk_fma_f32 v[226:227], v[182:183], v[226:227], s[42:43] op_sel_hi:[1,1,0]
	s_nop 0
	v_pk_fma_f32 v[182:183], v[182:183], v[226:227], s[44:45] op_sel_hi:[1,1,0]
	s_nop 0
	v_pk_mul_f32 v[176:177], v[176:177], v[182:183]
	s_nop 0
	v_pk_fma_f32 v[172:173], v[172:173], v[176:177], v[172:173]
	s_nop 0
	v_mul_f32_e32 v164, v112, v172
	v_mul_f32_e32 v169, v184, v164
	v_mul_f32_e32 v164, v113, v173
	v_mul_f32_e32 v182, v184, v164
	v_lshlrev_b32_e32 v164, 16, v165
	v_and_b32_e32 v165, 0xffff0000, v165
	v_pk_fma_f32 v[164:165], v[134:135], v[164:165], v[170:171]
	s_nop 0
	v_pk_mul_f32 v[170:171], v[164:165], s[26:27] op_sel_hi:[1,0]
	v_pk_mul_f32 v[164:165], v[164:165], 0.5 op_sel_hi:[1,0]
	v_med3_f32 v170, v170, s71, v224
	v_med3_f32 v171, v171, s71, v224
	v_pk_mul_f32 v[172:173], v[170:171], v[170:171]
	s_nop 0
	v_pk_fma_f32 v[176:177], v[172:173], s[28:29], v[148:149] op_sel_hi:[1,0,0] neg_lo:[1,0,0] neg_hi:[1,0,0]
	s_nop 0
	v_pk_fma_f32 v[176:177], v[172:173], v[176:177], s[34:35] op_sel_hi:[1,1,0]
	s_nop 0
	v_pk_fma_f32 v[176:177], v[172:173], v[176:177], s[36:37] op_sel_hi:[1,1,0]
	s_nop 0
	v_pk_fma_f32 v[176:177], v[172:173], v[176:177], s[38:39] op_sel_hi:[1,1,0]
	s_nop 0
	v_pk_fma_f32 v[176:177], v[172:173], v[176:177], s[40:41] op_sel_hi:[1,1,0]
	s_nop 0
	v_pk_fma_f32 v[176:177], v[172:173], v[176:177], s[42:43] op_sel_hi:[1,1,0]
	s_nop 0
	v_pk_fma_f32 v[172:173], v[172:173], v[176:177], s[44:45] op_sel_hi:[1,1,0]
	s_waitcnt vmcnt(0)
;     static __device__ __forceinline__ void unpk4(const u32x2 w, float (&o)[4]) { o[0] = bf_lo(w.x); o[1] = bf_hi(w.x); o[2] = bf_lo(w.y); o[3] = bf_hi(w.y); }
;     template <int N> static __device__ __forceinline__ u32x2 dpp_prev(const u32x2 pv, const u32x2 cur) { u32x2 r; r.x = dpp_prev1<N>(pv.x, cur.x); r.y = dpp_prev1<N>(pv.y, cur.y); return r; }
;     __device__ __forceinline__ void operator()(const f32x4 (&acc)[2][2][4][2], const Unit& u, int wr, int wc, int fr, int fq) const {
;     ...
;             const int col = u.pn * BM + bj * HALF + wc * 32 + 8 * fq + 4 * hv;
;             float w0[4], w1[4], w2[4], bb[4];
;             ld4f(cw + col, w0); ld4f(cw + 2816 + col, w1); ld4f(cw + 2 * 2816 + col, w2); ld4f(cb + col, bb);
;             {
;                 const int i = fr & 7;
;                 u32x2 gq[4];
; #pragma unroll
;                 for (int m = 0; m < 4; ++m) { const int row = row0 + m * 16; gq[m] = *(const u32x2*)(G + (size_t)row * 2816 + col); }
;     ...
;                 for (int m = mh; m < mh + 2; ++m) { const int row = row0 + m * 16; const u32x2 cur = gq[m];
;                     const u32x2 q1 = dpp_prev<1>(cur, cur), q2 = dpp_prev<2>(cur, cur);
;                     float g0[4], g1[4], g2[4]; unpk4(cur, g0); unpk4(q1, g1); unpk4(q2, g2);
; #pragma unroll
;                     for (int j = 0; j < 4; ++j) { const float x1 = c1[m][j], x0 = c0[m][j];
;                         if (i < 1) g1[j] = x1;
;                         if (i < 2) g2[j] = (i == 1) ? x1 : x0; }
;                     finish(g0, g1, g2, w0, w1, w2, bb, acc[0][bj][m][hv], rs8[0][m], H + (size_t)row * 2816 + col); }
	v_cndmask_b32_e32 v177, v178, v212, vcc
	v_pk_mul_f32 v[170:171], v[170:171], v[172:173]
	v_cndmask_b32_e32 v178, v179, v213, vcc
	v_pk_fma_f32 v[164:165], v[164:165], v[170:171], v[164:165]
	s_nop 0
	v_mul_f32_e32 v164, v114, v164
	v_mul_f32_e32 v170, v184, v164
	v_mul_f32_e32 v164, v115, v165
	v_mul_f32_e32 v165, v184, v164
	v_cvt_pk_bf16_f32 v164, v169, v182
	v_cvt_pk_bf16_f32 v165, v170, v165
	global_store_dwordx2 v[174:175], v[164:165], off nt
	v_mov_b32_dpp v169, v162 row_ror:2 row_mask:0xf bank_mask:0xf bound_ctrl:1
	v_mov_b32_dpp v165, v163 row_ror:1 row_mask:0xf bank_mask:0xf bound_ctrl:1
	v_mov_b32_dpp v170, v163 row_ror:2 row_mask:0xf bank_mask:0xf bound_ctrl:1
	v_mov_b32_dpp v164, v162 row_ror:1 row_mask:0xf bank_mask:0xf bound_ctrl:1
	v_mov_b32_dpp v165, v163 row_shr:1 row_mask:0xf bank_mask:0xf
	v_mov_b32_dpp v169, v162 row_shr:2 row_mask:0xf bank_mask:0xf
	v_mov_b32_dpp v170, v163 row_shr:2 row_mask:0xf bank_mask:0xf
	v_lshlrev_b32_e32 v172, 16, v165
	v_mov_b32_dpp v164, v162 row_shr:1 row_mask:0xf bank_mask:0xf
	v_lshlrev_b32_e32 v174, 16, v169
	v_and_b32_e32 v169, 0xffff0000, v169
	v_lshlrev_b32_e32 v175, 16, v170
	v_and_b32_e32 v176, 0xffff0000, v170
	v_cndmask_b32_e64 v170, v172, v214, s[6:7]
	v_cndmask_b32_e32 v172, v180, v214, vcc
	v_lshlrev_b32_e32 v171, 16, v164
	v_and_b32_e32 v164, 0xffff0000, v164
	v_and_b32_e32 v173, 0xffff0000, v165
	v_cndmask_b32_e64 v172, v175, v172, s[0:1]
	v_cndmask_b32_e64 v175, v169, v178, s[0:1]
	v_cndmask_b32_e64 v174, v174, v177, s[0:1]
	v_cndmask_b32_e64 v165, v164, v213, s[6:7]
	v_cndmask_b32_e64 v164, v171, v212, s[6:7]
	v_cndmask_b32_e64 v171, v173, v215, s[6:7]
	v_cndmask_b32_e32 v173, v181, v215, vcc
	v_pk_fma_f32 v[140:141], v[140:141], v[174:175], v[144:145]
	v_cndmask_b32_e64 v173, v176, v173, s[0:1]
	v_lshlrev_b32_e32 v176, 16, v162
	v_and_b32_e32 v177, 0xffff0000, v162
	v_pk_fma_f32 v[136:137], v[136:137], v[164:165], v[140:141]
	v_pk_fma_f32 v[142:143], v[142:143], v[172:173], v[146:147]
	v_pk_fma_f32 v[132:133], v[132:133], v[176:177], v[136:137]
	v_pk_fma_f32 v[138:139], v[138:139], v[170:171], v[142:143]
	v_pk_mul_f32 v[136:137], v[132:133], s[26:27] op_sel_hi:[1,0]
	v_pk_mul_f32 v[132:133], v[132:133], 0.5 op_sel_hi:[1,0]
	v_med3_f32 v136, v136, s71, v224
	v_med3_f32 v137, v137, s71, v224
	v_pk_mul_f32 v[140:141], v[136:137], v[136:137]
	s_nop 0
	v_pk_fma_f32 v[142:143], v[140:141], s[28:29], v[148:149] op_sel_hi:[1,0,0] neg_lo:[1,0,0] neg_hi:[1,0,0]
	s_nop 0
	v_pk_fma_f32 v[142:143], v[140:141], v[142:143], s[34:35] op_sel_hi:[1,1,0]
	s_nop 0
	v_pk_fma_f32 v[142:143], v[140:141], v[142:143], s[36:37] op_sel_hi:[1,1,0]
	s_nop 0
	v_pk_fma_f32 v[142:143], v[140:141], v[142:143], s[38:39] op_sel_hi:[1,1,0]
	s_nop 0
	v_pk_fma_f32 v[142:143], v[140:141], v[142:143], s[40:41] op_sel_hi:[1,1,0]
	s_nop 0
	v_pk_fma_f32 v[142:143], v[140:141], v[142:143], s[42:43] op_sel_hi:[1,1,0]
	s_nop 0
	v_pk_fma_f32 v[140:141], v[140:141], v[142:143], s[44:45] op_sel_hi:[1,1,0]
	s_nop 0
	v_pk_mul_f32 v[136:137], v[136:137], v[140:141]
	s_nop 0
	v_pk_fma_f32 v[132:133], v[132:133], v[136:137], v[132:133]
	s_nop 0
	v_mul_f32_e32 v132, v104, v132
	v_mul_f32_e32 v140, v2, v132
	v_mul_f32_e32 v132, v105, v133
	v_mul_f32_e32 v141, v2, v132
	v_lshlrev_b32_e32 v132, 16, v163
	v_and_b32_e32 v133, 0xffff0000, v163
	v_pk_fma_f32 v[132:133], v[134:135], v[132:133], v[138:139]
	s_nop 0
	v_pk_mul_f32 v[134:135], v[132:133], s[26:27] op_sel_hi:[1,0]
	v_pk_mul_f32 v[132:133], v[132:133], 0.5 op_sel_hi:[1,0]
	v_med3_f32 v134, v134, s71, v224
	v_med3_f32 v135, v135, s71, v224
	v_pk_mul_f32 v[136:137], v[134:135], v[134:135]
	s_nop 0
	v_pk_fma_f32 v[138:139], v[136:137], s[28:29], v[148:149] op_sel_hi:[1,0,0] neg_lo:[1,0,0] neg_hi:[1,0,0]
	s_nop 0
	v_pk_fma_f32 v[138:139], v[136:137], v[138:139], s[34:35] op_sel_hi:[1,1,0]
	s_nop 0
	v_pk_fma_f32 v[138:139], v[136:137], v[138:139], s[36:37] op_sel_hi:[1,1,0]
	s_nop 0
	v_pk_fma_f32 v[138:139], v[136:137], v[138:139], s[38:39] op_sel_hi:[1,1,0]
	s_nop 0
	v_pk_fma_f32 v[138:139], v[136:137], v[138:139], s[40:41] op_sel_hi:[1,1,0]
	s_nop 0
	v_pk_fma_f32 v[138:139], v[136:137], v[138:139], s[42:43] op_sel_hi:[1,1,0]
	s_nop 0
	v_pk_fma_f32 v[136:137], v[136:137], v[138:139], s[44:45] op_sel_hi:[1,1,0]
	s_nop 0
	v_pk_mul_f32 v[134:135], v[134:135], v[136:137]
	s_nop 0
	v_pk_fma_f32 v[132:133], v[132:133], v[134:135], v[132:133]
	s_nop 0
	v_mul_f32_e32 v132, v106, v132
	v_mul_f32_e32 v134, v2, v132
	v_mul_f32_e32 v132, v107, v133
	v_mul_f32_e32 v133, v2, v132
	v_cvt_pk_bf16_f32 v132, v140, v141
	v_cvt_pk_bf16_f32 v133, v134, v133
	global_store_dwordx2 v[160:161], v[132:133], off nt
	v_add_u32_e32 v132, 4, v150
	v_ashrrev_i32_e32 v133, 31, v132
	v_lshlrev_b64 v[162:163], 1, v[132:133]
	v_lshl_add_u64 v[160:161], s[56:57], 0, v[162:163]
	v_lshlrev_b64 v[132:133], 2, v[132:133]
	v_mad_i64_i32 v[134:135], s[8:9], v210, s67, v[160:161]
	v_lshl_add_u64 v[226:227], s[16:17], 0, v[132:133]
	global_load_dwordx2 v[182:183], v[134:135], off
	v_mad_i64_i32 v[134:135], s[8:9], v151, s70, v[226:227]
	v_add_co_u32_e64 v136, s[8:9], s41, v134
	s_waitcnt vmcnt(0)
;     static __device__ __forceinline__ void unpk4(const u32x2 w, float (&o)[4]) { o[0] = bf_lo(w.x); o[1] = bf_hi(w.x); o[2] = bf_lo(w.y); o[3] = bf_hi(w.y); }
;     template <int N> static __device__ __forceinline__ u32x2 dpp_prev(const u32x2 pv, const u32x2 cur) { u32x2 r; r.x = dpp_prev1<N>(pv.x, cur.x); r.y = dpp_prev1<N>(pv.y, cur.y); return r; }
;     __device__ __forceinline__ void operator()(const f32x4 (&acc)[2][2][4][2], const Unit& u, int wr, int wc, int fr, int fq) const {
;     ...
;             const int col = u.pn * BM + bj * HALF + wc * 32 + 8 * fq + 4 * hv;
;             float w0[4], w1[4], w2[4], bb[4];
;             ld4f(cw + col, w0); ld4f(cw + 2816 + col, w1); ld4f(cw + 2 * 2816 + col, w2); ld4f(cb + col, bb);
;             {
;                 const int i = fr & 7;
;                 u32x2 gq[4];
; #pragma unroll
;                 for (int m = 0; m < 4; ++m) { const int row = row0 + m * 16; gq[m] = *(const u32x2*)(G + (size_t)row * 2816 + col); }
; #pragma unroll
;                 for (int mh = 0; mh < 4; mh += 2) {
;                 f32x4 c0[4], c1[4];
; #pragma unroll
;                 for (int m = mh; m < mh + 2; ++m) { const int row = row0 + m * 16; const float* cx = ctx + (size_t)((row - 32768) >> 3) * 2 * 2816 + col;
;                     c0[m] = *(const f32x4*)cx; c1[m] = *(const f32x4*)(cx + 2816); }
; #pragma unroll
;                 for (int m = mh; m < mh + 2; ++m) { const int row = row0 + m * 16; const u32x2 cur = gq[m];
;                     const u32x2 q1 = dpp_prev<1>(cur, cur), q2 = dpp_prev<2>(cur, cur);
;                     float g0[4], g1[4], g2[4]; unpk4(cur, g0); unpk4(q1, g1); unpk4(q2, g2);
; #pragma unroll
;                     for (int j = 0; j < 4; ++j) { const float x1 = c1[m][j], x0 = c0[m][j];
;                         if (i < 1) g1[j] = x1;
;                         if (i < 2) g2[j] = (i == 1) ? x1 : x0; }
;                     finish(g0, g1, g2, w0, w1, w2, bb, acc[0][bj][m][hv], rs8[0][m], H + (size_t)row * 2816 + col); }
	v_mov_b32_dpp v169, v182 row_ror:1 row_mask:0xf bank_mask:0xf bound_ctrl:1
	v_addc_co_u32_e64 v137, s[8:9], 0, v135, s[8:9]
	global_load_dwordx4 v[170:173], v[136:137], off offset:3072
	global_load_dwordx4 v[174:177], v[134:135], off
	v_lshl_add_u64 v[134:135], s[12:13], 0, v[132:133]
	global_load_dwordx4 v[140:143], v[134:135], off
	v_lshl_add_u64 v[134:135], s[14:15], 0, v[132:133]
	global_load_dwordx4 v[144:147], v[134:135], off
	v_lshl_add_u64 v[134:135], s[18:19], 0, v[132:133]
	global_load_dwordx4 v[136:139], v[134:135], off
	v_lshl_add_u64 v[132:133], s[20:21], 0, v[132:133]
	global_load_dwordx4 v[132:135], v[132:133], off
	v_mad_i64_i32 v[164:165], s[8:9], v194, s67, v[160:161]
	v_mad_i64_i32 v[178:179], s[8:9], v192, s67, v[160:161]
	v_mad_i64_i32 v[160:161], s[8:9], v190, s67, v[160:161]
	global_load_dwordx2 v[228:229], v[164:165], off
	s_nop 0
	global_load_dwordx2 v[164:165], v[178:179], off
	s_nop 0
	global_load_dwordx2 v[160:161], v[160:161], off
	v_mad_i64_i32 v[178:179], s[8:9], v166, s70, v[226:227]
	v_add_co_u32_e64 v212, s[8:9], s41, v178
	v_mov_b32_dpp v169, v182 row_shr:1 row_mask:0xf bank_mask:0xf
	s_nop 0
	v_addc_co_u32_e64 v213, s[8:9], 0, v179, s[8:9]
	global_load_dwordx4 v[178:181], v[178:179], off
	s_nop 0
	global_load_dwordx4 v[212:215], v[212:213], off offset:3072
	v_mov_b32_dpp v185, v183 row_ror:1 row_mask:0xf bank_mask:0xf bound_ctrl:1
	v_mov_b32_dpp v187, v182 row_ror:2 row_mask:0xf bank_mask:0xf bound_ctrl:1
	v_lshlrev_b32_e32 v191, 16, v169
	v_mov_b32_dpp v185, v183 row_shr:1 row_mask:0xf bank_mask:0xf
	v_mov_b32_dpp v187, v182 row_shr:2 row_mask:0xf bank_mask:0xf
	v_and_b32_e32 v169, 0xffff0000, v169
	v_lshlrev_b32_e32 v193, 16, v185
	v_and_b32_e32 v185, 0xffff0000, v185
	v_lshlrev_b32_e32 v195, 16, v187
	v_and_b32_e32 v187, 0xffff0000, v187
	v_mov_b32_dpp v189, v183 row_ror:2 row_mask:0xf bank_mask:0xf bound_ctrl:1
	s_waitcnt vmcnt(10)
	v_cndmask_b32_e64 v231, v169, v171, s[6:7]
	s_waitcnt vmcnt(9)
	v_cndmask_b32_e32 v169, v174, v170, vcc
	v_cndmask_b32_e32 v174, v175, v171, vcc
	v_cndmask_b32_e64 v230, v191, v170, s[6:7]
	v_cndmask_b32_e64 v233, v185, v173, s[6:7]
	v_cndmask_b32_e64 v232, v193, v172, s[6:7]
	v_cndmask_b32_e32 v170, v176, v172, vcc
	v_cndmask_b32_e32 v171, v177, v173, vcc
	v_cndmask_b32_e64 v173, v187, v174, s[0:1]
	v_cndmask_b32_e64 v172, v195, v169, s[0:1]
	s_waitcnt vmcnt(7)
	v_pk_fma_f32 v[172:173], v[140:141], v[172:173], v[144:145]
	v_lshlrev_b32_e32 v176, 16, v182
	v_and_b32_e32 v177, 0xffff0000, v182
	s_waitcnt vmcnt(6)
	v_pk_fma_f32 v[172:173], v[136:137], v[230:231], v[172:173]
	v_mov_b32_dpp v189, v183 row_shr:2 row_mask:0xf bank_mask:0xf
	s_waitcnt vmcnt(5)
	v_pk_fma_f32 v[172:173], v[132:133], v[176:177], v[172:173]
	v_lshlrev_b32_e32 v211, 16, v189
	v_and_b32_e32 v189, 0xffff0000, v189
	v_pk_mul_f32 v[176:177], v[172:173], s[26:27] op_sel_hi:[1,0]
	v_cndmask_b32_e64 v171, v189, v171, s[0:1]
	v_cndmask_b32_e64 v170, v211, v170, s[0:1]
	v_med3_f32 v176, v176, s71, v224
	v_med3_f32 v177, v177, s71, v224
	v_pk_fma_f32 v[170:171], v[142:143], v[170:171], v[146:147]
	v_pk_mul_f32 v[230:231], v[176:177], v[176:177]
	v_pk_fma_f32 v[170:171], v[138:139], v[232:233], v[170:171]
	v_pk_fma_f32 v[232:233], v[230:231], s[28:29], v[148:149] op_sel_hi:[1,0,0] neg_lo:[1,0,0] neg_hi:[1,0,0]
	v_pk_mul_f32 v[172:173], v[172:173], 0.5 op_sel_hi:[1,0]
	v_pk_fma_f32 v[232:233], v[230:231], v[232:233], s[34:35] op_sel_hi:[1,1,0]
	v_lshl_add_u64 v[174:175], v[152:153], 0, v[162:163]
	v_pk_fma_f32 v[232:233], v[230:231], v[232:233], s[36:37] op_sel_hi:[1,1,0]
	s_nop 0
	v_pk_fma_f32 v[232:233], v[230:231], v[232:233], s[38:39] op_sel_hi:[1,1,0]
	s_nop 0
	v_pk_fma_f32 v[232:233], v[230:231], v[232:233], s[40:41] op_sel_hi:[1,1,0]
	s_nop 0
	v_pk_fma_f32 v[232:233], v[230:231], v[232:233], s[42:43] op_sel_hi:[1,1,0]
	s_nop 0
	v_pk_fma_f32 v[230:231], v[230:231], v[232:233], s[44:45] op_sel_hi:[1,1,0]
	s_nop 0
	v_pk_mul_f32 v[176:177], v[176:177], v[230:231]
	s_nop 0
	v_pk_fma_f32 v[172:173], v[172:173], v[176:177], v[172:173]
	s_nop 0
	v_mul_f32_e32 v169, v124, v172
	v_mul_f32_e32 v172, v125, v173
	v_mul_f32_e32 v185, v188, v172
	v_lshlrev_b32_e32 v172, 16, v183
	v_and_b32_e32 v173, 0xffff0000, v183
	v_pk_fma_f32 v[170:171], v[134:135], v[172:173], v[170:171]
	v_mul_f32_e32 v169, v188, v169
	v_pk_mul_f32 v[172:173], v[170:171], s[26:27] op_sel_hi:[1,0]
	v_pk_mul_f32 v[170:171], v[170:171], 0.5 op_sel_hi:[1,0]
	v_med3_f32 v172, v172, s71, v224
	v_med3_f32 v173, v173, s71, v224
	v_pk_mul_f32 v[176:177], v[172:173], v[172:173]
	s_nop 0
	v_pk_fma_f32 v[182:183], v[176:177], s[28:29], v[148:149] op_sel_hi:[1,0,0] neg_lo:[1,0,0] neg_hi:[1,0,0]
	s_nop 0
	v_pk_fma_f32 v[182:183], v[176:177], v[182:183], s[34:35] op_sel_hi:[1,1,0]
	s_nop 0
	v_pk_fma_f32 v[182:183], v[176:177], v[182:183], s[36:37] op_sel_hi:[1,1,0]
	s_nop 0
	v_pk_fma_f32 v[182:183], v[176:177], v[182:183], s[38:39] op_sel_hi:[1,1,0]
	s_nop 0
	v_pk_fma_f32 v[182:183], v[176:177], v[182:183], s[40:41] op_sel_hi:[1,1,0]
	s_nop 0
	v_pk_fma_f32 v[182:183], v[176:177], v[182:183], s[42:43] op_sel_hi:[1,1,0]
	s_nop 0
	v_pk_fma_f32 v[176:177], v[176:177], v[182:183], s[44:45] op_sel_hi:[1,1,0]
	s_nop 0
	v_pk_mul_f32 v[172:173], v[172:173], v[176:177]
	s_nop 0
	v_pk_fma_f32 v[170:171], v[170:171], v[172:173], v[170:171]
	s_nop 0
	v_mul_f32_e32 v170, v126, v170
	v_mul_f32_e32 v172, v188, v170
	v_mul_f32_e32 v170, v127, v171
	v_mul_f32_e32 v171, v188, v170
	v_cvt_pk_bf16_f32 v170, v169, v185
	v_cvt_pk_bf16_f32 v171, v172, v171
	s_waitcnt vmcnt(4)
;     static __device__ __forceinline__ void unpk4(const u32x2 w, float (&o)[4]) { o[0] = bf_lo(w.x); o[1] = bf_hi(w.x); o[2] = bf_lo(w.y); o[3] = bf_hi(w.y); }
;     template <int N> static __device__ __forceinline__ u32x2 dpp_prev(const u32x2 pv, const u32x2 cur) { u32x2 r; r.x = dpp_prev1<N>(pv.x, cur.x); r.y = dpp_prev1<N>(pv.y, cur.y); return r; }
;     __device__ __forceinline__ void operator()(const f32x4 (&acc)[2][2][4][2], const Unit& u, int wr, int wc, int fr, int fq) const {
;     ...
;                 for (int m = mh; m < mh + 2; ++m) { const int row = row0 + m * 16; const float* cx = ctx + (size_t)((row - 32768) >> 3) * 2 * 2816 + col;
;                     c0[m] = *(const f32x4*)cx; c1[m] = *(const f32x4*)(cx + 2816); }
;     ...
;                 for (int m = mh; m < mh + 2; ++m) { const int row = row0 + m * 16; const u32x2 cur = gq[m];
;                     const u32x2 q1 = dpp_prev<1>(cur, cur), q2 = dpp_prev<2>(cur, cur);
;                     float g0[4], g1[4], g2[4]; unpk4(cur, g0); unpk4(q1, g1); unpk4(q2, g2);
; #pragma unroll
;                     for (int j = 0; j < 4; ++j) { const float x1 = c1[m][j], x0 = c0[m][j];
;                         if (i < 1) g1[j] = x1;
;                         if (i < 2) g2[j] = (i == 1) ? x1 : x0; }
;                     finish(g0, g1, g2, w0, w1, w2, bb, acc[0][bj][m][hv], rs8[0][m], H + (size_t)row * 2816 + col); }
	v_mov_b32_dpp v169, v228 row_ror:1 row_mask:0xf bank_mask:0xf bound_ctrl:1
	global_store_dwordx2 v[174:175], v[170:171], off nt
	v_mov_b32_dpp v171, v228 row_ror:2 row_mask:0xf bank_mask:0xf bound_ctrl:1
	v_mov_b32_dpp v169, v228 row_shr:1 row_mask:0xf bank_mask:0xf
	v_mov_b32_dpp v170, v229 row_ror:1 row_mask:0xf bank_mask:0xf bound_ctrl:1
	v_mov_b32_dpp v171, v228 row_shr:2 row_mask:0xf bank_mask:0xf
	v_lshlrev_b32_e32 v173, 16, v169
	v_and_b32_e32 v169, 0xffff0000, v169
	v_mov_b32_dpp v170, v229 row_shr:1 row_mask:0xf bank_mask:0xf
	v_mov_b32_dpp v172, v229 row_ror:2 row_mask:0xf bank_mask:0xf bound_ctrl:1
	v_lshlrev_b32_e32 v176, 16, v171
	v_and_b32_e32 v177, 0xffff0000, v171
	s_waitcnt vmcnt(1)
	v_cndmask_b32_e64 v171, v169, v213, s[6:7]
	v_cndmask_b32_e32 v169, v178, v212, vcc
	v_cndmask_b32_e32 v178, v179, v213, vcc
	v_mov_b32_dpp v172, v229 row_shr:2 row_mask:0xf bank_mask:0xf
	v_lshlrev_b32_e32 v174, 16, v170
	v_and_b32_e32 v175, 0xffff0000, v170
	v_cndmask_b32_e64 v177, v177, v178, s[0:1]
	v_cndmask_b32_e64 v176, v176, v169, s[0:1]
	v_lshlrev_b32_e32 v182, 16, v172
	v_and_b32_e32 v183, 0xffff0000, v172
	v_cndmask_b32_e64 v170, v173, v212, s[6:7]
	v_cndmask_b32_e64 v173, v175, v215, s[6:7]
	v_cndmask_b32_e64 v172, v174, v214, s[6:7]
	v_cndmask_b32_e32 v174, v180, v214, vcc
	v_cndmask_b32_e32 v175, v181, v215, vcc
	v_pk_fma_f32 v[176:177], v[140:141], v[176:177], v[144:145]
	v_cndmask_b32_e64 v175, v183, v175, s[0:1]
	v_cndmask_b32_e64 v174, v182, v174, s[0:1]
	v_lshlrev_b32_e32 v180, 16, v228
	v_and_b32_e32 v181, 0xffff0000, v228
	v_pk_fma_f32 v[170:171], v[136:137], v[170:171], v[176:177]
	v_pk_fma_f32 v[174:175], v[142:143], v[174:175], v[146:147]
	v_pk_fma_f32 v[170:171], v[132:133], v[180:181], v[170:171]
	v_pk_fma_f32 v[172:173], v[138:139], v[172:173], v[174:175]
	v_pk_mul_f32 v[174:175], v[170:171], s[26:27] op_sel_hi:[1,0]
	v_pk_mul_f32 v[170:171], v[170:171], 0.5 op_sel_hi:[1,0]
	v_med3_f32 v174, v174, s71, v224
	v_med3_f32 v175, v175, s71, v224
	v_pk_mul_f32 v[176:177], v[174:175], v[174:175]
	v_lshl_add_u64 v[178:179], v[154:155], 0, v[162:163]
	v_pk_fma_f32 v[180:181], v[176:177], s[28:29], v[148:149] op_sel_hi:[1,0,0] neg_lo:[1,0,0] neg_hi:[1,0,0]
	v_mov_b32_dpp v185, v165 row_ror:2 row_mask:0xf bank_mask:0xf bound_ctrl:1
	v_pk_fma_f32 v[180:181], v[176:177], v[180:181], s[34:35] op_sel_hi:[1,1,0]
	s_nop 0
	v_pk_fma_f32 v[180:181], v[176:177], v[180:181], s[36:37] op_sel_hi:[1,1,0]
	v_mov_b32_dpp v185, v165 row_shr:2 row_mask:0xf bank_mask:0xf
	v_pk_fma_f32 v[180:181], v[176:177], v[180:181], s[38:39] op_sel_hi:[1,1,0]
	v_lshlrev_b32_e32 v211, 16, v185
	v_pk_fma_f32 v[180:181], v[176:177], v[180:181], s[40:41] op_sel_hi:[1,1,0]
	v_and_b32_e32 v185, 0xffff0000, v185
	v_pk_fma_f32 v[180:181], v[176:177], v[180:181], s[42:43] op_sel_hi:[1,1,0]
	s_nop 0
	v_pk_fma_f32 v[176:177], v[176:177], v[180:181], s[44:45] op_sel_hi:[1,1,0]
	s_nop 0
	v_pk_mul_f32 v[174:175], v[174:175], v[176:177]
	s_nop 0
	v_pk_fma_f32 v[170:171], v[170:171], v[174:175], v[170:171]
	s_nop 0
	v_mul_f32_e32 v169, v116, v170
	v_mul_f32_e32 v170, v117, v171
	v_mul_f32_e32 v180, v186, v170
	v_lshlrev_b32_e32 v170, 16, v229
	v_and_b32_e32 v171, 0xffff0000, v229
	v_pk_fma_f32 v[170:171], v[134:135], v[170:171], v[172:173]
	v_mul_f32_e32 v169, v186, v169
	v_pk_mul_f32 v[172:173], v[170:171], s[26:27] op_sel_hi:[1,0]
	v_pk_mul_f32 v[170:171], v[170:171], 0.5 op_sel_hi:[1,0]
	v_med3_f32 v172, v172, s71, v224
	v_med3_f32 v173, v173, s71, v224
	v_pk_mul_f32 v[174:175], v[172:173], v[172:173]
	s_nop 0
	v_pk_fma_f32 v[176:177], v[174:175], s[28:29], v[148:149] op_sel_hi:[1,0,0] neg_lo:[1,0,0] neg_hi:[1,0,0]
	s_nop 0
	v_pk_fma_f32 v[176:177], v[174:175], v[176:177], s[34:35] op_sel_hi:[1,1,0]
	s_nop 0
	v_pk_fma_f32 v[176:177], v[174:175], v[176:177], s[36:37] op_sel_hi:[1,1,0]
	s_nop 0
	v_pk_fma_f32 v[176:177], v[174:175], v[176:177], s[38:39] op_sel_hi:[1,1,0]
	s_nop 0
	v_pk_fma_f32 v[176:177], v[174:175], v[176:177], s[40:41] op_sel_hi:[1,1,0]
	s_nop 0
	v_pk_fma_f32 v[176:177], v[174:175], v[176:177], s[42:43] op_sel_hi:[1,1,0]
	s_nop 0
	v_pk_fma_f32 v[174:175], v[174:175], v[176:177], s[44:45] op_sel_hi:[1,1,0]
	s_nop 0
	v_pk_mul_f32 v[172:173], v[172:173], v[174:175]
	v_mad_i64_i32 v[174:175], s[8:9], v167, s70, v[226:227]
	v_pk_fma_f32 v[170:171], v[170:171], v[172:173], v[170:171]
	s_nop 0
	v_mul_f32_e32 v170, v118, v170
	v_mul_f32_e32 v172, v186, v170
	v_mul_f32_e32 v170, v119, v171
	v_mul_f32_e32 v171, v186, v170
	v_cvt_pk_bf16_f32 v170, v169, v180
	v_cvt_pk_bf16_f32 v171, v172, v171
	global_store_dwordx2 v[178:179], v[170:171], off nt
	v_add_co_u32_e64 v170, s[8:9], s41, v174
	v_mov_b32_dpp v169, v164 row_ror:1 row_mask:0xf bank_mask:0xf bound_ctrl:1
	s_nop 0
	v_addc_co_u32_e64 v171, s[8:9], 0, v175, s[8:9]
	global_load_dwordx4 v[170:173], v[170:171], off offset:3072
	s_nop 0
	global_load_dwordx4 v[174:177], v[174:175], off
	v_mad_i64_i32 v[178:179], s[8:9], v168, s70, v[226:227]
	v_add_co_u32_e64 v182, s[8:9], s41, v178
	v_mov_b32_dpp v169, v164 row_shr:1 row_mask:0xf bank_mask:0xf
	s_nop 0
	v_addc_co_u32_e64 v183, s[8:9], 0, v179, s[8:9]
	global_load_dwordx4 v[178:181], v[178:179], off
	s_nop 0
	global_load_dwordx4 v[212:215], v[182:183], off offset:3072
	v_mov_b32_dpp v182, v165 row_ror:1 row_mask:0xf bank_mask:0xf bound_ctrl:1
	v_mov_b32_dpp v183, v164 row_ror:2 row_mask:0xf bank_mask:0xf bound_ctrl:1
	v_lshlrev_b32_e32 v187, 16, v169
	v_mov_b32_dpp v182, v165 row_shr:1 row_mask:0xf bank_mask:0xf
	v_mov_b32_dpp v183, v164 row_shr:2 row_mask:0xf bank_mask:0xf
	v_and_b32_e32 v169, 0xffff0000, v169
	v_lshlrev_b32_e32 v189, 16, v182
	v_and_b32_e32 v191, 0xffff0000, v182
	v_lshlrev_b32_e32 v193, 16, v183
	v_and_b32_e32 v195, 0xffff0000, v183
	s_waitcnt vmcnt(3)
; __device__ __forceinline__ unsigned cvt_pk_bf16(float lo, float hi) { unsigned r; asm volatile("v_cvt_pk_bf16_f32 %0, %1, %2" : "=v"(r) : "v"(lo), "v"(hi)); return r; }
;     static __device__ __forceinline__ void unpk4(const u32x2 w, float (&o)[4]) { o[0] = bf_lo(w.x); o[1] = bf_hi(w.x); o[2] = bf_lo(w.y); o[3] = bf_hi(w.y); }
;     template <int N> static __device__ __forceinline__ u32x2 dpp_prev(const u32x2 pv, const u32x2 cur) { u32x2 r; r.x = dpp_prev1<N>(pv.x, cur.x); r.y = dpp_prev1<N>(pv.y, cur.y); return r; }
;     static __device__ __forceinline__ void finish(const float (&g0)[4], const float (&g1)[4], const float (&g2)[4], const float (&w0)[4], const float (&w1)[4], const float (&w2)[4], const float (&bb)[4],
;                                                   const f32x4 v, float rs, bf16_t* dst) {
;         float h[4];
; #pragma unroll
;         for (int j = 0; j < 4; j += 2) {
;             const f32x2 gc = (f32x2){bb[j] + w0[j] * g2[j] + w1[j] * g1[j] + w2[j] * g0[j], bb[j + 1] + w0[j + 1] * g2[j + 1] + w1[j + 1] * g1[j + 1] + w2[j + 1] * g0[j + 1]};
;             const f32x2 ge = gelu_pk(gc); h[j] = ge.x * v[j] * rs; h[j + 1] = ge.y * v[j + 1] * rs; }
;         u32x2 w; w.x = cvt_pk_bf16(h[0], h[1]); w.y = cvt_pk_bf16(h[2], h[3]);
;         *(u32x2*)dst = w;
;     __device__ __forceinline__ void operator()(const f32x4 (&acc)[2][2][4][2], const Unit& u, int wr, int wc, int fr, int fq) const {
;     ...
;                 for (int m = mh; m < mh + 2; ++m) { const int row = row0 + m * 16; const u32x2 cur = gq[m];
;                     const u32x2 q1 = dpp_prev<1>(cur, cur), q2 = dpp_prev<2>(cur, cur);
;                     float g0[4], g1[4], g2[4]; unpk4(cur, g0); unpk4(q1, g1); unpk4(q2, g2);
; #pragma unroll
;                     for (int j = 0; j < 4; ++j) { const float x1 = c1[m][j], x0 = c0[m][j];
;                         if (i < 1) g1[j] = x1;
;                         if (i < 2) g2[j] = (i == 1) ? x1 : x0; }
;                     finish(g0, g1, g2, w0, w1, w2, bb, acc[0][bj][m][hv], rs8[0][m], H + (size_t)row * 2816 + col); }
	v_cndmask_b32_e64 v183, v169, v171, s[6:7]
	s_waitcnt vmcnt(2)
	v_cndmask_b32_e32 v169, v174, v170, vcc
	v_cndmask_b32_e32 v174, v175, v171, vcc
	v_cndmask_b32_e64 v182, v187, v170, s[6:7]
	v_cndmask_b32_e64 v227, v191, v173, s[6:7]
	v_cndmask_b32_e64 v226, v189, v172, s[6:7]
	v_cndmask_b32_e32 v170, v176, v172, vcc
	v_cndmask_b32_e32 v171, v177, v173, vcc
	v_cndmask_b32_e64 v173, v195, v174, s[0:1]
	v_cndmask_b32_e64 v172, v193, v169, s[0:1]
	v_pk_fma_f32 v[172:173], v[140:141], v[172:173], v[144:145]
	v_lshlrev_b32_e32 v176, 16, v164
	v_and_b32_e32 v177, 0xffff0000, v164
	v_pk_fma_f32 v[172:173], v[136:137], v[182:183], v[172:173]
	v_cndmask_b32_e64 v171, v185, v171, s[0:1]
	v_pk_fma_f32 v[172:173], v[132:133], v[176:177], v[172:173]
	v_cndmask_b32_e64 v170, v211, v170, s[0:1]
	v_pk_mul_f32 v[176:177], v[172:173], s[26:27] op_sel_hi:[1,0]
	v_pk_fma_f32 v[170:171], v[142:143], v[170:171], v[146:147]
	v_med3_f32 v176, v176, s71, v224
	v_med3_f32 v177, v177, s71, v224
	v_pk_mul_f32 v[182:183], v[176:177], v[176:177]
	v_pk_fma_f32 v[170:171], v[138:139], v[226:227], v[170:171]
	v_pk_fma_f32 v[226:227], v[182:183], s[28:29], v[148:149] op_sel_hi:[1,0,0] neg_lo:[1,0,0] neg_hi:[1,0,0]
	v_pk_mul_f32 v[172:173], v[172:173], 0.5 op_sel_hi:[1,0]
	v_pk_fma_f32 v[226:227], v[182:183], v[226:227], s[34:35] op_sel_hi:[1,1,0]
	v_lshl_add_u64 v[174:175], v[156:157], 0, v[162:163]
	v_pk_fma_f32 v[226:227], v[182:183], v[226:227], s[36:37] op_sel_hi:[1,1,0]
	v_lshl_add_u64 v[162:163], v[158:159], 0, v[162:163]
	v_pk_fma_f32 v[226:227], v[182:183], v[226:227], s[38:39] op_sel_hi:[1,1,0]
	s_nop 0
	v_pk_fma_f32 v[226:227], v[182:183], v[226:227], s[40:41] op_sel_hi:[1,1,0]
	s_nop 0
	v_pk_fma_f32 v[226:227], v[182:183], v[226:227], s[42:43] op_sel_hi:[1,1,0]
	s_nop 0
	v_pk_fma_f32 v[182:183], v[182:183], v[226:227], s[44:45] op_sel_hi:[1,1,0]
	s_nop 0
	v_pk_mul_f32 v[176:177], v[176:177], v[182:183]
	s_nop 0
	v_pk_fma_f32 v[172:173], v[172:173], v[176:177], v[172:173]
	s_nop 0
	v_mul_f32_e32 v164, v108, v172
	v_mul_f32_e32 v169, v184, v164
	v_mul_f32_e32 v164, v109, v173
	v_mul_f32_e32 v182, v184, v164
	v_lshlrev_b32_e32 v164, 16, v165
	v_and_b32_e32 v165, 0xffff0000, v165
	v_pk_fma_f32 v[164:165], v[134:135], v[164:165], v[170:171]
	s_nop 0
	v_pk_mul_f32 v[170:171], v[164:165], s[26:27] op_sel_hi:[1,0]
	v_pk_mul_f32 v[164:165], v[164:165], 0.5 op_sel_hi:[1,0]
	v_med3_f32 v170, v170, s71, v224
	v_med3_f32 v171, v171, s71, v224
	v_pk_mul_f32 v[172:173], v[170:171], v[170:171]
	s_nop 0
	v_pk_fma_f32 v[176:177], v[172:173], s[28:29], v[148:149] op_sel_hi:[1,0,0] neg_lo:[1,0,0] neg_hi:[1,0,0]
	s_nop 0
	v_pk_fma_f32 v[176:177], v[172:173], v[176:177], s[34:35] op_sel_hi:[1,1,0]
	s_nop 0
	v_pk_fma_f32 v[176:177], v[172:173], v[176:177], s[36:37] op_sel_hi:[1,1,0]
	s_nop 0
	v_pk_fma_f32 v[176:177], v[172:173], v[176:177], s[38:39] op_sel_hi:[1,1,0]
	s_nop 0
	v_pk_fma_f32 v[176:177], v[172:173], v[176:177], s[40:41] op_sel_hi:[1,1,0]
	s_nop 0
	v_pk_fma_f32 v[176:177], v[172:173], v[176:177], s[42:43] op_sel_hi:[1,1,0]
	s_nop 0
	v_pk_fma_f32 v[172:173], v[172:173], v[176:177], s[44:45] op_sel_hi:[1,1,0]
	s_waitcnt vmcnt(0)
	v_cndmask_b32_e32 v177, v178, v212, vcc
	v_pk_mul_f32 v[170:171], v[170:171], v[172:173]
	v_cndmask_b32_e32 v178, v179, v213, vcc
	v_pk_fma_f32 v[164:165], v[164:165], v[170:171], v[164:165]
	s_nop 0
	v_mul_f32_e32 v164, v110, v164
	v_mul_f32_e32 v170, v184, v164
	v_mul_f32_e32 v164, v111, v165
	v_mul_f32_e32 v165, v184, v164
	v_cvt_pk_bf16_f32 v164, v169, v182
	v_cvt_pk_bf16_f32 v165, v170, v165
	global_store_dwordx2 v[174:175], v[164:165], off nt
	v_mov_b32_dpp v169, v160 row_ror:2 row_mask:0xf bank_mask:0xf bound_ctrl:1
	v_mov_b32_dpp v165, v161 row_ror:1 row_mask:0xf bank_mask:0xf bound_ctrl:1
	v_mov_b32_dpp v170, v161 row_ror:2 row_mask:0xf bank_mask:0xf bound_ctrl:1
	v_mov_b32_dpp v164, v160 row_ror:1 row_mask:0xf bank_mask:0xf bound_ctrl:1
	v_mov_b32_dpp v165, v161 row_shr:1 row_mask:0xf bank_mask:0xf
	v_mov_b32_dpp v169, v160 row_shr:2 row_mask:0xf bank_mask:0xf
	v_mov_b32_dpp v170, v161 row_shr:2 row_mask:0xf bank_mask:0xf
	v_lshlrev_b32_e32 v172, 16, v165
	v_mov_b32_dpp v164, v160 row_shr:1 row_mask:0xf bank_mask:0xf
	v_lshlrev_b32_e32 v174, 16, v169
	v_and_b32_e32 v169, 0xffff0000, v169
	v_lshlrev_b32_e32 v175, 16, v170
	v_and_b32_e32 v176, 0xffff0000, v170
	v_cndmask_b32_e64 v170, v172, v214, s[6:7]
	v_cndmask_b32_e32 v172, v180, v214, vcc
	v_lshlrev_b32_e32 v171, 16, v164
	v_and_b32_e32 v164, 0xffff0000, v164
	v_and_b32_e32 v173, 0xffff0000, v165
	v_cndmask_b32_e64 v172, v175, v172, s[0:1]
	v_cndmask_b32_e64 v175, v169, v178, s[0:1]
	v_cndmask_b32_e64 v174, v174, v177, s[0:1]
	v_cndmask_b32_e64 v165, v164, v213, s[6:7]
	v_cndmask_b32_e64 v164, v171, v212, s[6:7]
	v_cndmask_b32_e64 v171, v173, v215, s[6:7]
	v_cndmask_b32_e32 v173, v181, v215, vcc
	v_pk_fma_f32 v[140:141], v[140:141], v[174:175], v[144:145]
	v_cndmask_b32_e64 v173, v176, v173, s[0:1]
	v_lshlrev_b32_e32 v176, 16, v160
	v_and_b32_e32 v177, 0xffff0000, v160
	v_pk_fma_f32 v[136:137], v[136:137], v[164:165], v[140:141]
	v_pk_fma_f32 v[142:143], v[142:143], v[172:173], v[146:147]
	v_pk_fma_f32 v[132:133], v[132:133], v[176:177], v[136:137]
	v_pk_fma_f32 v[138:139], v[138:139], v[170:171], v[142:143]
	v_pk_mul_f32 v[136:137], v[132:133], s[26:27] op_sel_hi:[1,0]
	v_pk_mul_f32 v[132:133], v[132:133], 0.5 op_sel_hi:[1,0]
	v_med3_f32 v136, v136, s71, v224
	v_med3_f32 v137, v137, s71, v224
	v_pk_mul_f32 v[140:141], v[136:137], v[136:137]
	s_nop 0
	v_pk_fma_f32 v[142:143], v[140:141], s[28:29], v[148:149] op_sel_hi:[1,0,0] neg_lo:[1,0,0] neg_hi:[1,0,0]
	s_nop 0
;     static __device__ __forceinline__ void finish(const float (&g0)[4], const float (&g1)[4], const float (&g2)[4], const float (&w0)[4], const float (&w1)[4], const float (&w2)[4], const float (&bb)[4],
;                                                   const f32x4 v, float rs, bf16_t* dst) {
;         float h[4];
; #pragma unroll
;         for (int j = 0; j < 4; j += 2) {
;             const f32x2 gc = (f32x2){bb[j] + w0[j] * g2[j] + w1[j] * g1[j] + w2[j] * g0[j], bb[j + 1] + w0[j + 1] * g2[j + 1] + w1[j + 1] * g1[j + 1] + w2[j + 1] * g0[j + 1]};
;             const f32x2 ge = gelu_pk(gc); h[j] = ge.x * v[j] * rs; h[j + 1] = ge.y * v[j + 1] * rs; }
;     __device__ __forceinline__ void operator()(const f32x4 (&acc)[2][2][4][2], const Unit& u, int wr, int wc, int fr, int fq) const {
;     ...
;           for (int hv = 0; hv < 2; ++hv) {
;             const int col = u.pn * BM + bj * HALF + wc * 32 + 8 * fq + 4 * hv;
;             float w0[4], w1[4], w2[4], bb[4];
;             ld4f(cw + col, w0); ld4f(cw + 2816 + col, w1); ld4f(cw + 2 * 2816 + col, w2); ld4f(cb + col, bb);
;             {
;                 const int i = fr & 7;
;                 u32x2 gq[4];
; #pragma unroll
;                 for (int m = 0; m < 4; ++m) { const int row = row0 + m * 16; gq[m] = *(const u32x2*)(G + (size_t)row * 2816 + col); }
; #pragma unroll
;                 for (int mh = 0; mh < 4; mh += 2) {
;                 f32x4 c0[4], c1[4];
; #pragma unroll
;                 for (int m = mh; m < mh + 2; ++m) { const int row = row0 + m * 16; const float* cx = ctx + (size_t)((row - 32768) >> 3) * 2 * 2816 + col;
;                     c0[m] = *(const f32x4*)cx; c1[m] = *(const f32x4*)(cx + 2816); }
; #pragma unroll
;                 for (int m = mh; m < mh + 2; ++m) { const int row = row0 + m * 16; const u32x2 cur = gq[m];
;                     const u32x2 q1 = dpp_prev<1>(cur, cur), q2 = dpp_prev<2>(cur, cur);
;                     float g0[4], g1[4], g2[4]; unpk4(cur, g0); unpk4(q1, g1); unpk4(q2, g2);
; #pragma unroll
;                     for (int j = 0; j < 4; ++j) { const float x1 = c1[m][j], x0 = c0[m][j];
;                         if (i < 1) g1[j] = x1;
;                         if (i < 2) g2[j] = (i == 1) ? x1 : x0; }
;                     finish(g0, g1, g2, w0, w1, w2, bb, acc[0][bj][m][hv], rs8[0][m], H + (size_t)row * 2816 + col); }
	v_pk_fma_f32 v[142:143], v[140:141], v[142:143], s[34:35] op_sel_hi:[1,1,0]
	s_nop 0
	v_pk_fma_f32 v[142:143], v[140:141], v[142:143], s[36:37] op_sel_hi:[1,1,0]
	s_nop 0
	v_pk_fma_f32 v[142:143], v[140:141], v[142:143], s[38:39] op_sel_hi:[1,1,0]
	s_nop 0
	v_pk_fma_f32 v[142:143], v[140:141], v[142:143], s[40:41] op_sel_hi:[1,1,0]
	s_nop 0
	v_pk_fma_f32 v[142:143], v[140:141], v[142:143], s[42:43] op_sel_hi:[1,1,0]
	s_nop 0
	v_pk_fma_f32 v[140:141], v[140:141], v[142:143], s[44:45] op_sel_hi:[1,1,0]
	s_nop 0
	v_pk_mul_f32 v[136:137], v[136:137], v[140:141]
	s_nop 0
	v_pk_fma_f32 v[132:133], v[132:133], v[136:137], v[132:133]
	s_nop 0
	v_mul_f32_e32 v132, v100, v132
	v_mul_f32_e32 v140, v2, v132
	v_mul_f32_e32 v132, v101, v133
	v_mul_f32_e32 v141, v2, v132
	v_lshlrev_b32_e32 v132, 16, v161
	v_and_b32_e32 v133, 0xffff0000, v161
	v_pk_fma_f32 v[132:133], v[134:135], v[132:133], v[138:139]
	s_nop 0
	v_pk_mul_f32 v[134:135], v[132:133], s[26:27] op_sel_hi:[1,0]
	v_pk_mul_f32 v[132:133], v[132:133], 0.5 op_sel_hi:[1,0]
	v_med3_f32 v134, v134, s71, v224
	v_med3_f32 v135, v135, s71, v224
	v_pk_mul_f32 v[136:137], v[134:135], v[134:135]
	s_nop 0
	v_pk_fma_f32 v[138:139], v[136:137], s[28:29], v[148:149] op_sel_hi:[1,0,0] neg_lo:[1,0,0] neg_hi:[1,0,0]
	s_nop 0
	v_pk_fma_f32 v[138:139], v[136:137], v[138:139], s[34:35] op_sel_hi:[1,1,0]
	s_nop 0
	v_pk_fma_f32 v[138:139], v[136:137], v[138:139], s[36:37] op_sel_hi:[1,1,0]
	s_nop 0
	v_pk_fma_f32 v[138:139], v[136:137], v[138:139], s[38:39] op_sel_hi:[1,1,0]
	s_nop 0
	v_pk_fma_f32 v[138:139], v[136:137], v[138:139], s[40:41] op_sel_hi:[1,1,0]
	s_nop 0
	v_pk_fma_f32 v[138:139], v[136:137], v[138:139], s[42:43] op_sel_hi:[1,1,0]
	s_nop 0
	v_pk_fma_f32 v[136:137], v[136:137], v[138:139], s[44:45] op_sel_hi:[1,1,0]
	s_nop 0
	v_pk_mul_f32 v[134:135], v[134:135], v[136:137]
	s_nop 0
	v_pk_fma_f32 v[132:133], v[132:133], v[134:135], v[132:133]
	s_nop 0
	v_mul_f32_e32 v132, v102, v132
	v_mul_f32_e32 v134, v2, v132
	v_mul_f32_e32 v132, v103, v133
	v_mul_f32_e32 v133, v2, v132
	v_cvt_pk_bf16_f32 v132, v140, v141
	v_cvt_pk_bf16_f32 v133, v134, v133
	global_store_dwordx2 v[162:163], v[132:133], off nt
	v_add_u32_e32 v132, 0x80, v150
	v_ashrrev_i32_e32 v133, 31, v132
	v_lshlrev_b64 v[162:163], 1, v[132:133]
	v_lshl_add_u64 v[160:161], s[56:57], 0, v[162:163]
	v_lshlrev_b64 v[132:133], 2, v[132:133]
	v_mad_i64_i32 v[134:135], s[8:9], v210, s67, v[160:161]
	v_lshl_add_u64 v[226:227], s[16:17], 0, v[132:133]
	global_load_dwordx2 v[182:183], v[134:135], off
	v_mad_i64_i32 v[134:135], s[8:9], v151, s70, v[226:227]
	v_add_co_u32_e64 v136, s[8:9], s41, v134
	s_waitcnt vmcnt(0)
	v_mov_b32_dpp v169, v182 row_ror:1 row_mask:0xf bank_mask:0xf bound_ctrl:1
	v_addc_co_u32_e64 v137, s[8:9], 0, v135, s[8:9]
	global_load_dwordx4 v[170:173], v[136:137], off offset:3072
	global_load_dwordx4 v[174:177], v[134:135], off
	v_lshl_add_u64 v[134:135], s[12:13], 0, v[132:133]
	global_load_dwordx4 v[140:143], v[134:135], off
	v_lshl_add_u64 v[134:135], s[14:15], 0, v[132:133]
	global_load_dwordx4 v[144:147], v[134:135], off
	v_lshl_add_u64 v[134:135], s[18:19], 0, v[132:133]
	global_load_dwordx4 v[136:139], v[134:135], off
	v_lshl_add_u64 v[132:133], s[20:21], 0, v[132:133]
	global_load_dwordx4 v[132:135], v[132:133], off
	v_mad_i64_i32 v[164:165], s[8:9], v194, s67, v[160:161]
	v_mad_i64_i32 v[178:179], s[8:9], v192, s67, v[160:161]
	v_mad_i64_i32 v[160:161], s[8:9], v190, s67, v[160:161]
	global_load_dwordx2 v[228:229], v[164:165], off
	s_nop 0
	global_load_dwordx2 v[164:165], v[178:179], off
	s_nop 0
	global_load_dwordx2 v[160:161], v[160:161], off
	v_mad_i64_i32 v[178:179], s[8:9], v166, s70, v[226:227]
	v_add_co_u32_e64 v212, s[8:9], s41, v178
	v_mov_b32_dpp v169, v182 row_shr:1 row_mask:0xf bank_mask:0xf
	s_nop 0
	v_addc_co_u32_e64 v213, s[8:9], 0, v179, s[8:9]
	global_load_dwordx4 v[178:181], v[178:179], off
	s_nop 0
	global_load_dwordx4 v[212:215], v[212:213], off offset:3072
	v_mov_b32_dpp v185, v183 row_ror:1 row_mask:0xf bank_mask:0xf bound_ctrl:1
	v_mov_b32_dpp v187, v182 row_ror:2 row_mask:0xf bank_mask:0xf bound_ctrl:1
	v_lshlrev_b32_e32 v191, 16, v169
	v_mov_b32_dpp v185, v183 row_shr:1 row_mask:0xf bank_mask:0xf
	v_mov_b32_dpp v187, v182 row_shr:2 row_mask:0xf bank_mask:0xf
	v_and_b32_e32 v169, 0xffff0000, v169
	v_lshlrev_b32_e32 v193, 16, v185
	v_and_b32_e32 v185, 0xffff0000, v185
	v_lshlrev_b32_e32 v195, 16, v187
	v_and_b32_e32 v187, 0xffff0000, v187
	v_mov_b32_dpp v189, v183 row_ror:2 row_mask:0xf bank_mask:0xf bound_ctrl:1
	s_waitcnt vmcnt(10)
	v_cndmask_b32_e64 v231, v169, v171, s[6:7]
	s_waitcnt vmcnt(9)
	v_cndmask_b32_e32 v169, v174, v170, vcc
	v_cndmask_b32_e32 v174, v175, v171, vcc
	v_cndmask_b32_e64 v230, v191, v170, s[6:7]
	v_cndmask_b32_e64 v233, v185, v173, s[6:7]
	v_cndmask_b32_e64 v232, v193, v172, s[6:7]
	v_cndmask_b32_e32 v170, v176, v172, vcc
	v_cndmask_b32_e32 v171, v177, v173, vcc
	v_cndmask_b32_e64 v173, v187, v174, s[0:1]
	v_cndmask_b32_e64 v172, v195, v169, s[0:1]
	s_waitcnt vmcnt(7)
	v_pk_fma_f32 v[172:173], v[140:141], v[172:173], v[144:145]
	v_lshlrev_b32_e32 v176, 16, v182
	v_and_b32_e32 v177, 0xffff0000, v182
	s_waitcnt vmcnt(6)
	v_pk_fma_f32 v[172:173], v[136:137], v[230:231], v[172:173]
	v_mov_b32_dpp v189, v183 row_shr:2 row_mask:0xf bank_mask:0xf
	s_waitcnt vmcnt(5)
;     static __device__ __forceinline__ void finish(const float (&g0)[4], const float (&g1)[4], const float (&g2)[4], const float (&w0)[4], const float (&w1)[4], const float (&w2)[4], const float (&bb)[4],
;                                                   const f32x4 v, float rs, bf16_t* dst) {
;         float h[4];
; #pragma unroll
;         for (int j = 0; j < 4; j += 2) {
;             const f32x2 gc = (f32x2){bb[j] + w0[j] * g2[j] + w1[j] * g1[j] + w2[j] * g0[j], bb[j + 1] + w0[j + 1] * g2[j + 1] + w1[j + 1] * g1[j + 1] + w2[j + 1] * g0[j + 1]};
;             const f32x2 ge = gelu_pk(gc); h[j] = ge.x * v[j] * rs; h[j + 1] = ge.y * v[j + 1] * rs; }
;     __device__ __forceinline__ void operator()(const f32x4 (&acc)[2][2][4][2], const Unit& u, int wr, int wc, int fr, int fq) const {
;     ...
;           for (int hv = 0; hv < 2; ++hv) {
;             const int col = u.pn * BM + bj * HALF + wc * 32 + 8 * fq + 4 * hv;
;             float w0[4], w1[4], w2[4], bb[4];
;             ld4f(cw + col, w0); ld4f(cw + 2816 + col, w1); ld4f(cw + 2 * 2816 + col, w2); ld4f(cb + col, bb);
;             {
;                 const int i = fr & 7;
;                 u32x2 gq[4];
; #pragma unroll
;                 for (int m = 0; m < 4; ++m) { const int row = row0 + m * 16; gq[m] = *(const u32x2*)(G + (size_t)row * 2816 + col); }
; #pragma unroll
;                 for (int mh = 0; mh < 4; mh += 2) {
;                 f32x4 c0[4], c1[4];
; #pragma unroll
;                 for (int m = mh; m < mh + 2; ++m) { const int row = row0 + m * 16; const float* cx = ctx + (size_t)((row - 32768) >> 3) * 2 * 2816 + col;
;                     c0[m] = *(const f32x4*)cx; c1[m] = *(const f32x4*)(cx + 2816); }
; #pragma unroll
;                 for (int m = mh; m < mh + 2; ++m) { const int row = row0 + m * 16; const u32x2 cur = gq[m];
;                     const u32x2 q1 = dpp_prev<1>(cur, cur), q2 = dpp_prev<2>(cur, cur);
;                     float g0[4], g1[4], g2[4]; unpk4(cur, g0); unpk4(q1, g1); unpk4(q2, g2);
; #pragma unroll
;                     for (int j = 0; j < 4; ++j) { const float x1 = c1[m][j], x0 = c0[m][j];
;                         if (i < 1) g1[j] = x1;
;                         if (i < 2) g2[j] = (i == 1) ? x1 : x0; }
;                     finish(g0, g1, g2, w0, w1, w2, bb, acc[0][bj][m][hv], rs8[0][m], H + (size_t)row * 2816 + col); }
	v_pk_fma_f32 v[172:173], v[132:133], v[176:177], v[172:173]
	v_lshlrev_b32_e32 v211, 16, v189
	v_and_b32_e32 v189, 0xffff0000, v189
	v_pk_mul_f32 v[176:177], v[172:173], s[26:27] op_sel_hi:[1,0]
	v_cndmask_b32_e64 v171, v189, v171, s[0:1]
	v_cndmask_b32_e64 v170, v211, v170, s[0:1]
	v_med3_f32 v176, v176, s71, v224
	v_med3_f32 v177, v177, s71, v224
	v_pk_fma_f32 v[170:171], v[142:143], v[170:171], v[146:147]
	v_pk_mul_f32 v[230:231], v[176:177], v[176:177]
	v_pk_fma_f32 v[170:171], v[138:139], v[232:233], v[170:171]
	v_pk_fma_f32 v[232:233], v[230:231], s[28:29], v[148:149] op_sel_hi:[1,0,0] neg_lo:[1,0,0] neg_hi:[1,0,0]
	v_pk_mul_f32 v[172:173], v[172:173], 0.5 op_sel_hi:[1,0]
	v_pk_fma_f32 v[232:233], v[230:231], v[232:233], s[34:35] op_sel_hi:[1,1,0]
	v_lshl_add_u64 v[174:175], v[152:153], 0, v[162:163]
	v_pk_fma_f32 v[232:233], v[230:231], v[232:233], s[36:37] op_sel_hi:[1,1,0]
	s_nop 0
	v_pk_fma_f32 v[232:233], v[230:231], v[232:233], s[38:39] op_sel_hi:[1,1,0]
	s_nop 0
	v_pk_fma_f32 v[232:233], v[230:231], v[232:233], s[40:41] op_sel_hi:[1,1,0]
	s_nop 0
	v_pk_fma_f32 v[232:233], v[230:231], v[232:233], s[42:43] op_sel_hi:[1,1,0]
	s_nop 0
	v_pk_fma_f32 v[230:231], v[230:231], v[232:233], s[44:45] op_sel_hi:[1,1,0]
	s_nop 0
	v_pk_mul_f32 v[176:177], v[176:177], v[230:231]
	s_nop 0
	v_pk_fma_f32 v[172:173], v[172:173], v[176:177], v[172:173]
	s_nop 0
	v_mul_f32_e32 v169, v68, v172
	v_mul_f32_e32 v172, v69, v173
	v_mul_f32_e32 v185, v188, v172
	v_lshlrev_b32_e32 v172, 16, v183
	v_and_b32_e32 v173, 0xffff0000, v183
	v_pk_fma_f32 v[170:171], v[134:135], v[172:173], v[170:171]
	v_mul_f32_e32 v169, v188, v169
	v_pk_mul_f32 v[172:173], v[170:171], s[26:27] op_sel_hi:[1,0]
	v_pk_mul_f32 v[170:171], v[170:171], 0.5 op_sel_hi:[1,0]
	v_med3_f32 v172, v172, s71, v224
	v_med3_f32 v173, v173, s71, v224
	v_pk_mul_f32 v[176:177], v[172:173], v[172:173]
	s_nop 0
	v_pk_fma_f32 v[182:183], v[176:177], s[28:29], v[148:149] op_sel_hi:[1,0,0] neg_lo:[1,0,0] neg_hi:[1,0,0]
	s_nop 0
	v_pk_fma_f32 v[182:183], v[176:177], v[182:183], s[34:35] op_sel_hi:[1,1,0]
	s_nop 0
	v_pk_fma_f32 v[182:183], v[176:177], v[182:183], s[36:37] op_sel_hi:[1,1,0]
	s_nop 0
	v_pk_fma_f32 v[182:183], v[176:177], v[182:183], s[38:39] op_sel_hi:[1,1,0]
	s_nop 0
	v_pk_fma_f32 v[182:183], v[176:177], v[182:183], s[40:41] op_sel_hi:[1,1,0]
	s_nop 0
	v_pk_fma_f32 v[182:183], v[176:177], v[182:183], s[42:43] op_sel_hi:[1,1,0]
	s_nop 0
	v_pk_fma_f32 v[176:177], v[176:177], v[182:183], s[44:45] op_sel_hi:[1,1,0]
	s_nop 0
	v_pk_mul_f32 v[172:173], v[172:173], v[176:177]
	s_nop 0
	v_pk_fma_f32 v[170:171], v[170:171], v[172:173], v[170:171]
	s_nop 0
	v_mul_f32_e32 v170, v70, v170
	v_mul_f32_e32 v172, v188, v170
	v_mul_f32_e32 v170, v71, v171
	v_mul_f32_e32 v171, v188, v170
	v_cvt_pk_bf16_f32 v170, v169, v185
	v_cvt_pk_bf16_f32 v171, v172, v171
	s_waitcnt vmcnt(4)
	v_mov_b32_dpp v169, v228 row_ror:1 row_mask:0xf bank_mask:0xf bound_ctrl:1
	global_store_dwordx2 v[174:175], v[170:171], off nt
	v_mov_b32_dpp v171, v228 row_ror:2 row_mask:0xf bank_mask:0xf bound_ctrl:1
	v_mov_b32_dpp v169, v228 row_shr:1 row_mask:0xf bank_mask:0xf
	v_mov_b32_dpp v170, v229 row_ror:1 row_mask:0xf bank_mask:0xf bound_ctrl:1
	v_mov_b32_dpp v171, v228 row_shr:2 row_mask:0xf bank_mask:0xf
	v_lshlrev_b32_e32 v173, 16, v169
	v_and_b32_e32 v169, 0xffff0000, v169
	v_mov_b32_dpp v170, v229 row_shr:1 row_mask:0xf bank_mask:0xf
	v_mov_b32_dpp v172, v229 row_ror:2 row_mask:0xf bank_mask:0xf bound_ctrl:1
	v_lshlrev_b32_e32 v176, 16, v171
	v_and_b32_e32 v177, 0xffff0000, v171
	s_waitcnt vmcnt(1)
	v_cndmask_b32_e64 v171, v169, v213, s[6:7]
	v_cndmask_b32_e32 v169, v178, v212, vcc
	v_cndmask_b32_e32 v178, v179, v213, vcc
	v_mov_b32_dpp v172, v229 row_shr:2 row_mask:0xf bank_mask:0xf
	v_lshlrev_b32_e32 v174, 16, v170
	v_and_b32_e32 v175, 0xffff0000, v170
	v_cndmask_b32_e64 v177, v177, v178, s[0:1]
	v_cndmask_b32_e64 v176, v176, v169, s[0:1]
	v_lshlrev_b32_e32 v182, 16, v172
	v_and_b32_e32 v183, 0xffff0000, v172
	v_cndmask_b32_e64 v170, v173, v212, s[6:7]
	v_cndmask_b32_e64 v173, v175, v215, s[6:7]
	v_cndmask_b32_e64 v172, v174, v214, s[6:7]
	v_cndmask_b32_e32 v174, v180, v214, vcc
	v_cndmask_b32_e32 v175, v181, v215, vcc
	v_pk_fma_f32 v[176:177], v[140:141], v[176:177], v[144:145]
	v_cndmask_b32_e64 v175, v183, v175, s[0:1]
	v_cndmask_b32_e64 v174, v182, v174, s[0:1]
	v_lshlrev_b32_e32 v180, 16, v228
	v_and_b32_e32 v181, 0xffff0000, v228
	v_pk_fma_f32 v[170:171], v[136:137], v[170:171], v[176:177]
	v_pk_fma_f32 v[174:175], v[142:143], v[174:175], v[146:147]
	v_pk_fma_f32 v[170:171], v[132:133], v[180:181], v[170:171]
	v_pk_fma_f32 v[172:173], v[138:139], v[172:173], v[174:175]
	v_pk_mul_f32 v[174:175], v[170:171], s[26:27] op_sel_hi:[1,0]
	v_pk_mul_f32 v[170:171], v[170:171], 0.5 op_sel_hi:[1,0]
	v_med3_f32 v174, v174, s71, v224
	v_med3_f32 v175, v175, s71, v224
	v_pk_mul_f32 v[176:177], v[174:175], v[174:175]
	v_lshl_add_u64 v[178:179], v[154:155], 0, v[162:163]
	v_pk_fma_f32 v[180:181], v[176:177], s[28:29], v[148:149] op_sel_hi:[1,0,0] neg_lo:[1,0,0] neg_hi:[1,0,0]
	v_mov_b32_dpp v185, v165 row_ror:2 row_mask:0xf bank_mask:0xf bound_ctrl:1
	v_pk_fma_f32 v[180:181], v[176:177], v[180:181], s[34:35] op_sel_hi:[1,1,0]
	s_nop 0
	v_pk_fma_f32 v[180:181], v[176:177], v[180:181], s[36:37] op_sel_hi:[1,1,0]
	v_mov_b32_dpp v185, v165 row_shr:2 row_mask:0xf bank_mask:0xf
	v_pk_fma_f32 v[180:181], v[176:177], v[180:181], s[38:39] op_sel_hi:[1,1,0]
	v_lshlrev_b32_e32 v211, 16, v185
	v_pk_fma_f32 v[180:181], v[176:177], v[180:181], s[40:41] op_sel_hi:[1,1,0]
	v_and_b32_e32 v185, 0xffff0000, v185
	v_pk_fma_f32 v[180:181], v[176:177], v[180:181], s[42:43] op_sel_hi:[1,1,0]
;     static __device__ __forceinline__ void finish(const float (&g0)[4], const float (&g1)[4], const float (&g2)[4], const float (&w0)[4], const float (&w1)[4], const float (&w2)[4], const float (&bb)[4],
;                                                   const f32x4 v, float rs, bf16_t* dst) {
;         float h[4];
; #pragma unroll
;         for (int j = 0; j < 4; j += 2) {
;             const f32x2 gc = (f32x2){bb[j] + w0[j] * g2[j] + w1[j] * g1[j] + w2[j] * g0[j], bb[j + 1] + w0[j + 1] * g2[j + 1] + w1[j + 1] * g1[j + 1] + w2[j + 1] * g0[j + 1]};
;             const f32x2 ge = gelu_pk(gc); h[j] = ge.x * v[j] * rs; h[j + 1] = ge.y * v[j + 1] * rs; }
;     __device__ __forceinline__ void operator()(const f32x4 (&acc)[2][2][4][2], const Unit& u, int wr, int wc, int fr, int fq) const {
;     ...
;           for (int hv = 0; hv < 2; ++hv) {
;             const int col = u.pn * BM + bj * HALF + wc * 32 + 8 * fq + 4 * hv;
;             float w0[4], w1[4], w2[4], bb[4];
;             ld4f(cw + col, w0); ld4f(cw + 2816 + col, w1); ld4f(cw + 2 * 2816 + col, w2); ld4f(cb + col, bb);
;             {
;                 const int i = fr & 7;
;                 u32x2 gq[4];
; #pragma unroll
;                 for (int m = 0; m < 4; ++m) { const int row = row0 + m * 16; gq[m] = *(const u32x2*)(G + (size_t)row * 2816 + col); }
; #pragma unroll
;                 for (int mh = 0; mh < 4; mh += 2) {
;                 f32x4 c0[4], c1[4];
; #pragma unroll
;                 for (int m = mh; m < mh + 2; ++m) { const int row = row0 + m * 16; const float* cx = ctx + (size_t)((row - 32768) >> 3) * 2 * 2816 + col;
;                     c0[m] = *(const f32x4*)cx; c1[m] = *(const f32x4*)(cx + 2816); }
; #pragma unroll
;                 for (int m = mh; m < mh + 2; ++m) { const int row = row0 + m * 16; const u32x2 cur = gq[m];
;                     const u32x2 q1 = dpp_prev<1>(cur, cur), q2 = dpp_prev<2>(cur, cur);
;                     float g0[4], g1[4], g2[4]; unpk4(cur, g0); unpk4(q1, g1); unpk4(q2, g2);
; #pragma unroll
;                     for (int j = 0; j < 4; ++j) { const float x1 = c1[m][j], x0 = c0[m][j];
;                         if (i < 1) g1[j] = x1;
;                         if (i < 2) g2[j] = (i == 1) ? x1 : x0; }
;                     finish(g0, g1, g2, w0, w1, w2, bb, acc[0][bj][m][hv], rs8[0][m], H + (size_t)row * 2816 + col); }
	s_nop 0
	v_pk_fma_f32 v[176:177], v[176:177], v[180:181], s[44:45] op_sel_hi:[1,1,0]
	s_nop 0
	v_pk_mul_f32 v[174:175], v[174:175], v[176:177]
	s_nop 0
	v_pk_fma_f32 v[170:171], v[170:171], v[174:175], v[170:171]
	s_nop 0
	v_mul_f32_e32 v169, v56, v170
	v_mul_f32_e32 v170, v57, v171
	v_mul_f32_e32 v180, v186, v170
	v_lshlrev_b32_e32 v170, 16, v229
	v_and_b32_e32 v171, 0xffff0000, v229
	v_pk_fma_f32 v[170:171], v[134:135], v[170:171], v[172:173]
	v_mul_f32_e32 v169, v186, v169
	v_pk_mul_f32 v[172:173], v[170:171], s[26:27] op_sel_hi:[1,0]
	v_pk_mul_f32 v[170:171], v[170:171], 0.5 op_sel_hi:[1,0]
	v_med3_f32 v172, v172, s71, v224
	v_med3_f32 v173, v173, s71, v224
	v_pk_mul_f32 v[174:175], v[172:173], v[172:173]
	s_nop 0
	v_pk_fma_f32 v[176:177], v[174:175], s[28:29], v[148:149] op_sel_hi:[1,0,0] neg_lo:[1,0,0] neg_hi:[1,0,0]
	s_nop 0
	v_pk_fma_f32 v[176:177], v[174:175], v[176:177], s[34:35] op_sel_hi:[1,1,0]
	s_nop 0
	v_pk_fma_f32 v[176:177], v[174:175], v[176:177], s[36:37] op_sel_hi:[1,1,0]
	s_nop 0
	v_pk_fma_f32 v[176:177], v[174:175], v[176:177], s[38:39] op_sel_hi:[1,1,0]
	s_nop 0
	v_pk_fma_f32 v[176:177], v[174:175], v[176:177], s[40:41] op_sel_hi:[1,1,0]
	s_nop 0
	v_pk_fma_f32 v[176:177], v[174:175], v[176:177], s[42:43] op_sel_hi:[1,1,0]
	s_nop 0
	v_pk_fma_f32 v[174:175], v[174:175], v[176:177], s[44:45] op_sel_hi:[1,1,0]
	s_nop 0
	v_pk_mul_f32 v[172:173], v[172:173], v[174:175]
	v_mad_i64_i32 v[174:175], s[8:9], v167, s70, v[226:227]
	v_pk_fma_f32 v[170:171], v[170:171], v[172:173], v[170:171]
	s_nop 0
	v_mul_f32_e32 v170, v58, v170
	v_mul_f32_e32 v172, v186, v170
	v_mul_f32_e32 v170, v59, v171
	v_mul_f32_e32 v171, v186, v170
	v_cvt_pk_bf16_f32 v170, v169, v180
	v_cvt_pk_bf16_f32 v171, v172, v171
	global_store_dwordx2 v[178:179], v[170:171], off nt
	v_add_co_u32_e64 v170, s[8:9], s41, v174
	v_mov_b32_dpp v169, v164 row_ror:1 row_mask:0xf bank_mask:0xf bound_ctrl:1
	s_nop 0
	v_addc_co_u32_e64 v171, s[8:9], 0, v175, s[8:9]
	global_load_dwordx4 v[170:173], v[170:171], off offset:3072
	s_nop 0
	global_load_dwordx4 v[174:177], v[174:175], off
	v_mad_i64_i32 v[178:179], s[8:9], v168, s70, v[226:227]
	v_add_co_u32_e64 v182, s[8:9], s41, v178
	v_mov_b32_dpp v169, v164 row_shr:1 row_mask:0xf bank_mask:0xf
	s_nop 0
	v_addc_co_u32_e64 v183, s[8:9], 0, v179, s[8:9]
	global_load_dwordx4 v[178:181], v[178:179], off
	s_nop 0
	global_load_dwordx4 v[212:215], v[182:183], off offset:3072
	v_mov_b32_dpp v182, v165 row_ror:1 row_mask:0xf bank_mask:0xf bound_ctrl:1
	v_mov_b32_dpp v183, v164 row_ror:2 row_mask:0xf bank_mask:0xf bound_ctrl:1
	v_lshlrev_b32_e32 v187, 16, v169
	v_mov_b32_dpp v182, v165 row_shr:1 row_mask:0xf bank_mask:0xf
	v_mov_b32_dpp v183, v164 row_shr:2 row_mask:0xf bank_mask:0xf
	v_and_b32_e32 v169, 0xffff0000, v169
	v_lshlrev_b32_e32 v189, 16, v182
	v_and_b32_e32 v191, 0xffff0000, v182
	v_lshlrev_b32_e32 v193, 16, v183
	v_and_b32_e32 v195, 0xffff0000, v183
	s_waitcnt vmcnt(3)
	v_cndmask_b32_e64 v183, v169, v171, s[6:7]
	s_waitcnt vmcnt(2)
	v_cndmask_b32_e32 v169, v174, v170, vcc
	v_cndmask_b32_e32 v174, v175, v171, vcc
	v_cndmask_b32_e64 v182, v187, v170, s[6:7]
	v_cndmask_b32_e64 v227, v191, v173, s[6:7]
	v_cndmask_b32_e64 v226, v189, v172, s[6:7]
	v_cndmask_b32_e32 v170, v176, v172, vcc
	v_cndmask_b32_e32 v171, v177, v173, vcc
	v_cndmask_b32_e64 v173, v195, v174, s[0:1]
	v_cndmask_b32_e64 v172, v193, v169, s[0:1]
	v_pk_fma_f32 v[172:173], v[140:141], v[172:173], v[144:145]
	v_lshlrev_b32_e32 v176, 16, v164
	v_and_b32_e32 v177, 0xffff0000, v164
	v_pk_fma_f32 v[172:173], v[136:137], v[182:183], v[172:173]
	v_cndmask_b32_e64 v171, v185, v171, s[0:1]
	v_pk_fma_f32 v[172:173], v[132:133], v[176:177], v[172:173]
	v_cndmask_b32_e64 v170, v211, v170, s[0:1]
	v_pk_mul_f32 v[176:177], v[172:173], s[26:27] op_sel_hi:[1,0]
	v_pk_fma_f32 v[170:171], v[142:143], v[170:171], v[146:147]
	v_med3_f32 v176, v176, s71, v224
	v_med3_f32 v177, v177, s71, v224
	v_pk_mul_f32 v[182:183], v[176:177], v[176:177]
	v_pk_fma_f32 v[170:171], v[138:139], v[226:227], v[170:171]
	v_pk_fma_f32 v[226:227], v[182:183], s[28:29], v[148:149] op_sel_hi:[1,0,0] neg_lo:[1,0,0] neg_hi:[1,0,0]
	v_pk_mul_f32 v[172:173], v[172:173], 0.5 op_sel_hi:[1,0]
	v_pk_fma_f32 v[226:227], v[182:183], v[226:227], s[34:35] op_sel_hi:[1,1,0]
	v_lshl_add_u64 v[174:175], v[156:157], 0, v[162:163]
	v_pk_fma_f32 v[226:227], v[182:183], v[226:227], s[36:37] op_sel_hi:[1,1,0]
	v_lshl_add_u64 v[162:163], v[158:159], 0, v[162:163]
	v_pk_fma_f32 v[226:227], v[182:183], v[226:227], s[38:39] op_sel_hi:[1,1,0]
	s_nop 0
	v_pk_fma_f32 v[226:227], v[182:183], v[226:227], s[40:41] op_sel_hi:[1,1,0]
	s_nop 0
	v_pk_fma_f32 v[226:227], v[182:183], v[226:227], s[42:43] op_sel_hi:[1,1,0]
	s_nop 0
	v_pk_fma_f32 v[182:183], v[182:183], v[226:227], s[44:45] op_sel_hi:[1,1,0]
	s_nop 0
	v_pk_mul_f32 v[176:177], v[176:177], v[182:183]
	s_nop 0
	v_pk_fma_f32 v[172:173], v[172:173], v[176:177], v[172:173]
	s_nop 0
	v_mul_f32_e32 v164, v48, v172
	v_mul_f32_e32 v169, v184, v164
	v_mul_f32_e32 v164, v49, v173
	v_mul_f32_e32 v182, v184, v164
	v_lshlrev_b32_e32 v164, 16, v165
	v_and_b32_e32 v165, 0xffff0000, v165
	v_pk_fma_f32 v[164:165], v[134:135], v[164:165], v[170:171]
	s_nop 0
	v_pk_mul_f32 v[170:171], v[164:165], s[26:27] op_sel_hi:[1,0]
	v_pk_mul_f32 v[164:165], v[164:165], 0.5 op_sel_hi:[1,0]
	v_med3_f32 v170, v170, s71, v224
	v_med3_f32 v171, v171, s71, v224
	v_pk_mul_f32 v[172:173], v[170:171], v[170:171]
	s_nop 0
	v_pk_fma_f32 v[176:177], v[172:173], s[28:29], v[148:149] op_sel_hi:[1,0,0] neg_lo:[1,0,0] neg_hi:[1,0,0]
	s_nop 0
	v_pk_fma_f32 v[176:177], v[172:173], v[176:177], s[34:35] op_sel_hi:[1,1,0]
	s_nop 0
	v_pk_fma_f32 v[176:177], v[172:173], v[176:177], s[36:37] op_sel_hi:[1,1,0]
	s_nop 0
	v_pk_fma_f32 v[176:177], v[172:173], v[176:177], s[38:39] op_sel_hi:[1,1,0]
	s_nop 0
	v_pk_fma_f32 v[176:177], v[172:173], v[176:177], s[40:41] op_sel_hi:[1,1,0]
	s_nop 0
	v_pk_fma_f32 v[176:177], v[172:173], v[176:177], s[42:43] op_sel_hi:[1,1,0]
	s_nop 0
	v_pk_fma_f32 v[172:173], v[172:173], v[176:177], s[44:45] op_sel_hi:[1,1,0]
	s_waitcnt vmcnt(0)
;     static __device__ __forceinline__ void finish(const float (&g0)[4], const float (&g1)[4], const float (&g2)[4], const float (&w0)[4], const float (&w1)[4], const float (&w2)[4], const float (&bb)[4],
;                                                   const f32x4 v, float rs, bf16_t* dst) {
;         float h[4];
; #pragma unroll
;         for (int j = 0; j < 4; j += 2) {
;             const f32x2 gc = (f32x2){bb[j] + w0[j] * g2[j] + w1[j] * g1[j] + w2[j] * g0[j], bb[j + 1] + w0[j + 1] * g2[j + 1] + w1[j + 1] * g1[j + 1] + w2[j + 1] * g0[j + 1]};
;             const f32x2 ge = gelu_pk(gc); h[j] = ge.x * v[j] * rs; h[j + 1] = ge.y * v[j + 1] * rs; }
;     __device__ __forceinline__ void operator()(const f32x4 (&acc)[2][2][4][2], const Unit& u, int wr, int wc, int fr, int fq) const {
;     ...
;           for (int hv = 0; hv < 2; ++hv) {
;             const int col = u.pn * BM + bj * HALF + wc * 32 + 8 * fq + 4 * hv;
;             float w0[4], w1[4], w2[4], bb[4];
;             ld4f(cw + col, w0); ld4f(cw + 2816 + col, w1); ld4f(cw + 2 * 2816 + col, w2); ld4f(cb + col, bb);
;             {
;                 const int i = fr & 7;
;                 u32x2 gq[4];
; #pragma unroll
;                 for (int m = 0; m < 4; ++m) { const int row = row0 + m * 16; gq[m] = *(const u32x2*)(G + (size_t)row * 2816 + col); }
; #pragma unroll
;                 for (int mh = 0; mh < 4; mh += 2) {
;                 f32x4 c0[4], c1[4];
; #pragma unroll
;                 for (int m = mh; m < mh + 2; ++m) { const int row = row0 + m * 16; const float* cx = ctx + (size_t)((row - 32768) >> 3) * 2 * 2816 + col;
;                     c0[m] = *(const f32x4*)cx; c1[m] = *(const f32x4*)(cx + 2816); }
; #pragma unroll
;                 for (int m = mh; m < mh + 2; ++m) { const int row = row0 + m * 16; const u32x2 cur = gq[m];
;                     const u32x2 q1 = dpp_prev<1>(cur, cur), q2 = dpp_prev<2>(cur, cur);
;                     float g0[4], g1[4], g2[4]; unpk4(cur, g0); unpk4(q1, g1); unpk4(q2, g2);
; #pragma unroll
;                     for (int j = 0; j < 4; ++j) { const float x1 = c1[m][j], x0 = c0[m][j];
;                         if (i < 1) g1[j] = x1;
;                         if (i < 2) g2[j] = (i == 1) ? x1 : x0; }
;                     finish(g0, g1, g2, w0, w1, w2, bb, acc[0][bj][m][hv], rs8[0][m], H + (size_t)row * 2816 + col); }
	v_cndmask_b32_e32 v177, v178, v212, vcc
	v_pk_mul_f32 v[170:171], v[170:171], v[172:173]
	v_cndmask_b32_e32 v178, v179, v213, vcc
	v_pk_fma_f32 v[164:165], v[164:165], v[170:171], v[164:165]
	s_nop 0
	v_mul_f32_e32 v164, v50, v164
	v_mul_f32_e32 v170, v184, v164
	v_mul_f32_e32 v164, v51, v165
	v_mul_f32_e32 v165, v184, v164
	v_cvt_pk_bf16_f32 v164, v169, v182
	v_cvt_pk_bf16_f32 v165, v170, v165
	global_store_dwordx2 v[174:175], v[164:165], off nt
	v_mov_b32_dpp v169, v160 row_ror:2 row_mask:0xf bank_mask:0xf bound_ctrl:1
	v_mov_b32_dpp v165, v161 row_ror:1 row_mask:0xf bank_mask:0xf bound_ctrl:1
	v_mov_b32_dpp v170, v161 row_ror:2 row_mask:0xf bank_mask:0xf bound_ctrl:1
	v_mov_b32_dpp v164, v160 row_ror:1 row_mask:0xf bank_mask:0xf bound_ctrl:1
	v_mov_b32_dpp v165, v161 row_shr:1 row_mask:0xf bank_mask:0xf
	v_mov_b32_dpp v169, v160 row_shr:2 row_mask:0xf bank_mask:0xf
	v_mov_b32_dpp v170, v161 row_shr:2 row_mask:0xf bank_mask:0xf
	v_lshlrev_b32_e32 v172, 16, v165
	v_mov_b32_dpp v164, v160 row_shr:1 row_mask:0xf bank_mask:0xf
	v_lshlrev_b32_e32 v174, 16, v169
	v_and_b32_e32 v169, 0xffff0000, v169
	v_lshlrev_b32_e32 v175, 16, v170
	v_and_b32_e32 v176, 0xffff0000, v170
	v_cndmask_b32_e64 v170, v172, v214, s[6:7]
	v_cndmask_b32_e32 v172, v180, v214, vcc
	v_lshlrev_b32_e32 v171, 16, v164
	v_and_b32_e32 v164, 0xffff0000, v164
	v_and_b32_e32 v173, 0xffff0000, v165
	v_cndmask_b32_e64 v172, v175, v172, s[0:1]
	v_cndmask_b32_e64 v175, v169, v178, s[0:1]
	v_cndmask_b32_e64 v174, v174, v177, s[0:1]
	v_cndmask_b32_e64 v165, v164, v213, s[6:7]
	v_cndmask_b32_e64 v164, v171, v212, s[6:7]
	v_cndmask_b32_e64 v171, v173, v215, s[6:7]
	v_cndmask_b32_e32 v173, v181, v215, vcc
	v_pk_fma_f32 v[140:141], v[140:141], v[174:175], v[144:145]
	v_cndmask_b32_e64 v173, v176, v173, s[0:1]
	v_lshlrev_b32_e32 v176, 16, v160
	v_and_b32_e32 v177, 0xffff0000, v160
	v_pk_fma_f32 v[136:137], v[136:137], v[164:165], v[140:141]
	v_pk_fma_f32 v[142:143], v[142:143], v[172:173], v[146:147]
	v_pk_fma_f32 v[132:133], v[132:133], v[176:177], v[136:137]
	v_pk_fma_f32 v[138:139], v[138:139], v[170:171], v[142:143]
	v_pk_mul_f32 v[136:137], v[132:133], s[26:27] op_sel_hi:[1,0]
	v_pk_mul_f32 v[132:133], v[132:133], 0.5 op_sel_hi:[1,0]
	v_med3_f32 v136, v136, s71, v224
	v_med3_f32 v137, v137, s71, v224
	v_pk_mul_f32 v[140:141], v[136:137], v[136:137]
	s_nop 0
	v_pk_fma_f32 v[142:143], v[140:141], s[28:29], v[148:149] op_sel_hi:[1,0,0] neg_lo:[1,0,0] neg_hi:[1,0,0]
	s_nop 0
	v_pk_fma_f32 v[142:143], v[140:141], v[142:143], s[34:35] op_sel_hi:[1,1,0]
	s_nop 0
	v_pk_fma_f32 v[142:143], v[140:141], v[142:143], s[36:37] op_sel_hi:[1,1,0]
	s_nop 0
	v_pk_fma_f32 v[142:143], v[140:141], v[142:143], s[38:39] op_sel_hi:[1,1,0]
	s_nop 0
	v_pk_fma_f32 v[142:143], v[140:141], v[142:143], s[40:41] op_sel_hi:[1,1,0]
	s_nop 0
	v_pk_fma_f32 v[142:143], v[140:141], v[142:143], s[42:43] op_sel_hi:[1,1,0]
	s_nop 0
	v_pk_fma_f32 v[140:141], v[140:141], v[142:143], s[44:45] op_sel_hi:[1,1,0]
	s_nop 0
	v_pk_mul_f32 v[136:137], v[136:137], v[140:141]
	s_nop 0
	v_pk_fma_f32 v[132:133], v[132:133], v[136:137], v[132:133]
	s_nop 0
	v_mul_f32_e32 v132, v40, v132
	v_mul_f32_e32 v140, v2, v132
	v_mul_f32_e32 v132, v41, v133
	v_mul_f32_e32 v141, v2, v132
	v_lshlrev_b32_e32 v132, 16, v161
	v_and_b32_e32 v133, 0xffff0000, v161
	v_pk_fma_f32 v[132:133], v[134:135], v[132:133], v[138:139]
	s_nop 0
	v_pk_mul_f32 v[134:135], v[132:133], s[26:27] op_sel_hi:[1,0]
	v_pk_mul_f32 v[132:133], v[132:133], 0.5 op_sel_hi:[1,0]
	v_med3_f32 v134, v134, s71, v224
	v_med3_f32 v135, v135, s71, v224
	v_pk_mul_f32 v[136:137], v[134:135], v[134:135]
	s_nop 0
	v_pk_fma_f32 v[138:139], v[136:137], s[28:29], v[148:149] op_sel_hi:[1,0,0] neg_lo:[1,0,0] neg_hi:[1,0,0]
	s_nop 0
	v_pk_fma_f32 v[138:139], v[136:137], v[138:139], s[34:35] op_sel_hi:[1,1,0]
	s_nop 0
	v_pk_fma_f32 v[138:139], v[136:137], v[138:139], s[36:37] op_sel_hi:[1,1,0]
	s_nop 0
	v_pk_fma_f32 v[138:139], v[136:137], v[138:139], s[38:39] op_sel_hi:[1,1,0]
	s_nop 0
	v_pk_fma_f32 v[138:139], v[136:137], v[138:139], s[40:41] op_sel_hi:[1,1,0]
	s_nop 0
	v_pk_fma_f32 v[138:139], v[136:137], v[138:139], s[42:43] op_sel_hi:[1,1,0]
	s_nop 0
	v_pk_fma_f32 v[136:137], v[136:137], v[138:139], s[44:45] op_sel_hi:[1,1,0]
	s_nop 0
	v_pk_mul_f32 v[134:135], v[134:135], v[136:137]
	s_nop 0
	v_pk_fma_f32 v[132:133], v[132:133], v[134:135], v[132:133]
	s_nop 0
	v_mul_f32_e32 v132, v42, v132
	v_mul_f32_e32 v134, v2, v132
	v_mul_f32_e32 v132, v43, v133
	v_mul_f32_e32 v133, v2, v132
	v_cvt_pk_bf16_f32 v132, v140, v141
	v_cvt_pk_bf16_f32 v133, v134, v133
	global_store_dwordx2 v[162:163], v[132:133], off nt
	v_add_u32_e32 v132, 0x84, v150
	v_ashrrev_i32_e32 v133, 31, v132
	v_lshlrev_b64 v[160:161], 1, v[132:133]
	v_lshl_add_u64 v[162:163], s[56:57], 0, v[160:161]
	v_lshlrev_b64 v[132:133], 2, v[132:133]
	v_mad_i64_i32 v[134:135], s[8:9], v210, s67, v[162:163]
	v_lshl_add_u64 v[182:183], s[16:17], 0, v[132:133]
	global_load_dwordx2 v[164:165], v[134:135], off
	v_mad_i64_i32 v[134:135], s[8:9], v151, s70, v[182:183]
	v_add_co_u32_e64 v136, s[8:9], s41, v134
	v_lshl_add_u64 v[152:153], v[152:153], 0, v[160:161]
	s_nop 0
	v_addc_co_u32_e64 v137, s[8:9], 0, v135, s[8:9]
	global_load_dwordx4 v[170:173], v[136:137], off offset:3072
	global_load_dwordx4 v[174:177], v[134:135], off
	v_lshl_add_u64 v[134:135], s[12:13], 0, v[132:133]
	global_load_dwordx4 v[140:143], v[134:135], off
	v_lshl_add_u64 v[134:135], s[14:15], 0, v[132:133]
	global_load_dwordx4 v[144:147], v[134:135], off
	v_lshl_add_u64 v[134:135], s[18:19], 0, v[132:133]
	global_load_dwordx4 v[136:139], v[134:135], off
	v_lshl_add_u64 v[132:133], s[20:21], 0, v[132:133]
	global_load_dwordx4 v[132:135], v[132:133], off
	v_mad_i64_i32 v[150:151], s[8:9], v194, s67, v[162:163]
	v_mad_i64_i32 v[178:179], s[8:9], v192, s67, v[162:163]
	v_mad_i64_i32 v[180:181], s[8:9], v190, s67, v[162:163]
	global_load_dwordx2 v[226:227], v[150:151], off
	global_load_dwordx2 v[162:163], v[178:179], off
	s_nop 0
	global_load_dwordx2 v[150:151], v[180:181], off
	v_mad_i64_i32 v[178:179], s[8:9], v166, s70, v[182:183]
	v_add_co_u32_e64 v212, s[8:9], s41, v178
	v_lshl_add_u64 v[154:155], v[154:155], 0, v[160:161]
	s_nop 0
	v_addc_co_u32_e64 v213, s[8:9], 0, v179, s[8:9]
	global_load_dwordx4 v[178:181], v[178:179], off
	s_nop 0
	global_load_dwordx4 v[212:215], v[212:213], off offset:3072
	v_lshl_add_u64 v[156:157], v[156:157], 0, v[160:161]
	v_lshl_add_u64 v[158:159], v[158:159], 0, v[160:161]
	s_waitcnt vmcnt(11)
;     static __device__ __forceinline__ void finish(const float (&g0)[4], const float (&g1)[4], const float (&g2)[4], const float (&w0)[4], const float (&w1)[4], const float (&w2)[4], const float (&bb)[4],
;                                                   const f32x4 v, float rs, bf16_t* dst) {
;         float h[4];
; #pragma unroll
;         for (int j = 0; j < 4; j += 2) {
;             const f32x2 gc = (f32x2){bb[j] + w0[j] * g2[j] + w1[j] * g1[j] + w2[j] * g0[j], bb[j + 1] + w0[j + 1] * g2[j + 1] + w1[j + 1] * g1[j + 1] + w2[j + 1] * g0[j + 1]};
;             const f32x2 ge = gelu_pk(gc); h[j] = ge.x * v[j] * rs; h[j + 1] = ge.y * v[j + 1] * rs; }
;     __device__ __forceinline__ void operator()(const f32x4 (&acc)[2][2][4][2], const Unit& u, int wr, int wc, int fr, int fq) const {
;     ...
;           for (int hv = 0; hv < 2; ++hv) {
;             const int col = u.pn * BM + bj * HALF + wc * 32 + 8 * fq + 4 * hv;
;             float w0[4], w1[4], w2[4], bb[4];
;             ld4f(cw + col, w0); ld4f(cw + 2816 + col, w1); ld4f(cw + 2 * 2816 + col, w2); ld4f(cb + col, bb);
;             {
;                 const int i = fr & 7;
;                 u32x2 gq[4];
; #pragma unroll
;                 for (int m = 0; m < 4; ++m) { const int row = row0 + m * 16; gq[m] = *(const u32x2*)(G + (size_t)row * 2816 + col); }
; #pragma unroll
;                 for (int mh = 0; mh < 4; mh += 2) {
;                 f32x4 c0[4], c1[4];
; #pragma unroll
;                 for (int m = mh; m < mh + 2; ++m) { const int row = row0 + m * 16; const float* cx = ctx + (size_t)((row - 32768) >> 3) * 2 * 2816 + col;
;                     c0[m] = *(const f32x4*)cx; c1[m] = *(const f32x4*)(cx + 2816); }
; #pragma unroll
;                 for (int m = mh; m < mh + 2; ++m) { const int row = row0 + m * 16; const u32x2 cur = gq[m];
;                     const u32x2 q1 = dpp_prev<1>(cur, cur), q2 = dpp_prev<2>(cur, cur);
;                     float g0[4], g1[4], g2[4]; unpk4(cur, g0); unpk4(q1, g1); unpk4(q2, g2);
; #pragma unroll
;                     for (int j = 0; j < 4; ++j) { const float x1 = c1[m][j], x0 = c0[m][j];
;                         if (i < 1) g1[j] = x1;
;                         if (i < 2) g2[j] = (i == 1) ? x1 : x0; }
;                     finish(g0, g1, g2, w0, w1, w2, bb, acc[0][bj][m][hv], rs8[0][m], H + (size_t)row * 2816 + col); }
	v_mov_b32_dpp v166, v164 row_ror:1 row_mask:0xf bank_mask:0xf bound_ctrl:1
	v_mov_b32_dpp v169, v165 row_ror:1 row_mask:0xf bank_mask:0xf bound_ctrl:1
	s_nop 0
	v_mov_b32_dpp v166, v164 row_shr:1 row_mask:0xf bank_mask:0xf
	v_mov_b32_dpp v185, v164 row_ror:2 row_mask:0xf bank_mask:0xf bound_ctrl:1
	v_mov_b32_dpp v169, v165 row_shr:1 row_mask:0xf bank_mask:0xf
	v_lshlrev_b32_e32 v189, 16, v166
	v_mov_b32_dpp v185, v164 row_shr:2 row_mask:0xf bank_mask:0xf
	v_and_b32_e32 v166, 0xffff0000, v166
	v_lshlrev_b32_e32 v191, 16, v169
	v_and_b32_e32 v169, 0xffff0000, v169
	v_lshlrev_b32_e32 v193, 16, v185
	v_and_b32_e32 v185, 0xffff0000, v185
	s_waitcnt vmcnt(10)
	v_cndmask_b32_e64 v229, v166, v171, s[6:7]
	v_cndmask_b32_e64 v231, v169, v173, s[6:7]
	s_waitcnt vmcnt(9)
	v_cndmask_b32_e32 v166, v174, v170, vcc
	v_cndmask_b32_e32 v169, v175, v171, vcc
	v_cndmask_b32_e64 v228, v189, v170, s[6:7]
	v_cndmask_b32_e64 v230, v191, v172, s[6:7]
	v_cndmask_b32_e32 v170, v176, v172, vcc
	v_cndmask_b32_e32 v171, v177, v173, vcc
	v_cndmask_b32_e64 v173, v185, v169, s[0:1]
	v_cndmask_b32_e64 v172, v193, v166, s[0:1]
	s_waitcnt vmcnt(7)
	v_pk_fma_f32 v[172:173], v[140:141], v[172:173], v[144:145]
	v_lshlrev_b32_e32 v174, 16, v164
	v_and_b32_e32 v175, 0xffff0000, v164
	s_waitcnt vmcnt(6)
	v_pk_fma_f32 v[172:173], v[136:137], v[228:229], v[172:173]
	v_mov_b32_dpp v187, v165 row_ror:2 row_mask:0xf bank_mask:0xf bound_ctrl:1
	s_waitcnt vmcnt(5)
	v_pk_fma_f32 v[172:173], v[132:133], v[174:175], v[172:173]
	s_waitcnt vmcnt(2)
	v_lshlrev_b32_e32 v160, 16, v150
	v_pk_mul_f32 v[174:175], v[172:173], s[26:27] op_sel_hi:[1,0]
	v_mov_b32_dpp v187, v165 row_shr:2 row_mask:0xf bank_mask:0xf
	v_med3_f32 v174, v174, s71, v224
	v_med3_f32 v175, v175, s71, v224
	v_pk_mul_f32 v[176:177], v[174:175], v[174:175]
	v_pk_mul_f32 v[172:173], v[172:173], 0.5 op_sel_hi:[1,0]
	v_pk_fma_f32 v[228:229], v[176:177], s[28:29], v[148:149] op_sel_hi:[1,0,0] neg_lo:[1,0,0] neg_hi:[1,0,0]
	v_lshlrev_b32_e32 v195, 16, v187
	v_pk_fma_f32 v[228:229], v[176:177], v[228:229], s[34:35] op_sel_hi:[1,1,0]
	v_and_b32_e32 v187, 0xffff0000, v187
	v_pk_fma_f32 v[228:229], v[176:177], v[228:229], s[36:37] op_sel_hi:[1,1,0]
	v_cndmask_b32_e64 v171, v187, v171, s[0:1]
	v_pk_fma_f32 v[228:229], v[176:177], v[228:229], s[38:39] op_sel_hi:[1,1,0]
	v_cndmask_b32_e64 v170, v195, v170, s[0:1]
	v_pk_fma_f32 v[228:229], v[176:177], v[228:229], s[40:41] op_sel_hi:[1,1,0]
	v_pk_fma_f32 v[170:171], v[142:143], v[170:171], v[146:147]
	v_pk_fma_f32 v[228:229], v[176:177], v[228:229], s[42:43] op_sel_hi:[1,1,0]
	v_pk_fma_f32 v[170:171], v[138:139], v[230:231], v[170:171]
	v_pk_fma_f32 v[176:177], v[176:177], v[228:229], s[44:45] op_sel_hi:[1,1,0]
	v_and_b32_e32 v161, 0xffff0000, v150
	v_pk_mul_f32 v[174:175], v[174:175], v[176:177]
	v_mov_b32_dpp v176, v162 row_ror:1 row_mask:0xf bank_mask:0xf bound_ctrl:1
	v_pk_fma_f32 v[172:173], v[172:173], v[174:175], v[172:173]
	v_mov_b32_dpp v177, v163 row_ror:1 row_mask:0xf bank_mask:0xf bound_ctrl:1
	v_mul_f32_e32 v164, v60, v172
	v_mul_f32_e32 v166, v188, v164
	v_mul_f32_e32 v164, v61, v173
	v_mul_f32_e32 v169, v188, v164
	v_lshlrev_b32_e32 v164, 16, v165
	v_and_b32_e32 v165, 0xffff0000, v165
	v_pk_fma_f32 v[164:165], v[134:135], v[164:165], v[170:171]
	v_mov_b32_dpp v176, v162 row_shr:1 row_mask:0xf bank_mask:0xf
	v_pk_mul_f32 v[170:171], v[164:165], s[26:27] op_sel_hi:[1,0]
	v_pk_mul_f32 v[164:165], v[164:165], 0.5 op_sel_hi:[1,0]
	v_med3_f32 v170, v170, s71, v224
	v_med3_f32 v171, v171, s71, v224
	v_pk_mul_f32 v[172:173], v[170:171], v[170:171]
	v_mov_b32_dpp v177, v163 row_shr:1 row_mask:0xf bank_mask:0xf
	v_pk_fma_f32 v[174:175], v[172:173], s[28:29], v[148:149] op_sel_hi:[1,0,0] neg_lo:[1,0,0] neg_hi:[1,0,0]
	s_nop 0
	v_pk_fma_f32 v[174:175], v[172:173], v[174:175], s[34:35] op_sel_hi:[1,1,0]
	s_nop 0
	v_pk_fma_f32 v[174:175], v[172:173], v[174:175], s[36:37] op_sel_hi:[1,1,0]
	s_nop 0
	v_pk_fma_f32 v[174:175], v[172:173], v[174:175], s[38:39] op_sel_hi:[1,1,0]
	s_nop 0
	v_pk_fma_f32 v[174:175], v[172:173], v[174:175], s[40:41] op_sel_hi:[1,1,0]
	s_nop 0
	v_pk_fma_f32 v[174:175], v[172:173], v[174:175], s[42:43] op_sel_hi:[1,1,0]
	s_nop 0
	v_pk_fma_f32 v[172:173], v[172:173], v[174:175], s[44:45] op_sel_hi:[1,1,0]
	s_waitcnt vmcnt(0)
;     static __device__ __forceinline__ void finish(const float (&g0)[4], const float (&g1)[4], const float (&g2)[4], const float (&w0)[4], const float (&w1)[4], const float (&w2)[4], const float (&bb)[4],
;                                                   const f32x4 v, float rs, bf16_t* dst) {
;         float h[4];
; #pragma unroll
;         for (int j = 0; j < 4; j += 2) {
;             const f32x2 gc = (f32x2){bb[j] + w0[j] * g2[j] + w1[j] * g1[j] + w2[j] * g0[j], bb[j + 1] + w0[j + 1] * g2[j + 1] + w1[j + 1] * g1[j + 1] + w2[j + 1] * g0[j + 1]};
;             const f32x2 ge = gelu_pk(gc); h[j] = ge.x * v[j] * rs; h[j + 1] = ge.y * v[j + 1] * rs; }
;     __device__ __forceinline__ void operator()(const f32x4 (&acc)[2][2][4][2], const Unit& u, int wr, int wc, int fr, int fq) const {
;     ...
;           for (int hv = 0; hv < 2; ++hv) {
;             const int col = u.pn * BM + bj * HALF + wc * 32 + 8 * fq + 4 * hv;
;             float w0[4], w1[4], w2[4], bb[4];
;             ld4f(cw + col, w0); ld4f(cw + 2816 + col, w1); ld4f(cw + 2 * 2816 + col, w2); ld4f(cb + col, bb);
;             {
;                 const int i = fr & 7;
;                 u32x2 gq[4];
; #pragma unroll
;                 for (int m = 0; m < 4; ++m) { const int row = row0 + m * 16; gq[m] = *(const u32x2*)(G + (size_t)row * 2816 + col); }
; #pragma unroll
;                 for (int mh = 0; mh < 4; mh += 2) {
;                 f32x4 c0[4], c1[4];
; #pragma unroll
;                 for (int m = mh; m < mh + 2; ++m) { const int row = row0 + m * 16; const float* cx = ctx + (size_t)((row - 32768) >> 3) * 2 * 2816 + col;
;                     c0[m] = *(const f32x4*)cx; c1[m] = *(const f32x4*)(cx + 2816); }
; #pragma unroll
;                 for (int m = mh; m < mh + 2; ++m) { const int row = row0 + m * 16; const u32x2 cur = gq[m];
;                     const u32x2 q1 = dpp_prev<1>(cur, cur), q2 = dpp_prev<2>(cur, cur);
;                     float g0[4], g1[4], g2[4]; unpk4(cur, g0); unpk4(q1, g1); unpk4(q2, g2);
; #pragma unroll
;                     for (int j = 0; j < 4; ++j) { const float x1 = c1[m][j], x0 = c0[m][j];
;                         if (i < 1) g1[j] = x1;
;                         if (i < 2) g2[j] = (i == 1) ? x1 : x0; }
;                     finish(g0, g1, g2, w0, w1, w2, bb, acc[0][bj][m][hv], rs8[0][m], H + (size_t)row * 2816 + col); }
	v_cndmask_b32_e32 v175, v181, v215, vcc
	v_pk_mul_f32 v[170:171], v[170:171], v[172:173]
	v_lshlrev_b32_e32 v181, 16, v177
	v_pk_fma_f32 v[164:165], v[164:165], v[170:171], v[164:165]
	s_nop 0
	v_mul_f32_e32 v164, v62, v164
	v_mul_f32_e32 v170, v188, v164
	v_mul_f32_e32 v164, v63, v165
	v_mul_f32_e32 v165, v188, v164
	v_cvt_pk_bf16_f32 v164, v166, v169
	v_cvt_pk_bf16_f32 v165, v170, v165
	global_store_dwordx2 v[152:153], v[164:165], off nt
	v_mov_b32_dpp v152, v226 row_ror:1 row_mask:0xf bank_mask:0xf bound_ctrl:1
	v_mov_b32_dpp v153, v227 row_ror:1 row_mask:0xf bank_mask:0xf bound_ctrl:1
	v_mov_b32_dpp v164, v226 row_ror:2 row_mask:0xf bank_mask:0xf bound_ctrl:1
	v_mov_b32_dpp v152, v226 row_shr:1 row_mask:0xf bank_mask:0xf
	v_mov_b32_dpp v153, v227 row_shr:1 row_mask:0xf bank_mask:0xf
	v_mov_b32_dpp v164, v226 row_shr:2 row_mask:0xf bank_mask:0xf
	v_lshlrev_b32_e32 v166, 16, v152
	v_and_b32_e32 v152, 0xffff0000, v152
	v_lshlrev_b32_e32 v169, 16, v153
	v_mov_b32_dpp v165, v227 row_ror:2 row_mask:0xf bank_mask:0xf bound_ctrl:1
	v_and_b32_e32 v170, 0xffff0000, v153
	v_lshlrev_b32_e32 v172, 16, v164
	v_and_b32_e32 v173, 0xffff0000, v164
	v_cndmask_b32_e64 v153, v152, v213, s[6:7]
	v_cndmask_b32_e64 v152, v166, v212, s[6:7]
	v_cndmask_b32_e64 v164, v169, v214, s[6:7]
	v_cndmask_b32_e32 v166, v178, v212, vcc
	v_cndmask_b32_e32 v169, v179, v213, vcc
	v_mov_b32_dpp v165, v227 row_shr:2 row_mask:0xf bank_mask:0xf
	v_cndmask_b32_e64 v173, v173, v169, s[0:1]
	v_cndmask_b32_e64 v172, v172, v166, s[0:1]
	v_lshlrev_b32_e32 v174, 16, v165
	v_and_b32_e32 v171, 0xffff0000, v165
	v_cndmask_b32_e64 v165, v170, v215, s[6:7]
	v_cndmask_b32_e32 v170, v180, v214, vcc
	v_pk_fma_f32 v[172:173], v[140:141], v[172:173], v[144:145]
	v_cndmask_b32_e64 v171, v171, v175, s[0:1]
	v_cndmask_b32_e64 v170, v174, v170, s[0:1]
	v_lshlrev_b32_e32 v174, 16, v226
	v_and_b32_e32 v175, 0xffff0000, v226
	v_pk_fma_f32 v[152:153], v[136:137], v[152:153], v[172:173]
	v_pk_fma_f32 v[170:171], v[142:143], v[170:171], v[146:147]
	v_pk_fma_f32 v[152:153], v[132:133], v[174:175], v[152:153]
	v_pk_fma_f32 v[164:165], v[138:139], v[164:165], v[170:171]
	v_pk_mul_f32 v[170:171], v[152:153], s[26:27] op_sel_hi:[1,0]
	v_pk_mul_f32 v[152:153], v[152:153], 0.5 op_sel_hi:[1,0]
	v_med3_f32 v170, v170, s71, v224
	v_med3_f32 v171, v171, s71, v224
	v_pk_mul_f32 v[172:173], v[170:171], v[170:171]
	v_mov_b32_dpp v178, v162 row_ror:2 row_mask:0xf bank_mask:0xf bound_ctrl:1
	v_pk_fma_f32 v[174:175], v[172:173], s[28:29], v[148:149] op_sel_hi:[1,0,0] neg_lo:[1,0,0] neg_hi:[1,0,0]
	v_mov_b32_dpp v179, v163 row_ror:2 row_mask:0xf bank_mask:0xf bound_ctrl:1
	v_pk_fma_f32 v[174:175], v[172:173], v[174:175], s[34:35] op_sel_hi:[1,1,0]
	v_mov_b32_dpp v178, v162 row_shr:2 row_mask:0xf bank_mask:0xf
	v_pk_fma_f32 v[174:175], v[172:173], v[174:175], s[36:37] op_sel_hi:[1,1,0]
	v_mov_b32_dpp v179, v163 row_shr:2 row_mask:0xf bank_mask:0xf
	v_pk_fma_f32 v[174:175], v[172:173], v[174:175], s[38:39] op_sel_hi:[1,1,0]
	v_lshlrev_b32_e32 v180, 16, v176
	v_pk_fma_f32 v[174:175], v[172:173], v[174:175], s[40:41] op_sel_hi:[1,1,0]
	v_and_b32_e32 v176, 0xffff0000, v176
	v_pk_fma_f32 v[174:175], v[172:173], v[174:175], s[42:43] op_sel_hi:[1,1,0]
	v_and_b32_e32 v185, 0xffff0000, v178
	v_pk_fma_f32 v[172:173], v[172:173], v[174:175], s[44:45] op_sel_hi:[1,1,0]
	v_lshlrev_b32_e32 v187, 16, v179
	v_pk_mul_f32 v[170:171], v[170:171], v[172:173]
	v_and_b32_e32 v189, 0xffff0000, v179
	v_pk_fma_f32 v[152:153], v[152:153], v[170:171], v[152:153]
	s_nop 0
	v_mul_f32_e32 v152, v52, v152
	v_mul_f32_e32 v166, v186, v152
	v_mul_f32_e32 v152, v53, v153
	v_mul_f32_e32 v169, v186, v152
	v_lshlrev_b32_e32 v152, 16, v227
	v_and_b32_e32 v153, 0xffff0000, v227
	v_pk_fma_f32 v[152:153], v[134:135], v[152:153], v[164:165]
	s_nop 0
	v_pk_mul_f32 v[164:165], v[152:153], s[26:27] op_sel_hi:[1,0]
	v_pk_mul_f32 v[152:153], v[152:153], 0.5 op_sel_hi:[1,0]
	v_med3_f32 v164, v164, s71, v224
	v_med3_f32 v165, v165, s71, v224
	v_pk_mul_f32 v[170:171], v[164:165], v[164:165]
	s_nop 0
	v_pk_fma_f32 v[172:173], v[170:171], s[28:29], v[148:149] op_sel_hi:[1,0,0] neg_lo:[1,0,0] neg_hi:[1,0,0]
	s_nop 0
	v_pk_fma_f32 v[172:173], v[170:171], v[172:173], s[34:35] op_sel_hi:[1,1,0]
	s_nop 0
	v_pk_fma_f32 v[172:173], v[170:171], v[172:173], s[36:37] op_sel_hi:[1,1,0]
	s_nop 0
	v_pk_fma_f32 v[172:173], v[170:171], v[172:173], s[38:39] op_sel_hi:[1,1,0]
	s_nop 0
	v_pk_fma_f32 v[172:173], v[170:171], v[172:173], s[40:41] op_sel_hi:[1,1,0]
	s_nop 0
	v_pk_fma_f32 v[172:173], v[170:171], v[172:173], s[42:43] op_sel_hi:[1,1,0]
	s_nop 0
	v_pk_fma_f32 v[170:171], v[170:171], v[172:173], s[44:45] op_sel_hi:[1,1,0]
	s_nop 0
	v_pk_mul_f32 v[164:165], v[164:165], v[170:171]
	s_nop 0
	v_pk_fma_f32 v[152:153], v[152:153], v[164:165], v[152:153]
	s_nop 0
	v_mul_f32_e32 v152, v54, v152
	v_mul_f32_e32 v164, v186, v152
	v_mul_f32_e32 v152, v55, v153
	v_mul_f32_e32 v153, v186, v152
	v_cvt_pk_bf16_f32 v152, v166, v169
	v_cvt_pk_bf16_f32 v153, v164, v153
	v_mad_i64_i32 v[164:165], s[8:9], v167, s70, v[182:183]
	global_store_dwordx2 v[154:155], v[152:153], off nt
	v_add_co_u32_e64 v152, s[8:9], s41, v164
	s_nop 1
	v_addc_co_u32_e64 v153, s[8:9], 0, v165, s[8:9]
	global_load_dwordx4 v[152:155], v[152:153], off offset:3072
	s_nop 0
	global_load_dwordx4 v[164:167], v[164:165], off
	v_mad_i64_i32 v[168:169], s[8:9], v168, s70, v[182:183]
	v_add_co_u32_e64 v172, s[8:9], s41, v168
	v_and_b32_e32 v182, 0xffff0000, v177
	s_nop 0
	v_addc_co_u32_e64 v173, s[8:9], 0, v169, s[8:9]
	global_load_dwordx4 v[168:171], v[168:169], off
	s_nop 0
	global_load_dwordx4 v[172:175], v[172:173], off offset:3072
	v_lshlrev_b32_e32 v183, 16, v178
	s_waitcnt vmcnt(3)
;     static __device__ __forceinline__ void finish(const float (&g0)[4], const float (&g1)[4], const float (&g2)[4], const float (&w0)[4], const float (&w1)[4], const float (&w2)[4], const float (&bb)[4],
;                                                   const f32x4 v, float rs, bf16_t* dst) {
;         float h[4];
; #pragma unroll
;         for (int j = 0; j < 4; j += 2) {
;             const f32x2 gc = (f32x2){bb[j] + w0[j] * g2[j] + w1[j] * g1[j] + w2[j] * g0[j], bb[j + 1] + w0[j + 1] * g2[j + 1] + w1[j + 1] * g1[j + 1] + w2[j + 1] * g0[j + 1]};
;             const f32x2 ge = gelu_pk(gc); h[j] = ge.x * v[j] * rs; h[j + 1] = ge.y * v[j + 1] * rs; }
;     __device__ __forceinline__ void operator()(const f32x4 (&acc)[2][2][4][2], const Unit& u, int wr, int wc, int fr, int fq) const {
;     ...
;           for (int hv = 0; hv < 2; ++hv) {
;             const int col = u.pn * BM + bj * HALF + wc * 32 + 8 * fq + 4 * hv;
;             float w0[4], w1[4], w2[4], bb[4];
;             ld4f(cw + col, w0); ld4f(cw + 2816 + col, w1); ld4f(cw + 2 * 2816 + col, w2); ld4f(cb + col, bb);
;             {
;                 const int i = fr & 7;
;                 u32x2 gq[4];
; #pragma unroll
;                 for (int m = 0; m < 4; ++m) { const int row = row0 + m * 16; gq[m] = *(const u32x2*)(G + (size_t)row * 2816 + col); }
; #pragma unroll
;                 for (int mh = 0; mh < 4; mh += 2) {
;                 f32x4 c0[4], c1[4];
; #pragma unroll
;                 for (int m = mh; m < mh + 2; ++m) { const int row = row0 + m * 16; const float* cx = ctx + (size_t)((row - 32768) >> 3) * 2 * 2816 + col;
;                     c0[m] = *(const f32x4*)cx; c1[m] = *(const f32x4*)(cx + 2816); }
; #pragma unroll
;                 for (int m = mh; m < mh + 2; ++m) { const int row = row0 + m * 16; const u32x2 cur = gq[m];
;                     const u32x2 q1 = dpp_prev<1>(cur, cur), q2 = dpp_prev<2>(cur, cur);
;                     float g0[4], g1[4], g2[4]; unpk4(cur, g0); unpk4(q1, g1); unpk4(q2, g2);
; #pragma unroll
;                     for (int j = 0; j < 4; ++j) { const float x1 = c1[m][j], x0 = c0[m][j];
;                         if (i < 1) g1[j] = x1;
;                         if (i < 2) g2[j] = (i == 1) ? x1 : x0; }
;                     finish(g0, g1, g2, w0, w1, w2, bb, acc[0][bj][m][hv], rs8[0][m], H + (size_t)row * 2816 + col); }
	v_cndmask_b32_e64 v177, v176, v153, s[6:7]
	s_waitcnt vmcnt(2)
	v_cndmask_b32_e32 v164, v164, v152, vcc
	v_cndmask_b32_e32 v165, v165, v153, vcc
	v_cndmask_b32_e64 v176, v180, v152, s[6:7]
	v_cndmask_b32_e64 v179, v182, v155, s[6:7]
	v_cndmask_b32_e64 v178, v181, v154, s[6:7]
	v_cndmask_b32_e32 v152, v166, v154, vcc
	v_cndmask_b32_e32 v153, v167, v155, vcc
	v_cndmask_b32_e64 v155, v185, v165, s[0:1]
	v_cndmask_b32_e64 v154, v183, v164, s[0:1]
	v_pk_fma_f32 v[154:155], v[140:141], v[154:155], v[144:145]
	v_lshlrev_b32_e32 v164, 16, v162
	v_and_b32_e32 v165, 0xffff0000, v162
	v_pk_fma_f32 v[154:155], v[136:137], v[176:177], v[154:155]
	v_cndmask_b32_e64 v153, v189, v153, s[0:1]
	v_pk_fma_f32 v[154:155], v[132:133], v[164:165], v[154:155]
	v_cndmask_b32_e64 v152, v187, v152, s[0:1]
	v_pk_mul_f32 v[164:165], v[154:155], s[26:27] op_sel_hi:[1,0]
	v_pk_mul_f32 v[154:155], v[154:155], 0.5 op_sel_hi:[1,0]
	v_med3_f32 v164, v164, s71, v224
	v_med3_f32 v165, v165, s71, v224
	v_pk_mul_f32 v[166:167], v[164:165], v[164:165]
	v_pk_fma_f32 v[152:153], v[142:143], v[152:153], v[146:147]
	v_pk_fma_f32 v[176:177], v[166:167], s[28:29], v[148:149] op_sel_hi:[1,0,0] neg_lo:[1,0,0] neg_hi:[1,0,0]
	v_pk_fma_f32 v[152:153], v[138:139], v[178:179], v[152:153]
	v_pk_fma_f32 v[176:177], v[166:167], v[176:177], s[34:35] op_sel_hi:[1,1,0]
	s_nop 0
	v_pk_fma_f32 v[176:177], v[166:167], v[176:177], s[36:37] op_sel_hi:[1,1,0]
	s_nop 0
	v_pk_fma_f32 v[176:177], v[166:167], v[176:177], s[38:39] op_sel_hi:[1,1,0]
	s_nop 0
	v_pk_fma_f32 v[176:177], v[166:167], v[176:177], s[40:41] op_sel_hi:[1,1,0]
	s_nop 0
	v_pk_fma_f32 v[176:177], v[166:167], v[176:177], s[42:43] op_sel_hi:[1,1,0]
	s_nop 0
	v_pk_fma_f32 v[166:167], v[166:167], v[176:177], s[44:45] op_sel_hi:[1,1,0]
	s_nop 0
	v_pk_mul_f32 v[164:165], v[164:165], v[166:167]
	s_nop 0
	v_pk_fma_f32 v[154:155], v[154:155], v[164:165], v[154:155]
	s_nop 0
	v_mul_f32_e32 v154, v44, v154
	v_mul_f32_e32 v166, v184, v154
	v_mul_f32_e32 v154, v45, v155
	v_mul_f32_e32 v167, v184, v154
	v_lshlrev_b32_e32 v154, 16, v163
	v_and_b32_e32 v155, 0xffff0000, v163
	v_pk_fma_f32 v[152:153], v[134:135], v[154:155], v[152:153]
	s_nop 0
	v_pk_mul_f32 v[154:155], v[152:153], s[26:27] op_sel_hi:[1,0]
	v_pk_mul_f32 v[152:153], v[152:153], 0.5 op_sel_hi:[1,0]
	v_med3_f32 v154, v154, s71, v224
	v_med3_f32 v155, v155, s71, v224
	v_pk_mul_f32 v[162:163], v[154:155], v[154:155]
	s_nop 0
	v_pk_fma_f32 v[164:165], v[162:163], s[28:29], v[148:149] op_sel_hi:[1,0,0] neg_lo:[1,0,0] neg_hi:[1,0,0]
	s_nop 0
	v_pk_fma_f32 v[164:165], v[162:163], v[164:165], s[34:35] op_sel_hi:[1,1,0]
	s_nop 0
	v_pk_fma_f32 v[164:165], v[162:163], v[164:165], s[36:37] op_sel_hi:[1,1,0]
	s_nop 0
	v_pk_fma_f32 v[164:165], v[162:163], v[164:165], s[38:39] op_sel_hi:[1,1,0]
	s_nop 0
	v_pk_fma_f32 v[164:165], v[162:163], v[164:165], s[40:41] op_sel_hi:[1,1,0]
	s_nop 0
	v_pk_fma_f32 v[164:165], v[162:163], v[164:165], s[42:43] op_sel_hi:[1,1,0]
	s_nop 0
	v_pk_fma_f32 v[162:163], v[162:163], v[164:165], s[44:45] op_sel_hi:[1,1,0]
	s_nop 0
	v_pk_mul_f32 v[154:155], v[154:155], v[162:163]
	s_nop 0
	v_pk_fma_f32 v[152:153], v[152:153], v[154:155], v[152:153]
	v_mov_b32_dpp v155, v151 row_ror:2 row_mask:0xf bank_mask:0xf bound_ctrl:1
	v_mul_f32_e32 v152, v46, v152
	v_mul_f32_e32 v154, v184, v152
	v_mul_f32_e32 v152, v47, v153
	v_mul_f32_e32 v153, v184, v152
	v_cvt_pk_bf16_f32 v152, v166, v167
	v_cvt_pk_bf16_f32 v153, v154, v153
	global_store_dwordx2 v[156:157], v[152:153], off nt
	v_mov_b32_dpp v154, v150 row_ror:2 row_mask:0xf bank_mask:0xf bound_ctrl:1
	v_mov_b32_dpp v153, v151 row_ror:1 row_mask:0xf bank_mask:0xf bound_ctrl:1
	v_mov_b32_dpp v152, v150 row_ror:1 row_mask:0xf bank_mask:0xf bound_ctrl:1
	v_mov_b32_dpp v154, v150 row_shr:2 row_mask:0xf bank_mask:0xf
	v_mov_b32_dpp v153, v151 row_shr:1 row_mask:0xf bank_mask:0xf
	v_mov_b32_dpp v155, v151 row_shr:2 row_mask:0xf bank_mask:0xf
	v_and_b32_e32 v162, 0xffff0000, v153
	v_mov_b32_dpp v152, v150 row_shr:1 row_mask:0xf bank_mask:0xf
	v_lshlrev_b32_e32 v164, 16, v154
	v_and_b32_e32 v163, 0xffff0000, v154
	v_lshlrev_b32_e32 v165, 16, v155
	v_and_b32_e32 v166, 0xffff0000, v155
	s_waitcnt vmcnt(1)
;     static __device__ __forceinline__ void finish(const float (&g0)[4], const float (&g1)[4], const float (&g2)[4], const float (&w0)[4], const float (&w1)[4], const float (&w2)[4], const float (&bb)[4],
;                                                   const f32x4 v, float rs, bf16_t* dst) {
;         float h[4];
; #pragma unroll
;         for (int j = 0; j < 4; j += 2) {
;             const f32x2 gc = (f32x2){bb[j] + w0[j] * g2[j] + w1[j] * g1[j] + w2[j] * g0[j], bb[j + 1] + w0[j + 1] * g2[j + 1] + w1[j + 1] * g1[j + 1] + w2[j + 1] * g0[j + 1]};
;             const f32x2 ge = gelu_pk(gc); h[j] = ge.x * v[j] * rs; h[j + 1] = ge.y * v[j + 1] * rs; }
;     __device__ __forceinline__ void operator()(const f32x4 (&acc)[2][2][4][2], const Unit& u, int wr, int wc, int fr, int fq) const {
;     ...
;           for (int hv = 0; hv < 2; ++hv) {
;             const int col = u.pn * BM + bj * HALF + wc * 32 + 8 * fq + 4 * hv;
;             float w0[4], w1[4], w2[4], bb[4];
;             ld4f(cw + col, w0); ld4f(cw + 2816 + col, w1); ld4f(cw + 2 * 2816 + col, w2); ld4f(cb + col, bb);
;             {
;                 const int i = fr & 7;
;                 u32x2 gq[4];
; #pragma unroll
;                 for (int m = 0; m < 4; ++m) { const int row = row0 + m * 16; gq[m] = *(const u32x2*)(G + (size_t)row * 2816 + col); }
; #pragma unroll
;                 for (int mh = 0; mh < 4; mh += 2) {
;                 f32x4 c0[4], c1[4];
; #pragma unroll
;                 for (int m = mh; m < mh + 2; ++m) { const int row = row0 + m * 16; const float* cx = ctx + (size_t)((row - 32768) >> 3) * 2 * 2816 + col;
;                     c0[m] = *(const f32x4*)cx; c1[m] = *(const f32x4*)(cx + 2816); }
; #pragma unroll
;                 for (int m = mh; m < mh + 2; ++m) { const int row = row0 + m * 16; const u32x2 cur = gq[m];
;                     const u32x2 q1 = dpp_prev<1>(cur, cur), q2 = dpp_prev<2>(cur, cur);
;                     float g0[4], g1[4], g2[4]; unpk4(cur, g0); unpk4(q1, g1); unpk4(q2, g2);
; #pragma unroll
;                     for (int j = 0; j < 4; ++j) { const float x1 = c1[m][j], x0 = c0[m][j];
;                         if (i < 1) g1[j] = x1;
;                         if (i < 2) g2[j] = (i == 1) ? x1 : x0; }
;                     finish(g0, g1, g2, w0, w1, w2, bb, acc[0][bj][m][hv], rs8[0][m], H + (size_t)row * 2816 + col); }
	v_cndmask_b32_e64 v155, v162, v175, s[6:7]
	v_cndmask_b32_e32 v162, v168, v172, vcc
	v_cndmask_b32_e32 v167, v169, v173, vcc
	v_lshlrev_b32_e32 v156, 16, v152
	v_and_b32_e32 v152, 0xffff0000, v152
	v_cndmask_b32_e64 v163, v163, v167, s[0:1]
	v_cndmask_b32_e64 v162, v164, v162, s[0:1]
	v_lshlrev_b32_e32 v157, 16, v153
	v_cndmask_b32_e64 v153, v152, v173, s[6:7]
	v_cndmask_b32_e64 v152, v156, v172, s[6:7]
	v_pk_fma_f32 v[140:141], v[140:141], v[162:163], v[144:145]
	v_cndmask_b32_e64 v154, v157, v174, s[6:7]
	v_pk_fma_f32 v[136:137], v[136:137], v[152:153], v[140:141]
	v_cndmask_b32_e32 v156, v170, v174, vcc
	v_pk_fma_f32 v[132:133], v[132:133], v[160:161], v[136:137]
	v_cndmask_b32_e32 v157, v171, v175, vcc
	v_pk_mul_f32 v[136:137], v[132:133], s[26:27] op_sel_hi:[1,0]
	v_cndmask_b32_e64 v157, v166, v157, s[0:1]
	v_cndmask_b32_e64 v156, v165, v156, s[0:1]
	v_med3_f32 v136, v136, s71, v224
	v_med3_f32 v137, v137, s71, v224
	v_pk_fma_f32 v[142:143], v[142:143], v[156:157], v[146:147]
	v_pk_mul_f32 v[140:141], v[136:137], v[136:137]
	v_pk_fma_f32 v[138:139], v[138:139], v[154:155], v[142:143]
	v_pk_fma_f32 v[142:143], v[140:141], s[28:29], v[148:149] op_sel_hi:[1,0,0] neg_lo:[1,0,0] neg_hi:[1,0,0]
	v_pk_mul_f32 v[132:133], v[132:133], 0.5 op_sel_hi:[1,0]
	v_pk_fma_f32 v[142:143], v[140:141], v[142:143], s[34:35] op_sel_hi:[1,1,0]
	s_nop 0
	v_pk_fma_f32 v[142:143], v[140:141], v[142:143], s[36:37] op_sel_hi:[1,1,0]
	s_nop 0
	v_pk_fma_f32 v[142:143], v[140:141], v[142:143], s[38:39] op_sel_hi:[1,1,0]
	s_nop 0
	v_pk_fma_f32 v[142:143], v[140:141], v[142:143], s[40:41] op_sel_hi:[1,1,0]
	s_nop 0
	v_pk_fma_f32 v[142:143], v[140:141], v[142:143], s[42:43] op_sel_hi:[1,1,0]
	s_nop 0
	v_pk_fma_f32 v[140:141], v[140:141], v[142:143], s[44:45] op_sel_hi:[1,1,0]
	s_nop 0
	v_pk_mul_f32 v[136:137], v[136:137], v[140:141]
	s_nop 0
	v_pk_fma_f32 v[132:133], v[132:133], v[136:137], v[132:133]
	s_nop 0
	v_mul_f32_e32 v132, v36, v132
	v_mul_f32_e32 v140, v2, v132
	v_mul_f32_e32 v132, v37, v133
	v_mul_f32_e32 v141, v2, v132
	v_lshlrev_b32_e32 v132, 16, v151
	v_and_b32_e32 v133, 0xffff0000, v151
	v_pk_fma_f32 v[132:133], v[134:135], v[132:133], v[138:139]
	s_nop 0
	v_pk_mul_f32 v[134:135], v[132:133], s[26:27] op_sel_hi:[1,0]
	v_pk_mul_f32 v[132:133], v[132:133], 0.5 op_sel_hi:[1,0]
	v_med3_f32 v134, v134, s71, v224
	v_med3_f32 v135, v135, s71, v224
	v_pk_mul_f32 v[136:137], v[134:135], v[134:135]
	s_nop 0
	v_pk_fma_f32 v[138:139], v[136:137], s[28:29], v[148:149] op_sel_hi:[1,0,0] neg_lo:[1,0,0] neg_hi:[1,0,0]
	s_nop 0
	v_pk_fma_f32 v[138:139], v[136:137], v[138:139], s[34:35] op_sel_hi:[1,1,0]
	s_nop 0
	v_pk_fma_f32 v[138:139], v[136:137], v[138:139], s[36:37] op_sel_hi:[1,1,0]
	s_nop 0
	v_pk_fma_f32 v[138:139], v[136:137], v[138:139], s[38:39] op_sel_hi:[1,1,0]
	s_nop 0
	v_pk_fma_f32 v[138:139], v[136:137], v[138:139], s[40:41] op_sel_hi:[1,1,0]
	s_nop 0
	v_pk_fma_f32 v[138:139], v[136:137], v[138:139], s[42:43] op_sel_hi:[1,1,0]
	s_nop 0
	v_pk_fma_f32 v[136:137], v[136:137], v[138:139], s[44:45] op_sel_hi:[1,1,0]
	s_nop 0
	v_pk_mul_f32 v[134:135], v[134:135], v[136:137]
	s_nop 0
	v_pk_fma_f32 v[132:133], v[132:133], v[134:135], v[132:133]
	s_nop 0
	v_mul_f32_e32 v132, v38, v132
	v_mul_f32_e32 v134, v2, v132
	v_mul_f32_e32 v132, v39, v133
	v_mul_f32_e32 v133, v2, v132
	v_cvt_pk_bf16_f32 v132, v140, v141
	v_cvt_pk_bf16_f32 v133, v134, v133
	global_store_dwordx2 v[158:159], v[132:133], off nt
	s_cbranch_execz .LBB0_3142

; __device__ __forceinline__ unsigned cvt_pk_bf16(float lo, float hi) { unsigned r; asm volatile("v_cvt_pk_bf16_f32 %0, %1, %2" : "=v"(r) : "v"(lo), "v"(hi)); return r; }
;     static __device__ __forceinline__ u32x2 finish2(const float (&g0)[4], const float (&g1)[4], const float (&g2)[4], const float (&w0)[4], const float (&w1)[4], const float (&w2)[4], const float (&bb)[4],
;                                                     const f32x4 v, float rs) {
;         float h[4];
; #pragma unroll
;         for (int j = 0; j < 4; j += 2) {
;             const f32x2 gc = (f32x2){bb[j] + w0[j] * g2[j] + w1[j] * g1[j] + w2[j] * g0[j], bb[j + 1] + w0[j + 1] * g2[j + 1] + w1[j + 1] * g1[j + 1] + w2[j + 1] * g0[j + 1]};
;             const f32x2 ge = gelu_pk(gc) * ((f32x2){v[j], v[j + 1]} * rs); h[j] = ge.x; h[j + 1] = ge.y; }
;         u32x2 w; w.x = cvt_pk_bf16(h[0], h[1]); w.y = cvt_pk_bf16(h[2], h[3]); return w;
;     }
;     __device__ __forceinline__ void operator()(const f32x4 (&acc)[2][2][4][2], const Unit& u, int wr, int wc, int fr, int fq) const {
;     ...
;             for (int ai = 0; ai < 2; ++ai) { const int R0 = u.rb + ai * HALF + wr * 64; const bf16_t* gp = G + (size_t)(R0 + fr) * 2816 + col8;
;                 u32x4 gq[4], prv = (u32x4){0u, 0u, 0u, 0u};
; #pragma unroll
;                 for (int m = 0; m < 4; ++m) gq[m] = *(const u32x4*)(gp + (size_t)m * 16 * 2816);
;                 if ((R0 & 8191) != 0) prv = *(const u32x4*)(gp - (size_t)16 * 2816);
;                 u32x4 pv = prv;
; #pragma unroll
;                 for (int m = 0; m < 4; ++m) { const u32x4 cur = gq[m]; u32x4 hw;
; #pragma unroll
;                     for (int hv = 0; hv < 2; ++hv) { const u32x2 c2 = half2(cur, hv), p2 = half2(pv, hv);
;                         const u32x2 q1 = dpp_prev<1>(p2, c2), q2 = dpp_prev<2>(p2, c2);
;                         float g0[4], g1[4], g2[4]; unpk4(c2, g0); unpk4(q1, g1); unpk4(q2, g2);
;                         const u32x2 r = finish2(g0, g1, g2, w0[hv], w1[hv], w2[hv], bb[hv], acc[ai][bj][m][hv], rs8[ai][m]);
;                         if (hv == 0) { hw.x = r.x; hw.y = r.y; } else { hw.z = r.x; hw.w = r.y; } }
;                     *(u32x4*)(H + (size_t)(R0 + fr + 16 * m) * 2816 + col8) = hw;
;                     pv = cur; } }
.LBB0_3145:
	s_waitcnt vmcnt(0)
	v_mov_b32_dpp v195, v180 row_ror:2 row_mask:0xf bank_mask:0xf bound_ctrl:1
	v_mov_b32_dpp v191, v180 row_ror:1 row_mask:0xf bank_mask:0xf bound_ctrl:1
	v_mad_i64_i32 v[230:231], s[0:1], v210, s67, 0
	v_mov_b32_dpp v195, v176 row_shr:2 row_mask:0xf bank_mask:0xf
	v_mov_b32_dpp v191, v176 row_shr:1 row_mask:0xf bank_mask:0xf
	v_lshlrev_b32_e32 v210, 16, v195
	v_and_b32_e32 v211, 0xffff0000, v195
	v_mov_b32_dpp v193, v181 row_ror:1 row_mask:0xf bank_mask:0xf bound_ctrl:1
	v_mov_b32_dpp v225, v181 row_ror:2 row_mask:0xf bank_mask:0xf bound_ctrl:1
	v_lshlrev_b32_e32 v180, 16, v191
	v_and_b32_e32 v181, 0xffff0000, v191
	v_pk_fma_f32 v[210:211], v[148:149], v[210:211], v[160:161]
	v_lshlrev_b32_e32 v232, 16, v176
	v_and_b32_e32 v233, 0xffff0000, v176
	v_pk_fma_f32 v[180:181], v[152:153], v[180:181], v[210:211]
	v_mov_b32_dpp v225, v177 row_shr:2 row_mask:0xf bank_mask:0xf
	v_pk_fma_f32 v[180:181], v[156:157], v[232:233], v[180:181]
	v_mov_b32_dpp v193, v177 row_shr:1 row_mask:0xf bank_mask:0xf
	v_pk_mul_f32 v[210:211], v[180:181], s[26:27] op_sel_hi:[1,0]
	v_lshlrev_b32_e32 v228, 16, v225
	v_med3_f32 v232, v210, s71, v224
	v_med3_f32 v233, v211, s71, v224
	v_pk_mul_f32 v[234:235], v[232:233], v[232:233]
	v_mov_b64_e32 v[210:211], s[30:31]
	v_pk_fma_f32 v[236:237], v[234:235], s[28:29], v[210:211] op_sel_hi:[1,0,0] neg_lo:[1,0,0] neg_hi:[1,0,0]
	v_and_b32_e32 v229, 0xffff0000, v225
	v_pk_fma_f32 v[236:237], v[234:235], v[236:237], s[34:35] op_sel_hi:[1,1,0]
	v_pk_mul_f32 v[180:181], v[180:181], 0.5 op_sel_hi:[1,0]
	v_pk_fma_f32 v[236:237], v[234:235], v[236:237], s[36:37] op_sel_hi:[1,1,0]
	v_lshlrev_b32_e32 v226, 16, v193
	v_pk_fma_f32 v[236:237], v[234:235], v[236:237], s[38:39] op_sel_hi:[1,1,0]
	v_and_b32_e32 v227, 0xffff0000, v193
	v_pk_fma_f32 v[236:237], v[234:235], v[236:237], s[40:41] op_sel_hi:[1,1,0]
	v_pk_mul_f32 v[128:129], v[128:129], v[188:189] op_sel_hi:[1,0]
	v_pk_fma_f32 v[236:237], v[234:235], v[236:237], s[42:43] op_sel_hi:[1,1,0]
	v_pk_fma_f32 v[228:229], v[150:151], v[228:229], v[162:163]
	v_pk_fma_f32 v[234:235], v[234:235], v[236:237], s[44:45] op_sel_hi:[1,1,0]
	v_pk_fma_f32 v[226:227], v[154:155], v[226:227], v[228:229]
	v_pk_mul_f32 v[232:233], v[232:233], v[234:235]
	v_pk_mul_f32 v[130:131], v[130:131], v[188:189] op_sel_hi:[1,0]
	v_pk_fma_f32 v[180:181], v[180:181], v[232:233], v[180:181]
	v_pk_mul_f32 v[124:125], v[124:125], v[188:189] op_sel_hi:[1,0]
	v_pk_mul_f32 v[128:129], v[128:129], v[180:181]
	v_lshlrev_b32_e32 v180, 16, v177
	v_and_b32_e32 v181, 0xffff0000, v177
	v_pk_fma_f32 v[180:181], v[158:159], v[180:181], v[226:227]
	v_readlane_b32 s0, v240, 58
	v_pk_mul_f32 v[226:227], v[180:181], s[26:27] op_sel_hi:[1,0]
	v_pk_mul_f32 v[180:181], v[180:181], 0.5 op_sel_hi:[1,0]
	v_med3_f32 v226, v226, s71, v224
	v_med3_f32 v227, v227, s71, v224
	v_pk_mul_f32 v[228:229], v[226:227], v[226:227]
	v_readlane_b32 s1, v240, 59
	v_pk_fma_f32 v[232:233], v[228:229], s[28:29], v[210:211] op_sel_hi:[1,0,0] neg_lo:[1,0,0] neg_hi:[1,0,0]
	v_pk_mul_f32 v[126:127], v[126:127], v[188:189] op_sel_hi:[1,0]
	v_pk_fma_f32 v[232:233], v[228:229], v[232:233], s[34:35] op_sel_hi:[1,1,0]
	v_pk_mul_f32 v[120:121], v[120:121], v[186:187] op_sel_hi:[1,0]
	v_pk_fma_f32 v[232:233], v[228:229], v[232:233], s[36:37] op_sel_hi:[1,1,0]
	v_pk_mul_f32 v[122:123], v[122:123], v[186:187] op_sel_hi:[1,0]
	v_pk_fma_f32 v[232:233], v[228:229], v[232:233], s[38:39] op_sel_hi:[1,1,0]
	v_pk_mul_f32 v[116:117], v[116:117], v[186:187] op_sel_hi:[1,0]
	v_pk_fma_f32 v[232:233], v[228:229], v[232:233], s[40:41] op_sel_hi:[1,1,0]
	v_pk_mul_f32 v[118:119], v[118:119], v[186:187] op_sel_hi:[1,0]
	v_pk_fma_f32 v[232:233], v[228:229], v[232:233], s[42:43] op_sel_hi:[1,1,0]
	v_pk_mul_f32 v[112:113], v[112:113], v[184:185] op_sel_hi:[1,0]
	v_pk_fma_f32 v[228:229], v[228:229], v[232:233], s[44:45] op_sel_hi:[1,1,0]
	v_pk_mul_f32 v[114:115], v[114:115], v[184:185] op_sel_hi:[1,0]
	v_pk_mul_f32 v[226:227], v[226:227], v[228:229]
	v_lshlrev_b32_e32 v228, 16, v178
	v_pk_fma_f32 v[180:181], v[180:181], v[226:227], v[180:181]
	v_cvt_pk_bf16_f32 v226, v128, v129
	v_mov_b32_dpp v129, v182 row_ror:1 row_mask:0xf bank_mask:0xf bound_ctrl:1
	v_pk_mul_f32 v[130:131], v[130:131], v[180:181]
	v_mov_b32_dpp v181, v182 row_ror:2 row_mask:0xf bank_mask:0xf bound_ctrl:1
	v_mov_b32_dpp v129, v178 row_shr:1 row_mask:0xf bank_mask:0xf
	v_lshlrev_b32_e32 v128, 16, v129
	v_mov_b32_dpp v181, v178 row_shr:2 row_mask:0xf bank_mask:0xf
	v_lshlrev_b32_e32 v180, 16, v181
	v_and_b32_e32 v181, 0xffff0000, v181
	v_and_b32_e32 v129, 0xffff0000, v129
	v_pk_fma_f32 v[180:181], v[132:133], v[180:181], v[144:145]
	v_and_b32_e32 v229, 0xffff0000, v178
	v_pk_fma_f32 v[128:129], v[136:137], v[128:129], v[180:181]
	v_cvt_pk_bf16_f32 v227, v130, v131
	v_mov_b32_dpp v131, v183 row_ror:1 row_mask:0xf bank_mask:0xf bound_ctrl:1
	v_pk_fma_f32 v[128:129], v[140:141], v[228:229], v[128:129]
	v_mov_b32_dpp v183, v183 row_ror:2 row_mask:0xf bank_mask:0xf bound_ctrl:1
	v_pk_mul_f32 v[180:181], v[128:129], s[26:27] op_sel_hi:[1,0]
	v_mov_b32_dpp v131, v179 row_shr:1 row_mask:0xf bank_mask:0xf
	v_med3_f32 v180, v180, s71, v224
	v_med3_f32 v181, v181, s71, v224
	v_pk_mul_f32 v[228:229], v[180:181], v[180:181]
	v_mov_b32_dpp v183, v179 row_shr:2 row_mask:0xf bank_mask:0xf
	v_pk_fma_f32 v[232:233], v[228:229], s[28:29], v[210:211] op_sel_hi:[1,0,0] neg_lo:[1,0,0] neg_hi:[1,0,0]
	v_lshlrev_b32_e32 v182, 16, v183
	v_pk_fma_f32 v[232:233], v[228:229], v[232:233], s[34:35] op_sel_hi:[1,1,0]
	v_and_b32_e32 v183, 0xffff0000, v183
	v_pk_fma_f32 v[232:233], v[228:229], v[232:233], s[36:37] op_sel_hi:[1,1,0]
; __device__ __forceinline__ unsigned cvt_pk_bf16(float lo, float hi) { unsigned r; asm volatile("v_cvt_pk_bf16_f32 %0, %1, %2" : "=v"(r) : "v"(lo), "v"(hi)); return r; }
;     static __device__ __forceinline__ u32x2 finish2(const float (&g0)[4], const float (&g1)[4], const float (&g2)[4], const float (&w0)[4], const float (&w1)[4], const float (&w2)[4], const float (&bb)[4],
;                                                     const f32x4 v, float rs) {
;         float h[4];
; #pragma unroll
;         for (int j = 0; j < 4; j += 2) {
;             const f32x2 gc = (f32x2){bb[j] + w0[j] * g2[j] + w1[j] * g1[j] + w2[j] * g0[j], bb[j + 1] + w0[j + 1] * g2[j + 1] + w1[j + 1] * g1[j + 1] + w2[j + 1] * g0[j + 1]};
;             const f32x2 ge = gelu_pk(gc) * ((f32x2){v[j], v[j + 1]} * rs); h[j] = ge.x; h[j + 1] = ge.y; }
;         u32x2 w; w.x = cvt_pk_bf16(h[0], h[1]); w.y = cvt_pk_bf16(h[2], h[3]); return w;
;     }
;     __device__ __forceinline__ void operator()(const f32x4 (&acc)[2][2][4][2], const Unit& u, int wr, int wc, int fr, int fq) const {
;     ...
;             for (int ai = 0; ai < 2; ++ai) { const int R0 = u.rb + ai * HALF + wr * 64; const bf16_t* gp = G + (size_t)(R0 + fr) * 2816 + col8;
;                 u32x4 gq[4], prv = (u32x4){0u, 0u, 0u, 0u};
; #pragma unroll
;                 for (int m = 0; m < 4; ++m) gq[m] = *(const u32x4*)(gp + (size_t)m * 16 * 2816);
;                 if ((R0 & 8191) != 0) prv = *(const u32x4*)(gp - (size_t)16 * 2816);
;                 u32x4 pv = prv;
; #pragma unroll
;                 for (int m = 0; m < 4; ++m) { const u32x4 cur = gq[m]; u32x4 hw;
; #pragma unroll
;                     for (int hv = 0; hv < 2; ++hv) { const u32x2 c2 = half2(cur, hv), p2 = half2(pv, hv);
;                         const u32x2 q1 = dpp_prev<1>(p2, c2), q2 = dpp_prev<2>(p2, c2);
;                         float g0[4], g1[4], g2[4]; unpk4(c2, g0); unpk4(q1, g1); unpk4(q2, g2);
;                         const u32x2 r = finish2(g0, g1, g2, w0[hv], w1[hv], w2[hv], bb[hv], acc[ai][bj][m][hv], rs8[ai][m]);
;                         if (hv == 0) { hw.x = r.x; hw.y = r.y; } else { hw.z = r.x; hw.w = r.y; } }
;                     *(u32x4*)(H + (size_t)(R0 + fr + 16 * m) * 2816 + col8) = hw;
;                     pv = cur; } }
	v_pk_mul_f32 v[128:129], v[128:129], 0.5 op_sel_hi:[1,0]
	v_pk_fma_f32 v[232:233], v[228:229], v[232:233], s[38:39] op_sel_hi:[1,1,0]
	v_lshlrev_b32_e32 v130, 16, v131
	v_pk_fma_f32 v[232:233], v[228:229], v[232:233], s[40:41] op_sel_hi:[1,1,0]
	v_and_b32_e32 v131, 0xffff0000, v131
	v_pk_fma_f32 v[232:233], v[228:229], v[232:233], s[42:43] op_sel_hi:[1,1,0]
	v_pk_mul_f32 v[108:109], v[108:109], v[184:185] op_sel_hi:[1,0]
	v_pk_fma_f32 v[228:229], v[228:229], v[232:233], s[44:45] op_sel_hi:[1,1,0]
	v_pk_mul_f32 v[110:111], v[110:111], v[184:185] op_sel_hi:[1,0]
	v_pk_mul_f32 v[180:181], v[180:181], v[228:229]
	v_pk_mul_f32 v[104:105], v[104:105], v[2:3] op_sel_hi:[1,0]
	v_pk_fma_f32 v[128:129], v[128:129], v[180:181], v[128:129]
	v_pk_fma_f32 v[180:181], v[134:135], v[182:183], v[146:147]
	v_pk_mul_f32 v[124:125], v[124:125], v[128:129]
	v_lshlrev_b32_e32 v128, 16, v179
	v_and_b32_e32 v129, 0xffff0000, v179
	v_pk_fma_f32 v[130:131], v[138:139], v[130:131], v[180:181]
	v_cvt_pk_bf16_f32 v228, v124, v125
	v_pk_mul_f32 v[106:107], v[106:107], v[2:3] op_sel_hi:[1,0]
	v_pk_fma_f32 v[128:129], v[142:143], v[128:129], v[130:131]
	v_pk_mul_f32 v[100:101], v[100:101], v[2:3] op_sel_hi:[1,0]
	v_pk_mul_f32 v[130:131], v[128:129], s[26:27] op_sel_hi:[1,0]
	v_pk_mul_f32 v[128:129], v[128:129], 0.5 op_sel_hi:[1,0]
	v_med3_f32 v130, v130, s71, v224
	v_med3_f32 v131, v131, s71, v224
	v_pk_mul_f32 v[180:181], v[130:131], v[130:131]
	s_addk_i32 s47, 0x80
	v_pk_fma_f32 v[182:183], v[180:181], s[28:29], v[210:211] op_sel_hi:[1,0,0] neg_lo:[1,0,0] neg_hi:[1,0,0]
	v_add_u32_e32 v1, s47, v1
	v_pk_fma_f32 v[182:183], v[180:181], v[182:183], s[34:35] op_sel_hi:[1,1,0]
	v_pk_mul_f32 v[102:103], v[102:103], v[2:3] op_sel_hi:[1,0]
	v_pk_fma_f32 v[182:183], v[180:181], v[182:183], s[36:37] op_sel_hi:[1,1,0]
	s_nop 0
	v_pk_fma_f32 v[182:183], v[180:181], v[182:183], s[38:39] op_sel_hi:[1,1,0]
	s_nop 0
	v_pk_fma_f32 v[182:183], v[180:181], v[182:183], s[40:41] op_sel_hi:[1,1,0]
	s_nop 0
	v_pk_fma_f32 v[182:183], v[180:181], v[182:183], s[42:43] op_sel_hi:[1,1,0]
	s_nop 0
	v_pk_fma_f32 v[180:181], v[180:181], v[182:183], s[44:45] op_sel_hi:[1,1,0]
	v_lshlrev_b32_e32 v182, 16, v172
	v_pk_mul_f32 v[130:131], v[130:131], v[180:181]
	v_lshlrev_b64 v[180:181], 1, v[212:213]
	v_pk_fma_f32 v[128:129], v[128:129], v[130:131], v[128:129]
	v_lshl_add_u64 v[130:131], s[0:1], 0, v[230:231]
	v_pk_mul_f32 v[126:127], v[126:127], v[128:129]
	v_lshl_add_u64 v[124:125], v[130:131], 0, v[180:181]
	v_mov_b32_dpp v129, v176 row_ror:2 row_mask:0xf bank_mask:0xf bound_ctrl:1
	v_cvt_pk_bf16_f32 v229, v126, v127
	global_store_dwordx4 v[124:125], v[226:229], off nt
	v_mov_b32_dpp v125, v176 row_ror:1 row_mask:0xf bank_mask:0xf bound_ctrl:1
	v_mov_b32_dpp v129, v172 row_shr:2 row_mask:0xf bank_mask:0xf
	v_lshlrev_b32_e32 v128, 16, v129
	v_mov_b32_dpp v125, v172 row_shr:1 row_mask:0xf bank_mask:0xf
	v_and_b32_e32 v129, 0xffff0000, v129
	v_lshlrev_b32_e32 v124, 16, v125
	v_and_b32_e32 v125, 0xffff0000, v125
	v_pk_fma_f32 v[128:129], v[148:149], v[128:129], v[160:161]
	v_and_b32_e32 v183, 0xffff0000, v172
	v_pk_fma_f32 v[124:125], v[152:153], v[124:125], v[128:129]
	v_mov_b32_dpp v127, v177 row_ror:1 row_mask:0xf bank_mask:0xf bound_ctrl:1
	v_pk_fma_f32 v[124:125], v[156:157], v[182:183], v[124:125]
	v_mov_b32_dpp v177, v177 row_ror:2 row_mask:0xf bank_mask:0xf bound_ctrl:1
	v_pk_mul_f32 v[128:129], v[124:125], s[26:27] op_sel_hi:[1,0]
	v_mov_b32_dpp v127, v173 row_shr:1 row_mask:0xf bank_mask:0xf
	v_med3_f32 v128, v128, s71, v224
	v_med3_f32 v129, v129, s71, v224
	v_pk_mul_f32 v[182:183], v[128:129], v[128:129]
	v_mov_b32_dpp v177, v173 row_shr:2 row_mask:0xf bank_mask:0xf
	v_pk_fma_f32 v[226:227], v[182:183], s[28:29], v[210:211] op_sel_hi:[1,0,0] neg_lo:[1,0,0] neg_hi:[1,0,0]
	v_lshlrev_b32_e32 v176, 16, v177
	v_pk_fma_f32 v[226:227], v[182:183], v[226:227], s[34:35] op_sel_hi:[1,1,0]
	v_and_b32_e32 v177, 0xffff0000, v177
	v_pk_fma_f32 v[226:227], v[182:183], v[226:227], s[36:37] op_sel_hi:[1,1,0]
	v_pk_mul_f32 v[124:125], v[124:125], 0.5 op_sel_hi:[1,0]
	v_pk_fma_f32 v[226:227], v[182:183], v[226:227], s[38:39] op_sel_hi:[1,1,0]
	v_lshlrev_b32_e32 v126, 16, v127
	v_pk_fma_f32 v[226:227], v[182:183], v[226:227], s[40:41] op_sel_hi:[1,1,0]
	v_and_b32_e32 v127, 0xffff0000, v127
	v_pk_fma_f32 v[226:227], v[182:183], v[226:227], s[42:43] op_sel_hi:[1,1,0]
	s_nop 0
	v_pk_fma_f32 v[182:183], v[182:183], v[226:227], s[44:45] op_sel_hi:[1,1,0]
	s_nop 0
	v_pk_mul_f32 v[128:129], v[128:129], v[182:183]
	s_nop 0
	v_pk_fma_f32 v[124:125], v[124:125], v[128:129], v[124:125]
	v_pk_fma_f32 v[128:129], v[150:151], v[176:177], v[162:163]
	v_pk_mul_f32 v[120:121], v[120:121], v[124:125]
	v_lshlrev_b32_e32 v124, 16, v173
	v_and_b32_e32 v125, 0xffff0000, v173
	v_pk_fma_f32 v[126:127], v[154:155], v[126:127], v[128:129]
	v_cvt_pk_bf16_f32 v120, v120, v121
	s_nop 0
	v_pk_fma_f32 v[124:125], v[158:159], v[124:125], v[126:127]
	s_nop 0
	v_pk_mul_f32 v[126:127], v[124:125], s[26:27] op_sel_hi:[1,0]
	v_pk_mul_f32 v[124:125], v[124:125], 0.5 op_sel_hi:[1,0]
	v_med3_f32 v126, v126, s71, v224
	v_med3_f32 v127, v127, s71, v224
	v_pk_mul_f32 v[128:129], v[126:127], v[126:127]
	s_nop 0
	v_pk_fma_f32 v[176:177], v[128:129], s[28:29], v[210:211] op_sel_hi:[1,0,0] neg_lo:[1,0,0] neg_hi:[1,0,0]
	s_nop 0
	v_pk_fma_f32 v[176:177], v[128:129], v[176:177], s[34:35] op_sel_hi:[1,1,0]
	s_nop 0
	v_pk_fma_f32 v[176:177], v[128:129], v[176:177], s[36:37] op_sel_hi:[1,1,0]
	s_nop 0
	v_pk_fma_f32 v[176:177], v[128:129], v[176:177], s[38:39] op_sel_hi:[1,1,0]
	s_nop 0
	v_pk_fma_f32 v[176:177], v[128:129], v[176:177], s[40:41] op_sel_hi:[1,1,0]
; __device__ __forceinline__ unsigned cvt_pk_bf16(float lo, float hi) { unsigned r; asm volatile("v_cvt_pk_bf16_f32 %0, %1, %2" : "=v"(r) : "v"(lo), "v"(hi)); return r; }
;     static __device__ __forceinline__ u32x2 finish2(const float (&g0)[4], const float (&g1)[4], const float (&g2)[4], const float (&w0)[4], const float (&w1)[4], const float (&w2)[4], const float (&bb)[4],
;                                                     const f32x4 v, float rs) {
;         float h[4];
; #pragma unroll
;         for (int j = 0; j < 4; j += 2) {
;             const f32x2 gc = (f32x2){bb[j] + w0[j] * g2[j] + w1[j] * g1[j] + w2[j] * g0[j], bb[j + 1] + w0[j + 1] * g2[j + 1] + w1[j + 1] * g1[j + 1] + w2[j + 1] * g0[j + 1]};
;             const f32x2 ge = gelu_pk(gc) * ((f32x2){v[j], v[j + 1]} * rs); h[j] = ge.x; h[j + 1] = ge.y; }
;         u32x2 w; w.x = cvt_pk_bf16(h[0], h[1]); w.y = cvt_pk_bf16(h[2], h[3]); return w;
;     }
;     __device__ __forceinline__ void operator()(const f32x4 (&acc)[2][2][4][2], const Unit& u, int wr, int wc, int fr, int fq) const {
;     ...
;             for (int ai = 0; ai < 2; ++ai) { const int R0 = u.rb + ai * HALF + wr * 64; const bf16_t* gp = G + (size_t)(R0 + fr) * 2816 + col8;
;                 u32x4 gq[4], prv = (u32x4){0u, 0u, 0u, 0u};
; #pragma unroll
;                 for (int m = 0; m < 4; ++m) gq[m] = *(const u32x4*)(gp + (size_t)m * 16 * 2816);
;                 if ((R0 & 8191) != 0) prv = *(const u32x4*)(gp - (size_t)16 * 2816);
;                 u32x4 pv = prv;
; #pragma unroll
;                 for (int m = 0; m < 4; ++m) { const u32x4 cur = gq[m]; u32x4 hw;
; #pragma unroll
;                     for (int hv = 0; hv < 2; ++hv) { const u32x2 c2 = half2(cur, hv), p2 = half2(pv, hv);
;                         const u32x2 q1 = dpp_prev<1>(p2, c2), q2 = dpp_prev<2>(p2, c2);
;                         float g0[4], g1[4], g2[4]; unpk4(c2, g0); unpk4(q1, g1); unpk4(q2, g2);
;                         const u32x2 r = finish2(g0, g1, g2, w0[hv], w1[hv], w2[hv], bb[hv], acc[ai][bj][m][hv], rs8[ai][m]);
;                         if (hv == 0) { hw.x = r.x; hw.y = r.y; } else { hw.z = r.x; hw.w = r.y; } }
;                     *(u32x4*)(H + (size_t)(R0 + fr + 16 * m) * 2816 + col8) = hw;
;                     pv = cur; } }
	s_nop 0
	v_pk_fma_f32 v[176:177], v[128:129], v[176:177], s[42:43] op_sel_hi:[1,1,0]
	s_nop 0
	v_pk_fma_f32 v[128:129], v[128:129], v[176:177], s[44:45] op_sel_hi:[1,1,0]
	v_lshlrev_b32_e32 v176, 16, v174
	v_pk_mul_f32 v[126:127], v[126:127], v[128:129]
	v_and_b32_e32 v177, 0xffff0000, v174
	v_pk_fma_f32 v[124:125], v[124:125], v[126:127], v[124:125]
	v_mov_b32_dpp v127, v178 row_ror:2 row_mask:0xf bank_mask:0xf bound_ctrl:1
	v_pk_mul_f32 v[122:123], v[122:123], v[124:125]
	v_mov_b32_dpp v125, v179 row_ror:1 row_mask:0xf bank_mask:0xf bound_ctrl:1
	v_cvt_pk_bf16_f32 v121, v122, v123
	v_mov_b32_dpp v127, v174 row_shr:2 row_mask:0xf bank_mask:0xf
	v_mov_b32_dpp v123, v178 row_ror:1 row_mask:0xf bank_mask:0xf bound_ctrl:1
	v_lshlrev_b32_e32 v126, 16, v127
	v_and_b32_e32 v127, 0xffff0000, v127
	v_mov_b32_dpp v123, v174 row_shr:1 row_mask:0xf bank_mask:0xf
	v_lshlrev_b32_e32 v122, 16, v123
	v_and_b32_e32 v123, 0xffff0000, v123
	v_pk_fma_f32 v[126:127], v[132:133], v[126:127], v[144:145]
	v_mov_b32_dpp v129, v179 row_ror:2 row_mask:0xf bank_mask:0xf bound_ctrl:1
	v_pk_fma_f32 v[122:123], v[136:137], v[122:123], v[126:127]
	v_mov_b32_dpp v125, v175 row_shr:1 row_mask:0xf bank_mask:0xf
	v_pk_fma_f32 v[122:123], v[140:141], v[176:177], v[122:123]
	v_mov_b32_dpp v129, v175 row_shr:2 row_mask:0xf bank_mask:0xf
	v_pk_mul_f32 v[126:127], v[122:123], s[26:27] op_sel_hi:[1,0]
	v_lshlrev_b32_e32 v128, 16, v129
	v_med3_f32 v126, v126, s71, v224
	v_med3_f32 v127, v127, s71, v224
	v_pk_mul_f32 v[176:177], v[126:127], v[126:127]
	v_and_b32_e32 v129, 0xffff0000, v129
	v_pk_fma_f32 v[178:179], v[176:177], s[28:29], v[210:211] op_sel_hi:[1,0,0] neg_lo:[1,0,0] neg_hi:[1,0,0]
	v_pk_mul_f32 v[122:123], v[122:123], 0.5 op_sel_hi:[1,0]
	v_pk_fma_f32 v[178:179], v[176:177], v[178:179], s[34:35] op_sel_hi:[1,1,0]
	v_lshlrev_b32_e32 v124, 16, v125
	v_pk_fma_f32 v[178:179], v[176:177], v[178:179], s[36:37] op_sel_hi:[1,1,0]
	v_and_b32_e32 v125, 0xffff0000, v125
	v_pk_fma_f32 v[178:179], v[176:177], v[178:179], s[38:39] op_sel_hi:[1,1,0]
	s_nop 0
	v_pk_fma_f32 v[178:179], v[176:177], v[178:179], s[40:41] op_sel_hi:[1,1,0]
	s_nop 0
	v_pk_fma_f32 v[178:179], v[176:177], v[178:179], s[42:43] op_sel_hi:[1,1,0]
	s_nop 0
	v_pk_fma_f32 v[176:177], v[176:177], v[178:179], s[44:45] op_sel_hi:[1,1,0]
	s_nop 0
	v_pk_mul_f32 v[126:127], v[126:127], v[176:177]
	s_nop 0
	v_pk_fma_f32 v[122:123], v[122:123], v[126:127], v[122:123]
	v_pk_fma_f32 v[126:127], v[134:135], v[128:129], v[146:147]
	v_pk_mul_f32 v[116:117], v[116:117], v[122:123]
	v_lshlrev_b32_e32 v122, 16, v175
	v_and_b32_e32 v123, 0xffff0000, v175
	v_pk_fma_f32 v[124:125], v[138:139], v[124:125], v[126:127]
	s_nop 0
	v_pk_fma_f32 v[122:123], v[142:143], v[122:123], v[124:125]
	s_nop 0
	v_pk_mul_f32 v[124:125], v[122:123], s[26:27] op_sel_hi:[1,0]
	v_pk_mul_f32 v[122:123], v[122:123], 0.5 op_sel_hi:[1,0]
	v_med3_f32 v124, v124, s71, v224
	v_med3_f32 v125, v125, s71, v224
	v_pk_mul_f32 v[126:127], v[124:125], v[124:125]
	s_nop 0
	v_pk_fma_f32 v[128:129], v[126:127], s[28:29], v[210:211] op_sel_hi:[1,0,0] neg_lo:[1,0,0] neg_hi:[1,0,0]
	s_nop 0
	v_pk_fma_f32 v[128:129], v[126:127], v[128:129], s[34:35] op_sel_hi:[1,1,0]
	s_nop 0
	v_pk_fma_f32 v[128:129], v[126:127], v[128:129], s[36:37] op_sel_hi:[1,1,0]
	s_nop 0
	v_pk_fma_f32 v[128:129], v[126:127], v[128:129], s[38:39] op_sel_hi:[1,1,0]
	s_nop 0
	v_pk_fma_f32 v[128:129], v[126:127], v[128:129], s[40:41] op_sel_hi:[1,1,0]
	s_nop 0
	v_pk_fma_f32 v[128:129], v[126:127], v[128:129], s[42:43] op_sel_hi:[1,1,0]
	s_nop 0
	v_pk_fma_f32 v[126:127], v[126:127], v[128:129], s[44:45] op_sel_hi:[1,1,0]
	s_nop 0
	v_pk_mul_f32 v[124:125], v[124:125], v[126:127]
	v_lshlrev_b32_e32 v126, 16, v168
	v_pk_fma_f32 v[122:123], v[122:123], v[124:125], v[122:123]
	v_and_b32_e32 v127, 0xffff0000, v168
	v_pk_mul_f32 v[118:119], v[118:119], v[122:123]
	v_cvt_pk_bf16_f32 v122, v116, v117
	v_mov_b64_e32 v[116:117], s[0:1]
	v_mad_i64_i32 v[176:177], s[0:1], v194, s67, v[116:117]
	v_cvt_pk_bf16_f32 v123, v118, v119
	v_lshl_add_u64 v[118:119], v[176:177], 0, v[180:181]
	global_store_dwordx4 v[118:119], v[120:123], off nt
	v_mov_b32_dpp v125, v173 row_ror:2 row_mask:0xf bank_mask:0xf bound_ctrl:1
	v_mov_b32_dpp v119, v172 row_ror:1 row_mask:0xf bank_mask:0xf bound_ctrl:1
	v_mov_b32_dpp v123, v172 row_ror:2 row_mask:0xf bank_mask:0xf bound_ctrl:1
	v_mov_b32_dpp v121, v173 row_ror:1 row_mask:0xf bank_mask:0xf bound_ctrl:1
	v_mov_b32_dpp v119, v168 row_shr:1 row_mask:0xf bank_mask:0xf
	v_mov_b32_dpp v123, v168 row_shr:2 row_mask:0xf bank_mask:0xf
	v_lshlrev_b32_e32 v122, 16, v123
	v_and_b32_e32 v123, 0xffff0000, v123
	v_lshlrev_b32_e32 v118, 16, v119
	v_and_b32_e32 v119, 0xffff0000, v119
	v_pk_fma_f32 v[122:123], v[148:149], v[122:123], v[160:161]
	v_mov_b32_dpp v125, v169 row_shr:2 row_mask:0xf bank_mask:0xf
	v_pk_fma_f32 v[118:119], v[152:153], v[118:119], v[122:123]
	v_mov_b32_dpp v121, v169 row_shr:1 row_mask:0xf bank_mask:0xf
	v_pk_fma_f32 v[118:119], v[156:157], v[126:127], v[118:119]
	v_lshlrev_b32_e32 v124, 16, v125
	v_pk_mul_f32 v[122:123], v[118:119], s[26:27] op_sel_hi:[1,0]
	v_and_b32_e32 v125, 0xffff0000, v125
	v_med3_f32 v122, v122, s71, v224
	v_med3_f32 v123, v123, s71, v224
	v_pk_mul_f32 v[126:127], v[122:123], v[122:123]
	v_pk_mul_f32 v[118:119], v[118:119], 0.5 op_sel_hi:[1,0]
	v_pk_fma_f32 v[128:129], v[126:127], s[28:29], v[210:211] op_sel_hi:[1,0,0] neg_lo:[1,0,0] neg_hi:[1,0,0]
	v_lshlrev_b32_e32 v120, 16, v121
	v_pk_fma_f32 v[128:129], v[126:127], v[128:129], s[34:35] op_sel_hi:[1,1,0]
	v_and_b32_e32 v121, 0xffff0000, v121
	v_pk_fma_f32 v[128:129], v[126:127], v[128:129], s[36:37] op_sel_hi:[1,1,0]
; __device__ __forceinline__ unsigned cvt_pk_bf16(float lo, float hi) { unsigned r; asm volatile("v_cvt_pk_bf16_f32 %0, %1, %2" : "=v"(r) : "v"(lo), "v"(hi)); return r; }
;     static __device__ __forceinline__ u32x2 finish2(const float (&g0)[4], const float (&g1)[4], const float (&g2)[4], const float (&w0)[4], const float (&w1)[4], const float (&w2)[4], const float (&bb)[4],
;                                                     const f32x4 v, float rs) {
;         float h[4];
; #pragma unroll
;         for (int j = 0; j < 4; j += 2) {
;             const f32x2 gc = (f32x2){bb[j] + w0[j] * g2[j] + w1[j] * g1[j] + w2[j] * g0[j], bb[j + 1] + w0[j + 1] * g2[j + 1] + w1[j + 1] * g1[j + 1] + w2[j + 1] * g0[j + 1]};
;             const f32x2 ge = gelu_pk(gc) * ((f32x2){v[j], v[j + 1]} * rs); h[j] = ge.x; h[j + 1] = ge.y; }
;         u32x2 w; w.x = cvt_pk_bf16(h[0], h[1]); w.y = cvt_pk_bf16(h[2], h[3]); return w;
;     }
;     __device__ __forceinline__ void operator()(const f32x4 (&acc)[2][2][4][2], const Unit& u, int wr, int wc, int fr, int fq) const {
;     ...
;             for (int ai = 0; ai < 2; ++ai) { const int R0 = u.rb + ai * HALF + wr * 64; const bf16_t* gp = G + (size_t)(R0 + fr) * 2816 + col8;
;                 u32x4 gq[4], prv = (u32x4){0u, 0u, 0u, 0u};
; #pragma unroll
;                 for (int m = 0; m < 4; ++m) gq[m] = *(const u32x4*)(gp + (size_t)m * 16 * 2816);
;                 if ((R0 & 8191) != 0) prv = *(const u32x4*)(gp - (size_t)16 * 2816);
;                 u32x4 pv = prv;
; #pragma unroll
;                 for (int m = 0; m < 4; ++m) { const u32x4 cur = gq[m]; u32x4 hw;
; #pragma unroll
;                     for (int hv = 0; hv < 2; ++hv) { const u32x2 c2 = half2(cur, hv), p2 = half2(pv, hv);
;                         const u32x2 q1 = dpp_prev<1>(p2, c2), q2 = dpp_prev<2>(p2, c2);
;                         float g0[4], g1[4], g2[4]; unpk4(c2, g0); unpk4(q1, g1); unpk4(q2, g2);
;                         const u32x2 r = finish2(g0, g1, g2, w0[hv], w1[hv], w2[hv], bb[hv], acc[ai][bj][m][hv], rs8[ai][m]);
;                         if (hv == 0) { hw.x = r.x; hw.y = r.y; } else { hw.z = r.x; hw.w = r.y; } }
;                     *(u32x4*)(H + (size_t)(R0 + fr + 16 * m) * 2816 + col8) = hw;
;                     pv = cur; } }
	v_mad_i64_i32 v[172:173], s[0:1], v192, s67, v[116:117]
	v_pk_fma_f32 v[128:129], v[126:127], v[128:129], s[38:39] op_sel_hi:[1,1,0]
	v_readlane_b32 s0, v240, 12
	v_pk_fma_f32 v[128:129], v[126:127], v[128:129], s[40:41] op_sel_hi:[1,1,0]
	v_readlane_b32 s1, v240, 13
	v_pk_fma_f32 v[128:129], v[126:127], v[128:129], s[42:43] op_sel_hi:[1,1,0]
	s_nop 0
	v_pk_fma_f32 v[126:127], v[126:127], v[128:129], s[44:45] op_sel_hi:[1,1,0]
	s_nop 0
	v_pk_mul_f32 v[122:123], v[122:123], v[126:127]
	s_nop 0
	v_pk_fma_f32 v[118:119], v[118:119], v[122:123], v[118:119]
	v_pk_fma_f32 v[122:123], v[150:151], v[124:125], v[162:163]
	v_pk_mul_f32 v[112:113], v[112:113], v[118:119]
	v_lshlrev_b32_e32 v118, 16, v169
	v_and_b32_e32 v119, 0xffff0000, v169
	v_pk_fma_f32 v[120:121], v[154:155], v[120:121], v[122:123]
	v_cvt_pk_bf16_f32 v112, v112, v113
	s_nop 0
	v_pk_fma_f32 v[118:119], v[158:159], v[118:119], v[120:121]
	s_nop 0
	v_pk_mul_f32 v[120:121], v[118:119], s[26:27] op_sel_hi:[1,0]
	v_pk_mul_f32 v[118:119], v[118:119], 0.5 op_sel_hi:[1,0]
	v_med3_f32 v120, v120, s71, v224
	v_med3_f32 v121, v121, s71, v224
	v_pk_mul_f32 v[122:123], v[120:121], v[120:121]
	s_nop 0
	v_pk_fma_f32 v[124:125], v[122:123], s[28:29], v[210:211] op_sel_hi:[1,0,0] neg_lo:[1,0,0] neg_hi:[1,0,0]
	s_nop 0
	v_pk_fma_f32 v[124:125], v[122:123], v[124:125], s[34:35] op_sel_hi:[1,1,0]
	s_nop 0
	v_pk_fma_f32 v[124:125], v[122:123], v[124:125], s[36:37] op_sel_hi:[1,1,0]
	s_nop 0
	v_pk_fma_f32 v[124:125], v[122:123], v[124:125], s[38:39] op_sel_hi:[1,1,0]
	s_nop 0
	v_pk_fma_f32 v[124:125], v[122:123], v[124:125], s[40:41] op_sel_hi:[1,1,0]
	s_nop 0
	v_pk_fma_f32 v[124:125], v[122:123], v[124:125], s[42:43] op_sel_hi:[1,1,0]
	s_nop 0
	v_pk_fma_f32 v[122:123], v[122:123], v[124:125], s[44:45] op_sel_hi:[1,1,0]
	v_lshlrev_b32_e32 v124, 16, v170
	v_pk_mul_f32 v[120:121], v[120:121], v[122:123]
	v_and_b32_e32 v125, 0xffff0000, v170
	v_pk_fma_f32 v[118:119], v[118:119], v[120:121], v[118:119]
	v_mov_b32_dpp v121, v174 row_ror:2 row_mask:0xf bank_mask:0xf bound_ctrl:1
	v_pk_mul_f32 v[114:115], v[114:115], v[118:119]
	v_mov_b32_dpp v123, v175 row_ror:2 row_mask:0xf bank_mask:0xf bound_ctrl:1
	v_cvt_pk_bf16_f32 v113, v114, v115
	v_mov_b32_dpp v121, v170 row_shr:2 row_mask:0xf bank_mask:0xf
	v_mov_b32_dpp v115, v174 row_ror:1 row_mask:0xf bank_mask:0xf bound_ctrl:1
	v_lshlrev_b32_e32 v120, 16, v121
	v_and_b32_e32 v121, 0xffff0000, v121
	v_mov_b32_dpp v115, v170 row_shr:1 row_mask:0xf bank_mask:0xf
	v_lshlrev_b32_e32 v114, 16, v115
	v_and_b32_e32 v115, 0xffff0000, v115
	v_pk_fma_f32 v[120:121], v[132:133], v[120:121], v[144:145]
	v_mov_b32_dpp v119, v175 row_ror:1 row_mask:0xf bank_mask:0xf bound_ctrl:1
	v_pk_fma_f32 v[114:115], v[136:137], v[114:115], v[120:121]
	v_mov_b32_dpp v123, v171 row_shr:2 row_mask:0xf bank_mask:0xf
	v_pk_fma_f32 v[114:115], v[140:141], v[124:125], v[114:115]
	v_mov_b32_dpp v119, v171 row_shr:1 row_mask:0xf bank_mask:0xf
	v_pk_mul_f32 v[120:121], v[114:115], s[26:27] op_sel_hi:[1,0]
	v_lshlrev_b32_e32 v122, 16, v123
	v_med3_f32 v120, v120, s71, v224
	v_med3_f32 v121, v121, s71, v224
	v_pk_mul_f32 v[124:125], v[120:121], v[120:121]
	v_and_b32_e32 v123, 0xffff0000, v123
	v_pk_fma_f32 v[126:127], v[124:125], s[28:29], v[210:211] op_sel_hi:[1,0,0] neg_lo:[1,0,0] neg_hi:[1,0,0]
	v_pk_mul_f32 v[114:115], v[114:115], 0.5 op_sel_hi:[1,0]
	v_pk_fma_f32 v[126:127], v[124:125], v[126:127], s[34:35] op_sel_hi:[1,1,0]
	v_lshlrev_b32_e32 v118, 16, v119
	v_pk_fma_f32 v[126:127], v[124:125], v[126:127], s[36:37] op_sel_hi:[1,1,0]
	v_and_b32_e32 v119, 0xffff0000, v119
	v_pk_fma_f32 v[126:127], v[124:125], v[126:127], s[38:39] op_sel_hi:[1,1,0]
	s_nop 0
	v_pk_fma_f32 v[126:127], v[124:125], v[126:127], s[40:41] op_sel_hi:[1,1,0]
	s_nop 0
	v_pk_fma_f32 v[126:127], v[124:125], v[126:127], s[42:43] op_sel_hi:[1,1,0]
	s_nop 0
	v_pk_fma_f32 v[124:125], v[124:125], v[126:127], s[44:45] op_sel_hi:[1,1,0]
	s_nop 0
	v_pk_mul_f32 v[120:121], v[120:121], v[124:125]
	s_nop 0
	v_pk_fma_f32 v[114:115], v[114:115], v[120:121], v[114:115]
	v_pk_fma_f32 v[120:121], v[134:135], v[122:123], v[146:147]
	v_pk_mul_f32 v[108:109], v[108:109], v[114:115]
	v_lshlrev_b32_e32 v114, 16, v171
	v_and_b32_e32 v115, 0xffff0000, v171
	v_pk_fma_f32 v[118:119], v[138:139], v[118:119], v[120:121]
	s_nop 0
	v_pk_fma_f32 v[114:115], v[142:143], v[114:115], v[118:119]
	s_nop 0
	v_pk_mul_f32 v[118:119], v[114:115], s[26:27] op_sel_hi:[1,0]
	v_pk_mul_f32 v[114:115], v[114:115], 0.5 op_sel_hi:[1,0]
	v_med3_f32 v118, v118, s71, v224
	v_med3_f32 v119, v119, s71, v224
	v_pk_mul_f32 v[120:121], v[118:119], v[118:119]
	s_nop 0
	v_pk_fma_f32 v[122:123], v[120:121], s[28:29], v[210:211] op_sel_hi:[1,0,0] neg_lo:[1,0,0] neg_hi:[1,0,0]
	s_nop 0
	v_pk_fma_f32 v[122:123], v[120:121], v[122:123], s[34:35] op_sel_hi:[1,1,0]
	s_nop 0
	v_pk_fma_f32 v[122:123], v[120:121], v[122:123], s[36:37] op_sel_hi:[1,1,0]
	s_nop 0
	v_pk_fma_f32 v[122:123], v[120:121], v[122:123], s[38:39] op_sel_hi:[1,1,0]
	s_nop 0
	v_pk_fma_f32 v[122:123], v[120:121], v[122:123], s[40:41] op_sel_hi:[1,1,0]
	s_nop 0
	v_pk_fma_f32 v[122:123], v[120:121], v[122:123], s[42:43] op_sel_hi:[1,1,0]
	s_nop 0
	v_pk_fma_f32 v[120:121], v[120:121], v[122:123], s[44:45] op_sel_hi:[1,1,0]
	s_nop 0
	v_pk_mul_f32 v[118:119], v[118:119], v[120:121]
	s_nop 0
	v_pk_fma_f32 v[114:115], v[114:115], v[118:119], v[114:115]
	v_lshlrev_b32_e32 v118, 16, v164
	v_pk_mul_f32 v[110:111], v[110:111], v[114:115]
	v_cvt_pk_bf16_f32 v114, v108, v109
	v_lshl_add_u64 v[108:109], v[172:173], 0, v[180:181]
	v_cvt_pk_bf16_f32 v115, v110, v111
	global_store_dwordx4 v[108:109], v[112:115], off nt
; __device__ __forceinline__ unsigned cvt_pk_bf16(float lo, float hi) { unsigned r; asm volatile("v_cvt_pk_bf16_f32 %0, %1, %2" : "=v"(r) : "v"(lo), "v"(hi)); return r; }
;     static __device__ __forceinline__ u32x2 finish2(const float (&g0)[4], const float (&g1)[4], const float (&g2)[4], const float (&w0)[4], const float (&w1)[4], const float (&w2)[4], const float (&bb)[4],
;                                                     const f32x4 v, float rs) {
;         float h[4];
; #pragma unroll
;         for (int j = 0; j < 4; j += 2) {
;             const f32x2 gc = (f32x2){bb[j] + w0[j] * g2[j] + w1[j] * g1[j] + w2[j] * g0[j], bb[j + 1] + w0[j + 1] * g2[j + 1] + w1[j + 1] * g1[j + 1] + w2[j + 1] * g0[j + 1]};
;             const f32x2 ge = gelu_pk(gc) * ((f32x2){v[j], v[j + 1]} * rs); h[j] = ge.x; h[j + 1] = ge.y; }
;         u32x2 w; w.x = cvt_pk_bf16(h[0], h[1]); w.y = cvt_pk_bf16(h[2], h[3]); return w;
;     }
;     __device__ __forceinline__ void operator()(const f32x4 (&acc)[2][2][4][2], const Unit& u, int wr, int wc, int fr, int fq) const {
;     ...
;             for (int ai = 0; ai < 2; ++ai) { const int R0 = u.rb + ai * HALF + wr * 64; const bf16_t* gp = G + (size_t)(R0 + fr) * 2816 + col8;
;                 u32x4 gq[4], prv = (u32x4){0u, 0u, 0u, 0u};
; #pragma unroll
;                 for (int m = 0; m < 4; ++m) gq[m] = *(const u32x4*)(gp + (size_t)m * 16 * 2816);
;                 if ((R0 & 8191) != 0) prv = *(const u32x4*)(gp - (size_t)16 * 2816);
;                 u32x4 pv = prv;
; #pragma unroll
;                 for (int m = 0; m < 4; ++m) { const u32x4 cur = gq[m]; u32x4 hw;
; #pragma unroll
;                     for (int hv = 0; hv < 2; ++hv) { const u32x2 c2 = half2(cur, hv), p2 = half2(pv, hv);
;                         const u32x2 q1 = dpp_prev<1>(p2, c2), q2 = dpp_prev<2>(p2, c2);
;                         float g0[4], g1[4], g2[4]; unpk4(c2, g0); unpk4(q1, g1); unpk4(q2, g2);
;                         const u32x2 r = finish2(g0, g1, g2, w0[hv], w1[hv], w2[hv], bb[hv], acc[ai][bj][m][hv], rs8[ai][m]);
;                         if (hv == 0) { hw.x = r.x; hw.y = r.y; } else { hw.z = r.x; hw.w = r.y; } }
;                     *(u32x4*)(H + (size_t)(R0 + fr + 16 * m) * 2816 + col8) = hw;
;                     pv = cur; } }
	v_and_b32_e32 v119, 0xffff0000, v164
	v_mov_b32_dpp v109, v168 row_ror:1 row_mask:0xf bank_mask:0xf bound_ctrl:1
	v_mov_b32_dpp v113, v168 row_ror:2 row_mask:0xf bank_mask:0xf bound_ctrl:1
	v_mov_b32_dpp v115, v169 row_ror:2 row_mask:0xf bank_mask:0xf bound_ctrl:1
	v_mov_b32_dpp v109, v164 row_shr:1 row_mask:0xf bank_mask:0xf
	v_mov_b32_dpp v113, v164 row_shr:2 row_mask:0xf bank_mask:0xf
	v_lshlrev_b32_e32 v112, 16, v113
	v_and_b32_e32 v113, 0xffff0000, v113
	v_lshlrev_b32_e32 v108, 16, v109
	v_and_b32_e32 v109, 0xffff0000, v109
	v_pk_fma_f32 v[112:113], v[148:149], v[112:113], v[160:161]
	v_mov_b32_dpp v111, v169 row_ror:1 row_mask:0xf bank_mask:0xf bound_ctrl:1
	v_pk_fma_f32 v[108:109], v[152:153], v[108:109], v[112:113]
	v_mov_b32_dpp v115, v165 row_shr:2 row_mask:0xf bank_mask:0xf
	v_pk_fma_f32 v[108:109], v[156:157], v[118:119], v[108:109]
	v_mov_b32_dpp v111, v165 row_shr:1 row_mask:0xf bank_mask:0xf
	v_pk_mul_f32 v[112:113], v[108:109], s[26:27] op_sel_hi:[1,0]
	v_lshlrev_b32_e32 v114, 16, v115
	v_med3_f32 v112, v112, s71, v224
	v_med3_f32 v113, v113, s71, v224
	v_pk_mul_f32 v[118:119], v[112:113], v[112:113]
	v_and_b32_e32 v115, 0xffff0000, v115
	v_pk_fma_f32 v[120:121], v[118:119], s[28:29], v[210:211] op_sel_hi:[1,0,0] neg_lo:[1,0,0] neg_hi:[1,0,0]
	v_pk_mul_f32 v[108:109], v[108:109], 0.5 op_sel_hi:[1,0]
	v_pk_fma_f32 v[120:121], v[118:119], v[120:121], s[34:35] op_sel_hi:[1,1,0]
	v_lshlrev_b32_e32 v110, 16, v111
	v_pk_fma_f32 v[120:121], v[118:119], v[120:121], s[36:37] op_sel_hi:[1,1,0]
	v_and_b32_e32 v111, 0xffff0000, v111
	v_pk_fma_f32 v[120:121], v[118:119], v[120:121], s[38:39] op_sel_hi:[1,1,0]
	s_nop 0
	v_pk_fma_f32 v[120:121], v[118:119], v[120:121], s[40:41] op_sel_hi:[1,1,0]
	s_nop 0
	v_pk_fma_f32 v[120:121], v[118:119], v[120:121], s[42:43] op_sel_hi:[1,1,0]
	s_nop 0
	v_pk_fma_f32 v[118:119], v[118:119], v[120:121], s[44:45] op_sel_hi:[1,1,0]
	s_nop 0
	v_pk_mul_f32 v[112:113], v[112:113], v[118:119]
	s_nop 0
	v_pk_fma_f32 v[108:109], v[108:109], v[112:113], v[108:109]
	v_pk_fma_f32 v[112:113], v[150:151], v[114:115], v[162:163]
	v_pk_mul_f32 v[104:105], v[104:105], v[108:109]
	v_lshlrev_b32_e32 v108, 16, v165
	v_and_b32_e32 v109, 0xffff0000, v165
	v_pk_fma_f32 v[110:111], v[154:155], v[110:111], v[112:113]
	v_cvt_pk_bf16_f32 v120, v104, v105
	v_mov_b32_dpp v105, v170 row_ror:1 row_mask:0xf bank_mask:0xf bound_ctrl:1
	v_pk_fma_f32 v[108:109], v[158:159], v[108:109], v[110:111]
	s_nop 0
	v_pk_mul_f32 v[110:111], v[108:109], s[26:27] op_sel_hi:[1,0]
	v_pk_mul_f32 v[108:109], v[108:109], 0.5 op_sel_hi:[1,0]
	v_med3_f32 v110, v110, s71, v224
	v_med3_f32 v111, v111, s71, v224
	v_pk_mul_f32 v[112:113], v[110:111], v[110:111]
	v_mov_b32_dpp v105, v166 row_shr:1 row_mask:0xf bank_mask:0xf
	v_pk_fma_f32 v[114:115], v[112:113], s[28:29], v[210:211] op_sel_hi:[1,0,0] neg_lo:[1,0,0] neg_hi:[1,0,0]
	v_lshlrev_b32_e32 v104, 16, v105
	v_pk_fma_f32 v[114:115], v[112:113], v[114:115], s[34:35] op_sel_hi:[1,1,0]
	v_and_b32_e32 v105, 0xffff0000, v105
	v_pk_fma_f32 v[114:115], v[112:113], v[114:115], s[36:37] op_sel_hi:[1,1,0]
	s_nop 0
	v_pk_fma_f32 v[114:115], v[112:113], v[114:115], s[38:39] op_sel_hi:[1,1,0]
	s_nop 0
	v_pk_fma_f32 v[114:115], v[112:113], v[114:115], s[40:41] op_sel_hi:[1,1,0]
	s_nop 0
	v_pk_fma_f32 v[114:115], v[112:113], v[114:115], s[42:43] op_sel_hi:[1,1,0]
	s_nop 0
	v_pk_fma_f32 v[112:113], v[112:113], v[114:115], s[44:45] op_sel_hi:[1,1,0]
	s_nop 0
	v_pk_mul_f32 v[110:111], v[110:111], v[112:113]
	v_lshlrev_b32_e32 v112, 16, v166
	v_pk_fma_f32 v[108:109], v[108:109], v[110:111], v[108:109]
	v_and_b32_e32 v113, 0xffff0000, v166
	v_pk_mul_f32 v[106:107], v[106:107], v[108:109]
	v_mov_b32_dpp v109, v170 row_ror:2 row_mask:0xf bank_mask:0xf bound_ctrl:1
	v_mov_b32_dpp v111, v171 row_ror:2 row_mask:0xf bank_mask:0xf bound_ctrl:1
	v_cvt_pk_bf16_f32 v121, v106, v107
	v_mov_b32_dpp v107, v171 row_ror:1 row_mask:0xf bank_mask:0xf bound_ctrl:1
	v_mov_b32_dpp v109, v166 row_shr:2 row_mask:0xf bank_mask:0xf
; __device__ __forceinline__ unsigned cvt_pk_bf16(float lo, float hi) { unsigned r; asm volatile("v_cvt_pk_bf16_f32 %0, %1, %2" : "=v"(r) : "v"(lo), "v"(hi)); return r; }
;     static __device__ __forceinline__ u32x2 finish2(const float (&g0)[4], const float (&g1)[4], const float (&g2)[4], const float (&w0)[4], const float (&w1)[4], const float (&w2)[4], const float (&bb)[4],
;                                                     const f32x4 v, float rs) {
;         float h[4];
; #pragma unroll
;         for (int j = 0; j < 4; j += 2) {
;             const f32x2 gc = (f32x2){bb[j] + w0[j] * g2[j] + w1[j] * g1[j] + w2[j] * g0[j], bb[j + 1] + w0[j + 1] * g2[j + 1] + w1[j + 1] * g1[j + 1] + w2[j + 1] * g0[j + 1]};
;             const f32x2 ge = gelu_pk(gc) * ((f32x2){v[j], v[j + 1]} * rs); h[j] = ge.x; h[j + 1] = ge.y; }
;         u32x2 w; w.x = cvt_pk_bf16(h[0], h[1]); w.y = cvt_pk_bf16(h[2], h[3]); return w;
;     }
;     __device__ __forceinline__ void operator()(const f32x4 (&acc)[2][2][4][2], const Unit& u, int wr, int wc, int fr, int fq) const {
;     ...
;             for (int ai = 0; ai < 2; ++ai) { const int R0 = u.rb + ai * HALF + wr * 64; const bf16_t* gp = G + (size_t)(R0 + fr) * 2816 + col8;
;                 u32x4 gq[4], prv = (u32x4){0u, 0u, 0u, 0u};
; #pragma unroll
;                 for (int m = 0; m < 4; ++m) gq[m] = *(const u32x4*)(gp + (size_t)m * 16 * 2816);
;                 if ((R0 & 8191) != 0) prv = *(const u32x4*)(gp - (size_t)16 * 2816);
;                 u32x4 pv = prv;
; #pragma unroll
;                 for (int m = 0; m < 4; ++m) { const u32x4 cur = gq[m]; u32x4 hw;
; #pragma unroll
;                     for (int hv = 0; hv < 2; ++hv) { const u32x2 c2 = half2(cur, hv), p2 = half2(pv, hv);
;                         const u32x2 q1 = dpp_prev<1>(p2, c2), q2 = dpp_prev<2>(p2, c2);
;                         float g0[4], g1[4], g2[4]; unpk4(c2, g0); unpk4(q1, g1); unpk4(q2, g2);
;                         const u32x2 r = finish2(g0, g1, g2, w0[hv], w1[hv], w2[hv], bb[hv], acc[ai][bj][m][hv], rs8[ai][m]);
;                         if (hv == 0) { hw.x = r.x; hw.y = r.y; } else { hw.z = r.x; hw.w = r.y; } }
;                     *(u32x4*)(H + (size_t)(R0 + fr + 16 * m) * 2816 + col8) = hw;
;                     pv = cur; } }
	v_lshlrev_b32_e32 v108, 16, v109
	v_and_b32_e32 v109, 0xffff0000, v109
	v_pk_fma_f32 v[108:109], v[132:133], v[108:109], v[144:145]
	v_mov_b32_dpp v111, v167 row_shr:2 row_mask:0xf bank_mask:0xf
	v_pk_fma_f32 v[104:105], v[136:137], v[104:105], v[108:109]
	v_mov_b32_dpp v107, v167 row_shr:1 row_mask:0xf bank_mask:0xf
	v_pk_fma_f32 v[104:105], v[140:141], v[112:113], v[104:105]
	v_lshlrev_b32_e32 v110, 16, v111
	v_pk_mul_f32 v[108:109], v[104:105], s[26:27] op_sel_hi:[1,0]
	v_and_b32_e32 v111, 0xffff0000, v111
	v_med3_f32 v108, v108, s71, v224
	v_med3_f32 v109, v109, s71, v224
	v_pk_mul_f32 v[112:113], v[108:109], v[108:109]
	v_pk_mul_f32 v[104:105], v[104:105], 0.5 op_sel_hi:[1,0]
	v_pk_fma_f32 v[114:115], v[112:113], s[28:29], v[210:211] op_sel_hi:[1,0,0] neg_lo:[1,0,0] neg_hi:[1,0,0]
	v_lshlrev_b32_e32 v106, 16, v107
	v_pk_fma_f32 v[114:115], v[112:113], v[114:115], s[34:35] op_sel_hi:[1,1,0]
	v_and_b32_e32 v107, 0xffff0000, v107
	v_pk_fma_f32 v[114:115], v[112:113], v[114:115], s[36:37] op_sel_hi:[1,1,0]
	s_nop 0
	v_pk_fma_f32 v[114:115], v[112:113], v[114:115], s[38:39] op_sel_hi:[1,1,0]
	s_nop 0
	v_pk_fma_f32 v[114:115], v[112:113], v[114:115], s[40:41] op_sel_hi:[1,1,0]
	s_nop 0
	v_pk_fma_f32 v[114:115], v[112:113], v[114:115], s[42:43] op_sel_hi:[1,1,0]
	s_nop 0
	v_pk_fma_f32 v[112:113], v[112:113], v[114:115], s[44:45] op_sel_hi:[1,1,0]
	s_nop 0
	v_pk_mul_f32 v[108:109], v[108:109], v[112:113]
	s_nop 0
	v_pk_fma_f32 v[104:105], v[104:105], v[108:109], v[104:105]
	v_pk_fma_f32 v[108:109], v[134:135], v[110:111], v[146:147]
	v_pk_mul_f32 v[100:101], v[100:101], v[104:105]
	v_lshlrev_b32_e32 v104, 16, v167
	v_and_b32_e32 v105, 0xffff0000, v167
	v_pk_fma_f32 v[106:107], v[138:139], v[106:107], v[108:109]
	v_cvt_pk_bf16_f32 v122, v100, v101
	v_mov_b64_e32 v[100:101], s[0:1]
	v_pk_fma_f32 v[104:105], v[142:143], v[104:105], v[106:107]
	v_mad_i64_i32 v[164:165], s[0:1], v1, s67, v[100:101]
	v_pk_mul_f32 v[106:107], v[104:105], s[26:27] op_sel_hi:[1,0]
	v_lshl_add_u64 v[118:119], v[164:165], 0, v[180:181]
	v_med3_f32 v106, v106, s71, v224
	v_med3_f32 v107, v107, s71, v224
	v_pk_mul_f32 v[108:109], v[106:107], v[106:107]
	v_pk_mul_f32 v[104:105], v[104:105], 0.5 op_sel_hi:[1,0]
	v_pk_fma_f32 v[110:111], v[108:109], s[28:29], v[210:211] op_sel_hi:[1,0,0] neg_lo:[1,0,0] neg_hi:[1,0,0]
	v_add_co_u32_e32 v100, vcc, s45, v118
	v_pk_fma_f32 v[110:111], v[108:109], v[110:111], s[34:35] op_sel_hi:[1,1,0]
	s_nop 0
	v_addc_co_u32_e32 v101, vcc, 0, v119, vcc
	v_pk_fma_f32 v[110:111], v[108:109], v[110:111], s[36:37] op_sel_hi:[1,1,0]
	v_mad_i64_i32 v[166:167], s[0:1], v190, s67, v[116:117]
	v_pk_fma_f32 v[110:111], v[108:109], v[110:111], s[38:39] op_sel_hi:[1,1,0]
	s_and_b32 s0, s47, 0x1fff
	v_pk_fma_f32 v[110:111], v[108:109], v[110:111], s[40:41] op_sel_hi:[1,1,0]
	s_cmp_lg_u32 s0, 0
	v_pk_fma_f32 v[110:111], v[108:109], v[110:111], s[42:43] op_sel_hi:[1,1,0]
	v_lshl_add_u64 v[116:117], v[166:167], 0, v[180:181]
	v_pk_fma_f32 v[108:109], v[108:109], v[110:111], s[44:45] op_sel_hi:[1,1,0]
	s_cselect_b64 s[8:9], -1, 0
	v_pk_mul_f32 v[106:107], v[106:107], v[108:109]
	s_cmp_eq_u32 s0, 0
	v_pk_fma_f32 v[104:105], v[104:105], v[106:107], v[104:105]
	s_nop 0
	v_pk_mul_f32 v[102:103], v[102:103], v[104:105]
	s_nop 0
	v_cvt_pk_bf16_f32 v123, v102, v103
	global_load_dwordx4 v[112:115], v[118:119], off
	global_load_dwordx4 v[108:111], v[100:101], off
	v_add_co_u32_e32 v100, vcc, 0x2c000, v118
	s_nop 1
	v_addc_co_u32_e32 v101, vcc, 0, v119, vcc
	v_add_co_u32_e32 v102, vcc, 0x42000, v118
	s_nop 1
	v_addc_co_u32_e32 v103, vcc, 0, v119, vcc
	global_load_dwordx4 v[104:107], v[100:101], off
	s_nop 0
	global_load_dwordx4 v[100:103], v[102:103], off
	s_nop 0
	global_store_dwordx4 v[116:117], v[120:123], off nt
	s_cbranch_scc1 .LBB0_3147
	v_add_co_u32_e32 v116, vcc, 0xfffea000, v118
	s_nop 1
	v_addc_co_u32_e32 v117, vcc, -1, v119, vcc
	global_load_dwordx4 v[116:119], v[116:117], off
	s_branch .LBB0_3148

;     static __device__ __forceinline__ u32x2 finish2(const float (&g0)[4], const float (&g1)[4], const float (&g2)[4], const float (&w0)[4], const float (&w1)[4], const float (&w2)[4], const float (&bb)[4],
;                                                     const f32x4 v, float rs) {
;         float h[4];
; #pragma unroll
;         for (int j = 0; j < 4; j += 2) {
;             const f32x2 gc = (f32x2){bb[j] + w0[j] * g2[j] + w1[j] * g1[j] + w2[j] * g0[j], bb[j + 1] + w0[j + 1] * g2[j + 1] + w1[j + 1] * g1[j + 1] + w2[j + 1] * g0[j + 1]};
;             const f32x2 ge = gelu_pk(gc) * ((f32x2){v[j], v[j + 1]} * rs); h[j] = ge.x; h[j + 1] = ge.y; }
;         u32x2 w; w.x = cvt_pk_bf16(h[0], h[1]); w.y = cvt_pk_bf16(h[2], h[3]); return w;
;     }
;     __device__ __forceinline__ void operator()(const f32x4 (&acc)[2][2][4][2], const Unit& u, int wr, int wc, int fr, int fq) const {
;     ...
;             for (int m = 0; m < 4; ++m) rs8[ai][m] = rsqrtf(SS[u.rb + (u.half ? 0 : ai * HALF) + wr * 64 + fr + 16 * m] * (1.f / 1024.f) + 1e-6f);
;     ...
;             for (int ai = 0; ai < 2; ++ai) { const int R0 = u.rb + ai * HALF + wr * 64; const bf16_t* gp = G + (size_t)(R0 + fr) * 2816 + col8;
;                 u32x4 gq[4], prv = (u32x4){0u, 0u, 0u, 0u};
; #pragma unroll
;                 for (int m = 0; m < 4; ++m) gq[m] = *(const u32x4*)(gp + (size_t)m * 16 * 2816);
;                 if ((R0 & 8191) != 0) prv = *(const u32x4*)(gp - (size_t)16 * 2816);
;                 u32x4 pv = prv;
; #pragma unroll
;                 for (int m = 0; m < 4; ++m) { const u32x4 cur = gq[m]; u32x4 hw;
; #pragma unroll
;                     for (int hv = 0; hv < 2; ++hv) { const u32x2 c2 = half2(cur, hv), p2 = half2(pv, hv);
;                         const u32x2 q1 = dpp_prev<1>(p2, c2), q2 = dpp_prev<2>(p2, c2);
;                         float g0[4], g1[4], g2[4]; unpk4(c2, g0); unpk4(q1, g1); unpk4(q2, g2);
;                         const u32x2 r = finish2(g0, g1, g2, w0[hv], w1[hv], w2[hv], bb[hv], acc[ai][bj][m][hv], rs8[ai][m]);
;                         if (hv == 0) { hw.x = r.x; hw.y = r.y; } else { hw.z = r.x; hw.w = r.y; } }
;                     *(u32x4*)(H + (size_t)(R0 + fr + 16 * m) * 2816 + col8) = hw;
;                     pv = cur; } }
.LBB0_3148:
	v_fmamk_f32 v120, v189, 0x3a800000, v223
	v_mul_f32_e32 v121, 0x4b800000, v120
	v_cmp_gt_f32_e32 vcc, s66, v120
	v_fmamk_f32 v3, v3, 0x3a800000, v223
	s_waitcnt vmcnt(0)
	v_mov_b32_dpp v127, v117 row_ror:2 row_mask:0xf bank_mask:0xf bound_ctrl:1
	v_cndmask_b32_e32 v120, v120, v121, vcc
	v_rsq_f32_e32 v122, v120
	v_fmamk_f32 v120, v187, 0x3a800000, v223
	v_mul_f32_e32 v121, 0x4b800000, v120
	v_cmp_gt_f32_e64 s[0:1], s66, v120
	v_mul_f32_e32 v124, 0x45800000, v122
	v_cndmask_b32_e32 v128, v122, v124, vcc
	v_cndmask_b32_e64 v120, v120, v121, s[0:1]
	v_mul_f32_e32 v124, 0x4b800000, v3
	v_cmp_gt_f32_e32 vcc, s66, v3
	v_rsq_f32_e32 v123, v120
	v_mad_i64_i32 v[120:121], s[6:7], v1, s67, 0
	v_cndmask_b32_e32 v3, v3, v124, vcc
	v_fmamk_f32 v124, v185, 0x3a800000, v223
	v_mul_f32_e32 v125, 0x4b800000, v124
	v_cmp_gt_f32_e64 s[6:7], s66, v124
	v_rsq_f32_e32 v3, v3
	v_mul_f32_e32 v122, 0x45800000, v123
	v_cndmask_b32_e64 v124, v124, v125, s[6:7]
	v_rsq_f32_e32 v125, v124
	v_cndmask_b32_e64 v126, v123, v122, s[0:1]
	v_mul_f32_e32 v122, 0x45800000, v3
	v_cndmask_b32_e32 v124, v3, v122, vcc
	v_mul_f32_e32 v3, 0x45800000, v125
	v_cndmask_b32_e64 v122, v125, v3, s[6:7]
	v_mov_b32_dpp v125, v116 row_ror:2 row_mask:0xf bank_mask:0xf bound_ctrl:1
	v_mov_b32_dpp v3, v116 row_ror:1 row_mask:0xf bank_mask:0xf bound_ctrl:1
	v_mov_b32_dpp v123, v117 row_ror:1 row_mask:0xf bank_mask:0xf bound_ctrl:1
	v_mov_b32_dpp v125, v112 row_shr:2 row_mask:0xf bank_mask:0xf
	v_mov_b32_dpp v3, v112 row_shr:1 row_mask:0xf bank_mask:0xf
	v_lshlrev_b32_e32 v170, 16, v125
	v_and_b32_e32 v171, 0xffff0000, v125
	v_lshlrev_b32_e32 v116, 16, v3
	v_and_b32_e32 v117, 0xffff0000, v3
	v_pk_fma_f32 v[170:171], v[148:149], v[170:171], v[160:161]
	v_lshlrev_b32_e32 v178, 16, v112
	v_and_b32_e32 v179, 0xffff0000, v112
	v_pk_fma_f32 v[116:117], v[152:153], v[116:117], v[170:171]
	v_mov_b32_dpp v127, v113 row_shr:2 row_mask:0xf bank_mask:0xf
	v_pk_fma_f32 v[170:171], v[156:157], v[178:179], v[116:117]
	v_mov_b32_dpp v123, v113 row_shr:1 row_mask:0xf bank_mask:0xf
	v_pk_mul_f32 v[116:117], v[170:171], s[26:27] op_sel_hi:[1,0]
	v_lshlrev_b32_e32 v174, 16, v127
	v_med3_f32 v178, v116, s71, v224
	v_med3_f32 v179, v117, s71, v224
	v_pk_mul_f32 v[182:183], v[178:179], v[178:179]
	v_mov_b64_e32 v[116:117], s[30:31]
	v_pk_fma_f32 v[190:191], v[182:183], s[28:29], v[116:117] op_sel_hi:[1,0,0] neg_lo:[1,0,0] neg_hi:[1,0,0]
	v_and_b32_e32 v175, 0xffff0000, v127
	v_pk_fma_f32 v[190:191], v[182:183], v[190:191], s[34:35] op_sel_hi:[1,1,0]
	v_pk_mul_f32 v[170:171], v[170:171], 0.5 op_sel_hi:[1,0]
	v_pk_fma_f32 v[190:191], v[182:183], v[190:191], s[36:37] op_sel_hi:[1,1,0]
	v_lshlrev_b32_e32 v168, 16, v123
	v_pk_fma_f32 v[190:191], v[182:183], v[190:191], s[38:39] op_sel_hi:[1,1,0]
	v_and_b32_e32 v169, 0xffff0000, v123
	v_pk_fma_f32 v[190:191], v[182:183], v[190:191], s[40:41] op_sel_hi:[1,1,0]
	v_pk_mul_f32 v[96:97], v[96:97], v[128:129] op_sel_hi:[1,0]
	v_pk_fma_f32 v[190:191], v[182:183], v[190:191], s[42:43] op_sel_hi:[1,1,0]
	v_pk_fma_f32 v[174:175], v[150:151], v[174:175], v[162:163]
	v_pk_fma_f32 v[182:183], v[182:183], v[190:191], s[44:45] op_sel_hi:[1,1,0]
	v_pk_fma_f32 v[168:169], v[154:155], v[168:169], v[174:175]
	v_pk_mul_f32 v[178:179], v[178:179], v[182:183]
	v_mov_b32_dpp v125, v118 row_ror:2 row_mask:0xf bank_mask:0xf bound_ctrl:1
	v_pk_fma_f32 v[170:171], v[170:171], v[178:179], v[170:171]
	v_pk_mul_f32 v[98:99], v[98:99], v[128:129] op_sel_hi:[1,0]
	v_pk_mul_f32 v[96:97], v[96:97], v[170:171]
	v_lshlrev_b32_e32 v170, 16, v113
	v_and_b32_e32 v171, 0xffff0000, v113
	v_pk_fma_f32 v[168:169], v[158:159], v[170:171], v[168:169]
	v_mov_b32_dpp v3, v118 row_ror:1 row_mask:0xf bank_mask:0xf bound_ctrl:1
	v_pk_mul_f32 v[170:171], v[168:169], s[26:27] op_sel_hi:[1,0]
	v_pk_mul_f32 v[168:169], v[168:169], 0.5 op_sel_hi:[1,0]
	v_med3_f32 v170, v170, s71, v224
	v_med3_f32 v171, v171, s71, v224
	v_pk_mul_f32 v[174:175], v[170:171], v[170:171]
	v_mov_b32_dpp v125, v114 row_shr:2 row_mask:0xf bank_mask:0xf
	v_pk_fma_f32 v[178:179], v[174:175], s[28:29], v[116:117] op_sel_hi:[1,0,0] neg_lo:[1,0,0] neg_hi:[1,0,0]
	v_mov_b32_dpp v3, v114 row_shr:1 row_mask:0xf bank_mask:0xf
	v_pk_fma_f32 v[178:179], v[174:175], v[178:179], s[34:35] op_sel_hi:[1,1,0]
	v_cvt_pk_bf16_f32 v96, v96, v97
	v_mov_b32_dpp v127, v119 row_ror:2 row_mask:0xf bank_mask:0xf bound_ctrl:1
	v_pk_fma_f32 v[178:179], v[174:175], v[178:179], s[36:37] op_sel_hi:[1,1,0]
	v_mov_b32_dpp v123, v119 row_ror:1 row_mask:0xf bank_mask:0xf bound_ctrl:1
	v_pk_fma_f32 v[178:179], v[174:175], v[178:179], s[38:39] op_sel_hi:[1,1,0]
	v_mov_b32_dpp v127, v115 row_shr:2 row_mask:0xf bank_mask:0xf
	v_pk_fma_f32 v[178:179], v[174:175], v[178:179], s[40:41] op_sel_hi:[1,1,0]
	v_mov_b32_dpp v123, v115 row_shr:1 row_mask:0xf bank_mask:0xf
	v_pk_fma_f32 v[178:179], v[174:175], v[178:179], s[42:43] op_sel_hi:[1,1,0]
	v_lshlrev_b32_e32 v118, 16, v123
	v_pk_fma_f32 v[174:175], v[174:175], v[178:179], s[44:45] op_sel_hi:[1,1,0]
	v_and_b32_e32 v119, 0xffff0000, v123
	v_pk_mul_f32 v[170:171], v[170:171], v[174:175]
	v_lshlrev_b32_e32 v174, 16, v114
	v_pk_fma_f32 v[168:169], v[168:169], v[170:171], v[168:169]
	v_and_b32_e32 v175, 0xffff0000, v114
	v_pk_mul_f32 v[98:99], v[98:99], v[168:169]
	v_lshlrev_b32_e32 v168, 16, v125
	v_and_b32_e32 v169, 0xffff0000, v125
	v_cvt_pk_bf16_f32 v97, v98, v99
	v_lshlrev_b32_e32 v98, 16, v3
	v_and_b32_e32 v99, 0xffff0000, v3
	v_pk_fma_f32 v[168:169], v[132:133], v[168:169], v[144:145]
	v_lshlrev_b32_e32 v170, 16, v127
	v_pk_fma_f32 v[98:99], v[136:137], v[98:99], v[168:169]
	v_and_b32_e32 v171, 0xffff0000, v127
; __device__ __forceinline__ unsigned cvt_pk_bf16(float lo, float hi) { unsigned r; asm volatile("v_cvt_pk_bf16_f32 %0, %1, %2" : "=v"(r) : "v"(lo), "v"(hi)); return r; }
;     static __device__ __forceinline__ u32x2 finish2(const float (&g0)[4], const float (&g1)[4], const float (&g2)[4], const float (&w0)[4], const float (&w1)[4], const float (&w2)[4], const float (&bb)[4],
;                                                     const f32x4 v, float rs) {
;         float h[4];
; #pragma unroll
;         for (int j = 0; j < 4; j += 2) {
;             const f32x2 gc = (f32x2){bb[j] + w0[j] * g2[j] + w1[j] * g1[j] + w2[j] * g0[j], bb[j + 1] + w0[j + 1] * g2[j + 1] + w1[j + 1] * g1[j + 1] + w2[j + 1] * g0[j + 1]};
;             const f32x2 ge = gelu_pk(gc) * ((f32x2){v[j], v[j + 1]} * rs); h[j] = ge.x; h[j + 1] = ge.y; }
;         u32x2 w; w.x = cvt_pk_bf16(h[0], h[1]); w.y = cvt_pk_bf16(h[2], h[3]); return w;
;     }
;     __device__ __forceinline__ void operator()(const f32x4 (&acc)[2][2][4][2], const Unit& u, int wr, int wc, int fr, int fq) const {
;     ...
;             for (int ai = 0; ai < 2; ++ai) { const int R0 = u.rb + ai * HALF + wr * 64; const bf16_t* gp = G + (size_t)(R0 + fr) * 2816 + col8;
;                 u32x4 gq[4], prv = (u32x4){0u, 0u, 0u, 0u};
; #pragma unroll
;                 for (int m = 0; m < 4; ++m) gq[m] = *(const u32x4*)(gp + (size_t)m * 16 * 2816);
;                 if ((R0 & 8191) != 0) prv = *(const u32x4*)(gp - (size_t)16 * 2816);
;                 u32x4 pv = prv;
; #pragma unroll
;                 for (int m = 0; m < 4; ++m) { const u32x4 cur = gq[m]; u32x4 hw;
; #pragma unroll
;                     for (int hv = 0; hv < 2; ++hv) { const u32x2 c2 = half2(cur, hv), p2 = half2(pv, hv);
;                         const u32x2 q1 = dpp_prev<1>(p2, c2), q2 = dpp_prev<2>(p2, c2);
;                         float g0[4], g1[4], g2[4]; unpk4(c2, g0); unpk4(q1, g1); unpk4(q2, g2);
;                         const u32x2 r = finish2(g0, g1, g2, w0[hv], w1[hv], w2[hv], bb[hv], acc[ai][bj][m][hv], rs8[ai][m]);
;                         if (hv == 0) { hw.x = r.x; hw.y = r.y; } else { hw.z = r.x; hw.w = r.y; } }
;                     *(u32x4*)(H + (size_t)(R0 + fr + 16 * m) * 2816 + col8) = hw;
;                     pv = cur; } }
	v_pk_fma_f32 v[98:99], v[140:141], v[174:175], v[98:99]
	v_pk_mul_f32 v[92:93], v[92:93], v[128:129] op_sel_hi:[1,0]
	v_pk_mul_f32 v[168:169], v[98:99], s[26:27] op_sel_hi:[1,0]
	v_pk_mul_f32 v[98:99], v[98:99], 0.5 op_sel_hi:[1,0]
	v_med3_f32 v168, v168, s71, v224
	v_med3_f32 v169, v169, s71, v224
	v_pk_mul_f32 v[174:175], v[168:169], v[168:169]
	v_readlane_b32 s0, v240, 58
	v_pk_fma_f32 v[178:179], v[174:175], s[28:29], v[116:117] op_sel_hi:[1,0,0] neg_lo:[1,0,0] neg_hi:[1,0,0]
	v_readlane_b32 s1, v240, 59
	v_pk_fma_f32 v[178:179], v[174:175], v[178:179], s[34:35] op_sel_hi:[1,1,0]
	v_pk_mul_f32 v[94:95], v[94:95], v[128:129] op_sel_hi:[1,0]
	v_pk_fma_f32 v[178:179], v[174:175], v[178:179], s[36:37] op_sel_hi:[1,1,0]
	v_mov_b32_dpp v3, v112 row_ror:1 row_mask:0xf bank_mask:0xf bound_ctrl:1
	v_pk_fma_f32 v[178:179], v[174:175], v[178:179], s[38:39] op_sel_hi:[1,1,0]
	v_pk_mul_f32 v[88:89], v[88:89], v[126:127] op_sel_hi:[1,0]
	v_pk_fma_f32 v[178:179], v[174:175], v[178:179], s[40:41] op_sel_hi:[1,1,0]
	v_mov_b32_dpp v3, v108 row_shr:1 row_mask:0xf bank_mask:0xf
	v_pk_fma_f32 v[178:179], v[174:175], v[178:179], s[42:43] op_sel_hi:[1,1,0]
	v_pk_mul_f32 v[90:91], v[90:91], v[126:127] op_sel_hi:[1,0]
	v_pk_fma_f32 v[174:175], v[174:175], v[178:179], s[44:45] op_sel_hi:[1,1,0]
	v_pk_mul_f32 v[84:85], v[84:85], v[126:127] op_sel_hi:[1,0]
	v_pk_mul_f32 v[168:169], v[168:169], v[174:175]
	v_pk_mul_f32 v[86:87], v[86:87], v[126:127] op_sel_hi:[1,0]
	v_pk_fma_f32 v[98:99], v[98:99], v[168:169], v[98:99]
	v_pk_fma_f32 v[168:169], v[134:135], v[170:171], v[146:147]
	v_pk_mul_f32 v[92:93], v[92:93], v[98:99]
	v_lshlrev_b32_e32 v98, 16, v115
	v_and_b32_e32 v99, 0xffff0000, v115
	v_pk_fma_f32 v[118:119], v[138:139], v[118:119], v[168:169]
	v_pk_mul_f32 v[80:81], v[80:81], v[124:125] op_sel_hi:[1,0]
	v_pk_fma_f32 v[98:99], v[142:143], v[98:99], v[118:119]
	v_pk_mul_f32 v[82:83], v[82:83], v[124:125] op_sel_hi:[1,0]
	v_pk_mul_f32 v[118:119], v[98:99], s[26:27] op_sel_hi:[1,0]
	v_pk_mul_f32 v[98:99], v[98:99], 0.5 op_sel_hi:[1,0]
	v_med3_f32 v118, v118, s71, v224
	v_med3_f32 v119, v119, s71, v224
	v_pk_mul_f32 v[168:169], v[118:119], v[118:119]
	v_pk_mul_f32 v[76:77], v[76:77], v[124:125] op_sel_hi:[1,0]
	v_pk_fma_f32 v[170:171], v[168:169], s[28:29], v[116:117] op_sel_hi:[1,0,0] neg_lo:[1,0,0] neg_hi:[1,0,0]
	v_pk_mul_f32 v[78:79], v[78:79], v[124:125] op_sel_hi:[1,0]
	v_pk_fma_f32 v[170:171], v[168:169], v[170:171], s[34:35] op_sel_hi:[1,1,0]
	v_pk_mul_f32 v[72:73], v[72:73], v[122:123] op_sel_hi:[1,0]
	v_pk_fma_f32 v[170:171], v[168:169], v[170:171], s[36:37] op_sel_hi:[1,1,0]
	v_pk_mul_f32 v[74:75], v[74:75], v[122:123] op_sel_hi:[1,0]
	v_pk_fma_f32 v[170:171], v[168:169], v[170:171], s[38:39] op_sel_hi:[1,1,0]
	v_pk_mul_f32 v[64:65], v[64:65], v[122:123] op_sel_hi:[1,0]
	v_pk_fma_f32 v[170:171], v[168:169], v[170:171], s[40:41] op_sel_hi:[1,1,0]
	v_pk_mul_f32 v[66:67], v[66:67], v[122:123] op_sel_hi:[1,0]
	v_pk_fma_f32 v[170:171], v[168:169], v[170:171], s[42:43] op_sel_hi:[1,1,0]
	s_nop 0
	v_pk_fma_f32 v[168:169], v[168:169], v[170:171], s[44:45] op_sel_hi:[1,1,0]
	s_nop 0
	v_pk_mul_f32 v[118:119], v[118:119], v[168:169]
	v_lshl_add_u64 v[168:169], s[0:1], 0, v[120:121]
	v_pk_fma_f32 v[98:99], v[98:99], v[118:119], v[98:99]
	v_mov_b32_e32 v120, 0
	v_pk_mul_f32 v[94:95], v[94:95], v[98:99]
	v_cvt_pk_bf16_f32 v98, v92, v93
	v_lshl_add_u64 v[92:93], v[168:169], 0, v[180:181]
	v_cvt_pk_bf16_f32 v99, v94, v95
	global_store_dwordx4 v[92:93], v[96:99], off nt
	v_lshlrev_b32_e32 v92, 16, v3
	v_and_b32_e32 v93, 0xffff0000, v3
	v_mov_b32_dpp v97, v112 row_ror:2 row_mask:0xf bank_mask:0xf bound_ctrl:1
	v_mov_b32_dpp v95, v113 row_ror:1 row_mask:0xf bank_mask:0xf bound_ctrl:1
	v_mov_b32_dpp v99, v113 row_ror:2 row_mask:0xf bank_mask:0xf bound_ctrl:1
	v_mov_b32_dpp v97, v108 row_shr:2 row_mask:0xf bank_mask:0xf
	v_lshlrev_b32_e32 v96, 16, v97
	v_and_b32_e32 v97, 0xffff0000, v97
	v_pk_fma_f32 v[96:97], v[148:149], v[96:97], v[160:161]
	v_lshlrev_b32_e32 v112, 16, v108
	v_and_b32_e32 v113, 0xffff0000, v108
	v_pk_fma_f32 v[92:93], v[152:153], v[92:93], v[96:97]
	v_mov_b32_dpp v99, v109 row_shr:2 row_mask:0xf bank_mask:0xf
	v_pk_fma_f32 v[92:93], v[156:157], v[112:113], v[92:93]
	v_mov_b32_dpp v95, v109 row_shr:1 row_mask:0xf bank_mask:0xf
	v_pk_mul_f32 v[96:97], v[92:93], s[26:27] op_sel_hi:[1,0]
	v_lshlrev_b32_e32 v98, 16, v99
	v_med3_f32 v96, v96, s71, v224
	v_med3_f32 v97, v97, s71, v224
	v_pk_mul_f32 v[112:113], v[96:97], v[96:97]
	v_and_b32_e32 v99, 0xffff0000, v99
	v_pk_fma_f32 v[118:119], v[112:113], s[28:29], v[116:117] op_sel_hi:[1,0,0] neg_lo:[1,0,0] neg_hi:[1,0,0]
	v_pk_mul_f32 v[92:93], v[92:93], 0.5 op_sel_hi:[1,0]
	v_pk_fma_f32 v[118:119], v[112:113], v[118:119], s[34:35] op_sel_hi:[1,1,0]
	v_lshlrev_b32_e32 v94, 16, v95
	v_pk_fma_f32 v[118:119], v[112:113], v[118:119], s[36:37] op_sel_hi:[1,1,0]
	v_and_b32_e32 v95, 0xffff0000, v95
	v_pk_fma_f32 v[118:119], v[112:113], v[118:119], s[38:39] op_sel_hi:[1,1,0]
	v_mov_b32_dpp v3, v114 row_ror:1 row_mask:0xf bank_mask:0xf bound_ctrl:1
	v_pk_fma_f32 v[118:119], v[112:113], v[118:119], s[40:41] op_sel_hi:[1,1,0]
	v_mov_b32_e32 v121, 0
	v_pk_fma_f32 v[118:119], v[112:113], v[118:119], s[42:43] op_sel_hi:[1,1,0]
	v_mov_b32_dpp v3, v110 row_shr:1 row_mask:0xf bank_mask:0xf
	v_pk_fma_f32 v[112:113], v[112:113], v[118:119], s[44:45] op_sel_hi:[1,1,0]
	v_mov_b32_e32 v118, 0
	v_pk_mul_f32 v[96:97], v[96:97], v[112:113]
	v_mov_b32_e32 v119, 0
	v_pk_fma_f32 v[92:93], v[92:93], v[96:97], v[92:93]
	v_pk_fma_f32 v[96:97], v[150:151], v[98:99], v[162:163]
	v_pk_mul_f32 v[88:89], v[88:89], v[92:93]
	v_lshlrev_b32_e32 v92, 16, v109
; __device__ __forceinline__ unsigned cvt_pk_bf16(float lo, float hi) { unsigned r; asm volatile("v_cvt_pk_bf16_f32 %0, %1, %2" : "=v"(r) : "v"(lo), "v"(hi)); return r; }
;     static __device__ __forceinline__ u32x2 finish2(const float (&g0)[4], const float (&g1)[4], const float (&g2)[4], const float (&w0)[4], const float (&w1)[4], const float (&w2)[4], const float (&bb)[4],
;                                                     const f32x4 v, float rs) {
;         float h[4];
; #pragma unroll
;         for (int j = 0; j < 4; j += 2) {
;             const f32x2 gc = (f32x2){bb[j] + w0[j] * g2[j] + w1[j] * g1[j] + w2[j] * g0[j], bb[j + 1] + w0[j + 1] * g2[j + 1] + w1[j + 1] * g1[j + 1] + w2[j + 1] * g0[j + 1]};
;             const f32x2 ge = gelu_pk(gc) * ((f32x2){v[j], v[j + 1]} * rs); h[j] = ge.x; h[j + 1] = ge.y; }
;         u32x2 w; w.x = cvt_pk_bf16(h[0], h[1]); w.y = cvt_pk_bf16(h[2], h[3]); return w;
;     }
;     __device__ __forceinline__ void operator()(const f32x4 (&acc)[2][2][4][2], const Unit& u, int wr, int wc, int fr, int fq) const {
;     ...
;             for (int ai = 0; ai < 2; ++ai) { const int R0 = u.rb + ai * HALF + wr * 64; const bf16_t* gp = G + (size_t)(R0 + fr) * 2816 + col8;
;                 u32x4 gq[4], prv = (u32x4){0u, 0u, 0u, 0u};
; #pragma unroll
;                 for (int m = 0; m < 4; ++m) gq[m] = *(const u32x4*)(gp + (size_t)m * 16 * 2816);
;                 if ((R0 & 8191) != 0) prv = *(const u32x4*)(gp - (size_t)16 * 2816);
;                 u32x4 pv = prv;
; #pragma unroll
;                 for (int m = 0; m < 4; ++m) { const u32x4 cur = gq[m]; u32x4 hw;
; #pragma unroll
;                     for (int hv = 0; hv < 2; ++hv) { const u32x2 c2 = half2(cur, hv), p2 = half2(pv, hv);
;                         const u32x2 q1 = dpp_prev<1>(p2, c2), q2 = dpp_prev<2>(p2, c2);
;                         float g0[4], g1[4], g2[4]; unpk4(c2, g0); unpk4(q1, g1); unpk4(q2, g2);
;                         const u32x2 r = finish2(g0, g1, g2, w0[hv], w1[hv], w2[hv], bb[hv], acc[ai][bj][m][hv], rs8[ai][m]);
;                         if (hv == 0) { hw.x = r.x; hw.y = r.y; } else { hw.z = r.x; hw.w = r.y; } }
;                     *(u32x4*)(H + (size_t)(R0 + fr + 16 * m) * 2816 + col8) = hw;
;                     pv = cur; } }
	v_and_b32_e32 v93, 0xffff0000, v109
	v_pk_fma_f32 v[94:95], v[154:155], v[94:95], v[96:97]
	v_cvt_pk_bf16_f32 v88, v88, v89
	s_nop 0
	v_pk_fma_f32 v[92:93], v[158:159], v[92:93], v[94:95]
	s_nop 0
	v_pk_mul_f32 v[94:95], v[92:93], s[26:27] op_sel_hi:[1,0]
	v_pk_mul_f32 v[92:93], v[92:93], 0.5 op_sel_hi:[1,0]
	v_med3_f32 v94, v94, s71, v224
	v_med3_f32 v95, v95, s71, v224
	v_pk_mul_f32 v[96:97], v[94:95], v[94:95]
	s_nop 0
	v_pk_fma_f32 v[98:99], v[96:97], s[28:29], v[116:117] op_sel_hi:[1,0,0] neg_lo:[1,0,0] neg_hi:[1,0,0]
	s_nop 0
	v_pk_fma_f32 v[98:99], v[96:97], v[98:99], s[34:35] op_sel_hi:[1,1,0]
	s_nop 0
	v_pk_fma_f32 v[98:99], v[96:97], v[98:99], s[36:37] op_sel_hi:[1,1,0]
	s_nop 0
	v_pk_fma_f32 v[98:99], v[96:97], v[98:99], s[38:39] op_sel_hi:[1,1,0]
	s_nop 0
	v_pk_fma_f32 v[98:99], v[96:97], v[98:99], s[40:41] op_sel_hi:[1,1,0]
	s_nop 0
	v_pk_fma_f32 v[98:99], v[96:97], v[98:99], s[42:43] op_sel_hi:[1,1,0]
	s_nop 0
	v_pk_fma_f32 v[96:97], v[96:97], v[98:99], s[44:45] op_sel_hi:[1,1,0]
	v_lshlrev_b32_e32 v98, 16, v110
	v_pk_mul_f32 v[94:95], v[94:95], v[96:97]
	v_and_b32_e32 v99, 0xffff0000, v110
	v_pk_fma_f32 v[92:93], v[92:93], v[94:95], v[92:93]
	v_mov_b32_dpp v95, v114 row_ror:2 row_mask:0xf bank_mask:0xf bound_ctrl:1
	v_pk_mul_f32 v[90:91], v[90:91], v[92:93]
	v_mov_b32_dpp v97, v115 row_ror:2 row_mask:0xf bank_mask:0xf bound_ctrl:1
	v_mov_b32_dpp v95, v110 row_shr:2 row_mask:0xf bank_mask:0xf
	v_lshlrev_b32_e32 v94, 16, v95
	v_and_b32_e32 v95, 0xffff0000, v95
	v_cvt_pk_bf16_f32 v89, v90, v91
	v_lshlrev_b32_e32 v90, 16, v3
	v_and_b32_e32 v91, 0xffff0000, v3
	v_pk_fma_f32 v[94:95], v[132:133], v[94:95], v[144:145]
	v_mov_b32_dpp v93, v115 row_ror:1 row_mask:0xf bank_mask:0xf bound_ctrl:1
	v_pk_fma_f32 v[90:91], v[136:137], v[90:91], v[94:95]
	v_mov_b32_dpp v97, v111 row_shr:2 row_mask:0xf bank_mask:0xf
	v_pk_fma_f32 v[90:91], v[140:141], v[98:99], v[90:91]
	v_mov_b32_dpp v93, v111 row_shr:1 row_mask:0xf bank_mask:0xf
	v_pk_mul_f32 v[94:95], v[90:91], s[26:27] op_sel_hi:[1,0]
	v_lshlrev_b32_e32 v96, 16, v97
	v_med3_f32 v94, v94, s71, v224
	v_med3_f32 v95, v95, s71, v224
	v_pk_mul_f32 v[98:99], v[94:95], v[94:95]
	v_and_b32_e32 v97, 0xffff0000, v97
	v_pk_fma_f32 v[112:113], v[98:99], s[28:29], v[116:117] op_sel_hi:[1,0,0] neg_lo:[1,0,0] neg_hi:[1,0,0]
	v_pk_mul_f32 v[90:91], v[90:91], 0.5 op_sel_hi:[1,0]
	v_pk_fma_f32 v[112:113], v[98:99], v[112:113], s[34:35] op_sel_hi:[1,1,0]
	v_lshlrev_b32_e32 v92, 16, v93
	v_pk_fma_f32 v[112:113], v[98:99], v[112:113], s[36:37] op_sel_hi:[1,1,0]
	v_and_b32_e32 v93, 0xffff0000, v93
	v_pk_fma_f32 v[112:113], v[98:99], v[112:113], s[38:39] op_sel_hi:[1,1,0]
	v_add_u32_e32 v3, 16, v1
	v_pk_fma_f32 v[112:113], v[98:99], v[112:113], s[40:41] op_sel_hi:[1,1,0]
	s_nop 0
	v_pk_fma_f32 v[112:113], v[98:99], v[112:113], s[42:43] op_sel_hi:[1,1,0]
	s_nop 0
	v_pk_fma_f32 v[98:99], v[98:99], v[112:113], s[44:45] op_sel_hi:[1,1,0]
	s_nop 0
	v_pk_mul_f32 v[94:95], v[94:95], v[98:99]
	s_nop 0
	v_pk_fma_f32 v[90:91], v[90:91], v[94:95], v[90:91]
	v_pk_fma_f32 v[94:95], v[134:135], v[96:97], v[146:147]
	v_pk_mul_f32 v[84:85], v[84:85], v[90:91]
	v_lshlrev_b32_e32 v90, 16, v111
	v_and_b32_e32 v91, 0xffff0000, v111
	v_pk_fma_f32 v[92:93], v[138:139], v[92:93], v[94:95]
	s_nop 0
	v_pk_fma_f32 v[90:91], v[142:143], v[90:91], v[92:93]
	s_nop 0
	v_pk_mul_f32 v[92:93], v[90:91], s[26:27] op_sel_hi:[1,0]
	v_pk_mul_f32 v[90:91], v[90:91], 0.5 op_sel_hi:[1,0]
	v_med3_f32 v92, v92, s71, v224
	v_med3_f32 v93, v93, s71, v224
	v_pk_mul_f32 v[94:95], v[92:93], v[92:93]
	s_nop 0
	v_pk_fma_f32 v[96:97], v[94:95], s[28:29], v[116:117] op_sel_hi:[1,0,0] neg_lo:[1,0,0] neg_hi:[1,0,0]
	s_nop 0
	v_pk_fma_f32 v[96:97], v[94:95], v[96:97], s[34:35] op_sel_hi:[1,1,0]
	s_nop 0
	v_pk_fma_f32 v[96:97], v[94:95], v[96:97], s[36:37] op_sel_hi:[1,1,0]
	s_nop 0
	v_pk_fma_f32 v[96:97], v[94:95], v[96:97], s[38:39] op_sel_hi:[1,1,0]
	s_nop 0
	v_pk_fma_f32 v[96:97], v[94:95], v[96:97], s[40:41] op_sel_hi:[1,1,0]
	s_nop 0
	v_pk_fma_f32 v[96:97], v[94:95], v[96:97], s[42:43] op_sel_hi:[1,1,0]
	s_nop 0
	v_pk_fma_f32 v[94:95], v[94:95], v[96:97], s[44:45] op_sel_hi:[1,1,0]
	s_nop 0
	v_pk_mul_f32 v[92:93], v[92:93], v[94:95]
	v_lshlrev_b32_e32 v94, 16, v104
	v_pk_fma_f32 v[90:91], v[90:91], v[92:93], v[90:91]
	v_and_b32_e32 v95, 0xffff0000, v104
	v_pk_mul_f32 v[86:87], v[86:87], v[90:91]
	v_cvt_pk_bf16_f32 v90, v84, v85
	v_mov_b64_e32 v[84:85], s[0:1]
	v_mad_i64_i32 v[170:171], s[0:1], v3, s67, v[84:85]
	v_cvt_pk_bf16_f32 v91, v86, v87
	v_lshl_add_u64 v[86:87], v[170:171], 0, v[180:181]
	global_store_dwordx4 v[86:87], v[88:91], off nt
	v_mov_b32_dpp v3, v108 row_ror:1 row_mask:0xf bank_mask:0xf bound_ctrl:1
	v_mov_b32_dpp v93, v109 row_ror:2 row_mask:0xf bank_mask:0xf bound_ctrl:1
	v_mov_b32_dpp v91, v108 row_ror:2 row_mask:0xf bank_mask:0xf bound_ctrl:1
	v_mov_b32_dpp v3, v104 row_shr:1 row_mask:0xf bank_mask:0xf
	v_lshlrev_b32_e32 v86, 16, v3
	v_mov_b32_dpp v91, v104 row_shr:2 row_mask:0xf bank_mask:0xf
	v_lshlrev_b32_e32 v90, 16, v91
	v_and_b32_e32 v91, 0xffff0000, v91
	v_and_b32_e32 v87, 0xffff0000, v3
	v_pk_fma_f32 v[90:91], v[148:149], v[90:91], v[160:161]
	v_mov_b32_dpp v89, v109 row_ror:1 row_mask:0xf bank_mask:0xf bound_ctrl:1
	v_pk_fma_f32 v[86:87], v[152:153], v[86:87], v[90:91]
	v_mov_b32_dpp v93, v105 row_shr:2 row_mask:0xf bank_mask:0xf
	v_pk_fma_f32 v[86:87], v[156:157], v[94:95], v[86:87]
	v_mov_b32_dpp v89, v105 row_shr:1 row_mask:0xf bank_mask:0xf
	v_pk_mul_f32 v[90:91], v[86:87], s[26:27] op_sel_hi:[1,0]
	v_lshlrev_b32_e32 v92, 16, v93
	v_med3_f32 v90, v90, s71, v224
	v_med3_f32 v91, v91, s71, v224
	v_pk_mul_f32 v[94:95], v[90:91], v[90:91]
; __device__ __forceinline__ unsigned cvt_pk_bf16(float lo, float hi) { unsigned r; asm volatile("v_cvt_pk_bf16_f32 %0, %1, %2" : "=v"(r) : "v"(lo), "v"(hi)); return r; }
;     static __device__ __forceinline__ u32x2 finish2(const float (&g0)[4], const float (&g1)[4], const float (&g2)[4], const float (&w0)[4], const float (&w1)[4], const float (&w2)[4], const float (&bb)[4],
;                                                     const f32x4 v, float rs) {
;         float h[4];
; #pragma unroll
;         for (int j = 0; j < 4; j += 2) {
;             const f32x2 gc = (f32x2){bb[j] + w0[j] * g2[j] + w1[j] * g1[j] + w2[j] * g0[j], bb[j + 1] + w0[j + 1] * g2[j + 1] + w1[j + 1] * g1[j + 1] + w2[j + 1] * g0[j + 1]};
;             const f32x2 ge = gelu_pk(gc) * ((f32x2){v[j], v[j + 1]} * rs); h[j] = ge.x; h[j + 1] = ge.y; }
;         u32x2 w; w.x = cvt_pk_bf16(h[0], h[1]); w.y = cvt_pk_bf16(h[2], h[3]); return w;
;     }
;     __device__ __forceinline__ void operator()(const f32x4 (&acc)[2][2][4][2], const Unit& u, int wr, int wc, int fr, int fq) const {
;     ...
;             for (int ai = 0; ai < 2; ++ai) { const int R0 = u.rb + ai * HALF + wr * 64; const bf16_t* gp = G + (size_t)(R0 + fr) * 2816 + col8;
;                 u32x4 gq[4], prv = (u32x4){0u, 0u, 0u, 0u};
; #pragma unroll
;                 for (int m = 0; m < 4; ++m) gq[m] = *(const u32x4*)(gp + (size_t)m * 16 * 2816);
;                 if ((R0 & 8191) != 0) prv = *(const u32x4*)(gp - (size_t)16 * 2816);
;                 u32x4 pv = prv;
; #pragma unroll
;                 for (int m = 0; m < 4; ++m) { const u32x4 cur = gq[m]; u32x4 hw;
; #pragma unroll
;                     for (int hv = 0; hv < 2; ++hv) { const u32x2 c2 = half2(cur, hv), p2 = half2(pv, hv);
;                         const u32x2 q1 = dpp_prev<1>(p2, c2), q2 = dpp_prev<2>(p2, c2);
;                         float g0[4], g1[4], g2[4]; unpk4(c2, g0); unpk4(q1, g1); unpk4(q2, g2);
;                         const u32x2 r = finish2(g0, g1, g2, w0[hv], w1[hv], w2[hv], bb[hv], acc[ai][bj][m][hv], rs8[ai][m]);
;                         if (hv == 0) { hw.x = r.x; hw.y = r.y; } else { hw.z = r.x; hw.w = r.y; } }
;                     *(u32x4*)(H + (size_t)(R0 + fr + 16 * m) * 2816 + col8) = hw;
;                     pv = cur; } }
	v_and_b32_e32 v93, 0xffff0000, v93
	v_pk_fma_f32 v[96:97], v[94:95], s[28:29], v[116:117] op_sel_hi:[1,0,0] neg_lo:[1,0,0] neg_hi:[1,0,0]
	v_pk_mul_f32 v[86:87], v[86:87], 0.5 op_sel_hi:[1,0]
	v_pk_fma_f32 v[96:97], v[94:95], v[96:97], s[34:35] op_sel_hi:[1,1,0]
	v_lshlrev_b32_e32 v88, 16, v89
	v_pk_fma_f32 v[96:97], v[94:95], v[96:97], s[36:37] op_sel_hi:[1,1,0]
	v_and_b32_e32 v89, 0xffff0000, v89
	v_pk_fma_f32 v[96:97], v[94:95], v[96:97], s[38:39] op_sel_hi:[1,1,0]
	v_mov_b32_dpp v3, v110 row_ror:1 row_mask:0xf bank_mask:0xf bound_ctrl:1
	v_pk_fma_f32 v[96:97], v[94:95], v[96:97], s[40:41] op_sel_hi:[1,1,0]
	s_nop 0
	v_pk_fma_f32 v[96:97], v[94:95], v[96:97], s[42:43] op_sel_hi:[1,1,0]
	v_mov_b32_dpp v3, v106 row_shr:1 row_mask:0xf bank_mask:0xf
	v_pk_fma_f32 v[94:95], v[94:95], v[96:97], s[44:45] op_sel_hi:[1,1,0]
	s_nop 0
	v_pk_mul_f32 v[90:91], v[90:91], v[94:95]
	s_nop 0
	v_pk_fma_f32 v[86:87], v[86:87], v[90:91], v[86:87]
	v_pk_fma_f32 v[90:91], v[150:151], v[92:93], v[162:163]
	v_pk_mul_f32 v[80:81], v[80:81], v[86:87]
	v_lshlrev_b32_e32 v86, 16, v105
	v_and_b32_e32 v87, 0xffff0000, v105
	v_pk_fma_f32 v[88:89], v[154:155], v[88:89], v[90:91]
	v_cvt_pk_bf16_f32 v80, v80, v81
	s_nop 0
	v_pk_fma_f32 v[86:87], v[158:159], v[86:87], v[88:89]
	s_nop 0
	v_pk_mul_f32 v[88:89], v[86:87], s[26:27] op_sel_hi:[1,0]
	v_pk_mul_f32 v[86:87], v[86:87], 0.5 op_sel_hi:[1,0]
	v_med3_f32 v88, v88, s71, v224
	v_med3_f32 v89, v89, s71, v224
	v_pk_mul_f32 v[90:91], v[88:89], v[88:89]
	s_nop 0
	v_pk_fma_f32 v[92:93], v[90:91], s[28:29], v[116:117] op_sel_hi:[1,0,0] neg_lo:[1,0,0] neg_hi:[1,0,0]
	s_nop 0
	v_pk_fma_f32 v[92:93], v[90:91], v[92:93], s[34:35] op_sel_hi:[1,1,0]
	s_nop 0
	v_pk_fma_f32 v[92:93], v[90:91], v[92:93], s[36:37] op_sel_hi:[1,1,0]
	s_nop 0
	v_pk_fma_f32 v[92:93], v[90:91], v[92:93], s[38:39] op_sel_hi:[1,1,0]
	s_nop 0
	v_pk_fma_f32 v[92:93], v[90:91], v[92:93], s[40:41] op_sel_hi:[1,1,0]
	s_nop 0
	v_pk_fma_f32 v[92:93], v[90:91], v[92:93], s[42:43] op_sel_hi:[1,1,0]
	s_nop 0
	v_pk_fma_f32 v[90:91], v[90:91], v[92:93], s[44:45] op_sel_hi:[1,1,0]
	v_lshlrev_b32_e32 v92, 16, v106
	v_pk_mul_f32 v[88:89], v[88:89], v[90:91]
	v_and_b32_e32 v93, 0xffff0000, v106
	v_pk_fma_f32 v[86:87], v[86:87], v[88:89], v[86:87]
	v_mov_b32_dpp v89, v110 row_ror:2 row_mask:0xf bank_mask:0xf bound_ctrl:1
	v_pk_mul_f32 v[82:83], v[82:83], v[86:87]
	v_mov_b32_dpp v91, v111 row_ror:2 row_mask:0xf bank_mask:0xf bound_ctrl:1
	v_mov_b32_dpp v89, v106 row_shr:2 row_mask:0xf bank_mask:0xf
	v_lshlrev_b32_e32 v88, 16, v89
	v_and_b32_e32 v89, 0xffff0000, v89
	v_cvt_pk_bf16_f32 v81, v82, v83
	v_lshlrev_b32_e32 v82, 16, v3
	v_and_b32_e32 v83, 0xffff0000, v3
	v_pk_fma_f32 v[88:89], v[132:133], v[88:89], v[144:145]
	v_mov_b32_dpp v87, v111 row_ror:1 row_mask:0xf bank_mask:0xf bound_ctrl:1
	v_pk_fma_f32 v[82:83], v[136:137], v[82:83], v[88:89]
	v_mov_b32_dpp v91, v107 row_shr:2 row_mask:0xf bank_mask:0xf
	v_pk_fma_f32 v[82:83], v[140:141], v[92:93], v[82:83]
	v_mov_b32_dpp v87, v107 row_shr:1 row_mask:0xf bank_mask:0xf
	v_pk_mul_f32 v[88:89], v[82:83], s[26:27] op_sel_hi:[1,0]
	v_lshlrev_b32_e32 v90, 16, v91
	v_med3_f32 v88, v88, s71, v224
	v_med3_f32 v89, v89, s71, v224
	v_pk_mul_f32 v[92:93], v[88:89], v[88:89]
	v_and_b32_e32 v91, 0xffff0000, v91
	v_pk_fma_f32 v[94:95], v[92:93], s[28:29], v[116:117] op_sel_hi:[1,0,0] neg_lo:[1,0,0] neg_hi:[1,0,0]
	v_pk_mul_f32 v[82:83], v[82:83], 0.5 op_sel_hi:[1,0]
	v_pk_fma_f32 v[94:95], v[92:93], v[94:95], s[34:35] op_sel_hi:[1,1,0]
	v_lshlrev_b32_e32 v86, 16, v87
	v_pk_fma_f32 v[94:95], v[92:93], v[94:95], s[36:37] op_sel_hi:[1,1,0]
	v_and_b32_e32 v87, 0xffff0000, v87
	v_pk_fma_f32 v[94:95], v[92:93], v[94:95], s[38:39] op_sel_hi:[1,1,0]
	v_add_u32_e32 v3, 32, v1
	v_pk_fma_f32 v[94:95], v[92:93], v[94:95], s[40:41] op_sel_hi:[1,1,0]
	v_mad_i64_i32 v[174:175], s[0:1], v3, s67, v[84:85]
	v_pk_fma_f32 v[94:95], v[92:93], v[94:95], s[42:43] op_sel_hi:[1,1,0]
	v_mov_b32_dpp v3, v104 row_ror:1 row_mask:0xf bank_mask:0xf bound_ctrl:1
	v_pk_fma_f32 v[92:93], v[92:93], v[94:95], s[44:45] op_sel_hi:[1,1,0]
	v_add_u32_e32 v1, 48, v1
	v_pk_mul_f32 v[88:89], v[88:89], v[92:93]
	v_mov_b32_dpp v3, v100 row_shr:1 row_mask:0xf bank_mask:0xf
	v_pk_fma_f32 v[82:83], v[82:83], v[88:89], v[82:83]
	v_pk_fma_f32 v[88:89], v[134:135], v[90:91], v[146:147]
	v_pk_mul_f32 v[76:77], v[76:77], v[82:83]
	v_lshlrev_b32_e32 v82, 16, v107
	v_and_b32_e32 v83, 0xffff0000, v107
	v_pk_fma_f32 v[86:87], v[138:139], v[86:87], v[88:89]
	s_nop 0
	v_pk_fma_f32 v[82:83], v[142:143], v[82:83], v[86:87]
	s_nop 0
	v_pk_mul_f32 v[86:87], v[82:83], s[26:27] op_sel_hi:[1,0]
	v_pk_mul_f32 v[82:83], v[82:83], 0.5 op_sel_hi:[1,0]
	v_med3_f32 v86, v86, s71, v224
	v_med3_f32 v87, v87, s71, v224
	v_pk_mul_f32 v[88:89], v[86:87], v[86:87]
	s_nop 0
	v_pk_fma_f32 v[90:91], v[88:89], s[28:29], v[116:117] op_sel_hi:[1,0,0] neg_lo:[1,0,0] neg_hi:[1,0,0]
	s_nop 0
	v_pk_fma_f32 v[90:91], v[88:89], v[90:91], s[34:35] op_sel_hi:[1,1,0]
	s_nop 0
	v_pk_fma_f32 v[90:91], v[88:89], v[90:91], s[36:37] op_sel_hi:[1,1,0]
	s_nop 0
	v_pk_fma_f32 v[90:91], v[88:89], v[90:91], s[38:39] op_sel_hi:[1,1,0]
	s_nop 0
	v_pk_fma_f32 v[90:91], v[88:89], v[90:91], s[40:41] op_sel_hi:[1,1,0]
	s_nop 0
	v_pk_fma_f32 v[90:91], v[88:89], v[90:91], s[42:43] op_sel_hi:[1,1,0]
	s_nop 0
	v_pk_fma_f32 v[88:89], v[88:89], v[90:91], s[44:45] op_sel_hi:[1,1,0]
	s_nop 0
	v_pk_mul_f32 v[86:87], v[86:87], v[88:89]
	s_nop 0
	v_pk_fma_f32 v[82:83], v[82:83], v[86:87], v[82:83]
	v_lshlrev_b32_e32 v86, 16, v100
	v_pk_mul_f32 v[78:79], v[78:79], v[82:83]
	v_cvt_pk_bf16_f32 v82, v76, v77
	v_lshl_add_u64 v[76:77], v[174:175], 0, v[180:181]
; __device__ __forceinline__ unsigned cvt_pk_bf16(float lo, float hi) { unsigned r; asm volatile("v_cvt_pk_bf16_f32 %0, %1, %2" : "=v"(r) : "v"(lo), "v"(hi)); return r; }
;     static __device__ __forceinline__ u32x2 finish2(const float (&g0)[4], const float (&g1)[4], const float (&g2)[4], const float (&w0)[4], const float (&w1)[4], const float (&w2)[4], const float (&bb)[4],
;                                                     const f32x4 v, float rs) {
;         float h[4];
; #pragma unroll
;         for (int j = 0; j < 4; j += 2) {
;             const f32x2 gc = (f32x2){bb[j] + w0[j] * g2[j] + w1[j] * g1[j] + w2[j] * g0[j], bb[j + 1] + w0[j + 1] * g2[j + 1] + w1[j + 1] * g1[j + 1] + w2[j + 1] * g0[j + 1]};
;             const f32x2 ge = gelu_pk(gc) * ((f32x2){v[j], v[j + 1]} * rs); h[j] = ge.x; h[j + 1] = ge.y; }
;         u32x2 w; w.x = cvt_pk_bf16(h[0], h[1]); w.y = cvt_pk_bf16(h[2], h[3]); return w;
;     }
;     __device__ __forceinline__ void operator()(const f32x4 (&acc)[2][2][4][2], const Unit& u, int wr, int wc, int fr, int fq) const {
;     ...
;             for (int ai = 0; ai < 2; ++ai) { const int R0 = u.rb + ai * HALF + wr * 64; const bf16_t* gp = G + (size_t)(R0 + fr) * 2816 + col8;
;                 u32x4 gq[4], prv = (u32x4){0u, 0u, 0u, 0u};
; #pragma unroll
;                 for (int m = 0; m < 4; ++m) gq[m] = *(const u32x4*)(gp + (size_t)m * 16 * 2816);
;                 if ((R0 & 8191) != 0) prv = *(const u32x4*)(gp - (size_t)16 * 2816);
;                 u32x4 pv = prv;
; #pragma unroll
;                 for (int m = 0; m < 4; ++m) { const u32x4 cur = gq[m]; u32x4 hw;
; #pragma unroll
;                     for (int hv = 0; hv < 2; ++hv) { const u32x2 c2 = half2(cur, hv), p2 = half2(pv, hv);
;                         const u32x2 q1 = dpp_prev<1>(p2, c2), q2 = dpp_prev<2>(p2, c2);
;                         float g0[4], g1[4], g2[4]; unpk4(c2, g0); unpk4(q1, g1); unpk4(q2, g2);
;                         const u32x2 r = finish2(g0, g1, g2, w0[hv], w1[hv], w2[hv], bb[hv], acc[ai][bj][m][hv], rs8[ai][m]);
;                         if (hv == 0) { hw.x = r.x; hw.y = r.y; } else { hw.z = r.x; hw.w = r.y; } }
;                     *(u32x4*)(H + (size_t)(R0 + fr + 16 * m) * 2816 + col8) = hw;
;                     pv = cur; } }
	v_cvt_pk_bf16_f32 v83, v78, v79
	global_store_dwordx4 v[76:77], v[80:83], off nt
	v_lshlrev_b32_e32 v76, 16, v3
	v_and_b32_e32 v77, 0xffff0000, v3
	v_mov_b32_dpp v81, v104 row_ror:2 row_mask:0xf bank_mask:0xf bound_ctrl:1
	v_and_b32_e32 v87, 0xffff0000, v100
	v_mov_b32_dpp v83, v105 row_ror:2 row_mask:0xf bank_mask:0xf bound_ctrl:1
	v_mov_b32_dpp v81, v100 row_shr:2 row_mask:0xf bank_mask:0xf
	v_lshlrev_b32_e32 v80, 16, v81
	v_and_b32_e32 v81, 0xffff0000, v81
	v_pk_fma_f32 v[80:81], v[148:149], v[80:81], v[160:161]
	v_mov_b32_dpp v79, v105 row_ror:1 row_mask:0xf bank_mask:0xf bound_ctrl:1
	v_pk_fma_f32 v[76:77], v[152:153], v[76:77], v[80:81]
	v_mov_b32_dpp v83, v101 row_shr:2 row_mask:0xf bank_mask:0xf
	v_pk_fma_f32 v[76:77], v[156:157], v[86:87], v[76:77]
	v_mov_b32_dpp v79, v101 row_shr:1 row_mask:0xf bank_mask:0xf
	v_pk_mul_f32 v[80:81], v[76:77], s[26:27] op_sel_hi:[1,0]
	v_lshlrev_b32_e32 v82, 16, v83
	v_med3_f32 v80, v80, s71, v224
	v_med3_f32 v81, v81, s71, v224
	v_pk_mul_f32 v[86:87], v[80:81], v[80:81]
	v_and_b32_e32 v83, 0xffff0000, v83
	v_pk_fma_f32 v[88:89], v[86:87], s[28:29], v[116:117] op_sel_hi:[1,0,0] neg_lo:[1,0,0] neg_hi:[1,0,0]
	v_pk_mul_f32 v[76:77], v[76:77], 0.5 op_sel_hi:[1,0]
	v_pk_fma_f32 v[88:89], v[86:87], v[88:89], s[34:35] op_sel_hi:[1,1,0]
	v_lshlrev_b32_e32 v78, 16, v79
	v_pk_fma_f32 v[88:89], v[86:87], v[88:89], s[36:37] op_sel_hi:[1,1,0]
	v_and_b32_e32 v79, 0xffff0000, v79
	v_pk_fma_f32 v[88:89], v[86:87], v[88:89], s[38:39] op_sel_hi:[1,1,0]
	v_mov_b32_dpp v3, v106 row_ror:1 row_mask:0xf bank_mask:0xf bound_ctrl:1
	v_pk_fma_f32 v[88:89], v[86:87], v[88:89], s[40:41] op_sel_hi:[1,1,0]
	s_nop 0
	v_pk_fma_f32 v[88:89], v[86:87], v[88:89], s[42:43] op_sel_hi:[1,1,0]
	v_mov_b32_dpp v3, v102 row_shr:1 row_mask:0xf bank_mask:0xf
	v_pk_fma_f32 v[86:87], v[86:87], v[88:89], s[44:45] op_sel_hi:[1,1,0]
	s_nop 0
	v_pk_mul_f32 v[80:81], v[80:81], v[86:87]
	s_nop 0
	v_pk_fma_f32 v[76:77], v[76:77], v[80:81], v[76:77]
	v_pk_fma_f32 v[80:81], v[150:151], v[82:83], v[162:163]
	v_pk_mul_f32 v[72:73], v[72:73], v[76:77]
	v_lshlrev_b32_e32 v76, 16, v101
	v_and_b32_e32 v77, 0xffff0000, v101
	v_pk_fma_f32 v[78:79], v[154:155], v[78:79], v[80:81]
	v_cvt_pk_bf16_f32 v72, v72, v73
	s_nop 0
	v_pk_fma_f32 v[76:77], v[158:159], v[76:77], v[78:79]
	s_nop 0
	v_pk_mul_f32 v[78:79], v[76:77], s[26:27] op_sel_hi:[1,0]
	v_pk_mul_f32 v[76:77], v[76:77], 0.5 op_sel_hi:[1,0]
	v_med3_f32 v78, v78, s71, v224
	v_med3_f32 v79, v79, s71, v224
	v_pk_mul_f32 v[80:81], v[78:79], v[78:79]
	s_nop 0
	v_pk_fma_f32 v[82:83], v[80:81], s[28:29], v[116:117] op_sel_hi:[1,0,0] neg_lo:[1,0,0] neg_hi:[1,0,0]
	s_nop 0
	v_pk_fma_f32 v[82:83], v[80:81], v[82:83], s[34:35] op_sel_hi:[1,1,0]
	s_nop 0
	v_pk_fma_f32 v[82:83], v[80:81], v[82:83], s[36:37] op_sel_hi:[1,1,0]
	s_nop 0
	v_pk_fma_f32 v[82:83], v[80:81], v[82:83], s[38:39] op_sel_hi:[1,1,0]
	s_nop 0
	v_pk_fma_f32 v[82:83], v[80:81], v[82:83], s[40:41] op_sel_hi:[1,1,0]
	s_nop 0
	v_pk_fma_f32 v[82:83], v[80:81], v[82:83], s[42:43] op_sel_hi:[1,1,0]
	s_nop 0
	v_pk_fma_f32 v[80:81], v[80:81], v[82:83], s[44:45] op_sel_hi:[1,1,0]
	v_lshlrev_b32_e32 v82, 16, v102
	v_pk_mul_f32 v[78:79], v[78:79], v[80:81]
	v_and_b32_e32 v83, 0xffff0000, v102
	v_pk_fma_f32 v[76:77], v[76:77], v[78:79], v[76:77]
	v_mov_b32_dpp v79, v106 row_ror:2 row_mask:0xf bank_mask:0xf bound_ctrl:1
	v_pk_mul_f32 v[74:75], v[74:75], v[76:77]
	v_mov_b32_dpp v81, v107 row_ror:2 row_mask:0xf bank_mask:0xf bound_ctrl:1
	v_mov_b32_dpp v79, v102 row_shr:2 row_mask:0xf bank_mask:0xf
	v_lshlrev_b32_e32 v78, 16, v79
	v_and_b32_e32 v79, 0xffff0000, v79
	v_cvt_pk_bf16_f32 v73, v74, v75
	v_lshlrev_b32_e32 v74, 16, v3
	v_and_b32_e32 v75, 0xffff0000, v3
	v_pk_fma_f32 v[78:79], v[132:133], v[78:79], v[144:145]
	v_mov_b32_dpp v77, v107 row_ror:1 row_mask:0xf bank_mask:0xf bound_ctrl:1
	v_pk_fma_f32 v[74:75], v[136:137], v[74:75], v[78:79]
	v_mov_b32_dpp v81, v103 row_shr:2 row_mask:0xf bank_mask:0xf
	v_pk_fma_f32 v[74:75], v[140:141], v[82:83], v[74:75]
	v_mov_b32_dpp v77, v103 row_shr:1 row_mask:0xf bank_mask:0xf
	v_pk_mul_f32 v[78:79], v[74:75], s[26:27] op_sel_hi:[1,0]
	v_lshlrev_b32_e32 v80, 16, v81
	v_med3_f32 v78, v78, s71, v224
	v_med3_f32 v79, v79, s71, v224
	v_pk_mul_f32 v[82:83], v[78:79], v[78:79]
	v_and_b32_e32 v81, 0xffff0000, v81
	v_pk_fma_f32 v[86:87], v[82:83], s[28:29], v[116:117] op_sel_hi:[1,0,0] neg_lo:[1,0,0] neg_hi:[1,0,0]
	v_pk_mul_f32 v[74:75], v[74:75], 0.5 op_sel_hi:[1,0]
	v_pk_fma_f32 v[86:87], v[82:83], v[86:87], s[34:35] op_sel_hi:[1,1,0]
	v_lshlrev_b32_e32 v76, 16, v77
	v_pk_fma_f32 v[86:87], v[82:83], v[86:87], s[36:37] op_sel_hi:[1,1,0]
	v_and_b32_e32 v77, 0xffff0000, v77
	v_pk_fma_f32 v[86:87], v[82:83], v[86:87], s[38:39] op_sel_hi:[1,1,0]
	v_mad_i64_i32 v[132:133], s[0:1], v1, s67, v[84:85]
	v_pk_fma_f32 v[86:87], v[82:83], v[86:87], s[40:41] op_sel_hi:[1,1,0]
	s_nop 0
	v_pk_fma_f32 v[86:87], v[82:83], v[86:87], s[42:43] op_sel_hi:[1,1,0]
	s_nop 0
	v_pk_fma_f32 v[82:83], v[82:83], v[86:87], s[44:45] op_sel_hi:[1,1,0]
	s_nop 0
	v_pk_mul_f32 v[78:79], v[78:79], v[82:83]
	s_nop 0
	v_pk_fma_f32 v[74:75], v[74:75], v[78:79], v[74:75]
	v_pk_fma_f32 v[78:79], v[134:135], v[80:81], v[146:147]
	v_pk_mul_f32 v[64:65], v[64:65], v[74:75]
	v_lshlrev_b32_e32 v74, 16, v103
	v_and_b32_e32 v75, 0xffff0000, v103
	v_pk_fma_f32 v[76:77], v[138:139], v[76:77], v[78:79]
	v_add_u32_e32 v134, 0x80, v212
	v_pk_fma_f32 v[74:75], v[142:143], v[74:75], v[76:77]
	v_ashrrev_i32_e32 v135, 31, v134
	v_pk_mul_f32 v[76:77], v[74:75], s[26:27] op_sel_hi:[1,0]
	v_pk_mul_f32 v[74:75], v[74:75], 0.5 op_sel_hi:[1,0]
	v_med3_f32 v76, v76, s71, v224
;     static __device__ __forceinline__ u32x2 finish2(const float (&g0)[4], const float (&g1)[4], const float (&g2)[4], const float (&w0)[4], const float (&w1)[4], const float (&w2)[4], const float (&bb)[4],
;                                                     const f32x4 v, float rs) {
;         float h[4];
; #pragma unroll
;         for (int j = 0; j < 4; j += 2) {
;             const f32x2 gc = (f32x2){bb[j] + w0[j] * g2[j] + w1[j] * g1[j] + w2[j] * g0[j], bb[j + 1] + w0[j + 1] * g2[j + 1] + w1[j + 1] * g1[j + 1] + w2[j + 1] * g0[j + 1]};
;             const f32x2 ge = gelu_pk(gc) * ((f32x2){v[j], v[j + 1]} * rs); h[j] = ge.x; h[j + 1] = ge.y; }
;         u32x2 w; w.x = cvt_pk_bf16(h[0], h[1]); w.y = cvt_pk_bf16(h[2], h[3]); return w;
;     }
;     __device__ __forceinline__ void operator()(const f32x4 (&acc)[2][2][4][2], const Unit& u, int wr, int wc, int fr, int fq) const {
;     ...
;             for (int hv = 0; hv < 2; ++hv) { ld4f(cw + col8 + 4 * hv, w0[hv]); ld4f(cw + 2816 + col8 + 4 * hv, w1[hv]); ld4f(cw + 2 * 2816 + col8 + 4 * hv, w2[hv]); ld4f(cb + col8 + 4 * hv, bb[hv]); }
; #pragma unroll
;             for (int ai = 0; ai < 2; ++ai) { const int R0 = u.rb + ai * HALF + wr * 64; const bf16_t* gp = G + (size_t)(R0 + fr) * 2816 + col8;
;                 u32x4 gq[4], prv = (u32x4){0u, 0u, 0u, 0u};
; #pragma unroll
;                 for (int m = 0; m < 4; ++m) gq[m] = *(const u32x4*)(gp + (size_t)m * 16 * 2816);
;                 if ((R0 & 8191) != 0) prv = *(const u32x4*)(gp - (size_t)16 * 2816);
;                 u32x4 pv = prv;
; #pragma unroll
;                 for (int m = 0; m < 4; ++m) { const u32x4 cur = gq[m]; u32x4 hw;
; #pragma unroll
;                     for (int hv = 0; hv < 2; ++hv) { const u32x2 c2 = half2(cur, hv), p2 = half2(pv, hv);
;                         const u32x2 q1 = dpp_prev<1>(p2, c2), q2 = dpp_prev<2>(p2, c2);
;                         float g0[4], g1[4], g2[4]; unpk4(c2, g0); unpk4(q1, g1); unpk4(q2, g2);
;                         const u32x2 r = finish2(g0, g1, g2, w0[hv], w1[hv], w2[hv], bb[hv], acc[ai][bj][m][hv], rs8[ai][m]);
;                         if (hv == 0) { hw.x = r.x; hw.y = r.y; } else { hw.z = r.x; hw.w = r.y; } }
;                     *(u32x4*)(H + (size_t)(R0 + fr + 16 * m) * 2816 + col8) = hw;
;                     pv = cur; } }
	v_med3_f32 v77, v77, s71, v224
	v_pk_mul_f32 v[78:79], v[76:77], v[76:77]
	v_lshl_add_u64 v[136:137], v[134:135], 1, v[214:215]
	v_pk_fma_f32 v[80:81], v[78:79], s[28:29], v[116:117] op_sel_hi:[1,0,0] neg_lo:[1,0,0] neg_hi:[1,0,0]
	v_add_co_u32_e32 v100, vcc, s45, v136
	v_pk_fma_f32 v[80:81], v[78:79], v[80:81], s[34:35] op_sel_hi:[1,1,0]
	s_nop 0
	v_addc_co_u32_e32 v101, vcc, 0, v137, vcc
	v_pk_fma_f32 v[80:81], v[78:79], v[80:81], s[36:37] op_sel_hi:[1,1,0]
	v_add_co_u32_e32 v102, vcc, 0x2c000, v136
	v_pk_fma_f32 v[80:81], v[78:79], v[80:81], s[38:39] op_sel_hi:[1,1,0]
	s_nop 0
	v_addc_co_u32_e32 v103, vcc, 0, v137, vcc
	v_pk_fma_f32 v[80:81], v[78:79], v[80:81], s[40:41] op_sel_hi:[1,1,0]
	s_nop 0
	v_pk_fma_f32 v[80:81], v[78:79], v[80:81], s[42:43] op_sel_hi:[1,1,0]
	s_nop 0
	v_pk_fma_f32 v[78:79], v[78:79], v[80:81], s[44:45] op_sel_hi:[1,1,0]
	s_nop 0
	v_pk_mul_f32 v[76:77], v[76:77], v[78:79]
	s_nop 0
	v_pk_fma_f32 v[74:75], v[74:75], v[76:77], v[74:75]
	s_nop 0
	v_pk_mul_f32 v[66:67], v[66:67], v[74:75]
	v_cvt_pk_bf16_f32 v74, v64, v65
	v_lshl_add_u64 v[64:65], v[132:133], 0, v[180:181]
	v_cvt_pk_bf16_f32 v75, v66, v67
	global_store_dwordx4 v[64:65], v[72:75], off nt
	v_lshlrev_b64 v[64:65], 2, v[134:135]
	v_lshl_add_u64 v[76:77], s[18:19], 0, v[64:65]
	v_lshl_add_u64 v[72:73], s[12:13], 0, v[64:65]
	v_lshl_add_u64 v[80:81], s[20:21], 0, v[64:65]
	v_lshl_add_u64 v[96:97], s[14:15], 0, v[64:65]
	global_load_dwordx4 v[64:67], v[72:73], off offset:16
	global_load_dwordx4 v[84:87], v[72:73], off
	s_nop 0
	global_load_dwordx4 v[72:75], v[76:77], off offset:16
	global_load_dwordx4 v[88:91], v[76:77], off
	s_nop 0
	global_load_dwordx4 v[76:79], v[80:81], off offset:16
	global_load_dwordx4 v[92:95], v[80:81], off
	s_nop 0
	global_load_dwordx4 v[80:83], v[96:97], off offset:16
	s_nop 0
	global_load_dwordx4 v[96:99], v[96:97], off
	s_nop 0
	global_load_dwordx4 v[114:117], v[136:137], off
	global_load_dwordx4 v[110:113], v[100:101], off
	global_load_dwordx4 v[106:109], v[102:103], off
	v_add_co_u32_e32 v100, vcc, 0x42000, v136
	s_nop 1
	v_addc_co_u32_e32 v101, vcc, 0, v137, vcc
	global_load_dwordx4 v[102:105], v[100:101], off
	v_mov_b32_e32 v100, 0
	s_andn2_b64 vcc, exec, s[2:3]
	s_cbranch_vccnz .LBB0_3150
	v_add_co_u32_e32 v118, vcc, 0xfffea000, v136
	s_nop 1
	v_addc_co_u32_e32 v119, vcc, -1, v137, vcc
	global_load_dwordx4 v[118:121], v[118:119], off
.LBB0_3150:
	s_waitcnt vmcnt(0)
	s_nop 0
	v_mov_b32_dpp v123, v118 row_ror:2 row_mask:0xf bank_mask:0xf bound_ctrl:1
	v_mov_b32_dpp v1, v118 row_ror:1 row_mask:0xf bank_mask:0xf bound_ctrl:1
	v_mov_b32_dpp v101, v119 row_ror:1 row_mask:0xf bank_mask:0xf bound_ctrl:1
	v_mov_b32_dpp v123, v114 row_shr:2 row_mask:0xf bank_mask:0xf
	v_mov_b32_dpp v1, v114 row_shr:1 row_mask:0xf bank_mask:0xf
	v_lshlrev_b32_e32 v138, 16, v123
	v_and_b32_e32 v139, 0xffff0000, v123
	v_mov_b32_dpp v125, v119 row_ror:2 row_mask:0xf bank_mask:0xf bound_ctrl:1
	v_lshlrev_b32_e32 v118, 16, v1
	v_and_b32_e32 v119, 0xffff0000, v1
	v_pk_fma_f32 v[138:139], v[84:85], v[138:139], v[96:97]
	v_lshlrev_b32_e32 v142, 16, v114
	v_and_b32_e32 v143, 0xffff0000, v114
	v_pk_fma_f32 v[118:119], v[88:89], v[118:119], v[138:139]
	v_mov_b32_dpp v125, v115 row_shr:2 row_mask:0xf bank_mask:0xf
	v_pk_fma_f32 v[138:139], v[92:93], v[142:143], v[118:119]
	v_mov_b32_e32 v189, v188
	v_pk_mul_f32 v[118:119], v[138:139], s[26:27] op_sel_hi:[1,0]
	v_mov_b32_dpp v101, v115 row_shr:1 row_mask:0xf bank_mask:0xf
	v_med3_f32 v142, v118, s71, v224
	v_med3_f32 v143, v119, s71, v224
	v_pk_mul_f32 v[144:145], v[142:143], v[142:143]
	v_mov_b64_e32 v[118:119], s[30:31]
	v_pk_fma_f32 v[146:147], v[144:145], s[28:29], v[118:119] op_sel_hi:[1,0,0] neg_lo:[1,0,0] neg_hi:[1,0,0]
	v_lshlrev_b32_e32 v140, 16, v125
	v_pk_fma_f32 v[146:147], v[144:145], v[146:147], s[34:35] op_sel_hi:[1,1,0]
	v_and_b32_e32 v141, 0xffff0000, v125
	v_pk_fma_f32 v[146:147], v[144:145], v[146:147], s[36:37] op_sel_hi:[1,1,0]
	v_pk_mul_f32 v[138:139], v[138:139], 0.5 op_sel_hi:[1,0]
	v_pk_fma_f32 v[146:147], v[144:145], v[146:147], s[38:39] op_sel_hi:[1,1,0]
	v_lshlrev_b32_e32 v136, 16, v101
	v_pk_fma_f32 v[146:147], v[144:145], v[146:147], s[40:41] op_sel_hi:[1,1,0]
	v_and_b32_e32 v137, 0xffff0000, v101
	v_pk_fma_f32 v[146:147], v[144:145], v[146:147], s[42:43] op_sel_hi:[1,1,0]
	v_pk_mul_f32 v[68:69], v[68:69], v[188:189]
	v_pk_fma_f32 v[144:145], v[144:145], v[146:147], s[44:45] op_sel_hi:[1,1,0]
	v_pk_fma_f32 v[140:141], v[86:87], v[140:141], v[98:99]
	v_pk_mul_f32 v[142:143], v[142:143], v[144:145]
	v_pk_fma_f32 v[136:137], v[90:91], v[136:137], v[140:141]
	v_pk_fma_f32 v[138:139], v[138:139], v[142:143], v[138:139]
	v_mov_b32_dpp v123, v120 row_ror:2 row_mask:0xf bank_mask:0xf bound_ctrl:1
	v_pk_mul_f32 v[68:69], v[68:69], v[138:139]
	v_lshlrev_b32_e32 v138, 16, v115
	v_and_b32_e32 v139, 0xffff0000, v115
	v_pk_fma_f32 v[136:137], v[94:95], v[138:139], v[136:137]
	v_pk_mul_f32 v[70:71], v[70:71], v[188:189]
	v_pk_mul_f32 v[138:139], v[136:137], s[26:27] op_sel_hi:[1,0]
	v_pk_mul_f32 v[136:137], v[136:137], 0.5 op_sel_hi:[1,0]
	v_med3_f32 v138, v138, s71, v224
	v_med3_f32 v139, v139, s71, v224
	v_pk_mul_f32 v[140:141], v[138:139], v[138:139]
	v_mov_b32_dpp v1, v120 row_ror:1 row_mask:0xf bank_mask:0xf bound_ctrl:1
	v_pk_fma_f32 v[142:143], v[140:141], s[28:29], v[118:119] op_sel_hi:[1,0,0] neg_lo:[1,0,0] neg_hi:[1,0,0]
	v_mov_b32_dpp v123, v116 row_shr:2 row_mask:0xf bank_mask:0xf
	v_pk_fma_f32 v[142:143], v[140:141], v[142:143], s[34:35] op_sel_hi:[1,1,0]
	v_mov_b32_dpp v1, v116 row_shr:1 row_mask:0xf bank_mask:0xf
	v_pk_fma_f32 v[142:143], v[140:141], v[142:143], s[36:37] op_sel_hi:[1,1,0]
; __device__ __forceinline__ unsigned cvt_pk_bf16(float lo, float hi) { unsigned r; asm volatile("v_cvt_pk_bf16_f32 %0, %1, %2" : "=v"(r) : "v"(lo), "v"(hi)); return r; }
;     static __device__ __forceinline__ u32x2 finish2(const float (&g0)[4], const float (&g1)[4], const float (&g2)[4], const float (&w0)[4], const float (&w1)[4], const float (&w2)[4], const float (&bb)[4],
;                                                     const f32x4 v, float rs) {
;         float h[4];
; #pragma unroll
;         for (int j = 0; j < 4; j += 2) {
;             const f32x2 gc = (f32x2){bb[j] + w0[j] * g2[j] + w1[j] * g1[j] + w2[j] * g0[j], bb[j + 1] + w0[j + 1] * g2[j + 1] + w1[j + 1] * g1[j + 1] + w2[j + 1] * g0[j + 1]};
;             const f32x2 ge = gelu_pk(gc) * ((f32x2){v[j], v[j + 1]} * rs); h[j] = ge.x; h[j + 1] = ge.y; }
;         u32x2 w; w.x = cvt_pk_bf16(h[0], h[1]); w.y = cvt_pk_bf16(h[2], h[3]); return w;
;     }
;     __device__ __forceinline__ void operator()(const f32x4 (&acc)[2][2][4][2], const Unit& u, int wr, int wc, int fr, int fq) const {
;     ...
;             for (int ai = 0; ai < 2; ++ai) { const int R0 = u.rb + ai * HALF + wr * 64; const bf16_t* gp = G + (size_t)(R0 + fr) * 2816 + col8;
;                 u32x4 gq[4], prv = (u32x4){0u, 0u, 0u, 0u};
; #pragma unroll
;                 for (int m = 0; m < 4; ++m) gq[m] = *(const u32x4*)(gp + (size_t)m * 16 * 2816);
;                 if ((R0 & 8191) != 0) prv = *(const u32x4*)(gp - (size_t)16 * 2816);
;                 u32x4 pv = prv;
; #pragma unroll
;                 for (int m = 0; m < 4; ++m) { const u32x4 cur = gq[m]; u32x4 hw;
; #pragma unroll
;                     for (int hv = 0; hv < 2; ++hv) { const u32x2 c2 = half2(cur, hv), p2 = half2(pv, hv);
;                         const u32x2 q1 = dpp_prev<1>(p2, c2), q2 = dpp_prev<2>(p2, c2);
;                         float g0[4], g1[4], g2[4]; unpk4(c2, g0); unpk4(q1, g1); unpk4(q2, g2);
;                         const u32x2 r = finish2(g0, g1, g2, w0[hv], w1[hv], w2[hv], bb[hv], acc[ai][bj][m][hv], rs8[ai][m]);
;                         if (hv == 0) { hw.x = r.x; hw.y = r.y; } else { hw.z = r.x; hw.w = r.y; } }
;                     *(u32x4*)(H + (size_t)(R0 + fr + 16 * m) * 2816 + col8) = hw;
;                     pv = cur; } }
	v_cvt_pk_bf16_f32 v68, v68, v69
	v_mov_b32_dpp v125, v121 row_ror:2 row_mask:0xf bank_mask:0xf bound_ctrl:1
	v_pk_fma_f32 v[142:143], v[140:141], v[142:143], s[38:39] op_sel_hi:[1,1,0]
	v_mov_b32_dpp v101, v121 row_ror:1 row_mask:0xf bank_mask:0xf bound_ctrl:1
	v_pk_fma_f32 v[142:143], v[140:141], v[142:143], s[40:41] op_sel_hi:[1,1,0]
	v_mov_b32_dpp v125, v117 row_shr:2 row_mask:0xf bank_mask:0xf
	v_pk_fma_f32 v[142:143], v[140:141], v[142:143], s[42:43] op_sel_hi:[1,1,0]
	v_mov_b32_dpp v101, v117 row_shr:1 row_mask:0xf bank_mask:0xf
	v_pk_fma_f32 v[140:141], v[140:141], v[142:143], s[44:45] op_sel_hi:[1,1,0]
	v_lshlrev_b32_e32 v120, 16, v101
	v_pk_mul_f32 v[138:139], v[138:139], v[140:141]
	v_lshlrev_b32_e32 v140, 16, v116
	v_pk_fma_f32 v[136:137], v[136:137], v[138:139], v[136:137]
	v_and_b32_e32 v141, 0xffff0000, v116
	v_pk_mul_f32 v[70:71], v[70:71], v[136:137]
	v_lshlrev_b32_e32 v136, 16, v123
	v_and_b32_e32 v137, 0xffff0000, v123
	v_cvt_pk_bf16_f32 v69, v70, v71
	v_lshlrev_b32_e32 v70, 16, v1
	v_and_b32_e32 v71, 0xffff0000, v1
	v_pk_fma_f32 v[136:137], v[64:65], v[136:137], v[80:81]
	v_lshlrev_b32_e32 v138, 16, v125
	v_pk_fma_f32 v[70:71], v[72:73], v[70:71], v[136:137]
	v_and_b32_e32 v139, 0xffff0000, v125
	v_pk_fma_f32 v[70:71], v[76:77], v[140:141], v[70:71]
	v_and_b32_e32 v121, 0xffff0000, v101
	v_pk_mul_f32 v[136:137], v[70:71], s[26:27] op_sel_hi:[1,0]
	v_pk_mul_f32 v[70:71], v[70:71], 0.5 op_sel_hi:[1,0]
	v_med3_f32 v136, v136, s71, v224
	v_med3_f32 v137, v137, s71, v224
	v_pk_mul_f32 v[140:141], v[136:137], v[136:137]
	v_pk_mul_f32 v[60:61], v[60:61], v[188:189]
	v_pk_fma_f32 v[142:143], v[140:141], s[28:29], v[118:119] op_sel_hi:[1,0,0] neg_lo:[1,0,0] neg_hi:[1,0,0]
	v_pk_mul_f32 v[62:63], v[62:63], v[188:189]
	v_pk_fma_f32 v[142:143], v[140:141], v[142:143], s[34:35] op_sel_hi:[1,1,0]
	v_mov_b32_dpp v1, v114 row_ror:1 row_mask:0xf bank_mask:0xf bound_ctrl:1
	v_pk_fma_f32 v[142:143], v[140:141], v[142:143], s[36:37] op_sel_hi:[1,1,0]
	v_mov_b32_dpp v101, v115 row_ror:2 row_mask:0xf bank_mask:0xf bound_ctrl:1
	v_pk_fma_f32 v[142:143], v[140:141], v[142:143], s[38:39] op_sel_hi:[1,1,0]
	v_mov_b32_dpp v1, v110 row_shr:1 row_mask:0xf bank_mask:0xf
	v_pk_fma_f32 v[142:143], v[140:141], v[142:143], s[40:41] op_sel_hi:[1,1,0]
	v_mov_b32_dpp v101, v111 row_shr:2 row_mask:0xf bank_mask:0xf
	v_pk_fma_f32 v[142:143], v[140:141], v[142:143], s[42:43] op_sel_hi:[1,1,0]
	v_mov_b32_e32 v187, v186
	v_pk_fma_f32 v[140:141], v[140:141], v[142:143], s[44:45] op_sel_hi:[1,1,0]
	v_pk_mul_f32 v[56:57], v[56:57], v[186:187]
	v_pk_mul_f32 v[136:137], v[136:137], v[140:141]
	v_pk_mul_f32 v[58:59], v[58:59], v[186:187]
	v_pk_fma_f32 v[70:71], v[70:71], v[136:137], v[70:71]
	v_pk_fma_f32 v[136:137], v[66:67], v[138:139], v[82:83]
	v_pk_mul_f32 v[60:61], v[60:61], v[70:71]
	v_lshlrev_b32_e32 v70, 16, v117
	v_and_b32_e32 v71, 0xffff0000, v117
	v_pk_fma_f32 v[120:121], v[74:75], v[120:121], v[136:137]
	v_pk_mul_f32 v[52:53], v[52:53], v[186:187]
	v_pk_fma_f32 v[70:71], v[78:79], v[70:71], v[120:121]
	v_pk_mul_f32 v[54:55], v[54:55], v[186:187]
	v_pk_mul_f32 v[120:121], v[70:71], s[26:27] op_sel_hi:[1,0]
	v_pk_mul_f32 v[70:71], v[70:71], 0.5 op_sel_hi:[1,0]
	v_med3_f32 v120, v120, s71, v224
	v_med3_f32 v121, v121, s71, v224
	v_pk_mul_f32 v[136:137], v[120:121], v[120:121]
	v_mov_b32_e32 v185, v184
	v_pk_fma_f32 v[138:139], v[136:137], s[28:29], v[118:119] op_sel_hi:[1,0,0] neg_lo:[1,0,0] neg_hi:[1,0,0]
	v_pk_mul_f32 v[48:49], v[48:49], v[184:185]
	v_pk_fma_f32 v[138:139], v[136:137], v[138:139], s[34:35] op_sel_hi:[1,1,0]
	v_pk_mul_f32 v[50:51], v[50:51], v[184:185]
	v_pk_fma_f32 v[138:139], v[136:137], v[138:139], s[36:37] op_sel_hi:[1,1,0]
	v_pk_mul_f32 v[44:45], v[44:45], v[184:185]
	v_pk_fma_f32 v[138:139], v[136:137], v[138:139], s[38:39] op_sel_hi:[1,1,0]
	v_pk_mul_f32 v[46:47], v[46:47], v[184:185]
	v_pk_fma_f32 v[138:139], v[136:137], v[138:139], s[40:41] op_sel_hi:[1,1,0]
	v_mov_b32_e32 v3, v2
	v_pk_fma_f32 v[138:139], v[136:137], v[138:139], s[42:43] op_sel_hi:[1,1,0]
	v_pk_mul_f32 v[40:41], v[40:41], v[2:3]
	v_pk_fma_f32 v[136:137], v[136:137], v[138:139], s[44:45] op_sel_hi:[1,1,0]
	v_pk_mul_f32 v[42:43], v[42:43], v[2:3]
	v_pk_mul_f32 v[120:121], v[120:121], v[136:137]
	v_pk_mul_f32 v[36:37], v[36:37], v[2:3]
	v_pk_fma_f32 v[70:71], v[70:71], v[120:121], v[70:71]
	v_lshlrev_b32_e32 v120, 16, v110
	v_pk_mul_f32 v[62:63], v[62:63], v[70:71]
	v_cvt_pk_bf16_f32 v70, v60, v61
	v_lshlrev_b64 v[60:61], 1, v[134:135]
	v_cvt_pk_bf16_f32 v71, v62, v63
	v_lshl_add_u64 v[62:63], v[130:131], 0, v[60:61]
	global_store_dwordx4 v[62:63], v[68:71], off nt
	v_lshlrev_b32_e32 v62, 16, v1
	v_and_b32_e32 v63, 0xffff0000, v1
	v_mov_b32_dpp v71, v114 row_ror:2 row_mask:0xf bank_mask:0xf bound_ctrl:1
	v_and_b32_e32 v121, 0xffff0000, v110
	v_mov_b32_dpp v69, v115 row_ror:1 row_mask:0xf bank_mask:0xf bound_ctrl:1
	v_mov_b32_dpp v71, v110 row_shr:2 row_mask:0xf bank_mask:0xf
	v_lshlrev_b32_e32 v70, 16, v71
	v_and_b32_e32 v71, 0xffff0000, v71
	v_pk_fma_f32 v[70:71], v[84:85], v[70:71], v[96:97]
	v_mov_b32_dpp v69, v111 row_shr:1 row_mask:0xf bank_mask:0xf
	v_pk_fma_f32 v[62:63], v[88:89], v[62:63], v[70:71]
	v_lshlrev_b32_e32 v114, 16, v101
	v_pk_fma_f32 v[62:63], v[92:93], v[120:121], v[62:63]
	v_and_b32_e32 v115, 0xffff0000, v101
	v_pk_mul_f32 v[70:71], v[62:63], s[26:27] op_sel_hi:[1,0]
	v_pk_mul_f32 v[62:63], v[62:63], 0.5 op_sel_hi:[1,0]
	v_med3_f32 v70, v70, s71, v224
	v_med3_f32 v71, v71, s71, v224
	v_pk_mul_f32 v[120:121], v[70:71], v[70:71]
	v_lshlrev_b32_e32 v68, 16, v69
	v_pk_fma_f32 v[130:131], v[120:121], s[28:29], v[118:119] op_sel_hi:[1,0,0] neg_lo:[1,0,0] neg_hi:[1,0,0]
; __device__ __forceinline__ unsigned cvt_pk_bf16(float lo, float hi) { unsigned r; asm volatile("v_cvt_pk_bf16_f32 %0, %1, %2" : "=v"(r) : "v"(lo), "v"(hi)); return r; }
;     static __device__ __forceinline__ u32x2 finish2(const float (&g0)[4], const float (&g1)[4], const float (&g2)[4], const float (&w0)[4], const float (&w1)[4], const float (&w2)[4], const float (&bb)[4],
;                                                     const f32x4 v, float rs) {
;         float h[4];
; #pragma unroll
;         for (int j = 0; j < 4; j += 2) {
;             const f32x2 gc = (f32x2){bb[j] + w0[j] * g2[j] + w1[j] * g1[j] + w2[j] * g0[j], bb[j + 1] + w0[j + 1] * g2[j + 1] + w1[j + 1] * g1[j + 1] + w2[j + 1] * g0[j + 1]};
;             const f32x2 ge = gelu_pk(gc) * ((f32x2){v[j], v[j + 1]} * rs); h[j] = ge.x; h[j + 1] = ge.y; }
;         u32x2 w; w.x = cvt_pk_bf16(h[0], h[1]); w.y = cvt_pk_bf16(h[2], h[3]); return w;
;     }
;     __device__ __forceinline__ void operator()(const f32x4 (&acc)[2][2][4][2], const Unit& u, int wr, int wc, int fr, int fq) const {
;     ...
;             for (int ai = 0; ai < 2; ++ai) { const int R0 = u.rb + ai * HALF + wr * 64; const bf16_t* gp = G + (size_t)(R0 + fr) * 2816 + col8;
;                 u32x4 gq[4], prv = (u32x4){0u, 0u, 0u, 0u};
; #pragma unroll
;                 for (int m = 0; m < 4; ++m) gq[m] = *(const u32x4*)(gp + (size_t)m * 16 * 2816);
;                 if ((R0 & 8191) != 0) prv = *(const u32x4*)(gp - (size_t)16 * 2816);
;                 u32x4 pv = prv;
; #pragma unroll
;                 for (int m = 0; m < 4; ++m) { const u32x4 cur = gq[m]; u32x4 hw;
; #pragma unroll
;                     for (int hv = 0; hv < 2; ++hv) { const u32x2 c2 = half2(cur, hv), p2 = half2(pv, hv);
;                         const u32x2 q1 = dpp_prev<1>(p2, c2), q2 = dpp_prev<2>(p2, c2);
;                         float g0[4], g1[4], g2[4]; unpk4(c2, g0); unpk4(q1, g1); unpk4(q2, g2);
;                         const u32x2 r = finish2(g0, g1, g2, w0[hv], w1[hv], w2[hv], bb[hv], acc[ai][bj][m][hv], rs8[ai][m]);
;                         if (hv == 0) { hw.x = r.x; hw.y = r.y; } else { hw.z = r.x; hw.w = r.y; } }
;                     *(u32x4*)(H + (size_t)(R0 + fr + 16 * m) * 2816 + col8) = hw;
;                     pv = cur; } }
	v_and_b32_e32 v69, 0xffff0000, v69
	v_pk_fma_f32 v[130:131], v[120:121], v[130:131], s[34:35] op_sel_hi:[1,1,0]
	v_mov_b32_dpp v1, v116 row_ror:1 row_mask:0xf bank_mask:0xf bound_ctrl:1
	v_pk_fma_f32 v[130:131], v[120:121], v[130:131], s[36:37] op_sel_hi:[1,1,0]
	v_pk_mul_f32 v[2:3], v[38:39], v[2:3]
	v_pk_fma_f32 v[130:131], v[120:121], v[130:131], s[38:39] op_sel_hi:[1,1,0]
	v_mov_b32_dpp v1, v112 row_shr:1 row_mask:0xf bank_mask:0xf
	v_pk_fma_f32 v[130:131], v[120:121], v[130:131], s[40:41] op_sel_hi:[1,1,0]
	v_mov_b32_e32 v101, 0
	v_pk_fma_f32 v[130:131], v[120:121], v[130:131], s[42:43] op_sel_hi:[1,1,0]
	s_nop 0
	v_pk_fma_f32 v[120:121], v[120:121], v[130:131], s[44:45] op_sel_hi:[1,1,0]
	s_nop 0
	v_pk_mul_f32 v[70:71], v[70:71], v[120:121]
	s_nop 0
	v_pk_fma_f32 v[62:63], v[62:63], v[70:71], v[62:63]
	v_pk_fma_f32 v[70:71], v[86:87], v[114:115], v[98:99]
	v_pk_mul_f32 v[56:57], v[56:57], v[62:63]
	v_lshlrev_b32_e32 v62, 16, v111
	v_and_b32_e32 v63, 0xffff0000, v111
	v_pk_fma_f32 v[68:69], v[90:91], v[68:69], v[70:71]
	v_cvt_pk_bf16_f32 v56, v56, v57
	s_nop 0
	v_pk_fma_f32 v[62:63], v[94:95], v[62:63], v[68:69]
	s_nop 0
	v_pk_mul_f32 v[68:69], v[62:63], s[26:27] op_sel_hi:[1,0]
	v_pk_mul_f32 v[62:63], v[62:63], 0.5 op_sel_hi:[1,0]
	v_med3_f32 v68, v68, s71, v224
	v_med3_f32 v69, v69, s71, v224
	v_pk_mul_f32 v[70:71], v[68:69], v[68:69]
	s_nop 0
	v_pk_fma_f32 v[114:115], v[70:71], s[28:29], v[118:119] op_sel_hi:[1,0,0] neg_lo:[1,0,0] neg_hi:[1,0,0]
	s_nop 0
	v_pk_fma_f32 v[114:115], v[70:71], v[114:115], s[34:35] op_sel_hi:[1,1,0]
	s_nop 0
	v_pk_fma_f32 v[114:115], v[70:71], v[114:115], s[36:37] op_sel_hi:[1,1,0]
	s_nop 0
	v_pk_fma_f32 v[114:115], v[70:71], v[114:115], s[38:39] op_sel_hi:[1,1,0]
	s_nop 0
	v_pk_fma_f32 v[114:115], v[70:71], v[114:115], s[40:41] op_sel_hi:[1,1,0]
	s_nop 0
	v_pk_fma_f32 v[114:115], v[70:71], v[114:115], s[42:43] op_sel_hi:[1,1,0]
	s_nop 0
	v_pk_fma_f32 v[70:71], v[70:71], v[114:115], s[44:45] op_sel_hi:[1,1,0]
	v_lshlrev_b32_e32 v114, 16, v112
	v_pk_mul_f32 v[68:69], v[68:69], v[70:71]
	v_and_b32_e32 v115, 0xffff0000, v112
	v_pk_fma_f32 v[62:63], v[62:63], v[68:69], v[62:63]
	v_mov_b32_dpp v69, v116 row_ror:2 row_mask:0xf bank_mask:0xf bound_ctrl:1
	v_pk_mul_f32 v[58:59], v[58:59], v[62:63]
	v_mov_b32_dpp v63, v117 row_ror:1 row_mask:0xf bank_mask:0xf bound_ctrl:1
	v_mov_b32_dpp v69, v112 row_shr:2 row_mask:0xf bank_mask:0xf
	v_lshlrev_b32_e32 v68, 16, v69
	v_and_b32_e32 v69, 0xffff0000, v69
	v_cvt_pk_bf16_f32 v57, v58, v59
	v_lshlrev_b32_e32 v58, 16, v1
	v_and_b32_e32 v59, 0xffff0000, v1
	v_pk_fma_f32 v[68:69], v[64:65], v[68:69], v[80:81]
	v_mov_b32_dpp v71, v117 row_ror:2 row_mask:0xf bank_mask:0xf bound_ctrl:1
	v_pk_fma_f32 v[58:59], v[72:73], v[58:59], v[68:69]
	v_mov_b32_dpp v63, v113 row_shr:1 row_mask:0xf bank_mask:0xf
	v_pk_fma_f32 v[58:59], v[76:77], v[114:115], v[58:59]
	v_mov_b32_dpp v71, v113 row_shr:2 row_mask:0xf bank_mask:0xf
	v_pk_mul_f32 v[68:69], v[58:59], s[26:27] op_sel_hi:[1,0]
	v_lshlrev_b32_e32 v70, 16, v71
	v_med3_f32 v68, v68, s71, v224
	v_med3_f32 v69, v69, s71, v224
	v_pk_mul_f32 v[114:115], v[68:69], v[68:69]
	v_and_b32_e32 v71, 0xffff0000, v71
	v_pk_fma_f32 v[116:117], v[114:115], s[28:29], v[118:119] op_sel_hi:[1,0,0] neg_lo:[1,0,0] neg_hi:[1,0,0]
	v_pk_mul_f32 v[58:59], v[58:59], 0.5 op_sel_hi:[1,0]
	v_pk_fma_f32 v[116:117], v[114:115], v[116:117], s[34:35] op_sel_hi:[1,1,0]
	v_lshlrev_b32_e32 v62, 16, v63
	v_pk_fma_f32 v[116:117], v[114:115], v[116:117], s[36:37] op_sel_hi:[1,1,0]
	v_and_b32_e32 v63, 0xffff0000, v63
	v_pk_fma_f32 v[116:117], v[114:115], v[116:117], s[38:39] op_sel_hi:[1,1,0]
	v_mov_b32_dpp v1, v110 row_ror:1 row_mask:0xf bank_mask:0xf bound_ctrl:1
	v_pk_fma_f32 v[116:117], v[114:115], v[116:117], s[40:41] op_sel_hi:[1,1,0]
	s_nop 0
	v_pk_fma_f32 v[116:117], v[114:115], v[116:117], s[42:43] op_sel_hi:[1,1,0]
	v_mov_b32_dpp v1, v106 row_shr:1 row_mask:0xf bank_mask:0xf
	v_pk_fma_f32 v[114:115], v[114:115], v[116:117], s[44:45] op_sel_hi:[1,1,0]
	s_nop 0
	v_pk_mul_f32 v[68:69], v[68:69], v[114:115]
	s_nop 0
	v_pk_fma_f32 v[58:59], v[58:59], v[68:69], v[58:59]
	v_pk_fma_f32 v[68:69], v[66:67], v[70:71], v[82:83]
	v_pk_mul_f32 v[52:53], v[52:53], v[58:59]
	v_lshlrev_b32_e32 v58, 16, v113
	v_and_b32_e32 v59, 0xffff0000, v113
	v_pk_fma_f32 v[62:63], v[74:75], v[62:63], v[68:69]
	s_nop 0
	v_pk_fma_f32 v[58:59], v[78:79], v[58:59], v[62:63]
	s_nop 0
	v_pk_mul_f32 v[62:63], v[58:59], s[26:27] op_sel_hi:[1,0]
	v_pk_mul_f32 v[58:59], v[58:59], 0.5 op_sel_hi:[1,0]
	v_med3_f32 v62, v62, s71, v224
	v_med3_f32 v63, v63, s71, v224
	v_pk_mul_f32 v[68:69], v[62:63], v[62:63]
	s_nop 0
	v_pk_fma_f32 v[70:71], v[68:69], s[28:29], v[118:119] op_sel_hi:[1,0,0] neg_lo:[1,0,0] neg_hi:[1,0,0]
	s_nop 0
	v_pk_fma_f32 v[70:71], v[68:69], v[70:71], s[34:35] op_sel_hi:[1,1,0]
	s_nop 0
	v_pk_fma_f32 v[70:71], v[68:69], v[70:71], s[36:37] op_sel_hi:[1,1,0]
	s_nop 0
	v_pk_fma_f32 v[70:71], v[68:69], v[70:71], s[38:39] op_sel_hi:[1,1,0]
	s_nop 0
	v_pk_fma_f32 v[70:71], v[68:69], v[70:71], s[40:41] op_sel_hi:[1,1,0]
	s_nop 0
	v_pk_fma_f32 v[70:71], v[68:69], v[70:71], s[42:43] op_sel_hi:[1,1,0]
	s_nop 0
	v_pk_fma_f32 v[68:69], v[68:69], v[70:71], s[44:45] op_sel_hi:[1,1,0]
	s_nop 0
	v_pk_mul_f32 v[62:63], v[62:63], v[68:69]
	s_nop 0
	v_pk_fma_f32 v[58:59], v[58:59], v[62:63], v[58:59]
	v_lshlrev_b32_e32 v62, 16, v106
	v_pk_mul_f32 v[54:55], v[54:55], v[58:59]
	v_cvt_pk_bf16_f32 v58, v52, v53
	v_lshl_add_u64 v[52:53], v[176:177], 0, v[60:61]
	v_cvt_pk_bf16_f32 v59, v54, v55
	global_store_dwordx4 v[52:53], v[56:59], off nt
	v_lshlrev_b32_e32 v52, 16, v1
	v_and_b32_e32 v53, 0xffff0000, v1
; __device__ __forceinline__ unsigned cvt_pk_bf16(float lo, float hi) { unsigned r; asm volatile("v_cvt_pk_bf16_f32 %0, %1, %2" : "=v"(r) : "v"(lo), "v"(hi)); return r; }
;     static __device__ __forceinline__ u32x2 finish2(const float (&g0)[4], const float (&g1)[4], const float (&g2)[4], const float (&w0)[4], const float (&w1)[4], const float (&w2)[4], const float (&bb)[4],
;                                                     const f32x4 v, float rs) {
;         float h[4];
; #pragma unroll
;         for (int j = 0; j < 4; j += 2) {
;             const f32x2 gc = (f32x2){bb[j] + w0[j] * g2[j] + w1[j] * g1[j] + w2[j] * g0[j], bb[j + 1] + w0[j + 1] * g2[j + 1] + w1[j + 1] * g1[j + 1] + w2[j + 1] * g0[j + 1]};
;             const f32x2 ge = gelu_pk(gc) * ((f32x2){v[j], v[j + 1]} * rs); h[j] = ge.x; h[j + 1] = ge.y; }
;         u32x2 w; w.x = cvt_pk_bf16(h[0], h[1]); w.y = cvt_pk_bf16(h[2], h[3]); return w;
;     }
;     __device__ __forceinline__ void operator()(const f32x4 (&acc)[2][2][4][2], const Unit& u, int wr, int wc, int fr, int fq) const {
;     ...
;             for (int ai = 0; ai < 2; ++ai) { const int R0 = u.rb + ai * HALF + wr * 64; const bf16_t* gp = G + (size_t)(R0 + fr) * 2816 + col8;
;                 u32x4 gq[4], prv = (u32x4){0u, 0u, 0u, 0u};
; #pragma unroll
;                 for (int m = 0; m < 4; ++m) gq[m] = *(const u32x4*)(gp + (size_t)m * 16 * 2816);
;                 if ((R0 & 8191) != 0) prv = *(const u32x4*)(gp - (size_t)16 * 2816);
;                 u32x4 pv = prv;
; #pragma unroll
;                 for (int m = 0; m < 4; ++m) { const u32x4 cur = gq[m]; u32x4 hw;
; #pragma unroll
;                     for (int hv = 0; hv < 2; ++hv) { const u32x2 c2 = half2(cur, hv), p2 = half2(pv, hv);
;                         const u32x2 q1 = dpp_prev<1>(p2, c2), q2 = dpp_prev<2>(p2, c2);
;                         float g0[4], g1[4], g2[4]; unpk4(c2, g0); unpk4(q1, g1); unpk4(q2, g2);
;                         const u32x2 r = finish2(g0, g1, g2, w0[hv], w1[hv], w2[hv], bb[hv], acc[ai][bj][m][hv], rs8[ai][m]);
;                         if (hv == 0) { hw.x = r.x; hw.y = r.y; } else { hw.z = r.x; hw.w = r.y; } }
;                     *(u32x4*)(H + (size_t)(R0 + fr + 16 * m) * 2816 + col8) = hw;
;                     pv = cur; } }
	v_mov_b32_dpp v57, v110 row_ror:2 row_mask:0xf bank_mask:0xf bound_ctrl:1
	v_and_b32_e32 v63, 0xffff0000, v106
	v_mov_b32_dpp v59, v111 row_ror:2 row_mask:0xf bank_mask:0xf bound_ctrl:1
	v_mov_b32_dpp v57, v106 row_shr:2 row_mask:0xf bank_mask:0xf
	v_lshlrev_b32_e32 v56, 16, v57
	v_and_b32_e32 v57, 0xffff0000, v57
	v_pk_fma_f32 v[56:57], v[84:85], v[56:57], v[96:97]
	v_mov_b32_dpp v55, v111 row_ror:1 row_mask:0xf bank_mask:0xf bound_ctrl:1
	v_pk_fma_f32 v[52:53], v[88:89], v[52:53], v[56:57]
	v_mov_b32_dpp v59, v107 row_shr:2 row_mask:0xf bank_mask:0xf
	v_pk_fma_f32 v[52:53], v[92:93], v[62:63], v[52:53]
	v_mov_b32_dpp v55, v107 row_shr:1 row_mask:0xf bank_mask:0xf
	v_pk_mul_f32 v[56:57], v[52:53], s[26:27] op_sel_hi:[1,0]
	v_lshlrev_b32_e32 v58, 16, v59
	v_med3_f32 v56, v56, s71, v224
	v_med3_f32 v57, v57, s71, v224
	v_pk_mul_f32 v[62:63], v[56:57], v[56:57]
	v_and_b32_e32 v59, 0xffff0000, v59
	v_pk_fma_f32 v[68:69], v[62:63], s[28:29], v[118:119] op_sel_hi:[1,0,0] neg_lo:[1,0,0] neg_hi:[1,0,0]
	v_pk_mul_f32 v[52:53], v[52:53], 0.5 op_sel_hi:[1,0]
	v_pk_fma_f32 v[68:69], v[62:63], v[68:69], s[34:35] op_sel_hi:[1,1,0]
	v_lshlrev_b32_e32 v54, 16, v55
	v_pk_fma_f32 v[68:69], v[62:63], v[68:69], s[36:37] op_sel_hi:[1,1,0]
	v_and_b32_e32 v55, 0xffff0000, v55
	v_pk_fma_f32 v[68:69], v[62:63], v[68:69], s[38:39] op_sel_hi:[1,1,0]
	v_mov_b32_dpp v1, v112 row_ror:1 row_mask:0xf bank_mask:0xf bound_ctrl:1
	v_pk_fma_f32 v[68:69], v[62:63], v[68:69], s[40:41] op_sel_hi:[1,1,0]
	s_nop 0
	v_pk_fma_f32 v[68:69], v[62:63], v[68:69], s[42:43] op_sel_hi:[1,1,0]
	v_mov_b32_dpp v1, v108 row_shr:1 row_mask:0xf bank_mask:0xf
	v_pk_fma_f32 v[62:63], v[62:63], v[68:69], s[44:45] op_sel_hi:[1,1,0]
	s_nop 0
	v_pk_mul_f32 v[56:57], v[56:57], v[62:63]
	s_nop 0
	v_pk_fma_f32 v[52:53], v[52:53], v[56:57], v[52:53]
	v_pk_fma_f32 v[56:57], v[86:87], v[58:59], v[98:99]
	v_pk_mul_f32 v[48:49], v[48:49], v[52:53]
	v_lshlrev_b32_e32 v52, 16, v107
	v_and_b32_e32 v53, 0xffff0000, v107
	v_pk_fma_f32 v[54:55], v[90:91], v[54:55], v[56:57]
	v_cvt_pk_bf16_f32 v48, v48, v49
	s_nop 0
	v_pk_fma_f32 v[52:53], v[94:95], v[52:53], v[54:55]
	s_nop 0
	v_pk_mul_f32 v[54:55], v[52:53], s[26:27] op_sel_hi:[1,0]
	v_pk_mul_f32 v[52:53], v[52:53], 0.5 op_sel_hi:[1,0]
	v_med3_f32 v54, v54, s71, v224
	v_med3_f32 v55, v55, s71, v224
	v_pk_mul_f32 v[56:57], v[54:55], v[54:55]
	s_nop 0
	v_pk_fma_f32 v[58:59], v[56:57], s[28:29], v[118:119] op_sel_hi:[1,0,0] neg_lo:[1,0,0] neg_hi:[1,0,0]
	s_nop 0
	v_pk_fma_f32 v[58:59], v[56:57], v[58:59], s[34:35] op_sel_hi:[1,1,0]
	s_nop 0
	v_pk_fma_f32 v[58:59], v[56:57], v[58:59], s[36:37] op_sel_hi:[1,1,0]
	s_nop 0
	v_pk_fma_f32 v[58:59], v[56:57], v[58:59], s[38:39] op_sel_hi:[1,1,0]
	s_nop 0
	v_pk_fma_f32 v[58:59], v[56:57], v[58:59], s[40:41] op_sel_hi:[1,1,0]
	s_nop 0
	v_pk_fma_f32 v[58:59], v[56:57], v[58:59], s[42:43] op_sel_hi:[1,1,0]
	s_nop 0
	v_pk_fma_f32 v[56:57], v[56:57], v[58:59], s[44:45] op_sel_hi:[1,1,0]
	v_lshlrev_b32_e32 v58, 16, v108
	v_pk_mul_f32 v[54:55], v[54:55], v[56:57]
	v_and_b32_e32 v59, 0xffff0000, v108
	v_pk_fma_f32 v[52:53], v[52:53], v[54:55], v[52:53]
	v_mov_b32_dpp v55, v112 row_ror:2 row_mask:0xf bank_mask:0xf bound_ctrl:1
	v_pk_mul_f32 v[50:51], v[50:51], v[52:53]
	v_mov_b32_dpp v57, v113 row_ror:2 row_mask:0xf bank_mask:0xf bound_ctrl:1
	v_mov_b32_dpp v55, v108 row_shr:2 row_mask:0xf bank_mask:0xf
	v_lshlrev_b32_e32 v54, 16, v55
	v_and_b32_e32 v55, 0xffff0000, v55
	v_cvt_pk_bf16_f32 v49, v50, v51
	v_lshlrev_b32_e32 v50, 16, v1
	v_and_b32_e32 v51, 0xffff0000, v1
	v_pk_fma_f32 v[54:55], v[64:65], v[54:55], v[80:81]
	v_mov_b32_dpp v53, v113 row_ror:1 row_mask:0xf bank_mask:0xf bound_ctrl:1
	v_pk_fma_f32 v[50:51], v[72:73], v[50:51], v[54:55]
	v_mov_b32_dpp v57, v109 row_shr:2 row_mask:0xf bank_mask:0xf
	v_pk_fma_f32 v[50:51], v[76:77], v[58:59], v[50:51]
	v_mov_b32_dpp v53, v109 row_shr:1 row_mask:0xf bank_mask:0xf
	v_pk_mul_f32 v[54:55], v[50:51], s[26:27] op_sel_hi:[1,0]
	v_lshlrev_b32_e32 v56, 16, v57
	v_med3_f32 v54, v54, s71, v224
	v_med3_f32 v55, v55, s71, v224
	v_pk_mul_f32 v[58:59], v[54:55], v[54:55]
	v_and_b32_e32 v57, 0xffff0000, v57
	v_pk_fma_f32 v[62:63], v[58:59], s[28:29], v[118:119] op_sel_hi:[1,0,0] neg_lo:[1,0,0] neg_hi:[1,0,0]
	v_pk_mul_f32 v[50:51], v[50:51], 0.5 op_sel_hi:[1,0]
	v_pk_fma_f32 v[62:63], v[58:59], v[62:63], s[34:35] op_sel_hi:[1,1,0]
	v_lshlrev_b32_e32 v52, 16, v53
	v_pk_fma_f32 v[62:63], v[58:59], v[62:63], s[36:37] op_sel_hi:[1,1,0]
	v_and_b32_e32 v53, 0xffff0000, v53
	v_pk_fma_f32 v[62:63], v[58:59], v[62:63], s[38:39] op_sel_hi:[1,1,0]
	v_mov_b32_dpp v1, v106 row_ror:1 row_mask:0xf bank_mask:0xf bound_ctrl:1
	v_pk_fma_f32 v[62:63], v[58:59], v[62:63], s[40:41] op_sel_hi:[1,1,0]
	s_nop 0
	v_pk_fma_f32 v[62:63], v[58:59], v[62:63], s[42:43] op_sel_hi:[1,1,0]
	v_mov_b32_dpp v1, v102 row_shr:1 row_mask:0xf bank_mask:0xf
	v_pk_fma_f32 v[58:59], v[58:59], v[62:63], s[44:45] op_sel_hi:[1,1,0]
	s_nop 0
	v_pk_mul_f32 v[54:55], v[54:55], v[58:59]
	s_nop 0
	v_pk_fma_f32 v[50:51], v[50:51], v[54:55], v[50:51]
	v_pk_fma_f32 v[54:55], v[66:67], v[56:57], v[82:83]
	v_pk_mul_f32 v[44:45], v[44:45], v[50:51]
	v_lshlrev_b32_e32 v50, 16, v109
	v_and_b32_e32 v51, 0xffff0000, v109
	v_pk_fma_f32 v[52:53], v[74:75], v[52:53], v[54:55]
	s_nop 0
	v_pk_fma_f32 v[50:51], v[78:79], v[50:51], v[52:53]
	s_nop 0
	v_pk_mul_f32 v[52:53], v[50:51], s[26:27] op_sel_hi:[1,0]
	v_pk_mul_f32 v[50:51], v[50:51], 0.5 op_sel_hi:[1,0]
	v_med3_f32 v52, v52, s71, v224
	v_med3_f32 v53, v53, s71, v224
	v_pk_mul_f32 v[54:55], v[52:53], v[52:53]
	s_nop 0
	v_pk_fma_f32 v[56:57], v[54:55], s[28:29], v[118:119] op_sel_hi:[1,0,0] neg_lo:[1,0,0] neg_hi:[1,0,0]
;     static __device__ __forceinline__ u32x2 finish2(const float (&g0)[4], const float (&g1)[4], const float (&g2)[4], const float (&w0)[4], const float (&w1)[4], const float (&w2)[4], const float (&bb)[4],
;                                                     const f32x4 v, float rs) {
;         float h[4];
; #pragma unroll
;         for (int j = 0; j < 4; j += 2) {
;             const f32x2 gc = (f32x2){bb[j] + w0[j] * g2[j] + w1[j] * g1[j] + w2[j] * g0[j], bb[j + 1] + w0[j + 1] * g2[j + 1] + w1[j + 1] * g1[j + 1] + w2[j + 1] * g0[j + 1]};
;             const f32x2 ge = gelu_pk(gc) * ((f32x2){v[j], v[j + 1]} * rs); h[j] = ge.x; h[j + 1] = ge.y; }
;         u32x2 w; w.x = cvt_pk_bf16(h[0], h[1]); w.y = cvt_pk_bf16(h[2], h[3]); return w;
;     }
;     __device__ __forceinline__ void operator()(const f32x4 (&acc)[2][2][4][2], const Unit& u, int wr, int wc, int fr, int fq) const {
;         asm volatile("" : "+v"(fr), "+v"(fq));
;         const int row0 = u.rb + wr * 64 + fr;
;         const int lane = fq * 16 + fr;
;         const int s1 = fr >= 1 ? lane - 1 : lane + 15, s2 = fr >= 2 ? lane - 2 : lane + 14; (void)s1; (void)s2;
;         float rs8[2][4];
; #pragma unroll
;         for (int ai = 0; ai < 2; ++ai)
; #pragma unroll
;             for (int m = 0; m < 4; ++m) rs8[ai][m] = rsqrtf(SS[u.rb + (u.half ? 0 : ai * HALF) + wr * 64 + fr + 16 * m] * (1.f / 1024.f) + 1e-6f);
;         if (u.pm < 128) {
; #pragma unroll
;           for (int bj = 0; bj < 2; ++bj) {
;             const int col8 = u.pn * BM + bj * HALF + wc * 32 + 8 * fq;
;             float w0[2][4], w1[2][4], w2[2][4], bb[2][4];
; #pragma unroll
;             for (int hv = 0; hv < 2; ++hv) { ld4f(cw + col8 + 4 * hv, w0[hv]); ld4f(cw + 2816 + col8 + 4 * hv, w1[hv]); ld4f(cw + 2 * 2816 + col8 + 4 * hv, w2[hv]); ld4f(cb + col8 + 4 * hv, bb[hv]); }
; #pragma unroll
;             for (int ai = 0; ai < 2; ++ai) { const int R0 = u.rb + ai * HALF + wr * 64; const bf16_t* gp = G + (size_t)(R0 + fr) * 2816 + col8;
;                 u32x4 gq[4], prv = (u32x4){0u, 0u, 0u, 0u};
; #pragma unroll
;                 for (int m = 0; m < 4; ++m) gq[m] = *(const u32x4*)(gp + (size_t)m * 16 * 2816);
;                 if ((R0 & 8191) != 0) prv = *(const u32x4*)(gp - (size_t)16 * 2816);
;                 u32x4 pv = prv;
; #pragma unroll
	s_nop 0
	v_pk_fma_f32 v[56:57], v[54:55], v[56:57], s[34:35] op_sel_hi:[1,1,0]
	s_nop 0
	v_pk_fma_f32 v[56:57], v[54:55], v[56:57], s[36:37] op_sel_hi:[1,1,0]
	s_nop 0
	v_pk_fma_f32 v[56:57], v[54:55], v[56:57], s[38:39] op_sel_hi:[1,1,0]
	s_nop 0
	v_pk_fma_f32 v[56:57], v[54:55], v[56:57], s[40:41] op_sel_hi:[1,1,0]
	s_nop 0
	v_pk_fma_f32 v[56:57], v[54:55], v[56:57], s[42:43] op_sel_hi:[1,1,0]
	s_nop 0
	v_pk_fma_f32 v[54:55], v[54:55], v[56:57], s[44:45] op_sel_hi:[1,1,0]
	v_lshl_add_u64 v[56:57], v[166:167], 0, v[60:61]
	v_pk_mul_f32 v[52:53], v[52:53], v[54:55]
	s_nop 0
	v_pk_fma_f32 v[50:51], v[50:51], v[52:53], v[50:51]
	v_lshlrev_b32_e32 v52, 16, v102
	v_pk_mul_f32 v[46:47], v[46:47], v[50:51]
	v_cvt_pk_bf16_f32 v50, v44, v45
	v_lshl_add_u64 v[44:45], v[172:173], 0, v[60:61]
	v_cvt_pk_bf16_f32 v51, v46, v47
	global_store_dwordx4 v[44:45], v[48:51], off nt
	v_lshlrev_b32_e32 v44, 16, v1
	v_and_b32_e32 v45, 0xffff0000, v1
	v_mov_b32_dpp v49, v106 row_ror:2 row_mask:0xf bank_mask:0xf bound_ctrl:1
	v_and_b32_e32 v53, 0xffff0000, v102
	v_mov_b32_dpp v51, v107 row_ror:2 row_mask:0xf bank_mask:0xf bound_ctrl:1
	v_mov_b32_dpp v49, v102 row_shr:2 row_mask:0xf bank_mask:0xf
	v_lshlrev_b32_e32 v48, 16, v49
	v_and_b32_e32 v49, 0xffff0000, v49
	v_pk_fma_f32 v[48:49], v[84:85], v[48:49], v[96:97]
	v_mov_b32_dpp v47, v107 row_ror:1 row_mask:0xf bank_mask:0xf bound_ctrl:1
	v_pk_fma_f32 v[44:45], v[88:89], v[44:45], v[48:49]
	v_mov_b32_dpp v51, v103 row_shr:2 row_mask:0xf bank_mask:0xf
	v_pk_fma_f32 v[44:45], v[92:93], v[52:53], v[44:45]
	v_mov_b32_dpp v47, v103 row_shr:1 row_mask:0xf bank_mask:0xf
	v_pk_mul_f32 v[48:49], v[44:45], s[26:27] op_sel_hi:[1,0]
	v_lshlrev_b32_e32 v50, 16, v51
	v_med3_f32 v48, v48, s71, v224
	v_med3_f32 v49, v49, s71, v224
	v_pk_mul_f32 v[52:53], v[48:49], v[48:49]
	v_and_b32_e32 v51, 0xffff0000, v51
	v_pk_fma_f32 v[54:55], v[52:53], s[28:29], v[118:119] op_sel_hi:[1,0,0] neg_lo:[1,0,0] neg_hi:[1,0,0]
	v_pk_mul_f32 v[44:45], v[44:45], 0.5 op_sel_hi:[1,0]
	v_pk_fma_f32 v[54:55], v[52:53], v[54:55], s[34:35] op_sel_hi:[1,1,0]
	v_lshlrev_b32_e32 v46, 16, v47
	v_pk_fma_f32 v[54:55], v[52:53], v[54:55], s[36:37] op_sel_hi:[1,1,0]
	v_and_b32_e32 v47, 0xffff0000, v47
	v_pk_fma_f32 v[54:55], v[52:53], v[54:55], s[38:39] op_sel_hi:[1,1,0]
	v_mov_b32_dpp v1, v108 row_ror:1 row_mask:0xf bank_mask:0xf bound_ctrl:1
	v_pk_fma_f32 v[54:55], v[52:53], v[54:55], s[40:41] op_sel_hi:[1,1,0]
	v_mov_b32_e32 v102, 0
	v_pk_fma_f32 v[54:55], v[52:53], v[54:55], s[42:43] op_sel_hi:[1,1,0]
	v_mov_b32_dpp v1, v104 row_shr:1 row_mask:0xf bank_mask:0xf
	v_pk_fma_f32 v[52:53], v[52:53], v[54:55], s[44:45] op_sel_hi:[1,1,0]
	s_nop 0
	v_pk_mul_f32 v[48:49], v[48:49], v[52:53]
	s_nop 0
	v_pk_fma_f32 v[44:45], v[44:45], v[48:49], v[44:45]
	v_pk_fma_f32 v[48:49], v[86:87], v[50:51], v[98:99]
	v_pk_mul_f32 v[40:41], v[40:41], v[44:45]
	v_lshlrev_b32_e32 v44, 16, v103
	v_and_b32_e32 v45, 0xffff0000, v103
	v_pk_fma_f32 v[46:47], v[90:91], v[46:47], v[48:49]
	v_cvt_pk_bf16_f32 v52, v40, v41
	v_lshlrev_b32_e32 v40, 16, v1
	v_pk_fma_f32 v[44:45], v[94:95], v[44:45], v[46:47]
	v_and_b32_e32 v41, 0xffff0000, v1
	v_pk_mul_f32 v[46:47], v[44:45], s[26:27] op_sel_hi:[1,0]
	v_pk_mul_f32 v[44:45], v[44:45], 0.5 op_sel_hi:[1,0]
	v_med3_f32 v46, v46, s71, v224
	v_med3_f32 v47, v47, s71, v224
	v_pk_mul_f32 v[48:49], v[46:47], v[46:47]
	v_mov_b32_e32 v103, 0
	v_pk_fma_f32 v[50:51], v[48:49], s[28:29], v[118:119] op_sel_hi:[1,0,0] neg_lo:[1,0,0] neg_hi:[1,0,0]
	s_nop 0
	v_pk_fma_f32 v[50:51], v[48:49], v[50:51], s[34:35] op_sel_hi:[1,1,0]
	s_nop 0
	v_pk_fma_f32 v[50:51], v[48:49], v[50:51], s[36:37] op_sel_hi:[1,1,0]
	s_nop 0
	v_pk_fma_f32 v[50:51], v[48:49], v[50:51], s[38:39] op_sel_hi:[1,1,0]
	s_nop 0
	v_pk_fma_f32 v[50:51], v[48:49], v[50:51], s[40:41] op_sel_hi:[1,1,0]
	s_nop 0
	v_pk_fma_f32 v[50:51], v[48:49], v[50:51], s[42:43] op_sel_hi:[1,1,0]
	s_nop 0
	v_pk_fma_f32 v[48:49], v[48:49], v[50:51], s[44:45] op_sel_hi:[1,1,0]
	s_nop 0
	v_pk_mul_f32 v[46:47], v[46:47], v[48:49]
	v_lshlrev_b32_e32 v48, 16, v104
	v_pk_fma_f32 v[44:45], v[44:45], v[46:47], v[44:45]
	v_and_b32_e32 v49, 0xffff0000, v104
	v_pk_mul_f32 v[42:43], v[42:43], v[44:45]
	v_mov_b32_dpp v45, v108 row_ror:2 row_mask:0xf bank_mask:0xf bound_ctrl:1
	v_mov_b32_dpp v47, v109 row_ror:2 row_mask:0xf bank_mask:0xf bound_ctrl:1
	v_cvt_pk_bf16_f32 v53, v42, v43
	v_mov_b32_dpp v43, v109 row_ror:1 row_mask:0xf bank_mask:0xf bound_ctrl:1
	v_mov_b32_dpp v45, v104 row_shr:2 row_mask:0xf bank_mask:0xf
	v_lshlrev_b32_e32 v44, 16, v45
	v_and_b32_e32 v45, 0xffff0000, v45
	v_pk_fma_f32 v[44:45], v[64:65], v[44:45], v[80:81]
	v_mov_b32_dpp v47, v105 row_shr:2 row_mask:0xf bank_mask:0xf
	v_pk_fma_f32 v[40:41], v[72:73], v[40:41], v[44:45]
	v_mov_b32_dpp v43, v105 row_shr:1 row_mask:0xf bank_mask:0xf
	v_pk_fma_f32 v[40:41], v[76:77], v[48:49], v[40:41]
	v_lshlrev_b32_e32 v46, 16, v47
	v_pk_mul_f32 v[44:45], v[40:41], s[26:27] op_sel_hi:[1,0]
	v_and_b32_e32 v47, 0xffff0000, v47
	v_med3_f32 v44, v44, s71, v224
	v_med3_f32 v45, v45, s71, v224
	v_pk_mul_f32 v[48:49], v[44:45], v[44:45]
	v_pk_mul_f32 v[40:41], v[40:41], 0.5 op_sel_hi:[1,0]
	v_pk_fma_f32 v[50:51], v[48:49], s[28:29], v[118:119] op_sel_hi:[1,0,0] neg_lo:[1,0,0] neg_hi:[1,0,0]
	v_lshlrev_b32_e32 v42, 16, v43
	v_pk_fma_f32 v[50:51], v[48:49], v[50:51], s[34:35] op_sel_hi:[1,1,0]
	v_and_b32_e32 v43, 0xffff0000, v43
	v_pk_fma_f32 v[50:51], v[48:49], v[50:51], s[36:37] op_sel_hi:[1,1,0]
	s_nop 0
	v_pk_fma_f32 v[50:51], v[48:49], v[50:51], s[38:39] op_sel_hi:[1,1,0]
	s_nop 0
	v_pk_fma_f32 v[50:51], v[48:49], v[50:51], s[40:41] op_sel_hi:[1,1,0]
	s_nop 0
; __device__ __forceinline__ unsigned cvt_pk_bf16(float lo, float hi) { unsigned r; asm volatile("v_cvt_pk_bf16_f32 %0, %1, %2" : "=v"(r) : "v"(lo), "v"(hi)); return r; }
;     static __device__ __forceinline__ u32x2 finish2(const float (&g0)[4], const float (&g1)[4], const float (&g2)[4], const float (&w0)[4], const float (&w1)[4], const float (&w2)[4], const float (&bb)[4],
;                                                     const f32x4 v, float rs) {
;         float h[4];
; #pragma unroll
;         for (int j = 0; j < 4; j += 2) {
;             const f32x2 gc = (f32x2){bb[j] + w0[j] * g2[j] + w1[j] * g1[j] + w2[j] * g0[j], bb[j + 1] + w0[j + 1] * g2[j + 1] + w1[j + 1] * g1[j + 1] + w2[j + 1] * g0[j + 1]};
;             const f32x2 ge = gelu_pk(gc) * ((f32x2){v[j], v[j + 1]} * rs); h[j] = ge.x; h[j + 1] = ge.y; }
;         u32x2 w; w.x = cvt_pk_bf16(h[0], h[1]); w.y = cvt_pk_bf16(h[2], h[3]); return w;
;     }
;     __device__ __forceinline__ void operator()(const f32x4 (&acc)[2][2][4][2], const Unit& u, int wr, int wc, int fr, int fq) const {
;     ...
;             for (int ai = 0; ai < 2; ++ai) { const int R0 = u.rb + ai * HALF + wr * 64; const bf16_t* gp = G + (size_t)(R0 + fr) * 2816 + col8;
;                 u32x4 gq[4], prv = (u32x4){0u, 0u, 0u, 0u};
; #pragma unroll
;                 for (int m = 0; m < 4; ++m) gq[m] = *(const u32x4*)(gp + (size_t)m * 16 * 2816);
;                 if ((R0 & 8191) != 0) prv = *(const u32x4*)(gp - (size_t)16 * 2816);
;                 u32x4 pv = prv;
; #pragma unroll
;                 for (int m = 0; m < 4; ++m) { const u32x4 cur = gq[m]; u32x4 hw;
; #pragma unroll
;                     for (int hv = 0; hv < 2; ++hv) { const u32x2 c2 = half2(cur, hv), p2 = half2(pv, hv);
;                         const u32x2 q1 = dpp_prev<1>(p2, c2), q2 = dpp_prev<2>(p2, c2);
;                         float g0[4], g1[4], g2[4]; unpk4(c2, g0); unpk4(q1, g1); unpk4(q2, g2);
;                         const u32x2 r = finish2(g0, g1, g2, w0[hv], w1[hv], w2[hv], bb[hv], acc[ai][bj][m][hv], rs8[ai][m]);
;                         if (hv == 0) { hw.x = r.x; hw.y = r.y; } else { hw.z = r.x; hw.w = r.y; } }
;                     *(u32x4*)(H + (size_t)(R0 + fr + 16 * m) * 2816 + col8) = hw;
;                     pv = cur; } }
	v_pk_fma_f32 v[50:51], v[48:49], v[50:51], s[42:43] op_sel_hi:[1,1,0]
	s_nop 0
	v_pk_fma_f32 v[48:49], v[48:49], v[50:51], s[44:45] op_sel_hi:[1,1,0]
	s_nop 0
	v_pk_mul_f32 v[44:45], v[44:45], v[48:49]
	s_nop 0
	v_pk_fma_f32 v[40:41], v[40:41], v[44:45], v[40:41]
	v_pk_fma_f32 v[44:45], v[66:67], v[46:47], v[82:83]
	v_pk_mul_f32 v[36:37], v[36:37], v[40:41]
	v_lshlrev_b32_e32 v40, 16, v105
	v_and_b32_e32 v41, 0xffff0000, v105
	v_pk_fma_f32 v[42:43], v[74:75], v[42:43], v[44:45]
	v_cvt_pk_bf16_f32 v54, v36, v37
	s_nop 0
	v_pk_fma_f32 v[40:41], v[78:79], v[40:41], v[42:43]
	s_nop 0
	v_pk_mul_f32 v[42:43], v[40:41], s[26:27] op_sel_hi:[1,0]
	v_pk_mul_f32 v[40:41], v[40:41], 0.5 op_sel_hi:[1,0]
	v_med3_f32 v42, v42, s71, v224
	v_med3_f32 v43, v43, s71, v224
	v_pk_mul_f32 v[44:45], v[42:43], v[42:43]
	s_nop 0
	v_pk_fma_f32 v[46:47], v[44:45], s[28:29], v[118:119] op_sel_hi:[1,0,0] neg_lo:[1,0,0] neg_hi:[1,0,0]
	s_nop 0
	v_pk_fma_f32 v[46:47], v[44:45], v[46:47], s[34:35] op_sel_hi:[1,1,0]
	s_nop 0
	v_pk_fma_f32 v[46:47], v[44:45], v[46:47], s[36:37] op_sel_hi:[1,1,0]
	s_nop 0
	v_pk_fma_f32 v[46:47], v[44:45], v[46:47], s[38:39] op_sel_hi:[1,1,0]
	s_nop 0
	v_pk_fma_f32 v[46:47], v[44:45], v[46:47], s[40:41] op_sel_hi:[1,1,0]
	s_nop 0
	v_pk_fma_f32 v[46:47], v[44:45], v[46:47], s[42:43] op_sel_hi:[1,1,0]
	s_nop 0
	v_pk_fma_f32 v[44:45], v[44:45], v[46:47], s[44:45] op_sel_hi:[1,1,0]
	s_nop 0
	v_pk_mul_f32 v[42:43], v[42:43], v[44:45]
	s_nop 0
	v_pk_fma_f32 v[40:41], v[40:41], v[42:43], v[40:41]
	s_nop 0
	v_pk_mul_f32 v[2:3], v[2:3], v[40:41]
	s_nop 0
	v_cvt_pk_bf16_f32 v55, v2, v3
	v_lshl_add_u64 v[2:3], v[164:165], 0, v[60:61]
	v_add_co_u32_e32 v36, vcc, s45, v2
	s_nop 1
	v_addc_co_u32_e32 v37, vcc, 0, v3, vcc
	global_load_dwordx4 v[48:51], v[2:3], off
	global_load_dwordx4 v[44:47], v[36:37], off
	v_add_co_u32_e32 v36, vcc, 0x2c000, v2
	s_nop 1
	v_addc_co_u32_e32 v37, vcc, 0, v3, vcc
	v_add_co_u32_e32 v38, vcc, 0x42000, v2
	s_nop 1
	v_addc_co_u32_e32 v39, vcc, 0, v3, vcc
	global_load_dwordx4 v[40:43], v[36:37], off
	s_nop 0
	global_load_dwordx4 v[36:39], v[38:39], off
	s_andn2_b64 vcc, exec, s[8:9]
	global_store_dwordx4 v[56:57], v[52:55], off nt
	s_cbranch_vccnz .LBB0_3152
	v_add_co_u32_e32 v2, vcc, 0xfffea000, v2
	s_nop 1
	v_addc_co_u32_e32 v3, vcc, -1, v3, vcc
	global_load_dwordx4 v[100:103], v[2:3], off
.LBB0_3152:
	s_waitcnt vmcnt(0)
	s_nop 0
	v_mov_b32_dpp v55, v100 row_ror:2 row_mask:0xf bank_mask:0xf bound_ctrl:1
	v_mov_b32_dpp v1, v100 row_ror:1 row_mask:0xf bank_mask:0xf bound_ctrl:1
	v_lshlrev_b32_e32 v58, 16, v48
	v_mov_b32_dpp v55, v48 row_shr:2 row_mask:0xf bank_mask:0xf
	v_mov_b32_dpp v1, v48 row_shr:1 row_mask:0xf bank_mask:0xf
	v_lshlrev_b32_e32 v54, 16, v55
	v_and_b32_e32 v55, 0xffff0000, v55
	v_lshlrev_b32_e32 v2, 16, v1
	v_and_b32_e32 v3, 0xffff0000, v1
	v_pk_fma_f32 v[54:55], v[84:85], v[54:55], v[96:97]
	v_and_b32_e32 v59, 0xffff0000, v48
	v_pk_fma_f32 v[2:3], v[88:89], v[2:3], v[54:55]
	v_mov_b32_dpp v57, v101 row_ror:2 row_mask:0xf bank_mask:0xf bound_ctrl:1
	v_pk_fma_f32 v[54:55], v[92:93], v[58:59], v[2:3]
	v_mov_b32_dpp v53, v101 row_ror:1 row_mask:0xf bank_mask:0xf bound_ctrl:1
	v_pk_mul_f32 v[2:3], v[54:55], s[26:27] op_sel_hi:[1,0]
	v_mov_b32_dpp v57, v49 row_shr:2 row_mask:0xf bank_mask:0xf
	v_med3_f32 v58, v2, s71, v224
	v_med3_f32 v59, v3, s71, v224
	v_pk_mul_f32 v[62:63], v[58:59], v[58:59]
	v_mov_b64_e32 v[2:3], s[30:31]
	v_pk_fma_f32 v[68:69], v[62:63], s[28:29], v[2:3] op_sel_hi:[1,0,0] neg_lo:[1,0,0] neg_hi:[1,0,0]
	v_mov_b32_e32 v129, v128
	v_pk_fma_f32 v[68:69], v[62:63], v[68:69], s[34:35] op_sel_hi:[1,1,0]
	v_mov_b32_dpp v53, v49 row_shr:1 row_mask:0xf bank_mask:0xf
	v_pk_fma_f32 v[68:69], v[62:63], v[68:69], s[36:37] op_sel_hi:[1,1,0]
	v_lshlrev_b32_e32 v56, 16, v57
	v_pk_fma_f32 v[68:69], v[62:63], v[68:69], s[38:39] op_sel_hi:[1,1,0]
	v_and_b32_e32 v57, 0xffff0000, v57
	v_pk_fma_f32 v[68:69], v[62:63], v[68:69], s[40:41] op_sel_hi:[1,1,0]
	v_pk_mul_f32 v[54:55], v[54:55], 0.5 op_sel_hi:[1,0]
	v_pk_fma_f32 v[68:69], v[62:63], v[68:69], s[42:43] op_sel_hi:[1,1,0]
	v_lshlrev_b32_e32 v52, 16, v53
	v_pk_fma_f32 v[62:63], v[62:63], v[68:69], s[44:45] op_sel_hi:[1,1,0]
	v_and_b32_e32 v53, 0xffff0000, v53
	v_pk_mul_f32 v[58:59], v[58:59], v[62:63]
	v_pk_mul_f32 v[32:33], v[32:33], v[128:129]
	v_pk_fma_f32 v[54:55], v[54:55], v[58:59], v[54:55]
	v_pk_fma_f32 v[56:57], v[86:87], v[56:57], v[98:99]
	v_pk_mul_f32 v[32:33], v[32:33], v[54:55]
	v_lshlrev_b32_e32 v54, 16, v49
	v_and_b32_e32 v55, 0xffff0000, v49
	v_pk_fma_f32 v[52:53], v[90:91], v[52:53], v[56:57]
	v_pk_mul_f32 v[34:35], v[34:35], v[128:129]
	v_pk_fma_f32 v[52:53], v[94:95], v[54:55], v[52:53]
	v_mov_b32_dpp v1, v102 row_ror:1 row_mask:0xf bank_mask:0xf bound_ctrl:1
	v_pk_mul_f32 v[54:55], v[52:53], s[26:27] op_sel_hi:[1,0]
	v_pk_mul_f32 v[52:53], v[52:53], 0.5 op_sel_hi:[1,0]
	v_med3_f32 v54, v54, s71, v224
	v_med3_f32 v55, v55, s71, v224
	v_pk_mul_f32 v[56:57], v[54:55], v[54:55]
	v_mov_b32_dpp v1, v50 row_shr:1 row_mask:0xf bank_mask:0xf
	v_pk_fma_f32 v[58:59], v[56:57], s[28:29], v[2:3] op_sel_hi:[1,0,0] neg_lo:[1,0,0] neg_hi:[1,0,0]
	v_cvt_pk_bf16_f32 v32, v32, v33
	v_pk_mul_f32 v[28:29], v[28:29], v[128:129]
	v_pk_fma_f32 v[58:59], v[56:57], v[58:59], s[34:35] op_sel_hi:[1,1,0]
	v_pk_mul_f32 v[30:31], v[30:31], v[128:129]
	v_pk_fma_f32 v[58:59], v[56:57], v[58:59], s[36:37] op_sel_hi:[1,1,0]
	v_mov_b32_e32 v127, v126
	v_pk_fma_f32 v[58:59], v[56:57], v[58:59], s[38:39] op_sel_hi:[1,1,0]
	v_pk_mul_f32 v[24:25], v[24:25], v[126:127]
	v_pk_fma_f32 v[58:59], v[56:57], v[58:59], s[40:41] op_sel_hi:[1,1,0]
	v_pk_mul_f32 v[26:27], v[26:27], v[126:127]
; __device__ __forceinline__ unsigned cvt_pk_bf16(float lo, float hi) { unsigned r; asm volatile("v_cvt_pk_bf16_f32 %0, %1, %2" : "=v"(r) : "v"(lo), "v"(hi)); return r; }
;     static __device__ __forceinline__ void unpk4(const u32x2 w, float (&o)[4]) { o[0] = bf_lo(w.x); o[1] = bf_hi(w.x); o[2] = bf_lo(w.y); o[3] = bf_hi(w.y); }
;     template <int N> static __device__ __forceinline__ u32x2 dpp_prev(const u32x2 pv, const u32x2 cur) { u32x2 r; r.x = dpp_prev1<N>(pv.x, cur.x); r.y = dpp_prev1<N>(pv.y, cur.y); return r; }
;     static __device__ __forceinline__ u32x2 finish2(const float (&g0)[4], const float (&g1)[4], const float (&g2)[4], const float (&w0)[4], const float (&w1)[4], const float (&w2)[4], const float (&bb)[4],
;                                                     const f32x4 v, float rs) {
;         float h[4];
; #pragma unroll
;         for (int j = 0; j < 4; j += 2) {
;             const f32x2 gc = (f32x2){bb[j] + w0[j] * g2[j] + w1[j] * g1[j] + w2[j] * g0[j], bb[j + 1] + w0[j + 1] * g2[j + 1] + w1[j + 1] * g1[j + 1] + w2[j + 1] * g0[j + 1]};
;             const f32x2 ge = gelu_pk(gc) * ((f32x2){v[j], v[j + 1]} * rs); h[j] = ge.x; h[j + 1] = ge.y; }
;         u32x2 w; w.x = cvt_pk_bf16(h[0], h[1]); w.y = cvt_pk_bf16(h[2], h[3]); return w;
;     }
;     __device__ __forceinline__ void operator()(const f32x4 (&acc)[2][2][4][2], const Unit& u, int wr, int wc, int fr, int fq) const {
;     ...
;                 for (int m = 0; m < 4; ++m) { const u32x4 cur = gq[m]; u32x4 hw;
; #pragma unroll
;                     for (int hv = 0; hv < 2; ++hv) { const u32x2 c2 = half2(cur, hv), p2 = half2(pv, hv);
;                         const u32x2 q1 = dpp_prev<1>(p2, c2), q2 = dpp_prev<2>(p2, c2);
;                         float g0[4], g1[4], g2[4]; unpk4(c2, g0); unpk4(q1, g1); unpk4(q2, g2);
;                         const u32x2 r = finish2(g0, g1, g2, w0[hv], w1[hv], w2[hv], bb[hv], acc[ai][bj][m][hv], rs8[ai][m]);
;                         if (hv == 0) { hw.x = r.x; hw.y = r.y; } else { hw.z = r.x; hw.w = r.y; } }
;                     *(u32x4*)(H + (size_t)(R0 + fr + 16 * m) * 2816 + col8) = hw;
;                     pv = cur; } }
	v_pk_fma_f32 v[58:59], v[56:57], v[58:59], s[42:43] op_sel_hi:[1,1,0]
	v_pk_mul_f32 v[20:21], v[20:21], v[126:127]
	v_pk_fma_f32 v[56:57], v[56:57], v[58:59], s[44:45] op_sel_hi:[1,1,0]
	v_lshlrev_b32_e32 v58, 16, v50
	v_pk_mul_f32 v[54:55], v[54:55], v[56:57]
	v_and_b32_e32 v59, 0xffff0000, v50
	v_pk_fma_f32 v[52:53], v[52:53], v[54:55], v[52:53]
	v_mov_b32_dpp v55, v102 row_ror:2 row_mask:0xf bank_mask:0xf bound_ctrl:1
	v_pk_mul_f32 v[34:35], v[34:35], v[52:53]
	v_mov_b32_dpp v57, v103 row_ror:2 row_mask:0xf bank_mask:0xf bound_ctrl:1
	v_mov_b32_dpp v55, v50 row_shr:2 row_mask:0xf bank_mask:0xf
	v_lshlrev_b32_e32 v54, 16, v55
	v_and_b32_e32 v55, 0xffff0000, v55
	v_cvt_pk_bf16_f32 v33, v34, v35
	v_lshlrev_b32_e32 v34, 16, v1
	v_and_b32_e32 v35, 0xffff0000, v1
	v_pk_fma_f32 v[54:55], v[64:65], v[54:55], v[80:81]
	v_mov_b32_dpp v53, v103 row_ror:1 row_mask:0xf bank_mask:0xf bound_ctrl:1
	v_pk_fma_f32 v[34:35], v[72:73], v[34:35], v[54:55]
	v_mov_b32_dpp v57, v51 row_shr:2 row_mask:0xf bank_mask:0xf
	v_pk_fma_f32 v[34:35], v[76:77], v[58:59], v[34:35]
	v_mov_b32_dpp v53, v51 row_shr:1 row_mask:0xf bank_mask:0xf
	v_pk_mul_f32 v[54:55], v[34:35], s[26:27] op_sel_hi:[1,0]
	v_lshlrev_b32_e32 v56, 16, v57
	v_med3_f32 v54, v54, s71, v224
	v_med3_f32 v55, v55, s71, v224
	v_pk_mul_f32 v[58:59], v[54:55], v[54:55]
	v_and_b32_e32 v57, 0xffff0000, v57
	v_pk_fma_f32 v[62:63], v[58:59], s[28:29], v[2:3] op_sel_hi:[1,0,0] neg_lo:[1,0,0] neg_hi:[1,0,0]
	v_pk_mul_f32 v[34:35], v[34:35], 0.5 op_sel_hi:[1,0]
	v_pk_fma_f32 v[62:63], v[58:59], v[62:63], s[34:35] op_sel_hi:[1,1,0]
	v_lshlrev_b32_e32 v52, 16, v53
	v_pk_fma_f32 v[62:63], v[58:59], v[62:63], s[36:37] op_sel_hi:[1,1,0]
	v_and_b32_e32 v53, 0xffff0000, v53
	v_pk_fma_f32 v[62:63], v[58:59], v[62:63], s[38:39] op_sel_hi:[1,1,0]
	v_mov_b32_dpp v1, v48 row_ror:1 row_mask:0xf bank_mask:0xf bound_ctrl:1
	v_pk_fma_f32 v[62:63], v[58:59], v[62:63], s[40:41] op_sel_hi:[1,1,0]
	v_pk_mul_f32 v[22:23], v[22:23], v[126:127]
	v_pk_fma_f32 v[62:63], v[58:59], v[62:63], s[42:43] op_sel_hi:[1,1,0]
	v_mov_b32_dpp v1, v44 row_shr:1 row_mask:0xf bank_mask:0xf
	v_pk_fma_f32 v[58:59], v[58:59], v[62:63], s[44:45] op_sel_hi:[1,1,0]
	v_mov_b32_e32 v125, v124
	v_pk_mul_f32 v[54:55], v[54:55], v[58:59]
	v_pk_mul_f32 v[16:17], v[16:17], v[124:125]
	v_pk_fma_f32 v[34:35], v[34:35], v[54:55], v[34:35]
	v_pk_fma_f32 v[54:55], v[66:67], v[56:57], v[82:83]
	v_pk_mul_f32 v[28:29], v[28:29], v[34:35]
	v_lshlrev_b32_e32 v34, 16, v51
	v_and_b32_e32 v35, 0xffff0000, v51
	v_pk_fma_f32 v[52:53], v[74:75], v[52:53], v[54:55]
	v_pk_mul_f32 v[18:19], v[18:19], v[124:125]
	v_pk_fma_f32 v[34:35], v[78:79], v[34:35], v[52:53]
	v_pk_mul_f32 v[12:13], v[12:13], v[124:125]
	v_pk_mul_f32 v[52:53], v[34:35], s[26:27] op_sel_hi:[1,0]
	v_pk_mul_f32 v[34:35], v[34:35], 0.5 op_sel_hi:[1,0]
	v_med3_f32 v52, v52, s71, v224
	v_med3_f32 v53, v53, s71, v224
	v_pk_mul_f32 v[54:55], v[52:53], v[52:53]
	v_pk_mul_f32 v[14:15], v[14:15], v[124:125]
	v_pk_fma_f32 v[56:57], v[54:55], s[28:29], v[2:3] op_sel_hi:[1,0,0] neg_lo:[1,0,0] neg_hi:[1,0,0]
	v_mov_b32_e32 v123, v122
	v_pk_fma_f32 v[56:57], v[54:55], v[56:57], s[34:35] op_sel_hi:[1,1,0]
	v_pk_mul_f32 v[8:9], v[8:9], v[122:123]
	v_pk_fma_f32 v[56:57], v[54:55], v[56:57], s[36:37] op_sel_hi:[1,1,0]
	v_pk_mul_f32 v[10:11], v[10:11], v[122:123]
	v_pk_fma_f32 v[56:57], v[54:55], v[56:57], s[38:39] op_sel_hi:[1,1,0]
	v_pk_mul_f32 v[4:5], v[4:5], v[122:123]
	v_pk_fma_f32 v[56:57], v[54:55], v[56:57], s[40:41] op_sel_hi:[1,1,0]
	v_pk_mul_f32 v[6:7], v[6:7], v[122:123]
	v_pk_fma_f32 v[56:57], v[54:55], v[56:57], s[42:43] op_sel_hi:[1,1,0]
	s_nop 0
	v_pk_fma_f32 v[54:55], v[54:55], v[56:57], s[44:45] op_sel_hi:[1,1,0]
	s_nop 0
	v_pk_mul_f32 v[52:53], v[52:53], v[54:55]
	s_nop 0
	v_pk_fma_f32 v[34:35], v[34:35], v[52:53], v[34:35]
	s_nop 0
	v_pk_mul_f32 v[30:31], v[30:31], v[34:35]
	v_cvt_pk_bf16_f32 v34, v28, v29
	v_lshl_add_u64 v[28:29], v[168:169], 0, v[60:61]
	v_cvt_pk_bf16_f32 v35, v30, v31
	global_store_dwordx4 v[28:29], v[32:35], off nt
	v_lshlrev_b32_e32 v28, 16, v1
	v_and_b32_e32 v29, 0xffff0000, v1
	v_mov_b32_dpp v33, v48 row_ror:2 row_mask:0xf bank_mask:0xf bound_ctrl:1
	v_mov_b32_dpp v31, v49 row_ror:1 row_mask:0xf bank_mask:0xf bound_ctrl:1
	v_mov_b32_dpp v35, v49 row_ror:2 row_mask:0xf bank_mask:0xf bound_ctrl:1
	v_mov_b32_dpp v33, v44 row_shr:2 row_mask:0xf bank_mask:0xf
	v_lshlrev_b32_e32 v32, 16, v33
	v_and_b32_e32 v33, 0xffff0000, v33
	v_pk_fma_f32 v[32:33], v[84:85], v[32:33], v[96:97]
	v_lshlrev_b32_e32 v48, 16, v44
	v_and_b32_e32 v49, 0xffff0000, v44
	v_pk_fma_f32 v[28:29], v[88:89], v[28:29], v[32:33]
	v_mov_b32_dpp v35, v45 row_shr:2 row_mask:0xf bank_mask:0xf
	v_pk_fma_f32 v[28:29], v[92:93], v[48:49], v[28:29]
	v_mov_b32_dpp v31, v45 row_shr:1 row_mask:0xf bank_mask:0xf
	v_pk_mul_f32 v[32:33], v[28:29], s[26:27] op_sel_hi:[1,0]
	v_lshlrev_b32_e32 v34, 16, v35
	v_med3_f32 v32, v32, s71, v224
	v_med3_f32 v33, v33, s71, v224
	v_pk_mul_f32 v[48:49], v[32:33], v[32:33]
	v_and_b32_e32 v35, 0xffff0000, v35
	v_pk_fma_f32 v[52:53], v[48:49], s[28:29], v[2:3] op_sel_hi:[1,0,0] neg_lo:[1,0,0] neg_hi:[1,0,0]
	v_pk_mul_f32 v[28:29], v[28:29], 0.5 op_sel_hi:[1,0]
	v_pk_fma_f32 v[52:53], v[48:49], v[52:53], s[34:35] op_sel_hi:[1,1,0]
	v_lshlrev_b32_e32 v30, 16, v31
	v_pk_fma_f32 v[52:53], v[48:49], v[52:53], s[36:37] op_sel_hi:[1,1,0]
	v_and_b32_e32 v31, 0xffff0000, v31
	v_pk_fma_f32 v[52:53], v[48:49], v[52:53], s[38:39] op_sel_hi:[1,1,0]
	v_mov_b32_dpp v1, v50 row_ror:1 row_mask:0xf bank_mask:0xf bound_ctrl:1
	v_pk_fma_f32 v[52:53], v[48:49], v[52:53], s[40:41] op_sel_hi:[1,1,0]
	s_nop 0
; __device__ __forceinline__ unsigned cvt_pk_bf16(float lo, float hi) { unsigned r; asm volatile("v_cvt_pk_bf16_f32 %0, %1, %2" : "=v"(r) : "v"(lo), "v"(hi)); return r; }
;     static __device__ __forceinline__ void unpk4(const u32x2 w, float (&o)[4]) { o[0] = bf_lo(w.x); o[1] = bf_hi(w.x); o[2] = bf_lo(w.y); o[3] = bf_hi(w.y); }
;     template <int N> static __device__ __forceinline__ u32x2 dpp_prev(const u32x2 pv, const u32x2 cur) { u32x2 r; r.x = dpp_prev1<N>(pv.x, cur.x); r.y = dpp_prev1<N>(pv.y, cur.y); return r; }
;     static __device__ __forceinline__ u32x2 finish2(const float (&g0)[4], const float (&g1)[4], const float (&g2)[4], const float (&w0)[4], const float (&w1)[4], const float (&w2)[4], const float (&bb)[4],
;                                                     const f32x4 v, float rs) {
;         float h[4];
; #pragma unroll
;         for (int j = 0; j < 4; j += 2) {
;             const f32x2 gc = (f32x2){bb[j] + w0[j] * g2[j] + w1[j] * g1[j] + w2[j] * g0[j], bb[j + 1] + w0[j + 1] * g2[j + 1] + w1[j + 1] * g1[j + 1] + w2[j + 1] * g0[j + 1]};
;             const f32x2 ge = gelu_pk(gc) * ((f32x2){v[j], v[j + 1]} * rs); h[j] = ge.x; h[j + 1] = ge.y; }
;         u32x2 w; w.x = cvt_pk_bf16(h[0], h[1]); w.y = cvt_pk_bf16(h[2], h[3]); return w;
;     }
;     __device__ __forceinline__ void operator()(const f32x4 (&acc)[2][2][4][2], const Unit& u, int wr, int wc, int fr, int fq) const {
;     ...
;                 for (int m = 0; m < 4; ++m) { const u32x4 cur = gq[m]; u32x4 hw;
; #pragma unroll
;                     for (int hv = 0; hv < 2; ++hv) { const u32x2 c2 = half2(cur, hv), p2 = half2(pv, hv);
;                         const u32x2 q1 = dpp_prev<1>(p2, c2), q2 = dpp_prev<2>(p2, c2);
;                         float g0[4], g1[4], g2[4]; unpk4(c2, g0); unpk4(q1, g1); unpk4(q2, g2);
;                         const u32x2 r = finish2(g0, g1, g2, w0[hv], w1[hv], w2[hv], bb[hv], acc[ai][bj][m][hv], rs8[ai][m]);
;                         if (hv == 0) { hw.x = r.x; hw.y = r.y; } else { hw.z = r.x; hw.w = r.y; } }
;                     *(u32x4*)(H + (size_t)(R0 + fr + 16 * m) * 2816 + col8) = hw;
;                     pv = cur; } }
	v_pk_fma_f32 v[52:53], v[48:49], v[52:53], s[42:43] op_sel_hi:[1,1,0]
	v_mov_b32_dpp v1, v46 row_shr:1 row_mask:0xf bank_mask:0xf
	v_pk_fma_f32 v[48:49], v[48:49], v[52:53], s[44:45] op_sel_hi:[1,1,0]
	s_nop 0
	v_pk_mul_f32 v[32:33], v[32:33], v[48:49]
	s_nop 0
	v_pk_fma_f32 v[28:29], v[28:29], v[32:33], v[28:29]
	v_pk_fma_f32 v[32:33], v[86:87], v[34:35], v[98:99]
	v_pk_mul_f32 v[24:25], v[24:25], v[28:29]
	v_lshlrev_b32_e32 v28, 16, v45
	v_and_b32_e32 v29, 0xffff0000, v45
	v_pk_fma_f32 v[30:31], v[90:91], v[30:31], v[32:33]
	v_cvt_pk_bf16_f32 v24, v24, v25
	s_nop 0
	v_pk_fma_f32 v[28:29], v[94:95], v[28:29], v[30:31]
	s_nop 0
	v_pk_mul_f32 v[30:31], v[28:29], s[26:27] op_sel_hi:[1,0]
	v_pk_mul_f32 v[28:29], v[28:29], 0.5 op_sel_hi:[1,0]
	v_med3_f32 v30, v30, s71, v224
	v_med3_f32 v31, v31, s71, v224
	v_pk_mul_f32 v[32:33], v[30:31], v[30:31]
	s_nop 0
	v_pk_fma_f32 v[34:35], v[32:33], s[28:29], v[2:3] op_sel_hi:[1,0,0] neg_lo:[1,0,0] neg_hi:[1,0,0]
	s_nop 0
	v_pk_fma_f32 v[34:35], v[32:33], v[34:35], s[34:35] op_sel_hi:[1,1,0]
	s_nop 0
	v_pk_fma_f32 v[34:35], v[32:33], v[34:35], s[36:37] op_sel_hi:[1,1,0]
	s_nop 0
	v_pk_fma_f32 v[34:35], v[32:33], v[34:35], s[38:39] op_sel_hi:[1,1,0]
	s_nop 0
	v_pk_fma_f32 v[34:35], v[32:33], v[34:35], s[40:41] op_sel_hi:[1,1,0]
	s_nop 0
	v_pk_fma_f32 v[34:35], v[32:33], v[34:35], s[42:43] op_sel_hi:[1,1,0]
	s_nop 0
	v_pk_fma_f32 v[32:33], v[32:33], v[34:35], s[44:45] op_sel_hi:[1,1,0]
	v_lshlrev_b32_e32 v34, 16, v46
	v_pk_mul_f32 v[30:31], v[30:31], v[32:33]
	v_and_b32_e32 v35, 0xffff0000, v46
	v_pk_fma_f32 v[28:29], v[28:29], v[30:31], v[28:29]
	v_mov_b32_dpp v31, v50 row_ror:2 row_mask:0xf bank_mask:0xf bound_ctrl:1
	v_pk_mul_f32 v[26:27], v[26:27], v[28:29]
	v_mov_b32_dpp v33, v51 row_ror:2 row_mask:0xf bank_mask:0xf bound_ctrl:1
	v_mov_b32_dpp v31, v46 row_shr:2 row_mask:0xf bank_mask:0xf
	v_lshlrev_b32_e32 v30, 16, v31
	v_and_b32_e32 v31, 0xffff0000, v31
	v_cvt_pk_bf16_f32 v25, v26, v27
	v_lshlrev_b32_e32 v26, 16, v1
	v_and_b32_e32 v27, 0xffff0000, v1
	v_pk_fma_f32 v[30:31], v[64:65], v[30:31], v[80:81]
	v_mov_b32_dpp v29, v51 row_ror:1 row_mask:0xf bank_mask:0xf bound_ctrl:1
	v_pk_fma_f32 v[26:27], v[72:73], v[26:27], v[30:31]
	v_mov_b32_dpp v33, v47 row_shr:2 row_mask:0xf bank_mask:0xf
	v_pk_fma_f32 v[26:27], v[76:77], v[34:35], v[26:27]
	v_mov_b32_dpp v29, v47 row_shr:1 row_mask:0xf bank_mask:0xf
	v_pk_mul_f32 v[30:31], v[26:27], s[26:27] op_sel_hi:[1,0]
	v_lshlrev_b32_e32 v32, 16, v33
	v_med3_f32 v30, v30, s71, v224
	v_med3_f32 v31, v31, s71, v224
	v_pk_mul_f32 v[34:35], v[30:31], v[30:31]
	v_and_b32_e32 v33, 0xffff0000, v33
	v_pk_fma_f32 v[48:49], v[34:35], s[28:29], v[2:3] op_sel_hi:[1,0,0] neg_lo:[1,0,0] neg_hi:[1,0,0]
	v_pk_mul_f32 v[26:27], v[26:27], 0.5 op_sel_hi:[1,0]
	v_pk_fma_f32 v[48:49], v[34:35], v[48:49], s[34:35] op_sel_hi:[1,1,0]
	v_lshlrev_b32_e32 v28, 16, v29
	v_pk_fma_f32 v[48:49], v[34:35], v[48:49], s[36:37] op_sel_hi:[1,1,0]
	v_and_b32_e32 v29, 0xffff0000, v29
	v_pk_fma_f32 v[48:49], v[34:35], v[48:49], s[38:39] op_sel_hi:[1,1,0]
	v_mov_b32_dpp v1, v44 row_ror:1 row_mask:0xf bank_mask:0xf bound_ctrl:1
	v_pk_fma_f32 v[48:49], v[34:35], v[48:49], s[40:41] op_sel_hi:[1,1,0]
	s_nop 0
	v_pk_fma_f32 v[48:49], v[34:35], v[48:49], s[42:43] op_sel_hi:[1,1,0]
	v_mov_b32_dpp v1, v40 row_shr:1 row_mask:0xf bank_mask:0xf
	v_pk_fma_f32 v[34:35], v[34:35], v[48:49], s[44:45] op_sel_hi:[1,1,0]
	s_nop 0
	v_pk_mul_f32 v[30:31], v[30:31], v[34:35]
	s_nop 0
	v_pk_fma_f32 v[26:27], v[26:27], v[30:31], v[26:27]
	v_pk_fma_f32 v[30:31], v[66:67], v[32:33], v[82:83]
	v_pk_mul_f32 v[20:21], v[20:21], v[26:27]
	v_lshlrev_b32_e32 v26, 16, v47
	v_and_b32_e32 v27, 0xffff0000, v47
	v_pk_fma_f32 v[28:29], v[74:75], v[28:29], v[30:31]
	s_nop 0
	v_pk_fma_f32 v[26:27], v[78:79], v[26:27], v[28:29]
	s_nop 0
	v_pk_mul_f32 v[28:29], v[26:27], s[26:27] op_sel_hi:[1,0]
	v_pk_mul_f32 v[26:27], v[26:27], 0.5 op_sel_hi:[1,0]
	v_med3_f32 v28, v28, s71, v224
	v_med3_f32 v29, v29, s71, v224
	v_pk_mul_f32 v[30:31], v[28:29], v[28:29]
	s_nop 0
	v_pk_fma_f32 v[32:33], v[30:31], s[28:29], v[2:3] op_sel_hi:[1,0,0] neg_lo:[1,0,0] neg_hi:[1,0,0]
	s_nop 0
	v_pk_fma_f32 v[32:33], v[30:31], v[32:33], s[34:35] op_sel_hi:[1,1,0]
	s_nop 0
	v_pk_fma_f32 v[32:33], v[30:31], v[32:33], s[36:37] op_sel_hi:[1,1,0]
	s_nop 0
	v_pk_fma_f32 v[32:33], v[30:31], v[32:33], s[38:39] op_sel_hi:[1,1,0]
	s_nop 0
	v_pk_fma_f32 v[32:33], v[30:31], v[32:33], s[40:41] op_sel_hi:[1,1,0]
	s_nop 0
	v_pk_fma_f32 v[32:33], v[30:31], v[32:33], s[42:43] op_sel_hi:[1,1,0]
	s_nop 0
	v_pk_fma_f32 v[30:31], v[30:31], v[32:33], s[44:45] op_sel_hi:[1,1,0]
	s_nop 0
	v_pk_mul_f32 v[28:29], v[28:29], v[30:31]
	s_nop 0
	v_pk_fma_f32 v[26:27], v[26:27], v[28:29], v[26:27]
	v_lshlrev_b32_e32 v28, 16, v40
	v_pk_mul_f32 v[22:23], v[22:23], v[26:27]
	v_cvt_pk_bf16_f32 v26, v20, v21
	v_lshl_add_u64 v[20:21], v[170:171], 0, v[60:61]
	v_cvt_pk_bf16_f32 v27, v22, v23
	global_store_dwordx4 v[20:21], v[24:27], off nt
	v_lshlrev_b32_e32 v20, 16, v1
	v_and_b32_e32 v21, 0xffff0000, v1
	v_mov_b32_dpp v25, v44 row_ror:2 row_mask:0xf bank_mask:0xf bound_ctrl:1
	v_and_b32_e32 v29, 0xffff0000, v40
	v_mov_b32_dpp v27, v45 row_ror:2 row_mask:0xf bank_mask:0xf bound_ctrl:1
	v_mov_b32_dpp v25, v40 row_shr:2 row_mask:0xf bank_mask:0xf
	v_lshlrev_b32_e32 v24, 16, v25
	v_and_b32_e32 v25, 0xffff0000, v25
	v_pk_fma_f32 v[24:25], v[84:85], v[24:25], v[96:97]
	v_mov_b32_dpp v23, v45 row_ror:1 row_mask:0xf bank_mask:0xf bound_ctrl:1
	v_pk_fma_f32 v[20:21], v[88:89], v[20:21], v[24:25]
	v_mov_b32_dpp v27, v41 row_shr:2 row_mask:0xf bank_mask:0xf
	v_pk_fma_f32 v[20:21], v[92:93], v[28:29], v[20:21]
; __device__ __forceinline__ unsigned cvt_pk_bf16(float lo, float hi) { unsigned r; asm volatile("v_cvt_pk_bf16_f32 %0, %1, %2" : "=v"(r) : "v"(lo), "v"(hi)); return r; }
;     static __device__ __forceinline__ void unpk4(const u32x2 w, float (&o)[4]) { o[0] = bf_lo(w.x); o[1] = bf_hi(w.x); o[2] = bf_lo(w.y); o[3] = bf_hi(w.y); }
;     template <int N> static __device__ __forceinline__ u32x2 dpp_prev(const u32x2 pv, const u32x2 cur) { u32x2 r; r.x = dpp_prev1<N>(pv.x, cur.x); r.y = dpp_prev1<N>(pv.y, cur.y); return r; }
;     static __device__ __forceinline__ u32x2 finish2(const float (&g0)[4], const float (&g1)[4], const float (&g2)[4], const float (&w0)[4], const float (&w1)[4], const float (&w2)[4], const float (&bb)[4],
;                                                     const f32x4 v, float rs) {
;         float h[4];
; #pragma unroll
;         for (int j = 0; j < 4; j += 2) {
;             const f32x2 gc = (f32x2){bb[j] + w0[j] * g2[j] + w1[j] * g1[j] + w2[j] * g0[j], bb[j + 1] + w0[j + 1] * g2[j + 1] + w1[j + 1] * g1[j + 1] + w2[j + 1] * g0[j + 1]};
;             const f32x2 ge = gelu_pk(gc) * ((f32x2){v[j], v[j + 1]} * rs); h[j] = ge.x; h[j + 1] = ge.y; }
;         u32x2 w; w.x = cvt_pk_bf16(h[0], h[1]); w.y = cvt_pk_bf16(h[2], h[3]); return w;
;     }
;     __device__ __forceinline__ void operator()(const f32x4 (&acc)[2][2][4][2], const Unit& u, int wr, int wc, int fr, int fq) const {
;     ...
;                 for (int m = 0; m < 4; ++m) { const u32x4 cur = gq[m]; u32x4 hw;
; #pragma unroll
;                     for (int hv = 0; hv < 2; ++hv) { const u32x2 c2 = half2(cur, hv), p2 = half2(pv, hv);
;                         const u32x2 q1 = dpp_prev<1>(p2, c2), q2 = dpp_prev<2>(p2, c2);
;                         float g0[4], g1[4], g2[4]; unpk4(c2, g0); unpk4(q1, g1); unpk4(q2, g2);
;                         const u32x2 r = finish2(g0, g1, g2, w0[hv], w1[hv], w2[hv], bb[hv], acc[ai][bj][m][hv], rs8[ai][m]);
;                         if (hv == 0) { hw.x = r.x; hw.y = r.y; } else { hw.z = r.x; hw.w = r.y; } }
	v_mov_b32_dpp v23, v41 row_shr:1 row_mask:0xf bank_mask:0xf
	v_pk_mul_f32 v[24:25], v[20:21], s[26:27] op_sel_hi:[1,0]
	v_lshlrev_b32_e32 v26, 16, v27
	v_med3_f32 v24, v24, s71, v224
	v_med3_f32 v25, v25, s71, v224
	v_pk_mul_f32 v[28:29], v[24:25], v[24:25]
	v_and_b32_e32 v27, 0xffff0000, v27
	v_pk_fma_f32 v[30:31], v[28:29], s[28:29], v[2:3] op_sel_hi:[1,0,0] neg_lo:[1,0,0] neg_hi:[1,0,0]
	v_pk_mul_f32 v[20:21], v[20:21], 0.5 op_sel_hi:[1,0]
	v_pk_fma_f32 v[30:31], v[28:29], v[30:31], s[34:35] op_sel_hi:[1,1,0]
	v_lshlrev_b32_e32 v22, 16, v23
	v_pk_fma_f32 v[30:31], v[28:29], v[30:31], s[36:37] op_sel_hi:[1,1,0]
	v_and_b32_e32 v23, 0xffff0000, v23
	v_pk_fma_f32 v[30:31], v[28:29], v[30:31], s[38:39] op_sel_hi:[1,1,0]
	v_mov_b32_dpp v1, v46 row_ror:1 row_mask:0xf bank_mask:0xf bound_ctrl:1
	v_pk_fma_f32 v[30:31], v[28:29], v[30:31], s[40:41] op_sel_hi:[1,1,0]
	s_nop 0
	v_pk_fma_f32 v[30:31], v[28:29], v[30:31], s[42:43] op_sel_hi:[1,1,0]
	v_mov_b32_dpp v1, v42 row_shr:1 row_mask:0xf bank_mask:0xf
	v_pk_fma_f32 v[28:29], v[28:29], v[30:31], s[44:45] op_sel_hi:[1,1,0]
	s_nop 0
	v_pk_mul_f32 v[24:25], v[24:25], v[28:29]
	s_nop 0
	v_pk_fma_f32 v[20:21], v[20:21], v[24:25], v[20:21]
	v_pk_fma_f32 v[24:25], v[86:87], v[26:27], v[98:99]
	v_pk_mul_f32 v[16:17], v[16:17], v[20:21]
	v_lshlrev_b32_e32 v20, 16, v41
	v_and_b32_e32 v21, 0xffff0000, v41
	v_pk_fma_f32 v[22:23], v[90:91], v[22:23], v[24:25]
	v_cvt_pk_bf16_f32 v16, v16, v17
	s_nop 0
	v_pk_fma_f32 v[20:21], v[94:95], v[20:21], v[22:23]
	s_nop 0
	v_pk_mul_f32 v[22:23], v[20:21], s[26:27] op_sel_hi:[1,0]
	v_pk_mul_f32 v[20:21], v[20:21], 0.5 op_sel_hi:[1,0]
	v_med3_f32 v22, v22, s71, v224
	v_med3_f32 v23, v23, s71, v224
	v_pk_mul_f32 v[24:25], v[22:23], v[22:23]
	s_nop 0
	v_pk_fma_f32 v[26:27], v[24:25], s[28:29], v[2:3] op_sel_hi:[1,0,0] neg_lo:[1,0,0] neg_hi:[1,0,0]
	s_nop 0
	v_pk_fma_f32 v[26:27], v[24:25], v[26:27], s[34:35] op_sel_hi:[1,1,0]
	s_nop 0
	v_pk_fma_f32 v[26:27], v[24:25], v[26:27], s[36:37] op_sel_hi:[1,1,0]
	s_nop 0
	v_pk_fma_f32 v[26:27], v[24:25], v[26:27], s[38:39] op_sel_hi:[1,1,0]
	s_nop 0
	v_pk_fma_f32 v[26:27], v[24:25], v[26:27], s[40:41] op_sel_hi:[1,1,0]
	s_nop 0
	v_pk_fma_f32 v[26:27], v[24:25], v[26:27], s[42:43] op_sel_hi:[1,1,0]
	s_nop 0
	v_pk_fma_f32 v[24:25], v[24:25], v[26:27], s[44:45] op_sel_hi:[1,1,0]
	v_lshlrev_b32_e32 v26, 16, v42
	v_pk_mul_f32 v[22:23], v[22:23], v[24:25]
	v_and_b32_e32 v27, 0xffff0000, v42
	v_pk_fma_f32 v[20:21], v[20:21], v[22:23], v[20:21]
	v_mov_b32_dpp v23, v46 row_ror:2 row_mask:0xf bank_mask:0xf bound_ctrl:1
	v_pk_mul_f32 v[18:19], v[18:19], v[20:21]
	v_mov_b32_dpp v25, v47 row_ror:2 row_mask:0xf bank_mask:0xf bound_ctrl:1
	v_mov_b32_dpp v23, v42 row_shr:2 row_mask:0xf bank_mask:0xf
	v_lshlrev_b32_e32 v22, 16, v23
	v_and_b32_e32 v23, 0xffff0000, v23
	v_cvt_pk_bf16_f32 v17, v18, v19
	v_lshlrev_b32_e32 v18, 16, v1
	v_and_b32_e32 v19, 0xffff0000, v1
	v_pk_fma_f32 v[22:23], v[64:65], v[22:23], v[80:81]
	v_mov_b32_dpp v21, v47 row_ror:1 row_mask:0xf bank_mask:0xf bound_ctrl:1
	v_pk_fma_f32 v[18:19], v[72:73], v[18:19], v[22:23]
	v_mov_b32_dpp v25, v43 row_shr:2 row_mask:0xf bank_mask:0xf
	v_pk_fma_f32 v[18:19], v[76:77], v[26:27], v[18:19]
	v_mov_b32_dpp v21, v43 row_shr:1 row_mask:0xf bank_mask:0xf
	v_pk_mul_f32 v[22:23], v[18:19], s[26:27] op_sel_hi:[1,0]
	v_lshlrev_b32_e32 v24, 16, v25
	v_med3_f32 v22, v22, s71, v224
	v_med3_f32 v23, v23, s71, v224
	v_pk_mul_f32 v[26:27], v[22:23], v[22:23]
	v_and_b32_e32 v25, 0xffff0000, v25
	v_pk_fma_f32 v[28:29], v[26:27], s[28:29], v[2:3] op_sel_hi:[1,0,0] neg_lo:[1,0,0] neg_hi:[1,0,0]
	v_pk_mul_f32 v[18:19], v[18:19], 0.5 op_sel_hi:[1,0]
	v_pk_fma_f32 v[28:29], v[26:27], v[28:29], s[34:35] op_sel_hi:[1,1,0]
	v_lshlrev_b32_e32 v20, 16, v21
	v_pk_fma_f32 v[28:29], v[26:27], v[28:29], s[36:37] op_sel_hi:[1,1,0]
	v_and_b32_e32 v21, 0xffff0000, v21
	v_pk_fma_f32 v[28:29], v[26:27], v[28:29], s[38:39] op_sel_hi:[1,1,0]
	v_mov_b32_dpp v1, v40 row_ror:1 row_mask:0xf bank_mask:0xf bound_ctrl:1
	v_pk_fma_f32 v[28:29], v[26:27], v[28:29], s[40:41] op_sel_hi:[1,1,0]
	s_nop 0
	v_pk_fma_f32 v[28:29], v[26:27], v[28:29], s[42:43] op_sel_hi:[1,1,0]
	v_mov_b32_dpp v1, v36 row_shr:1 row_mask:0xf bank_mask:0xf
	v_pk_fma_f32 v[26:27], v[26:27], v[28:29], s[44:45] op_sel_hi:[1,1,0]
	s_nop 0
	v_pk_mul_f32 v[22:23], v[22:23], v[26:27]
	s_nop 0
	v_pk_fma_f32 v[18:19], v[18:19], v[22:23], v[18:19]
	v_pk_fma_f32 v[22:23], v[66:67], v[24:25], v[82:83]
	v_pk_mul_f32 v[12:13], v[12:13], v[18:19]
	v_lshlrev_b32_e32 v18, 16, v43
	v_and_b32_e32 v19, 0xffff0000, v43
	v_pk_fma_f32 v[20:21], v[74:75], v[20:21], v[22:23]
	s_nop 0
	v_pk_fma_f32 v[18:19], v[78:79], v[18:19], v[20:21]
	s_nop 0
	v_pk_mul_f32 v[20:21], v[18:19], s[26:27] op_sel_hi:[1,0]
	v_pk_mul_f32 v[18:19], v[18:19], 0.5 op_sel_hi:[1,0]
	v_med3_f32 v20, v20, s71, v224
	v_med3_f32 v21, v21, s71, v224
	v_pk_mul_f32 v[22:23], v[20:21], v[20:21]
	s_nop 0
	v_pk_fma_f32 v[24:25], v[22:23], s[28:29], v[2:3] op_sel_hi:[1,0,0] neg_lo:[1,0,0] neg_hi:[1,0,0]
	s_nop 0
	v_pk_fma_f32 v[24:25], v[22:23], v[24:25], s[34:35] op_sel_hi:[1,1,0]
	s_nop 0
	v_pk_fma_f32 v[24:25], v[22:23], v[24:25], s[36:37] op_sel_hi:[1,1,0]
	s_nop 0
	v_pk_fma_f32 v[24:25], v[22:23], v[24:25], s[38:39] op_sel_hi:[1,1,0]
	s_nop 0
	v_pk_fma_f32 v[24:25], v[22:23], v[24:25], s[40:41] op_sel_hi:[1,1,0]
	s_nop 0
	v_pk_fma_f32 v[24:25], v[22:23], v[24:25], s[42:43] op_sel_hi:[1,1,0]
	s_nop 0
	v_pk_fma_f32 v[22:23], v[22:23], v[24:25], s[44:45] op_sel_hi:[1,1,0]
	s_nop 0
	v_pk_mul_f32 v[20:21], v[20:21], v[22:23]
	s_nop 0
	v_pk_fma_f32 v[18:19], v[18:19], v[20:21], v[18:19]
	v_lshlrev_b32_e32 v20, 16, v36
; __device__ __forceinline__ unsigned cvt_pk_bf16(float lo, float hi) { unsigned r; asm volatile("v_cvt_pk_bf16_f32 %0, %1, %2" : "=v"(r) : "v"(lo), "v"(hi)); return r; }
;     static __device__ __forceinline__ void unpk4(const u32x2 w, float (&o)[4]) { o[0] = bf_lo(w.x); o[1] = bf_hi(w.x); o[2] = bf_lo(w.y); o[3] = bf_hi(w.y); }
;     template <int N> static __device__ __forceinline__ u32x2 dpp_prev(const u32x2 pv, const u32x2 cur) { u32x2 r; r.x = dpp_prev1<N>(pv.x, cur.x); r.y = dpp_prev1<N>(pv.y, cur.y); return r; }
;     static __device__ __forceinline__ u32x2 finish2(const float (&g0)[4], const float (&g1)[4], const float (&g2)[4], const float (&w0)[4], const float (&w1)[4], const float (&w2)[4], const float (&bb)[4],
;                                                     const f32x4 v, float rs) {
;         float h[4];
; #pragma unroll
;         for (int j = 0; j < 4; j += 2) {
;             const f32x2 gc = (f32x2){bb[j] + w0[j] * g2[j] + w1[j] * g1[j] + w2[j] * g0[j], bb[j + 1] + w0[j + 1] * g2[j + 1] + w1[j + 1] * g1[j + 1] + w2[j + 1] * g0[j + 1]};
;             const f32x2 ge = gelu_pk(gc) * ((f32x2){v[j], v[j + 1]} * rs); h[j] = ge.x; h[j + 1] = ge.y; }
;         u32x2 w; w.x = cvt_pk_bf16(h[0], h[1]); w.y = cvt_pk_bf16(h[2], h[3]); return w;
;     }
;     __device__ __forceinline__ void operator()(const f32x4 (&acc)[2][2][4][2], const Unit& u, int wr, int wc, int fr, int fq) const {
;     ...
;                 for (int m = 0; m < 4; ++m) { const u32x4 cur = gq[m]; u32x4 hw;
; #pragma unroll
;                     for (int hv = 0; hv < 2; ++hv) { const u32x2 c2 = half2(cur, hv), p2 = half2(pv, hv);
;                         const u32x2 q1 = dpp_prev<1>(p2, c2), q2 = dpp_prev<2>(p2, c2);
;                         float g0[4], g1[4], g2[4]; unpk4(c2, g0); unpk4(q1, g1); unpk4(q2, g2);
;                         const u32x2 r = finish2(g0, g1, g2, w0[hv], w1[hv], w2[hv], bb[hv], acc[ai][bj][m][hv], rs8[ai][m]);
;                         if (hv == 0) { hw.x = r.x; hw.y = r.y; } else { hw.z = r.x; hw.w = r.y; } }
;                     *(u32x4*)(H + (size_t)(R0 + fr + 16 * m) * 2816 + col8) = hw;
;                     pv = cur; } }
	v_pk_mul_f32 v[14:15], v[14:15], v[18:19]
	v_cvt_pk_bf16_f32 v18, v12, v13
	v_lshl_add_u64 v[12:13], v[174:175], 0, v[60:61]
	v_cvt_pk_bf16_f32 v19, v14, v15
	global_store_dwordx4 v[12:13], v[16:19], off nt
	v_lshlrev_b32_e32 v12, 16, v1
	v_and_b32_e32 v13, 0xffff0000, v1
	v_mov_b32_dpp v17, v40 row_ror:2 row_mask:0xf bank_mask:0xf bound_ctrl:1
	v_and_b32_e32 v21, 0xffff0000, v36
	v_mov_b32_dpp v19, v41 row_ror:2 row_mask:0xf bank_mask:0xf bound_ctrl:1
	v_mov_b32_dpp v17, v36 row_shr:2 row_mask:0xf bank_mask:0xf
	v_lshlrev_b32_e32 v16, 16, v17
	v_and_b32_e32 v17, 0xffff0000, v17
	v_pk_fma_f32 v[16:17], v[84:85], v[16:17], v[96:97]
	v_mov_b32_dpp v15, v41 row_ror:1 row_mask:0xf bank_mask:0xf bound_ctrl:1
	v_pk_fma_f32 v[12:13], v[88:89], v[12:13], v[16:17]
	v_mov_b32_dpp v19, v37 row_shr:2 row_mask:0xf bank_mask:0xf
	v_pk_fma_f32 v[12:13], v[92:93], v[20:21], v[12:13]
	v_mov_b32_dpp v15, v37 row_shr:1 row_mask:0xf bank_mask:0xf
	v_pk_mul_f32 v[16:17], v[12:13], s[26:27] op_sel_hi:[1,0]
	v_lshlrev_b32_e32 v18, 16, v19
	v_med3_f32 v16, v16, s71, v224
	v_med3_f32 v17, v17, s71, v224
	v_pk_mul_f32 v[20:21], v[16:17], v[16:17]
	v_and_b32_e32 v19, 0xffff0000, v19
	v_pk_fma_f32 v[22:23], v[20:21], s[28:29], v[2:3] op_sel_hi:[1,0,0] neg_lo:[1,0,0] neg_hi:[1,0,0]
	v_pk_mul_f32 v[12:13], v[12:13], 0.5 op_sel_hi:[1,0]
	v_pk_fma_f32 v[22:23], v[20:21], v[22:23], s[34:35] op_sel_hi:[1,1,0]
	v_lshlrev_b32_e32 v14, 16, v15
	v_pk_fma_f32 v[22:23], v[20:21], v[22:23], s[36:37] op_sel_hi:[1,1,0]
	v_and_b32_e32 v15, 0xffff0000, v15
	v_pk_fma_f32 v[22:23], v[20:21], v[22:23], s[38:39] op_sel_hi:[1,1,0]
	v_mov_b32_dpp v1, v42 row_ror:1 row_mask:0xf bank_mask:0xf bound_ctrl:1
	v_pk_fma_f32 v[22:23], v[20:21], v[22:23], s[40:41] op_sel_hi:[1,1,0]
	s_nop 0
	v_pk_fma_f32 v[22:23], v[20:21], v[22:23], s[42:43] op_sel_hi:[1,1,0]
	v_mov_b32_dpp v1, v38 row_shr:1 row_mask:0xf bank_mask:0xf
	v_pk_fma_f32 v[20:21], v[20:21], v[22:23], s[44:45] op_sel_hi:[1,1,0]
	s_nop 0
	v_pk_mul_f32 v[16:17], v[16:17], v[20:21]
	s_nop 0
	v_pk_fma_f32 v[12:13], v[12:13], v[16:17], v[12:13]
	v_pk_fma_f32 v[16:17], v[86:87], v[18:19], v[98:99]
	v_pk_mul_f32 v[8:9], v[8:9], v[12:13]
	v_lshlrev_b32_e32 v12, 16, v37
	v_and_b32_e32 v13, 0xffff0000, v37
	v_pk_fma_f32 v[14:15], v[90:91], v[14:15], v[16:17]
	v_cvt_pk_bf16_f32 v8, v8, v9
	s_nop 0
	v_pk_fma_f32 v[12:13], v[94:95], v[12:13], v[14:15]
	s_nop 0
	v_pk_mul_f32 v[14:15], v[12:13], s[26:27] op_sel_hi:[1,0]
	v_pk_mul_f32 v[12:13], v[12:13], 0.5 op_sel_hi:[1,0]
	v_med3_f32 v14, v14, s71, v224
	v_med3_f32 v15, v15, s71, v224
	v_pk_mul_f32 v[16:17], v[14:15], v[14:15]
	s_nop 0
	v_pk_fma_f32 v[18:19], v[16:17], s[28:29], v[2:3] op_sel_hi:[1,0,0] neg_lo:[1,0,0] neg_hi:[1,0,0]
	s_nop 0
	v_pk_fma_f32 v[18:19], v[16:17], v[18:19], s[34:35] op_sel_hi:[1,1,0]
	s_nop 0
	v_pk_fma_f32 v[18:19], v[16:17], v[18:19], s[36:37] op_sel_hi:[1,1,0]
	s_nop 0
	v_pk_fma_f32 v[18:19], v[16:17], v[18:19], s[38:39] op_sel_hi:[1,1,0]
	s_nop 0
	v_pk_fma_f32 v[18:19], v[16:17], v[18:19], s[40:41] op_sel_hi:[1,1,0]
	s_nop 0
	v_pk_fma_f32 v[18:19], v[16:17], v[18:19], s[42:43] op_sel_hi:[1,1,0]
	s_nop 0
	v_pk_fma_f32 v[16:17], v[16:17], v[18:19], s[44:45] op_sel_hi:[1,1,0]
	v_lshlrev_b32_e32 v18, 16, v38
	v_pk_mul_f32 v[14:15], v[14:15], v[16:17]
	v_and_b32_e32 v19, 0xffff0000, v38
	v_pk_fma_f32 v[12:13], v[12:13], v[14:15], v[12:13]
	v_mov_b32_dpp v15, v42 row_ror:2 row_mask:0xf bank_mask:0xf bound_ctrl:1
	v_pk_mul_f32 v[10:11], v[10:11], v[12:13]
	v_mov_b32_dpp v17, v43 row_ror:2 row_mask:0xf bank_mask:0xf bound_ctrl:1
	v_mov_b32_dpp v15, v38 row_shr:2 row_mask:0xf bank_mask:0xf
	v_lshlrev_b32_e32 v14, 16, v15
	v_and_b32_e32 v15, 0xffff0000, v15
	v_cvt_pk_bf16_f32 v9, v10, v11
	v_lshlrev_b32_e32 v10, 16, v1
	v_and_b32_e32 v11, 0xffff0000, v1
	v_pk_fma_f32 v[14:15], v[64:65], v[14:15], v[80:81]
	v_mov_b32_dpp v13, v43 row_ror:1 row_mask:0xf bank_mask:0xf bound_ctrl:1
	v_pk_fma_f32 v[10:11], v[72:73], v[10:11], v[14:15]
	v_mov_b32_dpp v17, v39 row_shr:2 row_mask:0xf bank_mask:0xf
	v_pk_fma_f32 v[10:11], v[76:77], v[18:19], v[10:11]
	v_mov_b32_dpp v13, v39 row_shr:1 row_mask:0xf bank_mask:0xf
	v_pk_mul_f32 v[14:15], v[10:11], s[26:27] op_sel_hi:[1,0]
	v_lshlrev_b32_e32 v16, 16, v17
	v_med3_f32 v14, v14, s71, v224
	v_med3_f32 v15, v15, s71, v224
	v_pk_mul_f32 v[18:19], v[14:15], v[14:15]
	v_and_b32_e32 v17, 0xffff0000, v17
	v_pk_fma_f32 v[20:21], v[18:19], s[28:29], v[2:3] op_sel_hi:[1,0,0] neg_lo:[1,0,0] neg_hi:[1,0,0]
	v_pk_mul_f32 v[10:11], v[10:11], 0.5 op_sel_hi:[1,0]
	v_pk_fma_f32 v[20:21], v[18:19], v[20:21], s[34:35] op_sel_hi:[1,1,0]
	v_lshlrev_b32_e32 v12, 16, v13
	v_pk_fma_f32 v[20:21], v[18:19], v[20:21], s[36:37] op_sel_hi:[1,1,0]
	v_and_b32_e32 v13, 0xffff0000, v13
	v_pk_fma_f32 v[20:21], v[18:19], v[20:21], s[38:39] op_sel_hi:[1,1,0]
	s_nop 0
	v_pk_fma_f32 v[20:21], v[18:19], v[20:21], s[40:41] op_sel_hi:[1,1,0]
	s_nop 0
	v_pk_fma_f32 v[20:21], v[18:19], v[20:21], s[42:43] op_sel_hi:[1,1,0]
	s_nop 0
	v_pk_fma_f32 v[18:19], v[18:19], v[20:21], s[44:45] op_sel_hi:[1,1,0]
	s_nop 0
	v_pk_mul_f32 v[14:15], v[14:15], v[18:19]
	s_nop 0
	v_pk_fma_f32 v[10:11], v[10:11], v[14:15], v[10:11]
	v_pk_fma_f32 v[14:15], v[66:67], v[16:17], v[82:83]
	v_pk_mul_f32 v[4:5], v[4:5], v[10:11]
	v_lshlrev_b32_e32 v10, 16, v39
	v_and_b32_e32 v11, 0xffff0000, v39
	v_pk_fma_f32 v[12:13], v[74:75], v[12:13], v[14:15]
	s_nop 0
	v_pk_fma_f32 v[10:11], v[78:79], v[10:11], v[12:13]
	s_nop 0
	v_pk_mul_f32 v[12:13], v[10:11], s[26:27] op_sel_hi:[1,0]
	v_pk_mul_f32 v[10:11], v[10:11], 0.5 op_sel_hi:[1,0]
	v_med3_f32 v12, v12, s71, v224
	v_med3_f32 v13, v13, s71, v224
	v_pk_mul_f32 v[14:15], v[12:13], v[12:13]
	s_nop 0
	v_pk_fma_f32 v[2:3], v[14:15], s[28:29], v[2:3] op_sel_hi:[1,0,0] neg_lo:[1,0,0] neg_hi:[1,0,0]
	s_nop 0
	v_pk_fma_f32 v[2:3], v[14:15], v[2:3], s[34:35] op_sel_hi:[1,1,0]
	s_nop 0
	v_pk_fma_f32 v[2:3], v[14:15], v[2:3], s[36:37] op_sel_hi:[1,1,0]
	s_nop 0
	v_pk_fma_f32 v[2:3], v[14:15], v[2:3], s[38:39] op_sel_hi:[1,1,0]
	s_nop 0
	v_pk_fma_f32 v[2:3], v[14:15], v[2:3], s[40:41] op_sel_hi:[1,1,0]
	s_nop 0
	v_pk_fma_f32 v[2:3], v[14:15], v[2:3], s[42:43] op_sel_hi:[1,1,0]
	s_nop 0
	v_pk_fma_f32 v[2:3], v[14:15], v[2:3], s[44:45] op_sel_hi:[1,1,0]
	s_nop 0
	v_pk_mul_f32 v[2:3], v[12:13], v[2:3]
	s_nop 0
	v_pk_fma_f32 v[2:3], v[10:11], v[2:3], v[10:11]
	v_cvt_pk_bf16_f32 v10, v4, v5
	s_nop 0
	v_pk_mul_f32 v[2:3], v[6:7], v[2:3]
	s_nop 0
	v_cvt_pk_bf16_f32 v11, v2, v3
	v_lshl_add_u64 v[2:3], v[132:133], 0, v[60:61]
	global_store_dwordx4 v[2:3], v[8:11], off nt
	s_andn2_b64 vcc, exec, s[50:51]
	s_mov_b64 s[0:1], -1
	s_cbranch_vccnz .LBB0_3124
